# GEMM MFMA issue order: consecutive MFMAs share no source operand (A alternates, B sequence 0,1,2,3,1,0,3,2 within each 2x4 group)
# baseline (speedup 1.0000x reference)
; #define PG8_STAGE(bufoff, gbase, voff) do { _Pragma("unroll") for (int _i = 0; _i < 2; ++_i) \
;         __builtin_amdgcn_global_load_lds((const unsigned*)((const char*)(gbase) + (voff)[_i]), (PG8_LAS unsigned*)(lds + (bufoff) + ldsw + _i * 8192), 16, 0, 0); } while (0)
; #define PG8_LDA(dst, b, h) do { _Pragma("unroll") for (int m = 0; m < 4; ++m) _Pragma("unroll") for (int k = 0; k < 2; ++k) dst[m][k] = *(const PG8_LAS bf16x8*)(lds + PG8_SA(b, h) + aoff + m * 2048 + k * 1024); } while (0)
; #define PG8_LDB(dst, b, h) do { _Pragma("unroll") for (int n = 0; n < 2; ++n) _Pragma("unroll") for (int k = 0; k < 2; ++k) dst[n][k] = *(const PG8_LAS bf16x8*)(lds + PG8_SB(b, h) + boff + n * 2048 + k * 1024); } while (0)
; #define PG8_MMA(ai, bj, At, Bt) do { __builtin_amdgcn_s_setprio(1); _Pragma("unroll") for (int m = 0; m < 4; ++m) _Pragma("unroll") for (int n = 0; n < 2; ++n) _Pragma("unroll") for (int k = 0; k < 2; ++k) \
;         acc[ai][bj][m][n] = __builtin_amdgcn_mfma_f32_16x16x32_bf16(Bt[n][k], At[m][k], acc[ai][bj][m][n], 0, 0, 0); __builtin_amdgcn_s_setprio(0); } while (0)
; #define PG8_BAR __builtin_amdgcn_s_barrier()
; template <class Epi, class Sched, bool ALIGN_EPI = false, bool SP2 = false>
; __device__ __forceinline__ void gemm_phase(PG8_LAS unsigned char* lds, const Gemm g, const Sched& S, const Epi& E) {
;     ...
;         const bool has_next = S.next(ui + 1, nxt);
;         const char* nA = has_next ? (const char*)g.A + (size_t)nxt.pm * tstep : cA; const char* nB = has_next ? (const char*)g.Bt + (size_t)nxt.pn * tstep : cB;
;         for (int t = 0; t < nt; t += 2) {
;             const bool last = (t == nt - 2);
;             const char* a1 = cA + (size_t)(t + 1) * kstep;
;             const char* a2 = last ? nA : cA + (size_t)(t + 2) * kstep; const char* b2 = last ? nB : cB + (size_t)(t + 2) * kstep;
;             const char* a3 = a2 + kstep; const char* b3 = b2 + kstep;
;             if (last && has_next) S.a_ready(nxt);
;             if constexpr (SP2) {
;             PG8_LDB(B0, 0, 0); PG8_LDB(B1, 0, 1); PG8_SCHED; PG8_LDA(At, 0, 0); PG8_STAGE(PG8_SA(1, 1), a1 + hstep, voffA);
;             PG8_WAIT_V(8); PG8_WAIT_L(0); PG8_BAR; PG8_MMA(0, 0, At, B0); PG8_MMA(0, 1, At, B1); PG8_BAR; PG8_SCHED;
;             PG8_LDA(At, 0, 1); PG8_STAGE(PG8_SB(0, 0), b2, voffB); PG8_STAGE(PG8_SB(0, 1), b2 + hstep, voffB); PG8_STAGE(PG8_SA(0, 0), a2, voffA);
.LBB0_190:
	s_ashr_i32 s27, s26, 31
	s_lshl_b64 s[14:15], s[26:27], 19
	s_add_u32 s28, s22, s14
	s_addc_u32 s29, s23, s15
	s_and_b64 s[14:15], s[0:1], exec
	s_cselect_b32 s27, s29, s49
	s_cselect_b32 s67, s28, s48
	s_ashr_i32 s25, s24, 31
	s_lshl_b64 s[14:15], s[24:25], 19
	s_add_u32 s40, s94, s14
	s_addc_u32 s41, s96, s15
	s_and_b64 s[14:15], s[0:1], exec
	s_cselect_b32 s25, s41, s51
	s_cselect_b32 s86, s40, s50
	s_add_u32 s48, s48, 0x40080
	s_addc_u32 s49, s49, 0
	s_add_u32 s87, s50, 0x100
	s_addc_u32 s88, s51, 0
	s_mov_b32 s89, -2
	ds_read_b128 v[144:147], v155
	ds_read_b128 v[148:151], v155 offset:1024
	ds_read_b128 v[160:163], v155 offset:2048
	ds_read_b128 v[168:171], v155 offset:3072
	ds_read_b128 v[172:175], v156
	ds_read_b128 v[176:179], v156 offset:1024
	ds_read_b128 v[182:185], v156 offset:2048
	ds_read_b128 v[186:189], v156 offset:3072
	s_add_u32 s3, s48, 0xfffc0080
	s_addc_u32 s14, s49, -1
	s_cmp_eq_u32 s89, 12
	s_cselect_b32 s55, s27, s14
	s_cselect_b32 s54, s67, s3
	s_cselect_b32 s51, s25, s88
	s_cselect_b32 s50, s86, s87
	v_lshl_add_u64 v[164:165], s[48:49], 0, v[136:137]
	s_add_i32 m0, s45, 0xc000
	ds_read_b128 v[190:193], v157
	ds_read_b128 v[194:197], v157 offset:1024
	ds_read_b128 v[198:201], v157 offset:2048
	ds_read_b128 v[208:211], v157 offset:3072
	ds_read_b128 v[212:215], v157 offset:4096
	ds_read_b128 v[216:219], v157 offset:5120
	ds_read_b128 v[220:223], v157 offset:6144
	ds_read_b128 v[224:227], v157 offset:7168
	global_load_lds_dwordx4 v[164:165], off
	v_lshl_add_u64 v[164:165], s[48:49], 0, v[138:139]
	s_add_i32 m0, s45, 0xe000
	s_nop 0
	global_load_lds_dwordx4 v[164:165], off
	s_waitcnt vmcnt(8)
	s_waitcnt lgkmcnt(0)
	s_barrier
	s_setprio 1
	s_waitcnt lgkmcnt(0)
	v_mfma_f32_16x16x32_bf16 v[124:127], v[144:147], v[190:193], 0
	v_mfma_f32_16x16x32_bf16 v[104:107], v[160:163], v[198:201], 0
	v_mfma_f32_16x16x32_bf16 v[92:95], v[144:147], v[212:215], 0
	v_mfma_f32_16x16x32_bf16 v[72:75], v[160:163], v[220:223], 0
	v_mfma_f32_16x16x32_bf16 v[108:111], v[144:147], v[198:201], 0
	v_mfma_f32_16x16x32_bf16 v[120:123], v[160:163], v[190:193], 0
	v_mfma_f32_16x16x32_bf16 v[76:79], v[144:147], v[220:223], 0
	v_mfma_f32_16x16x32_bf16 v[88:91], v[160:163], v[212:215], 0
	v_mfma_f32_16x16x32_bf16 v[124:127], v[148:151], v[194:197], v[124:127]
	v_mfma_f32_16x16x32_bf16 v[104:107], v[168:171], v[208:211], v[104:107]
	v_mfma_f32_16x16x32_bf16 v[92:95], v[148:151], v[216:219], v[92:95]
	v_mfma_f32_16x16x32_bf16 v[72:75], v[168:171], v[224:227], v[72:75]
	v_mfma_f32_16x16x32_bf16 v[108:111], v[148:151], v[208:211], v[108:111]
	v_mfma_f32_16x16x32_bf16 v[120:123], v[168:171], v[194:197], v[120:123]
	v_mfma_f32_16x16x32_bf16 v[76:79], v[148:151], v[224:227], v[76:79]
	v_mfma_f32_16x16x32_bf16 v[88:91], v[168:171], v[216:219], v[88:91]
	s_setprio 0
	s_setprio 1
	v_mfma_f32_16x16x32_bf16 v[116:119], v[172:175], v[190:193], 0
	v_mfma_f32_16x16x32_bf16 v[96:99], v[182:185], v[198:201], 0
	v_mfma_f32_16x16x32_bf16 v[84:87], v[172:175], v[212:215], 0
	v_mfma_f32_16x16x32_bf16 v[64:67], v[182:185], v[220:223], 0
	v_mfma_f32_16x16x32_bf16 v[100:103], v[172:175], v[198:201], 0
	v_mfma_f32_16x16x32_bf16 v[112:115], v[182:185], v[190:193], 0
	v_mfma_f32_16x16x32_bf16 v[68:71], v[172:175], v[220:223], 0
	v_mfma_f32_16x16x32_bf16 v[80:83], v[182:185], v[212:215], 0
	v_mfma_f32_16x16x32_bf16 v[116:119], v[176:179], v[194:197], v[116:119]
	v_mfma_f32_16x16x32_bf16 v[96:99], v[186:189], v[208:211], v[96:99]
	v_mfma_f32_16x16x32_bf16 v[84:87], v[176:179], v[216:219], v[84:87]
	v_mfma_f32_16x16x32_bf16 v[64:67], v[186:189], v[224:227], v[64:67]
	v_mfma_f32_16x16x32_bf16 v[100:103], v[176:179], v[208:211], v[100:103]
	v_mfma_f32_16x16x32_bf16 v[112:115], v[186:189], v[194:197], v[112:115]
	v_mfma_f32_16x16x32_bf16 v[68:71], v[176:179], v[224:227], v[68:71]
	v_mfma_f32_16x16x32_bf16 v[80:83], v[186:189], v[216:219], v[80:83]
	s_setprio 0
	s_barrier
	s_add_i32 s3, s63, s43
	v_lshl_add_u64 v[164:165], s[50:51], 0, v[132:133]
	s_mov_b32 m0, s3
	ds_read_b128 v[190:193], v157 offset:16384
	ds_read_b128 v[194:197], v157 offset:17408
	ds_read_b128 v[198:201], v157 offset:18432
	ds_read_b128 v[208:211], v157 offset:19456
	ds_read_b128 v[212:215], v157 offset:20480
	ds_read_b128 v[216:219], v157 offset:21504
	ds_read_b128 v[220:223], v157 offset:22528
	ds_read_b128 v[224:227], v157 offset:23552
	global_load_lds_dwordx4 v[164:165], off
	s_add_i32 m0, s3, 0x2000
	s_add_u32 s14, s50, 0x40000
	v_lshl_add_u64 v[202:203], s[50:51], 0, v[128:129]
	s_addc_u32 s15, s51, 0
	s_add_i32 s3, s64, s43
	global_load_lds_dwordx4 v[202:203], off
	v_lshl_add_u64 v[228:229], s[14:15], 0, v[132:133]
	s_mov_b32 m0, s3
	global_load_lds_dwordx4 v[228:229], off
	v_lshl_add_u64 v[228:229], s[14:15], 0, v[128:129]
	s_add_i32 m0, s3, 0x2000
	s_nop 0
	global_load_lds_dwordx4 v[228:229], off
	s_waitcnt vmcnt(6)
	s_waitcnt lgkmcnt(0)
	s_barrier
; #define PG8_STAGE(bufoff, gbase, voff) do { _Pragma("unroll") for (int _i = 0; _i < 2; ++_i) \
;         __builtin_amdgcn_global_load_lds((const unsigned*)((const char*)(gbase) + (voff)[_i]), (PG8_LAS unsigned*)(lds + (bufoff) + ldsw + _i * 8192), 16, 0, 0); } while (0)
; #define PG8_LDA(dst, b, h) do { _Pragma("unroll") for (int m = 0; m < 4; ++m) _Pragma("unroll") for (int k = 0; k < 2; ++k) dst[m][k] = *(const PG8_LAS bf16x8*)(lds + PG8_SA(b, h) + aoff + m * 2048 + k * 1024); } while (0)
; #define PG8_LDB(dst, b, h) do { _Pragma("unroll") for (int n = 0; n < 2; ++n) _Pragma("unroll") for (int k = 0; k < 2; ++k) dst[n][k] = *(const PG8_LAS bf16x8*)(lds + PG8_SB(b, h) + boff + n * 2048 + k * 1024); } while (0)
; #define PG8_MMA(ai, bj, At, Bt) do { __builtin_amdgcn_s_setprio(1); _Pragma("unroll") for (int m = 0; m < 4; ++m) _Pragma("unroll") for (int n = 0; n < 2; ++n) _Pragma("unroll") for (int k = 0; k < 2; ++k) \
;         acc[ai][bj][m][n] = __builtin_amdgcn_mfma_f32_16x16x32_bf16(Bt[n][k], At[m][k], acc[ai][bj][m][n], 0, 0, 0); __builtin_amdgcn_s_setprio(0); } while (0)
; #define PG8_WAIT_V(n) asm volatile("s_waitcnt vmcnt(" #n ")" ::: "memory")
; #define PG8_WAIT_L(n) asm volatile("s_waitcnt lgkmcnt(" #n ")" ::: "memory")
; #define PG8_BAR __builtin_amdgcn_s_barrier()
; #define PG8_SCHED __builtin_amdgcn_sched_barrier(0)
; template <class Epi, class Sched, bool ALIGN_EPI = false, bool SP2 = false>
; __device__ __forceinline__ void gemm_phase(PG8_LAS unsigned char* lds, const Gemm g, const Sched& S, const Epi& E) {
;     ...
;             PG8_WAIT_V(8); PG8_WAIT_L(0); PG8_BAR; PG8_MMA(0, 0, At, B0); PG8_MMA(0, 1, At, B1); PG8_BAR; PG8_SCHED;
;             PG8_LDA(At, 0, 1); PG8_STAGE(PG8_SB(0, 0), b2, voffB); PG8_STAGE(PG8_SB(0, 1), b2 + hstep, voffB); PG8_STAGE(PG8_SA(0, 0), a2, voffA);
;             PG8_WAIT_V(8); PG8_WAIT_L(0); PG8_BAR; PG8_MMA(1, 0, At, B0); PG8_MMA(1, 1, At, B1); PG8_BAR; PG8_SCHED;
;             PG8_LDB(B0, 1, 0); PG8_LDB(B1, 1, 1); PG8_SCHED; PG8_LDA(At, 1, 0); PG8_STAGE(PG8_SA(0, 1), a2 + hstep, voffA);
;             PG8_WAIT_V(8); PG8_WAIT_L(0); PG8_BAR; PG8_MMA(0, 0, At, B0); PG8_MMA(0, 1, At, B1); PG8_BAR; PG8_SCHED;
	s_setprio 1
	s_waitcnt lgkmcnt(0)
	v_mfma_f32_16x16x32_bf16 v[60:63], v[144:147], v[190:193], 0
	v_mfma_f32_16x16x32_bf16 v[40:43], v[160:163], v[198:201], 0
	v_mfma_f32_16x16x32_bf16 v[28:31], v[144:147], v[212:215], 0
	v_mfma_f32_16x16x32_bf16 v[8:11], v[160:163], v[220:223], 0
	v_mfma_f32_16x16x32_bf16 v[44:47], v[144:147], v[198:201], 0
	v_mfma_f32_16x16x32_bf16 v[56:59], v[160:163], v[190:193], 0
	v_mfma_f32_16x16x32_bf16 v[12:15], v[144:147], v[220:223], 0
	v_mfma_f32_16x16x32_bf16 v[24:27], v[160:163], v[212:215], 0
	v_mfma_f32_16x16x32_bf16 v[60:63], v[148:151], v[194:197], v[60:63]
	v_mfma_f32_16x16x32_bf16 v[40:43], v[168:171], v[208:211], v[40:43]
	v_mfma_f32_16x16x32_bf16 v[28:31], v[148:151], v[216:219], v[28:31]
	v_mfma_f32_16x16x32_bf16 v[8:11], v[168:171], v[224:227], v[8:11]
	v_mfma_f32_16x16x32_bf16 v[44:47], v[148:151], v[208:211], v[44:47]
	v_mfma_f32_16x16x32_bf16 v[56:59], v[168:171], v[194:197], v[56:59]
	v_lshl_add_u64 v[228:229], s[54:55], 0, v[134:135]
	s_mov_b32 m0, s45
	s_nop 0
	global_load_lds_dwordx4 v[228:229], off
	v_mfma_f32_16x16x32_bf16 v[12:15], v[148:151], v[224:227], v[12:15]
	v_mfma_f32_16x16x32_bf16 v[24:27], v[168:171], v[216:219], v[24:27]
	s_setprio 0
	s_setprio 1
	v_mfma_f32_16x16x32_bf16 v[52:55], v[172:175], v[190:193], 0
	v_mfma_f32_16x16x32_bf16 v[32:35], v[182:185], v[198:201], 0
	v_mfma_f32_16x16x32_bf16 v[20:23], v[172:175], v[212:215], 0
	v_mfma_f32_16x16x32_bf16 v[0:3], v[182:185], v[220:223], 0
	v_mfma_f32_16x16x32_bf16 v[36:39], v[172:175], v[198:201], 0
	v_mfma_f32_16x16x32_bf16 v[48:51], v[182:185], v[190:193], 0
	v_mfma_f32_16x16x32_bf16 v[4:7], v[172:175], v[220:223], 0
	v_mfma_f32_16x16x32_bf16 v[16:19], v[182:185], v[212:215], 0
	v_mfma_f32_16x16x32_bf16 v[52:55], v[176:179], v[194:197], v[52:55]
	v_mfma_f32_16x16x32_bf16 v[32:35], v[186:189], v[208:211], v[32:35]
	v_mfma_f32_16x16x32_bf16 v[20:23], v[176:179], v[216:219], v[20:23]
	v_mfma_f32_16x16x32_bf16 v[0:3], v[186:189], v[224:227], v[0:3]
	v_mfma_f32_16x16x32_bf16 v[36:39], v[176:179], v[208:211], v[36:39]
	v_mfma_f32_16x16x32_bf16 v[48:51], v[186:189], v[194:197], v[48:51]
	v_lshl_add_u64 v[230:231], s[54:55], 0, v[130:131]
	s_mov_b32 m0, s57
	s_nop 0
	global_load_lds_dwordx4 v[230:231], off
	v_mfma_f32_16x16x32_bf16 v[4:7], v[176:179], v[224:227], v[4:7]
	v_mfma_f32_16x16x32_bf16 v[16:19], v[186:189], v[216:219], v[16:19]
	s_setprio 0
	s_barrier
	s_add_i32 s3, 0, 0x18000
	v_add_u32_e32 v159, s3, v153
	s_add_i32 s33, 0, 0x1c000
	ds_read_b128 v[144:147], v159
	ds_read_b128 v[148:151], v159 offset:1024
	ds_read_b128 v[160:163], v159 offset:2048
	ds_read_b128 v[168:171], v159 offset:3072
	v_add_u32_e32 v159, s33, v153
	ds_read_b128 v[172:175], v159
	ds_read_b128 v[176:179], v159 offset:1024
	ds_read_b128 v[182:185], v159 offset:2048
	ds_read_b128 v[186:189], v159 offset:3072
	s_add_u32 s14, s54, 0x40000
	s_addc_u32 s15, s55, 0
	s_mov_b32 m0, s58
	v_lshl_add_u64 v[232:233], s[14:15], 0, v[134:135]
	ds_read_b128 v[190:193], v157 offset:32768
	ds_read_b128 v[194:197], v157 offset:33792
	ds_read_b128 v[198:201], v157 offset:34816
	ds_read_b128 v[208:211], v157 offset:35840
	ds_read_b128 v[212:215], v157 offset:36864
	ds_read_b128 v[216:219], v157 offset:37888
	ds_read_b128 v[220:223], v157 offset:38912
	ds_read_b128 v[224:227], v157 offset:39936
	global_load_lds_dwordx4 v[232:233], off
	v_lshl_add_u64 v[232:233], s[14:15], 0, v[130:131]
	s_mov_b32 m0, s59
	s_nop 0
	global_load_lds_dwordx4 v[232:233], off
	s_waitcnt vmcnt(8)
	s_waitcnt lgkmcnt(0)
	s_barrier
	s_setprio 1
	s_waitcnt lgkmcnt(0)
	v_mfma_f32_16x16x32_bf16 v[124:127], v[144:147], v[190:193], v[124:127]
	v_mfma_f32_16x16x32_bf16 v[104:107], v[160:163], v[198:201], v[104:107]
	v_mfma_f32_16x16x32_bf16 v[92:95], v[144:147], v[212:215], v[92:95]
	v_mfma_f32_16x16x32_bf16 v[72:75], v[160:163], v[220:223], v[72:75]
	v_mfma_f32_16x16x32_bf16 v[108:111], v[144:147], v[198:201], v[108:111]
	v_mfma_f32_16x16x32_bf16 v[120:123], v[160:163], v[190:193], v[120:123]
	v_mfma_f32_16x16x32_bf16 v[76:79], v[144:147], v[220:223], v[76:79]
	v_mfma_f32_16x16x32_bf16 v[88:91], v[160:163], v[212:215], v[88:91]
	v_mfma_f32_16x16x32_bf16 v[124:127], v[148:151], v[194:197], v[124:127]
	v_mfma_f32_16x16x32_bf16 v[104:107], v[168:171], v[208:211], v[104:107]
	v_mfma_f32_16x16x32_bf16 v[92:95], v[148:151], v[216:219], v[92:95]
	v_mfma_f32_16x16x32_bf16 v[72:75], v[168:171], v[224:227], v[72:75]
	v_mfma_f32_16x16x32_bf16 v[108:111], v[148:151], v[208:211], v[108:111]
	v_mfma_f32_16x16x32_bf16 v[120:123], v[168:171], v[194:197], v[120:123]
	v_mfma_f32_16x16x32_bf16 v[76:79], v[148:151], v[224:227], v[76:79]
	v_mfma_f32_16x16x32_bf16 v[88:91], v[168:171], v[216:219], v[88:91]
	s_setprio 0
	s_setprio 1
	v_mfma_f32_16x16x32_bf16 v[116:119], v[172:175], v[190:193], v[116:119]
	v_mfma_f32_16x16x32_bf16 v[96:99], v[182:185], v[198:201], v[96:99]
	v_mfma_f32_16x16x32_bf16 v[84:87], v[172:175], v[212:215], v[84:87]
	v_mfma_f32_16x16x32_bf16 v[64:67], v[182:185], v[220:223], v[64:67]
	v_mfma_f32_16x16x32_bf16 v[100:103], v[172:175], v[198:201], v[100:103]
	v_mfma_f32_16x16x32_bf16 v[112:115], v[182:185], v[190:193], v[112:115]
	v_mfma_f32_16x16x32_bf16 v[68:71], v[172:175], v[220:223], v[68:71]
	v_mfma_f32_16x16x32_bf16 v[80:83], v[182:185], v[212:215], v[80:83]
	v_mfma_f32_16x16x32_bf16 v[116:119], v[176:179], v[194:197], v[116:119]
	v_mfma_f32_16x16x32_bf16 v[96:99], v[186:189], v[208:211], v[96:99]
	v_mfma_f32_16x16x32_bf16 v[84:87], v[176:179], v[216:219], v[84:87]
	v_mfma_f32_16x16x32_bf16 v[64:67], v[186:189], v[224:227], v[64:67]
	v_mfma_f32_16x16x32_bf16 v[100:103], v[176:179], v[208:211], v[100:103]
	v_mfma_f32_16x16x32_bf16 v[112:115], v[186:189], v[194:197], v[112:115]
	v_mfma_f32_16x16x32_bf16 v[68:71], v[176:179], v[224:227], v[68:71]
	v_mfma_f32_16x16x32_bf16 v[80:83], v[186:189], v[216:219], v[80:83]
	s_setprio 0
	s_barrier
; #define PG8_STAGE(bufoff, gbase, voff) do { _Pragma("unroll") for (int _i = 0; _i < 2; ++_i) \
;         __builtin_amdgcn_global_load_lds((const unsigned*)((const char*)(gbase) + (voff)[_i]), (PG8_LAS unsigned*)(lds + (bufoff) + ldsw + _i * 8192), 16, 0, 0); } while (0)
; #define PG8_LDA(dst, b, h) do { _Pragma("unroll") for (int m = 0; m < 4; ++m) _Pragma("unroll") for (int k = 0; k < 2; ++k) dst[m][k] = *(const PG8_LAS bf16x8*)(lds + PG8_SA(b, h) + aoff + m * 2048 + k * 1024); } while (0)
; #define PG8_LDB(dst, b, h) do { _Pragma("unroll") for (int n = 0; n < 2; ++n) _Pragma("unroll") for (int k = 0; k < 2; ++k) dst[n][k] = *(const PG8_LAS bf16x8*)(lds + PG8_SB(b, h) + boff + n * 2048 + k * 1024); } while (0)
; #define PG8_MMA(ai, bj, At, Bt) do { __builtin_amdgcn_s_setprio(1); _Pragma("unroll") for (int m = 0; m < 4; ++m) _Pragma("unroll") for (int n = 0; n < 2; ++n) _Pragma("unroll") for (int k = 0; k < 2; ++k) \
;         acc[ai][bj][m][n] = __builtin_amdgcn_mfma_f32_16x16x32_bf16(Bt[n][k], At[m][k], acc[ai][bj][m][n], 0, 0, 0); __builtin_amdgcn_s_setprio(0); } while (0)
; #define PG8_WAIT_V(n) asm volatile("s_waitcnt vmcnt(" #n ")" ::: "memory")
; template <class Epi, class Sched, bool ALIGN_EPI = false, bool SP2 = false>
; __device__ __forceinline__ void gemm_phase(PG8_LAS unsigned char* lds, const Gemm g, const Sched& S, const Epi& E) {
;     ...
;             PG8_LDB(B0, 0, 0); PG8_LDB(B1, 0, 1); PG8_SCHED; PG8_LDA(At, 0, 0); PG8_STAGE(PG8_SA(1, 1), a1 + hstep, voffA);
;             PG8_WAIT_V(8); PG8_WAIT_L(0); PG8_BAR; PG8_MMA(0, 0, At, B0); PG8_MMA(0, 1, At, B1); PG8_BAR; PG8_SCHED;
;             PG8_LDA(At, 0, 1); PG8_STAGE(PG8_SB(0, 0), b2, voffB); PG8_STAGE(PG8_SB(0, 1), b2 + hstep, voffB); PG8_STAGE(PG8_SA(0, 0), a2, voffA);
;             PG8_WAIT_V(8); PG8_WAIT_L(0); PG8_BAR; PG8_MMA(1, 0, At, B0); PG8_MMA(1, 1, At, B1); PG8_BAR; PG8_SCHED;
;             PG8_LDB(B0, 1, 0); PG8_LDB(B1, 1, 1); PG8_SCHED; PG8_LDA(At, 1, 0); PG8_STAGE(PG8_SA(0, 1), a2 + hstep, voffA);
;             PG8_WAIT_V(8); PG8_WAIT_L(0); PG8_BAR; PG8_MMA(0, 0, At, B0); PG8_MMA(0, 1, At, B1); PG8_BAR; PG8_SCHED;
;             PG8_LDA(At, 1, 1); PG8_STAGE(PG8_SB(1, 0), b3, voffB); PG8_STAGE(PG8_SB(1, 1), b3 + hstep, voffB); PG8_STAGE(PG8_SA(1, 0), a3, voffA);
;             PG8_WAIT_V(8); PG8_WAIT_L(0); PG8_BAR; PG8_MMA(1, 0, At, B0); PG8_MMA(1, 1, At, B1); PG8_BAR; PG8_SCHED;
	s_add_i32 s3, s3, s43
	v_lshl_add_u64 v[164:165], v[164:165], 0, s[10:11]
	s_mov_b32 m0, s3
	ds_read_b128 v[190:193], v157 offset:49152
	ds_read_b128 v[194:197], v157 offset:50176
	ds_read_b128 v[198:201], v157 offset:51200
	ds_read_b128 v[208:211], v157 offset:52224
	ds_read_b128 v[212:215], v157 offset:53248
	ds_read_b128 v[216:219], v157 offset:54272
	ds_read_b128 v[220:223], v157 offset:55296
	ds_read_b128 v[224:227], v157 offset:56320
	global_load_lds_dwordx4 v[164:165], off
	s_add_i32 m0, s3, 0x2000
	s_add_u32 s14, s50, 0x40080
	v_lshl_add_u64 v[164:165], v[202:203], 0, s[10:11]
	s_addc_u32 s15, s51, 0
	s_add_i32 s3, s33, s43
	global_load_lds_dwordx4 v[164:165], off
	v_lshl_add_u64 v[164:165], s[14:15], 0, v[132:133]
	s_mov_b32 m0, s3
	s_nop 0
	global_load_lds_dwordx4 v[164:165], off
	v_lshl_add_u64 v[164:165], s[14:15], 0, v[128:129]
	s_add_i32 m0, s3, 0x2000
	s_nop 0
	global_load_lds_dwordx4 v[164:165], off
	s_waitcnt vmcnt(6)
	s_waitcnt lgkmcnt(0)
	s_barrier
	s_setprio 1
	s_waitcnt lgkmcnt(0)
	v_mfma_f32_16x16x32_bf16 v[60:63], v[144:147], v[190:193], v[60:63]
	v_mfma_f32_16x16x32_bf16 v[40:43], v[160:163], v[198:201], v[40:43]
	v_mfma_f32_16x16x32_bf16 v[28:31], v[144:147], v[212:215], v[28:31]
	v_mfma_f32_16x16x32_bf16 v[8:11], v[160:163], v[220:223], v[8:11]
	v_mfma_f32_16x16x32_bf16 v[44:47], v[144:147], v[198:201], v[44:47]
	v_mfma_f32_16x16x32_bf16 v[56:59], v[160:163], v[190:193], v[56:59]
	v_mfma_f32_16x16x32_bf16 v[12:15], v[144:147], v[220:223], v[12:15]
	v_mfma_f32_16x16x32_bf16 v[24:27], v[160:163], v[212:215], v[24:27]
	v_mfma_f32_16x16x32_bf16 v[60:63], v[148:151], v[194:197], v[60:63]
	v_mfma_f32_16x16x32_bf16 v[40:43], v[168:171], v[208:211], v[40:43]
	v_mfma_f32_16x16x32_bf16 v[28:31], v[148:151], v[216:219], v[28:31]
	v_mfma_f32_16x16x32_bf16 v[8:11], v[168:171], v[224:227], v[8:11]
	v_mfma_f32_16x16x32_bf16 v[44:47], v[148:151], v[208:211], v[44:47]
	v_mfma_f32_16x16x32_bf16 v[56:59], v[168:171], v[194:197], v[56:59]
	v_lshl_add_u64 v[164:165], v[228:229], 0, s[10:11]
	s_mov_b32 m0, s61
	s_nop 0
	global_load_lds_dwordx4 v[164:165], off
	v_mfma_f32_16x16x32_bf16 v[12:15], v[148:151], v[224:227], v[12:15]
	v_mfma_f32_16x16x32_bf16 v[24:27], v[168:171], v[216:219], v[24:27]
	s_setprio 0
	s_setprio 1
	v_mfma_f32_16x16x32_bf16 v[52:55], v[172:175], v[190:193], v[52:55]
	v_mfma_f32_16x16x32_bf16 v[32:35], v[182:185], v[198:201], v[32:35]
	v_mfma_f32_16x16x32_bf16 v[20:23], v[172:175], v[212:215], v[20:23]
	v_mfma_f32_16x16x32_bf16 v[0:3], v[182:185], v[220:223], v[0:3]
	v_mfma_f32_16x16x32_bf16 v[36:39], v[172:175], v[198:201], v[36:39]
	v_mfma_f32_16x16x32_bf16 v[48:51], v[182:185], v[190:193], v[48:51]
	v_mfma_f32_16x16x32_bf16 v[4:7], v[172:175], v[220:223], v[4:7]
	v_mfma_f32_16x16x32_bf16 v[16:19], v[182:185], v[212:215], v[16:19]
	v_mfma_f32_16x16x32_bf16 v[52:55], v[176:179], v[194:197], v[52:55]
	v_mfma_f32_16x16x32_bf16 v[32:35], v[186:189], v[208:211], v[32:35]
	v_mfma_f32_16x16x32_bf16 v[20:23], v[176:179], v[216:219], v[20:23]
	v_mfma_f32_16x16x32_bf16 v[0:3], v[186:189], v[224:227], v[0:3]
	v_mfma_f32_16x16x32_bf16 v[36:39], v[176:179], v[208:211], v[36:39]
	v_mfma_f32_16x16x32_bf16 v[48:51], v[186:189], v[194:197], v[48:51]
	v_lshl_add_u64 v[164:165], v[230:231], 0, s[10:11]
	s_mov_b32 m0, s62
	s_nop 0
	global_load_lds_dwordx4 v[164:165], off
	v_mfma_f32_16x16x32_bf16 v[4:7], v[176:179], v[224:227], v[4:7]
	v_mfma_f32_16x16x32_bf16 v[16:19], v[186:189], v[216:219], v[16:19]
	s_setprio 0
	s_barrier
	s_add_i32 s89, s89, 2
	s_add_u32 s48, s48, 0x100
	s_addc_u32 s49, s49, 0
	s_add_u32 s87, s87, 0x100
	s_addc_u32 s88, s88, 0
.LBB0_191:
	ds_read_b128 v[144:147], v155
	ds_read_b128 v[148:151], v155 offset:1024
	ds_read_b128 v[160:163], v155 offset:2048
	ds_read_b128 v[168:171], v155 offset:3072
	ds_read_b128 v[172:175], v156
	ds_read_b128 v[176:179], v156 offset:1024
	ds_read_b128 v[182:185], v156 offset:2048
	ds_read_b128 v[186:189], v156 offset:3072
	s_add_u32 s3, s48, 0xfffc0080
	s_addc_u32 s14, s49, -1
	s_cmp_eq_u32 s89, 12
	s_cselect_b32 s55, s27, s14
	s_cselect_b32 s54, s67, s3
	s_cselect_b32 s51, s25, s88
	s_cselect_b32 s50, s86, s87
	v_lshl_add_u64 v[164:165], s[48:49], 0, v[136:137]
	s_add_i32 m0, s45, 0xc000
	ds_read_b128 v[190:193], v157
	ds_read_b128 v[194:197], v157 offset:1024
	ds_read_b128 v[198:201], v157 offset:2048
	ds_read_b128 v[208:211], v157 offset:3072
	ds_read_b128 v[212:215], v157 offset:4096
	ds_read_b128 v[216:219], v157 offset:5120
	ds_read_b128 v[220:223], v157 offset:6144
	ds_read_b128 v[224:227], v157 offset:7168
	global_load_lds_dwordx4 v[164:165], off
	v_lshl_add_u64 v[164:165], s[48:49], 0, v[138:139]
	s_add_i32 m0, s45, 0xe000
	s_nop 0
	global_load_lds_dwordx4 v[164:165], off
	s_waitcnt vmcnt(8)
	s_waitcnt lgkmcnt(0)
	s_barrier
; #define PG8_STAGE(bufoff, gbase, voff) do { _Pragma("unroll") for (int _i = 0; _i < 2; ++_i) \
;         __builtin_amdgcn_global_load_lds((const unsigned*)((const char*)(gbase) + (voff)[_i]), (PG8_LAS unsigned*)(lds + (bufoff) + ldsw + _i * 8192), 16, 0, 0); } while (0)
; #define PG8_LDA(dst, b, h) do { _Pragma("unroll") for (int m = 0; m < 4; ++m) _Pragma("unroll") for (int k = 0; k < 2; ++k) dst[m][k] = *(const PG8_LAS bf16x8*)(lds + PG8_SA(b, h) + aoff + m * 2048 + k * 1024); } while (0)
; #define PG8_LDB(dst, b, h) do { _Pragma("unroll") for (int n = 0; n < 2; ++n) _Pragma("unroll") for (int k = 0; k < 2; ++k) dst[n][k] = *(const PG8_LAS bf16x8*)(lds + PG8_SB(b, h) + boff + n * 2048 + k * 1024); } while (0)
; #define PG8_MMA(ai, bj, At, Bt) do { __builtin_amdgcn_s_setprio(1); _Pragma("unroll") for (int m = 0; m < 4; ++m) _Pragma("unroll") for (int n = 0; n < 2; ++n) _Pragma("unroll") for (int k = 0; k < 2; ++k) \
;         acc[ai][bj][m][n] = __builtin_amdgcn_mfma_f32_16x16x32_bf16(Bt[n][k], At[m][k], acc[ai][bj][m][n], 0, 0, 0); __builtin_amdgcn_s_setprio(0); } while (0)
; #define PG8_WAIT_V(n) asm volatile("s_waitcnt vmcnt(" #n ")" ::: "memory")
; #define PG8_WAIT_L(n) asm volatile("s_waitcnt lgkmcnt(" #n ")" ::: "memory")
; #define PG8_BAR __builtin_amdgcn_s_barrier()
; #define PG8_SCHED __builtin_amdgcn_sched_barrier(0)
; template <class Epi, class Sched, bool ALIGN_EPI = false, bool SP2 = false>
; __device__ __forceinline__ void gemm_phase(PG8_LAS unsigned char* lds, const Gemm g, const Sched& S, const Epi& E) {
;     ...
;             PG8_LDB(B0, 0, 0); PG8_LDB(B1, 0, 1); PG8_SCHED; PG8_LDA(At, 0, 0); PG8_STAGE(PG8_SA(1, 1), a1 + hstep, voffA);
;             PG8_WAIT_V(8); PG8_WAIT_L(0); PG8_BAR; PG8_MMA(0, 0, At, B0); PG8_MMA(0, 1, At, B1); PG8_BAR; PG8_SCHED;
;             PG8_LDA(At, 0, 1); PG8_STAGE(PG8_SB(0, 0), b2, voffB); PG8_STAGE(PG8_SB(0, 1), b2 + hstep, voffB); PG8_STAGE(PG8_SA(0, 0), a2, voffA);
;             PG8_WAIT_V(8); PG8_WAIT_L(0); PG8_BAR; PG8_MMA(1, 0, At, B0); PG8_MMA(1, 1, At, B1); PG8_BAR; PG8_SCHED;
	s_setprio 1
	s_waitcnt lgkmcnt(0)
	v_mfma_f32_16x16x32_bf16 v[124:127], v[144:147], v[190:193], v[124:127]
	v_mfma_f32_16x16x32_bf16 v[104:107], v[160:163], v[198:201], v[104:107]
	v_mfma_f32_16x16x32_bf16 v[92:95], v[144:147], v[212:215], v[92:95]
	v_mfma_f32_16x16x32_bf16 v[72:75], v[160:163], v[220:223], v[72:75]
	v_mfma_f32_16x16x32_bf16 v[108:111], v[144:147], v[198:201], v[108:111]
	v_mfma_f32_16x16x32_bf16 v[120:123], v[160:163], v[190:193], v[120:123]
	v_mfma_f32_16x16x32_bf16 v[76:79], v[144:147], v[220:223], v[76:79]
	v_mfma_f32_16x16x32_bf16 v[88:91], v[160:163], v[212:215], v[88:91]
	v_mfma_f32_16x16x32_bf16 v[124:127], v[148:151], v[194:197], v[124:127]
	v_mfma_f32_16x16x32_bf16 v[104:107], v[168:171], v[208:211], v[104:107]
	v_mfma_f32_16x16x32_bf16 v[92:95], v[148:151], v[216:219], v[92:95]
	v_mfma_f32_16x16x32_bf16 v[72:75], v[168:171], v[224:227], v[72:75]
	v_mfma_f32_16x16x32_bf16 v[108:111], v[148:151], v[208:211], v[108:111]
	v_mfma_f32_16x16x32_bf16 v[120:123], v[168:171], v[194:197], v[120:123]
	v_mfma_f32_16x16x32_bf16 v[76:79], v[148:151], v[224:227], v[76:79]
	v_mfma_f32_16x16x32_bf16 v[88:91], v[168:171], v[216:219], v[88:91]
	s_setprio 0
	s_setprio 1
	v_mfma_f32_16x16x32_bf16 v[116:119], v[172:175], v[190:193], v[116:119]
	v_mfma_f32_16x16x32_bf16 v[96:99], v[182:185], v[198:201], v[96:99]
	v_mfma_f32_16x16x32_bf16 v[84:87], v[172:175], v[212:215], v[84:87]
	v_mfma_f32_16x16x32_bf16 v[64:67], v[182:185], v[220:223], v[64:67]
	v_mfma_f32_16x16x32_bf16 v[100:103], v[172:175], v[198:201], v[100:103]
	v_mfma_f32_16x16x32_bf16 v[112:115], v[182:185], v[190:193], v[112:115]
	v_mfma_f32_16x16x32_bf16 v[68:71], v[172:175], v[220:223], v[68:71]
	v_mfma_f32_16x16x32_bf16 v[80:83], v[182:185], v[212:215], v[80:83]
	v_mfma_f32_16x16x32_bf16 v[116:119], v[176:179], v[194:197], v[116:119]
	v_mfma_f32_16x16x32_bf16 v[96:99], v[186:189], v[208:211], v[96:99]
	v_mfma_f32_16x16x32_bf16 v[84:87], v[176:179], v[216:219], v[84:87]
	v_mfma_f32_16x16x32_bf16 v[64:67], v[186:189], v[224:227], v[64:67]
	v_mfma_f32_16x16x32_bf16 v[100:103], v[176:179], v[208:211], v[100:103]
	v_mfma_f32_16x16x32_bf16 v[112:115], v[186:189], v[194:197], v[112:115]
	v_mfma_f32_16x16x32_bf16 v[68:71], v[176:179], v[224:227], v[68:71]
	v_mfma_f32_16x16x32_bf16 v[80:83], v[186:189], v[216:219], v[80:83]
	s_setprio 0
	s_barrier
	s_add_i32 s3, s63, s43
	v_lshl_add_u64 v[164:165], s[50:51], 0, v[132:133]
	s_mov_b32 m0, s3
	ds_read_b128 v[190:193], v157 offset:16384
	ds_read_b128 v[194:197], v157 offset:17408
	ds_read_b128 v[198:201], v157 offset:18432
	ds_read_b128 v[208:211], v157 offset:19456
	ds_read_b128 v[212:215], v157 offset:20480
	ds_read_b128 v[216:219], v157 offset:21504
	ds_read_b128 v[220:223], v157 offset:22528
	ds_read_b128 v[224:227], v157 offset:23552
	global_load_lds_dwordx4 v[164:165], off
	s_add_i32 m0, s3, 0x2000
	s_add_u32 s14, s50, 0x40000
	v_lshl_add_u64 v[202:203], s[50:51], 0, v[128:129]
	s_addc_u32 s15, s51, 0
	s_add_i32 s3, s64, s43
	global_load_lds_dwordx4 v[202:203], off
	v_lshl_add_u64 v[228:229], s[14:15], 0, v[132:133]
	s_mov_b32 m0, s3
	global_load_lds_dwordx4 v[228:229], off
	v_lshl_add_u64 v[228:229], s[14:15], 0, v[128:129]
	s_add_i32 m0, s3, 0x2000
	s_nop 0
	global_load_lds_dwordx4 v[228:229], off
	s_waitcnt vmcnt(6)
	s_waitcnt lgkmcnt(0)
	s_barrier
	s_setprio 1
	s_waitcnt lgkmcnt(0)
	v_mfma_f32_16x16x32_bf16 v[60:63], v[144:147], v[190:193], v[60:63]
	v_mfma_f32_16x16x32_bf16 v[40:43], v[160:163], v[198:201], v[40:43]
	v_mfma_f32_16x16x32_bf16 v[28:31], v[144:147], v[212:215], v[28:31]
	v_mfma_f32_16x16x32_bf16 v[8:11], v[160:163], v[220:223], v[8:11]
	v_mfma_f32_16x16x32_bf16 v[44:47], v[144:147], v[198:201], v[44:47]
	v_mfma_f32_16x16x32_bf16 v[56:59], v[160:163], v[190:193], v[56:59]
	v_mfma_f32_16x16x32_bf16 v[12:15], v[144:147], v[220:223], v[12:15]
	v_mfma_f32_16x16x32_bf16 v[24:27], v[160:163], v[212:215], v[24:27]
	v_mfma_f32_16x16x32_bf16 v[60:63], v[148:151], v[194:197], v[60:63]
	v_mfma_f32_16x16x32_bf16 v[40:43], v[168:171], v[208:211], v[40:43]
	v_mfma_f32_16x16x32_bf16 v[28:31], v[148:151], v[216:219], v[28:31]
	v_mfma_f32_16x16x32_bf16 v[8:11], v[168:171], v[224:227], v[8:11]
	v_mfma_f32_16x16x32_bf16 v[44:47], v[148:151], v[208:211], v[44:47]
	v_mfma_f32_16x16x32_bf16 v[56:59], v[168:171], v[194:197], v[56:59]
	v_lshl_add_u64 v[228:229], s[54:55], 0, v[134:135]
	s_mov_b32 m0, s45
	s_nop 0
	global_load_lds_dwordx4 v[228:229], off
	v_mfma_f32_16x16x32_bf16 v[12:15], v[148:151], v[224:227], v[12:15]
	v_mfma_f32_16x16x32_bf16 v[24:27], v[168:171], v[216:219], v[24:27]
	s_setprio 0
	s_setprio 1
	v_mfma_f32_16x16x32_bf16 v[52:55], v[172:175], v[190:193], v[52:55]
	v_mfma_f32_16x16x32_bf16 v[32:35], v[182:185], v[198:201], v[32:35]
	v_mfma_f32_16x16x32_bf16 v[20:23], v[172:175], v[212:215], v[20:23]
	v_mfma_f32_16x16x32_bf16 v[0:3], v[182:185], v[220:223], v[0:3]
	v_mfma_f32_16x16x32_bf16 v[36:39], v[172:175], v[198:201], v[36:39]
	v_mfma_f32_16x16x32_bf16 v[48:51], v[182:185], v[190:193], v[48:51]
	v_mfma_f32_16x16x32_bf16 v[4:7], v[172:175], v[220:223], v[4:7]
	v_mfma_f32_16x16x32_bf16 v[16:19], v[182:185], v[212:215], v[16:19]
	v_mfma_f32_16x16x32_bf16 v[52:55], v[176:179], v[194:197], v[52:55]
	v_mfma_f32_16x16x32_bf16 v[32:35], v[186:189], v[208:211], v[32:35]
	v_mfma_f32_16x16x32_bf16 v[20:23], v[176:179], v[216:219], v[20:23]
	v_mfma_f32_16x16x32_bf16 v[0:3], v[186:189], v[224:227], v[0:3]
	v_mfma_f32_16x16x32_bf16 v[36:39], v[176:179], v[208:211], v[36:39]
	v_mfma_f32_16x16x32_bf16 v[48:51], v[186:189], v[194:197], v[48:51]
	v_lshl_add_u64 v[230:231], s[54:55], 0, v[130:131]
	s_mov_b32 m0, s57
	s_nop 0
	global_load_lds_dwordx4 v[230:231], off
	v_mfma_f32_16x16x32_bf16 v[4:7], v[176:179], v[224:227], v[4:7]
	v_mfma_f32_16x16x32_bf16 v[16:19], v[186:189], v[216:219], v[16:19]
	s_setprio 0
	s_barrier
; #define PG8_STAGE(bufoff, gbase, voff) do { _Pragma("unroll") for (int _i = 0; _i < 2; ++_i) \
;         __builtin_amdgcn_global_load_lds((const unsigned*)((const char*)(gbase) + (voff)[_i]), (PG8_LAS unsigned*)(lds + (bufoff) + ldsw + _i * 8192), 16, 0, 0); } while (0)
; #define PG8_LDA(dst, b, h) do { _Pragma("unroll") for (int m = 0; m < 4; ++m) _Pragma("unroll") for (int k = 0; k < 2; ++k) dst[m][k] = *(const PG8_LAS bf16x8*)(lds + PG8_SA(b, h) + aoff + m * 2048 + k * 1024); } while (0)
; #define PG8_LDB(dst, b, h) do { _Pragma("unroll") for (int n = 0; n < 2; ++n) _Pragma("unroll") for (int k = 0; k < 2; ++k) dst[n][k] = *(const PG8_LAS bf16x8*)(lds + PG8_SB(b, h) + boff + n * 2048 + k * 1024); } while (0)
; #define PG8_MMA(ai, bj, At, Bt) do { __builtin_amdgcn_s_setprio(1); _Pragma("unroll") for (int m = 0; m < 4; ++m) _Pragma("unroll") for (int n = 0; n < 2; ++n) _Pragma("unroll") for (int k = 0; k < 2; ++k) \
;         acc[ai][bj][m][n] = __builtin_amdgcn_mfma_f32_16x16x32_bf16(Bt[n][k], At[m][k], acc[ai][bj][m][n], 0, 0, 0); __builtin_amdgcn_s_setprio(0); } while (0)
; #define PG8_WAIT_V(n) asm volatile("s_waitcnt vmcnt(" #n ")" ::: "memory")
; #define PG8_WAIT_L(n) asm volatile("s_waitcnt lgkmcnt(" #n ")" ::: "memory")
; #define PG8_BAR __builtin_amdgcn_s_barrier()
; #define PG8_SCHED __builtin_amdgcn_sched_barrier(0)
; template <class Epi, class Sched, bool ALIGN_EPI = false, bool SP2 = false>
; __device__ __forceinline__ void gemm_phase(PG8_LAS unsigned char* lds, const Gemm g, const Sched& S, const Epi& E) {
;     ...
;             PG8_LDB(B0, 1, 0); PG8_LDB(B1, 1, 1); PG8_SCHED; PG8_LDA(At, 1, 0); PG8_STAGE(PG8_SA(0, 1), a2 + hstep, voffA);
;             PG8_WAIT_V(8); PG8_WAIT_L(0); PG8_BAR; PG8_MMA(0, 0, At, B0); PG8_MMA(0, 1, At, B1); PG8_BAR; PG8_SCHED;
	s_add_i32 s3, 0, 0x18000
	v_add_u32_e32 v159, s3, v153
	s_add_i32 s33, 0, 0x1c000
	ds_read_b128 v[144:147], v159
	ds_read_b128 v[148:151], v159 offset:1024
	ds_read_b128 v[160:163], v159 offset:2048
	ds_read_b128 v[168:171], v159 offset:3072
	v_add_u32_e32 v159, s33, v153
	ds_read_b128 v[172:175], v159
	ds_read_b128 v[176:179], v159 offset:1024
	ds_read_b128 v[182:185], v159 offset:2048
	ds_read_b128 v[186:189], v159 offset:3072
	s_add_u32 s14, s54, 0x40000
	s_addc_u32 s15, s55, 0
	s_mov_b32 m0, s58
	v_lshl_add_u64 v[232:233], s[14:15], 0, v[134:135]
	ds_read_b128 v[190:193], v157 offset:32768
	ds_read_b128 v[194:197], v157 offset:33792
	ds_read_b128 v[198:201], v157 offset:34816
	ds_read_b128 v[208:211], v157 offset:35840
	ds_read_b128 v[212:215], v157 offset:36864
	ds_read_b128 v[216:219], v157 offset:37888
	ds_read_b128 v[220:223], v157 offset:38912
	ds_read_b128 v[224:227], v157 offset:39936
	global_load_lds_dwordx4 v[232:233], off
	v_lshl_add_u64 v[232:233], s[14:15], 0, v[130:131]
	s_mov_b32 m0, s59
	s_nop 0
	global_load_lds_dwordx4 v[232:233], off
	s_waitcnt vmcnt(8)
	s_waitcnt lgkmcnt(0)
	s_barrier
	s_setprio 1
	s_waitcnt lgkmcnt(0)
	v_mfma_f32_16x16x32_bf16 v[124:127], v[144:147], v[190:193], v[124:127]
	v_mfma_f32_16x16x32_bf16 v[104:107], v[160:163], v[198:201], v[104:107]
	v_mfma_f32_16x16x32_bf16 v[92:95], v[144:147], v[212:215], v[92:95]
	v_mfma_f32_16x16x32_bf16 v[72:75], v[160:163], v[220:223], v[72:75]
	v_mfma_f32_16x16x32_bf16 v[108:111], v[144:147], v[198:201], v[108:111]
	v_mfma_f32_16x16x32_bf16 v[120:123], v[160:163], v[190:193], v[120:123]
	v_mfma_f32_16x16x32_bf16 v[76:79], v[144:147], v[220:223], v[76:79]
	v_mfma_f32_16x16x32_bf16 v[88:91], v[160:163], v[212:215], v[88:91]
	v_mfma_f32_16x16x32_bf16 v[124:127], v[148:151], v[194:197], v[124:127]
	v_mfma_f32_16x16x32_bf16 v[104:107], v[168:171], v[208:211], v[104:107]
	v_mfma_f32_16x16x32_bf16 v[92:95], v[148:151], v[216:219], v[92:95]
	v_mfma_f32_16x16x32_bf16 v[72:75], v[168:171], v[224:227], v[72:75]
	v_mfma_f32_16x16x32_bf16 v[108:111], v[148:151], v[208:211], v[108:111]
	v_mfma_f32_16x16x32_bf16 v[120:123], v[168:171], v[194:197], v[120:123]
	v_mfma_f32_16x16x32_bf16 v[76:79], v[148:151], v[224:227], v[76:79]
	v_mfma_f32_16x16x32_bf16 v[88:91], v[168:171], v[216:219], v[88:91]
	s_setprio 0
	s_setprio 1
	v_mfma_f32_16x16x32_bf16 v[116:119], v[172:175], v[190:193], v[116:119]
	v_mfma_f32_16x16x32_bf16 v[96:99], v[182:185], v[198:201], v[96:99]
	v_mfma_f32_16x16x32_bf16 v[84:87], v[172:175], v[212:215], v[84:87]
	v_mfma_f32_16x16x32_bf16 v[64:67], v[182:185], v[220:223], v[64:67]
	v_mfma_f32_16x16x32_bf16 v[100:103], v[172:175], v[198:201], v[100:103]
	v_mfma_f32_16x16x32_bf16 v[112:115], v[182:185], v[190:193], v[112:115]
	v_mfma_f32_16x16x32_bf16 v[68:71], v[172:175], v[220:223], v[68:71]
	v_mfma_f32_16x16x32_bf16 v[80:83], v[182:185], v[212:215], v[80:83]
	v_mfma_f32_16x16x32_bf16 v[116:119], v[176:179], v[194:197], v[116:119]
	v_mfma_f32_16x16x32_bf16 v[96:99], v[186:189], v[208:211], v[96:99]
	v_mfma_f32_16x16x32_bf16 v[84:87], v[176:179], v[216:219], v[84:87]
	v_mfma_f32_16x16x32_bf16 v[64:67], v[186:189], v[224:227], v[64:67]
	v_mfma_f32_16x16x32_bf16 v[100:103], v[176:179], v[208:211], v[100:103]
	v_mfma_f32_16x16x32_bf16 v[112:115], v[186:189], v[194:197], v[112:115]
	v_mfma_f32_16x16x32_bf16 v[68:71], v[176:179], v[224:227], v[68:71]
	v_mfma_f32_16x16x32_bf16 v[80:83], v[186:189], v[216:219], v[80:83]
	s_setprio 0
	s_barrier
; #define PG8_STAGE(bufoff, gbase, voff) do { _Pragma("unroll") for (int _i = 0; _i < 2; ++_i) \
;         __builtin_amdgcn_global_load_lds((const unsigned*)((const char*)(gbase) + (voff)[_i]), (PG8_LAS unsigned*)(lds + (bufoff) + ldsw + _i * 8192), 16, 0, 0); } while (0)
; #define PG8_LDA(dst, b, h) do { _Pragma("unroll") for (int m = 0; m < 4; ++m) _Pragma("unroll") for (int k = 0; k < 2; ++k) dst[m][k] = *(const PG8_LAS bf16x8*)(lds + PG8_SA(b, h) + aoff + m * 2048 + k * 1024); } while (0)
; #define PG8_MMA(ai, bj, At, Bt) do { __builtin_amdgcn_s_setprio(1); _Pragma("unroll") for (int m = 0; m < 4; ++m) _Pragma("unroll") for (int n = 0; n < 2; ++n) _Pragma("unroll") for (int k = 0; k < 2; ++k) \
;         acc[ai][bj][m][n] = __builtin_amdgcn_mfma_f32_16x16x32_bf16(Bt[n][k], At[m][k], acc[ai][bj][m][n], 0, 0, 0); __builtin_amdgcn_s_setprio(0); } while (0)
; #define PG8_WAIT_V(n) asm volatile("s_waitcnt vmcnt(" #n ")" ::: "memory")
; #define PG8_WAIT_L(n) asm volatile("s_waitcnt lgkmcnt(" #n ")" ::: "memory")
; #define PG8_BAR __builtin_amdgcn_s_barrier()
; #define PG8_SCHED __builtin_amdgcn_sched_barrier(0)
; __device__ __forceinline__ float row_rs(const float* ssp, int row) { const unsigned long long v = ((const unsigned long long*)ssp)[row];
;     return __builtin_amdgcn_rsqf((float)v * (1.0f / 4294967296.0f) * (1.0f / 1024.0f) + RMS_EPS); }
; template <class Epi, class Sched, bool ALIGN_EPI = false, bool SP2 = false>
; __device__ __forceinline__ void gemm_phase(PG8_LAS unsigned char* lds, const Gemm g, const Sched& S, const Epi& E) {
;     ...
;             PG8_LDA(At, 1, 1); PG8_STAGE(PG8_SB(1, 0), b3, voffB); PG8_STAGE(PG8_SB(1, 1), b3 + hstep, voffB); PG8_STAGE(PG8_SA(1, 0), a3, voffA);
;             PG8_WAIT_V(8); PG8_WAIT_L(0); PG8_BAR; PG8_MMA(1, 0, At, B0); PG8_MMA(1, 1, At, B1); PG8_BAR; PG8_SCHED;
	s_add_i32 s3, s3, s43
	v_lshl_add_u64 v[164:165], v[164:165], 0, s[10:11]
	s_mov_b32 m0, s3
	ds_read_b128 v[190:193], v157 offset:49152
	ds_read_b128 v[194:197], v157 offset:50176
	ds_read_b128 v[198:201], v157 offset:51200
	ds_read_b128 v[208:211], v157 offset:52224
	ds_read_b128 v[212:215], v157 offset:53248
	ds_read_b128 v[216:219], v157 offset:54272
	ds_read_b128 v[220:223], v157 offset:55296
	ds_read_b128 v[224:227], v157 offset:56320
	global_load_lds_dwordx4 v[164:165], off
	s_add_i32 m0, s3, 0x2000
	s_add_u32 s14, s50, 0x40080
	v_lshl_add_u64 v[164:165], v[202:203], 0, s[10:11]
	s_addc_u32 s15, s51, 0
	s_add_i32 s3, s33, s43
	global_load_lds_dwordx4 v[164:165], off
	v_lshl_add_u64 v[164:165], s[14:15], 0, v[132:133]
	s_mov_b32 m0, s3
	s_nop 0
	global_load_lds_dwordx4 v[164:165], off
	v_lshl_add_u64 v[164:165], s[14:15], 0, v[128:129]
	s_add_i32 m0, s3, 0x2000
	s_nop 0
	global_load_lds_dwordx4 v[164:165], off
	s_waitcnt vmcnt(6)
	s_waitcnt lgkmcnt(0)
	s_barrier
	s_setprio 1
	s_waitcnt lgkmcnt(0)
	v_mfma_f32_16x16x32_bf16 v[60:63], v[144:147], v[190:193], v[60:63]
	v_mfma_f32_16x16x32_bf16 v[40:43], v[160:163], v[198:201], v[40:43]
	v_mfma_f32_16x16x32_bf16 v[28:31], v[144:147], v[212:215], v[28:31]
	v_mfma_f32_16x16x32_bf16 v[8:11], v[160:163], v[220:223], v[8:11]
	v_mfma_f32_16x16x32_bf16 v[44:47], v[144:147], v[198:201], v[44:47]
	v_mfma_f32_16x16x32_bf16 v[56:59], v[160:163], v[190:193], v[56:59]
	v_mfma_f32_16x16x32_bf16 v[12:15], v[144:147], v[220:223], v[12:15]
	v_mfma_f32_16x16x32_bf16 v[24:27], v[160:163], v[212:215], v[24:27]
	v_mfma_f32_16x16x32_bf16 v[60:63], v[148:151], v[194:197], v[60:63]
	v_mfma_f32_16x16x32_bf16 v[40:43], v[168:171], v[208:211], v[40:43]
	v_mfma_f32_16x16x32_bf16 v[28:31], v[148:151], v[216:219], v[28:31]
	v_mfma_f32_16x16x32_bf16 v[8:11], v[168:171], v[224:227], v[8:11]
	v_mfma_f32_16x16x32_bf16 v[44:47], v[148:151], v[208:211], v[44:47]
	v_mfma_f32_16x16x32_bf16 v[56:59], v[168:171], v[194:197], v[56:59]
	v_lshl_add_u64 v[164:165], v[228:229], 0, s[10:11]
	s_mov_b32 m0, s61
	s_nop 0
	global_load_lds_dwordx4 v[164:165], off
	v_mfma_f32_16x16x32_bf16 v[12:15], v[148:151], v[224:227], v[12:15]
	v_mfma_f32_16x16x32_bf16 v[24:27], v[168:171], v[216:219], v[24:27]
	s_setprio 0
	s_setprio 1
	v_mfma_f32_16x16x32_bf16 v[52:55], v[172:175], v[190:193], v[52:55]
	v_mfma_f32_16x16x32_bf16 v[32:35], v[182:185], v[198:201], v[32:35]
	v_mfma_f32_16x16x32_bf16 v[20:23], v[172:175], v[212:215], v[20:23]
	v_mfma_f32_16x16x32_bf16 v[0:3], v[182:185], v[220:223], v[0:3]
	v_mfma_f32_16x16x32_bf16 v[36:39], v[172:175], v[198:201], v[36:39]
	v_mfma_f32_16x16x32_bf16 v[48:51], v[182:185], v[190:193], v[48:51]
	v_mfma_f32_16x16x32_bf16 v[4:7], v[172:175], v[220:223], v[4:7]
	v_mfma_f32_16x16x32_bf16 v[16:19], v[182:185], v[212:215], v[16:19]
	v_mfma_f32_16x16x32_bf16 v[52:55], v[176:179], v[194:197], v[52:55]
	v_mfma_f32_16x16x32_bf16 v[32:35], v[186:189], v[208:211], v[32:35]
	v_mfma_f32_16x16x32_bf16 v[20:23], v[176:179], v[216:219], v[20:23]
	v_mfma_f32_16x16x32_bf16 v[0:3], v[186:189], v[224:227], v[0:3]
	v_mfma_f32_16x16x32_bf16 v[36:39], v[176:179], v[208:211], v[36:39]
	v_mfma_f32_16x16x32_bf16 v[48:51], v[186:189], v[194:197], v[48:51]
	v_lshl_add_u64 v[164:165], v[230:231], 0, s[10:11]
	s_mov_b32 m0, s62
	s_nop 0
	global_load_lds_dwordx4 v[164:165], off
	v_mfma_f32_16x16x32_bf16 v[4:7], v[176:179], v[224:227], v[4:7]
	v_mfma_f32_16x16x32_bf16 v[16:19], v[186:189], v[216:219], v[16:19]
	s_setprio 0
	s_barrier
	s_add_i32 s89, s89, 2
	s_add_u32 s48, s48, 0x100
	s_addc_u32 s49, s49, 0
	s_add_u32 s87, s87, 0x100
	s_addc_u32 s88, s88, 0
	s_cmp_gt_u32 s89, 13
	s_cbranch_scc0 .LBB0_191
	v_lshl_add_u32 v144, s44, 8, v152
	v_ashrrev_i32_e32 v145, 31, v144
	v_lshl_add_u64 v[150:151], v[144:145], 3, s[6:7]
	global_load_dwordx2 v[182:183], v[150:151], off
	global_load_dwordx2 v[184:185], v[150:151], off offset:128
	global_load_dwordx2 v[186:187], v[150:151], off offset:256
	global_load_dwordx2 v[188:189], v[150:151], off offset:384
	global_load_dwordx2 v[190:191], v[150:151], off offset:1024
	global_load_dwordx2 v[192:193], v[150:151], off offset:1152
	global_load_dwordx2 v[194:195], v[150:151], off offset:1280
	global_load_dwordx2 v[196:197], v[150:151], off offset:1408
	s_and_b64 vcc, exec, s[16:17]
	s_cbranch_vccz .LBB0_194
	s_barrier

; #define PG8_STAGE(bufoff, gbase, voff) do { _Pragma("unroll") for (int _i = 0; _i < 2; ++_i) \
;         __builtin_amdgcn_global_load_lds((const unsigned*)((const char*)(gbase) + (voff)[_i]), (PG8_LAS unsigned*)(lds + (bufoff) + ldsw + _i * 8192), 16, 0, 0); } while (0)
; #define PG8_LDA(dst, b, h) do { _Pragma("unroll") for (int m = 0; m < 4; ++m) _Pragma("unroll") for (int k = 0; k < 2; ++k) dst[m][k] = *(const PG8_LAS bf16x8*)(lds + PG8_SA(b, h) + aoff + m * 2048 + k * 1024); } while (0)
; #define PG8_LDB(dst, b, h) do { _Pragma("unroll") for (int n = 0; n < 2; ++n) _Pragma("unroll") for (int k = 0; k < 2; ++k) dst[n][k] = *(const PG8_LAS bf16x8*)(lds + PG8_SB(b, h) + boff + n * 2048 + k * 1024); } while (0)
; #define PG8_MMA(ai, bj, At, Bt) do { __builtin_amdgcn_s_setprio(1); _Pragma("unroll") for (int m = 0; m < 4; ++m) _Pragma("unroll") for (int n = 0; n < 2; ++n) _Pragma("unroll") for (int k = 0; k < 2; ++k) \
;         acc[ai][bj][m][n] = __builtin_amdgcn_mfma_f32_16x16x32_bf16(Bt[n][k], At[m][k], acc[ai][bj][m][n], 0, 0, 0); __builtin_amdgcn_s_setprio(0); } while (0)
; #define PG8_WAIT_V(n) asm volatile("s_waitcnt vmcnt(" #n ")" ::: "memory")
; #define PG8_WAIT_L(n) asm volatile("s_waitcnt lgkmcnt(" #n ")" ::: "memory")
; #define PG8_BAR __builtin_amdgcn_s_barrier()
; #define PG8_SCHED __builtin_amdgcn_sched_barrier(0)
; template <class Epi, class Sched, bool ALIGN_EPI = false, bool SP2 = false>
; __device__ __forceinline__ void gemm_phase(PG8_LAS unsigned char* lds, const Gemm g, const Sched& S, const Epi& E) {
;     ...
;         for (int t = 0; t < nt; t += 2) {
;             const bool last = (t == nt - 2);
;             const char* a1 = cA + (size_t)(t + 1) * kstep;
;             const char* a2 = last ? nA : cA + (size_t)(t + 2) * kstep; const char* b2 = last ? nB : cB + (size_t)(t + 2) * kstep;
;             const char* a3 = a2 + kstep; const char* b3 = b2 + kstep;
;             if (last && has_next) S.a_ready(nxt);
;             if constexpr (SP2) {
;             PG8_LDB(B0, 0, 0); PG8_LDB(B1, 0, 1); PG8_SCHED; PG8_LDA(At, 0, 0); PG8_STAGE(PG8_SA(1, 1), a1 + hstep, voffA);
;             PG8_WAIT_V(8); PG8_WAIT_L(0); PG8_BAR; PG8_MMA(0, 0, At, B0); PG8_MMA(0, 1, At, B1); PG8_BAR; PG8_SCHED;
;             PG8_LDA(At, 0, 1); PG8_STAGE(PG8_SB(0, 0), b2, voffB); PG8_STAGE(PG8_SB(0, 1), b2 + hstep, voffB); PG8_STAGE(PG8_SA(0, 0), a2, voffA);
.LBB0_268:
	s_add_u32 s91, s50, 0x100
	s_addc_u32 s92, s51, 0
	s_mov_b32 s93, -2
	s_waitcnt lgkmcnt(0)
	ds_read_b128 v[128:131], v165
	ds_read_b128 v[132:135], v165 offset:1024
	ds_read_b128 v[152:155], v165 offset:2048
	ds_read_b128 v[156:159], v165 offset:3072
	ds_read_b128 v[172:175], v168
	ds_read_b128 v[176:179], v168 offset:1024
	ds_read_b128 v[182:185], v168 offset:2048
	ds_read_b128 v[186:189], v168 offset:3072
	s_add_u32 s50, s10, 0x100
	s_addc_u32 s51, s11, 0
	s_cmp_eq_u32 s93, 40
	s_cselect_b32 s57, s1, s51
	s_cselect_b32 s56, s0, s50
	s_cselect_b32 s55, s49, s92
	s_cselect_b32 s54, s48, s91
	v_lshl_add_u64 v[160:161], s[10:11], 0, v[144:145]
	s_add_i32 m0, s58, 0xc000
	ds_read_b128 v[190:193], v169
	ds_read_b128 v[194:197], v169 offset:1024
	ds_read_b128 v[198:201], v169 offset:2048
	ds_read_b128 v[208:211], v169 offset:3072
	ds_read_b128 v[212:215], v169 offset:4096
	ds_read_b128 v[216:219], v169 offset:5120
	ds_read_b128 v[220:223], v169 offset:6144
	ds_read_b128 v[224:227], v169 offset:7168
	global_load_lds_dwordx4 v[160:161], off
	v_lshl_add_u64 v[160:161], s[10:11], 0, v[146:147]
	s_add_i32 m0, s58, 0xe000
	s_nop 0
	global_load_lds_dwordx4 v[160:161], off
	s_waitcnt vmcnt(8)
	s_waitcnt lgkmcnt(0)
	s_barrier
	s_setprio 1
	s_waitcnt lgkmcnt(0)
	v_mfma_f32_16x16x32_bf16 v[124:127], v[128:131], v[190:193], 0
	v_mfma_f32_16x16x32_bf16 v[104:107], v[152:155], v[198:201], 0
	v_mfma_f32_16x16x32_bf16 v[92:95], v[128:131], v[212:215], 0
	v_mfma_f32_16x16x32_bf16 v[72:75], v[152:155], v[220:223], 0
	v_mfma_f32_16x16x32_bf16 v[108:111], v[128:131], v[198:201], 0
	v_mfma_f32_16x16x32_bf16 v[120:123], v[152:155], v[190:193], 0
	v_mfma_f32_16x16x32_bf16 v[76:79], v[128:131], v[220:223], 0
	v_mfma_f32_16x16x32_bf16 v[88:91], v[152:155], v[212:215], 0
	v_mfma_f32_16x16x32_bf16 v[124:127], v[132:135], v[194:197], v[124:127]
	v_mfma_f32_16x16x32_bf16 v[104:107], v[156:159], v[208:211], v[104:107]
	v_mfma_f32_16x16x32_bf16 v[92:95], v[132:135], v[216:219], v[92:95]
	v_mfma_f32_16x16x32_bf16 v[72:75], v[156:159], v[224:227], v[72:75]
	v_mfma_f32_16x16x32_bf16 v[108:111], v[132:135], v[208:211], v[108:111]
	v_mfma_f32_16x16x32_bf16 v[120:123], v[156:159], v[194:197], v[120:123]
	v_mfma_f32_16x16x32_bf16 v[76:79], v[132:135], v[224:227], v[76:79]
	v_mfma_f32_16x16x32_bf16 v[88:91], v[156:159], v[216:219], v[88:91]
	s_setprio 0
	s_setprio 1
	v_mfma_f32_16x16x32_bf16 v[116:119], v[172:175], v[190:193], 0
	v_mfma_f32_16x16x32_bf16 v[96:99], v[182:185], v[198:201], 0
	v_mfma_f32_16x16x32_bf16 v[84:87], v[172:175], v[212:215], 0
	v_mfma_f32_16x16x32_bf16 v[64:67], v[182:185], v[220:223], 0
	v_mfma_f32_16x16x32_bf16 v[100:103], v[172:175], v[198:201], 0
	v_mfma_f32_16x16x32_bf16 v[112:115], v[182:185], v[190:193], 0
	v_mfma_f32_16x16x32_bf16 v[68:71], v[172:175], v[220:223], 0
	v_mfma_f32_16x16x32_bf16 v[80:83], v[182:185], v[212:215], 0
	v_mfma_f32_16x16x32_bf16 v[116:119], v[176:179], v[194:197], v[116:119]
	v_mfma_f32_16x16x32_bf16 v[96:99], v[186:189], v[208:211], v[96:99]
	v_mfma_f32_16x16x32_bf16 v[84:87], v[176:179], v[216:219], v[84:87]
	v_mfma_f32_16x16x32_bf16 v[64:67], v[186:189], v[224:227], v[64:67]
	v_mfma_f32_16x16x32_bf16 v[100:103], v[176:179], v[208:211], v[100:103]
	v_mfma_f32_16x16x32_bf16 v[112:115], v[186:189], v[194:197], v[112:115]
	v_mfma_f32_16x16x32_bf16 v[68:71], v[176:179], v[224:227], v[68:71]
	v_mfma_f32_16x16x32_bf16 v[80:83], v[186:189], v[216:219], v[80:83]
	s_setprio 0
	s_barrier
	s_add_i32 s3, s65, s43
	v_lshl_add_u64 v[160:161], s[54:55], 0, v[138:139]
	s_mov_b32 m0, s3
	ds_read_b128 v[190:193], v169 offset:16384
	ds_read_b128 v[194:197], v169 offset:17408
	ds_read_b128 v[198:201], v169 offset:18432
	ds_read_b128 v[208:211], v169 offset:19456
	ds_read_b128 v[212:215], v169 offset:20480
	ds_read_b128 v[216:219], v169 offset:21504
	ds_read_b128 v[220:223], v169 offset:22528
	ds_read_b128 v[224:227], v169 offset:23552
	global_load_lds_dwordx4 v[160:161], off
	s_add_i32 m0, s3, 0x2000
	s_add_u32 s10, s54, 0xb0000
	v_lshl_add_u64 v[202:203], s[54:55], 0, v[142:143]
	s_addc_u32 s11, s55, 0
	s_add_i32 s3, s66, s43
	global_load_lds_dwordx4 v[202:203], off
	v_lshl_add_u64 v[228:229], s[10:11], 0, v[138:139]
	s_mov_b32 m0, s3
	global_load_lds_dwordx4 v[228:229], off
	v_lshl_add_u64 v[228:229], s[10:11], 0, v[142:143]
	s_add_i32 m0, s3, 0x2000
	s_nop 0
	global_load_lds_dwordx4 v[228:229], off
	s_waitcnt vmcnt(6)
	s_waitcnt lgkmcnt(0)
	s_barrier
; #define PG8_STAGE(bufoff, gbase, voff) do { _Pragma("unroll") for (int _i = 0; _i < 2; ++_i) \
;         __builtin_amdgcn_global_load_lds((const unsigned*)((const char*)(gbase) + (voff)[_i]), (PG8_LAS unsigned*)(lds + (bufoff) + ldsw + _i * 8192), 16, 0, 0); } while (0)
; #define PG8_LDA(dst, b, h) do { _Pragma("unroll") for (int m = 0; m < 4; ++m) _Pragma("unroll") for (int k = 0; k < 2; ++k) dst[m][k] = *(const PG8_LAS bf16x8*)(lds + PG8_SA(b, h) + aoff + m * 2048 + k * 1024); } while (0)
; #define PG8_LDB(dst, b, h) do { _Pragma("unroll") for (int n = 0; n < 2; ++n) _Pragma("unroll") for (int k = 0; k < 2; ++k) dst[n][k] = *(const PG8_LAS bf16x8*)(lds + PG8_SB(b, h) + boff + n * 2048 + k * 1024); } while (0)
; #define PG8_MMA(ai, bj, At, Bt) do { __builtin_amdgcn_s_setprio(1); _Pragma("unroll") for (int m = 0; m < 4; ++m) _Pragma("unroll") for (int n = 0; n < 2; ++n) _Pragma("unroll") for (int k = 0; k < 2; ++k) \
;         acc[ai][bj][m][n] = __builtin_amdgcn_mfma_f32_16x16x32_bf16(Bt[n][k], At[m][k], acc[ai][bj][m][n], 0, 0, 0); __builtin_amdgcn_s_setprio(0); } while (0)
; #define PG8_WAIT_V(n) asm volatile("s_waitcnt vmcnt(" #n ")" ::: "memory")
; #define PG8_WAIT_L(n) asm volatile("s_waitcnt lgkmcnt(" #n ")" ::: "memory")
; #define PG8_BAR __builtin_amdgcn_s_barrier()
; #define PG8_SCHED __builtin_amdgcn_sched_barrier(0)
; template <class Epi, class Sched, bool ALIGN_EPI = false, bool SP2 = false>
; __device__ __forceinline__ void gemm_phase(PG8_LAS unsigned char* lds, const Gemm g, const Sched& S, const Epi& E) {
;     ...
;             PG8_WAIT_V(8); PG8_WAIT_L(0); PG8_BAR; PG8_MMA(0, 0, At, B0); PG8_MMA(0, 1, At, B1); PG8_BAR; PG8_SCHED;
;             PG8_LDA(At, 0, 1); PG8_STAGE(PG8_SB(0, 0), b2, voffB); PG8_STAGE(PG8_SB(0, 1), b2 + hstep, voffB); PG8_STAGE(PG8_SA(0, 0), a2, voffA);
;             PG8_WAIT_V(8); PG8_WAIT_L(0); PG8_BAR; PG8_MMA(1, 0, At, B0); PG8_MMA(1, 1, At, B1); PG8_BAR; PG8_SCHED;
;             PG8_LDB(B0, 1, 0); PG8_LDB(B1, 1, 1); PG8_SCHED; PG8_LDA(At, 1, 0); PG8_STAGE(PG8_SA(0, 1), a2 + hstep, voffA);
;             PG8_WAIT_V(8); PG8_WAIT_L(0); PG8_BAR; PG8_MMA(0, 0, At, B0); PG8_MMA(0, 1, At, B1); PG8_BAR; PG8_SCHED;
	s_setprio 1
	s_waitcnt lgkmcnt(0)
	v_mfma_f32_16x16x32_bf16 v[60:63], v[128:131], v[190:193], 0
	v_mfma_f32_16x16x32_bf16 v[40:43], v[152:155], v[198:201], 0
	v_mfma_f32_16x16x32_bf16 v[28:31], v[128:131], v[212:215], 0
	v_mfma_f32_16x16x32_bf16 v[8:11], v[152:155], v[220:223], 0
	v_mfma_f32_16x16x32_bf16 v[44:47], v[128:131], v[198:201], 0
	v_mfma_f32_16x16x32_bf16 v[56:59], v[152:155], v[190:193], 0
	v_mfma_f32_16x16x32_bf16 v[12:15], v[128:131], v[220:223], 0
	v_mfma_f32_16x16x32_bf16 v[24:27], v[152:155], v[212:215], 0
	v_mfma_f32_16x16x32_bf16 v[60:63], v[132:135], v[194:197], v[60:63]
	v_mfma_f32_16x16x32_bf16 v[40:43], v[156:159], v[208:211], v[40:43]
	v_mfma_f32_16x16x32_bf16 v[28:31], v[132:135], v[216:219], v[28:31]
	v_mfma_f32_16x16x32_bf16 v[8:11], v[156:159], v[224:227], v[8:11]
	v_mfma_f32_16x16x32_bf16 v[44:47], v[132:135], v[208:211], v[44:47]
	v_mfma_f32_16x16x32_bf16 v[56:59], v[156:159], v[194:197], v[56:59]
	v_lshl_add_u64 v[228:229], s[56:57], 0, v[136:137]
	s_mov_b32 m0, s58
	s_nop 0
	global_load_lds_dwordx4 v[228:229], off
	v_mfma_f32_16x16x32_bf16 v[12:15], v[132:135], v[224:227], v[12:15]
	v_mfma_f32_16x16x32_bf16 v[24:27], v[156:159], v[216:219], v[24:27]
	s_setprio 0
	s_setprio 1
	v_mfma_f32_16x16x32_bf16 v[52:55], v[172:175], v[190:193], 0
	v_mfma_f32_16x16x32_bf16 v[32:35], v[182:185], v[198:201], 0
	v_mfma_f32_16x16x32_bf16 v[20:23], v[172:175], v[212:215], 0
	v_mfma_f32_16x16x32_bf16 v[0:3], v[182:185], v[220:223], 0
	v_mfma_f32_16x16x32_bf16 v[36:39], v[172:175], v[198:201], 0
	v_mfma_f32_16x16x32_bf16 v[48:51], v[182:185], v[190:193], 0
	v_mfma_f32_16x16x32_bf16 v[4:7], v[172:175], v[220:223], 0
	v_mfma_f32_16x16x32_bf16 v[16:19], v[182:185], v[212:215], 0
	v_mfma_f32_16x16x32_bf16 v[52:55], v[176:179], v[194:197], v[52:55]
	v_mfma_f32_16x16x32_bf16 v[32:35], v[186:189], v[208:211], v[32:35]
	v_mfma_f32_16x16x32_bf16 v[20:23], v[176:179], v[216:219], v[20:23]
	v_mfma_f32_16x16x32_bf16 v[0:3], v[186:189], v[224:227], v[0:3]
	v_mfma_f32_16x16x32_bf16 v[36:39], v[176:179], v[208:211], v[36:39]
	v_mfma_f32_16x16x32_bf16 v[48:51], v[186:189], v[194:197], v[48:51]
	v_lshl_add_u64 v[230:231], s[56:57], 0, v[140:141]
	s_mov_b32 m0, s59
	s_nop 0
	global_load_lds_dwordx4 v[230:231], off
	v_mfma_f32_16x16x32_bf16 v[4:7], v[176:179], v[224:227], v[4:7]
	v_mfma_f32_16x16x32_bf16 v[16:19], v[186:189], v[216:219], v[16:19]
	s_setprio 0
	s_barrier
	s_add_i32 s3, 0, 0x18000
	s_add_i32 s14, 0, 0x1c000
	v_add_u32_e32 v156, s3, v163
	v_add_u32_e32 v171, s14, v163
	ds_read_b128 v[128:131], v156
	ds_read_b128 v[132:135], v156 offset:1024
	ds_read_b128 v[152:155], v156 offset:2048
	ds_read_b128 v[156:159], v156 offset:3072
	ds_read_b128 v[172:175], v171
	ds_read_b128 v[176:179], v171 offset:1024
	ds_read_b128 v[182:185], v171 offset:2048
	ds_read_b128 v[186:189], v171 offset:3072
	s_add_u32 s10, s56, 0xb0000
	s_addc_u32 s11, s57, 0
	s_mov_b32 m0, s60
	v_lshl_add_u64 v[232:233], s[10:11], 0, v[136:137]
	ds_read_b128 v[190:193], v169 offset:32768
	ds_read_b128 v[194:197], v169 offset:33792
	ds_read_b128 v[198:201], v169 offset:34816
	ds_read_b128 v[208:211], v169 offset:35840
	ds_read_b128 v[212:215], v169 offset:36864
	ds_read_b128 v[216:219], v169 offset:37888
	ds_read_b128 v[220:223], v169 offset:38912
	ds_read_b128 v[224:227], v169 offset:39936
	global_load_lds_dwordx4 v[232:233], off
	v_lshl_add_u64 v[232:233], s[10:11], 0, v[140:141]
	s_mov_b32 m0, s61
	s_nop 0
	global_load_lds_dwordx4 v[232:233], off
	s_waitcnt vmcnt(8)
	s_waitcnt lgkmcnt(0)
	s_barrier
	s_setprio 1
	s_waitcnt lgkmcnt(0)
	v_mfma_f32_16x16x32_bf16 v[124:127], v[128:131], v[190:193], v[124:127]
	v_mfma_f32_16x16x32_bf16 v[104:107], v[152:155], v[198:201], v[104:107]
	v_mfma_f32_16x16x32_bf16 v[92:95], v[128:131], v[212:215], v[92:95]
	v_mfma_f32_16x16x32_bf16 v[72:75], v[152:155], v[220:223], v[72:75]
	v_mfma_f32_16x16x32_bf16 v[108:111], v[128:131], v[198:201], v[108:111]
	v_mfma_f32_16x16x32_bf16 v[120:123], v[152:155], v[190:193], v[120:123]
	v_mfma_f32_16x16x32_bf16 v[76:79], v[128:131], v[220:223], v[76:79]
	v_mfma_f32_16x16x32_bf16 v[88:91], v[152:155], v[212:215], v[88:91]
	v_mfma_f32_16x16x32_bf16 v[124:127], v[132:135], v[194:197], v[124:127]
	v_mfma_f32_16x16x32_bf16 v[104:107], v[156:159], v[208:211], v[104:107]
	v_mfma_f32_16x16x32_bf16 v[92:95], v[132:135], v[216:219], v[92:95]
	v_mfma_f32_16x16x32_bf16 v[72:75], v[156:159], v[224:227], v[72:75]
	v_mfma_f32_16x16x32_bf16 v[108:111], v[132:135], v[208:211], v[108:111]
	v_mfma_f32_16x16x32_bf16 v[120:123], v[156:159], v[194:197], v[120:123]
	v_mfma_f32_16x16x32_bf16 v[76:79], v[132:135], v[224:227], v[76:79]
	v_mfma_f32_16x16x32_bf16 v[88:91], v[156:159], v[216:219], v[88:91]
	s_setprio 0
	s_setprio 1
	v_mfma_f32_16x16x32_bf16 v[116:119], v[172:175], v[190:193], v[116:119]
	v_mfma_f32_16x16x32_bf16 v[96:99], v[182:185], v[198:201], v[96:99]
	v_mfma_f32_16x16x32_bf16 v[84:87], v[172:175], v[212:215], v[84:87]
	v_mfma_f32_16x16x32_bf16 v[64:67], v[182:185], v[220:223], v[64:67]
	v_mfma_f32_16x16x32_bf16 v[100:103], v[172:175], v[198:201], v[100:103]
	v_mfma_f32_16x16x32_bf16 v[112:115], v[182:185], v[190:193], v[112:115]
	v_mfma_f32_16x16x32_bf16 v[68:71], v[172:175], v[220:223], v[68:71]
	v_mfma_f32_16x16x32_bf16 v[80:83], v[182:185], v[212:215], v[80:83]
	v_mfma_f32_16x16x32_bf16 v[116:119], v[176:179], v[194:197], v[116:119]
	v_mfma_f32_16x16x32_bf16 v[96:99], v[186:189], v[208:211], v[96:99]
	v_mfma_f32_16x16x32_bf16 v[84:87], v[176:179], v[216:219], v[84:87]
	v_mfma_f32_16x16x32_bf16 v[64:67], v[186:189], v[224:227], v[64:67]
	v_mfma_f32_16x16x32_bf16 v[100:103], v[176:179], v[208:211], v[100:103]
	v_mfma_f32_16x16x32_bf16 v[112:115], v[186:189], v[194:197], v[112:115]
	v_mfma_f32_16x16x32_bf16 v[68:71], v[176:179], v[224:227], v[68:71]
	v_mfma_f32_16x16x32_bf16 v[80:83], v[186:189], v[216:219], v[80:83]
	s_setprio 0
	s_barrier
; #define PG8_STAGE(bufoff, gbase, voff) do { _Pragma("unroll") for (int _i = 0; _i < 2; ++_i) \
;         __builtin_amdgcn_global_load_lds((const unsigned*)((const char*)(gbase) + (voff)[_i]), (PG8_LAS unsigned*)(lds + (bufoff) + ldsw + _i * 8192), 16, 0, 0); } while (0)
; #define PG8_LDA(dst, b, h) do { _Pragma("unroll") for (int m = 0; m < 4; ++m) _Pragma("unroll") for (int k = 0; k < 2; ++k) dst[m][k] = *(const PG8_LAS bf16x8*)(lds + PG8_SA(b, h) + aoff + m * 2048 + k * 1024); } while (0)
; #define PG8_LDB(dst, b, h) do { _Pragma("unroll") for (int n = 0; n < 2; ++n) _Pragma("unroll") for (int k = 0; k < 2; ++k) dst[n][k] = *(const PG8_LAS bf16x8*)(lds + PG8_SB(b, h) + boff + n * 2048 + k * 1024); } while (0)
; #define PG8_MMA(ai, bj, At, Bt) do { __builtin_amdgcn_s_setprio(1); _Pragma("unroll") for (int m = 0; m < 4; ++m) _Pragma("unroll") for (int n = 0; n < 2; ++n) _Pragma("unroll") for (int k = 0; k < 2; ++k) \
;         acc[ai][bj][m][n] = __builtin_amdgcn_mfma_f32_16x16x32_bf16(Bt[n][k], At[m][k], acc[ai][bj][m][n], 0, 0, 0); __builtin_amdgcn_s_setprio(0); } while (0)
; #define PG8_WAIT_V(n) asm volatile("s_waitcnt vmcnt(" #n ")" ::: "memory")
; template <class Epi, class Sched, bool ALIGN_EPI = false, bool SP2 = false>
; __device__ __forceinline__ void gemm_phase(PG8_LAS unsigned char* lds, const Gemm g, const Sched& S, const Epi& E) {
;     ...
;             PG8_LDB(B0, 0, 0); PG8_LDB(B1, 0, 1); PG8_SCHED; PG8_LDA(At, 0, 0); PG8_STAGE(PG8_SA(1, 1), a1 + hstep, voffA);
;             PG8_WAIT_V(8); PG8_WAIT_L(0); PG8_BAR; PG8_MMA(0, 0, At, B0); PG8_MMA(0, 1, At, B1); PG8_BAR; PG8_SCHED;
;             PG8_LDA(At, 0, 1); PG8_STAGE(PG8_SB(0, 0), b2, voffB); PG8_STAGE(PG8_SB(0, 1), b2 + hstep, voffB); PG8_STAGE(PG8_SA(0, 0), a2, voffA);
;             PG8_WAIT_V(8); PG8_WAIT_L(0); PG8_BAR; PG8_MMA(1, 0, At, B0); PG8_MMA(1, 1, At, B1); PG8_BAR; PG8_SCHED;
;             PG8_LDB(B0, 1, 0); PG8_LDB(B1, 1, 1); PG8_SCHED; PG8_LDA(At, 1, 0); PG8_STAGE(PG8_SA(0, 1), a2 + hstep, voffA);
;             PG8_WAIT_V(8); PG8_WAIT_L(0); PG8_BAR; PG8_MMA(0, 0, At, B0); PG8_MMA(0, 1, At, B1); PG8_BAR; PG8_SCHED;
;             PG8_LDA(At, 1, 1); PG8_STAGE(PG8_SB(1, 0), b3, voffB); PG8_STAGE(PG8_SB(1, 1), b3 + hstep, voffB); PG8_STAGE(PG8_SA(1, 0), a3, voffA);
;             PG8_WAIT_V(8); PG8_WAIT_L(0); PG8_BAR; PG8_MMA(1, 0, At, B0); PG8_MMA(1, 1, At, B1); PG8_BAR; PG8_SCHED;
	s_add_i32 s3, s3, s43
	v_lshl_add_u64 v[160:161], v[160:161], 0, s[40:41]
	s_mov_b32 m0, s3
	ds_read_b128 v[190:193], v169 offset:49152
	ds_read_b128 v[194:197], v169 offset:50176
	ds_read_b128 v[198:201], v169 offset:51200
	ds_read_b128 v[208:211], v169 offset:52224
	ds_read_b128 v[212:215], v169 offset:53248
	ds_read_b128 v[216:219], v169 offset:54272
	ds_read_b128 v[220:223], v169 offset:55296
	ds_read_b128 v[224:227], v169 offset:56320
	global_load_lds_dwordx4 v[160:161], off
	s_add_i32 m0, s3, 0x2000
	s_add_u32 s10, s54, 0xb0080
	v_lshl_add_u64 v[160:161], v[202:203], 0, s[40:41]
	s_addc_u32 s11, s55, 0
	s_add_i32 s3, s14, s43
	global_load_lds_dwordx4 v[160:161], off
	v_lshl_add_u64 v[160:161], s[10:11], 0, v[138:139]
	s_mov_b32 m0, s3
	s_nop 0
	global_load_lds_dwordx4 v[160:161], off
	v_lshl_add_u64 v[160:161], s[10:11], 0, v[142:143]
	s_add_i32 m0, s3, 0x2000
	s_nop 0
	global_load_lds_dwordx4 v[160:161], off
	s_waitcnt vmcnt(6)
	s_waitcnt lgkmcnt(0)
	s_barrier
	s_setprio 1
	s_waitcnt lgkmcnt(0)
	v_mfma_f32_16x16x32_bf16 v[60:63], v[128:131], v[190:193], v[60:63]
	v_mfma_f32_16x16x32_bf16 v[40:43], v[152:155], v[198:201], v[40:43]
	v_mfma_f32_16x16x32_bf16 v[28:31], v[128:131], v[212:215], v[28:31]
	v_mfma_f32_16x16x32_bf16 v[8:11], v[152:155], v[220:223], v[8:11]
	v_mfma_f32_16x16x32_bf16 v[44:47], v[128:131], v[198:201], v[44:47]
	v_mfma_f32_16x16x32_bf16 v[56:59], v[152:155], v[190:193], v[56:59]
	v_mfma_f32_16x16x32_bf16 v[12:15], v[128:131], v[220:223], v[12:15]
	v_mfma_f32_16x16x32_bf16 v[24:27], v[152:155], v[212:215], v[24:27]
	v_mfma_f32_16x16x32_bf16 v[60:63], v[132:135], v[194:197], v[60:63]
	v_mfma_f32_16x16x32_bf16 v[40:43], v[156:159], v[208:211], v[40:43]
	v_mfma_f32_16x16x32_bf16 v[28:31], v[132:135], v[216:219], v[28:31]
	v_mfma_f32_16x16x32_bf16 v[8:11], v[156:159], v[224:227], v[8:11]
	v_mfma_f32_16x16x32_bf16 v[44:47], v[132:135], v[208:211], v[44:47]
	v_mfma_f32_16x16x32_bf16 v[56:59], v[156:159], v[194:197], v[56:59]
	v_lshl_add_u64 v[160:161], v[228:229], 0, s[40:41]
	s_mov_b32 m0, s63
	s_nop 0
	global_load_lds_dwordx4 v[160:161], off
	v_mfma_f32_16x16x32_bf16 v[12:15], v[132:135], v[224:227], v[12:15]
	v_mfma_f32_16x16x32_bf16 v[24:27], v[156:159], v[216:219], v[24:27]
	s_setprio 0
	s_setprio 1
	v_mfma_f32_16x16x32_bf16 v[52:55], v[172:175], v[190:193], v[52:55]
	v_mfma_f32_16x16x32_bf16 v[32:35], v[182:185], v[198:201], v[32:35]
	v_mfma_f32_16x16x32_bf16 v[20:23], v[172:175], v[212:215], v[20:23]
	v_mfma_f32_16x16x32_bf16 v[0:3], v[182:185], v[220:223], v[0:3]
	v_mfma_f32_16x16x32_bf16 v[36:39], v[172:175], v[198:201], v[36:39]
	v_mfma_f32_16x16x32_bf16 v[48:51], v[182:185], v[190:193], v[48:51]
	v_mfma_f32_16x16x32_bf16 v[4:7], v[172:175], v[220:223], v[4:7]
	v_mfma_f32_16x16x32_bf16 v[16:19], v[182:185], v[212:215], v[16:19]
	v_mfma_f32_16x16x32_bf16 v[52:55], v[176:179], v[194:197], v[52:55]
	v_mfma_f32_16x16x32_bf16 v[32:35], v[186:189], v[208:211], v[32:35]
	v_mfma_f32_16x16x32_bf16 v[20:23], v[176:179], v[216:219], v[20:23]
	v_mfma_f32_16x16x32_bf16 v[0:3], v[186:189], v[224:227], v[0:3]
	v_mfma_f32_16x16x32_bf16 v[36:39], v[176:179], v[208:211], v[36:39]
	v_mfma_f32_16x16x32_bf16 v[48:51], v[186:189], v[194:197], v[48:51]
	v_lshl_add_u64 v[160:161], v[230:231], 0, s[40:41]
	s_mov_b32 m0, s64
	s_nop 0
	global_load_lds_dwordx4 v[160:161], off
	v_mfma_f32_16x16x32_bf16 v[4:7], v[176:179], v[224:227], v[4:7]
	v_mfma_f32_16x16x32_bf16 v[16:19], v[186:189], v[216:219], v[16:19]
	s_setprio 0
	s_barrier
	s_add_i32 s93, s93, 2
	s_add_u32 s91, s91, 0x100
	s_addc_u32 s92, s92, 0
	s_mov_b64 s[10:11], s[50:51]
.LBB0_269:
	ds_read_b128 v[128:131], v165
	ds_read_b128 v[132:135], v165 offset:1024
	ds_read_b128 v[152:155], v165 offset:2048
	ds_read_b128 v[156:159], v165 offset:3072
	ds_read_b128 v[172:175], v168
	ds_read_b128 v[176:179], v168 offset:1024
	ds_read_b128 v[182:185], v168 offset:2048
	ds_read_b128 v[186:189], v168 offset:3072
	s_add_u32 s50, s10, 0x100
	s_addc_u32 s51, s11, 0
	s_cmp_eq_u32 s93, 40
	s_cselect_b32 s57, s1, s51
	s_cselect_b32 s56, s0, s50
	s_cselect_b32 s55, s49, s92
	s_cselect_b32 s54, s48, s91
	v_lshl_add_u64 v[160:161], s[10:11], 0, v[144:145]
	s_add_i32 m0, s58, 0xc000
	ds_read_b128 v[190:193], v169
	ds_read_b128 v[194:197], v169 offset:1024
	ds_read_b128 v[198:201], v169 offset:2048
	ds_read_b128 v[208:211], v169 offset:3072
	ds_read_b128 v[212:215], v169 offset:4096
	ds_read_b128 v[216:219], v169 offset:5120
	ds_read_b128 v[220:223], v169 offset:6144
	ds_read_b128 v[224:227], v169 offset:7168
	global_load_lds_dwordx4 v[160:161], off
	v_lshl_add_u64 v[160:161], s[10:11], 0, v[146:147]
	s_add_i32 m0, s58, 0xe000
	s_nop 0
	global_load_lds_dwordx4 v[160:161], off
	s_waitcnt vmcnt(8)
	s_waitcnt lgkmcnt(0)
	s_barrier
; #define PG8_STAGE(bufoff, gbase, voff) do { _Pragma("unroll") for (int _i = 0; _i < 2; ++_i) \
;         __builtin_amdgcn_global_load_lds((const unsigned*)((const char*)(gbase) + (voff)[_i]), (PG8_LAS unsigned*)(lds + (bufoff) + ldsw + _i * 8192), 16, 0, 0); } while (0)
; #define PG8_LDA(dst, b, h) do { _Pragma("unroll") for (int m = 0; m < 4; ++m) _Pragma("unroll") for (int k = 0; k < 2; ++k) dst[m][k] = *(const PG8_LAS bf16x8*)(lds + PG8_SA(b, h) + aoff + m * 2048 + k * 1024); } while (0)
; #define PG8_LDB(dst, b, h) do { _Pragma("unroll") for (int n = 0; n < 2; ++n) _Pragma("unroll") for (int k = 0; k < 2; ++k) dst[n][k] = *(const PG8_LAS bf16x8*)(lds + PG8_SB(b, h) + boff + n * 2048 + k * 1024); } while (0)
; #define PG8_MMA(ai, bj, At, Bt) do { __builtin_amdgcn_s_setprio(1); _Pragma("unroll") for (int m = 0; m < 4; ++m) _Pragma("unroll") for (int n = 0; n < 2; ++n) _Pragma("unroll") for (int k = 0; k < 2; ++k) \
;         acc[ai][bj][m][n] = __builtin_amdgcn_mfma_f32_16x16x32_bf16(Bt[n][k], At[m][k], acc[ai][bj][m][n], 0, 0, 0); __builtin_amdgcn_s_setprio(0); } while (0)
; #define PG8_WAIT_V(n) asm volatile("s_waitcnt vmcnt(" #n ")" ::: "memory")
; #define PG8_WAIT_L(n) asm volatile("s_waitcnt lgkmcnt(" #n ")" ::: "memory")
; #define PG8_BAR __builtin_amdgcn_s_barrier()
; #define PG8_SCHED __builtin_amdgcn_sched_barrier(0)
; template <class Epi, class Sched, bool ALIGN_EPI = false, bool SP2 = false>
; __device__ __forceinline__ void gemm_phase(PG8_LAS unsigned char* lds, const Gemm g, const Sched& S, const Epi& E) {
;     ...
;             PG8_LDB(B0, 0, 0); PG8_LDB(B1, 0, 1); PG8_SCHED; PG8_LDA(At, 0, 0); PG8_STAGE(PG8_SA(1, 1), a1 + hstep, voffA);
;             PG8_WAIT_V(8); PG8_WAIT_L(0); PG8_BAR; PG8_MMA(0, 0, At, B0); PG8_MMA(0, 1, At, B1); PG8_BAR; PG8_SCHED;
;             PG8_LDA(At, 0, 1); PG8_STAGE(PG8_SB(0, 0), b2, voffB); PG8_STAGE(PG8_SB(0, 1), b2 + hstep, voffB); PG8_STAGE(PG8_SA(0, 0), a2, voffA);
;             PG8_WAIT_V(8); PG8_WAIT_L(0); PG8_BAR; PG8_MMA(1, 0, At, B0); PG8_MMA(1, 1, At, B1); PG8_BAR; PG8_SCHED;
	s_setprio 1
	s_waitcnt lgkmcnt(0)
	v_mfma_f32_16x16x32_bf16 v[124:127], v[128:131], v[190:193], v[124:127]
	v_mfma_f32_16x16x32_bf16 v[104:107], v[152:155], v[198:201], v[104:107]
	v_mfma_f32_16x16x32_bf16 v[92:95], v[128:131], v[212:215], v[92:95]
	v_mfma_f32_16x16x32_bf16 v[72:75], v[152:155], v[220:223], v[72:75]
	v_mfma_f32_16x16x32_bf16 v[108:111], v[128:131], v[198:201], v[108:111]
	v_mfma_f32_16x16x32_bf16 v[120:123], v[152:155], v[190:193], v[120:123]
	v_mfma_f32_16x16x32_bf16 v[76:79], v[128:131], v[220:223], v[76:79]
	v_mfma_f32_16x16x32_bf16 v[88:91], v[152:155], v[212:215], v[88:91]
	v_mfma_f32_16x16x32_bf16 v[124:127], v[132:135], v[194:197], v[124:127]
	v_mfma_f32_16x16x32_bf16 v[104:107], v[156:159], v[208:211], v[104:107]
	v_mfma_f32_16x16x32_bf16 v[92:95], v[132:135], v[216:219], v[92:95]
	v_mfma_f32_16x16x32_bf16 v[72:75], v[156:159], v[224:227], v[72:75]
	v_mfma_f32_16x16x32_bf16 v[108:111], v[132:135], v[208:211], v[108:111]
	v_mfma_f32_16x16x32_bf16 v[120:123], v[156:159], v[194:197], v[120:123]
	v_mfma_f32_16x16x32_bf16 v[76:79], v[132:135], v[224:227], v[76:79]
	v_mfma_f32_16x16x32_bf16 v[88:91], v[156:159], v[216:219], v[88:91]
	s_setprio 0
	s_setprio 1
	v_mfma_f32_16x16x32_bf16 v[116:119], v[172:175], v[190:193], v[116:119]
	v_mfma_f32_16x16x32_bf16 v[96:99], v[182:185], v[198:201], v[96:99]
	v_mfma_f32_16x16x32_bf16 v[84:87], v[172:175], v[212:215], v[84:87]
	v_mfma_f32_16x16x32_bf16 v[64:67], v[182:185], v[220:223], v[64:67]
	v_mfma_f32_16x16x32_bf16 v[100:103], v[172:175], v[198:201], v[100:103]
	v_mfma_f32_16x16x32_bf16 v[112:115], v[182:185], v[190:193], v[112:115]
	v_mfma_f32_16x16x32_bf16 v[68:71], v[172:175], v[220:223], v[68:71]
	v_mfma_f32_16x16x32_bf16 v[80:83], v[182:185], v[212:215], v[80:83]
	v_mfma_f32_16x16x32_bf16 v[116:119], v[176:179], v[194:197], v[116:119]
	v_mfma_f32_16x16x32_bf16 v[96:99], v[186:189], v[208:211], v[96:99]
	v_mfma_f32_16x16x32_bf16 v[84:87], v[176:179], v[216:219], v[84:87]
	v_mfma_f32_16x16x32_bf16 v[64:67], v[186:189], v[224:227], v[64:67]
	v_mfma_f32_16x16x32_bf16 v[100:103], v[176:179], v[208:211], v[100:103]
	v_mfma_f32_16x16x32_bf16 v[112:115], v[186:189], v[194:197], v[112:115]
	v_mfma_f32_16x16x32_bf16 v[68:71], v[176:179], v[224:227], v[68:71]
	v_mfma_f32_16x16x32_bf16 v[80:83], v[186:189], v[216:219], v[80:83]
	s_setprio 0
	s_barrier
	s_add_i32 s3, s65, s43
	v_lshl_add_u64 v[160:161], s[54:55], 0, v[138:139]
	s_mov_b32 m0, s3
	ds_read_b128 v[190:193], v169 offset:16384
	ds_read_b128 v[194:197], v169 offset:17408
	ds_read_b128 v[198:201], v169 offset:18432
	ds_read_b128 v[208:211], v169 offset:19456
	ds_read_b128 v[212:215], v169 offset:20480
	ds_read_b128 v[216:219], v169 offset:21504
	ds_read_b128 v[220:223], v169 offset:22528
	ds_read_b128 v[224:227], v169 offset:23552
	global_load_lds_dwordx4 v[160:161], off
	s_add_i32 m0, s3, 0x2000
	s_add_u32 s10, s54, 0xb0000
	v_lshl_add_u64 v[202:203], s[54:55], 0, v[142:143]
	s_addc_u32 s11, s55, 0
	s_add_i32 s3, s66, s43
	global_load_lds_dwordx4 v[202:203], off
	v_lshl_add_u64 v[228:229], s[10:11], 0, v[138:139]
	s_mov_b32 m0, s3
	global_load_lds_dwordx4 v[228:229], off
	v_lshl_add_u64 v[228:229], s[10:11], 0, v[142:143]
	s_add_i32 m0, s3, 0x2000
	s_nop 0
	global_load_lds_dwordx4 v[228:229], off
	s_waitcnt vmcnt(6)
	s_waitcnt lgkmcnt(0)
	s_barrier
	s_setprio 1
	s_waitcnt lgkmcnt(0)
	v_mfma_f32_16x16x32_bf16 v[60:63], v[128:131], v[190:193], v[60:63]
	v_mfma_f32_16x16x32_bf16 v[40:43], v[152:155], v[198:201], v[40:43]
	v_mfma_f32_16x16x32_bf16 v[28:31], v[128:131], v[212:215], v[28:31]
	v_mfma_f32_16x16x32_bf16 v[8:11], v[152:155], v[220:223], v[8:11]
	v_mfma_f32_16x16x32_bf16 v[44:47], v[128:131], v[198:201], v[44:47]
	v_mfma_f32_16x16x32_bf16 v[56:59], v[152:155], v[190:193], v[56:59]
	v_mfma_f32_16x16x32_bf16 v[12:15], v[128:131], v[220:223], v[12:15]
	v_mfma_f32_16x16x32_bf16 v[24:27], v[152:155], v[212:215], v[24:27]
	v_mfma_f32_16x16x32_bf16 v[60:63], v[132:135], v[194:197], v[60:63]
	v_mfma_f32_16x16x32_bf16 v[40:43], v[156:159], v[208:211], v[40:43]
	v_mfma_f32_16x16x32_bf16 v[28:31], v[132:135], v[216:219], v[28:31]
	v_mfma_f32_16x16x32_bf16 v[8:11], v[156:159], v[224:227], v[8:11]
	v_mfma_f32_16x16x32_bf16 v[44:47], v[132:135], v[208:211], v[44:47]
	v_mfma_f32_16x16x32_bf16 v[56:59], v[156:159], v[194:197], v[56:59]
	v_lshl_add_u64 v[228:229], s[56:57], 0, v[136:137]
	s_mov_b32 m0, s58
	s_nop 0
	global_load_lds_dwordx4 v[228:229], off
	v_mfma_f32_16x16x32_bf16 v[12:15], v[132:135], v[224:227], v[12:15]
	v_mfma_f32_16x16x32_bf16 v[24:27], v[156:159], v[216:219], v[24:27]
	s_setprio 0
	s_setprio 1
	v_mfma_f32_16x16x32_bf16 v[52:55], v[172:175], v[190:193], v[52:55]
	v_mfma_f32_16x16x32_bf16 v[32:35], v[182:185], v[198:201], v[32:35]
	v_mfma_f32_16x16x32_bf16 v[20:23], v[172:175], v[212:215], v[20:23]
	v_mfma_f32_16x16x32_bf16 v[0:3], v[182:185], v[220:223], v[0:3]
	v_mfma_f32_16x16x32_bf16 v[36:39], v[172:175], v[198:201], v[36:39]
	v_mfma_f32_16x16x32_bf16 v[48:51], v[182:185], v[190:193], v[48:51]
	v_mfma_f32_16x16x32_bf16 v[4:7], v[172:175], v[220:223], v[4:7]
	v_mfma_f32_16x16x32_bf16 v[16:19], v[182:185], v[212:215], v[16:19]
	v_mfma_f32_16x16x32_bf16 v[52:55], v[176:179], v[194:197], v[52:55]
	v_mfma_f32_16x16x32_bf16 v[32:35], v[186:189], v[208:211], v[32:35]
	v_mfma_f32_16x16x32_bf16 v[20:23], v[176:179], v[216:219], v[20:23]
	v_mfma_f32_16x16x32_bf16 v[0:3], v[186:189], v[224:227], v[0:3]
	v_mfma_f32_16x16x32_bf16 v[36:39], v[176:179], v[208:211], v[36:39]
	v_mfma_f32_16x16x32_bf16 v[48:51], v[186:189], v[194:197], v[48:51]
	v_lshl_add_u64 v[230:231], s[56:57], 0, v[140:141]
	s_mov_b32 m0, s59
	s_nop 0
	global_load_lds_dwordx4 v[230:231], off
	v_mfma_f32_16x16x32_bf16 v[4:7], v[176:179], v[224:227], v[4:7]
	v_mfma_f32_16x16x32_bf16 v[16:19], v[186:189], v[216:219], v[16:19]
	s_setprio 0
	s_barrier
; #define PG8_STAGE(bufoff, gbase, voff) do { _Pragma("unroll") for (int _i = 0; _i < 2; ++_i) \
;         __builtin_amdgcn_global_load_lds((const unsigned*)((const char*)(gbase) + (voff)[_i]), (PG8_LAS unsigned*)(lds + (bufoff) + ldsw + _i * 8192), 16, 0, 0); } while (0)
; #define PG8_LDA(dst, b, h) do { _Pragma("unroll") for (int m = 0; m < 4; ++m) _Pragma("unroll") for (int k = 0; k < 2; ++k) dst[m][k] = *(const PG8_LAS bf16x8*)(lds + PG8_SA(b, h) + aoff + m * 2048 + k * 1024); } while (0)
; #define PG8_LDB(dst, b, h) do { _Pragma("unroll") for (int n = 0; n < 2; ++n) _Pragma("unroll") for (int k = 0; k < 2; ++k) dst[n][k] = *(const PG8_LAS bf16x8*)(lds + PG8_SB(b, h) + boff + n * 2048 + k * 1024); } while (0)
; #define PG8_MMA(ai, bj, At, Bt) do { __builtin_amdgcn_s_setprio(1); _Pragma("unroll") for (int m = 0; m < 4; ++m) _Pragma("unroll") for (int n = 0; n < 2; ++n) _Pragma("unroll") for (int k = 0; k < 2; ++k) \
;         acc[ai][bj][m][n] = __builtin_amdgcn_mfma_f32_16x16x32_bf16(Bt[n][k], At[m][k], acc[ai][bj][m][n], 0, 0, 0); __builtin_amdgcn_s_setprio(0); } while (0)
; #define PG8_WAIT_V(n) asm volatile("s_waitcnt vmcnt(" #n ")" ::: "memory")
; #define PG8_WAIT_L(n) asm volatile("s_waitcnt lgkmcnt(" #n ")" ::: "memory")
; #define PG8_BAR __builtin_amdgcn_s_barrier()
; #define PG8_SCHED __builtin_amdgcn_sched_barrier(0)
; template <class Epi, class Sched, bool ALIGN_EPI = false, bool SP2 = false>
; __device__ __forceinline__ void gemm_phase(PG8_LAS unsigned char* lds, const Gemm g, const Sched& S, const Epi& E) {
;     ...
;             PG8_LDB(B0, 1, 0); PG8_LDB(B1, 1, 1); PG8_SCHED; PG8_LDA(At, 1, 0); PG8_STAGE(PG8_SA(0, 1), a2 + hstep, voffA);
;             PG8_WAIT_V(8); PG8_WAIT_L(0); PG8_BAR; PG8_MMA(0, 0, At, B0); PG8_MMA(0, 1, At, B1); PG8_BAR; PG8_SCHED;
	s_add_i32 s3, 0, 0x18000
	s_add_i32 s14, 0, 0x1c000
	v_add_u32_e32 v156, s3, v163
	v_add_u32_e32 v171, s14, v163
	ds_read_b128 v[128:131], v156
	ds_read_b128 v[132:135], v156 offset:1024
	ds_read_b128 v[152:155], v156 offset:2048
	ds_read_b128 v[156:159], v156 offset:3072
	ds_read_b128 v[172:175], v171
	ds_read_b128 v[176:179], v171 offset:1024
	ds_read_b128 v[182:185], v171 offset:2048
	ds_read_b128 v[186:189], v171 offset:3072
	s_add_u32 s10, s56, 0xb0000
	s_addc_u32 s11, s57, 0
	s_mov_b32 m0, s60
	v_lshl_add_u64 v[232:233], s[10:11], 0, v[136:137]
	ds_read_b128 v[190:193], v169 offset:32768
	ds_read_b128 v[194:197], v169 offset:33792
	ds_read_b128 v[198:201], v169 offset:34816
	ds_read_b128 v[208:211], v169 offset:35840
	ds_read_b128 v[212:215], v169 offset:36864
	ds_read_b128 v[216:219], v169 offset:37888
	ds_read_b128 v[220:223], v169 offset:38912
	ds_read_b128 v[224:227], v169 offset:39936
	global_load_lds_dwordx4 v[232:233], off
	v_lshl_add_u64 v[232:233], s[10:11], 0, v[140:141]
	s_mov_b32 m0, s61
	s_nop 0
	global_load_lds_dwordx4 v[232:233], off
	s_waitcnt vmcnt(8)
	s_waitcnt lgkmcnt(0)
	s_barrier
	s_setprio 1
	s_waitcnt lgkmcnt(0)
	v_mfma_f32_16x16x32_bf16 v[124:127], v[128:131], v[190:193], v[124:127]
	v_mfma_f32_16x16x32_bf16 v[104:107], v[152:155], v[198:201], v[104:107]
	v_mfma_f32_16x16x32_bf16 v[92:95], v[128:131], v[212:215], v[92:95]
	v_mfma_f32_16x16x32_bf16 v[72:75], v[152:155], v[220:223], v[72:75]
	v_mfma_f32_16x16x32_bf16 v[108:111], v[128:131], v[198:201], v[108:111]
	v_mfma_f32_16x16x32_bf16 v[120:123], v[152:155], v[190:193], v[120:123]
	v_mfma_f32_16x16x32_bf16 v[76:79], v[128:131], v[220:223], v[76:79]
	v_mfma_f32_16x16x32_bf16 v[88:91], v[152:155], v[212:215], v[88:91]
	v_mfma_f32_16x16x32_bf16 v[124:127], v[132:135], v[194:197], v[124:127]
	v_mfma_f32_16x16x32_bf16 v[104:107], v[156:159], v[208:211], v[104:107]
	v_mfma_f32_16x16x32_bf16 v[92:95], v[132:135], v[216:219], v[92:95]
	v_mfma_f32_16x16x32_bf16 v[72:75], v[156:159], v[224:227], v[72:75]
	v_mfma_f32_16x16x32_bf16 v[108:111], v[132:135], v[208:211], v[108:111]
	v_mfma_f32_16x16x32_bf16 v[120:123], v[156:159], v[194:197], v[120:123]
	v_mfma_f32_16x16x32_bf16 v[76:79], v[132:135], v[224:227], v[76:79]
	v_mfma_f32_16x16x32_bf16 v[88:91], v[156:159], v[216:219], v[88:91]
	s_setprio 0
	s_setprio 1
	v_mfma_f32_16x16x32_bf16 v[116:119], v[172:175], v[190:193], v[116:119]
	v_mfma_f32_16x16x32_bf16 v[96:99], v[182:185], v[198:201], v[96:99]
	v_mfma_f32_16x16x32_bf16 v[84:87], v[172:175], v[212:215], v[84:87]
	v_mfma_f32_16x16x32_bf16 v[64:67], v[182:185], v[220:223], v[64:67]
	v_mfma_f32_16x16x32_bf16 v[100:103], v[172:175], v[198:201], v[100:103]
	v_mfma_f32_16x16x32_bf16 v[112:115], v[182:185], v[190:193], v[112:115]
	v_mfma_f32_16x16x32_bf16 v[68:71], v[172:175], v[220:223], v[68:71]
	v_mfma_f32_16x16x32_bf16 v[80:83], v[182:185], v[212:215], v[80:83]
	v_mfma_f32_16x16x32_bf16 v[116:119], v[176:179], v[194:197], v[116:119]
	v_mfma_f32_16x16x32_bf16 v[96:99], v[186:189], v[208:211], v[96:99]
	v_mfma_f32_16x16x32_bf16 v[84:87], v[176:179], v[216:219], v[84:87]
	v_mfma_f32_16x16x32_bf16 v[64:67], v[186:189], v[224:227], v[64:67]
	v_mfma_f32_16x16x32_bf16 v[100:103], v[176:179], v[208:211], v[100:103]
	v_mfma_f32_16x16x32_bf16 v[112:115], v[186:189], v[194:197], v[112:115]
	v_mfma_f32_16x16x32_bf16 v[68:71], v[176:179], v[224:227], v[68:71]
	v_mfma_f32_16x16x32_bf16 v[80:83], v[186:189], v[216:219], v[80:83]
	s_setprio 0
	s_barrier
; #define PG8_STAGE(bufoff, gbase, voff) do { _Pragma("unroll") for (int _i = 0; _i < 2; ++_i) \
;         __builtin_amdgcn_global_load_lds((const unsigned*)((const char*)(gbase) + (voff)[_i]), (PG8_LAS unsigned*)(lds + (bufoff) + ldsw + _i * 8192), 16, 0, 0); } while (0)
; #define PG8_LDA(dst, b, h) do { _Pragma("unroll") for (int m = 0; m < 4; ++m) _Pragma("unroll") for (int k = 0; k < 2; ++k) dst[m][k] = *(const PG8_LAS bf16x8*)(lds + PG8_SA(b, h) + aoff + m * 2048 + k * 1024); } while (0)
; #define PG8_MMA(ai, bj, At, Bt) do { __builtin_amdgcn_s_setprio(1); _Pragma("unroll") for (int m = 0; m < 4; ++m) _Pragma("unroll") for (int n = 0; n < 2; ++n) _Pragma("unroll") for (int k = 0; k < 2; ++k) \
;         acc[ai][bj][m][n] = __builtin_amdgcn_mfma_f32_16x16x32_bf16(Bt[n][k], At[m][k], acc[ai][bj][m][n], 0, 0, 0); __builtin_amdgcn_s_setprio(0); } while (0)
; #define PG8_WAIT_V(n) asm volatile("s_waitcnt vmcnt(" #n ")" ::: "memory")
; #define PG8_WAIT_L(n) asm volatile("s_waitcnt lgkmcnt(" #n ")" ::: "memory")
; #define PG8_BAR __builtin_amdgcn_s_barrier()
; #define PG8_SCHED __builtin_amdgcn_sched_barrier(0)
; template <class Epi, class Sched, bool ALIGN_EPI = false, bool SP2 = false>
; __device__ __forceinline__ void gemm_phase(PG8_LAS unsigned char* lds, const Gemm g, const Sched& S, const Epi& E) {
;     ...
;             PG8_LDA(At, 1, 1); PG8_STAGE(PG8_SB(1, 0), b3, voffB); PG8_STAGE(PG8_SB(1, 1), b3 + hstep, voffB); PG8_STAGE(PG8_SA(1, 0), a3, voffA);
;             PG8_WAIT_V(8); PG8_WAIT_L(0); PG8_BAR; PG8_MMA(1, 0, At, B0); PG8_MMA(1, 1, At, B1); PG8_BAR; PG8_SCHED;
;     ...
;         if constexpr (ALIGN_EPI) { if (wr == 0) PG8_BAR; }
	s_add_i32 s3, s3, s43
	v_lshl_add_u64 v[160:161], v[160:161], 0, s[40:41]
	s_mov_b32 m0, s3
	ds_read_b128 v[190:193], v169 offset:49152
	ds_read_b128 v[194:197], v169 offset:50176
	ds_read_b128 v[198:201], v169 offset:51200
	ds_read_b128 v[208:211], v169 offset:52224
	ds_read_b128 v[212:215], v169 offset:53248
	ds_read_b128 v[216:219], v169 offset:54272
	ds_read_b128 v[220:223], v169 offset:55296
	ds_read_b128 v[224:227], v169 offset:56320
	global_load_lds_dwordx4 v[160:161], off
	s_add_i32 m0, s3, 0x2000
	s_add_u32 s10, s54, 0xb0080
	v_lshl_add_u64 v[160:161], v[202:203], 0, s[40:41]
	s_addc_u32 s11, s55, 0
	s_add_i32 s3, s14, s43
	global_load_lds_dwordx4 v[160:161], off
	v_lshl_add_u64 v[160:161], s[10:11], 0, v[138:139]
	s_mov_b32 m0, s3
	s_nop 0
	global_load_lds_dwordx4 v[160:161], off
	v_lshl_add_u64 v[160:161], s[10:11], 0, v[142:143]
	s_add_i32 m0, s3, 0x2000
	s_nop 0
	global_load_lds_dwordx4 v[160:161], off
	s_waitcnt vmcnt(6)
	s_waitcnt lgkmcnt(0)
	s_barrier
	s_setprio 1
	s_waitcnt lgkmcnt(0)
	v_mfma_f32_16x16x32_bf16 v[60:63], v[128:131], v[190:193], v[60:63]
	v_mfma_f32_16x16x32_bf16 v[40:43], v[152:155], v[198:201], v[40:43]
	v_mfma_f32_16x16x32_bf16 v[28:31], v[128:131], v[212:215], v[28:31]
	v_mfma_f32_16x16x32_bf16 v[8:11], v[152:155], v[220:223], v[8:11]
	v_mfma_f32_16x16x32_bf16 v[44:47], v[128:131], v[198:201], v[44:47]
	v_mfma_f32_16x16x32_bf16 v[56:59], v[152:155], v[190:193], v[56:59]
	v_mfma_f32_16x16x32_bf16 v[12:15], v[128:131], v[220:223], v[12:15]
	v_mfma_f32_16x16x32_bf16 v[24:27], v[152:155], v[212:215], v[24:27]
	v_mfma_f32_16x16x32_bf16 v[60:63], v[132:135], v[194:197], v[60:63]
	v_mfma_f32_16x16x32_bf16 v[40:43], v[156:159], v[208:211], v[40:43]
	v_mfma_f32_16x16x32_bf16 v[28:31], v[132:135], v[216:219], v[28:31]
	v_mfma_f32_16x16x32_bf16 v[8:11], v[156:159], v[224:227], v[8:11]
	v_mfma_f32_16x16x32_bf16 v[44:47], v[132:135], v[208:211], v[44:47]
	v_mfma_f32_16x16x32_bf16 v[56:59], v[156:159], v[194:197], v[56:59]
	v_lshl_add_u64 v[160:161], v[228:229], 0, s[40:41]
	s_mov_b32 m0, s63
	s_nop 0
	global_load_lds_dwordx4 v[160:161], off
	v_mfma_f32_16x16x32_bf16 v[12:15], v[132:135], v[224:227], v[12:15]
	v_mfma_f32_16x16x32_bf16 v[24:27], v[156:159], v[216:219], v[24:27]
	s_setprio 0
	s_setprio 1
	v_mfma_f32_16x16x32_bf16 v[52:55], v[172:175], v[190:193], v[52:55]
	v_mfma_f32_16x16x32_bf16 v[32:35], v[182:185], v[198:201], v[32:35]
	v_mfma_f32_16x16x32_bf16 v[20:23], v[172:175], v[212:215], v[20:23]
	v_mfma_f32_16x16x32_bf16 v[0:3], v[182:185], v[220:223], v[0:3]
	v_mfma_f32_16x16x32_bf16 v[36:39], v[172:175], v[198:201], v[36:39]
	v_mfma_f32_16x16x32_bf16 v[48:51], v[182:185], v[190:193], v[48:51]
	v_mfma_f32_16x16x32_bf16 v[4:7], v[172:175], v[220:223], v[4:7]
	v_mfma_f32_16x16x32_bf16 v[16:19], v[182:185], v[212:215], v[16:19]
	v_mfma_f32_16x16x32_bf16 v[52:55], v[176:179], v[194:197], v[52:55]
	v_mfma_f32_16x16x32_bf16 v[32:35], v[186:189], v[208:211], v[32:35]
	v_mfma_f32_16x16x32_bf16 v[20:23], v[176:179], v[216:219], v[20:23]
	v_mfma_f32_16x16x32_bf16 v[0:3], v[186:189], v[224:227], v[0:3]
	v_mfma_f32_16x16x32_bf16 v[36:39], v[176:179], v[208:211], v[36:39]
	v_mfma_f32_16x16x32_bf16 v[48:51], v[186:189], v[194:197], v[48:51]
	v_lshl_add_u64 v[160:161], v[230:231], 0, s[40:41]
	s_mov_b32 m0, s64
	s_nop 0
	global_load_lds_dwordx4 v[160:161], off
	v_mfma_f32_16x16x32_bf16 v[4:7], v[176:179], v[224:227], v[4:7]
	v_mfma_f32_16x16x32_bf16 v[16:19], v[186:189], v[216:219], v[16:19]
	s_setprio 0
	s_barrier
	s_add_i32 s93, s93, 2
	s_add_u32 s91, s91, 0x100
	s_addc_u32 s92, s92, 0
	s_cmp_gt_u32 s93, 41
	s_mov_b64 s[10:11], s[50:51]
	s_cbranch_scc0 .LBB0_269
	s_and_b64 vcc, exec, s[44:45]
	s_cbranch_vccz .LBB0_272
	s_barrier

; #define PG8_STAGE(bufoff, gbase, voff) do { _Pragma("unroll") for (int _i = 0; _i < 2; ++_i) \
;         __builtin_amdgcn_global_load_lds((const unsigned*)((const char*)(gbase) + (voff)[_i]), (PG8_LAS unsigned*)(lds + (bufoff) + ldsw + _i * 8192), 16, 0, 0); } while (0)
; #define PG8_LDA(dst, b, h) do { _Pragma("unroll") for (int m = 0; m < 4; ++m) _Pragma("unroll") for (int k = 0; k < 2; ++k) dst[m][k] = *(const PG8_LAS bf16x8*)(lds + PG8_SA(b, h) + aoff + m * 2048 + k * 1024); } while (0)
; #define PG8_LDB(dst, b, h) do { _Pragma("unroll") for (int n = 0; n < 2; ++n) _Pragma("unroll") for (int k = 0; k < 2; ++k) dst[n][k] = *(const PG8_LAS bf16x8*)(lds + PG8_SB(b, h) + boff + n * 2048 + k * 1024); } while (0)
; #define PG8_MMA(ai, bj, At, Bt) do { __builtin_amdgcn_s_setprio(1); _Pragma("unroll") for (int m = 0; m < 4; ++m) _Pragma("unroll") for (int n = 0; n < 2; ++n) _Pragma("unroll") for (int k = 0; k < 2; ++k) \
;         acc[ai][bj][m][n] = __builtin_amdgcn_mfma_f32_16x16x32_bf16(Bt[n][k], At[m][k], acc[ai][bj][m][n], 0, 0, 0); __builtin_amdgcn_s_setprio(0); } while (0)
; #define PG8_BAR __builtin_amdgcn_s_barrier()
; template <class Epi, class Sched, bool ALIGN_EPI = false, bool SP2 = false>
; __device__ __forceinline__ void gemm_phase(PG8_LAS unsigned char* lds, const Gemm g, const Sched& S, const Epi& E) {
;     ...
;         const bool has_next = S.next(ui + 1, nxt);
;         const char* nA = has_next ? (const char*)g.A + (size_t)nxt.pm * tstep : cA; const char* nB = has_next ? (const char*)g.Bt + (size_t)nxt.pn * tstep : cB;
;         for (int t = 0; t < nt; t += 2) {
;             const bool last = (t == nt - 2);
;             const char* a1 = cA + (size_t)(t + 1) * kstep;
;             const char* a2 = last ? nA : cA + (size_t)(t + 2) * kstep; const char* b2 = last ? nB : cB + (size_t)(t + 2) * kstep;
;             const char* a3 = a2 + kstep; const char* b3 = b2 + kstep;
;             if (last && has_next) S.a_ready(nxt);
;             if constexpr (SP2) {
;             PG8_LDB(B0, 0, 0); PG8_LDB(B1, 0, 1); PG8_SCHED; PG8_LDA(At, 0, 0); PG8_STAGE(PG8_SA(1, 1), a1 + hstep, voffA);
;             PG8_WAIT_V(8); PG8_WAIT_L(0); PG8_BAR; PG8_MMA(0, 0, At, B0); PG8_MMA(0, 1, At, B1); PG8_BAR; PG8_SCHED;
;             PG8_LDA(At, 0, 1); PG8_STAGE(PG8_SB(0, 0), b2, voffB); PG8_STAGE(PG8_SB(0, 1), b2 + hstep, voffB); PG8_STAGE(PG8_SA(0, 0), a2, voffA);
.LBB0_416:
	s_ashr_i32 s45, s44, 31
	s_lshl_b64 s[14:15], s[44:45], 19
	s_add_u32 s48, s22, s14
	s_addc_u32 s49, s23, s15
	s_and_b64 s[14:15], s[6:7], exec
	s_cselect_b32 s45, s49, s55
	s_cselect_b32 s89, s48, s54
	s_ashr_i32 s41, s40, 31
	s_lshl_b64 s[14:15], s[40:41], 19
	s_add_u32 s50, s84, s14
	s_addc_u32 s51, s85, s15
	s_and_b64 s[14:15], s[6:7], exec
	s_cselect_b32 s41, s51, s57
	s_cselect_b32 s90, s50, s56
	s_add_u32 s54, s54, 0x40080
	s_addc_u32 s55, s55, 0
	s_add_u32 s91, s56, 0x100
	s_addc_u32 s92, s57, 0
	s_mov_b32 s93, -2
	ds_read_b128 v[154:157], v169
	ds_read_b128 v[158:161], v169 offset:1024
	ds_read_b128 v[162:165], v169 offset:2048
	ds_read_b128 v[174:177], v169 offset:3072
	ds_read_b128 v[182:185], v170
	ds_read_b128 v[186:189], v170 offset:1024
	ds_read_b128 v[190:193], v170 offset:2048
	ds_read_b128 v[194:197], v170 offset:3072
	s_add_u32 s3, s54, 0xfffc0080
	s_addc_u32 s14, s55, -1
	s_cmp_eq_u32 s93, 12
	s_cselect_b32 s59, s45, s14
	s_cselect_b32 s58, s89, s3
	s_cselect_b32 s57, s41, s92
	s_cselect_b32 s56, s90, s91
	v_lshl_add_u64 v[178:179], s[54:55], 0, v[146:147]
	s_add_i32 m0, s60, 0xc000
	ds_read_b128 v[198:201], v171
	ds_read_b128 v[208:211], v171 offset:1024
	ds_read_b128 v[212:215], v171 offset:2048
	ds_read_b128 v[216:219], v171 offset:3072
	ds_read_b128 v[220:223], v171 offset:4096
	ds_read_b128 v[224:227], v171 offset:5120
	ds_read_b128 v[228:231], v171 offset:6144
	ds_read_b128 v[232:235], v171 offset:7168
	global_load_lds_dwordx4 v[178:179], off
	v_lshl_add_u64 v[178:179], s[54:55], 0, v[148:149]
	s_add_i32 m0, s60, 0xe000
	s_nop 0
	global_load_lds_dwordx4 v[178:179], off
	s_waitcnt vmcnt(8)
	s_waitcnt lgkmcnt(0)
	s_barrier
	s_setprio 1
	s_waitcnt lgkmcnt(0)
	v_mfma_f32_16x16x32_bf16 v[124:127], v[154:157], v[198:201], 0
	v_mfma_f32_16x16x32_bf16 v[112:115], v[162:165], v[212:215], 0
	v_mfma_f32_16x16x32_bf16 v[108:111], v[154:157], v[220:223], 0
	v_mfma_f32_16x16x32_bf16 v[96:99], v[162:165], v[228:231], 0
	v_mfma_f32_16x16x32_bf16 v[116:119], v[154:157], v[212:215], 0
	v_mfma_f32_16x16x32_bf16 v[120:123], v[162:165], v[198:201], 0
	v_mfma_f32_16x16x32_bf16 v[100:103], v[154:157], v[228:231], 0
	v_mfma_f32_16x16x32_bf16 v[104:107], v[162:165], v[220:223], 0
	v_mfma_f32_16x16x32_bf16 v[124:127], v[158:161], v[208:211], v[124:127]
	v_mfma_f32_16x16x32_bf16 v[112:115], v[174:177], v[216:219], v[112:115]
	v_mfma_f32_16x16x32_bf16 v[108:111], v[158:161], v[224:227], v[108:111]
	v_mfma_f32_16x16x32_bf16 v[96:99], v[174:177], v[232:235], v[96:99]
	v_mfma_f32_16x16x32_bf16 v[116:119], v[158:161], v[216:219], v[116:119]
	v_mfma_f32_16x16x32_bf16 v[120:123], v[174:177], v[208:211], v[120:123]
	v_mfma_f32_16x16x32_bf16 v[100:103], v[158:161], v[232:235], v[100:103]
	v_mfma_f32_16x16x32_bf16 v[104:107], v[174:177], v[224:227], v[104:107]
	s_setprio 0
	s_setprio 1
	v_mfma_f32_16x16x32_bf16 v[68:71], v[182:185], v[198:201], 0
	v_mfma_f32_16x16x32_bf16 v[48:51], v[190:193], v[212:215], 0
	v_mfma_f32_16x16x32_bf16 v[44:47], v[182:185], v[220:223], 0
	v_mfma_f32_16x16x32_bf16 v[32:35], v[190:193], v[228:231], 0
	v_mfma_f32_16x16x32_bf16 v[52:55], v[182:185], v[212:215], 0
	v_mfma_f32_16x16x32_bf16 v[64:67], v[190:193], v[198:201], 0
	v_mfma_f32_16x16x32_bf16 v[36:39], v[182:185], v[228:231], 0
	v_mfma_f32_16x16x32_bf16 v[40:43], v[190:193], v[220:223], 0
	v_mfma_f32_16x16x32_bf16 v[68:71], v[186:189], v[208:211], v[68:71]
	v_mfma_f32_16x16x32_bf16 v[48:51], v[194:197], v[216:219], v[48:51]
	v_mfma_f32_16x16x32_bf16 v[44:47], v[186:189], v[224:227], v[44:47]
	v_mfma_f32_16x16x32_bf16 v[32:35], v[194:197], v[232:235], v[32:35]
	v_mfma_f32_16x16x32_bf16 v[52:55], v[186:189], v[216:219], v[52:55]
	v_mfma_f32_16x16x32_bf16 v[64:67], v[194:197], v[208:211], v[64:67]
	v_mfma_f32_16x16x32_bf16 v[36:39], v[186:189], v[232:235], v[36:39]
	v_mfma_f32_16x16x32_bf16 v[40:43], v[194:197], v[224:227], v[40:43]
	s_setprio 0
	s_barrier
	s_add_i32 s3, s86, s34
	v_lshl_add_u64 v[178:179], s[56:57], 0, v[132:133]
	s_mov_b32 m0, s3
	ds_read_b128 v[198:201], v171 offset:16384
	ds_read_b128 v[208:211], v171 offset:17408
	ds_read_b128 v[212:215], v171 offset:18432
	ds_read_b128 v[216:219], v171 offset:19456
	ds_read_b128 v[220:223], v171 offset:20480
	ds_read_b128 v[224:227], v171 offset:21504
	ds_read_b128 v[228:231], v171 offset:22528
	ds_read_b128 v[232:235], v171 offset:23552
	global_load_lds_dwordx4 v[178:179], off
	s_add_i32 m0, s3, 0x2000
	s_add_u32 s14, s56, 0x40000
	v_lshl_add_u64 v[202:203], s[56:57], 0, v[128:129]
	s_addc_u32 s15, s57, 0
	s_add_i32 s3, s87, s34
	global_load_lds_dwordx4 v[202:203], off
	v_lshl_add_u64 v[236:237], s[14:15], 0, v[132:133]
	s_mov_b32 m0, s3
	global_load_lds_dwordx4 v[236:237], off
	v_lshl_add_u64 v[236:237], s[14:15], 0, v[128:129]
	s_add_i32 m0, s3, 0x2000
	s_nop 0
	global_load_lds_dwordx4 v[236:237], off
	s_waitcnt vmcnt(6)
	s_waitcnt lgkmcnt(0)
	s_barrier
; #define PG8_STAGE(bufoff, gbase, voff) do { _Pragma("unroll") for (int _i = 0; _i < 2; ++_i) \
;         __builtin_amdgcn_global_load_lds((const unsigned*)((const char*)(gbase) + (voff)[_i]), (PG8_LAS unsigned*)(lds + (bufoff) + ldsw + _i * 8192), 16, 0, 0); } while (0)
; #define PG8_LDA(dst, b, h) do { _Pragma("unroll") for (int m = 0; m < 4; ++m) _Pragma("unroll") for (int k = 0; k < 2; ++k) dst[m][k] = *(const PG8_LAS bf16x8*)(lds + PG8_SA(b, h) + aoff + m * 2048 + k * 1024); } while (0)
; #define PG8_LDB(dst, b, h) do { _Pragma("unroll") for (int n = 0; n < 2; ++n) _Pragma("unroll") for (int k = 0; k < 2; ++k) dst[n][k] = *(const PG8_LAS bf16x8*)(lds + PG8_SB(b, h) + boff + n * 2048 + k * 1024); } while (0)
; #define PG8_MMA(ai, bj, At, Bt) do { __builtin_amdgcn_s_setprio(1); _Pragma("unroll") for (int m = 0; m < 4; ++m) _Pragma("unroll") for (int n = 0; n < 2; ++n) _Pragma("unroll") for (int k = 0; k < 2; ++k) \
;         acc[ai][bj][m][n] = __builtin_amdgcn_mfma_f32_16x16x32_bf16(Bt[n][k], At[m][k], acc[ai][bj][m][n], 0, 0, 0); __builtin_amdgcn_s_setprio(0); } while (0)
; #define PG8_WAIT_V(n) asm volatile("s_waitcnt vmcnt(" #n ")" ::: "memory")
; #define PG8_WAIT_L(n) asm volatile("s_waitcnt lgkmcnt(" #n ")" ::: "memory")
; #define PG8_BAR __builtin_amdgcn_s_barrier()
; #define PG8_SCHED __builtin_amdgcn_sched_barrier(0)
; template <class Epi, class Sched, bool ALIGN_EPI = false, bool SP2 = false>
; __device__ __forceinline__ void gemm_phase(PG8_LAS unsigned char* lds, const Gemm g, const Sched& S, const Epi& E) {
;     ...
;             PG8_WAIT_V(8); PG8_WAIT_L(0); PG8_BAR; PG8_MMA(0, 0, At, B0); PG8_MMA(0, 1, At, B1); PG8_BAR; PG8_SCHED;
;             PG8_LDA(At, 0, 1); PG8_STAGE(PG8_SB(0, 0), b2, voffB); PG8_STAGE(PG8_SB(0, 1), b2 + hstep, voffB); PG8_STAGE(PG8_SA(0, 0), a2, voffA);
;             PG8_WAIT_V(8); PG8_WAIT_L(0); PG8_BAR; PG8_MMA(1, 0, At, B0); PG8_MMA(1, 1, At, B1); PG8_BAR; PG8_SCHED;
;             PG8_LDB(B0, 1, 0); PG8_LDB(B1, 1, 1); PG8_SCHED; PG8_LDA(At, 1, 0); PG8_STAGE(PG8_SA(0, 1), a2 + hstep, voffA);
;             PG8_WAIT_V(8); PG8_WAIT_L(0); PG8_BAR; PG8_MMA(0, 0, At, B0); PG8_MMA(0, 1, At, B1); PG8_BAR; PG8_SCHED;
	s_setprio 1
	s_waitcnt lgkmcnt(0)
	v_mfma_f32_16x16x32_bf16 v[92:95], v[154:157], v[198:201], 0
	v_mfma_f32_16x16x32_bf16 v[80:83], v[162:165], v[212:215], 0
	v_mfma_f32_16x16x32_bf16 v[76:79], v[154:157], v[220:223], 0
	v_mfma_f32_16x16x32_bf16 v[56:59], v[162:165], v[228:231], 0
	v_mfma_f32_16x16x32_bf16 v[84:87], v[154:157], v[212:215], 0
	v_mfma_f32_16x16x32_bf16 v[88:91], v[162:165], v[198:201], 0
	v_mfma_f32_16x16x32_bf16 v[60:63], v[154:157], v[228:231], 0
	v_mfma_f32_16x16x32_bf16 v[72:75], v[162:165], v[220:223], 0
	v_mfma_f32_16x16x32_bf16 v[92:95], v[158:161], v[208:211], v[92:95]
	v_mfma_f32_16x16x32_bf16 v[80:83], v[174:177], v[216:219], v[80:83]
	v_mfma_f32_16x16x32_bf16 v[76:79], v[158:161], v[224:227], v[76:79]
	v_mfma_f32_16x16x32_bf16 v[56:59], v[174:177], v[232:235], v[56:59]
	v_mfma_f32_16x16x32_bf16 v[84:87], v[158:161], v[216:219], v[84:87]
	v_mfma_f32_16x16x32_bf16 v[88:91], v[174:177], v[208:211], v[88:91]
	v_lshl_add_u64 v[236:237], s[58:59], 0, v[134:135]
	s_mov_b32 m0, s60
	s_nop 0
	global_load_lds_dwordx4 v[236:237], off
	v_mfma_f32_16x16x32_bf16 v[60:63], v[158:161], v[232:235], v[60:63]
	v_mfma_f32_16x16x32_bf16 v[72:75], v[174:177], v[224:227], v[72:75]
	s_setprio 0
	s_setprio 1
	v_mfma_f32_16x16x32_bf16 v[28:31], v[182:185], v[198:201], 0
	v_mfma_f32_16x16x32_bf16 v[16:19], v[190:193], v[212:215], 0
	v_mfma_f32_16x16x32_bf16 v[12:15], v[182:185], v[220:223], 0
	v_mfma_f32_16x16x32_bf16 v[0:3], v[190:193], v[228:231], 0
	v_mfma_f32_16x16x32_bf16 v[20:23], v[182:185], v[212:215], 0
	v_mfma_f32_16x16x32_bf16 v[24:27], v[190:193], v[198:201], 0
	v_mfma_f32_16x16x32_bf16 v[4:7], v[182:185], v[228:231], 0
	v_mfma_f32_16x16x32_bf16 v[8:11], v[190:193], v[220:223], 0
	v_mfma_f32_16x16x32_bf16 v[28:31], v[186:189], v[208:211], v[28:31]
	v_mfma_f32_16x16x32_bf16 v[16:19], v[194:197], v[216:219], v[16:19]
	v_mfma_f32_16x16x32_bf16 v[12:15], v[186:189], v[224:227], v[12:15]
	v_mfma_f32_16x16x32_bf16 v[0:3], v[194:197], v[232:235], v[0:3]
	v_mfma_f32_16x16x32_bf16 v[20:23], v[186:189], v[216:219], v[20:23]
	v_mfma_f32_16x16x32_bf16 v[24:27], v[194:197], v[208:211], v[24:27]
	v_lshl_add_u64 v[238:239], s[58:59], 0, v[130:131]
	s_mov_b32 m0, s61
	s_nop 0
	global_load_lds_dwordx4 v[238:239], off
	v_mfma_f32_16x16x32_bf16 v[4:7], v[186:189], v[232:235], v[4:7]
	v_mfma_f32_16x16x32_bf16 v[8:11], v[194:197], v[224:227], v[8:11]
	s_setprio 0
	s_barrier
	s_add_i32 s3, 0, 0x18000
	v_add_u32_e32 v136, s3, v143
	s_add_i32 s33, 0, 0x1c000
	ds_read_b128 v[154:157], v136
	ds_read_b128 v[158:161], v136 offset:1024
	ds_read_b128 v[162:165], v136 offset:2048
	ds_read_b128 v[174:177], v136 offset:3072
	v_add_u32_e32 v136, s33, v143
	ds_read_b128 v[182:185], v136
	ds_read_b128 v[186:189], v136 offset:1024
	ds_read_b128 v[190:193], v136 offset:2048
	ds_read_b128 v[194:197], v136 offset:3072
	s_add_u32 s14, s58, 0x40000
	s_addc_u32 s15, s59, 0
	s_mov_b32 m0, s62
	v_lshl_add_u64 v[240:241], s[14:15], 0, v[134:135]
	ds_read_b128 v[198:201], v171 offset:32768
	ds_read_b128 v[208:211], v171 offset:33792
	ds_read_b128 v[212:215], v171 offset:34816
	ds_read_b128 v[216:219], v171 offset:35840
	ds_read_b128 v[220:223], v171 offset:36864
	ds_read_b128 v[224:227], v171 offset:37888
	ds_read_b128 v[228:231], v171 offset:38912
	ds_read_b128 v[232:235], v171 offset:39936
	global_load_lds_dwordx4 v[240:241], off
	v_lshl_add_u64 v[240:241], s[14:15], 0, v[130:131]
	s_mov_b32 m0, s63
	s_nop 0
	global_load_lds_dwordx4 v[240:241], off
	s_waitcnt vmcnt(8)
	s_waitcnt lgkmcnt(0)
	s_barrier
	s_setprio 1
	s_waitcnt lgkmcnt(0)
	v_mfma_f32_16x16x32_bf16 v[124:127], v[154:157], v[198:201], v[124:127]
	v_mfma_f32_16x16x32_bf16 v[112:115], v[162:165], v[212:215], v[112:115]
	v_mfma_f32_16x16x32_bf16 v[108:111], v[154:157], v[220:223], v[108:111]
	v_mfma_f32_16x16x32_bf16 v[96:99], v[162:165], v[228:231], v[96:99]
	v_mfma_f32_16x16x32_bf16 v[116:119], v[154:157], v[212:215], v[116:119]
	v_mfma_f32_16x16x32_bf16 v[120:123], v[162:165], v[198:201], v[120:123]
	v_mfma_f32_16x16x32_bf16 v[100:103], v[154:157], v[228:231], v[100:103]
	v_mfma_f32_16x16x32_bf16 v[104:107], v[162:165], v[220:223], v[104:107]
	v_mfma_f32_16x16x32_bf16 v[124:127], v[158:161], v[208:211], v[124:127]
	v_mfma_f32_16x16x32_bf16 v[112:115], v[174:177], v[216:219], v[112:115]
	v_mfma_f32_16x16x32_bf16 v[108:111], v[158:161], v[224:227], v[108:111]
	v_mfma_f32_16x16x32_bf16 v[96:99], v[174:177], v[232:235], v[96:99]
	v_mfma_f32_16x16x32_bf16 v[116:119], v[158:161], v[216:219], v[116:119]
	v_mfma_f32_16x16x32_bf16 v[120:123], v[174:177], v[208:211], v[120:123]
	v_mfma_f32_16x16x32_bf16 v[100:103], v[158:161], v[232:235], v[100:103]
	v_mfma_f32_16x16x32_bf16 v[104:107], v[174:177], v[224:227], v[104:107]
	s_setprio 0
	s_setprio 1
	v_mfma_f32_16x16x32_bf16 v[68:71], v[182:185], v[198:201], v[68:71]
	v_mfma_f32_16x16x32_bf16 v[48:51], v[190:193], v[212:215], v[48:51]
	v_mfma_f32_16x16x32_bf16 v[44:47], v[182:185], v[220:223], v[44:47]
	v_mfma_f32_16x16x32_bf16 v[32:35], v[190:193], v[228:231], v[32:35]
	v_mfma_f32_16x16x32_bf16 v[52:55], v[182:185], v[212:215], v[52:55]
	v_mfma_f32_16x16x32_bf16 v[64:67], v[190:193], v[198:201], v[64:67]
	v_mfma_f32_16x16x32_bf16 v[36:39], v[182:185], v[228:231], v[36:39]
	v_mfma_f32_16x16x32_bf16 v[40:43], v[190:193], v[220:223], v[40:43]
	v_mfma_f32_16x16x32_bf16 v[68:71], v[186:189], v[208:211], v[68:71]
	v_mfma_f32_16x16x32_bf16 v[48:51], v[194:197], v[216:219], v[48:51]
	v_mfma_f32_16x16x32_bf16 v[44:47], v[186:189], v[224:227], v[44:47]
	v_mfma_f32_16x16x32_bf16 v[32:35], v[194:197], v[232:235], v[32:35]
	v_mfma_f32_16x16x32_bf16 v[52:55], v[186:189], v[216:219], v[52:55]
	v_mfma_f32_16x16x32_bf16 v[64:67], v[194:197], v[208:211], v[64:67]
	v_mfma_f32_16x16x32_bf16 v[36:39], v[186:189], v[232:235], v[36:39]
	v_mfma_f32_16x16x32_bf16 v[40:43], v[194:197], v[224:227], v[40:43]
	s_setprio 0
	s_barrier
; #define PG8_STAGE(bufoff, gbase, voff) do { _Pragma("unroll") for (int _i = 0; _i < 2; ++_i) \
;         __builtin_amdgcn_global_load_lds((const unsigned*)((const char*)(gbase) + (voff)[_i]), (PG8_LAS unsigned*)(lds + (bufoff) + ldsw + _i * 8192), 16, 0, 0); } while (0)
; #define PG8_LDA(dst, b, h) do { _Pragma("unroll") for (int m = 0; m < 4; ++m) _Pragma("unroll") for (int k = 0; k < 2; ++k) dst[m][k] = *(const PG8_LAS bf16x8*)(lds + PG8_SA(b, h) + aoff + m * 2048 + k * 1024); } while (0)
; #define PG8_LDB(dst, b, h) do { _Pragma("unroll") for (int n = 0; n < 2; ++n) _Pragma("unroll") for (int k = 0; k < 2; ++k) dst[n][k] = *(const PG8_LAS bf16x8*)(lds + PG8_SB(b, h) + boff + n * 2048 + k * 1024); } while (0)
; #define PG8_MMA(ai, bj, At, Bt) do { __builtin_amdgcn_s_setprio(1); _Pragma("unroll") for (int m = 0; m < 4; ++m) _Pragma("unroll") for (int n = 0; n < 2; ++n) _Pragma("unroll") for (int k = 0; k < 2; ++k) \
;         acc[ai][bj][m][n] = __builtin_amdgcn_mfma_f32_16x16x32_bf16(Bt[n][k], At[m][k], acc[ai][bj][m][n], 0, 0, 0); __builtin_amdgcn_s_setprio(0); } while (0)
; #define PG8_WAIT_V(n) asm volatile("s_waitcnt vmcnt(" #n ")" ::: "memory")
; template <class Epi, class Sched, bool ALIGN_EPI = false, bool SP2 = false>
; __device__ __forceinline__ void gemm_phase(PG8_LAS unsigned char* lds, const Gemm g, const Sched& S, const Epi& E) {
;     ...
;             PG8_LDB(B0, 0, 0); PG8_LDB(B1, 0, 1); PG8_SCHED; PG8_LDA(At, 0, 0); PG8_STAGE(PG8_SA(1, 1), a1 + hstep, voffA);
;             PG8_WAIT_V(8); PG8_WAIT_L(0); PG8_BAR; PG8_MMA(0, 0, At, B0); PG8_MMA(0, 1, At, B1); PG8_BAR; PG8_SCHED;
;             PG8_LDA(At, 0, 1); PG8_STAGE(PG8_SB(0, 0), b2, voffB); PG8_STAGE(PG8_SB(0, 1), b2 + hstep, voffB); PG8_STAGE(PG8_SA(0, 0), a2, voffA);
;             PG8_WAIT_V(8); PG8_WAIT_L(0); PG8_BAR; PG8_MMA(1, 0, At, B0); PG8_MMA(1, 1, At, B1); PG8_BAR; PG8_SCHED;
;             PG8_LDB(B0, 1, 0); PG8_LDB(B1, 1, 1); PG8_SCHED; PG8_LDA(At, 1, 0); PG8_STAGE(PG8_SA(0, 1), a2 + hstep, voffA);
;             PG8_WAIT_V(8); PG8_WAIT_L(0); PG8_BAR; PG8_MMA(0, 0, At, B0); PG8_MMA(0, 1, At, B1); PG8_BAR; PG8_SCHED;
;             PG8_LDA(At, 1, 1); PG8_STAGE(PG8_SB(1, 0), b3, voffB); PG8_STAGE(PG8_SB(1, 1), b3 + hstep, voffB); PG8_STAGE(PG8_SA(1, 0), a3, voffA);
;             PG8_WAIT_V(8); PG8_WAIT_L(0); PG8_BAR; PG8_MMA(1, 0, At, B0); PG8_MMA(1, 1, At, B1); PG8_BAR; PG8_SCHED;
	s_add_i32 s3, s3, s34
	v_lshl_add_u64 v[178:179], v[178:179], 0, s[8:9]
	s_mov_b32 m0, s3
	ds_read_b128 v[198:201], v171 offset:49152
	ds_read_b128 v[208:211], v171 offset:50176
	ds_read_b128 v[212:215], v171 offset:51200
	ds_read_b128 v[216:219], v171 offset:52224
	ds_read_b128 v[220:223], v171 offset:53248
	ds_read_b128 v[224:227], v171 offset:54272
	ds_read_b128 v[228:231], v171 offset:55296
	ds_read_b128 v[232:235], v171 offset:56320
	global_load_lds_dwordx4 v[178:179], off
	s_add_i32 m0, s3, 0x2000
	s_add_u32 s14, s56, 0x40080
	v_lshl_add_u64 v[178:179], v[202:203], 0, s[8:9]
	s_addc_u32 s15, s57, 0
	s_add_i32 s3, s33, s34
	global_load_lds_dwordx4 v[178:179], off
	v_lshl_add_u64 v[178:179], s[14:15], 0, v[132:133]
	s_mov_b32 m0, s3
	s_nop 0
	global_load_lds_dwordx4 v[178:179], off
	v_lshl_add_u64 v[178:179], s[14:15], 0, v[128:129]
	s_add_i32 m0, s3, 0x2000
	s_nop 0
	global_load_lds_dwordx4 v[178:179], off
	s_waitcnt vmcnt(6)
	s_waitcnt lgkmcnt(0)
	s_barrier
	s_setprio 1
	s_waitcnt lgkmcnt(0)
	v_mfma_f32_16x16x32_bf16 v[92:95], v[154:157], v[198:201], v[92:95]
	v_mfma_f32_16x16x32_bf16 v[80:83], v[162:165], v[212:215], v[80:83]
	v_mfma_f32_16x16x32_bf16 v[76:79], v[154:157], v[220:223], v[76:79]
	v_mfma_f32_16x16x32_bf16 v[56:59], v[162:165], v[228:231], v[56:59]
	v_mfma_f32_16x16x32_bf16 v[84:87], v[154:157], v[212:215], v[84:87]
	v_mfma_f32_16x16x32_bf16 v[88:91], v[162:165], v[198:201], v[88:91]
	v_mfma_f32_16x16x32_bf16 v[60:63], v[154:157], v[228:231], v[60:63]
	v_mfma_f32_16x16x32_bf16 v[72:75], v[162:165], v[220:223], v[72:75]
	v_mfma_f32_16x16x32_bf16 v[92:95], v[158:161], v[208:211], v[92:95]
	v_mfma_f32_16x16x32_bf16 v[80:83], v[174:177], v[216:219], v[80:83]
	v_mfma_f32_16x16x32_bf16 v[76:79], v[158:161], v[224:227], v[76:79]
	v_mfma_f32_16x16x32_bf16 v[56:59], v[174:177], v[232:235], v[56:59]
	v_mfma_f32_16x16x32_bf16 v[84:87], v[158:161], v[216:219], v[84:87]
	v_mfma_f32_16x16x32_bf16 v[88:91], v[174:177], v[208:211], v[88:91]
	v_lshl_add_u64 v[178:179], v[236:237], 0, s[8:9]
	s_mov_b32 m0, s66
	s_nop 0
	global_load_lds_dwordx4 v[178:179], off
	v_mfma_f32_16x16x32_bf16 v[60:63], v[158:161], v[232:235], v[60:63]
	v_mfma_f32_16x16x32_bf16 v[72:75], v[174:177], v[224:227], v[72:75]
	s_setprio 0
	s_setprio 1
	v_mfma_f32_16x16x32_bf16 v[28:31], v[182:185], v[198:201], v[28:31]
	v_mfma_f32_16x16x32_bf16 v[16:19], v[190:193], v[212:215], v[16:19]
	v_mfma_f32_16x16x32_bf16 v[12:15], v[182:185], v[220:223], v[12:15]
	v_mfma_f32_16x16x32_bf16 v[0:3], v[190:193], v[228:231], v[0:3]
	v_mfma_f32_16x16x32_bf16 v[20:23], v[182:185], v[212:215], v[20:23]
	v_mfma_f32_16x16x32_bf16 v[24:27], v[190:193], v[198:201], v[24:27]
	v_mfma_f32_16x16x32_bf16 v[4:7], v[182:185], v[228:231], v[4:7]
	v_mfma_f32_16x16x32_bf16 v[8:11], v[190:193], v[220:223], v[8:11]
	v_mfma_f32_16x16x32_bf16 v[28:31], v[186:189], v[208:211], v[28:31]
	v_mfma_f32_16x16x32_bf16 v[16:19], v[194:197], v[216:219], v[16:19]
	v_mfma_f32_16x16x32_bf16 v[12:15], v[186:189], v[224:227], v[12:15]
	v_mfma_f32_16x16x32_bf16 v[0:3], v[194:197], v[232:235], v[0:3]
	v_mfma_f32_16x16x32_bf16 v[20:23], v[186:189], v[216:219], v[20:23]
	v_mfma_f32_16x16x32_bf16 v[24:27], v[194:197], v[208:211], v[24:27]
	v_lshl_add_u64 v[178:179], v[238:239], 0, s[8:9]
	s_mov_b32 m0, s67
	s_nop 0
	global_load_lds_dwordx4 v[178:179], off
	v_mfma_f32_16x16x32_bf16 v[4:7], v[186:189], v[232:235], v[4:7]
	v_mfma_f32_16x16x32_bf16 v[8:11], v[194:197], v[224:227], v[8:11]
	s_setprio 0
	s_barrier
	s_add_i32 s93, s93, 2
	s_add_u32 s54, s54, 0x100
	s_addc_u32 s55, s55, 0
	s_add_u32 s91, s91, 0x100
	s_addc_u32 s92, s92, 0
.LBB0_417:
	ds_read_b128 v[154:157], v169
	ds_read_b128 v[158:161], v169 offset:1024
	ds_read_b128 v[162:165], v169 offset:2048
	ds_read_b128 v[174:177], v169 offset:3072
	ds_read_b128 v[182:185], v170
	ds_read_b128 v[186:189], v170 offset:1024
	ds_read_b128 v[190:193], v170 offset:2048
	ds_read_b128 v[194:197], v170 offset:3072
	s_add_u32 s3, s54, 0xfffc0080
	s_addc_u32 s14, s55, -1
	s_cmp_eq_u32 s93, 12
	s_cselect_b32 s59, s45, s14
	s_cselect_b32 s58, s89, s3
	s_cselect_b32 s57, s41, s92
	s_cselect_b32 s56, s90, s91
	v_lshl_add_u64 v[178:179], s[54:55], 0, v[146:147]
	s_add_i32 m0, s60, 0xc000
	ds_read_b128 v[198:201], v171
	ds_read_b128 v[208:211], v171 offset:1024
	ds_read_b128 v[212:215], v171 offset:2048
	ds_read_b128 v[216:219], v171 offset:3072
	ds_read_b128 v[220:223], v171 offset:4096
	ds_read_b128 v[224:227], v171 offset:5120
	ds_read_b128 v[228:231], v171 offset:6144
	ds_read_b128 v[232:235], v171 offset:7168
	global_load_lds_dwordx4 v[178:179], off
	v_lshl_add_u64 v[178:179], s[54:55], 0, v[148:149]
	s_add_i32 m0, s60, 0xe000
	s_nop 0
	global_load_lds_dwordx4 v[178:179], off
	s_waitcnt vmcnt(8)
	s_waitcnt lgkmcnt(0)
	s_barrier
; #define PG8_STAGE(bufoff, gbase, voff) do { _Pragma("unroll") for (int _i = 0; _i < 2; ++_i) \
;         __builtin_amdgcn_global_load_lds((const unsigned*)((const char*)(gbase) + (voff)[_i]), (PG8_LAS unsigned*)(lds + (bufoff) + ldsw + _i * 8192), 16, 0, 0); } while (0)
; #define PG8_LDA(dst, b, h) do { _Pragma("unroll") for (int m = 0; m < 4; ++m) _Pragma("unroll") for (int k = 0; k < 2; ++k) dst[m][k] = *(const PG8_LAS bf16x8*)(lds + PG8_SA(b, h) + aoff + m * 2048 + k * 1024); } while (0)
; #define PG8_LDB(dst, b, h) do { _Pragma("unroll") for (int n = 0; n < 2; ++n) _Pragma("unroll") for (int k = 0; k < 2; ++k) dst[n][k] = *(const PG8_LAS bf16x8*)(lds + PG8_SB(b, h) + boff + n * 2048 + k * 1024); } while (0)
; #define PG8_MMA(ai, bj, At, Bt) do { __builtin_amdgcn_s_setprio(1); _Pragma("unroll") for (int m = 0; m < 4; ++m) _Pragma("unroll") for (int n = 0; n < 2; ++n) _Pragma("unroll") for (int k = 0; k < 2; ++k) \
;         acc[ai][bj][m][n] = __builtin_amdgcn_mfma_f32_16x16x32_bf16(Bt[n][k], At[m][k], acc[ai][bj][m][n], 0, 0, 0); __builtin_amdgcn_s_setprio(0); } while (0)
; #define PG8_WAIT_V(n) asm volatile("s_waitcnt vmcnt(" #n ")" ::: "memory")
; #define PG8_WAIT_L(n) asm volatile("s_waitcnt lgkmcnt(" #n ")" ::: "memory")
; #define PG8_BAR __builtin_amdgcn_s_barrier()
; #define PG8_SCHED __builtin_amdgcn_sched_barrier(0)
; template <class Epi, class Sched, bool ALIGN_EPI = false, bool SP2 = false>
; __device__ __forceinline__ void gemm_phase(PG8_LAS unsigned char* lds, const Gemm g, const Sched& S, const Epi& E) {
;     ...
;             PG8_LDB(B0, 0, 0); PG8_LDB(B1, 0, 1); PG8_SCHED; PG8_LDA(At, 0, 0); PG8_STAGE(PG8_SA(1, 1), a1 + hstep, voffA);
;             PG8_WAIT_V(8); PG8_WAIT_L(0); PG8_BAR; PG8_MMA(0, 0, At, B0); PG8_MMA(0, 1, At, B1); PG8_BAR; PG8_SCHED;
;             PG8_LDA(At, 0, 1); PG8_STAGE(PG8_SB(0, 0), b2, voffB); PG8_STAGE(PG8_SB(0, 1), b2 + hstep, voffB); PG8_STAGE(PG8_SA(0, 0), a2, voffA);
;             PG8_WAIT_V(8); PG8_WAIT_L(0); PG8_BAR; PG8_MMA(1, 0, At, B0); PG8_MMA(1, 1, At, B1); PG8_BAR; PG8_SCHED;
	s_setprio 1
	s_waitcnt lgkmcnt(0)
	v_mfma_f32_16x16x32_bf16 v[124:127], v[154:157], v[198:201], v[124:127]
	v_mfma_f32_16x16x32_bf16 v[112:115], v[162:165], v[212:215], v[112:115]
	v_mfma_f32_16x16x32_bf16 v[108:111], v[154:157], v[220:223], v[108:111]
	v_mfma_f32_16x16x32_bf16 v[96:99], v[162:165], v[228:231], v[96:99]
	v_mfma_f32_16x16x32_bf16 v[116:119], v[154:157], v[212:215], v[116:119]
	v_mfma_f32_16x16x32_bf16 v[120:123], v[162:165], v[198:201], v[120:123]
	v_mfma_f32_16x16x32_bf16 v[100:103], v[154:157], v[228:231], v[100:103]
	v_mfma_f32_16x16x32_bf16 v[104:107], v[162:165], v[220:223], v[104:107]
	v_mfma_f32_16x16x32_bf16 v[124:127], v[158:161], v[208:211], v[124:127]
	v_mfma_f32_16x16x32_bf16 v[112:115], v[174:177], v[216:219], v[112:115]
	v_mfma_f32_16x16x32_bf16 v[108:111], v[158:161], v[224:227], v[108:111]
	v_mfma_f32_16x16x32_bf16 v[96:99], v[174:177], v[232:235], v[96:99]
	v_mfma_f32_16x16x32_bf16 v[116:119], v[158:161], v[216:219], v[116:119]
	v_mfma_f32_16x16x32_bf16 v[120:123], v[174:177], v[208:211], v[120:123]
	v_mfma_f32_16x16x32_bf16 v[100:103], v[158:161], v[232:235], v[100:103]
	v_mfma_f32_16x16x32_bf16 v[104:107], v[174:177], v[224:227], v[104:107]
	s_setprio 0
	s_setprio 1
	v_mfma_f32_16x16x32_bf16 v[68:71], v[182:185], v[198:201], v[68:71]
	v_mfma_f32_16x16x32_bf16 v[48:51], v[190:193], v[212:215], v[48:51]
	v_mfma_f32_16x16x32_bf16 v[44:47], v[182:185], v[220:223], v[44:47]
	v_mfma_f32_16x16x32_bf16 v[32:35], v[190:193], v[228:231], v[32:35]
	v_mfma_f32_16x16x32_bf16 v[52:55], v[182:185], v[212:215], v[52:55]
	v_mfma_f32_16x16x32_bf16 v[64:67], v[190:193], v[198:201], v[64:67]
	v_mfma_f32_16x16x32_bf16 v[36:39], v[182:185], v[228:231], v[36:39]
	v_mfma_f32_16x16x32_bf16 v[40:43], v[190:193], v[220:223], v[40:43]
	v_mfma_f32_16x16x32_bf16 v[68:71], v[186:189], v[208:211], v[68:71]
	v_mfma_f32_16x16x32_bf16 v[48:51], v[194:197], v[216:219], v[48:51]
	v_mfma_f32_16x16x32_bf16 v[44:47], v[186:189], v[224:227], v[44:47]
	v_mfma_f32_16x16x32_bf16 v[32:35], v[194:197], v[232:235], v[32:35]
	v_mfma_f32_16x16x32_bf16 v[52:55], v[186:189], v[216:219], v[52:55]
	v_mfma_f32_16x16x32_bf16 v[64:67], v[194:197], v[208:211], v[64:67]
	v_mfma_f32_16x16x32_bf16 v[36:39], v[186:189], v[232:235], v[36:39]
	v_mfma_f32_16x16x32_bf16 v[40:43], v[194:197], v[224:227], v[40:43]
	s_setprio 0
	s_barrier
	s_add_i32 s3, s86, s34
	v_lshl_add_u64 v[178:179], s[56:57], 0, v[132:133]
	s_mov_b32 m0, s3
	ds_read_b128 v[198:201], v171 offset:16384
	ds_read_b128 v[208:211], v171 offset:17408
	ds_read_b128 v[212:215], v171 offset:18432
	ds_read_b128 v[216:219], v171 offset:19456
	ds_read_b128 v[220:223], v171 offset:20480
	ds_read_b128 v[224:227], v171 offset:21504
	ds_read_b128 v[228:231], v171 offset:22528
	ds_read_b128 v[232:235], v171 offset:23552
	global_load_lds_dwordx4 v[178:179], off
	s_add_i32 m0, s3, 0x2000
	s_add_u32 s14, s56, 0x40000
	v_lshl_add_u64 v[202:203], s[56:57], 0, v[128:129]
	s_addc_u32 s15, s57, 0
	s_add_i32 s3, s87, s34
	global_load_lds_dwordx4 v[202:203], off
	v_lshl_add_u64 v[236:237], s[14:15], 0, v[132:133]
	s_mov_b32 m0, s3
	global_load_lds_dwordx4 v[236:237], off
	v_lshl_add_u64 v[236:237], s[14:15], 0, v[128:129]
	s_add_i32 m0, s3, 0x2000
	s_nop 0
	global_load_lds_dwordx4 v[236:237], off
	s_waitcnt vmcnt(6)
	s_waitcnt lgkmcnt(0)
	s_barrier
	s_setprio 1
	s_waitcnt lgkmcnt(0)
	v_mfma_f32_16x16x32_bf16 v[92:95], v[154:157], v[198:201], v[92:95]
	v_mfma_f32_16x16x32_bf16 v[80:83], v[162:165], v[212:215], v[80:83]
	v_mfma_f32_16x16x32_bf16 v[76:79], v[154:157], v[220:223], v[76:79]
	v_mfma_f32_16x16x32_bf16 v[56:59], v[162:165], v[228:231], v[56:59]
	v_mfma_f32_16x16x32_bf16 v[84:87], v[154:157], v[212:215], v[84:87]
	v_mfma_f32_16x16x32_bf16 v[88:91], v[162:165], v[198:201], v[88:91]
	v_mfma_f32_16x16x32_bf16 v[60:63], v[154:157], v[228:231], v[60:63]
	v_mfma_f32_16x16x32_bf16 v[72:75], v[162:165], v[220:223], v[72:75]
	v_mfma_f32_16x16x32_bf16 v[92:95], v[158:161], v[208:211], v[92:95]
	v_mfma_f32_16x16x32_bf16 v[80:83], v[174:177], v[216:219], v[80:83]
	v_mfma_f32_16x16x32_bf16 v[76:79], v[158:161], v[224:227], v[76:79]
	v_mfma_f32_16x16x32_bf16 v[56:59], v[174:177], v[232:235], v[56:59]
	v_mfma_f32_16x16x32_bf16 v[84:87], v[158:161], v[216:219], v[84:87]
	v_mfma_f32_16x16x32_bf16 v[88:91], v[174:177], v[208:211], v[88:91]
	v_lshl_add_u64 v[236:237], s[58:59], 0, v[134:135]
	s_mov_b32 m0, s60
	s_nop 0
	global_load_lds_dwordx4 v[236:237], off
	v_mfma_f32_16x16x32_bf16 v[60:63], v[158:161], v[232:235], v[60:63]
	v_mfma_f32_16x16x32_bf16 v[72:75], v[174:177], v[224:227], v[72:75]
	s_setprio 0
	s_setprio 1
	v_mfma_f32_16x16x32_bf16 v[28:31], v[182:185], v[198:201], v[28:31]
	v_mfma_f32_16x16x32_bf16 v[16:19], v[190:193], v[212:215], v[16:19]
	v_mfma_f32_16x16x32_bf16 v[12:15], v[182:185], v[220:223], v[12:15]
	v_mfma_f32_16x16x32_bf16 v[0:3], v[190:193], v[228:231], v[0:3]
	v_mfma_f32_16x16x32_bf16 v[20:23], v[182:185], v[212:215], v[20:23]
	v_mfma_f32_16x16x32_bf16 v[24:27], v[190:193], v[198:201], v[24:27]
	v_mfma_f32_16x16x32_bf16 v[4:7], v[182:185], v[228:231], v[4:7]
	v_mfma_f32_16x16x32_bf16 v[8:11], v[190:193], v[220:223], v[8:11]
	v_mfma_f32_16x16x32_bf16 v[28:31], v[186:189], v[208:211], v[28:31]
	v_mfma_f32_16x16x32_bf16 v[16:19], v[194:197], v[216:219], v[16:19]
	v_mfma_f32_16x16x32_bf16 v[12:15], v[186:189], v[224:227], v[12:15]
	v_mfma_f32_16x16x32_bf16 v[0:3], v[194:197], v[232:235], v[0:3]
	v_mfma_f32_16x16x32_bf16 v[20:23], v[186:189], v[216:219], v[20:23]
	v_mfma_f32_16x16x32_bf16 v[24:27], v[194:197], v[208:211], v[24:27]
	v_lshl_add_u64 v[238:239], s[58:59], 0, v[130:131]
	s_mov_b32 m0, s61
	s_nop 0
	global_load_lds_dwordx4 v[238:239], off
	v_mfma_f32_16x16x32_bf16 v[4:7], v[186:189], v[232:235], v[4:7]
	v_mfma_f32_16x16x32_bf16 v[8:11], v[194:197], v[224:227], v[8:11]
	s_setprio 0
	s_barrier
; #define PG8_STAGE(bufoff, gbase, voff) do { _Pragma("unroll") for (int _i = 0; _i < 2; ++_i) \
;         __builtin_amdgcn_global_load_lds((const unsigned*)((const char*)(gbase) + (voff)[_i]), (PG8_LAS unsigned*)(lds + (bufoff) + ldsw + _i * 8192), 16, 0, 0); } while (0)
; #define PG8_LDA(dst, b, h) do { _Pragma("unroll") for (int m = 0; m < 4; ++m) _Pragma("unroll") for (int k = 0; k < 2; ++k) dst[m][k] = *(const PG8_LAS bf16x8*)(lds + PG8_SA(b, h) + aoff + m * 2048 + k * 1024); } while (0)
; #define PG8_LDB(dst, b, h) do { _Pragma("unroll") for (int n = 0; n < 2; ++n) _Pragma("unroll") for (int k = 0; k < 2; ++k) dst[n][k] = *(const PG8_LAS bf16x8*)(lds + PG8_SB(b, h) + boff + n * 2048 + k * 1024); } while (0)
; #define PG8_MMA(ai, bj, At, Bt) do { __builtin_amdgcn_s_setprio(1); _Pragma("unroll") for (int m = 0; m < 4; ++m) _Pragma("unroll") for (int n = 0; n < 2; ++n) _Pragma("unroll") for (int k = 0; k < 2; ++k) \
;         acc[ai][bj][m][n] = __builtin_amdgcn_mfma_f32_16x16x32_bf16(Bt[n][k], At[m][k], acc[ai][bj][m][n], 0, 0, 0); __builtin_amdgcn_s_setprio(0); } while (0)
; #define PG8_WAIT_V(n) asm volatile("s_waitcnt vmcnt(" #n ")" ::: "memory")
; #define PG8_WAIT_L(n) asm volatile("s_waitcnt lgkmcnt(" #n ")" ::: "memory")
; #define PG8_BAR __builtin_amdgcn_s_barrier()
; #define PG8_SCHED __builtin_amdgcn_sched_barrier(0)
; template <class Epi, class Sched, bool ALIGN_EPI = false, bool SP2 = false>
; __device__ __forceinline__ void gemm_phase(PG8_LAS unsigned char* lds, const Gemm g, const Sched& S, const Epi& E) {
;     ...
;             PG8_LDB(B0, 1, 0); PG8_LDB(B1, 1, 1); PG8_SCHED; PG8_LDA(At, 1, 0); PG8_STAGE(PG8_SA(0, 1), a2 + hstep, voffA);
;             PG8_WAIT_V(8); PG8_WAIT_L(0); PG8_BAR; PG8_MMA(0, 0, At, B0); PG8_MMA(0, 1, At, B1); PG8_BAR; PG8_SCHED;
	s_add_i32 s3, 0, 0x18000
	v_add_u32_e32 v136, s3, v143
	s_add_i32 s33, 0, 0x1c000
	ds_read_b128 v[154:157], v136
	ds_read_b128 v[158:161], v136 offset:1024
	ds_read_b128 v[162:165], v136 offset:2048
	ds_read_b128 v[174:177], v136 offset:3072
	v_add_u32_e32 v136, s33, v143
	ds_read_b128 v[182:185], v136
	ds_read_b128 v[186:189], v136 offset:1024
	ds_read_b128 v[190:193], v136 offset:2048
	ds_read_b128 v[194:197], v136 offset:3072
	s_add_u32 s14, s58, 0x40000
	s_addc_u32 s15, s59, 0
	s_mov_b32 m0, s62
	v_lshl_add_u64 v[240:241], s[14:15], 0, v[134:135]
	ds_read_b128 v[198:201], v171 offset:32768
	ds_read_b128 v[208:211], v171 offset:33792
	ds_read_b128 v[212:215], v171 offset:34816
	ds_read_b128 v[216:219], v171 offset:35840
	ds_read_b128 v[220:223], v171 offset:36864
	ds_read_b128 v[224:227], v171 offset:37888
	ds_read_b128 v[228:231], v171 offset:38912
	ds_read_b128 v[232:235], v171 offset:39936
	global_load_lds_dwordx4 v[240:241], off
	v_lshl_add_u64 v[240:241], s[14:15], 0, v[130:131]
	s_mov_b32 m0, s63
	s_nop 0
	global_load_lds_dwordx4 v[240:241], off
	s_waitcnt vmcnt(8)
	s_waitcnt lgkmcnt(0)
	s_barrier
	s_setprio 1
	s_waitcnt lgkmcnt(0)
	v_mfma_f32_16x16x32_bf16 v[124:127], v[154:157], v[198:201], v[124:127]
	v_mfma_f32_16x16x32_bf16 v[112:115], v[162:165], v[212:215], v[112:115]
	v_mfma_f32_16x16x32_bf16 v[108:111], v[154:157], v[220:223], v[108:111]
	v_mfma_f32_16x16x32_bf16 v[96:99], v[162:165], v[228:231], v[96:99]
	v_mfma_f32_16x16x32_bf16 v[116:119], v[154:157], v[212:215], v[116:119]
	v_mfma_f32_16x16x32_bf16 v[120:123], v[162:165], v[198:201], v[120:123]
	v_mfma_f32_16x16x32_bf16 v[100:103], v[154:157], v[228:231], v[100:103]
	v_mfma_f32_16x16x32_bf16 v[104:107], v[162:165], v[220:223], v[104:107]
	v_mfma_f32_16x16x32_bf16 v[124:127], v[158:161], v[208:211], v[124:127]
	v_mfma_f32_16x16x32_bf16 v[112:115], v[174:177], v[216:219], v[112:115]
	v_mfma_f32_16x16x32_bf16 v[108:111], v[158:161], v[224:227], v[108:111]
	v_mfma_f32_16x16x32_bf16 v[96:99], v[174:177], v[232:235], v[96:99]
	v_mfma_f32_16x16x32_bf16 v[116:119], v[158:161], v[216:219], v[116:119]
	v_mfma_f32_16x16x32_bf16 v[120:123], v[174:177], v[208:211], v[120:123]
	v_mfma_f32_16x16x32_bf16 v[100:103], v[158:161], v[232:235], v[100:103]
	v_mfma_f32_16x16x32_bf16 v[104:107], v[174:177], v[224:227], v[104:107]
	s_setprio 0
	s_setprio 1
	v_mfma_f32_16x16x32_bf16 v[68:71], v[182:185], v[198:201], v[68:71]
	v_mfma_f32_16x16x32_bf16 v[48:51], v[190:193], v[212:215], v[48:51]
	v_mfma_f32_16x16x32_bf16 v[44:47], v[182:185], v[220:223], v[44:47]
	v_mfma_f32_16x16x32_bf16 v[32:35], v[190:193], v[228:231], v[32:35]
	v_mfma_f32_16x16x32_bf16 v[52:55], v[182:185], v[212:215], v[52:55]
	v_mfma_f32_16x16x32_bf16 v[64:67], v[190:193], v[198:201], v[64:67]
	v_mfma_f32_16x16x32_bf16 v[36:39], v[182:185], v[228:231], v[36:39]
	v_mfma_f32_16x16x32_bf16 v[40:43], v[190:193], v[220:223], v[40:43]
	v_mfma_f32_16x16x32_bf16 v[68:71], v[186:189], v[208:211], v[68:71]
	v_mfma_f32_16x16x32_bf16 v[48:51], v[194:197], v[216:219], v[48:51]
	v_mfma_f32_16x16x32_bf16 v[44:47], v[186:189], v[224:227], v[44:47]
	v_mfma_f32_16x16x32_bf16 v[32:35], v[194:197], v[232:235], v[32:35]
	v_mfma_f32_16x16x32_bf16 v[52:55], v[186:189], v[216:219], v[52:55]
	v_mfma_f32_16x16x32_bf16 v[64:67], v[194:197], v[208:211], v[64:67]
	v_mfma_f32_16x16x32_bf16 v[36:39], v[186:189], v[232:235], v[36:39]
	v_mfma_f32_16x16x32_bf16 v[40:43], v[194:197], v[224:227], v[40:43]
	s_setprio 0
	s_barrier
; #define PG8_STAGE(bufoff, gbase, voff) do { _Pragma("unroll") for (int _i = 0; _i < 2; ++_i) \
;         __builtin_amdgcn_global_load_lds((const unsigned*)((const char*)(gbase) + (voff)[_i]), (PG8_LAS unsigned*)(lds + (bufoff) + ldsw + _i * 8192), 16, 0, 0); } while (0)
; #define PG8_LDA(dst, b, h) do { _Pragma("unroll") for (int m = 0; m < 4; ++m) _Pragma("unroll") for (int k = 0; k < 2; ++k) dst[m][k] = *(const PG8_LAS bf16x8*)(lds + PG8_SA(b, h) + aoff + m * 2048 + k * 1024); } while (0)
; #define PG8_MMA(ai, bj, At, Bt) do { __builtin_amdgcn_s_setprio(1); _Pragma("unroll") for (int m = 0; m < 4; ++m) _Pragma("unroll") for (int n = 0; n < 2; ++n) _Pragma("unroll") for (int k = 0; k < 2; ++k) \
;         acc[ai][bj][m][n] = __builtin_amdgcn_mfma_f32_16x16x32_bf16(Bt[n][k], At[m][k], acc[ai][bj][m][n], 0, 0, 0); __builtin_amdgcn_s_setprio(0); } while (0)
; #define PG8_WAIT_V(n) asm volatile("s_waitcnt vmcnt(" #n ")" ::: "memory")
; #define PG8_WAIT_L(n) asm volatile("s_waitcnt lgkmcnt(" #n ")" ::: "memory")
; #define PG8_BAR __builtin_amdgcn_s_barrier()
; #define PG8_SCHED __builtin_amdgcn_sched_barrier(0)
; template <class Epi, class Sched, bool ALIGN_EPI = false, bool SP2 = false>
; __device__ __forceinline__ void gemm_phase(PG8_LAS unsigned char* lds, const Gemm g, const Sched& S, const Epi& E) {
;     ...
;             PG8_LDA(At, 1, 1); PG8_STAGE(PG8_SB(1, 0), b3, voffB); PG8_STAGE(PG8_SB(1, 1), b3 + hstep, voffB); PG8_STAGE(PG8_SA(1, 0), a3, voffA);
;             PG8_WAIT_V(8); PG8_WAIT_L(0); PG8_BAR; PG8_MMA(1, 0, At, B0); PG8_MMA(1, 1, At, B1); PG8_BAR; PG8_SCHED;
	s_add_i32 s3, s3, s34
	v_lshl_add_u64 v[178:179], v[178:179], 0, s[8:9]
	s_mov_b32 m0, s3
	ds_read_b128 v[198:201], v171 offset:49152
	ds_read_b128 v[208:211], v171 offset:50176
	ds_read_b128 v[212:215], v171 offset:51200
	ds_read_b128 v[216:219], v171 offset:52224
	ds_read_b128 v[220:223], v171 offset:53248
	ds_read_b128 v[224:227], v171 offset:54272
	ds_read_b128 v[228:231], v171 offset:55296
	ds_read_b128 v[232:235], v171 offset:56320
	global_load_lds_dwordx4 v[178:179], off
	s_add_i32 m0, s3, 0x2000
	s_add_u32 s14, s56, 0x40080
	v_lshl_add_u64 v[178:179], v[202:203], 0, s[8:9]
	s_addc_u32 s15, s57, 0
	s_add_i32 s3, s33, s34
	global_load_lds_dwordx4 v[178:179], off
	v_lshl_add_u64 v[178:179], s[14:15], 0, v[132:133]
	s_mov_b32 m0, s3
	s_nop 0
	global_load_lds_dwordx4 v[178:179], off
	v_lshl_add_u64 v[178:179], s[14:15], 0, v[128:129]
	s_add_i32 m0, s3, 0x2000
	s_nop 0
	global_load_lds_dwordx4 v[178:179], off
	s_waitcnt vmcnt(6)
	s_waitcnt lgkmcnt(0)
	s_barrier
	s_setprio 1
	s_waitcnt lgkmcnt(0)
	v_mfma_f32_16x16x32_bf16 v[92:95], v[154:157], v[198:201], v[92:95]
	v_mfma_f32_16x16x32_bf16 v[80:83], v[162:165], v[212:215], v[80:83]
	v_mfma_f32_16x16x32_bf16 v[76:79], v[154:157], v[220:223], v[76:79]
	v_mfma_f32_16x16x32_bf16 v[56:59], v[162:165], v[228:231], v[56:59]
	v_mfma_f32_16x16x32_bf16 v[84:87], v[154:157], v[212:215], v[84:87]
	v_mfma_f32_16x16x32_bf16 v[88:91], v[162:165], v[198:201], v[88:91]
	v_mfma_f32_16x16x32_bf16 v[60:63], v[154:157], v[228:231], v[60:63]
	v_mfma_f32_16x16x32_bf16 v[72:75], v[162:165], v[220:223], v[72:75]
	v_mfma_f32_16x16x32_bf16 v[92:95], v[158:161], v[208:211], v[92:95]
	v_mfma_f32_16x16x32_bf16 v[80:83], v[174:177], v[216:219], v[80:83]
	v_mfma_f32_16x16x32_bf16 v[76:79], v[158:161], v[224:227], v[76:79]
	v_mfma_f32_16x16x32_bf16 v[56:59], v[174:177], v[232:235], v[56:59]
	v_mfma_f32_16x16x32_bf16 v[84:87], v[158:161], v[216:219], v[84:87]
	v_mfma_f32_16x16x32_bf16 v[88:91], v[174:177], v[208:211], v[88:91]
	v_lshl_add_u64 v[178:179], v[236:237], 0, s[8:9]
	s_mov_b32 m0, s66
	s_nop 0
	global_load_lds_dwordx4 v[178:179], off
	v_mfma_f32_16x16x32_bf16 v[60:63], v[158:161], v[232:235], v[60:63]
	v_mfma_f32_16x16x32_bf16 v[72:75], v[174:177], v[224:227], v[72:75]
	s_setprio 0
	s_setprio 1
	v_mfma_f32_16x16x32_bf16 v[28:31], v[182:185], v[198:201], v[28:31]
	v_mfma_f32_16x16x32_bf16 v[16:19], v[190:193], v[212:215], v[16:19]
	v_mfma_f32_16x16x32_bf16 v[12:15], v[182:185], v[220:223], v[12:15]
	v_mfma_f32_16x16x32_bf16 v[0:3], v[190:193], v[228:231], v[0:3]
	v_mfma_f32_16x16x32_bf16 v[20:23], v[182:185], v[212:215], v[20:23]
	v_mfma_f32_16x16x32_bf16 v[24:27], v[190:193], v[198:201], v[24:27]
	v_mfma_f32_16x16x32_bf16 v[4:7], v[182:185], v[228:231], v[4:7]
	v_mfma_f32_16x16x32_bf16 v[8:11], v[190:193], v[220:223], v[8:11]
	v_mfma_f32_16x16x32_bf16 v[28:31], v[186:189], v[208:211], v[28:31]
	v_mfma_f32_16x16x32_bf16 v[16:19], v[194:197], v[216:219], v[16:19]
	v_mfma_f32_16x16x32_bf16 v[12:15], v[186:189], v[224:227], v[12:15]
	v_mfma_f32_16x16x32_bf16 v[0:3], v[194:197], v[232:235], v[0:3]
	v_mfma_f32_16x16x32_bf16 v[20:23], v[186:189], v[216:219], v[20:23]
	v_mfma_f32_16x16x32_bf16 v[24:27], v[194:197], v[208:211], v[24:27]
	v_lshl_add_u64 v[178:179], v[238:239], 0, s[8:9]
	s_mov_b32 m0, s67
	s_nop 0
	global_load_lds_dwordx4 v[178:179], off
	v_mfma_f32_16x16x32_bf16 v[4:7], v[186:189], v[232:235], v[4:7]
	v_mfma_f32_16x16x32_bf16 v[8:11], v[194:197], v[224:227], v[8:11]
	s_setprio 0
	s_barrier
	s_add_i32 s93, s93, 2
	s_add_u32 s54, s54, 0x100
	s_addc_u32 s55, s55, 0
	s_add_u32 s91, s91, 0x100
	s_addc_u32 s92, s92, 0
	s_cmp_gt_u32 s93, 13
	s_cbranch_scc0 .LBB0_417
	s_and_b64 vcc, exec, s[10:11]
	s_cbranch_vccz .LBB0_420
	s_barrier

; #define PG8_STAGE(bufoff, gbase, voff) do { _Pragma("unroll") for (int _i = 0; _i < 2; ++_i) \
;         __builtin_amdgcn_global_load_lds((const unsigned*)((const char*)(gbase) + (voff)[_i]), (PG8_LAS unsigned*)(lds + (bufoff) + ldsw + _i * 8192), 16, 0, 0); } while (0)
; #define PG8_LDA(dst, b, h) do { _Pragma("unroll") for (int m = 0; m < 4; ++m) _Pragma("unroll") for (int k = 0; k < 2; ++k) dst[m][k] = *(const PG8_LAS bf16x8*)(lds + PG8_SA(b, h) + aoff + m * 2048 + k * 1024); } while (0)
; #define PG8_LDB(dst, b, h) do { _Pragma("unroll") for (int n = 0; n < 2; ++n) _Pragma("unroll") for (int k = 0; k < 2; ++k) dst[n][k] = *(const PG8_LAS bf16x8*)(lds + PG8_SB(b, h) + boff + n * 2048 + k * 1024); } while (0)
; #define PG8_MMA(ai, bj, At, Bt) do { __builtin_amdgcn_s_setprio(1); _Pragma("unroll") for (int m = 0; m < 4; ++m) _Pragma("unroll") for (int n = 0; n < 2; ++n) _Pragma("unroll") for (int k = 0; k < 2; ++k) \
;         acc[ai][bj][m][n] = __builtin_amdgcn_mfma_f32_16x16x32_bf16(Bt[n][k], At[m][k], acc[ai][bj][m][n], 0, 0, 0); __builtin_amdgcn_s_setprio(0); } while (0)
; #define PG8_WAIT_V(n) asm volatile("s_waitcnt vmcnt(" #n ")" ::: "memory")
; template <class Epi, class Sched, bool ALIGN_EPI = false, bool SP2 = false>
; __device__ __forceinline__ void gemm_phase(PG8_LAS unsigned char* lds, const Gemm g, const Sched& S, const Epi& E) {
;     ...
;         const char* nA = has_next ? (const char*)g.A + (size_t)nxt.pm * tstep : cA; const char* nB = has_next ? (const char*)g.Bt + (size_t)nxt.pn * tstep : cB;
;         for (int t = 0; t < nt; t += 2) {
;             const bool last = (t == nt - 2);
;             const char* a1 = cA + (size_t)(t + 1) * kstep;
;             const char* a2 = last ? nA : cA + (size_t)(t + 2) * kstep; const char* b2 = last ? nB : cB + (size_t)(t + 2) * kstep;
;             const char* a3 = a2 + kstep; const char* b3 = b2 + kstep;
;             if (last && has_next) S.a_ready(nxt);
;             if constexpr (SP2) {
;             PG8_LDB(B0, 0, 0); PG8_LDB(B1, 0, 1); PG8_SCHED; PG8_LDA(At, 0, 0); PG8_STAGE(PG8_SA(1, 1), a1 + hstep, voffA);
;             PG8_WAIT_V(8); PG8_WAIT_L(0); PG8_BAR; PG8_MMA(0, 0, At, B0); PG8_MMA(0, 1, At, B1); PG8_BAR; PG8_SCHED;
;             PG8_LDA(At, 0, 1); PG8_STAGE(PG8_SB(0, 0), b2, voffB); PG8_STAGE(PG8_SB(0, 1), b2 + hstep, voffB); PG8_STAGE(PG8_SA(0, 0), a2, voffA);
.LBB0_458:
	s_ashr_i32 s49, s48, 31
	s_lshl_b64 s[14:15], s[48:49], 19
	s_add_u32 s50, s34, s14
	s_addc_u32 s51, s43, s15
	s_and_b64 s[14:15], s[40:41], exec
	s_cselect_b32 s49, s51, s59
	s_cselect_b32 s55, s50, s58
	s_ashr_i32 s45, s44, 31
	s_lshl_b64 s[14:15], s[44:45], 19
	v_readlane_b32 s3, v250, 13
	s_add_u32 s52, s3, s14
	v_readlane_b32 s3, v250, 14
	s_addc_u32 s53, s3, s15
	s_and_b64 s[14:15], s[40:41], exec
	s_cselect_b32 s45, s53, s61
	s_cselect_b32 s57, s52, s60
	s_add_u32 s58, s58, 0x40080
	s_addc_u32 s59, s59, 0
	s_add_u32 s96, s60, 0x100
	s_addc_u32 s97, s61, 0
	s_mov_b32 vcc_lo, -2
	ds_read_b128 v[170:173], v165
	ds_read_b128 v[174:177], v165 offset:1024
	ds_read_b128 v[182:185], v165 offset:2048
	ds_read_b128 v[186:189], v165 offset:3072
	ds_read_b128 v[190:193], v168
	ds_read_b128 v[194:197], v168 offset:1024
	ds_read_b128 v[198:201], v168 offset:2048
	ds_read_b128 v[208:211], v168 offset:3072
	s_add_u32 s3, s58, 0xfffc0080
	s_addc_u32 s14, s59, -1
	s_cmp_eq_u32 vcc_lo, 12
	s_cselect_b32 s63, s49, s14
	s_cselect_b32 s62, s55, s3
	s_cselect_b32 s61, s45, s97
	s_cselect_b32 s60, s57, s96
	v_lshl_add_u64 v[178:179], s[58:59], 0, v[160:161]
	s_add_i32 m0, s85, 0xc000
	ds_read_b128 v[212:215], v164
	ds_read_b128 v[216:219], v164 offset:1024
	ds_read_b128 v[220:223], v164 offset:2048
	ds_read_b128 v[224:227], v164 offset:3072
	ds_read_b128 v[228:231], v164 offset:4096
	ds_read_b128 v[232:235], v164 offset:5120
	ds_read_b128 v[236:239], v164 offset:6144
	ds_read_b128 v[240:243], v164 offset:7168
	global_load_lds_dwordx4 v[178:179], off
	v_lshl_add_u64 v[178:179], s[58:59], 0, v[162:163]
	s_add_i32 m0, s85, 0xe000
	s_nop 0
	global_load_lds_dwordx4 v[178:179], off
	s_waitcnt vmcnt(8)
	s_waitcnt lgkmcnt(0)
	s_barrier
	s_setprio 1
	s_waitcnt lgkmcnt(0)
	v_mfma_f32_16x16x32_bf16 v[124:127], v[170:173], v[212:215], 0
	v_mfma_f32_16x16x32_bf16 v[112:115], v[182:185], v[220:223], 0
	v_mfma_f32_16x16x32_bf16 v[108:111], v[170:173], v[228:231], 0
	v_mfma_f32_16x16x32_bf16 v[96:99], v[182:185], v[236:239], 0
	v_mfma_f32_16x16x32_bf16 v[116:119], v[170:173], v[220:223], 0
	v_mfma_f32_16x16x32_bf16 v[120:123], v[182:185], v[212:215], 0
	v_mfma_f32_16x16x32_bf16 v[100:103], v[170:173], v[236:239], 0
	v_mfma_f32_16x16x32_bf16 v[104:107], v[182:185], v[228:231], 0
	v_mfma_f32_16x16x32_bf16 v[124:127], v[174:177], v[216:219], v[124:127]
	v_mfma_f32_16x16x32_bf16 v[112:115], v[186:189], v[224:227], v[112:115]
	v_mfma_f32_16x16x32_bf16 v[108:111], v[174:177], v[232:235], v[108:111]
	v_mfma_f32_16x16x32_bf16 v[96:99], v[186:189], v[240:243], v[96:99]
	v_mfma_f32_16x16x32_bf16 v[116:119], v[174:177], v[224:227], v[116:119]
	v_mfma_f32_16x16x32_bf16 v[120:123], v[186:189], v[216:219], v[120:123]
	v_mfma_f32_16x16x32_bf16 v[100:103], v[174:177], v[240:243], v[100:103]
	v_mfma_f32_16x16x32_bf16 v[104:107], v[186:189], v[232:235], v[104:107]
	s_setprio 0
	s_setprio 1
	v_mfma_f32_16x16x32_bf16 v[60:63], v[190:193], v[212:215], 0
	v_mfma_f32_16x16x32_bf16 v[48:51], v[198:201], v[220:223], 0
	v_mfma_f32_16x16x32_bf16 v[44:47], v[190:193], v[228:231], 0
	v_mfma_f32_16x16x32_bf16 v[32:35], v[198:201], v[236:239], 0
	v_mfma_f32_16x16x32_bf16 v[52:55], v[190:193], v[220:223], 0
	v_mfma_f32_16x16x32_bf16 v[56:59], v[198:201], v[212:215], 0
	v_mfma_f32_16x16x32_bf16 v[36:39], v[190:193], v[236:239], 0
	v_mfma_f32_16x16x32_bf16 v[40:43], v[198:201], v[228:231], 0
	v_mfma_f32_16x16x32_bf16 v[60:63], v[194:197], v[216:219], v[60:63]
	v_mfma_f32_16x16x32_bf16 v[48:51], v[208:211], v[224:227], v[48:51]
	v_mfma_f32_16x16x32_bf16 v[44:47], v[194:197], v[232:235], v[44:47]
	v_mfma_f32_16x16x32_bf16 v[32:35], v[208:211], v[240:243], v[32:35]
	v_mfma_f32_16x16x32_bf16 v[52:55], v[194:197], v[224:227], v[52:55]
	v_mfma_f32_16x16x32_bf16 v[56:59], v[208:211], v[216:219], v[56:59]
	v_mfma_f32_16x16x32_bf16 v[36:39], v[194:197], v[240:243], v[36:39]
	v_mfma_f32_16x16x32_bf16 v[40:43], v[208:211], v[232:235], v[40:43]
	s_setprio 0
	s_barrier
	s_add_i32 s3, s94, s84
	v_lshl_add_u64 v[178:179], s[60:61], 0, v[130:131]
	s_mov_b32 m0, s3
	ds_read_b128 v[212:215], v164 offset:16384
	ds_read_b128 v[216:219], v164 offset:17408
	ds_read_b128 v[220:223], v164 offset:18432
	ds_read_b128 v[224:227], v164 offset:19456
	ds_read_b128 v[228:231], v164 offset:20480
	ds_read_b128 v[232:235], v164 offset:21504
	ds_read_b128 v[236:239], v164 offset:22528
	ds_read_b128 v[240:243], v164 offset:23552
	global_load_lds_dwordx4 v[178:179], off
	s_add_i32 m0, s3, 0x2000
	s_add_u32 s14, s60, 0x40000
	v_lshl_add_u64 v[202:203], s[60:61], 0, v[134:135]
	s_addc_u32 s15, s61, 0
	s_add_i32 s3, s95, s84
	global_load_lds_dwordx4 v[202:203], off
	v_lshl_add_u64 v[244:245], s[14:15], 0, v[130:131]
	s_mov_b32 m0, s3
	global_load_lds_dwordx4 v[244:245], off
	v_lshl_add_u64 v[244:245], s[14:15], 0, v[134:135]
	s_add_i32 m0, s3, 0x2000
	s_nop 0
	global_load_lds_dwordx4 v[244:245], off
	s_waitcnt vmcnt(6)
	s_waitcnt lgkmcnt(0)
	s_barrier
; #define PG8_STAGE(bufoff, gbase, voff) do { _Pragma("unroll") for (int _i = 0; _i < 2; ++_i) \
;         __builtin_amdgcn_global_load_lds((const unsigned*)((const char*)(gbase) + (voff)[_i]), (PG8_LAS unsigned*)(lds + (bufoff) + ldsw + _i * 8192), 16, 0, 0); } while (0)
; #define PG8_LDA(dst, b, h) do { _Pragma("unroll") for (int m = 0; m < 4; ++m) _Pragma("unroll") for (int k = 0; k < 2; ++k) dst[m][k] = *(const PG8_LAS bf16x8*)(lds + PG8_SA(b, h) + aoff + m * 2048 + k * 1024); } while (0)
; #define PG8_LDB(dst, b, h) do { _Pragma("unroll") for (int n = 0; n < 2; ++n) _Pragma("unroll") for (int k = 0; k < 2; ++k) dst[n][k] = *(const PG8_LAS bf16x8*)(lds + PG8_SB(b, h) + boff + n * 2048 + k * 1024); } while (0)
; #define PG8_MMA(ai, bj, At, Bt) do { __builtin_amdgcn_s_setprio(1); _Pragma("unroll") for (int m = 0; m < 4; ++m) _Pragma("unroll") for (int n = 0; n < 2; ++n) _Pragma("unroll") for (int k = 0; k < 2; ++k) \
;         acc[ai][bj][m][n] = __builtin_amdgcn_mfma_f32_16x16x32_bf16(Bt[n][k], At[m][k], acc[ai][bj][m][n], 0, 0, 0); __builtin_amdgcn_s_setprio(0); } while (0)
; #define PG8_WAIT_V(n) asm volatile("s_waitcnt vmcnt(" #n ")" ::: "memory")
; #define PG8_WAIT_L(n) asm volatile("s_waitcnt lgkmcnt(" #n ")" ::: "memory")
; #define PG8_BAR __builtin_amdgcn_s_barrier()
; #define PG8_SCHED __builtin_amdgcn_sched_barrier(0)
; template <class Epi, class Sched, bool ALIGN_EPI = false, bool SP2 = false>
; __device__ __forceinline__ void gemm_phase(PG8_LAS unsigned char* lds, const Gemm g, const Sched& S, const Epi& E) {
;     ...
;             PG8_WAIT_V(8); PG8_WAIT_L(0); PG8_BAR; PG8_MMA(1, 0, At, B0); PG8_MMA(1, 1, At, B1); PG8_BAR; PG8_SCHED;
;             PG8_LDB(B0, 1, 0); PG8_LDB(B1, 1, 1); PG8_SCHED; PG8_LDA(At, 1, 0); PG8_STAGE(PG8_SA(0, 1), a2 + hstep, voffA);
;             PG8_WAIT_V(8); PG8_WAIT_L(0); PG8_BAR; PG8_MMA(0, 0, At, B0); PG8_MMA(0, 1, At, B1); PG8_BAR; PG8_SCHED;
	s_setprio 1
	s_waitcnt lgkmcnt(0)
	v_mfma_f32_16x16x32_bf16 v[92:95], v[170:173], v[212:215], 0
	v_mfma_f32_16x16x32_bf16 v[80:83], v[182:185], v[220:223], 0
	v_mfma_f32_16x16x32_bf16 v[76:79], v[170:173], v[228:231], 0
	v_mfma_f32_16x16x32_bf16 v[64:67], v[182:185], v[236:239], 0
	v_mfma_f32_16x16x32_bf16 v[84:87], v[170:173], v[220:223], 0
	v_mfma_f32_16x16x32_bf16 v[88:91], v[182:185], v[212:215], 0
	v_mfma_f32_16x16x32_bf16 v[68:71], v[170:173], v[236:239], 0
	v_mfma_f32_16x16x32_bf16 v[72:75], v[182:185], v[228:231], 0
	v_mfma_f32_16x16x32_bf16 v[92:95], v[174:177], v[216:219], v[92:95]
	v_mfma_f32_16x16x32_bf16 v[80:83], v[186:189], v[224:227], v[80:83]
	v_mfma_f32_16x16x32_bf16 v[76:79], v[174:177], v[232:235], v[76:79]
	v_mfma_f32_16x16x32_bf16 v[64:67], v[186:189], v[240:243], v[64:67]
	v_mfma_f32_16x16x32_bf16 v[84:87], v[174:177], v[224:227], v[84:87]
	v_mfma_f32_16x16x32_bf16 v[88:91], v[186:189], v[216:219], v[88:91]
	v_lshl_add_u64 v[244:245], s[62:63], 0, v[128:129]
	s_mov_b32 m0, s85
	s_nop 0
	global_load_lds_dwordx4 v[244:245], off
	v_mfma_f32_16x16x32_bf16 v[68:71], v[174:177], v[240:243], v[68:71]
	v_mfma_f32_16x16x32_bf16 v[72:75], v[186:189], v[232:235], v[72:75]
	s_setprio 0
	s_setprio 1
	v_mfma_f32_16x16x32_bf16 v[28:31], v[190:193], v[212:215], 0
	v_mfma_f32_16x16x32_bf16 v[16:19], v[198:201], v[220:223], 0
	v_mfma_f32_16x16x32_bf16 v[12:15], v[190:193], v[228:231], 0
	v_mfma_f32_16x16x32_bf16 v[0:3], v[198:201], v[236:239], 0
	v_mfma_f32_16x16x32_bf16 v[20:23], v[190:193], v[220:223], 0
	v_mfma_f32_16x16x32_bf16 v[24:27], v[198:201], v[212:215], 0
	v_mfma_f32_16x16x32_bf16 v[4:7], v[190:193], v[236:239], 0
	v_mfma_f32_16x16x32_bf16 v[8:11], v[198:201], v[228:231], 0
	v_mfma_f32_16x16x32_bf16 v[28:31], v[194:197], v[216:219], v[28:31]
	v_mfma_f32_16x16x32_bf16 v[16:19], v[208:211], v[224:227], v[16:19]
	v_mfma_f32_16x16x32_bf16 v[12:15], v[194:197], v[232:235], v[12:15]
	v_mfma_f32_16x16x32_bf16 v[0:3], v[208:211], v[240:243], v[0:3]
	v_mfma_f32_16x16x32_bf16 v[20:23], v[194:197], v[224:227], v[20:23]
	v_mfma_f32_16x16x32_bf16 v[24:27], v[208:211], v[216:219], v[24:27]
	v_lshl_add_u64 v[246:247], s[62:63], 0, v[132:133]
	s_mov_b32 m0, s86
	s_nop 0
	global_load_lds_dwordx4 v[246:247], off
	v_mfma_f32_16x16x32_bf16 v[4:7], v[194:197], v[240:243], v[4:7]
	v_mfma_f32_16x16x32_bf16 v[8:11], v[208:211], v[232:235], v[8:11]
	s_setprio 0
	s_barrier
	s_add_i32 s3, 0, 0x18000
	v_add_u32_e32 v136, s3, v141
	s_add_i32 s33, 0, 0x1c000
	ds_read_b128 v[170:173], v136
	ds_read_b128 v[174:177], v136 offset:1024
	ds_read_b128 v[182:185], v136 offset:2048
	ds_read_b128 v[186:189], v136 offset:3072
	v_add_u32_e32 v136, s33, v141
	ds_read_b128 v[190:193], v136
	ds_read_b128 v[194:197], v136 offset:1024
	ds_read_b128 v[198:201], v136 offset:2048
	ds_read_b128 v[208:211], v136 offset:3072
	s_add_u32 s14, s62, 0x40000
	s_addc_u32 s15, s63, 0
	s_mov_b32 m0, s87
	v_lshl_add_u64 v[248:249], s[14:15], 0, v[128:129]
	ds_read_b128 v[212:215], v164 offset:32768
	ds_read_b128 v[216:219], v164 offset:33792
	ds_read_b128 v[220:223], v164 offset:34816
	ds_read_b128 v[224:227], v164 offset:35840
	ds_read_b128 v[228:231], v164 offset:36864
	ds_read_b128 v[232:235], v164 offset:37888
	ds_read_b128 v[236:239], v164 offset:38912
	ds_read_b128 v[240:243], v164 offset:39936
	global_load_lds_dwordx4 v[248:249], off
	v_lshl_add_u64 v[248:249], s[14:15], 0, v[132:133]
	s_mov_b32 m0, s88
	s_nop 0
	global_load_lds_dwordx4 v[248:249], off
	s_waitcnt vmcnt(8)
	s_waitcnt lgkmcnt(0)
	s_barrier
	s_setprio 1
	s_waitcnt lgkmcnt(0)
	v_mfma_f32_16x16x32_bf16 v[124:127], v[170:173], v[212:215], v[124:127]
	v_mfma_f32_16x16x32_bf16 v[112:115], v[182:185], v[220:223], v[112:115]
	v_mfma_f32_16x16x32_bf16 v[108:111], v[170:173], v[228:231], v[108:111]
	v_mfma_f32_16x16x32_bf16 v[96:99], v[182:185], v[236:239], v[96:99]
	v_mfma_f32_16x16x32_bf16 v[116:119], v[170:173], v[220:223], v[116:119]
	v_mfma_f32_16x16x32_bf16 v[120:123], v[182:185], v[212:215], v[120:123]
	v_mfma_f32_16x16x32_bf16 v[100:103], v[170:173], v[236:239], v[100:103]
	v_mfma_f32_16x16x32_bf16 v[104:107], v[182:185], v[228:231], v[104:107]
	v_mfma_f32_16x16x32_bf16 v[124:127], v[174:177], v[216:219], v[124:127]
	v_mfma_f32_16x16x32_bf16 v[112:115], v[186:189], v[224:227], v[112:115]
	v_mfma_f32_16x16x32_bf16 v[108:111], v[174:177], v[232:235], v[108:111]
	v_mfma_f32_16x16x32_bf16 v[96:99], v[186:189], v[240:243], v[96:99]
	v_mfma_f32_16x16x32_bf16 v[116:119], v[174:177], v[224:227], v[116:119]
	v_mfma_f32_16x16x32_bf16 v[120:123], v[186:189], v[216:219], v[120:123]
	v_mfma_f32_16x16x32_bf16 v[100:103], v[174:177], v[240:243], v[100:103]
	v_mfma_f32_16x16x32_bf16 v[104:107], v[186:189], v[232:235], v[104:107]
	s_setprio 0
	s_setprio 1
	v_mfma_f32_16x16x32_bf16 v[60:63], v[190:193], v[212:215], v[60:63]
	v_mfma_f32_16x16x32_bf16 v[48:51], v[198:201], v[220:223], v[48:51]
	v_mfma_f32_16x16x32_bf16 v[44:47], v[190:193], v[228:231], v[44:47]
	v_mfma_f32_16x16x32_bf16 v[32:35], v[198:201], v[236:239], v[32:35]
	v_mfma_f32_16x16x32_bf16 v[52:55], v[190:193], v[220:223], v[52:55]
	v_mfma_f32_16x16x32_bf16 v[56:59], v[198:201], v[212:215], v[56:59]
	v_mfma_f32_16x16x32_bf16 v[36:39], v[190:193], v[236:239], v[36:39]
	v_mfma_f32_16x16x32_bf16 v[40:43], v[198:201], v[228:231], v[40:43]
	v_mfma_f32_16x16x32_bf16 v[60:63], v[194:197], v[216:219], v[60:63]
	v_mfma_f32_16x16x32_bf16 v[48:51], v[208:211], v[224:227], v[48:51]
	v_mfma_f32_16x16x32_bf16 v[44:47], v[194:197], v[232:235], v[44:47]
	v_mfma_f32_16x16x32_bf16 v[32:35], v[208:211], v[240:243], v[32:35]
	v_mfma_f32_16x16x32_bf16 v[52:55], v[194:197], v[224:227], v[52:55]
	v_mfma_f32_16x16x32_bf16 v[56:59], v[208:211], v[216:219], v[56:59]
	v_mfma_f32_16x16x32_bf16 v[36:39], v[194:197], v[240:243], v[36:39]
	v_mfma_f32_16x16x32_bf16 v[40:43], v[208:211], v[232:235], v[40:43]
	s_setprio 0
	s_barrier
; #define PG8_STAGE(bufoff, gbase, voff) do { _Pragma("unroll") for (int _i = 0; _i < 2; ++_i) \
;         __builtin_amdgcn_global_load_lds((const unsigned*)((const char*)(gbase) + (voff)[_i]), (PG8_LAS unsigned*)(lds + (bufoff) + ldsw + _i * 8192), 16, 0, 0); } while (0)
; #define PG8_LDA(dst, b, h) do { _Pragma("unroll") for (int m = 0; m < 4; ++m) _Pragma("unroll") for (int k = 0; k < 2; ++k) dst[m][k] = *(const PG8_LAS bf16x8*)(lds + PG8_SA(b, h) + aoff + m * 2048 + k * 1024); } while (0)
; #define PG8_LDB(dst, b, h) do { _Pragma("unroll") for (int n = 0; n < 2; ++n) _Pragma("unroll") for (int k = 0; k < 2; ++k) dst[n][k] = *(const PG8_LAS bf16x8*)(lds + PG8_SB(b, h) + boff + n * 2048 + k * 1024); } while (0)
; #define PG8_MMA(ai, bj, At, Bt) do { __builtin_amdgcn_s_setprio(1); _Pragma("unroll") for (int m = 0; m < 4; ++m) _Pragma("unroll") for (int n = 0; n < 2; ++n) _Pragma("unroll") for (int k = 0; k < 2; ++k) \
;         acc[ai][bj][m][n] = __builtin_amdgcn_mfma_f32_16x16x32_bf16(Bt[n][k], At[m][k], acc[ai][bj][m][n], 0, 0, 0); __builtin_amdgcn_s_setprio(0); } while (0)
; #define PG8_WAIT_V(n) asm volatile("s_waitcnt vmcnt(" #n ")" ::: "memory")
; #define PG8_WAIT_L(n) asm volatile("s_waitcnt lgkmcnt(" #n ")" ::: "memory")
; #define PG8_BAR __builtin_amdgcn_s_barrier()
; #define PG8_SCHED __builtin_amdgcn_sched_barrier(0)
; template <class Epi, class Sched, bool ALIGN_EPI = false, bool SP2 = false>
; __device__ __forceinline__ void gemm_phase(PG8_LAS unsigned char* lds, const Gemm g, const Sched& S, const Epi& E) {
;     ...
;             PG8_LDB(B0, 0, 0); PG8_LDB(B1, 0, 1); PG8_SCHED; PG8_LDA(At, 0, 0); PG8_STAGE(PG8_SA(1, 1), a1 + hstep, voffA);
;             PG8_WAIT_V(8); PG8_WAIT_L(0); PG8_BAR; PG8_MMA(0, 0, At, B0); PG8_MMA(0, 1, At, B1); PG8_BAR; PG8_SCHED;
;     ...
;             PG8_LDA(At, 1, 1); PG8_STAGE(PG8_SB(1, 0), b3, voffB); PG8_STAGE(PG8_SB(1, 1), b3 + hstep, voffB); PG8_STAGE(PG8_SA(1, 0), a3, voffA);
;             PG8_WAIT_V(8); PG8_WAIT_L(0); PG8_BAR; PG8_MMA(1, 0, At, B0); PG8_MMA(1, 1, At, B1); PG8_BAR; PG8_SCHED;
	s_add_i32 s3, s3, s84
	v_lshl_add_u64 v[178:179], v[178:179], 0, s[8:9]
	s_mov_b32 m0, s3
	ds_read_b128 v[212:215], v164 offset:49152
	ds_read_b128 v[216:219], v164 offset:50176
	ds_read_b128 v[220:223], v164 offset:51200
	ds_read_b128 v[224:227], v164 offset:52224
	ds_read_b128 v[228:231], v164 offset:53248
	ds_read_b128 v[232:235], v164 offset:54272
	ds_read_b128 v[236:239], v164 offset:55296
	ds_read_b128 v[240:243], v164 offset:56320
	global_load_lds_dwordx4 v[178:179], off
	s_add_i32 m0, s3, 0x2000
	s_add_u32 s14, s60, 0x40080
	v_lshl_add_u64 v[178:179], v[202:203], 0, s[8:9]
	s_addc_u32 s15, s61, 0
	s_add_i32 s3, s33, s84
	global_load_lds_dwordx4 v[178:179], off
	v_lshl_add_u64 v[178:179], s[14:15], 0, v[130:131]
	s_mov_b32 m0, s3
	s_nop 0
	global_load_lds_dwordx4 v[178:179], off
	v_lshl_add_u64 v[178:179], s[14:15], 0, v[134:135]
	s_add_i32 m0, s3, 0x2000
	s_nop 0
	global_load_lds_dwordx4 v[178:179], off
	s_waitcnt vmcnt(6)
	s_waitcnt lgkmcnt(0)
	s_barrier
	s_setprio 1
	s_waitcnt lgkmcnt(0)
	v_mfma_f32_16x16x32_bf16 v[92:95], v[170:173], v[212:215], v[92:95]
	v_mfma_f32_16x16x32_bf16 v[80:83], v[182:185], v[220:223], v[80:83]
	v_mfma_f32_16x16x32_bf16 v[76:79], v[170:173], v[228:231], v[76:79]
	v_mfma_f32_16x16x32_bf16 v[64:67], v[182:185], v[236:239], v[64:67]
	v_mfma_f32_16x16x32_bf16 v[84:87], v[170:173], v[220:223], v[84:87]
	v_mfma_f32_16x16x32_bf16 v[88:91], v[182:185], v[212:215], v[88:91]
	v_mfma_f32_16x16x32_bf16 v[68:71], v[170:173], v[236:239], v[68:71]
	v_mfma_f32_16x16x32_bf16 v[72:75], v[182:185], v[228:231], v[72:75]
	v_mfma_f32_16x16x32_bf16 v[92:95], v[174:177], v[216:219], v[92:95]
	v_mfma_f32_16x16x32_bf16 v[80:83], v[186:189], v[224:227], v[80:83]
	v_mfma_f32_16x16x32_bf16 v[76:79], v[174:177], v[232:235], v[76:79]
	v_mfma_f32_16x16x32_bf16 v[64:67], v[186:189], v[240:243], v[64:67]
	v_mfma_f32_16x16x32_bf16 v[84:87], v[174:177], v[224:227], v[84:87]
	v_mfma_f32_16x16x32_bf16 v[88:91], v[186:189], v[216:219], v[88:91]
	v_lshl_add_u64 v[178:179], v[244:245], 0, s[8:9]
	s_mov_b32 m0, s90
	s_nop 0
	global_load_lds_dwordx4 v[178:179], off
	v_mfma_f32_16x16x32_bf16 v[68:71], v[174:177], v[240:243], v[68:71]
	v_mfma_f32_16x16x32_bf16 v[72:75], v[186:189], v[232:235], v[72:75]
	s_setprio 0
	s_setprio 1
	v_mfma_f32_16x16x32_bf16 v[28:31], v[190:193], v[212:215], v[28:31]
	v_mfma_f32_16x16x32_bf16 v[16:19], v[198:201], v[220:223], v[16:19]
	v_mfma_f32_16x16x32_bf16 v[12:15], v[190:193], v[228:231], v[12:15]
	v_mfma_f32_16x16x32_bf16 v[0:3], v[198:201], v[236:239], v[0:3]
	v_mfma_f32_16x16x32_bf16 v[20:23], v[190:193], v[220:223], v[20:23]
	v_mfma_f32_16x16x32_bf16 v[24:27], v[198:201], v[212:215], v[24:27]
	v_mfma_f32_16x16x32_bf16 v[4:7], v[190:193], v[236:239], v[4:7]
	v_mfma_f32_16x16x32_bf16 v[8:11], v[198:201], v[228:231], v[8:11]
	v_mfma_f32_16x16x32_bf16 v[28:31], v[194:197], v[216:219], v[28:31]
	v_mfma_f32_16x16x32_bf16 v[16:19], v[208:211], v[224:227], v[16:19]
	v_mfma_f32_16x16x32_bf16 v[12:15], v[194:197], v[232:235], v[12:15]
	v_mfma_f32_16x16x32_bf16 v[0:3], v[208:211], v[240:243], v[0:3]
	v_mfma_f32_16x16x32_bf16 v[20:23], v[194:197], v[224:227], v[20:23]
	v_mfma_f32_16x16x32_bf16 v[24:27], v[208:211], v[216:219], v[24:27]
	v_lshl_add_u64 v[178:179], v[246:247], 0, s[8:9]
	s_mov_b32 m0, s91
	s_nop 0
	global_load_lds_dwordx4 v[178:179], off
	v_mfma_f32_16x16x32_bf16 v[4:7], v[194:197], v[240:243], v[4:7]
	v_mfma_f32_16x16x32_bf16 v[8:11], v[208:211], v[232:235], v[8:11]
	s_setprio 0
	s_barrier
	s_add_i32 vcc_lo, vcc_lo, 2
	s_add_u32 s58, s58, 0x100
	s_addc_u32 s59, s59, 0
	s_add_u32 s96, s96, 0x100
	s_addc_u32 s97, s97, 0
.LBB0_459:
	ds_read_b128 v[170:173], v165
	ds_read_b128 v[174:177], v165 offset:1024
	ds_read_b128 v[182:185], v165 offset:2048
	ds_read_b128 v[186:189], v165 offset:3072
	ds_read_b128 v[190:193], v168
	ds_read_b128 v[194:197], v168 offset:1024
	ds_read_b128 v[198:201], v168 offset:2048
	ds_read_b128 v[208:211], v168 offset:3072
	s_add_u32 s3, s58, 0xfffc0080
	s_addc_u32 s14, s59, -1
	s_cmp_eq_u32 vcc_lo, 12
	s_cselect_b32 s63, s49, s14
	s_cselect_b32 s62, s55, s3
	s_cselect_b32 s61, s45, s97
	s_cselect_b32 s60, s57, s96
	v_lshl_add_u64 v[178:179], s[58:59], 0, v[160:161]
	s_add_i32 m0, s85, 0xc000
	ds_read_b128 v[212:215], v164
	ds_read_b128 v[216:219], v164 offset:1024
	ds_read_b128 v[220:223], v164 offset:2048
	ds_read_b128 v[224:227], v164 offset:3072
	ds_read_b128 v[228:231], v164 offset:4096
	ds_read_b128 v[232:235], v164 offset:5120
	ds_read_b128 v[236:239], v164 offset:6144
	ds_read_b128 v[240:243], v164 offset:7168
	global_load_lds_dwordx4 v[178:179], off
	v_lshl_add_u64 v[178:179], s[58:59], 0, v[162:163]
	s_add_i32 m0, s85, 0xe000
	s_nop 0
	global_load_lds_dwordx4 v[178:179], off
	s_waitcnt vmcnt(8)
	s_waitcnt lgkmcnt(0)
	s_barrier
; #define PG8_STAGE(bufoff, gbase, voff) do { _Pragma("unroll") for (int _i = 0; _i < 2; ++_i) \
;         __builtin_amdgcn_global_load_lds((const unsigned*)((const char*)(gbase) + (voff)[_i]), (PG8_LAS unsigned*)(lds + (bufoff) + ldsw + _i * 8192), 16, 0, 0); } while (0)
; #define PG8_LDA(dst, b, h) do { _Pragma("unroll") for (int m = 0; m < 4; ++m) _Pragma("unroll") for (int k = 0; k < 2; ++k) dst[m][k] = *(const PG8_LAS bf16x8*)(lds + PG8_SA(b, h) + aoff + m * 2048 + k * 1024); } while (0)
; #define PG8_LDB(dst, b, h) do { _Pragma("unroll") for (int n = 0; n < 2; ++n) _Pragma("unroll") for (int k = 0; k < 2; ++k) dst[n][k] = *(const PG8_LAS bf16x8*)(lds + PG8_SB(b, h) + boff + n * 2048 + k * 1024); } while (0)
; #define PG8_MMA(ai, bj, At, Bt) do { __builtin_amdgcn_s_setprio(1); _Pragma("unroll") for (int m = 0; m < 4; ++m) _Pragma("unroll") for (int n = 0; n < 2; ++n) _Pragma("unroll") for (int k = 0; k < 2; ++k) \
;         acc[ai][bj][m][n] = __builtin_amdgcn_mfma_f32_16x16x32_bf16(Bt[n][k], At[m][k], acc[ai][bj][m][n], 0, 0, 0); __builtin_amdgcn_s_setprio(0); } while (0)
; #define PG8_WAIT_V(n) asm volatile("s_waitcnt vmcnt(" #n ")" ::: "memory")
; #define PG8_WAIT_L(n) asm volatile("s_waitcnt lgkmcnt(" #n ")" ::: "memory")
; #define PG8_BAR __builtin_amdgcn_s_barrier()
; #define PG8_SCHED __builtin_amdgcn_sched_barrier(0)
; template <class Epi, class Sched, bool ALIGN_EPI = false, bool SP2 = false>
; __device__ __forceinline__ void gemm_phase(PG8_LAS unsigned char* lds, const Gemm g, const Sched& S, const Epi& E) {
;     ...
;             PG8_LDB(B0, 0, 0); PG8_LDB(B1, 0, 1); PG8_SCHED; PG8_LDA(At, 0, 0); PG8_STAGE(PG8_SA(1, 1), a1 + hstep, voffA);
;             PG8_WAIT_V(8); PG8_WAIT_L(0); PG8_BAR; PG8_MMA(0, 0, At, B0); PG8_MMA(0, 1, At, B1); PG8_BAR; PG8_SCHED;
;             PG8_LDA(At, 0, 1); PG8_STAGE(PG8_SB(0, 0), b2, voffB); PG8_STAGE(PG8_SB(0, 1), b2 + hstep, voffB); PG8_STAGE(PG8_SA(0, 0), a2, voffA);
;             PG8_WAIT_V(8); PG8_WAIT_L(0); PG8_BAR; PG8_MMA(1, 0, At, B0); PG8_MMA(1, 1, At, B1); PG8_BAR; PG8_SCHED;
	s_setprio 1
	s_waitcnt lgkmcnt(0)
	v_mfma_f32_16x16x32_bf16 v[124:127], v[170:173], v[212:215], v[124:127]
	v_mfma_f32_16x16x32_bf16 v[112:115], v[182:185], v[220:223], v[112:115]
	v_mfma_f32_16x16x32_bf16 v[108:111], v[170:173], v[228:231], v[108:111]
	v_mfma_f32_16x16x32_bf16 v[96:99], v[182:185], v[236:239], v[96:99]
	v_mfma_f32_16x16x32_bf16 v[116:119], v[170:173], v[220:223], v[116:119]
	v_mfma_f32_16x16x32_bf16 v[120:123], v[182:185], v[212:215], v[120:123]
	v_mfma_f32_16x16x32_bf16 v[100:103], v[170:173], v[236:239], v[100:103]
	v_mfma_f32_16x16x32_bf16 v[104:107], v[182:185], v[228:231], v[104:107]
	v_mfma_f32_16x16x32_bf16 v[124:127], v[174:177], v[216:219], v[124:127]
	v_mfma_f32_16x16x32_bf16 v[112:115], v[186:189], v[224:227], v[112:115]
	v_mfma_f32_16x16x32_bf16 v[108:111], v[174:177], v[232:235], v[108:111]
	v_mfma_f32_16x16x32_bf16 v[96:99], v[186:189], v[240:243], v[96:99]
	v_mfma_f32_16x16x32_bf16 v[116:119], v[174:177], v[224:227], v[116:119]
	v_mfma_f32_16x16x32_bf16 v[120:123], v[186:189], v[216:219], v[120:123]
	v_mfma_f32_16x16x32_bf16 v[100:103], v[174:177], v[240:243], v[100:103]
	v_mfma_f32_16x16x32_bf16 v[104:107], v[186:189], v[232:235], v[104:107]
	s_setprio 0
	s_setprio 1
	v_mfma_f32_16x16x32_bf16 v[60:63], v[190:193], v[212:215], v[60:63]
	v_mfma_f32_16x16x32_bf16 v[48:51], v[198:201], v[220:223], v[48:51]
	v_mfma_f32_16x16x32_bf16 v[44:47], v[190:193], v[228:231], v[44:47]
	v_mfma_f32_16x16x32_bf16 v[32:35], v[198:201], v[236:239], v[32:35]
	v_mfma_f32_16x16x32_bf16 v[52:55], v[190:193], v[220:223], v[52:55]
	v_mfma_f32_16x16x32_bf16 v[56:59], v[198:201], v[212:215], v[56:59]
	v_mfma_f32_16x16x32_bf16 v[36:39], v[190:193], v[236:239], v[36:39]
	v_mfma_f32_16x16x32_bf16 v[40:43], v[198:201], v[228:231], v[40:43]
	v_mfma_f32_16x16x32_bf16 v[60:63], v[194:197], v[216:219], v[60:63]
	v_mfma_f32_16x16x32_bf16 v[48:51], v[208:211], v[224:227], v[48:51]
	v_mfma_f32_16x16x32_bf16 v[44:47], v[194:197], v[232:235], v[44:47]
	v_mfma_f32_16x16x32_bf16 v[32:35], v[208:211], v[240:243], v[32:35]
	v_mfma_f32_16x16x32_bf16 v[52:55], v[194:197], v[224:227], v[52:55]
	v_mfma_f32_16x16x32_bf16 v[56:59], v[208:211], v[216:219], v[56:59]
	v_mfma_f32_16x16x32_bf16 v[36:39], v[194:197], v[240:243], v[36:39]
	v_mfma_f32_16x16x32_bf16 v[40:43], v[208:211], v[232:235], v[40:43]
	s_setprio 0
	s_barrier
	s_add_i32 s3, s94, s84
	v_lshl_add_u64 v[178:179], s[60:61], 0, v[130:131]
	s_mov_b32 m0, s3
	ds_read_b128 v[212:215], v164 offset:16384
	ds_read_b128 v[216:219], v164 offset:17408
	ds_read_b128 v[220:223], v164 offset:18432
	ds_read_b128 v[224:227], v164 offset:19456
	ds_read_b128 v[228:231], v164 offset:20480
	ds_read_b128 v[232:235], v164 offset:21504
	ds_read_b128 v[236:239], v164 offset:22528
	ds_read_b128 v[240:243], v164 offset:23552
	global_load_lds_dwordx4 v[178:179], off
	s_add_i32 m0, s3, 0x2000
	s_add_u32 s14, s60, 0x40000
	v_lshl_add_u64 v[202:203], s[60:61], 0, v[134:135]
	s_addc_u32 s15, s61, 0
	s_add_i32 s3, s95, s84
	global_load_lds_dwordx4 v[202:203], off
	v_lshl_add_u64 v[244:245], s[14:15], 0, v[130:131]
	s_mov_b32 m0, s3
	global_load_lds_dwordx4 v[244:245], off
	v_lshl_add_u64 v[244:245], s[14:15], 0, v[134:135]
	s_add_i32 m0, s3, 0x2000
	s_nop 0
	global_load_lds_dwordx4 v[244:245], off
	s_waitcnt vmcnt(6)
	s_waitcnt lgkmcnt(0)
	s_barrier
	s_setprio 1
	s_waitcnt lgkmcnt(0)
	v_mfma_f32_16x16x32_bf16 v[92:95], v[170:173], v[212:215], v[92:95]
	v_mfma_f32_16x16x32_bf16 v[80:83], v[182:185], v[220:223], v[80:83]
	v_mfma_f32_16x16x32_bf16 v[76:79], v[170:173], v[228:231], v[76:79]
	v_mfma_f32_16x16x32_bf16 v[64:67], v[182:185], v[236:239], v[64:67]
	v_mfma_f32_16x16x32_bf16 v[84:87], v[170:173], v[220:223], v[84:87]
	v_mfma_f32_16x16x32_bf16 v[88:91], v[182:185], v[212:215], v[88:91]
	v_mfma_f32_16x16x32_bf16 v[68:71], v[170:173], v[236:239], v[68:71]
	v_mfma_f32_16x16x32_bf16 v[72:75], v[182:185], v[228:231], v[72:75]
	v_mfma_f32_16x16x32_bf16 v[92:95], v[174:177], v[216:219], v[92:95]
	v_mfma_f32_16x16x32_bf16 v[80:83], v[186:189], v[224:227], v[80:83]
	v_mfma_f32_16x16x32_bf16 v[76:79], v[174:177], v[232:235], v[76:79]
	v_mfma_f32_16x16x32_bf16 v[64:67], v[186:189], v[240:243], v[64:67]
	v_mfma_f32_16x16x32_bf16 v[84:87], v[174:177], v[224:227], v[84:87]
	v_mfma_f32_16x16x32_bf16 v[88:91], v[186:189], v[216:219], v[88:91]
	v_lshl_add_u64 v[244:245], s[62:63], 0, v[128:129]
	s_mov_b32 m0, s85
	s_nop 0
	global_load_lds_dwordx4 v[244:245], off
	v_mfma_f32_16x16x32_bf16 v[68:71], v[174:177], v[240:243], v[68:71]
	v_mfma_f32_16x16x32_bf16 v[72:75], v[186:189], v[232:235], v[72:75]
	s_setprio 0
	s_setprio 1
	v_mfma_f32_16x16x32_bf16 v[28:31], v[190:193], v[212:215], v[28:31]
	v_mfma_f32_16x16x32_bf16 v[16:19], v[198:201], v[220:223], v[16:19]
	v_mfma_f32_16x16x32_bf16 v[12:15], v[190:193], v[228:231], v[12:15]
	v_mfma_f32_16x16x32_bf16 v[0:3], v[198:201], v[236:239], v[0:3]
	v_mfma_f32_16x16x32_bf16 v[20:23], v[190:193], v[220:223], v[20:23]
	v_mfma_f32_16x16x32_bf16 v[24:27], v[198:201], v[212:215], v[24:27]
	v_mfma_f32_16x16x32_bf16 v[4:7], v[190:193], v[236:239], v[4:7]
	v_mfma_f32_16x16x32_bf16 v[8:11], v[198:201], v[228:231], v[8:11]
	v_mfma_f32_16x16x32_bf16 v[28:31], v[194:197], v[216:219], v[28:31]
	v_mfma_f32_16x16x32_bf16 v[16:19], v[208:211], v[224:227], v[16:19]
	v_mfma_f32_16x16x32_bf16 v[12:15], v[194:197], v[232:235], v[12:15]
	v_mfma_f32_16x16x32_bf16 v[0:3], v[208:211], v[240:243], v[0:3]
	v_mfma_f32_16x16x32_bf16 v[20:23], v[194:197], v[224:227], v[20:23]
	v_mfma_f32_16x16x32_bf16 v[24:27], v[208:211], v[216:219], v[24:27]
	v_lshl_add_u64 v[246:247], s[62:63], 0, v[132:133]
	s_mov_b32 m0, s86
	s_nop 0
	global_load_lds_dwordx4 v[246:247], off
	v_mfma_f32_16x16x32_bf16 v[4:7], v[194:197], v[240:243], v[4:7]
	v_mfma_f32_16x16x32_bf16 v[8:11], v[208:211], v[232:235], v[8:11]
	s_setprio 0
	s_barrier
; #define PG8_STAGE(bufoff, gbase, voff) do { _Pragma("unroll") for (int _i = 0; _i < 2; ++_i) \
;         __builtin_amdgcn_global_load_lds((const unsigned*)((const char*)(gbase) + (voff)[_i]), (PG8_LAS unsigned*)(lds + (bufoff) + ldsw + _i * 8192), 16, 0, 0); } while (0)
; #define PG8_LDA(dst, b, h) do { _Pragma("unroll") for (int m = 0; m < 4; ++m) _Pragma("unroll") for (int k = 0; k < 2; ++k) dst[m][k] = *(const PG8_LAS bf16x8*)(lds + PG8_SA(b, h) + aoff + m * 2048 + k * 1024); } while (0)
; #define PG8_LDB(dst, b, h) do { _Pragma("unroll") for (int n = 0; n < 2; ++n) _Pragma("unroll") for (int k = 0; k < 2; ++k) dst[n][k] = *(const PG8_LAS bf16x8*)(lds + PG8_SB(b, h) + boff + n * 2048 + k * 1024); } while (0)
; #define PG8_MMA(ai, bj, At, Bt) do { __builtin_amdgcn_s_setprio(1); _Pragma("unroll") for (int m = 0; m < 4; ++m) _Pragma("unroll") for (int n = 0; n < 2; ++n) _Pragma("unroll") for (int k = 0; k < 2; ++k) \
;         acc[ai][bj][m][n] = __builtin_amdgcn_mfma_f32_16x16x32_bf16(Bt[n][k], At[m][k], acc[ai][bj][m][n], 0, 0, 0); __builtin_amdgcn_s_setprio(0); } while (0)
; #define PG8_WAIT_V(n) asm volatile("s_waitcnt vmcnt(" #n ")" ::: "memory")
; #define PG8_WAIT_L(n) asm volatile("s_waitcnt lgkmcnt(" #n ")" ::: "memory")
; #define PG8_BAR __builtin_amdgcn_s_barrier()
; #define PG8_SCHED __builtin_amdgcn_sched_barrier(0)
; template <class Epi, class Sched, bool ALIGN_EPI = false, bool SP2 = false>
; __device__ __forceinline__ void gemm_phase(PG8_LAS unsigned char* lds, const Gemm g, const Sched& S, const Epi& E) {
;     ...
;             PG8_LDB(B0, 1, 0); PG8_LDB(B1, 1, 1); PG8_SCHED; PG8_LDA(At, 1, 0); PG8_STAGE(PG8_SA(0, 1), a2 + hstep, voffA);
;             PG8_WAIT_V(8); PG8_WAIT_L(0); PG8_BAR; PG8_MMA(0, 0, At, B0); PG8_MMA(0, 1, At, B1); PG8_BAR; PG8_SCHED;
	s_add_i32 s3, 0, 0x18000
	v_add_u32_e32 v136, s3, v141
	s_add_i32 s33, 0, 0x1c000
	ds_read_b128 v[170:173], v136
	ds_read_b128 v[174:177], v136 offset:1024
	ds_read_b128 v[182:185], v136 offset:2048
	ds_read_b128 v[186:189], v136 offset:3072
	v_add_u32_e32 v136, s33, v141
	ds_read_b128 v[190:193], v136
	ds_read_b128 v[194:197], v136 offset:1024
	ds_read_b128 v[198:201], v136 offset:2048
	ds_read_b128 v[208:211], v136 offset:3072
	s_add_u32 s14, s62, 0x40000
	s_addc_u32 s15, s63, 0
	s_mov_b32 m0, s87
	v_lshl_add_u64 v[248:249], s[14:15], 0, v[128:129]
	ds_read_b128 v[212:215], v164 offset:32768
	ds_read_b128 v[216:219], v164 offset:33792
	ds_read_b128 v[220:223], v164 offset:34816
	ds_read_b128 v[224:227], v164 offset:35840
	ds_read_b128 v[228:231], v164 offset:36864
	ds_read_b128 v[232:235], v164 offset:37888
	ds_read_b128 v[236:239], v164 offset:38912
	ds_read_b128 v[240:243], v164 offset:39936
	global_load_lds_dwordx4 v[248:249], off
	v_lshl_add_u64 v[248:249], s[14:15], 0, v[132:133]
	s_mov_b32 m0, s88
	s_nop 0
	global_load_lds_dwordx4 v[248:249], off
	s_waitcnt vmcnt(8)
	s_waitcnt lgkmcnt(0)
	s_barrier
	s_setprio 1
	s_waitcnt lgkmcnt(0)
	v_mfma_f32_16x16x32_bf16 v[124:127], v[170:173], v[212:215], v[124:127]
	v_mfma_f32_16x16x32_bf16 v[112:115], v[182:185], v[220:223], v[112:115]
	v_mfma_f32_16x16x32_bf16 v[108:111], v[170:173], v[228:231], v[108:111]
	v_mfma_f32_16x16x32_bf16 v[96:99], v[182:185], v[236:239], v[96:99]
	v_mfma_f32_16x16x32_bf16 v[116:119], v[170:173], v[220:223], v[116:119]
	v_mfma_f32_16x16x32_bf16 v[120:123], v[182:185], v[212:215], v[120:123]
	v_mfma_f32_16x16x32_bf16 v[100:103], v[170:173], v[236:239], v[100:103]
	v_mfma_f32_16x16x32_bf16 v[104:107], v[182:185], v[228:231], v[104:107]
	v_mfma_f32_16x16x32_bf16 v[124:127], v[174:177], v[216:219], v[124:127]
	v_mfma_f32_16x16x32_bf16 v[112:115], v[186:189], v[224:227], v[112:115]
	v_mfma_f32_16x16x32_bf16 v[108:111], v[174:177], v[232:235], v[108:111]
	v_mfma_f32_16x16x32_bf16 v[96:99], v[186:189], v[240:243], v[96:99]
	v_mfma_f32_16x16x32_bf16 v[116:119], v[174:177], v[224:227], v[116:119]
	v_mfma_f32_16x16x32_bf16 v[120:123], v[186:189], v[216:219], v[120:123]
	v_mfma_f32_16x16x32_bf16 v[100:103], v[174:177], v[240:243], v[100:103]
	v_mfma_f32_16x16x32_bf16 v[104:107], v[186:189], v[232:235], v[104:107]
	s_setprio 0
	s_setprio 1
	v_mfma_f32_16x16x32_bf16 v[60:63], v[190:193], v[212:215], v[60:63]
	v_mfma_f32_16x16x32_bf16 v[48:51], v[198:201], v[220:223], v[48:51]
	v_mfma_f32_16x16x32_bf16 v[44:47], v[190:193], v[228:231], v[44:47]
	v_mfma_f32_16x16x32_bf16 v[32:35], v[198:201], v[236:239], v[32:35]
	v_mfma_f32_16x16x32_bf16 v[52:55], v[190:193], v[220:223], v[52:55]
	v_mfma_f32_16x16x32_bf16 v[56:59], v[198:201], v[212:215], v[56:59]
	v_mfma_f32_16x16x32_bf16 v[36:39], v[190:193], v[236:239], v[36:39]
	v_mfma_f32_16x16x32_bf16 v[40:43], v[198:201], v[228:231], v[40:43]
	v_mfma_f32_16x16x32_bf16 v[60:63], v[194:197], v[216:219], v[60:63]
	v_mfma_f32_16x16x32_bf16 v[48:51], v[208:211], v[224:227], v[48:51]
	v_mfma_f32_16x16x32_bf16 v[44:47], v[194:197], v[232:235], v[44:47]
	v_mfma_f32_16x16x32_bf16 v[32:35], v[208:211], v[240:243], v[32:35]
	v_mfma_f32_16x16x32_bf16 v[52:55], v[194:197], v[224:227], v[52:55]
	v_mfma_f32_16x16x32_bf16 v[56:59], v[208:211], v[216:219], v[56:59]
	v_mfma_f32_16x16x32_bf16 v[36:39], v[194:197], v[240:243], v[36:39]
	v_mfma_f32_16x16x32_bf16 v[40:43], v[208:211], v[232:235], v[40:43]
	s_setprio 0
	s_barrier
; #define PG8_STAGE(bufoff, gbase, voff) do { _Pragma("unroll") for (int _i = 0; _i < 2; ++_i) \
;         __builtin_amdgcn_global_load_lds((const unsigned*)((const char*)(gbase) + (voff)[_i]), (PG8_LAS unsigned*)(lds + (bufoff) + ldsw + _i * 8192), 16, 0, 0); } while (0)
; #define PG8_LDA(dst, b, h) do { _Pragma("unroll") for (int m = 0; m < 4; ++m) _Pragma("unroll") for (int k = 0; k < 2; ++k) dst[m][k] = *(const PG8_LAS bf16x8*)(lds + PG8_SA(b, h) + aoff + m * 2048 + k * 1024); } while (0)
; #define PG8_MMA(ai, bj, At, Bt) do { __builtin_amdgcn_s_setprio(1); _Pragma("unroll") for (int m = 0; m < 4; ++m) _Pragma("unroll") for (int n = 0; n < 2; ++n) _Pragma("unroll") for (int k = 0; k < 2; ++k) \
;         acc[ai][bj][m][n] = __builtin_amdgcn_mfma_f32_16x16x32_bf16(Bt[n][k], At[m][k], acc[ai][bj][m][n], 0, 0, 0); __builtin_amdgcn_s_setprio(0); } while (0)
; #define PG8_WAIT_V(n) asm volatile("s_waitcnt vmcnt(" #n ")" ::: "memory")
; #define PG8_WAIT_L(n) asm volatile("s_waitcnt lgkmcnt(" #n ")" ::: "memory")
; #define PG8_BAR __builtin_amdgcn_s_barrier()
; #define PG8_SCHED __builtin_amdgcn_sched_barrier(0)
; template <class Epi, class Sched, bool ALIGN_EPI = false, bool SP2 = false>
; __device__ __forceinline__ void gemm_phase(PG8_LAS unsigned char* lds, const Gemm g, const Sched& S, const Epi& E) {
;     ...
;             PG8_LDA(At, 1, 1); PG8_STAGE(PG8_SB(1, 0), b3, voffB); PG8_STAGE(PG8_SB(1, 1), b3 + hstep, voffB); PG8_STAGE(PG8_SA(1, 0), a3, voffA);
;             PG8_WAIT_V(8); PG8_WAIT_L(0); PG8_BAR; PG8_MMA(1, 0, At, B0); PG8_MMA(1, 1, At, B1); PG8_BAR; PG8_SCHED;
	s_add_i32 s3, s3, s84
	v_lshl_add_u64 v[178:179], v[178:179], 0, s[8:9]
	s_mov_b32 m0, s3
	ds_read_b128 v[212:215], v164 offset:49152
	ds_read_b128 v[216:219], v164 offset:50176
	ds_read_b128 v[220:223], v164 offset:51200
	ds_read_b128 v[224:227], v164 offset:52224
	ds_read_b128 v[228:231], v164 offset:53248
	ds_read_b128 v[232:235], v164 offset:54272
	ds_read_b128 v[236:239], v164 offset:55296
	ds_read_b128 v[240:243], v164 offset:56320
	global_load_lds_dwordx4 v[178:179], off
	s_add_i32 m0, s3, 0x2000
	s_add_u32 s14, s60, 0x40080
	v_lshl_add_u64 v[178:179], v[202:203], 0, s[8:9]
	s_addc_u32 s15, s61, 0
	s_add_i32 s3, s33, s84
	global_load_lds_dwordx4 v[178:179], off
	v_lshl_add_u64 v[178:179], s[14:15], 0, v[130:131]
	s_mov_b32 m0, s3
	s_nop 0
	global_load_lds_dwordx4 v[178:179], off
	v_lshl_add_u64 v[178:179], s[14:15], 0, v[134:135]
	s_add_i32 m0, s3, 0x2000
	s_nop 0
	global_load_lds_dwordx4 v[178:179], off
	s_waitcnt vmcnt(6)
	s_waitcnt lgkmcnt(0)
	s_barrier
	s_setprio 1
	s_waitcnt lgkmcnt(0)
	v_mfma_f32_16x16x32_bf16 v[92:95], v[170:173], v[212:215], v[92:95]
	v_mfma_f32_16x16x32_bf16 v[80:83], v[182:185], v[220:223], v[80:83]
	v_mfma_f32_16x16x32_bf16 v[76:79], v[170:173], v[228:231], v[76:79]
	v_mfma_f32_16x16x32_bf16 v[64:67], v[182:185], v[236:239], v[64:67]
	v_mfma_f32_16x16x32_bf16 v[84:87], v[170:173], v[220:223], v[84:87]
	v_mfma_f32_16x16x32_bf16 v[88:91], v[182:185], v[212:215], v[88:91]
	v_mfma_f32_16x16x32_bf16 v[68:71], v[170:173], v[236:239], v[68:71]
	v_mfma_f32_16x16x32_bf16 v[72:75], v[182:185], v[228:231], v[72:75]
	v_mfma_f32_16x16x32_bf16 v[92:95], v[174:177], v[216:219], v[92:95]
	v_mfma_f32_16x16x32_bf16 v[80:83], v[186:189], v[224:227], v[80:83]
	v_mfma_f32_16x16x32_bf16 v[76:79], v[174:177], v[232:235], v[76:79]
	v_mfma_f32_16x16x32_bf16 v[64:67], v[186:189], v[240:243], v[64:67]
	v_mfma_f32_16x16x32_bf16 v[84:87], v[174:177], v[224:227], v[84:87]
	v_mfma_f32_16x16x32_bf16 v[88:91], v[186:189], v[216:219], v[88:91]
	v_lshl_add_u64 v[178:179], v[244:245], 0, s[8:9]
	s_mov_b32 m0, s90
	s_nop 0
	global_load_lds_dwordx4 v[178:179], off
	v_mfma_f32_16x16x32_bf16 v[68:71], v[174:177], v[240:243], v[68:71]
	v_mfma_f32_16x16x32_bf16 v[72:75], v[186:189], v[232:235], v[72:75]
	s_setprio 0
	s_setprio 1
	v_mfma_f32_16x16x32_bf16 v[28:31], v[190:193], v[212:215], v[28:31]
	v_mfma_f32_16x16x32_bf16 v[16:19], v[198:201], v[220:223], v[16:19]
	v_mfma_f32_16x16x32_bf16 v[12:15], v[190:193], v[228:231], v[12:15]
	v_mfma_f32_16x16x32_bf16 v[0:3], v[198:201], v[236:239], v[0:3]
	v_mfma_f32_16x16x32_bf16 v[20:23], v[190:193], v[220:223], v[20:23]
	v_mfma_f32_16x16x32_bf16 v[24:27], v[198:201], v[212:215], v[24:27]
	v_mfma_f32_16x16x32_bf16 v[4:7], v[190:193], v[236:239], v[4:7]
	v_mfma_f32_16x16x32_bf16 v[8:11], v[198:201], v[228:231], v[8:11]
	v_mfma_f32_16x16x32_bf16 v[28:31], v[194:197], v[216:219], v[28:31]
	v_mfma_f32_16x16x32_bf16 v[16:19], v[208:211], v[224:227], v[16:19]
	v_mfma_f32_16x16x32_bf16 v[12:15], v[194:197], v[232:235], v[12:15]
	v_mfma_f32_16x16x32_bf16 v[0:3], v[208:211], v[240:243], v[0:3]
	v_mfma_f32_16x16x32_bf16 v[20:23], v[194:197], v[224:227], v[20:23]
	v_mfma_f32_16x16x32_bf16 v[24:27], v[208:211], v[216:219], v[24:27]
	v_lshl_add_u64 v[178:179], v[246:247], 0, s[8:9]
	s_mov_b32 m0, s91
	s_nop 0
	global_load_lds_dwordx4 v[178:179], off
	v_mfma_f32_16x16x32_bf16 v[4:7], v[194:197], v[240:243], v[4:7]
	v_mfma_f32_16x16x32_bf16 v[8:11], v[208:211], v[232:235], v[8:11]
	s_setprio 0
	s_barrier
	s_add_i32 vcc_lo, vcc_lo, 2
	s_add_u32 s58, s58, 0x100
	s_addc_u32 s59, s59, 0
	s_add_u32 s96, s96, 0x100
	s_addc_u32 s97, s97, 0
	s_cmp_gt_u32 vcc_lo, 13
	s_cbranch_scc0 .LBB0_459
	s_and_b64 vcc, exec, s[10:11]
	s_cbranch_vccz .LBB0_462
	s_barrier

; #define PG8_STAGE(bufoff, gbase, voff) do { _Pragma("unroll") for (int _i = 0; _i < 2; ++_i) \
;         __builtin_amdgcn_global_load_lds((const unsigned*)((const char*)(gbase) + (voff)[_i]), (PG8_LAS unsigned*)(lds + (bufoff) + ldsw + _i * 8192), 16, 0, 0); } while (0)
; #define PG8_LDA(dst, b, h) do { _Pragma("unroll") for (int m = 0; m < 4; ++m) _Pragma("unroll") for (int k = 0; k < 2; ++k) dst[m][k] = *(const PG8_LAS bf16x8*)(lds + PG8_SA(b, h) + aoff + m * 2048 + k * 1024); } while (0)
; #define PG8_LDB(dst, b, h) do { _Pragma("unroll") for (int n = 0; n < 2; ++n) _Pragma("unroll") for (int k = 0; k < 2; ++k) dst[n][k] = *(const PG8_LAS bf16x8*)(lds + PG8_SB(b, h) + boff + n * 2048 + k * 1024); } while (0)
; #define PG8_MMA(ai, bj, At, Bt) do { __builtin_amdgcn_s_setprio(1); _Pragma("unroll") for (int m = 0; m < 4; ++m) _Pragma("unroll") for (int n = 0; n < 2; ++n) _Pragma("unroll") for (int k = 0; k < 2; ++k) \
;         acc[ai][bj][m][n] = __builtin_amdgcn_mfma_f32_16x16x32_bf16(Bt[n][k], At[m][k], acc[ai][bj][m][n], 0, 0, 0); __builtin_amdgcn_s_setprio(0); } while (0)
; #define PG8_WAIT_V(n) asm volatile("s_waitcnt vmcnt(" #n ")" ::: "memory")
; #define PG8_WAIT_L(n) asm volatile("s_waitcnt lgkmcnt(" #n ")" ::: "memory")
; #define PG8_BAR __builtin_amdgcn_s_barrier()
; #define PG8_SCHED __builtin_amdgcn_sched_barrier(0)
; template <class Epi, class Sched, bool ALIGN_EPI = false, bool SP2 = false>
; __device__ __forceinline__ void gemm_phase(PG8_LAS unsigned char* lds, const Gemm g, const Sched& S, const Epi& E) {
;     ...
;             PG8_LDB(B0, 0, 0); PG8_LDB(B1, 0, 1); PG8_SCHED; PG8_LDA(At, 0, 0); PG8_STAGE(PG8_SA(1, 1), a1 + hstep, voffA);
;             PG8_WAIT_V(8); PG8_WAIT_L(0); PG8_BAR; PG8_MMA(0, 0, At, B0); PG8_MMA(0, 1, At, B1); PG8_BAR; PG8_SCHED;
;             PG8_LDA(At, 0, 1); PG8_STAGE(PG8_SB(0, 0), b2, voffB); PG8_STAGE(PG8_SB(0, 1), b2 + hstep, voffB); PG8_STAGE(PG8_SA(0, 0), a2, voffA);
.LBB0_495:
	ds_read_b128 v[170:173], v165
	ds_read_b128 v[174:177], v165 offset:1024
	ds_read_b128 v[182:185], v165 offset:2048
	ds_read_b128 v[186:189], v165 offset:3072
	ds_read_b128 v[190:193], v168
	ds_read_b128 v[194:197], v168 offset:1024
	ds_read_b128 v[198:201], v168 offset:2048
	ds_read_b128 v[208:211], v168 offset:3072
	s_add_u32 s3, s60, 0xfffc0080
	s_addc_u32 s14, s61, -1
	s_cmp_eq_u32 s97, 12
	s_cselect_b32 s65, s49, s14
	s_cselect_b32 s64, s57, s3
	s_cselect_b32 s63, s45, s96
	s_cselect_b32 s62, s94, s95
	v_lshl_add_u64 v[178:179], s[60:61], 0, v[160:161]
	s_add_i32 m0, s59, 0xc000
	ds_read_b128 v[212:215], v164
	ds_read_b128 v[216:219], v164 offset:1024
	ds_read_b128 v[220:223], v164 offset:2048
	ds_read_b128 v[224:227], v164 offset:3072
	ds_read_b128 v[228:231], v164 offset:4096
	ds_read_b128 v[232:235], v164 offset:5120
	ds_read_b128 v[236:239], v164 offset:6144
	ds_read_b128 v[240:243], v164 offset:7168
	global_load_lds_dwordx4 v[178:179], off
	v_lshl_add_u64 v[178:179], s[60:61], 0, v[162:163]
	s_add_i32 m0, s59, 0xe000
	s_nop 0
	global_load_lds_dwordx4 v[178:179], off
	s_waitcnt vmcnt(8)
	s_waitcnt lgkmcnt(0)
	s_barrier
	s_setprio 1
	s_waitcnt lgkmcnt(0)
	v_mfma_f32_16x16x32_bf16 v[124:127], v[170:173], v[212:215], v[124:127]
	v_mfma_f32_16x16x32_bf16 v[112:115], v[182:185], v[220:223], v[112:115]
	v_mfma_f32_16x16x32_bf16 v[108:111], v[170:173], v[228:231], v[108:111]
	v_mfma_f32_16x16x32_bf16 v[96:99], v[182:185], v[236:239], v[96:99]
	v_mfma_f32_16x16x32_bf16 v[116:119], v[170:173], v[220:223], v[116:119]
	v_mfma_f32_16x16x32_bf16 v[120:123], v[182:185], v[212:215], v[120:123]
	v_mfma_f32_16x16x32_bf16 v[100:103], v[170:173], v[236:239], v[100:103]
	v_mfma_f32_16x16x32_bf16 v[104:107], v[182:185], v[228:231], v[104:107]
	v_mfma_f32_16x16x32_bf16 v[124:127], v[174:177], v[216:219], v[124:127]
	v_mfma_f32_16x16x32_bf16 v[112:115], v[186:189], v[224:227], v[112:115]
	v_mfma_f32_16x16x32_bf16 v[108:111], v[174:177], v[232:235], v[108:111]
	v_mfma_f32_16x16x32_bf16 v[96:99], v[186:189], v[240:243], v[96:99]
	v_mfma_f32_16x16x32_bf16 v[116:119], v[174:177], v[224:227], v[116:119]
	v_mfma_f32_16x16x32_bf16 v[120:123], v[186:189], v[216:219], v[120:123]
	v_mfma_f32_16x16x32_bf16 v[100:103], v[174:177], v[240:243], v[100:103]
	v_mfma_f32_16x16x32_bf16 v[104:107], v[186:189], v[232:235], v[104:107]
	s_setprio 0
	s_setprio 1
	v_mfma_f32_16x16x32_bf16 v[60:63], v[190:193], v[212:215], v[60:63]
	v_mfma_f32_16x16x32_bf16 v[48:51], v[198:201], v[220:223], v[48:51]
	v_mfma_f32_16x16x32_bf16 v[44:47], v[190:193], v[228:231], v[44:47]
	v_mfma_f32_16x16x32_bf16 v[32:35], v[198:201], v[236:239], v[32:35]
	v_mfma_f32_16x16x32_bf16 v[52:55], v[190:193], v[220:223], v[52:55]
	v_mfma_f32_16x16x32_bf16 v[56:59], v[198:201], v[212:215], v[56:59]
	v_mfma_f32_16x16x32_bf16 v[36:39], v[190:193], v[236:239], v[36:39]
	v_mfma_f32_16x16x32_bf16 v[40:43], v[198:201], v[228:231], v[40:43]
	v_mfma_f32_16x16x32_bf16 v[60:63], v[194:197], v[216:219], v[60:63]
	v_mfma_f32_16x16x32_bf16 v[48:51], v[208:211], v[224:227], v[48:51]
	v_mfma_f32_16x16x32_bf16 v[44:47], v[194:197], v[232:235], v[44:47]
	v_mfma_f32_16x16x32_bf16 v[32:35], v[208:211], v[240:243], v[32:35]
	v_mfma_f32_16x16x32_bf16 v[52:55], v[194:197], v[224:227], v[52:55]
	v_mfma_f32_16x16x32_bf16 v[56:59], v[208:211], v[216:219], v[56:59]
	v_mfma_f32_16x16x32_bf16 v[36:39], v[194:197], v[240:243], v[36:39]
	v_mfma_f32_16x16x32_bf16 v[40:43], v[208:211], v[232:235], v[40:43]
	s_setprio 0
	s_barrier
	s_add_i32 s3, s92, s75
	v_lshl_add_u64 v[178:179], s[62:63], 0, v[130:131]
	s_mov_b32 m0, s3
	ds_read_b128 v[212:215], v164 offset:16384
	ds_read_b128 v[216:219], v164 offset:17408
	ds_read_b128 v[220:223], v164 offset:18432
	ds_read_b128 v[224:227], v164 offset:19456
	ds_read_b128 v[228:231], v164 offset:20480
	ds_read_b128 v[232:235], v164 offset:21504
	ds_read_b128 v[236:239], v164 offset:22528
	ds_read_b128 v[240:243], v164 offset:23552
	global_load_lds_dwordx4 v[178:179], off
	s_add_i32 m0, s3, 0x2000
	s_add_u32 s14, s62, 0x40000
	v_lshl_add_u64 v[202:203], s[62:63], 0, v[134:135]
	s_addc_u32 s15, s63, 0
	s_add_i32 s3, s93, s75
	global_load_lds_dwordx4 v[202:203], off
	v_lshl_add_u64 v[244:245], s[14:15], 0, v[130:131]
	s_mov_b32 m0, s3
	global_load_lds_dwordx4 v[244:245], off
	v_lshl_add_u64 v[244:245], s[14:15], 0, v[134:135]
	s_add_i32 m0, s3, 0x2000
	s_nop 0
	global_load_lds_dwordx4 v[244:245], off
	s_waitcnt vmcnt(6)
	s_waitcnt lgkmcnt(0)
	s_barrier
; #define PG8_STAGE(bufoff, gbase, voff) do { _Pragma("unroll") for (int _i = 0; _i < 2; ++_i) \
;         __builtin_amdgcn_global_load_lds((const unsigned*)((const char*)(gbase) + (voff)[_i]), (PG8_LAS unsigned*)(lds + (bufoff) + ldsw + _i * 8192), 16, 0, 0); } while (0)
; #define PG8_LDA(dst, b, h) do { _Pragma("unroll") for (int m = 0; m < 4; ++m) _Pragma("unroll") for (int k = 0; k < 2; ++k) dst[m][k] = *(const PG8_LAS bf16x8*)(lds + PG8_SA(b, h) + aoff + m * 2048 + k * 1024); } while (0)
; #define PG8_LDB(dst, b, h) do { _Pragma("unroll") for (int n = 0; n < 2; ++n) _Pragma("unroll") for (int k = 0; k < 2; ++k) dst[n][k] = *(const PG8_LAS bf16x8*)(lds + PG8_SB(b, h) + boff + n * 2048 + k * 1024); } while (0)
; #define PG8_MMA(ai, bj, At, Bt) do { __builtin_amdgcn_s_setprio(1); _Pragma("unroll") for (int m = 0; m < 4; ++m) _Pragma("unroll") for (int n = 0; n < 2; ++n) _Pragma("unroll") for (int k = 0; k < 2; ++k) \
;         acc[ai][bj][m][n] = __builtin_amdgcn_mfma_f32_16x16x32_bf16(Bt[n][k], At[m][k], acc[ai][bj][m][n], 0, 0, 0); __builtin_amdgcn_s_setprio(0); } while (0)
; #define PG8_WAIT_V(n) asm volatile("s_waitcnt vmcnt(" #n ")" ::: "memory")
; #define PG8_WAIT_L(n) asm volatile("s_waitcnt lgkmcnt(" #n ")" ::: "memory")
; #define PG8_BAR __builtin_amdgcn_s_barrier()
; #define PG8_SCHED __builtin_amdgcn_sched_barrier(0)
; template <class Epi, class Sched, bool ALIGN_EPI = false, bool SP2 = false>
; __device__ __forceinline__ void gemm_phase(PG8_LAS unsigned char* lds, const Gemm g, const Sched& S, const Epi& E) {
;     ...
;             PG8_WAIT_V(8); PG8_WAIT_L(0); PG8_BAR; PG8_MMA(1, 0, At, B0); PG8_MMA(1, 1, At, B1); PG8_BAR; PG8_SCHED;
;             PG8_LDB(B0, 1, 0); PG8_LDB(B1, 1, 1); PG8_SCHED; PG8_LDA(At, 1, 0); PG8_STAGE(PG8_SA(0, 1), a2 + hstep, voffA);
;             PG8_WAIT_V(8); PG8_WAIT_L(0); PG8_BAR; PG8_MMA(0, 0, At, B0); PG8_MMA(0, 1, At, B1); PG8_BAR; PG8_SCHED;
	s_setprio 1
	s_waitcnt lgkmcnt(0)
	v_mfma_f32_16x16x32_bf16 v[92:95], v[170:173], v[212:215], v[92:95]
	v_mfma_f32_16x16x32_bf16 v[80:83], v[182:185], v[220:223], v[80:83]
	v_mfma_f32_16x16x32_bf16 v[76:79], v[170:173], v[228:231], v[76:79]
	v_mfma_f32_16x16x32_bf16 v[64:67], v[182:185], v[236:239], v[64:67]
	v_mfma_f32_16x16x32_bf16 v[84:87], v[170:173], v[220:223], v[84:87]
	v_mfma_f32_16x16x32_bf16 v[88:91], v[182:185], v[212:215], v[88:91]
	v_mfma_f32_16x16x32_bf16 v[68:71], v[170:173], v[236:239], v[68:71]
	v_mfma_f32_16x16x32_bf16 v[72:75], v[182:185], v[228:231], v[72:75]
	v_mfma_f32_16x16x32_bf16 v[92:95], v[174:177], v[216:219], v[92:95]
	v_mfma_f32_16x16x32_bf16 v[80:83], v[186:189], v[224:227], v[80:83]
	v_mfma_f32_16x16x32_bf16 v[76:79], v[174:177], v[232:235], v[76:79]
	v_mfma_f32_16x16x32_bf16 v[64:67], v[186:189], v[240:243], v[64:67]
	v_mfma_f32_16x16x32_bf16 v[84:87], v[174:177], v[224:227], v[84:87]
	v_mfma_f32_16x16x32_bf16 v[88:91], v[186:189], v[216:219], v[88:91]
	v_lshl_add_u64 v[244:245], s[64:65], 0, v[128:129]
	s_mov_b32 m0, s59
	s_nop 0
	global_load_lds_dwordx4 v[244:245], off
	v_mfma_f32_16x16x32_bf16 v[68:71], v[174:177], v[240:243], v[68:71]
	v_mfma_f32_16x16x32_bf16 v[72:75], v[186:189], v[232:235], v[72:75]
	s_setprio 0
	s_setprio 1
	v_mfma_f32_16x16x32_bf16 v[28:31], v[190:193], v[212:215], v[28:31]
	v_mfma_f32_16x16x32_bf16 v[16:19], v[198:201], v[220:223], v[16:19]
	v_mfma_f32_16x16x32_bf16 v[12:15], v[190:193], v[228:231], v[12:15]
	v_mfma_f32_16x16x32_bf16 v[0:3], v[198:201], v[236:239], v[0:3]
	v_mfma_f32_16x16x32_bf16 v[20:23], v[190:193], v[220:223], v[20:23]
	v_mfma_f32_16x16x32_bf16 v[24:27], v[198:201], v[212:215], v[24:27]
	v_mfma_f32_16x16x32_bf16 v[4:7], v[190:193], v[236:239], v[4:7]
	v_mfma_f32_16x16x32_bf16 v[8:11], v[198:201], v[228:231], v[8:11]
	v_mfma_f32_16x16x32_bf16 v[28:31], v[194:197], v[216:219], v[28:31]
	v_mfma_f32_16x16x32_bf16 v[16:19], v[208:211], v[224:227], v[16:19]
	v_mfma_f32_16x16x32_bf16 v[12:15], v[194:197], v[232:235], v[12:15]
	v_mfma_f32_16x16x32_bf16 v[0:3], v[208:211], v[240:243], v[0:3]
	v_mfma_f32_16x16x32_bf16 v[20:23], v[194:197], v[224:227], v[20:23]
	v_mfma_f32_16x16x32_bf16 v[24:27], v[208:211], v[216:219], v[24:27]
	v_lshl_add_u64 v[246:247], s[64:65], 0, v[132:133]
	s_mov_b32 m0, s84
	s_nop 0
	global_load_lds_dwordx4 v[246:247], off
	v_mfma_f32_16x16x32_bf16 v[4:7], v[194:197], v[240:243], v[4:7]
	v_mfma_f32_16x16x32_bf16 v[8:11], v[208:211], v[232:235], v[8:11]
	s_setprio 0
	s_barrier
	s_add_i32 s3, 0, 0x18000
	v_add_u32_e32 v136, s3, v141
	s_add_i32 s33, 0, 0x1c000
	ds_read_b128 v[170:173], v136
	ds_read_b128 v[174:177], v136 offset:1024
	ds_read_b128 v[182:185], v136 offset:2048
	ds_read_b128 v[186:189], v136 offset:3072
	v_add_u32_e32 v136, s33, v141
	ds_read_b128 v[190:193], v136
	ds_read_b128 v[194:197], v136 offset:1024
	ds_read_b128 v[198:201], v136 offset:2048
	ds_read_b128 v[208:211], v136 offset:3072
	s_add_u32 s14, s64, 0x40000
	s_addc_u32 s15, s65, 0
	s_mov_b32 m0, s85
	v_lshl_add_u64 v[248:249], s[14:15], 0, v[128:129]
	ds_read_b128 v[212:215], v164 offset:32768
	ds_read_b128 v[216:219], v164 offset:33792
	ds_read_b128 v[220:223], v164 offset:34816
	ds_read_b128 v[224:227], v164 offset:35840
	ds_read_b128 v[228:231], v164 offset:36864
	ds_read_b128 v[232:235], v164 offset:37888
	ds_read_b128 v[236:239], v164 offset:38912
	ds_read_b128 v[240:243], v164 offset:39936
	global_load_lds_dwordx4 v[248:249], off
	v_lshl_add_u64 v[248:249], s[14:15], 0, v[132:133]
	s_mov_b32 m0, s86
	s_nop 0
	global_load_lds_dwordx4 v[248:249], off
	s_waitcnt vmcnt(8)
	s_waitcnt lgkmcnt(0)
	s_barrier
	s_setprio 1
	s_waitcnt lgkmcnt(0)
	v_mfma_f32_16x16x32_bf16 v[124:127], v[170:173], v[212:215], v[124:127]
	v_mfma_f32_16x16x32_bf16 v[112:115], v[182:185], v[220:223], v[112:115]
	v_mfma_f32_16x16x32_bf16 v[108:111], v[170:173], v[228:231], v[108:111]
	v_mfma_f32_16x16x32_bf16 v[96:99], v[182:185], v[236:239], v[96:99]
	v_mfma_f32_16x16x32_bf16 v[116:119], v[170:173], v[220:223], v[116:119]
	v_mfma_f32_16x16x32_bf16 v[120:123], v[182:185], v[212:215], v[120:123]
	v_mfma_f32_16x16x32_bf16 v[100:103], v[170:173], v[236:239], v[100:103]
	v_mfma_f32_16x16x32_bf16 v[104:107], v[182:185], v[228:231], v[104:107]
	v_mfma_f32_16x16x32_bf16 v[124:127], v[174:177], v[216:219], v[124:127]
	v_mfma_f32_16x16x32_bf16 v[112:115], v[186:189], v[224:227], v[112:115]
	v_mfma_f32_16x16x32_bf16 v[108:111], v[174:177], v[232:235], v[108:111]
	v_mfma_f32_16x16x32_bf16 v[96:99], v[186:189], v[240:243], v[96:99]
	v_mfma_f32_16x16x32_bf16 v[116:119], v[174:177], v[224:227], v[116:119]
	v_mfma_f32_16x16x32_bf16 v[120:123], v[186:189], v[216:219], v[120:123]
	v_mfma_f32_16x16x32_bf16 v[100:103], v[174:177], v[240:243], v[100:103]
	v_mfma_f32_16x16x32_bf16 v[104:107], v[186:189], v[232:235], v[104:107]
	s_setprio 0
	s_setprio 1
	v_mfma_f32_16x16x32_bf16 v[60:63], v[190:193], v[212:215], v[60:63]
	v_mfma_f32_16x16x32_bf16 v[48:51], v[198:201], v[220:223], v[48:51]
	v_mfma_f32_16x16x32_bf16 v[44:47], v[190:193], v[228:231], v[44:47]
	v_mfma_f32_16x16x32_bf16 v[32:35], v[198:201], v[236:239], v[32:35]
	v_mfma_f32_16x16x32_bf16 v[52:55], v[190:193], v[220:223], v[52:55]
	v_mfma_f32_16x16x32_bf16 v[56:59], v[198:201], v[212:215], v[56:59]
	v_mfma_f32_16x16x32_bf16 v[36:39], v[190:193], v[236:239], v[36:39]
	v_mfma_f32_16x16x32_bf16 v[40:43], v[198:201], v[228:231], v[40:43]
	v_mfma_f32_16x16x32_bf16 v[60:63], v[194:197], v[216:219], v[60:63]
	v_mfma_f32_16x16x32_bf16 v[48:51], v[208:211], v[224:227], v[48:51]
	v_mfma_f32_16x16x32_bf16 v[44:47], v[194:197], v[232:235], v[44:47]
	v_mfma_f32_16x16x32_bf16 v[32:35], v[208:211], v[240:243], v[32:35]
	v_mfma_f32_16x16x32_bf16 v[52:55], v[194:197], v[224:227], v[52:55]
	v_mfma_f32_16x16x32_bf16 v[56:59], v[208:211], v[216:219], v[56:59]
	v_mfma_f32_16x16x32_bf16 v[36:39], v[194:197], v[240:243], v[36:39]
	v_mfma_f32_16x16x32_bf16 v[40:43], v[208:211], v[232:235], v[40:43]
	s_setprio 0
	s_barrier
; #define PG8_STAGE(bufoff, gbase, voff) do { _Pragma("unroll") for (int _i = 0; _i < 2; ++_i) \
;         __builtin_amdgcn_global_load_lds((const unsigned*)((const char*)(gbase) + (voff)[_i]), (PG8_LAS unsigned*)(lds + (bufoff) + ldsw + _i * 8192), 16, 0, 0); } while (0)
; #define PG8_LDA(dst, b, h) do { _Pragma("unroll") for (int m = 0; m < 4; ++m) _Pragma("unroll") for (int k = 0; k < 2; ++k) dst[m][k] = *(const PG8_LAS bf16x8*)(lds + PG8_SA(b, h) + aoff + m * 2048 + k * 1024); } while (0)
; #define PG8_MMA(ai, bj, At, Bt) do { __builtin_amdgcn_s_setprio(1); _Pragma("unroll") for (int m = 0; m < 4; ++m) _Pragma("unroll") for (int n = 0; n < 2; ++n) _Pragma("unroll") for (int k = 0; k < 2; ++k) \
;         acc[ai][bj][m][n] = __builtin_amdgcn_mfma_f32_16x16x32_bf16(Bt[n][k], At[m][k], acc[ai][bj][m][n], 0, 0, 0); __builtin_amdgcn_s_setprio(0); } while (0)
; #define PG8_WAIT_V(n) asm volatile("s_waitcnt vmcnt(" #n ")" ::: "memory")
; #define PG8_WAIT_L(n) asm volatile("s_waitcnt lgkmcnt(" #n ")" ::: "memory")
; #define PG8_BAR __builtin_amdgcn_s_barrier()
; #define PG8_SCHED __builtin_amdgcn_sched_barrier(0)
; template <class Epi, class Sched, bool ALIGN_EPI = false, bool SP2 = false>
; __device__ __forceinline__ void gemm_phase(PG8_LAS unsigned char* lds, const Gemm g, const Sched& S, const Epi& E) {
;     ...
;             PG8_LDA(At, 1, 1); PG8_STAGE(PG8_SB(1, 0), b3, voffB); PG8_STAGE(PG8_SB(1, 1), b3 + hstep, voffB); PG8_STAGE(PG8_SA(1, 0), a3, voffA);
;             PG8_WAIT_V(8); PG8_WAIT_L(0); PG8_BAR; PG8_MMA(1, 0, At, B0); PG8_MMA(1, 1, At, B1); PG8_BAR; PG8_SCHED;
	s_add_i32 s3, s3, s75
	v_lshl_add_u64 v[178:179], v[178:179], 0, s[10:11]
	s_mov_b32 m0, s3
	ds_read_b128 v[212:215], v164 offset:49152
	ds_read_b128 v[216:219], v164 offset:50176
	ds_read_b128 v[220:223], v164 offset:51200
	ds_read_b128 v[224:227], v164 offset:52224
	ds_read_b128 v[228:231], v164 offset:53248
	ds_read_b128 v[232:235], v164 offset:54272
	ds_read_b128 v[236:239], v164 offset:55296
	ds_read_b128 v[240:243], v164 offset:56320
	global_load_lds_dwordx4 v[178:179], off
	s_add_i32 m0, s3, 0x2000
	s_add_u32 s14, s62, 0x40080
	v_lshl_add_u64 v[178:179], v[202:203], 0, s[10:11]
	s_addc_u32 s15, s63, 0
	s_add_i32 s3, s33, s75
	global_load_lds_dwordx4 v[178:179], off
	v_lshl_add_u64 v[178:179], s[14:15], 0, v[130:131]
	s_mov_b32 m0, s3
	s_nop 0
	global_load_lds_dwordx4 v[178:179], off
	v_lshl_add_u64 v[178:179], s[14:15], 0, v[134:135]
	s_add_i32 m0, s3, 0x2000
	s_nop 0
	global_load_lds_dwordx4 v[178:179], off
	s_waitcnt vmcnt(6)
	s_waitcnt lgkmcnt(0)
	s_barrier
	s_setprio 1
	s_waitcnt lgkmcnt(0)
	v_mfma_f32_16x16x32_bf16 v[92:95], v[170:173], v[212:215], v[92:95]
	v_mfma_f32_16x16x32_bf16 v[80:83], v[182:185], v[220:223], v[80:83]
	v_mfma_f32_16x16x32_bf16 v[76:79], v[170:173], v[228:231], v[76:79]
	v_mfma_f32_16x16x32_bf16 v[64:67], v[182:185], v[236:239], v[64:67]
	v_mfma_f32_16x16x32_bf16 v[84:87], v[170:173], v[220:223], v[84:87]
	v_mfma_f32_16x16x32_bf16 v[88:91], v[182:185], v[212:215], v[88:91]
	v_mfma_f32_16x16x32_bf16 v[68:71], v[170:173], v[236:239], v[68:71]
	v_mfma_f32_16x16x32_bf16 v[72:75], v[182:185], v[228:231], v[72:75]
	v_mfma_f32_16x16x32_bf16 v[92:95], v[174:177], v[216:219], v[92:95]
	v_mfma_f32_16x16x32_bf16 v[80:83], v[186:189], v[224:227], v[80:83]
	v_mfma_f32_16x16x32_bf16 v[76:79], v[174:177], v[232:235], v[76:79]
	v_mfma_f32_16x16x32_bf16 v[64:67], v[186:189], v[240:243], v[64:67]
	v_mfma_f32_16x16x32_bf16 v[84:87], v[174:177], v[224:227], v[84:87]
	v_mfma_f32_16x16x32_bf16 v[88:91], v[186:189], v[216:219], v[88:91]
	v_lshl_add_u64 v[178:179], v[244:245], 0, s[10:11]
	s_mov_b32 m0, s88
	s_nop 0
	global_load_lds_dwordx4 v[178:179], off
	v_mfma_f32_16x16x32_bf16 v[68:71], v[174:177], v[240:243], v[68:71]
	v_mfma_f32_16x16x32_bf16 v[72:75], v[186:189], v[232:235], v[72:75]
	s_setprio 0
	s_setprio 1
	v_mfma_f32_16x16x32_bf16 v[28:31], v[190:193], v[212:215], v[28:31]
	v_mfma_f32_16x16x32_bf16 v[16:19], v[198:201], v[220:223], v[16:19]
	v_mfma_f32_16x16x32_bf16 v[12:15], v[190:193], v[228:231], v[12:15]
	v_mfma_f32_16x16x32_bf16 v[0:3], v[198:201], v[236:239], v[0:3]
	v_mfma_f32_16x16x32_bf16 v[20:23], v[190:193], v[220:223], v[20:23]
	v_mfma_f32_16x16x32_bf16 v[24:27], v[198:201], v[212:215], v[24:27]
	v_mfma_f32_16x16x32_bf16 v[4:7], v[190:193], v[236:239], v[4:7]
	v_mfma_f32_16x16x32_bf16 v[8:11], v[198:201], v[228:231], v[8:11]
	v_mfma_f32_16x16x32_bf16 v[28:31], v[194:197], v[216:219], v[28:31]
	v_mfma_f32_16x16x32_bf16 v[16:19], v[208:211], v[224:227], v[16:19]
	v_mfma_f32_16x16x32_bf16 v[12:15], v[194:197], v[232:235], v[12:15]
	v_mfma_f32_16x16x32_bf16 v[0:3], v[208:211], v[240:243], v[0:3]
	v_mfma_f32_16x16x32_bf16 v[20:23], v[194:197], v[224:227], v[20:23]
	v_mfma_f32_16x16x32_bf16 v[24:27], v[208:211], v[216:219], v[24:27]
	v_lshl_add_u64 v[178:179], v[246:247], 0, s[10:11]
	s_mov_b32 m0, s89
	s_nop 0
	global_load_lds_dwordx4 v[178:179], off
	v_mfma_f32_16x16x32_bf16 v[4:7], v[194:197], v[240:243], v[4:7]
	v_mfma_f32_16x16x32_bf16 v[8:11], v[208:211], v[232:235], v[8:11]
	s_setprio 0
	s_barrier
	s_add_i32 s97, s97, 2
	s_add_u32 s60, s60, 0x100
	s_addc_u32 s61, s61, 0
	s_add_u32 s95, s95, 0x100
	s_addc_u32 s96, s96, 0
	s_cmp_lt_u32 s97, 14
	s_cbranch_scc1 .LBB0_495
	s_andn2_b64 vcc, exec, s[40:41]
	s_cbranch_vccnz .LBB0_498
	s_barrier

; #define PG8_STAGE(bufoff, gbase, voff) do { _Pragma("unroll") for (int _i = 0; _i < 2; ++_i) \
;         __builtin_amdgcn_global_load_lds((const unsigned*)((const char*)(gbase) + (voff)[_i]), (PG8_LAS unsigned*)(lds + (bufoff) + ldsw + _i * 8192), 16, 0, 0); } while (0)
; #define PG8_LDA(dst, b, h) do { _Pragma("unroll") for (int m = 0; m < 4; ++m) _Pragma("unroll") for (int k = 0; k < 2; ++k) dst[m][k] = *(const PG8_LAS bf16x8*)(lds + PG8_SA(b, h) + aoff + m * 2048 + k * 1024); } while (0)
; #define PG8_LDB(dst, b, h) do { _Pragma("unroll") for (int n = 0; n < 2; ++n) _Pragma("unroll") for (int k = 0; k < 2; ++k) dst[n][k] = *(const PG8_LAS bf16x8*)(lds + PG8_SB(b, h) + boff + n * 2048 + k * 1024); } while (0)
; #define PG8_MMA(ai, bj, At, Bt) do { __builtin_amdgcn_s_setprio(1); _Pragma("unroll") for (int m = 0; m < 4; ++m) _Pragma("unroll") for (int n = 0; n < 2; ++n) _Pragma("unroll") for (int k = 0; k < 2; ++k) \
;         acc[ai][bj][m][n] = __builtin_amdgcn_mfma_f32_16x16x32_bf16(Bt[n][k], At[m][k], acc[ai][bj][m][n], 0, 0, 0); __builtin_amdgcn_s_setprio(0); } while (0)
; #define PG8_WAIT_V(n) asm volatile("s_waitcnt vmcnt(" #n ")" ::: "memory")
; template <class Epi, class Sched, bool ALIGN_EPI = false, bool SP2 = false>
; __device__ __forceinline__ void gemm_phase(PG8_LAS unsigned char* lds, const Gemm g, const Sched& S, const Epi& E) {
;     ...
;         const char* nA = has_next ? (const char*)g.A + (size_t)nxt.pm * tstep : cA; const char* nB = has_next ? (const char*)g.Bt + (size_t)nxt.pn * tstep : cB;
;         for (int t = 0; t < nt; t += 2) {
;             const bool last = (t == nt - 2);
;             const char* a1 = cA + (size_t)(t + 1) * kstep;
;             const char* a2 = last ? nA : cA + (size_t)(t + 2) * kstep; const char* b2 = last ? nB : cB + (size_t)(t + 2) * kstep;
;             const char* a3 = a2 + kstep; const char* b3 = b2 + kstep;
;             if (last && has_next) S.a_ready(nxt);
;             if constexpr (SP2) {
;             PG8_LDB(B0, 0, 0); PG8_LDB(B1, 0, 1); PG8_SCHED; PG8_LDA(At, 0, 0); PG8_STAGE(PG8_SA(1, 1), a1 + hstep, voffA);
;             PG8_WAIT_V(8); PG8_WAIT_L(0); PG8_BAR; PG8_MMA(0, 0, At, B0); PG8_MMA(0, 1, At, B1); PG8_BAR; PG8_SCHED;
;             PG8_LDA(At, 0, 1); PG8_STAGE(PG8_SB(0, 0), b2, voffB); PG8_STAGE(PG8_SB(0, 1), b2 + hstep, voffB); PG8_STAGE(PG8_SA(0, 0), a2, voffA);
.LBB0_649:
	s_ashr_i32 s51, s50, 31
	s_lshl_b64 s[14:15], s[50:51], 19
	s_add_u32 s52, s40, s14
	s_addc_u32 s53, s41, s15
	s_and_b64 s[14:15], s[8:9], exec
	s_cselect_b32 s51, s53, s61
	s_cselect_b32 s57, s52, s60
	s_ashr_i32 s49, s48, 31
	s_lshl_b64 s[14:15], s[48:49], 19
	s_add_u32 s54, s82, s14
	s_addc_u32 s55, s83, s15
	s_and_b64 s[14:15], s[8:9], exec
	s_cselect_b32 s49, s55, s63
	s_cselect_b32 s89, s54, s62
	s_add_u32 s60, s60, 0x40080
	s_addc_u32 s61, s61, 0
	s_add_u32 s90, s62, 0x100
	s_addc_u32 s91, s63, 0
	s_mov_b32 s92, -2
	s_waitcnt lgkmcnt(0)
	s_waitcnt vmcnt(0)
	ds_read_b128 v[148:151], v155
	ds_read_b128 v[160:163], v155 offset:1024
	ds_read_b128 v[164:167], v155 offset:2048
	ds_read_b128 v[168:171], v155 offset:3072
	ds_read_b128 v[172:175], v156
	ds_read_b128 v[176:179], v156 offset:1024
	ds_read_b128 v[182:185], v156 offset:2048
	ds_read_b128 v[186:189], v156 offset:3072
	s_add_u32 s3, s60, 0xfffc0080
	s_addc_u32 s14, s61, -1
	s_cmp_eq_u32 s92, 12
	s_cselect_b32 s65, s51, s14
	s_cselect_b32 s64, s57, s3
	s_cselect_b32 s63, s49, s91
	s_cselect_b32 s62, s89, s90
	v_lshl_add_u64 v[202:203], s[60:61], 0, v[140:141]
	s_add_i32 m0, s43, 0xc000
	ds_read_b128 v[190:193], v157
	ds_read_b128 v[194:197], v157 offset:1024
	ds_read_b128 v[198:201], v157 offset:2048
	ds_read_b128 v[208:211], v157 offset:3072
	ds_read_b128 v[212:215], v157 offset:4096
	ds_read_b128 v[216:219], v157 offset:5120
	ds_read_b128 v[220:223], v157 offset:6144
	ds_read_b128 v[224:227], v157 offset:7168
	global_load_lds_dwordx4 v[202:203], off
	v_lshl_add_u64 v[202:203], s[60:61], 0, v[142:143]
	s_add_i32 m0, s43, 0xe000
	s_nop 0
	global_load_lds_dwordx4 v[202:203], off
	s_waitcnt vmcnt(8)
	s_waitcnt lgkmcnt(0)
	s_barrier
	s_setprio 1
	s_waitcnt lgkmcnt(0)
	v_mfma_f32_16x16x32_bf16 v[124:127], v[148:151], v[190:193], 0
	v_mfma_f32_16x16x32_bf16 v[104:107], v[164:167], v[198:201], 0
	v_mfma_f32_16x16x32_bf16 v[92:95], v[148:151], v[212:215], 0
	v_mfma_f32_16x16x32_bf16 v[72:75], v[164:167], v[220:223], 0
	v_mfma_f32_16x16x32_bf16 v[108:111], v[148:151], v[198:201], 0
	v_mfma_f32_16x16x32_bf16 v[120:123], v[164:167], v[190:193], 0
	v_mfma_f32_16x16x32_bf16 v[76:79], v[148:151], v[220:223], 0
	v_mfma_f32_16x16x32_bf16 v[88:91], v[164:167], v[212:215], 0
	v_mfma_f32_16x16x32_bf16 v[124:127], v[160:163], v[194:197], v[124:127]
	v_mfma_f32_16x16x32_bf16 v[104:107], v[168:171], v[208:211], v[104:107]
	v_mfma_f32_16x16x32_bf16 v[92:95], v[160:163], v[216:219], v[92:95]
	v_mfma_f32_16x16x32_bf16 v[72:75], v[168:171], v[224:227], v[72:75]
	v_mfma_f32_16x16x32_bf16 v[108:111], v[160:163], v[208:211], v[108:111]
	v_mfma_f32_16x16x32_bf16 v[120:123], v[168:171], v[194:197], v[120:123]
	v_mfma_f32_16x16x32_bf16 v[76:79], v[160:163], v[224:227], v[76:79]
	v_mfma_f32_16x16x32_bf16 v[88:91], v[168:171], v[216:219], v[88:91]
	s_setprio 0
	s_setprio 1
	v_mfma_f32_16x16x32_bf16 v[116:119], v[172:175], v[190:193], 0
	v_mfma_f32_16x16x32_bf16 v[96:99], v[182:185], v[198:201], 0
	v_mfma_f32_16x16x32_bf16 v[84:87], v[172:175], v[212:215], 0
	v_mfma_f32_16x16x32_bf16 v[64:67], v[182:185], v[220:223], 0
	v_mfma_f32_16x16x32_bf16 v[100:103], v[172:175], v[198:201], 0
	v_mfma_f32_16x16x32_bf16 v[112:115], v[182:185], v[190:193], 0
	v_mfma_f32_16x16x32_bf16 v[68:71], v[172:175], v[220:223], 0
	v_mfma_f32_16x16x32_bf16 v[80:83], v[182:185], v[212:215], 0
	v_mfma_f32_16x16x32_bf16 v[116:119], v[176:179], v[194:197], v[116:119]
	v_mfma_f32_16x16x32_bf16 v[96:99], v[186:189], v[208:211], v[96:99]
	v_mfma_f32_16x16x32_bf16 v[84:87], v[176:179], v[216:219], v[84:87]
	v_mfma_f32_16x16x32_bf16 v[64:67], v[186:189], v[224:227], v[64:67]
	v_mfma_f32_16x16x32_bf16 v[100:103], v[176:179], v[208:211], v[100:103]
	v_mfma_f32_16x16x32_bf16 v[112:115], v[186:189], v[194:197], v[112:115]
	v_mfma_f32_16x16x32_bf16 v[68:71], v[176:179], v[224:227], v[68:71]
	v_mfma_f32_16x16x32_bf16 v[80:83], v[186:189], v[216:219], v[80:83]
	s_setprio 0
	s_barrier
	s_add_i32 s3, s85, s34
	v_lshl_add_u64 v[202:203], s[62:63], 0, v[134:135]
	s_mov_b32 m0, s3
	ds_read_b128 v[190:193], v157 offset:16384
	ds_read_b128 v[194:197], v157 offset:17408
	ds_read_b128 v[198:201], v157 offset:18432
	ds_read_b128 v[208:211], v157 offset:19456
	ds_read_b128 v[212:215], v157 offset:20480
	ds_read_b128 v[216:219], v157 offset:21504
	ds_read_b128 v[220:223], v157 offset:22528
	ds_read_b128 v[224:227], v157 offset:23552
	global_load_lds_dwordx4 v[202:203], off
	s_add_i32 m0, s3, 0x2000
	s_add_u32 s14, s62, 0x40000
	v_lshl_add_u64 v[228:229], s[62:63], 0, v[138:139]
	s_addc_u32 s15, s63, 0
	s_add_i32 s3, s86, s34
	global_load_lds_dwordx4 v[228:229], off
	v_lshl_add_u64 v[230:231], s[14:15], 0, v[134:135]
	s_mov_b32 m0, s3
	global_load_lds_dwordx4 v[230:231], off
	v_lshl_add_u64 v[230:231], s[14:15], 0, v[138:139]
	s_add_i32 m0, s3, 0x2000
	s_nop 0
	global_load_lds_dwordx4 v[230:231], off
	s_waitcnt vmcnt(6)
	s_waitcnt lgkmcnt(0)
	s_barrier
; #define PG8_STAGE(bufoff, gbase, voff) do { _Pragma("unroll") for (int _i = 0; _i < 2; ++_i) \
;         __builtin_amdgcn_global_load_lds((const unsigned*)((const char*)(gbase) + (voff)[_i]), (PG8_LAS unsigned*)(lds + (bufoff) + ldsw + _i * 8192), 16, 0, 0); } while (0)
; #define PG8_LDA(dst, b, h) do { _Pragma("unroll") for (int m = 0; m < 4; ++m) _Pragma("unroll") for (int k = 0; k < 2; ++k) dst[m][k] = *(const PG8_LAS bf16x8*)(lds + PG8_SA(b, h) + aoff + m * 2048 + k * 1024); } while (0)
; #define PG8_LDB(dst, b, h) do { _Pragma("unroll") for (int n = 0; n < 2; ++n) _Pragma("unroll") for (int k = 0; k < 2; ++k) dst[n][k] = *(const PG8_LAS bf16x8*)(lds + PG8_SB(b, h) + boff + n * 2048 + k * 1024); } while (0)
; #define PG8_MMA(ai, bj, At, Bt) do { __builtin_amdgcn_s_setprio(1); _Pragma("unroll") for (int m = 0; m < 4; ++m) _Pragma("unroll") for (int n = 0; n < 2; ++n) _Pragma("unroll") for (int k = 0; k < 2; ++k) \
;         acc[ai][bj][m][n] = __builtin_amdgcn_mfma_f32_16x16x32_bf16(Bt[n][k], At[m][k], acc[ai][bj][m][n], 0, 0, 0); __builtin_amdgcn_s_setprio(0); } while (0)
; #define PG8_WAIT_V(n) asm volatile("s_waitcnt vmcnt(" #n ")" ::: "memory")
; #define PG8_WAIT_L(n) asm volatile("s_waitcnt lgkmcnt(" #n ")" ::: "memory")
; #define PG8_BAR __builtin_amdgcn_s_barrier()
; #define PG8_SCHED __builtin_amdgcn_sched_barrier(0)
; template <class Epi, class Sched, bool ALIGN_EPI = false, bool SP2 = false>
; __device__ __forceinline__ void gemm_phase(PG8_LAS unsigned char* lds, const Gemm g, const Sched& S, const Epi& E) {
;     ...
;             PG8_WAIT_V(8); PG8_WAIT_L(0); PG8_BAR; PG8_MMA(1, 0, At, B0); PG8_MMA(1, 1, At, B1); PG8_BAR; PG8_SCHED;
;             PG8_LDB(B0, 1, 0); PG8_LDB(B1, 1, 1); PG8_SCHED; PG8_LDA(At, 1, 0); PG8_STAGE(PG8_SA(0, 1), a2 + hstep, voffA);
;             PG8_WAIT_V(8); PG8_WAIT_L(0); PG8_BAR; PG8_MMA(0, 0, At, B0); PG8_MMA(0, 1, At, B1); PG8_BAR; PG8_SCHED;
	s_setprio 1
	s_waitcnt lgkmcnt(0)
	v_mfma_f32_16x16x32_bf16 v[60:63], v[148:151], v[190:193], 0
	v_mfma_f32_16x16x32_bf16 v[40:43], v[164:167], v[198:201], 0
	v_mfma_f32_16x16x32_bf16 v[28:31], v[148:151], v[212:215], 0
	v_mfma_f32_16x16x32_bf16 v[8:11], v[164:167], v[220:223], 0
	v_mfma_f32_16x16x32_bf16 v[44:47], v[148:151], v[198:201], 0
	v_mfma_f32_16x16x32_bf16 v[56:59], v[164:167], v[190:193], 0
	v_mfma_f32_16x16x32_bf16 v[12:15], v[148:151], v[220:223], 0
	v_mfma_f32_16x16x32_bf16 v[24:27], v[164:167], v[212:215], 0
	v_mfma_f32_16x16x32_bf16 v[60:63], v[160:163], v[194:197], v[60:63]
	v_mfma_f32_16x16x32_bf16 v[40:43], v[168:171], v[208:211], v[40:43]
	v_mfma_f32_16x16x32_bf16 v[28:31], v[160:163], v[216:219], v[28:31]
	v_mfma_f32_16x16x32_bf16 v[8:11], v[168:171], v[224:227], v[8:11]
	v_mfma_f32_16x16x32_bf16 v[44:47], v[160:163], v[208:211], v[44:47]
	v_mfma_f32_16x16x32_bf16 v[56:59], v[168:171], v[194:197], v[56:59]
	v_lshl_add_u64 v[230:231], s[64:65], 0, v[132:133]
	s_mov_b32 m0, s43
	s_nop 0
	global_load_lds_dwordx4 v[230:231], off
	v_mfma_f32_16x16x32_bf16 v[12:15], v[160:163], v[224:227], v[12:15]
	v_mfma_f32_16x16x32_bf16 v[24:27], v[168:171], v[216:219], v[24:27]
	s_setprio 0
	s_setprio 1
	v_mfma_f32_16x16x32_bf16 v[52:55], v[172:175], v[190:193], 0
	v_mfma_f32_16x16x32_bf16 v[32:35], v[182:185], v[198:201], 0
	v_mfma_f32_16x16x32_bf16 v[20:23], v[172:175], v[212:215], 0
	v_mfma_f32_16x16x32_bf16 v[0:3], v[182:185], v[220:223], 0
	v_mfma_f32_16x16x32_bf16 v[36:39], v[172:175], v[198:201], 0
	v_mfma_f32_16x16x32_bf16 v[48:51], v[182:185], v[190:193], 0
	v_mfma_f32_16x16x32_bf16 v[4:7], v[172:175], v[220:223], 0
	v_mfma_f32_16x16x32_bf16 v[16:19], v[182:185], v[212:215], 0
	v_mfma_f32_16x16x32_bf16 v[52:55], v[176:179], v[194:197], v[52:55]
	v_mfma_f32_16x16x32_bf16 v[32:35], v[186:189], v[208:211], v[32:35]
	v_mfma_f32_16x16x32_bf16 v[20:23], v[176:179], v[216:219], v[20:23]
	v_mfma_f32_16x16x32_bf16 v[0:3], v[186:189], v[224:227], v[0:3]
	v_mfma_f32_16x16x32_bf16 v[36:39], v[176:179], v[208:211], v[36:39]
	v_mfma_f32_16x16x32_bf16 v[48:51], v[186:189], v[194:197], v[48:51]
	v_lshl_add_u64 v[232:233], s[64:65], 0, v[136:137]
	s_mov_b32 m0, s59
	s_nop 0
	global_load_lds_dwordx4 v[232:233], off
	v_mfma_f32_16x16x32_bf16 v[4:7], v[176:179], v[224:227], v[4:7]
	v_mfma_f32_16x16x32_bf16 v[16:19], v[186:189], v[216:219], v[16:19]
	s_setprio 0
	s_barrier
	s_add_i32 s3, 0, 0x18000
	v_add_u32_e32 v159, s3, v131
	s_add_i32 s33, 0, 0x1c000
	ds_read_b128 v[148:151], v159
	ds_read_b128 v[160:163], v159 offset:1024
	ds_read_b128 v[164:167], v159 offset:2048
	ds_read_b128 v[168:171], v159 offset:3072
	v_add_u32_e32 v159, s33, v131
	ds_read_b128 v[172:175], v159
	ds_read_b128 v[176:179], v159 offset:1024
	ds_read_b128 v[182:185], v159 offset:2048
	ds_read_b128 v[186:189], v159 offset:3072
	s_add_u32 s14, s64, 0x40000
	s_addc_u32 s15, s65, 0
	s_mov_b32 m0, s66
	v_lshl_add_u64 v[234:235], s[14:15], 0, v[132:133]
	ds_read_b128 v[190:193], v157 offset:32768
	ds_read_b128 v[194:197], v157 offset:33792
	ds_read_b128 v[198:201], v157 offset:34816
	ds_read_b128 v[208:211], v157 offset:35840
	ds_read_b128 v[212:215], v157 offset:36864
	ds_read_b128 v[216:219], v157 offset:37888
	ds_read_b128 v[220:223], v157 offset:38912
	ds_read_b128 v[224:227], v157 offset:39936
	global_load_lds_dwordx4 v[234:235], off
	v_lshl_add_u64 v[234:235], s[14:15], 0, v[136:137]
	s_mov_b32 m0, s67
	s_nop 0
	global_load_lds_dwordx4 v[234:235], off
	s_waitcnt vmcnt(8)
	s_waitcnt lgkmcnt(0)
	s_barrier
	s_setprio 1
	s_waitcnt lgkmcnt(0)
	v_mfma_f32_16x16x32_bf16 v[124:127], v[148:151], v[190:193], v[124:127]
	v_mfma_f32_16x16x32_bf16 v[104:107], v[164:167], v[198:201], v[104:107]
	v_mfma_f32_16x16x32_bf16 v[92:95], v[148:151], v[212:215], v[92:95]
	v_mfma_f32_16x16x32_bf16 v[72:75], v[164:167], v[220:223], v[72:75]
	v_mfma_f32_16x16x32_bf16 v[108:111], v[148:151], v[198:201], v[108:111]
	v_mfma_f32_16x16x32_bf16 v[120:123], v[164:167], v[190:193], v[120:123]
	v_mfma_f32_16x16x32_bf16 v[76:79], v[148:151], v[220:223], v[76:79]
	v_mfma_f32_16x16x32_bf16 v[88:91], v[164:167], v[212:215], v[88:91]
	v_mfma_f32_16x16x32_bf16 v[124:127], v[160:163], v[194:197], v[124:127]
	v_mfma_f32_16x16x32_bf16 v[104:107], v[168:171], v[208:211], v[104:107]
	v_mfma_f32_16x16x32_bf16 v[92:95], v[160:163], v[216:219], v[92:95]
	v_mfma_f32_16x16x32_bf16 v[72:75], v[168:171], v[224:227], v[72:75]
	v_mfma_f32_16x16x32_bf16 v[108:111], v[160:163], v[208:211], v[108:111]
	v_mfma_f32_16x16x32_bf16 v[120:123], v[168:171], v[194:197], v[120:123]
	v_mfma_f32_16x16x32_bf16 v[76:79], v[160:163], v[224:227], v[76:79]
	v_mfma_f32_16x16x32_bf16 v[88:91], v[168:171], v[216:219], v[88:91]
	s_setprio 0
	s_setprio 1
	v_mfma_f32_16x16x32_bf16 v[116:119], v[172:175], v[190:193], v[116:119]
	v_mfma_f32_16x16x32_bf16 v[96:99], v[182:185], v[198:201], v[96:99]
	v_mfma_f32_16x16x32_bf16 v[84:87], v[172:175], v[212:215], v[84:87]
	v_mfma_f32_16x16x32_bf16 v[64:67], v[182:185], v[220:223], v[64:67]
	v_mfma_f32_16x16x32_bf16 v[100:103], v[172:175], v[198:201], v[100:103]
	v_mfma_f32_16x16x32_bf16 v[112:115], v[182:185], v[190:193], v[112:115]
	v_mfma_f32_16x16x32_bf16 v[68:71], v[172:175], v[220:223], v[68:71]
	v_mfma_f32_16x16x32_bf16 v[80:83], v[182:185], v[212:215], v[80:83]
	v_mfma_f32_16x16x32_bf16 v[116:119], v[176:179], v[194:197], v[116:119]
	v_mfma_f32_16x16x32_bf16 v[96:99], v[186:189], v[208:211], v[96:99]
	v_mfma_f32_16x16x32_bf16 v[84:87], v[176:179], v[216:219], v[84:87]
	v_mfma_f32_16x16x32_bf16 v[64:67], v[186:189], v[224:227], v[64:67]
	v_mfma_f32_16x16x32_bf16 v[100:103], v[176:179], v[208:211], v[100:103]
	v_mfma_f32_16x16x32_bf16 v[112:115], v[186:189], v[194:197], v[112:115]
	v_mfma_f32_16x16x32_bf16 v[68:71], v[176:179], v[224:227], v[68:71]
	v_mfma_f32_16x16x32_bf16 v[80:83], v[186:189], v[216:219], v[80:83]
	s_setprio 0
	s_barrier
; #define PG8_STAGE(bufoff, gbase, voff) do { _Pragma("unroll") for (int _i = 0; _i < 2; ++_i) \
;         __builtin_amdgcn_global_load_lds((const unsigned*)((const char*)(gbase) + (voff)[_i]), (PG8_LAS unsigned*)(lds + (bufoff) + ldsw + _i * 8192), 16, 0, 0); } while (0)
; #define PG8_LDA(dst, b, h) do { _Pragma("unroll") for (int m = 0; m < 4; ++m) _Pragma("unroll") for (int k = 0; k < 2; ++k) dst[m][k] = *(const PG8_LAS bf16x8*)(lds + PG8_SA(b, h) + aoff + m * 2048 + k * 1024); } while (0)
; #define PG8_LDB(dst, b, h) do { _Pragma("unroll") for (int n = 0; n < 2; ++n) _Pragma("unroll") for (int k = 0; k < 2; ++k) dst[n][k] = *(const PG8_LAS bf16x8*)(lds + PG8_SB(b, h) + boff + n * 2048 + k * 1024); } while (0)
; #define PG8_MMA(ai, bj, At, Bt) do { __builtin_amdgcn_s_setprio(1); _Pragma("unroll") for (int m = 0; m < 4; ++m) _Pragma("unroll") for (int n = 0; n < 2; ++n) _Pragma("unroll") for (int k = 0; k < 2; ++k) \
;         acc[ai][bj][m][n] = __builtin_amdgcn_mfma_f32_16x16x32_bf16(Bt[n][k], At[m][k], acc[ai][bj][m][n], 0, 0, 0); __builtin_amdgcn_s_setprio(0); } while (0)
; #define PG8_WAIT_V(n) asm volatile("s_waitcnt vmcnt(" #n ")" ::: "memory")
; #define PG8_WAIT_L(n) asm volatile("s_waitcnt lgkmcnt(" #n ")" ::: "memory")
; #define PG8_BAR __builtin_amdgcn_s_barrier()
; #define PG8_SCHED __builtin_amdgcn_sched_barrier(0)
; template <class Epi, class Sched, bool ALIGN_EPI = false, bool SP2 = false>
; __device__ __forceinline__ void gemm_phase(PG8_LAS unsigned char* lds, const Gemm g, const Sched& S, const Epi& E) {
;     ...
;             PG8_LDB(B0, 0, 0); PG8_LDB(B1, 0, 1); PG8_SCHED; PG8_LDA(At, 0, 0); PG8_STAGE(PG8_SA(1, 1), a1 + hstep, voffA);
;             PG8_WAIT_V(8); PG8_WAIT_L(0); PG8_BAR; PG8_MMA(0, 0, At, B0); PG8_MMA(0, 1, At, B1); PG8_BAR; PG8_SCHED;
;     ...
;             PG8_LDA(At, 1, 1); PG8_STAGE(PG8_SB(1, 0), b3, voffB); PG8_STAGE(PG8_SB(1, 1), b3 + hstep, voffB); PG8_STAGE(PG8_SA(1, 0), a3, voffA);
;             PG8_WAIT_V(8); PG8_WAIT_L(0); PG8_BAR; PG8_MMA(1, 0, At, B0); PG8_MMA(1, 1, At, B1); PG8_BAR; PG8_SCHED;
	s_add_i32 s3, s3, s34
	v_lshl_add_u64 v[202:203], v[202:203], 0, s[38:39]
	s_mov_b32 m0, s3
	ds_read_b128 v[190:193], v157 offset:49152
	ds_read_b128 v[194:197], v157 offset:50176
	ds_read_b128 v[198:201], v157 offset:51200
	ds_read_b128 v[208:211], v157 offset:52224
	ds_read_b128 v[212:215], v157 offset:53248
	ds_read_b128 v[216:219], v157 offset:54272
	ds_read_b128 v[220:223], v157 offset:55296
	ds_read_b128 v[224:227], v157 offset:56320
	global_load_lds_dwordx4 v[202:203], off
	s_add_i32 m0, s3, 0x2000
	s_add_u32 s14, s62, 0x40080
	v_lshl_add_u64 v[202:203], v[228:229], 0, s[38:39]
	s_addc_u32 s15, s63, 0
	s_add_i32 s3, s33, s34
	global_load_lds_dwordx4 v[202:203], off
	v_lshl_add_u64 v[202:203], s[14:15], 0, v[134:135]
	s_mov_b32 m0, s3
	s_nop 0
	global_load_lds_dwordx4 v[202:203], off
	v_lshl_add_u64 v[202:203], s[14:15], 0, v[138:139]
	s_add_i32 m0, s3, 0x2000
	s_nop 0
	global_load_lds_dwordx4 v[202:203], off
	s_waitcnt vmcnt(6)
	s_waitcnt lgkmcnt(0)
	s_barrier
	s_setprio 1
	s_waitcnt lgkmcnt(0)
	v_mfma_f32_16x16x32_bf16 v[60:63], v[148:151], v[190:193], v[60:63]
	v_mfma_f32_16x16x32_bf16 v[40:43], v[164:167], v[198:201], v[40:43]
	v_mfma_f32_16x16x32_bf16 v[28:31], v[148:151], v[212:215], v[28:31]
	v_mfma_f32_16x16x32_bf16 v[8:11], v[164:167], v[220:223], v[8:11]
	v_mfma_f32_16x16x32_bf16 v[44:47], v[148:151], v[198:201], v[44:47]
	v_mfma_f32_16x16x32_bf16 v[56:59], v[164:167], v[190:193], v[56:59]
	v_mfma_f32_16x16x32_bf16 v[12:15], v[148:151], v[220:223], v[12:15]
	v_mfma_f32_16x16x32_bf16 v[24:27], v[164:167], v[212:215], v[24:27]
	v_mfma_f32_16x16x32_bf16 v[60:63], v[160:163], v[194:197], v[60:63]
	v_mfma_f32_16x16x32_bf16 v[40:43], v[168:171], v[208:211], v[40:43]
	v_mfma_f32_16x16x32_bf16 v[28:31], v[160:163], v[216:219], v[28:31]
	v_mfma_f32_16x16x32_bf16 v[8:11], v[168:171], v[224:227], v[8:11]
	v_mfma_f32_16x16x32_bf16 v[44:47], v[160:163], v[208:211], v[44:47]
	v_mfma_f32_16x16x32_bf16 v[56:59], v[168:171], v[194:197], v[56:59]
	v_lshl_add_u64 v[202:203], v[230:231], 0, s[38:39]
	s_mov_b32 m0, s75
	s_nop 0
	global_load_lds_dwordx4 v[202:203], off
	v_mfma_f32_16x16x32_bf16 v[12:15], v[160:163], v[224:227], v[12:15]
	v_mfma_f32_16x16x32_bf16 v[24:27], v[168:171], v[216:219], v[24:27]
	s_setprio 0
	s_setprio 1
	v_mfma_f32_16x16x32_bf16 v[52:55], v[172:175], v[190:193], v[52:55]
	v_mfma_f32_16x16x32_bf16 v[32:35], v[182:185], v[198:201], v[32:35]
	v_mfma_f32_16x16x32_bf16 v[20:23], v[172:175], v[212:215], v[20:23]
	v_mfma_f32_16x16x32_bf16 v[0:3], v[182:185], v[220:223], v[0:3]
	v_mfma_f32_16x16x32_bf16 v[36:39], v[172:175], v[198:201], v[36:39]
	v_mfma_f32_16x16x32_bf16 v[48:51], v[182:185], v[190:193], v[48:51]
	v_mfma_f32_16x16x32_bf16 v[4:7], v[172:175], v[220:223], v[4:7]
	v_mfma_f32_16x16x32_bf16 v[16:19], v[182:185], v[212:215], v[16:19]
	v_mfma_f32_16x16x32_bf16 v[52:55], v[176:179], v[194:197], v[52:55]
	v_mfma_f32_16x16x32_bf16 v[32:35], v[186:189], v[208:211], v[32:35]
	v_mfma_f32_16x16x32_bf16 v[20:23], v[176:179], v[216:219], v[20:23]
	v_mfma_f32_16x16x32_bf16 v[0:3], v[186:189], v[224:227], v[0:3]
	v_mfma_f32_16x16x32_bf16 v[36:39], v[176:179], v[208:211], v[36:39]
	v_mfma_f32_16x16x32_bf16 v[48:51], v[186:189], v[194:197], v[48:51]
	v_lshl_add_u64 v[202:203], v[232:233], 0, s[38:39]
	s_mov_b32 m0, s84
	s_nop 0
	global_load_lds_dwordx4 v[202:203], off
	v_mfma_f32_16x16x32_bf16 v[4:7], v[176:179], v[224:227], v[4:7]
	v_mfma_f32_16x16x32_bf16 v[16:19], v[186:189], v[216:219], v[16:19]
	s_setprio 0
	s_barrier
	s_add_i32 s92, s92, 2
	s_add_u32 s60, s60, 0x100
	s_addc_u32 s61, s61, 0
	s_add_u32 s90, s90, 0x100
	s_addc_u32 s91, s91, 0
.LBB0_650:
	ds_read_b128 v[148:151], v155
	ds_read_b128 v[160:163], v155 offset:1024
	ds_read_b128 v[164:167], v155 offset:2048
	ds_read_b128 v[168:171], v155 offset:3072
	ds_read_b128 v[172:175], v156
	ds_read_b128 v[176:179], v156 offset:1024
	ds_read_b128 v[182:185], v156 offset:2048
	ds_read_b128 v[186:189], v156 offset:3072
	s_add_u32 s3, s60, 0xfffc0080
	s_addc_u32 s14, s61, -1
	s_cmp_eq_u32 s92, 12
	s_cselect_b32 s65, s51, s14
	s_cselect_b32 s64, s57, s3
	s_cselect_b32 s63, s49, s91
	s_cselect_b32 s62, s89, s90
	v_lshl_add_u64 v[202:203], s[60:61], 0, v[140:141]
	s_add_i32 m0, s43, 0xc000
	ds_read_b128 v[190:193], v157
	ds_read_b128 v[194:197], v157 offset:1024
	ds_read_b128 v[198:201], v157 offset:2048
	ds_read_b128 v[208:211], v157 offset:3072
	ds_read_b128 v[212:215], v157 offset:4096
	ds_read_b128 v[216:219], v157 offset:5120
	ds_read_b128 v[220:223], v157 offset:6144
	ds_read_b128 v[224:227], v157 offset:7168
	global_load_lds_dwordx4 v[202:203], off
	v_lshl_add_u64 v[202:203], s[60:61], 0, v[142:143]
	s_add_i32 m0, s43, 0xe000
	s_nop 0
	global_load_lds_dwordx4 v[202:203], off
	s_waitcnt vmcnt(8)
	s_waitcnt lgkmcnt(0)
	s_barrier
; #define PG8_STAGE(bufoff, gbase, voff) do { _Pragma("unroll") for (int _i = 0; _i < 2; ++_i) \
;         __builtin_amdgcn_global_load_lds((const unsigned*)((const char*)(gbase) + (voff)[_i]), (PG8_LAS unsigned*)(lds + (bufoff) + ldsw + _i * 8192), 16, 0, 0); } while (0)
; #define PG8_LDA(dst, b, h) do { _Pragma("unroll") for (int m = 0; m < 4; ++m) _Pragma("unroll") for (int k = 0; k < 2; ++k) dst[m][k] = *(const PG8_LAS bf16x8*)(lds + PG8_SA(b, h) + aoff + m * 2048 + k * 1024); } while (0)
; #define PG8_LDB(dst, b, h) do { _Pragma("unroll") for (int n = 0; n < 2; ++n) _Pragma("unroll") for (int k = 0; k < 2; ++k) dst[n][k] = *(const PG8_LAS bf16x8*)(lds + PG8_SB(b, h) + boff + n * 2048 + k * 1024); } while (0)
; #define PG8_MMA(ai, bj, At, Bt) do { __builtin_amdgcn_s_setprio(1); _Pragma("unroll") for (int m = 0; m < 4; ++m) _Pragma("unroll") for (int n = 0; n < 2; ++n) _Pragma("unroll") for (int k = 0; k < 2; ++k) \
;         acc[ai][bj][m][n] = __builtin_amdgcn_mfma_f32_16x16x32_bf16(Bt[n][k], At[m][k], acc[ai][bj][m][n], 0, 0, 0); __builtin_amdgcn_s_setprio(0); } while (0)
; #define PG8_WAIT_V(n) asm volatile("s_waitcnt vmcnt(" #n ")" ::: "memory")
; #define PG8_WAIT_L(n) asm volatile("s_waitcnt lgkmcnt(" #n ")" ::: "memory")
; #define PG8_BAR __builtin_amdgcn_s_barrier()
; #define PG8_SCHED __builtin_amdgcn_sched_barrier(0)
; template <class Epi, class Sched, bool ALIGN_EPI = false, bool SP2 = false>
; __device__ __forceinline__ void gemm_phase(PG8_LAS unsigned char* lds, const Gemm g, const Sched& S, const Epi& E) {
;     ...
;             PG8_LDB(B0, 0, 0); PG8_LDB(B1, 0, 1); PG8_SCHED; PG8_LDA(At, 0, 0); PG8_STAGE(PG8_SA(1, 1), a1 + hstep, voffA);
;             PG8_WAIT_V(8); PG8_WAIT_L(0); PG8_BAR; PG8_MMA(0, 0, At, B0); PG8_MMA(0, 1, At, B1); PG8_BAR; PG8_SCHED;
;             PG8_LDA(At, 0, 1); PG8_STAGE(PG8_SB(0, 0), b2, voffB); PG8_STAGE(PG8_SB(0, 1), b2 + hstep, voffB); PG8_STAGE(PG8_SA(0, 0), a2, voffA);
;             PG8_WAIT_V(8); PG8_WAIT_L(0); PG8_BAR; PG8_MMA(1, 0, At, B0); PG8_MMA(1, 1, At, B1); PG8_BAR; PG8_SCHED;
	s_setprio 1
	s_waitcnt lgkmcnt(0)
	v_mfma_f32_16x16x32_bf16 v[124:127], v[148:151], v[190:193], v[124:127]
	v_mfma_f32_16x16x32_bf16 v[104:107], v[164:167], v[198:201], v[104:107]
	v_mfma_f32_16x16x32_bf16 v[92:95], v[148:151], v[212:215], v[92:95]
	v_mfma_f32_16x16x32_bf16 v[72:75], v[164:167], v[220:223], v[72:75]
	v_mfma_f32_16x16x32_bf16 v[108:111], v[148:151], v[198:201], v[108:111]
	v_mfma_f32_16x16x32_bf16 v[120:123], v[164:167], v[190:193], v[120:123]
	v_mfma_f32_16x16x32_bf16 v[76:79], v[148:151], v[220:223], v[76:79]
	v_mfma_f32_16x16x32_bf16 v[88:91], v[164:167], v[212:215], v[88:91]
	v_mfma_f32_16x16x32_bf16 v[124:127], v[160:163], v[194:197], v[124:127]
	v_mfma_f32_16x16x32_bf16 v[104:107], v[168:171], v[208:211], v[104:107]
	v_mfma_f32_16x16x32_bf16 v[92:95], v[160:163], v[216:219], v[92:95]
	v_mfma_f32_16x16x32_bf16 v[72:75], v[168:171], v[224:227], v[72:75]
	v_mfma_f32_16x16x32_bf16 v[108:111], v[160:163], v[208:211], v[108:111]
	v_mfma_f32_16x16x32_bf16 v[120:123], v[168:171], v[194:197], v[120:123]
	v_mfma_f32_16x16x32_bf16 v[76:79], v[160:163], v[224:227], v[76:79]
	v_mfma_f32_16x16x32_bf16 v[88:91], v[168:171], v[216:219], v[88:91]
	s_setprio 0
	s_setprio 1
	v_mfma_f32_16x16x32_bf16 v[116:119], v[172:175], v[190:193], v[116:119]
	v_mfma_f32_16x16x32_bf16 v[96:99], v[182:185], v[198:201], v[96:99]
	v_mfma_f32_16x16x32_bf16 v[84:87], v[172:175], v[212:215], v[84:87]
	v_mfma_f32_16x16x32_bf16 v[64:67], v[182:185], v[220:223], v[64:67]
	v_mfma_f32_16x16x32_bf16 v[100:103], v[172:175], v[198:201], v[100:103]
	v_mfma_f32_16x16x32_bf16 v[112:115], v[182:185], v[190:193], v[112:115]
	v_mfma_f32_16x16x32_bf16 v[68:71], v[172:175], v[220:223], v[68:71]
	v_mfma_f32_16x16x32_bf16 v[80:83], v[182:185], v[212:215], v[80:83]
	v_mfma_f32_16x16x32_bf16 v[116:119], v[176:179], v[194:197], v[116:119]
	v_mfma_f32_16x16x32_bf16 v[96:99], v[186:189], v[208:211], v[96:99]
	v_mfma_f32_16x16x32_bf16 v[84:87], v[176:179], v[216:219], v[84:87]
	v_mfma_f32_16x16x32_bf16 v[64:67], v[186:189], v[224:227], v[64:67]
	v_mfma_f32_16x16x32_bf16 v[100:103], v[176:179], v[208:211], v[100:103]
	v_mfma_f32_16x16x32_bf16 v[112:115], v[186:189], v[194:197], v[112:115]
	v_mfma_f32_16x16x32_bf16 v[68:71], v[176:179], v[224:227], v[68:71]
	v_mfma_f32_16x16x32_bf16 v[80:83], v[186:189], v[216:219], v[80:83]
	s_setprio 0
	s_barrier
	s_add_i32 s3, s85, s34
	v_lshl_add_u64 v[202:203], s[62:63], 0, v[134:135]
	s_mov_b32 m0, s3
	ds_read_b128 v[190:193], v157 offset:16384
	ds_read_b128 v[194:197], v157 offset:17408
	ds_read_b128 v[198:201], v157 offset:18432
	ds_read_b128 v[208:211], v157 offset:19456
	ds_read_b128 v[212:215], v157 offset:20480
	ds_read_b128 v[216:219], v157 offset:21504
	ds_read_b128 v[220:223], v157 offset:22528
	ds_read_b128 v[224:227], v157 offset:23552
	global_load_lds_dwordx4 v[202:203], off
	s_add_i32 m0, s3, 0x2000
	s_add_u32 s14, s62, 0x40000
	v_lshl_add_u64 v[228:229], s[62:63], 0, v[138:139]
	s_addc_u32 s15, s63, 0
	s_add_i32 s3, s86, s34
	global_load_lds_dwordx4 v[228:229], off
	v_lshl_add_u64 v[230:231], s[14:15], 0, v[134:135]
	s_mov_b32 m0, s3
	global_load_lds_dwordx4 v[230:231], off
	v_lshl_add_u64 v[230:231], s[14:15], 0, v[138:139]
	s_add_i32 m0, s3, 0x2000
	s_nop 0
	global_load_lds_dwordx4 v[230:231], off
	s_waitcnt vmcnt(6)
	s_waitcnt lgkmcnt(0)
	s_barrier
	s_setprio 1
	s_waitcnt lgkmcnt(0)
	v_mfma_f32_16x16x32_bf16 v[60:63], v[148:151], v[190:193], v[60:63]
	v_mfma_f32_16x16x32_bf16 v[40:43], v[164:167], v[198:201], v[40:43]
	v_mfma_f32_16x16x32_bf16 v[28:31], v[148:151], v[212:215], v[28:31]
	v_mfma_f32_16x16x32_bf16 v[8:11], v[164:167], v[220:223], v[8:11]
	v_mfma_f32_16x16x32_bf16 v[44:47], v[148:151], v[198:201], v[44:47]
	v_mfma_f32_16x16x32_bf16 v[56:59], v[164:167], v[190:193], v[56:59]
	v_mfma_f32_16x16x32_bf16 v[12:15], v[148:151], v[220:223], v[12:15]
	v_mfma_f32_16x16x32_bf16 v[24:27], v[164:167], v[212:215], v[24:27]
	v_mfma_f32_16x16x32_bf16 v[60:63], v[160:163], v[194:197], v[60:63]
	v_mfma_f32_16x16x32_bf16 v[40:43], v[168:171], v[208:211], v[40:43]
	v_mfma_f32_16x16x32_bf16 v[28:31], v[160:163], v[216:219], v[28:31]
	v_mfma_f32_16x16x32_bf16 v[8:11], v[168:171], v[224:227], v[8:11]
	v_mfma_f32_16x16x32_bf16 v[44:47], v[160:163], v[208:211], v[44:47]
	v_mfma_f32_16x16x32_bf16 v[56:59], v[168:171], v[194:197], v[56:59]
	v_lshl_add_u64 v[230:231], s[64:65], 0, v[132:133]
	s_mov_b32 m0, s43
	s_nop 0
	global_load_lds_dwordx4 v[230:231], off
	v_mfma_f32_16x16x32_bf16 v[12:15], v[160:163], v[224:227], v[12:15]
	v_mfma_f32_16x16x32_bf16 v[24:27], v[168:171], v[216:219], v[24:27]
	s_setprio 0
	s_setprio 1
	v_mfma_f32_16x16x32_bf16 v[52:55], v[172:175], v[190:193], v[52:55]
	v_mfma_f32_16x16x32_bf16 v[32:35], v[182:185], v[198:201], v[32:35]
	v_mfma_f32_16x16x32_bf16 v[20:23], v[172:175], v[212:215], v[20:23]
	v_mfma_f32_16x16x32_bf16 v[0:3], v[182:185], v[220:223], v[0:3]
	v_mfma_f32_16x16x32_bf16 v[36:39], v[172:175], v[198:201], v[36:39]
	v_mfma_f32_16x16x32_bf16 v[48:51], v[182:185], v[190:193], v[48:51]
	v_mfma_f32_16x16x32_bf16 v[4:7], v[172:175], v[220:223], v[4:7]
	v_mfma_f32_16x16x32_bf16 v[16:19], v[182:185], v[212:215], v[16:19]
	v_mfma_f32_16x16x32_bf16 v[52:55], v[176:179], v[194:197], v[52:55]
	v_mfma_f32_16x16x32_bf16 v[32:35], v[186:189], v[208:211], v[32:35]
	v_mfma_f32_16x16x32_bf16 v[20:23], v[176:179], v[216:219], v[20:23]
	v_mfma_f32_16x16x32_bf16 v[0:3], v[186:189], v[224:227], v[0:3]
	v_mfma_f32_16x16x32_bf16 v[36:39], v[176:179], v[208:211], v[36:39]
	v_mfma_f32_16x16x32_bf16 v[48:51], v[186:189], v[194:197], v[48:51]
	v_lshl_add_u64 v[232:233], s[64:65], 0, v[136:137]
	s_mov_b32 m0, s59
	s_nop 0
	global_load_lds_dwordx4 v[232:233], off
	v_mfma_f32_16x16x32_bf16 v[4:7], v[176:179], v[224:227], v[4:7]
	v_mfma_f32_16x16x32_bf16 v[16:19], v[186:189], v[216:219], v[16:19]
	s_setprio 0
	s_barrier
; #define PG8_STAGE(bufoff, gbase, voff) do { _Pragma("unroll") for (int _i = 0; _i < 2; ++_i) \
;         __builtin_amdgcn_global_load_lds((const unsigned*)((const char*)(gbase) + (voff)[_i]), (PG8_LAS unsigned*)(lds + (bufoff) + ldsw + _i * 8192), 16, 0, 0); } while (0)
; #define PG8_LDA(dst, b, h) do { _Pragma("unroll") for (int m = 0; m < 4; ++m) _Pragma("unroll") for (int k = 0; k < 2; ++k) dst[m][k] = *(const PG8_LAS bf16x8*)(lds + PG8_SA(b, h) + aoff + m * 2048 + k * 1024); } while (0)
; #define PG8_LDB(dst, b, h) do { _Pragma("unroll") for (int n = 0; n < 2; ++n) _Pragma("unroll") for (int k = 0; k < 2; ++k) dst[n][k] = *(const PG8_LAS bf16x8*)(lds + PG8_SB(b, h) + boff + n * 2048 + k * 1024); } while (0)
; #define PG8_MMA(ai, bj, At, Bt) do { __builtin_amdgcn_s_setprio(1); _Pragma("unroll") for (int m = 0; m < 4; ++m) _Pragma("unroll") for (int n = 0; n < 2; ++n) _Pragma("unroll") for (int k = 0; k < 2; ++k) \
;         acc[ai][bj][m][n] = __builtin_amdgcn_mfma_f32_16x16x32_bf16(Bt[n][k], At[m][k], acc[ai][bj][m][n], 0, 0, 0); __builtin_amdgcn_s_setprio(0); } while (0)
; #define PG8_WAIT_V(n) asm volatile("s_waitcnt vmcnt(" #n ")" ::: "memory")
; #define PG8_WAIT_L(n) asm volatile("s_waitcnt lgkmcnt(" #n ")" ::: "memory")
; #define PG8_BAR __builtin_amdgcn_s_barrier()
; #define PG8_SCHED __builtin_amdgcn_sched_barrier(0)
; template <class Epi, class Sched, bool ALIGN_EPI = false, bool SP2 = false>
; __device__ __forceinline__ void gemm_phase(PG8_LAS unsigned char* lds, const Gemm g, const Sched& S, const Epi& E) {
;     ...
;             PG8_LDB(B0, 1, 0); PG8_LDB(B1, 1, 1); PG8_SCHED; PG8_LDA(At, 1, 0); PG8_STAGE(PG8_SA(0, 1), a2 + hstep, voffA);
;             PG8_WAIT_V(8); PG8_WAIT_L(0); PG8_BAR; PG8_MMA(0, 0, At, B0); PG8_MMA(0, 1, At, B1); PG8_BAR; PG8_SCHED;
	s_add_i32 s3, 0, 0x18000
	v_add_u32_e32 v159, s3, v131
	s_add_i32 s33, 0, 0x1c000
	ds_read_b128 v[148:151], v159
	ds_read_b128 v[160:163], v159 offset:1024
	ds_read_b128 v[164:167], v159 offset:2048
	ds_read_b128 v[168:171], v159 offset:3072
	v_add_u32_e32 v159, s33, v131
	ds_read_b128 v[172:175], v159
	ds_read_b128 v[176:179], v159 offset:1024
	ds_read_b128 v[182:185], v159 offset:2048
	ds_read_b128 v[186:189], v159 offset:3072
	s_add_u32 s14, s64, 0x40000
	s_addc_u32 s15, s65, 0
	s_mov_b32 m0, s66
	v_lshl_add_u64 v[234:235], s[14:15], 0, v[132:133]
	ds_read_b128 v[190:193], v157 offset:32768
	ds_read_b128 v[194:197], v157 offset:33792
	ds_read_b128 v[198:201], v157 offset:34816
	ds_read_b128 v[208:211], v157 offset:35840
	ds_read_b128 v[212:215], v157 offset:36864
	ds_read_b128 v[216:219], v157 offset:37888
	ds_read_b128 v[220:223], v157 offset:38912
	ds_read_b128 v[224:227], v157 offset:39936
	global_load_lds_dwordx4 v[234:235], off
	v_lshl_add_u64 v[234:235], s[14:15], 0, v[136:137]
	s_mov_b32 m0, s67
	s_nop 0
	global_load_lds_dwordx4 v[234:235], off
	s_waitcnt vmcnt(8)
	s_waitcnt lgkmcnt(0)
	s_barrier
	s_setprio 1
	s_waitcnt lgkmcnt(0)
	v_mfma_f32_16x16x32_bf16 v[124:127], v[148:151], v[190:193], v[124:127]
	v_mfma_f32_16x16x32_bf16 v[104:107], v[164:167], v[198:201], v[104:107]
	v_mfma_f32_16x16x32_bf16 v[92:95], v[148:151], v[212:215], v[92:95]
	v_mfma_f32_16x16x32_bf16 v[72:75], v[164:167], v[220:223], v[72:75]
	v_mfma_f32_16x16x32_bf16 v[108:111], v[148:151], v[198:201], v[108:111]
	v_mfma_f32_16x16x32_bf16 v[120:123], v[164:167], v[190:193], v[120:123]
	v_mfma_f32_16x16x32_bf16 v[76:79], v[148:151], v[220:223], v[76:79]
	v_mfma_f32_16x16x32_bf16 v[88:91], v[164:167], v[212:215], v[88:91]
	v_mfma_f32_16x16x32_bf16 v[124:127], v[160:163], v[194:197], v[124:127]
	v_mfma_f32_16x16x32_bf16 v[104:107], v[168:171], v[208:211], v[104:107]
	v_mfma_f32_16x16x32_bf16 v[92:95], v[160:163], v[216:219], v[92:95]
	v_mfma_f32_16x16x32_bf16 v[72:75], v[168:171], v[224:227], v[72:75]
	v_mfma_f32_16x16x32_bf16 v[108:111], v[160:163], v[208:211], v[108:111]
	v_mfma_f32_16x16x32_bf16 v[120:123], v[168:171], v[194:197], v[120:123]
	v_mfma_f32_16x16x32_bf16 v[76:79], v[160:163], v[224:227], v[76:79]
	v_mfma_f32_16x16x32_bf16 v[88:91], v[168:171], v[216:219], v[88:91]
	s_setprio 0
	s_setprio 1
	v_mfma_f32_16x16x32_bf16 v[116:119], v[172:175], v[190:193], v[116:119]
	v_mfma_f32_16x16x32_bf16 v[96:99], v[182:185], v[198:201], v[96:99]
	v_mfma_f32_16x16x32_bf16 v[84:87], v[172:175], v[212:215], v[84:87]
	v_mfma_f32_16x16x32_bf16 v[64:67], v[182:185], v[220:223], v[64:67]
	v_mfma_f32_16x16x32_bf16 v[100:103], v[172:175], v[198:201], v[100:103]
	v_mfma_f32_16x16x32_bf16 v[112:115], v[182:185], v[190:193], v[112:115]
	v_mfma_f32_16x16x32_bf16 v[68:71], v[172:175], v[220:223], v[68:71]
	v_mfma_f32_16x16x32_bf16 v[80:83], v[182:185], v[212:215], v[80:83]
	v_mfma_f32_16x16x32_bf16 v[116:119], v[176:179], v[194:197], v[116:119]
	v_mfma_f32_16x16x32_bf16 v[96:99], v[186:189], v[208:211], v[96:99]
	v_mfma_f32_16x16x32_bf16 v[84:87], v[176:179], v[216:219], v[84:87]
	v_mfma_f32_16x16x32_bf16 v[64:67], v[186:189], v[224:227], v[64:67]
	v_mfma_f32_16x16x32_bf16 v[100:103], v[176:179], v[208:211], v[100:103]
	v_mfma_f32_16x16x32_bf16 v[112:115], v[186:189], v[194:197], v[112:115]
	v_mfma_f32_16x16x32_bf16 v[68:71], v[176:179], v[224:227], v[68:71]
	v_mfma_f32_16x16x32_bf16 v[80:83], v[186:189], v[216:219], v[80:83]
	s_setprio 0
	s_barrier
; #define PG8_STAGE(bufoff, gbase, voff) do { _Pragma("unroll") for (int _i = 0; _i < 2; ++_i) \
;         __builtin_amdgcn_global_load_lds((const unsigned*)((const char*)(gbase) + (voff)[_i]), (PG8_LAS unsigned*)(lds + (bufoff) + ldsw + _i * 8192), 16, 0, 0); } while (0)
; #define PG8_LDA(dst, b, h) do { _Pragma("unroll") for (int m = 0; m < 4; ++m) _Pragma("unroll") for (int k = 0; k < 2; ++k) dst[m][k] = *(const PG8_LAS bf16x8*)(lds + PG8_SA(b, h) + aoff + m * 2048 + k * 1024); } while (0)
; #define PG8_MMA(ai, bj, At, Bt) do { __builtin_amdgcn_s_setprio(1); _Pragma("unroll") for (int m = 0; m < 4; ++m) _Pragma("unroll") for (int n = 0; n < 2; ++n) _Pragma("unroll") for (int k = 0; k < 2; ++k) \
;         acc[ai][bj][m][n] = __builtin_amdgcn_mfma_f32_16x16x32_bf16(Bt[n][k], At[m][k], acc[ai][bj][m][n], 0, 0, 0); __builtin_amdgcn_s_setprio(0); } while (0)
; #define PG8_WAIT_V(n) asm volatile("s_waitcnt vmcnt(" #n ")" ::: "memory")
; #define PG8_WAIT_L(n) asm volatile("s_waitcnt lgkmcnt(" #n ")" ::: "memory")
; #define PG8_BAR __builtin_amdgcn_s_barrier()
; #define PG8_SCHED __builtin_amdgcn_sched_barrier(0)
; template <class Epi, class Sched, bool ALIGN_EPI = false, bool SP2 = false>
; __device__ __forceinline__ void gemm_phase(PG8_LAS unsigned char* lds, const Gemm g, const Sched& S, const Epi& E) {
;     ...
;             PG8_LDA(At, 1, 1); PG8_STAGE(PG8_SB(1, 0), b3, voffB); PG8_STAGE(PG8_SB(1, 1), b3 + hstep, voffB); PG8_STAGE(PG8_SA(1, 0), a3, voffA);
;             PG8_WAIT_V(8); PG8_WAIT_L(0); PG8_BAR; PG8_MMA(1, 0, At, B0); PG8_MMA(1, 1, At, B1); PG8_BAR; PG8_SCHED;
	s_add_i32 s3, s3, s34
	v_lshl_add_u64 v[202:203], v[202:203], 0, s[38:39]
	s_mov_b32 m0, s3
	ds_read_b128 v[190:193], v157 offset:49152
	ds_read_b128 v[194:197], v157 offset:50176
	ds_read_b128 v[198:201], v157 offset:51200
	ds_read_b128 v[208:211], v157 offset:52224
	ds_read_b128 v[212:215], v157 offset:53248
	ds_read_b128 v[216:219], v157 offset:54272
	ds_read_b128 v[220:223], v157 offset:55296
	ds_read_b128 v[224:227], v157 offset:56320
	global_load_lds_dwordx4 v[202:203], off
	s_add_i32 m0, s3, 0x2000
	s_add_u32 s14, s62, 0x40080
	v_lshl_add_u64 v[202:203], v[228:229], 0, s[38:39]
	s_addc_u32 s15, s63, 0
	s_add_i32 s3, s33, s34
	global_load_lds_dwordx4 v[202:203], off
	v_lshl_add_u64 v[202:203], s[14:15], 0, v[134:135]
	s_mov_b32 m0, s3
	s_nop 0
	global_load_lds_dwordx4 v[202:203], off
	v_lshl_add_u64 v[202:203], s[14:15], 0, v[138:139]
	s_add_i32 m0, s3, 0x2000
	s_nop 0
	global_load_lds_dwordx4 v[202:203], off
	s_waitcnt vmcnt(6)
	s_waitcnt lgkmcnt(0)
	s_barrier
	s_setprio 1
	s_waitcnt lgkmcnt(0)
	v_mfma_f32_16x16x32_bf16 v[60:63], v[148:151], v[190:193], v[60:63]
	v_mfma_f32_16x16x32_bf16 v[40:43], v[164:167], v[198:201], v[40:43]
	v_mfma_f32_16x16x32_bf16 v[28:31], v[148:151], v[212:215], v[28:31]
	v_mfma_f32_16x16x32_bf16 v[8:11], v[164:167], v[220:223], v[8:11]
	v_mfma_f32_16x16x32_bf16 v[44:47], v[148:151], v[198:201], v[44:47]
	v_mfma_f32_16x16x32_bf16 v[56:59], v[164:167], v[190:193], v[56:59]
	v_mfma_f32_16x16x32_bf16 v[12:15], v[148:151], v[220:223], v[12:15]
	v_mfma_f32_16x16x32_bf16 v[24:27], v[164:167], v[212:215], v[24:27]
	v_mfma_f32_16x16x32_bf16 v[60:63], v[160:163], v[194:197], v[60:63]
	v_mfma_f32_16x16x32_bf16 v[40:43], v[168:171], v[208:211], v[40:43]
	v_mfma_f32_16x16x32_bf16 v[28:31], v[160:163], v[216:219], v[28:31]
	v_mfma_f32_16x16x32_bf16 v[8:11], v[168:171], v[224:227], v[8:11]
	v_mfma_f32_16x16x32_bf16 v[44:47], v[160:163], v[208:211], v[44:47]
	v_mfma_f32_16x16x32_bf16 v[56:59], v[168:171], v[194:197], v[56:59]
	v_lshl_add_u64 v[202:203], v[230:231], 0, s[38:39]
	s_mov_b32 m0, s75
	s_nop 0
	global_load_lds_dwordx4 v[202:203], off
	v_mfma_f32_16x16x32_bf16 v[12:15], v[160:163], v[224:227], v[12:15]
	v_mfma_f32_16x16x32_bf16 v[24:27], v[168:171], v[216:219], v[24:27]
	s_setprio 0
	s_setprio 1
	v_mfma_f32_16x16x32_bf16 v[52:55], v[172:175], v[190:193], v[52:55]
	v_mfma_f32_16x16x32_bf16 v[32:35], v[182:185], v[198:201], v[32:35]
	v_mfma_f32_16x16x32_bf16 v[20:23], v[172:175], v[212:215], v[20:23]
	v_mfma_f32_16x16x32_bf16 v[0:3], v[182:185], v[220:223], v[0:3]
	v_mfma_f32_16x16x32_bf16 v[36:39], v[172:175], v[198:201], v[36:39]
	v_mfma_f32_16x16x32_bf16 v[48:51], v[182:185], v[190:193], v[48:51]
	v_mfma_f32_16x16x32_bf16 v[4:7], v[172:175], v[220:223], v[4:7]
	v_mfma_f32_16x16x32_bf16 v[16:19], v[182:185], v[212:215], v[16:19]
	v_mfma_f32_16x16x32_bf16 v[52:55], v[176:179], v[194:197], v[52:55]
	v_mfma_f32_16x16x32_bf16 v[32:35], v[186:189], v[208:211], v[32:35]
	v_mfma_f32_16x16x32_bf16 v[20:23], v[176:179], v[216:219], v[20:23]
	v_mfma_f32_16x16x32_bf16 v[0:3], v[186:189], v[224:227], v[0:3]
	v_mfma_f32_16x16x32_bf16 v[36:39], v[176:179], v[208:211], v[36:39]
	v_mfma_f32_16x16x32_bf16 v[48:51], v[186:189], v[194:197], v[48:51]
	v_lshl_add_u64 v[202:203], v[232:233], 0, s[38:39]
	s_mov_b32 m0, s84
	s_nop 0
	global_load_lds_dwordx4 v[202:203], off
	v_mfma_f32_16x16x32_bf16 v[4:7], v[176:179], v[224:227], v[4:7]
	v_mfma_f32_16x16x32_bf16 v[16:19], v[186:189], v[216:219], v[16:19]
	s_setprio 0
	s_barrier
	s_add_i32 s92, s92, 2
	s_add_u32 s60, s60, 0x100
	s_addc_u32 s61, s61, 0
	s_add_u32 s90, s90, 0x100
	s_addc_u32 s91, s91, 0
	s_cmp_gt_u32 s92, 13
	s_cbranch_scc0 .LBB0_650
	s_and_b64 vcc, exec, s[44:45]
	s_cbranch_vccz .LBB0_653
	s_barrier

; #define PG8_STAGE(bufoff, gbase, voff) do { _Pragma("unroll") for (int _i = 0; _i < 2; ++_i) \
;         __builtin_amdgcn_global_load_lds((const unsigned*)((const char*)(gbase) + (voff)[_i]), (PG8_LAS unsigned*)(lds + (bufoff) + ldsw + _i * 8192), 16, 0, 0); } while (0)
; #define PG8_LDA(dst, b, h) do { _Pragma("unroll") for (int m = 0; m < 4; ++m) _Pragma("unroll") for (int k = 0; k < 2; ++k) dst[m][k] = *(const PG8_LAS bf16x8*)(lds + PG8_SA(b, h) + aoff + m * 2048 + k * 1024); } while (0)
; #define PG8_LDB(dst, b, h) do { _Pragma("unroll") for (int n = 0; n < 2; ++n) _Pragma("unroll") for (int k = 0; k < 2; ++k) dst[n][k] = *(const PG8_LAS bf16x8*)(lds + PG8_SB(b, h) + boff + n * 2048 + k * 1024); } while (0)
; #define PG8_MMA(ai, bj, At, Bt) do { __builtin_amdgcn_s_setprio(1); _Pragma("unroll") for (int m = 0; m < 4; ++m) _Pragma("unroll") for (int n = 0; n < 2; ++n) _Pragma("unroll") for (int k = 0; k < 2; ++k) \
;         acc[ai][bj][m][n] = __builtin_amdgcn_mfma_f32_16x16x32_bf16(Bt[n][k], At[m][k], acc[ai][bj][m][n], 0, 0, 0); __builtin_amdgcn_s_setprio(0); } while (0)
; #define PG8_WAIT_V(n) asm volatile("s_waitcnt vmcnt(" #n ")" ::: "memory")
; template <class Epi, class Sched, bool ALIGN_EPI = false, bool SP2 = false>
; __device__ __forceinline__ void gemm_phase(PG8_LAS unsigned char* lds, const Gemm g, const Sched& S, const Epi& E) {
;     ...
;         const char* nA = has_next ? (const char*)g.A + (size_t)nxt.pm * tstep : cA; const char* nB = has_next ? (const char*)g.Bt + (size_t)nxt.pn * tstep : cB;
;         for (int t = 0; t < nt; t += 2) {
;             const bool last = (t == nt - 2);
;             const char* a1 = cA + (size_t)(t + 1) * kstep;
;             const char* a2 = last ? nA : cA + (size_t)(t + 2) * kstep; const char* b2 = last ? nB : cB + (size_t)(t + 2) * kstep;
;             const char* a3 = a2 + kstep; const char* b3 = b2 + kstep;
;             if (last && has_next) S.a_ready(nxt);
;             if constexpr (SP2) {
;             PG8_LDB(B0, 0, 0); PG8_LDB(B1, 0, 1); PG8_SCHED; PG8_LDA(At, 0, 0); PG8_STAGE(PG8_SA(1, 1), a1 + hstep, voffA);
;             PG8_WAIT_V(8); PG8_WAIT_L(0); PG8_BAR; PG8_MMA(0, 0, At, B0); PG8_MMA(0, 1, At, B1); PG8_BAR; PG8_SCHED;
;             PG8_LDA(At, 0, 1); PG8_STAGE(PG8_SB(0, 0), b2, voffB); PG8_STAGE(PG8_SB(0, 1), b2 + hstep, voffB); PG8_STAGE(PG8_SA(0, 0), a2, voffA);
.LBB0_737:
	s_ashr_i32 s51, s50, 31
	s_lshl_b64 s[14:15], s[50:51], 19
	s_add_u32 s52, s22, s14
	s_addc_u32 s53, s23, s15
	s_and_b64 s[14:15], s[8:9], exec
	s_cselect_b32 s51, s53, s57
	s_cselect_b32 s82, s52, s56
	s_ashr_i32 s49, s48, 31
	s_lshl_b64 s[14:15], s[48:49], 19
	v_readlane_b32 s3, v250, 15
	s_add_u32 s54, s3, s14
	v_readlane_b32 s3, v250, 16
	s_addc_u32 s55, s3, s15
	s_and_b64 s[14:15], s[8:9], exec
	s_cselect_b32 s49, s55, s59
	s_cselect_b32 s83, s54, s58
	s_add_u32 s56, s56, 0x40080
	s_addc_u32 s57, s57, 0
	s_add_u32 s84, s58, 0x100
	s_addc_u32 s85, s59, 0
	s_mov_b32 s86, -2
	s_waitcnt vmcnt(0)
	ds_read_b128 v[148:151], v155
	ds_read_b128 v[160:163], v155 offset:1024
	ds_read_b128 v[164:167], v155 offset:2048
	ds_read_b128 v[168:171], v155 offset:3072
	ds_read_b128 v[172:175], v156
	ds_read_b128 v[176:179], v156 offset:1024
	ds_read_b128 v[182:185], v156 offset:2048
	ds_read_b128 v[186:189], v156 offset:3072
	s_add_u32 s3, s56, 0xfffc0080
	s_addc_u32 s14, s57, -1
	s_cmp_eq_u32 s86, 12
	s_cselect_b32 s61, s51, s14
	s_cselect_b32 s60, s82, s3
	s_cselect_b32 s59, s49, s85
	s_cselect_b32 s58, s83, s84
	v_lshl_add_u64 v[202:203], s[56:57], 0, v[140:141]
	s_add_i32 m0, s43, 0xc000
	ds_read_b128 v[190:193], v157
	ds_read_b128 v[194:197], v157 offset:1024
	ds_read_b128 v[198:201], v157 offset:2048
	ds_read_b128 v[208:211], v157 offset:3072
	ds_read_b128 v[212:215], v157 offset:4096
	ds_read_b128 v[216:219], v157 offset:5120
	ds_read_b128 v[220:223], v157 offset:6144
	ds_read_b128 v[224:227], v157 offset:7168
	global_load_lds_dwordx4 v[202:203], off
	v_lshl_add_u64 v[202:203], s[56:57], 0, v[142:143]
	s_add_i32 m0, s43, 0xe000
	s_nop 0
	global_load_lds_dwordx4 v[202:203], off
	s_waitcnt vmcnt(8)
	s_waitcnt lgkmcnt(0)
	s_barrier
	s_setprio 1
	s_waitcnt lgkmcnt(0)
	v_mfma_f32_16x16x32_bf16 v[124:127], v[148:151], v[190:193], 0
	v_mfma_f32_16x16x32_bf16 v[104:107], v[164:167], v[198:201], 0
	v_mfma_f32_16x16x32_bf16 v[92:95], v[148:151], v[212:215], 0
	v_mfma_f32_16x16x32_bf16 v[72:75], v[164:167], v[220:223], 0
	v_mfma_f32_16x16x32_bf16 v[108:111], v[148:151], v[198:201], 0
	v_mfma_f32_16x16x32_bf16 v[120:123], v[164:167], v[190:193], 0
	v_mfma_f32_16x16x32_bf16 v[76:79], v[148:151], v[220:223], 0
	v_mfma_f32_16x16x32_bf16 v[88:91], v[164:167], v[212:215], 0
	v_mfma_f32_16x16x32_bf16 v[124:127], v[160:163], v[194:197], v[124:127]
	v_mfma_f32_16x16x32_bf16 v[104:107], v[168:171], v[208:211], v[104:107]
	v_mfma_f32_16x16x32_bf16 v[92:95], v[160:163], v[216:219], v[92:95]
	v_mfma_f32_16x16x32_bf16 v[72:75], v[168:171], v[224:227], v[72:75]
	v_mfma_f32_16x16x32_bf16 v[108:111], v[160:163], v[208:211], v[108:111]
	v_mfma_f32_16x16x32_bf16 v[120:123], v[168:171], v[194:197], v[120:123]
	v_mfma_f32_16x16x32_bf16 v[76:79], v[160:163], v[224:227], v[76:79]
	v_mfma_f32_16x16x32_bf16 v[88:91], v[168:171], v[216:219], v[88:91]
	s_setprio 0
	s_setprio 1
	v_mfma_f32_16x16x32_bf16 v[116:119], v[172:175], v[190:193], 0
	v_mfma_f32_16x16x32_bf16 v[96:99], v[182:185], v[198:201], 0
	v_mfma_f32_16x16x32_bf16 v[84:87], v[172:175], v[212:215], 0
	v_mfma_f32_16x16x32_bf16 v[64:67], v[182:185], v[220:223], 0
	v_mfma_f32_16x16x32_bf16 v[100:103], v[172:175], v[198:201], 0
	v_mfma_f32_16x16x32_bf16 v[112:115], v[182:185], v[190:193], 0
	v_mfma_f32_16x16x32_bf16 v[68:71], v[172:175], v[220:223], 0
	v_mfma_f32_16x16x32_bf16 v[80:83], v[182:185], v[212:215], 0
	v_mfma_f32_16x16x32_bf16 v[116:119], v[176:179], v[194:197], v[116:119]
	v_mfma_f32_16x16x32_bf16 v[96:99], v[186:189], v[208:211], v[96:99]
	v_mfma_f32_16x16x32_bf16 v[84:87], v[176:179], v[216:219], v[84:87]
	v_mfma_f32_16x16x32_bf16 v[64:67], v[186:189], v[224:227], v[64:67]
	v_mfma_f32_16x16x32_bf16 v[100:103], v[176:179], v[208:211], v[100:103]
	v_mfma_f32_16x16x32_bf16 v[112:115], v[186:189], v[194:197], v[112:115]
	v_mfma_f32_16x16x32_bf16 v[68:71], v[176:179], v[224:227], v[68:71]
	v_mfma_f32_16x16x32_bf16 v[80:83], v[186:189], v[216:219], v[80:83]
	s_setprio 0
	s_barrier
	s_add_i32 s3, s74, s34
	v_lshl_add_u64 v[202:203], s[58:59], 0, v[136:137]
	s_mov_b32 m0, s3
	ds_read_b128 v[190:193], v157 offset:16384
	ds_read_b128 v[194:197], v157 offset:17408
	ds_read_b128 v[198:201], v157 offset:18432
	ds_read_b128 v[208:211], v157 offset:19456
	ds_read_b128 v[212:215], v157 offset:20480
	ds_read_b128 v[216:219], v157 offset:21504
	ds_read_b128 v[220:223], v157 offset:22528
	ds_read_b128 v[224:227], v157 offset:23552
	global_load_lds_dwordx4 v[202:203], off
	s_add_i32 m0, s3, 0x2000
	s_add_u32 s14, s58, 0x40000
	v_lshl_add_u64 v[228:229], s[58:59], 0, v[132:133]
	s_addc_u32 s15, s59, 0
	s_add_i32 s3, s75, s34
	global_load_lds_dwordx4 v[228:229], off
	v_lshl_add_u64 v[230:231], s[14:15], 0, v[136:137]
	s_mov_b32 m0, s3
	global_load_lds_dwordx4 v[230:231], off
	v_lshl_add_u64 v[230:231], s[14:15], 0, v[132:133]
	s_add_i32 m0, s3, 0x2000
	s_nop 0
	global_load_lds_dwordx4 v[230:231], off
	s_waitcnt vmcnt(6)
	s_waitcnt lgkmcnt(0)
	s_barrier
; #define PG8_STAGE(bufoff, gbase, voff) do { _Pragma("unroll") for (int _i = 0; _i < 2; ++_i) \
;         __builtin_amdgcn_global_load_lds((const unsigned*)((const char*)(gbase) + (voff)[_i]), (PG8_LAS unsigned*)(lds + (bufoff) + ldsw + _i * 8192), 16, 0, 0); } while (0)
; #define PG8_LDA(dst, b, h) do { _Pragma("unroll") for (int m = 0; m < 4; ++m) _Pragma("unroll") for (int k = 0; k < 2; ++k) dst[m][k] = *(const PG8_LAS bf16x8*)(lds + PG8_SA(b, h) + aoff + m * 2048 + k * 1024); } while (0)
; #define PG8_LDB(dst, b, h) do { _Pragma("unroll") for (int n = 0; n < 2; ++n) _Pragma("unroll") for (int k = 0; k < 2; ++k) dst[n][k] = *(const PG8_LAS bf16x8*)(lds + PG8_SB(b, h) + boff + n * 2048 + k * 1024); } while (0)
; #define PG8_MMA(ai, bj, At, Bt) do { __builtin_amdgcn_s_setprio(1); _Pragma("unroll") for (int m = 0; m < 4; ++m) _Pragma("unroll") for (int n = 0; n < 2; ++n) _Pragma("unroll") for (int k = 0; k < 2; ++k) \
;         acc[ai][bj][m][n] = __builtin_amdgcn_mfma_f32_16x16x32_bf16(Bt[n][k], At[m][k], acc[ai][bj][m][n], 0, 0, 0); __builtin_amdgcn_s_setprio(0); } while (0)
; #define PG8_WAIT_V(n) asm volatile("s_waitcnt vmcnt(" #n ")" ::: "memory")
; template <class Epi, class Sched, bool ALIGN_EPI = false, bool SP2 = false>
; __device__ __forceinline__ void gemm_phase(PG8_LAS unsigned char* lds, const Gemm g, const Sched& S, const Epi& E) {
;     ...
;             PG8_LDB(B0, 0, 0); PG8_LDB(B1, 0, 1); PG8_SCHED; PG8_LDA(At, 0, 0); PG8_STAGE(PG8_SA(1, 1), a1 + hstep, voffA);
;             PG8_WAIT_V(8); PG8_WAIT_L(0); PG8_BAR; PG8_MMA(0, 0, At, B0); PG8_MMA(0, 1, At, B1); PG8_BAR; PG8_SCHED;
;             PG8_LDA(At, 0, 1); PG8_STAGE(PG8_SB(0, 0), b2, voffB); PG8_STAGE(PG8_SB(0, 1), b2 + hstep, voffB); PG8_STAGE(PG8_SA(0, 0), a2, voffA);
;             PG8_WAIT_V(8); PG8_WAIT_L(0); PG8_BAR; PG8_MMA(1, 0, At, B0); PG8_MMA(1, 1, At, B1); PG8_BAR; PG8_SCHED;
;             PG8_LDB(B0, 1, 0); PG8_LDB(B1, 1, 1); PG8_SCHED; PG8_LDA(At, 1, 0); PG8_STAGE(PG8_SA(0, 1), a2 + hstep, voffA);
;             PG8_WAIT_V(8); PG8_WAIT_L(0); PG8_BAR; PG8_MMA(0, 0, At, B0); PG8_MMA(0, 1, At, B1); PG8_BAR; PG8_SCHED;
;             PG8_LDA(At, 1, 1); PG8_STAGE(PG8_SB(1, 0), b3, voffB); PG8_STAGE(PG8_SB(1, 1), b3 + hstep, voffB); PG8_STAGE(PG8_SA(1, 0), a3, voffA);
;             PG8_WAIT_V(8); PG8_WAIT_L(0); PG8_BAR; PG8_MMA(1, 0, At, B0); PG8_MMA(1, 1, At, B1); PG8_BAR; PG8_SCHED;
	s_setprio 1
	s_waitcnt lgkmcnt(0)
	v_mfma_f32_16x16x32_bf16 v[60:63], v[148:151], v[190:193], 0
	v_mfma_f32_16x16x32_bf16 v[40:43], v[164:167], v[198:201], 0
	v_mfma_f32_16x16x32_bf16 v[28:31], v[148:151], v[212:215], 0
	v_mfma_f32_16x16x32_bf16 v[8:11], v[164:167], v[220:223], 0
	v_mfma_f32_16x16x32_bf16 v[44:47], v[148:151], v[198:201], 0
	v_mfma_f32_16x16x32_bf16 v[56:59], v[164:167], v[190:193], 0
	v_mfma_f32_16x16x32_bf16 v[12:15], v[148:151], v[220:223], 0
	v_mfma_f32_16x16x32_bf16 v[24:27], v[164:167], v[212:215], 0
	v_mfma_f32_16x16x32_bf16 v[60:63], v[160:163], v[194:197], v[60:63]
	v_mfma_f32_16x16x32_bf16 v[40:43], v[168:171], v[208:211], v[40:43]
	v_mfma_f32_16x16x32_bf16 v[28:31], v[160:163], v[216:219], v[28:31]
	v_mfma_f32_16x16x32_bf16 v[8:11], v[168:171], v[224:227], v[8:11]
	v_mfma_f32_16x16x32_bf16 v[44:47], v[160:163], v[208:211], v[44:47]
	v_mfma_f32_16x16x32_bf16 v[56:59], v[168:171], v[194:197], v[56:59]
	v_lshl_add_u64 v[230:231], s[60:61], 0, v[138:139]
	s_mov_b32 m0, s43
	s_nop 0
	global_load_lds_dwordx4 v[230:231], off
	v_mfma_f32_16x16x32_bf16 v[12:15], v[160:163], v[224:227], v[12:15]
	v_mfma_f32_16x16x32_bf16 v[24:27], v[168:171], v[216:219], v[24:27]
	s_setprio 0
	s_setprio 1
	v_mfma_f32_16x16x32_bf16 v[52:55], v[172:175], v[190:193], 0
	v_mfma_f32_16x16x32_bf16 v[32:35], v[182:185], v[198:201], 0
	v_mfma_f32_16x16x32_bf16 v[20:23], v[172:175], v[212:215], 0
	v_mfma_f32_16x16x32_bf16 v[0:3], v[182:185], v[220:223], 0
	v_mfma_f32_16x16x32_bf16 v[36:39], v[172:175], v[198:201], 0
	v_mfma_f32_16x16x32_bf16 v[48:51], v[182:185], v[190:193], 0
	v_mfma_f32_16x16x32_bf16 v[4:7], v[172:175], v[220:223], 0
	v_mfma_f32_16x16x32_bf16 v[16:19], v[182:185], v[212:215], 0
	v_mfma_f32_16x16x32_bf16 v[52:55], v[176:179], v[194:197], v[52:55]
	v_mfma_f32_16x16x32_bf16 v[32:35], v[186:189], v[208:211], v[32:35]
	v_mfma_f32_16x16x32_bf16 v[20:23], v[176:179], v[216:219], v[20:23]
	v_mfma_f32_16x16x32_bf16 v[0:3], v[186:189], v[224:227], v[0:3]
	v_mfma_f32_16x16x32_bf16 v[36:39], v[176:179], v[208:211], v[36:39]
	v_mfma_f32_16x16x32_bf16 v[48:51], v[186:189], v[194:197], v[48:51]
	v_lshl_add_u64 v[232:233], s[60:61], 0, v[134:135]
	s_mov_b32 m0, s62
	s_nop 0
	global_load_lds_dwordx4 v[232:233], off
	v_mfma_f32_16x16x32_bf16 v[4:7], v[176:179], v[224:227], v[4:7]
	v_mfma_f32_16x16x32_bf16 v[16:19], v[186:189], v[216:219], v[16:19]
	s_setprio 0
	s_barrier
	s_add_i32 s3, 0, 0x18000
	v_add_u32_e32 v159, s3, v131
	s_add_i32 s33, 0, 0x1c000
	ds_read_b128 v[148:151], v159
	ds_read_b128 v[160:163], v159 offset:1024
	ds_read_b128 v[164:167], v159 offset:2048
	ds_read_b128 v[168:171], v159 offset:3072
	v_add_u32_e32 v159, s33, v131
	ds_read_b128 v[172:175], v159
	ds_read_b128 v[176:179], v159 offset:1024
	ds_read_b128 v[182:185], v159 offset:2048
	ds_read_b128 v[186:189], v159 offset:3072
	s_add_u32 s14, s60, 0x40000
	s_addc_u32 s15, s61, 0
	s_mov_b32 m0, s63
	v_lshl_add_u64 v[234:235], s[14:15], 0, v[138:139]
	ds_read_b128 v[190:193], v157 offset:32768
	ds_read_b128 v[194:197], v157 offset:33792
	ds_read_b128 v[198:201], v157 offset:34816
	ds_read_b128 v[208:211], v157 offset:35840
	ds_read_b128 v[212:215], v157 offset:36864
	ds_read_b128 v[216:219], v157 offset:37888
	ds_read_b128 v[220:223], v157 offset:38912
	ds_read_b128 v[224:227], v157 offset:39936
	global_load_lds_dwordx4 v[234:235], off
	v_lshl_add_u64 v[234:235], s[14:15], 0, v[134:135]
	s_mov_b32 m0, s64
	s_nop 0
	global_load_lds_dwordx4 v[234:235], off
	s_waitcnt vmcnt(8)
	s_waitcnt lgkmcnt(0)
	s_barrier
	s_setprio 1
	s_waitcnt lgkmcnt(0)
	v_mfma_f32_16x16x32_bf16 v[124:127], v[148:151], v[190:193], v[124:127]
	v_mfma_f32_16x16x32_bf16 v[104:107], v[164:167], v[198:201], v[104:107]
	v_mfma_f32_16x16x32_bf16 v[92:95], v[148:151], v[212:215], v[92:95]
	v_mfma_f32_16x16x32_bf16 v[72:75], v[164:167], v[220:223], v[72:75]
	v_mfma_f32_16x16x32_bf16 v[108:111], v[148:151], v[198:201], v[108:111]
	v_mfma_f32_16x16x32_bf16 v[120:123], v[164:167], v[190:193], v[120:123]
	v_mfma_f32_16x16x32_bf16 v[76:79], v[148:151], v[220:223], v[76:79]
	v_mfma_f32_16x16x32_bf16 v[88:91], v[164:167], v[212:215], v[88:91]
	v_mfma_f32_16x16x32_bf16 v[124:127], v[160:163], v[194:197], v[124:127]
	v_mfma_f32_16x16x32_bf16 v[104:107], v[168:171], v[208:211], v[104:107]
	v_mfma_f32_16x16x32_bf16 v[92:95], v[160:163], v[216:219], v[92:95]
	v_mfma_f32_16x16x32_bf16 v[72:75], v[168:171], v[224:227], v[72:75]
	v_mfma_f32_16x16x32_bf16 v[108:111], v[160:163], v[208:211], v[108:111]
	v_mfma_f32_16x16x32_bf16 v[120:123], v[168:171], v[194:197], v[120:123]
	v_mfma_f32_16x16x32_bf16 v[76:79], v[160:163], v[224:227], v[76:79]
	v_mfma_f32_16x16x32_bf16 v[88:91], v[168:171], v[216:219], v[88:91]
	s_setprio 0
	s_setprio 1
	v_mfma_f32_16x16x32_bf16 v[116:119], v[172:175], v[190:193], v[116:119]
	v_mfma_f32_16x16x32_bf16 v[96:99], v[182:185], v[198:201], v[96:99]
	v_mfma_f32_16x16x32_bf16 v[84:87], v[172:175], v[212:215], v[84:87]
	v_mfma_f32_16x16x32_bf16 v[64:67], v[182:185], v[220:223], v[64:67]
	v_mfma_f32_16x16x32_bf16 v[100:103], v[172:175], v[198:201], v[100:103]
	v_mfma_f32_16x16x32_bf16 v[112:115], v[182:185], v[190:193], v[112:115]
	v_mfma_f32_16x16x32_bf16 v[68:71], v[172:175], v[220:223], v[68:71]
	v_mfma_f32_16x16x32_bf16 v[80:83], v[182:185], v[212:215], v[80:83]
	v_mfma_f32_16x16x32_bf16 v[116:119], v[176:179], v[194:197], v[116:119]
	v_mfma_f32_16x16x32_bf16 v[96:99], v[186:189], v[208:211], v[96:99]
	v_mfma_f32_16x16x32_bf16 v[84:87], v[176:179], v[216:219], v[84:87]
	v_mfma_f32_16x16x32_bf16 v[64:67], v[186:189], v[224:227], v[64:67]
	v_mfma_f32_16x16x32_bf16 v[100:103], v[176:179], v[208:211], v[100:103]
	v_mfma_f32_16x16x32_bf16 v[112:115], v[186:189], v[194:197], v[112:115]
	v_mfma_f32_16x16x32_bf16 v[68:71], v[176:179], v[224:227], v[68:71]
	v_mfma_f32_16x16x32_bf16 v[80:83], v[186:189], v[216:219], v[80:83]
	s_setprio 0
	s_barrier
; #define PG8_STAGE(bufoff, gbase, voff) do { _Pragma("unroll") for (int _i = 0; _i < 2; ++_i) \
;         __builtin_amdgcn_global_load_lds((const unsigned*)((const char*)(gbase) + (voff)[_i]), (PG8_LAS unsigned*)(lds + (bufoff) + ldsw + _i * 8192), 16, 0, 0); } while (0)
; #define PG8_LDA(dst, b, h) do { _Pragma("unroll") for (int m = 0; m < 4; ++m) _Pragma("unroll") for (int k = 0; k < 2; ++k) dst[m][k] = *(const PG8_LAS bf16x8*)(lds + PG8_SA(b, h) + aoff + m * 2048 + k * 1024); } while (0)
; #define PG8_LDB(dst, b, h) do { _Pragma("unroll") for (int n = 0; n < 2; ++n) _Pragma("unroll") for (int k = 0; k < 2; ++k) dst[n][k] = *(const PG8_LAS bf16x8*)(lds + PG8_SB(b, h) + boff + n * 2048 + k * 1024); } while (0)
; template <class Epi, class Sched, bool ALIGN_EPI = false, bool SP2 = false>
; __device__ __forceinline__ void gemm_phase(PG8_LAS unsigned char* lds, const Gemm g, const Sched& S, const Epi& E) {
;     ...
;         for (int t = 0; t < nt; t += 2) {
;             const bool last = (t == nt - 2);
;             const char* a1 = cA + (size_t)(t + 1) * kstep;
;             const char* a2 = last ? nA : cA + (size_t)(t + 2) * kstep; const char* b2 = last ? nB : cB + (size_t)(t + 2) * kstep;
;             const char* a3 = a2 + kstep; const char* b3 = b2 + kstep;
;             if (last && has_next) S.a_ready(nxt);
;             if constexpr (SP2) {
;             PG8_LDB(B0, 0, 0); PG8_LDB(B1, 0, 1); PG8_SCHED; PG8_LDA(At, 0, 0); PG8_STAGE(PG8_SA(1, 1), a1 + hstep, voffA);
;             PG8_WAIT_V(8); PG8_WAIT_L(0); PG8_BAR; PG8_MMA(0, 0, At, B0); PG8_MMA(0, 1, At, B1); PG8_BAR; PG8_SCHED;
;             PG8_LDA(At, 0, 1); PG8_STAGE(PG8_SB(0, 0), b2, voffB); PG8_STAGE(PG8_SB(0, 1), b2 + hstep, voffB); PG8_STAGE(PG8_SA(0, 0), a2, voffA);
;             PG8_WAIT_V(8); PG8_WAIT_L(0); PG8_BAR; PG8_MMA(1, 0, At, B0); PG8_MMA(1, 1, At, B1); PG8_BAR; PG8_SCHED;
;             PG8_LDB(B0, 1, 0); PG8_LDB(B1, 1, 1); PG8_SCHED; PG8_LDA(At, 1, 0); PG8_STAGE(PG8_SA(0, 1), a2 + hstep, voffA);
;             PG8_WAIT_V(8); PG8_WAIT_L(0); PG8_BAR; PG8_MMA(0, 0, At, B0); PG8_MMA(0, 1, At, B1); PG8_BAR; PG8_SCHED;
;             PG8_LDA(At, 1, 1); PG8_STAGE(PG8_SB(1, 0), b3, voffB); PG8_STAGE(PG8_SB(1, 1), b3 + hstep, voffB); PG8_STAGE(PG8_SA(1, 0), a3, voffA);
;             PG8_WAIT_V(8); PG8_WAIT_L(0); PG8_BAR; PG8_MMA(1, 0, At, B0); PG8_MMA(1, 1, At, B1); PG8_BAR; PG8_SCHED;
	s_add_i32 s3, s3, s34
	v_lshl_add_u64 v[202:203], v[202:203], 0, s[38:39]
	s_mov_b32 m0, s3
	ds_read_b128 v[190:193], v157 offset:49152
	ds_read_b128 v[194:197], v157 offset:50176
	ds_read_b128 v[198:201], v157 offset:51200
	ds_read_b128 v[208:211], v157 offset:52224
	ds_read_b128 v[212:215], v157 offset:53248
	ds_read_b128 v[216:219], v157 offset:54272
	ds_read_b128 v[220:223], v157 offset:55296
	ds_read_b128 v[224:227], v157 offset:56320
	global_load_lds_dwordx4 v[202:203], off
	s_add_i32 m0, s3, 0x2000
	s_add_u32 s14, s58, 0x40080
	v_lshl_add_u64 v[202:203], v[228:229], 0, s[38:39]
	s_addc_u32 s15, s59, 0
	s_add_i32 s3, s33, s34
	global_load_lds_dwordx4 v[202:203], off
	v_lshl_add_u64 v[202:203], s[14:15], 0, v[136:137]
	s_mov_b32 m0, s3
	s_nop 0
	global_load_lds_dwordx4 v[202:203], off
	v_lshl_add_u64 v[202:203], s[14:15], 0, v[132:133]
	s_add_i32 m0, s3, 0x2000
	s_nop 0
	global_load_lds_dwordx4 v[202:203], off
	s_waitcnt vmcnt(6)
	s_waitcnt lgkmcnt(0)
	s_barrier
	s_setprio 1
	s_waitcnt lgkmcnt(0)
	v_mfma_f32_16x16x32_bf16 v[60:63], v[148:151], v[190:193], v[60:63]
	v_mfma_f32_16x16x32_bf16 v[40:43], v[164:167], v[198:201], v[40:43]
	v_mfma_f32_16x16x32_bf16 v[28:31], v[148:151], v[212:215], v[28:31]
	v_mfma_f32_16x16x32_bf16 v[8:11], v[164:167], v[220:223], v[8:11]
	v_mfma_f32_16x16x32_bf16 v[44:47], v[148:151], v[198:201], v[44:47]
	v_mfma_f32_16x16x32_bf16 v[56:59], v[164:167], v[190:193], v[56:59]
	v_mfma_f32_16x16x32_bf16 v[12:15], v[148:151], v[220:223], v[12:15]
	v_mfma_f32_16x16x32_bf16 v[24:27], v[164:167], v[212:215], v[24:27]
	v_mfma_f32_16x16x32_bf16 v[60:63], v[160:163], v[194:197], v[60:63]
	v_mfma_f32_16x16x32_bf16 v[40:43], v[168:171], v[208:211], v[40:43]
	v_mfma_f32_16x16x32_bf16 v[28:31], v[160:163], v[216:219], v[28:31]
	v_mfma_f32_16x16x32_bf16 v[8:11], v[168:171], v[224:227], v[8:11]
	v_mfma_f32_16x16x32_bf16 v[44:47], v[160:163], v[208:211], v[44:47]
	v_mfma_f32_16x16x32_bf16 v[56:59], v[168:171], v[194:197], v[56:59]
	v_lshl_add_u64 v[202:203], v[230:231], 0, s[38:39]
	s_mov_b32 m0, s66
	s_nop 0
	global_load_lds_dwordx4 v[202:203], off
	v_mfma_f32_16x16x32_bf16 v[12:15], v[160:163], v[224:227], v[12:15]
	v_mfma_f32_16x16x32_bf16 v[24:27], v[168:171], v[216:219], v[24:27]
	s_setprio 0
	s_setprio 1
	v_mfma_f32_16x16x32_bf16 v[52:55], v[172:175], v[190:193], v[52:55]
	v_mfma_f32_16x16x32_bf16 v[32:35], v[182:185], v[198:201], v[32:35]
	v_mfma_f32_16x16x32_bf16 v[20:23], v[172:175], v[212:215], v[20:23]
	v_mfma_f32_16x16x32_bf16 v[0:3], v[182:185], v[220:223], v[0:3]
	v_mfma_f32_16x16x32_bf16 v[36:39], v[172:175], v[198:201], v[36:39]
	v_mfma_f32_16x16x32_bf16 v[48:51], v[182:185], v[190:193], v[48:51]
	v_mfma_f32_16x16x32_bf16 v[4:7], v[172:175], v[220:223], v[4:7]
	v_mfma_f32_16x16x32_bf16 v[16:19], v[182:185], v[212:215], v[16:19]
	v_mfma_f32_16x16x32_bf16 v[52:55], v[176:179], v[194:197], v[52:55]
	v_mfma_f32_16x16x32_bf16 v[32:35], v[186:189], v[208:211], v[32:35]
	v_mfma_f32_16x16x32_bf16 v[20:23], v[176:179], v[216:219], v[20:23]
	v_mfma_f32_16x16x32_bf16 v[0:3], v[186:189], v[224:227], v[0:3]
	v_mfma_f32_16x16x32_bf16 v[36:39], v[176:179], v[208:211], v[36:39]
	v_mfma_f32_16x16x32_bf16 v[48:51], v[186:189], v[194:197], v[48:51]
	v_lshl_add_u64 v[202:203], v[232:233], 0, s[38:39]
	s_mov_b32 m0, s67
	s_nop 0
	global_load_lds_dwordx4 v[202:203], off
	v_mfma_f32_16x16x32_bf16 v[4:7], v[176:179], v[224:227], v[4:7]
	v_mfma_f32_16x16x32_bf16 v[16:19], v[186:189], v[216:219], v[16:19]
	s_setprio 0
	s_barrier
	s_add_i32 s86, s86, 2
	s_add_u32 s56, s56, 0x100
	s_addc_u32 s57, s57, 0
	s_add_u32 s84, s84, 0x100
	s_addc_u32 s85, s85, 0
.LBB0_738:
	ds_read_b128 v[148:151], v155
	ds_read_b128 v[160:163], v155 offset:1024
	ds_read_b128 v[164:167], v155 offset:2048
	ds_read_b128 v[168:171], v155 offset:3072
	ds_read_b128 v[172:175], v156
	ds_read_b128 v[176:179], v156 offset:1024
	ds_read_b128 v[182:185], v156 offset:2048
	ds_read_b128 v[186:189], v156 offset:3072
	s_add_u32 s3, s56, 0xfffc0080
	s_addc_u32 s14, s57, -1
	s_cmp_eq_u32 s86, 12
	s_cselect_b32 s61, s51, s14
	s_cselect_b32 s60, s82, s3
	s_cselect_b32 s59, s49, s85
	s_cselect_b32 s58, s83, s84
	v_lshl_add_u64 v[202:203], s[56:57], 0, v[140:141]
	s_add_i32 m0, s43, 0xc000
	ds_read_b128 v[190:193], v157
	ds_read_b128 v[194:197], v157 offset:1024
	ds_read_b128 v[198:201], v157 offset:2048
	ds_read_b128 v[208:211], v157 offset:3072
	ds_read_b128 v[212:215], v157 offset:4096
	ds_read_b128 v[216:219], v157 offset:5120
	ds_read_b128 v[220:223], v157 offset:6144
	ds_read_b128 v[224:227], v157 offset:7168
	global_load_lds_dwordx4 v[202:203], off
	v_lshl_add_u64 v[202:203], s[56:57], 0, v[142:143]
	s_add_i32 m0, s43, 0xe000
	s_nop 0
	global_load_lds_dwordx4 v[202:203], off
	s_waitcnt vmcnt(8)
	s_waitcnt lgkmcnt(0)
	s_barrier
; #define PG8_STAGE(bufoff, gbase, voff) do { _Pragma("unroll") for (int _i = 0; _i < 2; ++_i) \
;         __builtin_amdgcn_global_load_lds((const unsigned*)((const char*)(gbase) + (voff)[_i]), (PG8_LAS unsigned*)(lds + (bufoff) + ldsw + _i * 8192), 16, 0, 0); } while (0)
; #define PG8_LDA(dst, b, h) do { _Pragma("unroll") for (int m = 0; m < 4; ++m) _Pragma("unroll") for (int k = 0; k < 2; ++k) dst[m][k] = *(const PG8_LAS bf16x8*)(lds + PG8_SA(b, h) + aoff + m * 2048 + k * 1024); } while (0)
; #define PG8_LDB(dst, b, h) do { _Pragma("unroll") for (int n = 0; n < 2; ++n) _Pragma("unroll") for (int k = 0; k < 2; ++k) dst[n][k] = *(const PG8_LAS bf16x8*)(lds + PG8_SB(b, h) + boff + n * 2048 + k * 1024); } while (0)
; #define PG8_MMA(ai, bj, At, Bt) do { __builtin_amdgcn_s_setprio(1); _Pragma("unroll") for (int m = 0; m < 4; ++m) _Pragma("unroll") for (int n = 0; n < 2; ++n) _Pragma("unroll") for (int k = 0; k < 2; ++k) \
;         acc[ai][bj][m][n] = __builtin_amdgcn_mfma_f32_16x16x32_bf16(Bt[n][k], At[m][k], acc[ai][bj][m][n], 0, 0, 0); __builtin_amdgcn_s_setprio(0); } while (0)
; #define PG8_WAIT_V(n) asm volatile("s_waitcnt vmcnt(" #n ")" ::: "memory")
; template <class Epi, class Sched, bool ALIGN_EPI = false, bool SP2 = false>
; __device__ __forceinline__ void gemm_phase(PG8_LAS unsigned char* lds, const Gemm g, const Sched& S, const Epi& E) {
;     ...
;             PG8_LDB(B0, 0, 0); PG8_LDB(B1, 0, 1); PG8_SCHED; PG8_LDA(At, 0, 0); PG8_STAGE(PG8_SA(1, 1), a1 + hstep, voffA);
;             PG8_WAIT_V(8); PG8_WAIT_L(0); PG8_BAR; PG8_MMA(0, 0, At, B0); PG8_MMA(0, 1, At, B1); PG8_BAR; PG8_SCHED;
;             PG8_LDA(At, 0, 1); PG8_STAGE(PG8_SB(0, 0), b2, voffB); PG8_STAGE(PG8_SB(0, 1), b2 + hstep, voffB); PG8_STAGE(PG8_SA(0, 0), a2, voffA);
;             PG8_WAIT_V(8); PG8_WAIT_L(0); PG8_BAR; PG8_MMA(1, 0, At, B0); PG8_MMA(1, 1, At, B1); PG8_BAR; PG8_SCHED;
;             PG8_LDB(B0, 1, 0); PG8_LDB(B1, 1, 1); PG8_SCHED; PG8_LDA(At, 1, 0); PG8_STAGE(PG8_SA(0, 1), a2 + hstep, voffA);
;             PG8_WAIT_V(8); PG8_WAIT_L(0); PG8_BAR; PG8_MMA(0, 0, At, B0); PG8_MMA(0, 1, At, B1); PG8_BAR; PG8_SCHED;
;             PG8_LDA(At, 1, 1); PG8_STAGE(PG8_SB(1, 0), b3, voffB); PG8_STAGE(PG8_SB(1, 1), b3 + hstep, voffB); PG8_STAGE(PG8_SA(1, 0), a3, voffA);
;             PG8_WAIT_V(8); PG8_WAIT_L(0); PG8_BAR; PG8_MMA(1, 0, At, B0); PG8_MMA(1, 1, At, B1); PG8_BAR; PG8_SCHED;
	s_setprio 1
	s_waitcnt lgkmcnt(0)
	v_mfma_f32_16x16x32_bf16 v[124:127], v[148:151], v[190:193], v[124:127]
	v_mfma_f32_16x16x32_bf16 v[104:107], v[164:167], v[198:201], v[104:107]
	v_mfma_f32_16x16x32_bf16 v[92:95], v[148:151], v[212:215], v[92:95]
	v_mfma_f32_16x16x32_bf16 v[72:75], v[164:167], v[220:223], v[72:75]
	v_mfma_f32_16x16x32_bf16 v[108:111], v[148:151], v[198:201], v[108:111]
	v_mfma_f32_16x16x32_bf16 v[120:123], v[164:167], v[190:193], v[120:123]
	v_mfma_f32_16x16x32_bf16 v[76:79], v[148:151], v[220:223], v[76:79]
	v_mfma_f32_16x16x32_bf16 v[88:91], v[164:167], v[212:215], v[88:91]
	v_mfma_f32_16x16x32_bf16 v[124:127], v[160:163], v[194:197], v[124:127]
	v_mfma_f32_16x16x32_bf16 v[104:107], v[168:171], v[208:211], v[104:107]
	v_mfma_f32_16x16x32_bf16 v[92:95], v[160:163], v[216:219], v[92:95]
	v_mfma_f32_16x16x32_bf16 v[72:75], v[168:171], v[224:227], v[72:75]
	v_mfma_f32_16x16x32_bf16 v[108:111], v[160:163], v[208:211], v[108:111]
	v_mfma_f32_16x16x32_bf16 v[120:123], v[168:171], v[194:197], v[120:123]
	v_mfma_f32_16x16x32_bf16 v[76:79], v[160:163], v[224:227], v[76:79]
	v_mfma_f32_16x16x32_bf16 v[88:91], v[168:171], v[216:219], v[88:91]
	s_setprio 0
	s_setprio 1
	v_mfma_f32_16x16x32_bf16 v[116:119], v[172:175], v[190:193], v[116:119]
	v_mfma_f32_16x16x32_bf16 v[96:99], v[182:185], v[198:201], v[96:99]
	v_mfma_f32_16x16x32_bf16 v[84:87], v[172:175], v[212:215], v[84:87]
	v_mfma_f32_16x16x32_bf16 v[64:67], v[182:185], v[220:223], v[64:67]
	v_mfma_f32_16x16x32_bf16 v[100:103], v[172:175], v[198:201], v[100:103]
	v_mfma_f32_16x16x32_bf16 v[112:115], v[182:185], v[190:193], v[112:115]
	v_mfma_f32_16x16x32_bf16 v[68:71], v[172:175], v[220:223], v[68:71]
	v_mfma_f32_16x16x32_bf16 v[80:83], v[182:185], v[212:215], v[80:83]
	v_mfma_f32_16x16x32_bf16 v[116:119], v[176:179], v[194:197], v[116:119]
	v_mfma_f32_16x16x32_bf16 v[96:99], v[186:189], v[208:211], v[96:99]
	v_mfma_f32_16x16x32_bf16 v[84:87], v[176:179], v[216:219], v[84:87]
	v_mfma_f32_16x16x32_bf16 v[64:67], v[186:189], v[224:227], v[64:67]
	v_mfma_f32_16x16x32_bf16 v[100:103], v[176:179], v[208:211], v[100:103]
	v_mfma_f32_16x16x32_bf16 v[112:115], v[186:189], v[194:197], v[112:115]
	v_mfma_f32_16x16x32_bf16 v[68:71], v[176:179], v[224:227], v[68:71]
	v_mfma_f32_16x16x32_bf16 v[80:83], v[186:189], v[216:219], v[80:83]
	s_setprio 0
	s_barrier
	s_add_i32 s3, s74, s34
	v_lshl_add_u64 v[202:203], s[58:59], 0, v[136:137]
	s_mov_b32 m0, s3
	ds_read_b128 v[190:193], v157 offset:16384
	ds_read_b128 v[194:197], v157 offset:17408
	ds_read_b128 v[198:201], v157 offset:18432
	ds_read_b128 v[208:211], v157 offset:19456
	ds_read_b128 v[212:215], v157 offset:20480
	ds_read_b128 v[216:219], v157 offset:21504
	ds_read_b128 v[220:223], v157 offset:22528
	ds_read_b128 v[224:227], v157 offset:23552
	global_load_lds_dwordx4 v[202:203], off
	s_add_i32 m0, s3, 0x2000
	s_add_u32 s14, s58, 0x40000
	v_lshl_add_u64 v[228:229], s[58:59], 0, v[132:133]
	s_addc_u32 s15, s59, 0
	s_add_i32 s3, s75, s34
	global_load_lds_dwordx4 v[228:229], off
	v_lshl_add_u64 v[230:231], s[14:15], 0, v[136:137]
	s_mov_b32 m0, s3
	global_load_lds_dwordx4 v[230:231], off
	v_lshl_add_u64 v[230:231], s[14:15], 0, v[132:133]
	s_add_i32 m0, s3, 0x2000
	s_nop 0
	global_load_lds_dwordx4 v[230:231], off
	s_waitcnt vmcnt(6)
	s_waitcnt lgkmcnt(0)
	s_barrier
	s_setprio 1
	s_waitcnt lgkmcnt(0)
	v_mfma_f32_16x16x32_bf16 v[60:63], v[148:151], v[190:193], v[60:63]
	v_mfma_f32_16x16x32_bf16 v[40:43], v[164:167], v[198:201], v[40:43]
	v_mfma_f32_16x16x32_bf16 v[28:31], v[148:151], v[212:215], v[28:31]
	v_mfma_f32_16x16x32_bf16 v[8:11], v[164:167], v[220:223], v[8:11]
	v_mfma_f32_16x16x32_bf16 v[44:47], v[148:151], v[198:201], v[44:47]
	v_mfma_f32_16x16x32_bf16 v[56:59], v[164:167], v[190:193], v[56:59]
	v_mfma_f32_16x16x32_bf16 v[12:15], v[148:151], v[220:223], v[12:15]
	v_mfma_f32_16x16x32_bf16 v[24:27], v[164:167], v[212:215], v[24:27]
	v_mfma_f32_16x16x32_bf16 v[60:63], v[160:163], v[194:197], v[60:63]
	v_mfma_f32_16x16x32_bf16 v[40:43], v[168:171], v[208:211], v[40:43]
	v_mfma_f32_16x16x32_bf16 v[28:31], v[160:163], v[216:219], v[28:31]
	v_mfma_f32_16x16x32_bf16 v[8:11], v[168:171], v[224:227], v[8:11]
	v_mfma_f32_16x16x32_bf16 v[44:47], v[160:163], v[208:211], v[44:47]
	v_mfma_f32_16x16x32_bf16 v[56:59], v[168:171], v[194:197], v[56:59]
	v_lshl_add_u64 v[230:231], s[60:61], 0, v[138:139]
	s_mov_b32 m0, s43
	s_nop 0
	global_load_lds_dwordx4 v[230:231], off
	v_mfma_f32_16x16x32_bf16 v[12:15], v[160:163], v[224:227], v[12:15]
	v_mfma_f32_16x16x32_bf16 v[24:27], v[168:171], v[216:219], v[24:27]
	s_setprio 0
	s_setprio 1
	v_mfma_f32_16x16x32_bf16 v[52:55], v[172:175], v[190:193], v[52:55]
	v_mfma_f32_16x16x32_bf16 v[32:35], v[182:185], v[198:201], v[32:35]
	v_mfma_f32_16x16x32_bf16 v[20:23], v[172:175], v[212:215], v[20:23]
	v_mfma_f32_16x16x32_bf16 v[0:3], v[182:185], v[220:223], v[0:3]
	v_mfma_f32_16x16x32_bf16 v[36:39], v[172:175], v[198:201], v[36:39]
	v_mfma_f32_16x16x32_bf16 v[48:51], v[182:185], v[190:193], v[48:51]
	v_mfma_f32_16x16x32_bf16 v[4:7], v[172:175], v[220:223], v[4:7]
	v_mfma_f32_16x16x32_bf16 v[16:19], v[182:185], v[212:215], v[16:19]
	v_mfma_f32_16x16x32_bf16 v[52:55], v[176:179], v[194:197], v[52:55]
	v_mfma_f32_16x16x32_bf16 v[32:35], v[186:189], v[208:211], v[32:35]
	v_mfma_f32_16x16x32_bf16 v[20:23], v[176:179], v[216:219], v[20:23]
	v_mfma_f32_16x16x32_bf16 v[0:3], v[186:189], v[224:227], v[0:3]
	v_mfma_f32_16x16x32_bf16 v[36:39], v[176:179], v[208:211], v[36:39]
	v_mfma_f32_16x16x32_bf16 v[48:51], v[186:189], v[194:197], v[48:51]
	v_lshl_add_u64 v[232:233], s[60:61], 0, v[134:135]
	s_mov_b32 m0, s62
	s_nop 0
	global_load_lds_dwordx4 v[232:233], off
	v_mfma_f32_16x16x32_bf16 v[4:7], v[176:179], v[224:227], v[4:7]
	v_mfma_f32_16x16x32_bf16 v[16:19], v[186:189], v[216:219], v[16:19]
	s_setprio 0
	s_barrier
; #define PG8_STAGE(bufoff, gbase, voff) do { _Pragma("unroll") for (int _i = 0; _i < 2; ++_i) \
;         __builtin_amdgcn_global_load_lds((const unsigned*)((const char*)(gbase) + (voff)[_i]), (PG8_LAS unsigned*)(lds + (bufoff) + ldsw + _i * 8192), 16, 0, 0); } while (0)
; #define PG8_LDA(dst, b, h) do { _Pragma("unroll") for (int m = 0; m < 4; ++m) _Pragma("unroll") for (int k = 0; k < 2; ++k) dst[m][k] = *(const PG8_LAS bf16x8*)(lds + PG8_SA(b, h) + aoff + m * 2048 + k * 1024); } while (0)
; #define PG8_LDB(dst, b, h) do { _Pragma("unroll") for (int n = 0; n < 2; ++n) _Pragma("unroll") for (int k = 0; k < 2; ++k) dst[n][k] = *(const PG8_LAS bf16x8*)(lds + PG8_SB(b, h) + boff + n * 2048 + k * 1024); } while (0)
; #define PG8_MMA(ai, bj, At, Bt) do { __builtin_amdgcn_s_setprio(1); _Pragma("unroll") for (int m = 0; m < 4; ++m) _Pragma("unroll") for (int n = 0; n < 2; ++n) _Pragma("unroll") for (int k = 0; k < 2; ++k) \
;         acc[ai][bj][m][n] = __builtin_amdgcn_mfma_f32_16x16x32_bf16(Bt[n][k], At[m][k], acc[ai][bj][m][n], 0, 0, 0); __builtin_amdgcn_s_setprio(0); } while (0)
; #define PG8_WAIT_V(n) asm volatile("s_waitcnt vmcnt(" #n ")" ::: "memory")
; #define PG8_WAIT_L(n) asm volatile("s_waitcnt lgkmcnt(" #n ")" ::: "memory")
; #define PG8_BAR __builtin_amdgcn_s_barrier()
; #define PG8_SCHED __builtin_amdgcn_sched_barrier(0)
; template <class Epi, class Sched, bool ALIGN_EPI = false, bool SP2 = false>
; __device__ __forceinline__ void gemm_phase(PG8_LAS unsigned char* lds, const Gemm g, const Sched& S, const Epi& E) {
;     ...
;             PG8_LDB(B0, 1, 0); PG8_LDB(B1, 1, 1); PG8_SCHED; PG8_LDA(At, 1, 0); PG8_STAGE(PG8_SA(0, 1), a2 + hstep, voffA);
;             PG8_WAIT_V(8); PG8_WAIT_L(0); PG8_BAR; PG8_MMA(0, 0, At, B0); PG8_MMA(0, 1, At, B1); PG8_BAR; PG8_SCHED;
	s_add_i32 s3, 0, 0x18000
	v_add_u32_e32 v159, s3, v131
	s_add_i32 s33, 0, 0x1c000
	ds_read_b128 v[148:151], v159
	ds_read_b128 v[160:163], v159 offset:1024
	ds_read_b128 v[164:167], v159 offset:2048
	ds_read_b128 v[168:171], v159 offset:3072
	v_add_u32_e32 v159, s33, v131
	ds_read_b128 v[172:175], v159
	ds_read_b128 v[176:179], v159 offset:1024
	ds_read_b128 v[182:185], v159 offset:2048
	ds_read_b128 v[186:189], v159 offset:3072
	s_add_u32 s14, s60, 0x40000
	s_addc_u32 s15, s61, 0
	s_mov_b32 m0, s63
	v_lshl_add_u64 v[234:235], s[14:15], 0, v[138:139]
	ds_read_b128 v[190:193], v157 offset:32768
	ds_read_b128 v[194:197], v157 offset:33792
	ds_read_b128 v[198:201], v157 offset:34816
	ds_read_b128 v[208:211], v157 offset:35840
	ds_read_b128 v[212:215], v157 offset:36864
	ds_read_b128 v[216:219], v157 offset:37888
	ds_read_b128 v[220:223], v157 offset:38912
	ds_read_b128 v[224:227], v157 offset:39936
	global_load_lds_dwordx4 v[234:235], off
	v_lshl_add_u64 v[234:235], s[14:15], 0, v[134:135]
	s_mov_b32 m0, s64
	s_nop 0
	global_load_lds_dwordx4 v[234:235], off
	s_waitcnt vmcnt(8)
	s_waitcnt lgkmcnt(0)
	s_barrier
	s_setprio 1
	s_waitcnt lgkmcnt(0)
	v_mfma_f32_16x16x32_bf16 v[124:127], v[148:151], v[190:193], v[124:127]
	v_mfma_f32_16x16x32_bf16 v[104:107], v[164:167], v[198:201], v[104:107]
	v_mfma_f32_16x16x32_bf16 v[92:95], v[148:151], v[212:215], v[92:95]
	v_mfma_f32_16x16x32_bf16 v[72:75], v[164:167], v[220:223], v[72:75]
	v_mfma_f32_16x16x32_bf16 v[108:111], v[148:151], v[198:201], v[108:111]
	v_mfma_f32_16x16x32_bf16 v[120:123], v[164:167], v[190:193], v[120:123]
	v_mfma_f32_16x16x32_bf16 v[76:79], v[148:151], v[220:223], v[76:79]
	v_mfma_f32_16x16x32_bf16 v[88:91], v[164:167], v[212:215], v[88:91]
	v_mfma_f32_16x16x32_bf16 v[124:127], v[160:163], v[194:197], v[124:127]
	v_mfma_f32_16x16x32_bf16 v[104:107], v[168:171], v[208:211], v[104:107]
	v_mfma_f32_16x16x32_bf16 v[92:95], v[160:163], v[216:219], v[92:95]
	v_mfma_f32_16x16x32_bf16 v[72:75], v[168:171], v[224:227], v[72:75]
	v_mfma_f32_16x16x32_bf16 v[108:111], v[160:163], v[208:211], v[108:111]
	v_mfma_f32_16x16x32_bf16 v[120:123], v[168:171], v[194:197], v[120:123]
	v_mfma_f32_16x16x32_bf16 v[76:79], v[160:163], v[224:227], v[76:79]
	v_mfma_f32_16x16x32_bf16 v[88:91], v[168:171], v[216:219], v[88:91]
	s_setprio 0
	s_setprio 1
	v_mfma_f32_16x16x32_bf16 v[116:119], v[172:175], v[190:193], v[116:119]
	v_mfma_f32_16x16x32_bf16 v[96:99], v[182:185], v[198:201], v[96:99]
	v_mfma_f32_16x16x32_bf16 v[84:87], v[172:175], v[212:215], v[84:87]
	v_mfma_f32_16x16x32_bf16 v[64:67], v[182:185], v[220:223], v[64:67]
	v_mfma_f32_16x16x32_bf16 v[100:103], v[172:175], v[198:201], v[100:103]
	v_mfma_f32_16x16x32_bf16 v[112:115], v[182:185], v[190:193], v[112:115]
	v_mfma_f32_16x16x32_bf16 v[68:71], v[172:175], v[220:223], v[68:71]
	v_mfma_f32_16x16x32_bf16 v[80:83], v[182:185], v[212:215], v[80:83]
	v_mfma_f32_16x16x32_bf16 v[116:119], v[176:179], v[194:197], v[116:119]
	v_mfma_f32_16x16x32_bf16 v[96:99], v[186:189], v[208:211], v[96:99]
	v_mfma_f32_16x16x32_bf16 v[84:87], v[176:179], v[216:219], v[84:87]
	v_mfma_f32_16x16x32_bf16 v[64:67], v[186:189], v[224:227], v[64:67]
	v_mfma_f32_16x16x32_bf16 v[100:103], v[176:179], v[208:211], v[100:103]
	v_mfma_f32_16x16x32_bf16 v[112:115], v[186:189], v[194:197], v[112:115]
	v_mfma_f32_16x16x32_bf16 v[68:71], v[176:179], v[224:227], v[68:71]
	v_mfma_f32_16x16x32_bf16 v[80:83], v[186:189], v[216:219], v[80:83]
	s_setprio 0
	s_barrier
; #define PG8_STAGE(bufoff, gbase, voff) do { _Pragma("unroll") for (int _i = 0; _i < 2; ++_i) \
;         __builtin_amdgcn_global_load_lds((const unsigned*)((const char*)(gbase) + (voff)[_i]), (PG8_LAS unsigned*)(lds + (bufoff) + ldsw + _i * 8192), 16, 0, 0); } while (0)
; #define PG8_LDA(dst, b, h) do { _Pragma("unroll") for (int m = 0; m < 4; ++m) _Pragma("unroll") for (int k = 0; k < 2; ++k) dst[m][k] = *(const PG8_LAS bf16x8*)(lds + PG8_SA(b, h) + aoff + m * 2048 + k * 1024); } while (0)
; #define PG8_LDB(dst, b, h) do { _Pragma("unroll") for (int n = 0; n < 2; ++n) _Pragma("unroll") for (int k = 0; k < 2; ++k) dst[n][k] = *(const PG8_LAS bf16x8*)(lds + PG8_SB(b, h) + boff + n * 2048 + k * 1024); } while (0)
; template <class Epi, class Sched, bool ALIGN_EPI = false, bool SP2 = false>
; __device__ __forceinline__ void gemm_phase(PG8_LAS unsigned char* lds, const Gemm g, const Sched& S, const Epi& E) {
;     ...
;         for (int t = 0; t < nt; t += 2) {
;             const bool last = (t == nt - 2);
;             const char* a1 = cA + (size_t)(t + 1) * kstep;
;             const char* a2 = last ? nA : cA + (size_t)(t + 2) * kstep; const char* b2 = last ? nB : cB + (size_t)(t + 2) * kstep;
;             const char* a3 = a2 + kstep; const char* b3 = b2 + kstep;
;             if (last && has_next) S.a_ready(nxt);
;             if constexpr (SP2) {
;             PG8_LDB(B0, 0, 0); PG8_LDB(B1, 0, 1); PG8_SCHED; PG8_LDA(At, 0, 0); PG8_STAGE(PG8_SA(1, 1), a1 + hstep, voffA);
;             PG8_WAIT_V(8); PG8_WAIT_L(0); PG8_BAR; PG8_MMA(0, 0, At, B0); PG8_MMA(0, 1, At, B1); PG8_BAR; PG8_SCHED;
;             PG8_LDA(At, 0, 1); PG8_STAGE(PG8_SB(0, 0), b2, voffB); PG8_STAGE(PG8_SB(0, 1), b2 + hstep, voffB); PG8_STAGE(PG8_SA(0, 0), a2, voffA);
;             PG8_WAIT_V(8); PG8_WAIT_L(0); PG8_BAR; PG8_MMA(1, 0, At, B0); PG8_MMA(1, 1, At, B1); PG8_BAR; PG8_SCHED;
;             PG8_LDB(B0, 1, 0); PG8_LDB(B1, 1, 1); PG8_SCHED; PG8_LDA(At, 1, 0); PG8_STAGE(PG8_SA(0, 1), a2 + hstep, voffA);
;             PG8_WAIT_V(8); PG8_WAIT_L(0); PG8_BAR; PG8_MMA(0, 0, At, B0); PG8_MMA(0, 1, At, B1); PG8_BAR; PG8_SCHED;
;             PG8_LDA(At, 1, 1); PG8_STAGE(PG8_SB(1, 0), b3, voffB); PG8_STAGE(PG8_SB(1, 1), b3 + hstep, voffB); PG8_STAGE(PG8_SA(1, 0), a3, voffA);
;             PG8_WAIT_V(8); PG8_WAIT_L(0); PG8_BAR; PG8_MMA(1, 0, At, B0); PG8_MMA(1, 1, At, B1); PG8_BAR; PG8_SCHED;
	s_add_i32 s3, s3, s34
	v_lshl_add_u64 v[202:203], v[202:203], 0, s[38:39]
	s_mov_b32 m0, s3
	ds_read_b128 v[190:193], v157 offset:49152
	ds_read_b128 v[194:197], v157 offset:50176
	ds_read_b128 v[198:201], v157 offset:51200
	ds_read_b128 v[208:211], v157 offset:52224
	ds_read_b128 v[212:215], v157 offset:53248
	ds_read_b128 v[216:219], v157 offset:54272
	ds_read_b128 v[220:223], v157 offset:55296
	ds_read_b128 v[224:227], v157 offset:56320
	global_load_lds_dwordx4 v[202:203], off
	s_add_i32 m0, s3, 0x2000
	s_add_u32 s14, s58, 0x40080
	v_lshl_add_u64 v[202:203], v[228:229], 0, s[38:39]
	s_addc_u32 s15, s59, 0
	s_add_i32 s3, s33, s34
	global_load_lds_dwordx4 v[202:203], off
	v_lshl_add_u64 v[202:203], s[14:15], 0, v[136:137]
	s_mov_b32 m0, s3
	s_nop 0
	global_load_lds_dwordx4 v[202:203], off
	v_lshl_add_u64 v[202:203], s[14:15], 0, v[132:133]
	s_add_i32 m0, s3, 0x2000
	s_nop 0
	global_load_lds_dwordx4 v[202:203], off
	s_waitcnt vmcnt(6)
	s_waitcnt lgkmcnt(0)
	s_barrier
	s_setprio 1
	s_waitcnt lgkmcnt(0)
	v_mfma_f32_16x16x32_bf16 v[60:63], v[148:151], v[190:193], v[60:63]
	v_mfma_f32_16x16x32_bf16 v[40:43], v[164:167], v[198:201], v[40:43]
	v_mfma_f32_16x16x32_bf16 v[28:31], v[148:151], v[212:215], v[28:31]
	v_mfma_f32_16x16x32_bf16 v[8:11], v[164:167], v[220:223], v[8:11]
	v_mfma_f32_16x16x32_bf16 v[44:47], v[148:151], v[198:201], v[44:47]
	v_mfma_f32_16x16x32_bf16 v[56:59], v[164:167], v[190:193], v[56:59]
	v_mfma_f32_16x16x32_bf16 v[12:15], v[148:151], v[220:223], v[12:15]
	v_mfma_f32_16x16x32_bf16 v[24:27], v[164:167], v[212:215], v[24:27]
	v_mfma_f32_16x16x32_bf16 v[60:63], v[160:163], v[194:197], v[60:63]
	v_mfma_f32_16x16x32_bf16 v[40:43], v[168:171], v[208:211], v[40:43]
	v_mfma_f32_16x16x32_bf16 v[28:31], v[160:163], v[216:219], v[28:31]
	v_mfma_f32_16x16x32_bf16 v[8:11], v[168:171], v[224:227], v[8:11]
	v_mfma_f32_16x16x32_bf16 v[44:47], v[160:163], v[208:211], v[44:47]
	v_mfma_f32_16x16x32_bf16 v[56:59], v[168:171], v[194:197], v[56:59]
	v_lshl_add_u64 v[202:203], v[230:231], 0, s[38:39]
	s_mov_b32 m0, s66
	s_nop 0
	global_load_lds_dwordx4 v[202:203], off
	v_mfma_f32_16x16x32_bf16 v[12:15], v[160:163], v[224:227], v[12:15]
	v_mfma_f32_16x16x32_bf16 v[24:27], v[168:171], v[216:219], v[24:27]
	s_setprio 0
	s_setprio 1
	v_mfma_f32_16x16x32_bf16 v[52:55], v[172:175], v[190:193], v[52:55]
	v_mfma_f32_16x16x32_bf16 v[32:35], v[182:185], v[198:201], v[32:35]
	v_mfma_f32_16x16x32_bf16 v[20:23], v[172:175], v[212:215], v[20:23]
	v_mfma_f32_16x16x32_bf16 v[0:3], v[182:185], v[220:223], v[0:3]
	v_mfma_f32_16x16x32_bf16 v[36:39], v[172:175], v[198:201], v[36:39]
	v_mfma_f32_16x16x32_bf16 v[48:51], v[182:185], v[190:193], v[48:51]
	v_mfma_f32_16x16x32_bf16 v[4:7], v[172:175], v[220:223], v[4:7]
	v_mfma_f32_16x16x32_bf16 v[16:19], v[182:185], v[212:215], v[16:19]
	v_mfma_f32_16x16x32_bf16 v[52:55], v[176:179], v[194:197], v[52:55]
	v_mfma_f32_16x16x32_bf16 v[32:35], v[186:189], v[208:211], v[32:35]
	v_mfma_f32_16x16x32_bf16 v[20:23], v[176:179], v[216:219], v[20:23]
	v_mfma_f32_16x16x32_bf16 v[0:3], v[186:189], v[224:227], v[0:3]
	v_mfma_f32_16x16x32_bf16 v[36:39], v[176:179], v[208:211], v[36:39]
	v_mfma_f32_16x16x32_bf16 v[48:51], v[186:189], v[194:197], v[48:51]
	v_lshl_add_u64 v[202:203], v[232:233], 0, s[38:39]
	s_mov_b32 m0, s67
	s_nop 0
	global_load_lds_dwordx4 v[202:203], off
	v_mfma_f32_16x16x32_bf16 v[4:7], v[176:179], v[224:227], v[4:7]
	v_mfma_f32_16x16x32_bf16 v[16:19], v[186:189], v[216:219], v[16:19]
	s_setprio 0
	s_barrier
	s_add_i32 s86, s86, 2
	s_add_u32 s56, s56, 0x100
	s_addc_u32 s57, s57, 0
	s_add_u32 s84, s84, 0x100
	s_addc_u32 s85, s85, 0
	s_cmp_gt_u32 s86, 13
	s_cbranch_scc0 .LBB0_738
	s_and_b64 vcc, exec, s[44:45]
	s_cbranch_vccz .LBB0_741
	s_barrier

; #define PG8_STAGE(bufoff, gbase, voff) do { _Pragma("unroll") for (int _i = 0; _i < 2; ++_i) \
;         __builtin_amdgcn_global_load_lds((const unsigned*)((const char*)(gbase) + (voff)[_i]), (PG8_LAS unsigned*)(lds + (bufoff) + ldsw + _i * 8192), 16, 0, 0); } while (0)
; #define PG8_LDA(dst, b, h) do { _Pragma("unroll") for (int m = 0; m < 4; ++m) _Pragma("unroll") for (int k = 0; k < 2; ++k) dst[m][k] = *(const PG8_LAS bf16x8*)(lds + PG8_SA(b, h) + aoff + m * 2048 + k * 1024); } while (0)
; #define PG8_LDB(dst, b, h) do { _Pragma("unroll") for (int n = 0; n < 2; ++n) _Pragma("unroll") for (int k = 0; k < 2; ++k) dst[n][k] = *(const PG8_LAS bf16x8*)(lds + PG8_SB(b, h) + boff + n * 2048 + k * 1024); } while (0)
; #define PG8_BAR __builtin_amdgcn_s_barrier()
; template <class Epi, class Sched, bool ALIGN_EPI = false, bool SP2 = false>
; __device__ __forceinline__ void gemm_phase(PG8_LAS unsigned char* lds, const Gemm g, const Sched& S, const Epi& E) {
;     ...
;         const bool has_next = S.next(ui + 1, nxt);
;         const char* nA = has_next ? (const char*)g.A + (size_t)nxt.pm * tstep : cA; const char* nB = has_next ? (const char*)g.Bt + (size_t)nxt.pn * tstep : cB;
;         for (int t = 0; t < nt; t += 2) {
;             const bool last = (t == nt - 2);
;             const char* a1 = cA + (size_t)(t + 1) * kstep;
;             const char* a2 = last ? nA : cA + (size_t)(t + 2) * kstep; const char* b2 = last ? nB : cB + (size_t)(t + 2) * kstep;
;             const char* a3 = a2 + kstep; const char* b3 = b2 + kstep;
;             if (last && has_next) S.a_ready(nxt);
;             if constexpr (SP2) {
;             PG8_LDB(B0, 0, 0); PG8_LDB(B1, 0, 1); PG8_SCHED; PG8_LDA(At, 0, 0); PG8_STAGE(PG8_SA(1, 1), a1 + hstep, voffA);
;             PG8_WAIT_V(8); PG8_WAIT_L(0); PG8_BAR; PG8_MMA(0, 0, At, B0); PG8_MMA(0, 1, At, B1); PG8_BAR; PG8_SCHED;
;             PG8_LDA(At, 0, 1); PG8_STAGE(PG8_SB(0, 0), b2, voffB); PG8_STAGE(PG8_SB(0, 1), b2 + hstep, voffB); PG8_STAGE(PG8_SA(0, 0), a2, voffA);
;             PG8_WAIT_V(8); PG8_WAIT_L(0); PG8_BAR; PG8_MMA(1, 0, At, B0); PG8_MMA(1, 1, At, B1); PG8_BAR; PG8_SCHED;
;             PG8_LDB(B0, 1, 0); PG8_LDB(B1, 1, 1); PG8_SCHED; PG8_LDA(At, 1, 0); PG8_STAGE(PG8_SA(0, 1), a2 + hstep, voffA);
;             PG8_WAIT_V(8); PG8_WAIT_L(0); PG8_BAR; PG8_MMA(0, 0, At, B0); PG8_MMA(0, 1, At, B1); PG8_BAR; PG8_SCHED;
.LBB0_872:
	s_ashr_i32 s49, s48, 31
	s_lshl_b64 s[50:51], s[48:49], 18
	s_add_u32 s50, s92, s50
	s_addc_u32 s51, s93, s51
	s_and_b64 s[52:53], s[10:11], exec
	s_cselect_b32 s49, s51, s59
	s_cselect_b32 s55, s50, s58
	s_ashr_i32 s45, s44, 31
	s_lshl_b64 s[52:53], s[44:45], 18
	s_add_u32 s52, s76, s52
	s_addc_u32 s53, s77, s53
	s_and_b64 s[62:63], s[10:11], exec
	s_cselect_b32 s45, s53, s61
	s_cselect_b32 s84, s52, s60
	s_add_u32 s58, s58, 0x20080
	s_addc_u32 s59, s59, 0
	s_add_u32 s85, s60, 0x100
	s_addc_u32 s86, s61, 0
	s_mov_b32 s87, -2
	s_waitcnt lgkmcnt(0)
	ds_read_b128 v[144:147], v151
	ds_read_b128 v[156:159], v151 offset:1024
	ds_read_b128 v[160:163], v151 offset:2048
	ds_read_b128 v[164:167], v151 offset:3072
	ds_read_b128 v[168:171], v152
	ds_read_b128 v[172:175], v152 offset:1024
	ds_read_b128 v[176:179], v152 offset:2048
	ds_read_b128 v[182:185], v152 offset:3072
	s_add_u32 s3, s58, 0xfffe0080
	s_addc_u32 s33, s59, -1
	s_cmp_eq_u32 s87, 4
	s_cselect_b32 s63, s49, s33
	s_cselect_b32 s62, s55, s3
	s_cselect_b32 s61, s45, s86
	s_cselect_b32 s60, s84, s85
	v_lshl_add_u64 v[202:203], s[58:59], 0, v[136:137]
	s_add_i32 m0, s15, 0xc000
	ds_read_b128 v[186:189], v153
	ds_read_b128 v[190:193], v153 offset:1024
	ds_read_b128 v[194:197], v153 offset:2048
	ds_read_b128 v[198:201], v153 offset:3072
	ds_read_b128 v[208:211], v153 offset:4096
	ds_read_b128 v[212:215], v153 offset:5120
	ds_read_b128 v[216:219], v153 offset:6144
	ds_read_b128 v[220:223], v153 offset:7168
	global_load_lds_dwordx4 v[202:203], off
	v_lshl_add_u64 v[202:203], s[58:59], 0, v[138:139]
	s_add_i32 m0, s15, 0xe000
	s_nop 0
	global_load_lds_dwordx4 v[202:203], off
	s_waitcnt vmcnt(8)
	s_waitcnt lgkmcnt(0)
	s_barrier
	s_setprio 1
	s_waitcnt lgkmcnt(0)
	v_mfma_f32_16x16x32_bf16 v[124:127], v[144:147], v[186:189], 0
	v_mfma_f32_16x16x32_bf16 v[104:107], v[160:163], v[194:197], 0
	v_mfma_f32_16x16x32_bf16 v[92:95], v[144:147], v[208:211], 0
	v_mfma_f32_16x16x32_bf16 v[72:75], v[160:163], v[216:219], 0
	v_mfma_f32_16x16x32_bf16 v[108:111], v[144:147], v[194:197], 0
	v_mfma_f32_16x16x32_bf16 v[120:123], v[160:163], v[186:189], 0
	v_mfma_f32_16x16x32_bf16 v[76:79], v[144:147], v[216:219], 0
	v_mfma_f32_16x16x32_bf16 v[88:91], v[160:163], v[208:211], 0
	v_mfma_f32_16x16x32_bf16 v[124:127], v[156:159], v[190:193], v[124:127]
	v_mfma_f32_16x16x32_bf16 v[104:107], v[164:167], v[198:201], v[104:107]
	v_mfma_f32_16x16x32_bf16 v[92:95], v[156:159], v[212:215], v[92:95]
	v_mfma_f32_16x16x32_bf16 v[72:75], v[164:167], v[220:223], v[72:75]
	v_mfma_f32_16x16x32_bf16 v[108:111], v[156:159], v[198:201], v[108:111]
	v_mfma_f32_16x16x32_bf16 v[120:123], v[164:167], v[190:193], v[120:123]
	v_mfma_f32_16x16x32_bf16 v[76:79], v[156:159], v[220:223], v[76:79]
	v_mfma_f32_16x16x32_bf16 v[88:91], v[164:167], v[212:215], v[88:91]
	s_setprio 0
	s_setprio 1
	v_mfma_f32_16x16x32_bf16 v[116:119], v[168:171], v[186:189], 0
	v_mfma_f32_16x16x32_bf16 v[96:99], v[176:179], v[194:197], 0
	v_mfma_f32_16x16x32_bf16 v[84:87], v[168:171], v[208:211], 0
	v_mfma_f32_16x16x32_bf16 v[64:67], v[176:179], v[216:219], 0
	v_mfma_f32_16x16x32_bf16 v[100:103], v[168:171], v[194:197], 0
	v_mfma_f32_16x16x32_bf16 v[112:115], v[176:179], v[186:189], 0
	v_mfma_f32_16x16x32_bf16 v[68:71], v[168:171], v[216:219], 0
	v_mfma_f32_16x16x32_bf16 v[80:83], v[176:179], v[208:211], 0
	v_mfma_f32_16x16x32_bf16 v[116:119], v[172:175], v[190:193], v[116:119]
	v_mfma_f32_16x16x32_bf16 v[96:99], v[182:185], v[198:201], v[96:99]
	v_mfma_f32_16x16x32_bf16 v[84:87], v[172:175], v[212:215], v[84:87]
	v_mfma_f32_16x16x32_bf16 v[64:67], v[182:185], v[220:223], v[64:67]
	v_mfma_f32_16x16x32_bf16 v[100:103], v[172:175], v[198:201], v[100:103]
	v_mfma_f32_16x16x32_bf16 v[112:115], v[182:185], v[190:193], v[112:115]
	v_mfma_f32_16x16x32_bf16 v[68:71], v[172:175], v[220:223], v[68:71]
	v_mfma_f32_16x16x32_bf16 v[80:83], v[182:185], v[212:215], v[80:83]
	s_setprio 0
	s_barrier
	s_add_i32 s3, s74, s14
	v_lshl_add_u64 v[202:203], s[60:61], 0, v[130:131]
	s_mov_b32 m0, s3
	ds_read_b128 v[186:189], v153 offset:16384
	ds_read_b128 v[190:193], v153 offset:17408
	ds_read_b128 v[194:197], v153 offset:18432
	ds_read_b128 v[198:201], v153 offset:19456
	ds_read_b128 v[208:211], v153 offset:20480
	ds_read_b128 v[212:215], v153 offset:21504
	ds_read_b128 v[216:219], v153 offset:22528
	ds_read_b128 v[220:223], v153 offset:23552
	global_load_lds_dwordx4 v[202:203], off
	s_add_i32 m0, s3, 0x2000
	s_add_u32 s78, s60, 0x20000
	v_lshl_add_u64 v[224:225], s[60:61], 0, v[134:135]
	s_addc_u32 s79, s61, 0
	s_add_i32 s3, s75, s14
	global_load_lds_dwordx4 v[224:225], off
	v_lshl_add_u64 v[226:227], s[78:79], 0, v[130:131]
	s_mov_b32 m0, s3
	global_load_lds_dwordx4 v[226:227], off
	v_lshl_add_u64 v[226:227], s[78:79], 0, v[134:135]
	s_add_i32 m0, s3, 0x2000
	s_nop 0
	global_load_lds_dwordx4 v[226:227], off
	s_waitcnt vmcnt(6)
	s_waitcnt lgkmcnt(0)
	s_barrier
; #define PG8_STAGE(bufoff, gbase, voff) do { _Pragma("unroll") for (int _i = 0; _i < 2; ++_i) \
;         __builtin_amdgcn_global_load_lds((const unsigned*)((const char*)(gbase) + (voff)[_i]), (PG8_LAS unsigned*)(lds + (bufoff) + ldsw + _i * 8192), 16, 0, 0); } while (0)
; #define PG8_LDA(dst, b, h) do { _Pragma("unroll") for (int m = 0; m < 4; ++m) _Pragma("unroll") for (int k = 0; k < 2; ++k) dst[m][k] = *(const PG8_LAS bf16x8*)(lds + PG8_SA(b, h) + aoff + m * 2048 + k * 1024); } while (0)
; #define PG8_LDB(dst, b, h) do { _Pragma("unroll") for (int n = 0; n < 2; ++n) _Pragma("unroll") for (int k = 0; k < 2; ++k) dst[n][k] = *(const PG8_LAS bf16x8*)(lds + PG8_SB(b, h) + boff + n * 2048 + k * 1024); } while (0)
; #define PG8_MMA(ai, bj, At, Bt) do { __builtin_amdgcn_s_setprio(1); _Pragma("unroll") for (int m = 0; m < 4; ++m) _Pragma("unroll") for (int n = 0; n < 2; ++n) _Pragma("unroll") for (int k = 0; k < 2; ++k) \
;         acc[ai][bj][m][n] = __builtin_amdgcn_mfma_f32_16x16x32_bf16(Bt[n][k], At[m][k], acc[ai][bj][m][n], 0, 0, 0); __builtin_amdgcn_s_setprio(0); } while (0)
; #define PG8_WAIT_V(n) asm volatile("s_waitcnt vmcnt(" #n ")" ::: "memory")
; template <class Epi, class Sched, bool ALIGN_EPI = false, bool SP2 = false>
; __device__ __forceinline__ void gemm_phase(PG8_LAS unsigned char* lds, const Gemm g, const Sched& S, const Epi& E) {
;     ...
;             PG8_LDB(B0, 0, 0); PG8_LDB(B1, 0, 1); PG8_SCHED; PG8_LDA(At, 0, 0); PG8_STAGE(PG8_SA(1, 1), a1 + hstep, voffA);
;             PG8_WAIT_V(8); PG8_WAIT_L(0); PG8_BAR; PG8_MMA(0, 0, At, B0); PG8_MMA(0, 1, At, B1); PG8_BAR; PG8_SCHED;
;             PG8_LDA(At, 0, 1); PG8_STAGE(PG8_SB(0, 0), b2, voffB); PG8_STAGE(PG8_SB(0, 1), b2 + hstep, voffB); PG8_STAGE(PG8_SA(0, 0), a2, voffA);
;             PG8_WAIT_V(8); PG8_WAIT_L(0); PG8_BAR; PG8_MMA(1, 0, At, B0); PG8_MMA(1, 1, At, B1); PG8_BAR; PG8_SCHED;
;             PG8_LDB(B0, 1, 0); PG8_LDB(B1, 1, 1); PG8_SCHED; PG8_LDA(At, 1, 0); PG8_STAGE(PG8_SA(0, 1), a2 + hstep, voffA);
;             PG8_WAIT_V(8); PG8_WAIT_L(0); PG8_BAR; PG8_MMA(0, 0, At, B0); PG8_MMA(0, 1, At, B1); PG8_BAR; PG8_SCHED;
;             PG8_LDA(At, 1, 1); PG8_STAGE(PG8_SB(1, 0), b3, voffB); PG8_STAGE(PG8_SB(1, 1), b3 + hstep, voffB); PG8_STAGE(PG8_SA(1, 0), a3, voffA);
;             PG8_WAIT_V(8); PG8_WAIT_L(0); PG8_BAR; PG8_MMA(1, 0, At, B0); PG8_MMA(1, 1, At, B1); PG8_BAR; PG8_SCHED;
	s_setprio 1
	s_waitcnt lgkmcnt(0)
	v_mfma_f32_16x16x32_bf16 v[60:63], v[144:147], v[186:189], 0
	v_mfma_f32_16x16x32_bf16 v[40:43], v[160:163], v[194:197], 0
	v_mfma_f32_16x16x32_bf16 v[28:31], v[144:147], v[208:211], 0
	v_mfma_f32_16x16x32_bf16 v[8:11], v[160:163], v[216:219], 0
	v_mfma_f32_16x16x32_bf16 v[44:47], v[144:147], v[194:197], 0
	v_mfma_f32_16x16x32_bf16 v[56:59], v[160:163], v[186:189], 0
	v_mfma_f32_16x16x32_bf16 v[12:15], v[144:147], v[216:219], 0
	v_mfma_f32_16x16x32_bf16 v[24:27], v[160:163], v[208:211], 0
	v_mfma_f32_16x16x32_bf16 v[60:63], v[156:159], v[190:193], v[60:63]
	v_mfma_f32_16x16x32_bf16 v[40:43], v[164:167], v[198:201], v[40:43]
	v_mfma_f32_16x16x32_bf16 v[28:31], v[156:159], v[212:215], v[28:31]
	v_mfma_f32_16x16x32_bf16 v[8:11], v[164:167], v[220:223], v[8:11]
	v_mfma_f32_16x16x32_bf16 v[44:47], v[156:159], v[198:201], v[44:47]
	v_mfma_f32_16x16x32_bf16 v[56:59], v[164:167], v[190:193], v[56:59]
	v_lshl_add_u64 v[226:227], s[62:63], 0, v[128:129]
	s_mov_b32 m0, s15
	s_nop 0
	global_load_lds_dwordx4 v[226:227], off
	v_mfma_f32_16x16x32_bf16 v[12:15], v[156:159], v[220:223], v[12:15]
	v_mfma_f32_16x16x32_bf16 v[24:27], v[164:167], v[212:215], v[24:27]
	s_setprio 0
	s_setprio 1
	v_mfma_f32_16x16x32_bf16 v[52:55], v[168:171], v[186:189], 0
	v_mfma_f32_16x16x32_bf16 v[32:35], v[176:179], v[194:197], 0
	v_mfma_f32_16x16x32_bf16 v[20:23], v[168:171], v[208:211], 0
	v_mfma_f32_16x16x32_bf16 v[0:3], v[176:179], v[216:219], 0
	v_mfma_f32_16x16x32_bf16 v[36:39], v[168:171], v[194:197], 0
	v_mfma_f32_16x16x32_bf16 v[48:51], v[176:179], v[186:189], 0
	v_mfma_f32_16x16x32_bf16 v[4:7], v[168:171], v[216:219], 0
	v_mfma_f32_16x16x32_bf16 v[16:19], v[176:179], v[208:211], 0
	v_mfma_f32_16x16x32_bf16 v[52:55], v[172:175], v[190:193], v[52:55]
	v_mfma_f32_16x16x32_bf16 v[32:35], v[182:185], v[198:201], v[32:35]
	v_mfma_f32_16x16x32_bf16 v[20:23], v[172:175], v[212:215], v[20:23]
	v_mfma_f32_16x16x32_bf16 v[0:3], v[182:185], v[220:223], v[0:3]
	v_mfma_f32_16x16x32_bf16 v[36:39], v[172:175], v[198:201], v[36:39]
	v_mfma_f32_16x16x32_bf16 v[48:51], v[182:185], v[190:193], v[48:51]
	v_lshl_add_u64 v[228:229], s[62:63], 0, v[132:133]
	s_mov_b32 m0, s34
	s_nop 0
	global_load_lds_dwordx4 v[228:229], off
	v_mfma_f32_16x16x32_bf16 v[4:7], v[172:175], v[220:223], v[4:7]
	v_mfma_f32_16x16x32_bf16 v[16:19], v[182:185], v[212:215], v[16:19]
	s_setprio 0
	s_barrier
	s_add_i32 s3, 0, 0x18000
	v_add_u32_e32 v155, s3, v149
	s_add_i32 s33, 0, 0x1c000
	ds_read_b128 v[144:147], v155
	ds_read_b128 v[156:159], v155 offset:1024
	ds_read_b128 v[160:163], v155 offset:2048
	ds_read_b128 v[164:167], v155 offset:3072
	v_add_u32_e32 v155, s33, v149
	ds_read_b128 v[168:171], v155
	ds_read_b128 v[172:175], v155 offset:1024
	ds_read_b128 v[176:179], v155 offset:2048
	ds_read_b128 v[182:185], v155 offset:3072
	s_add_u32 s62, s62, 0x20000
	s_addc_u32 s63, s63, 0
	s_mov_b32 m0, s57
	v_lshl_add_u64 v[230:231], s[62:63], 0, v[128:129]
	ds_read_b128 v[186:189], v153 offset:32768
	ds_read_b128 v[190:193], v153 offset:33792
	ds_read_b128 v[194:197], v153 offset:34816
	ds_read_b128 v[198:201], v153 offset:35840
	ds_read_b128 v[208:211], v153 offset:36864
	ds_read_b128 v[212:215], v153 offset:37888
	ds_read_b128 v[216:219], v153 offset:38912
	ds_read_b128 v[220:223], v153 offset:39936
	global_load_lds_dwordx4 v[230:231], off
	v_lshl_add_u64 v[230:231], s[62:63], 0, v[132:133]
	s_mov_b32 m0, s64
	s_nop 0
	global_load_lds_dwordx4 v[230:231], off
	s_waitcnt vmcnt(8)
	s_waitcnt lgkmcnt(0)
	s_barrier
	s_setprio 1
	s_waitcnt lgkmcnt(0)
	v_mfma_f32_16x16x32_bf16 v[124:127], v[144:147], v[186:189], v[124:127]
	v_mfma_f32_16x16x32_bf16 v[104:107], v[160:163], v[194:197], v[104:107]
	v_mfma_f32_16x16x32_bf16 v[92:95], v[144:147], v[208:211], v[92:95]
	v_mfma_f32_16x16x32_bf16 v[72:75], v[160:163], v[216:219], v[72:75]
	v_mfma_f32_16x16x32_bf16 v[108:111], v[144:147], v[194:197], v[108:111]
	v_mfma_f32_16x16x32_bf16 v[120:123], v[160:163], v[186:189], v[120:123]
	v_mfma_f32_16x16x32_bf16 v[76:79], v[144:147], v[216:219], v[76:79]
	v_mfma_f32_16x16x32_bf16 v[88:91], v[160:163], v[208:211], v[88:91]
	v_mfma_f32_16x16x32_bf16 v[124:127], v[156:159], v[190:193], v[124:127]
	v_mfma_f32_16x16x32_bf16 v[104:107], v[164:167], v[198:201], v[104:107]
	v_mfma_f32_16x16x32_bf16 v[92:95], v[156:159], v[212:215], v[92:95]
	v_mfma_f32_16x16x32_bf16 v[72:75], v[164:167], v[220:223], v[72:75]
	v_mfma_f32_16x16x32_bf16 v[108:111], v[156:159], v[198:201], v[108:111]
	v_mfma_f32_16x16x32_bf16 v[120:123], v[164:167], v[190:193], v[120:123]
	v_mfma_f32_16x16x32_bf16 v[76:79], v[156:159], v[220:223], v[76:79]
	v_mfma_f32_16x16x32_bf16 v[88:91], v[164:167], v[212:215], v[88:91]
	s_setprio 0
	s_setprio 1
	v_mfma_f32_16x16x32_bf16 v[116:119], v[168:171], v[186:189], v[116:119]
	v_mfma_f32_16x16x32_bf16 v[96:99], v[176:179], v[194:197], v[96:99]
	v_mfma_f32_16x16x32_bf16 v[84:87], v[168:171], v[208:211], v[84:87]
	v_mfma_f32_16x16x32_bf16 v[64:67], v[176:179], v[216:219], v[64:67]
	v_mfma_f32_16x16x32_bf16 v[100:103], v[168:171], v[194:197], v[100:103]
	v_mfma_f32_16x16x32_bf16 v[112:115], v[176:179], v[186:189], v[112:115]
	v_mfma_f32_16x16x32_bf16 v[68:71], v[168:171], v[216:219], v[68:71]
	v_mfma_f32_16x16x32_bf16 v[80:83], v[176:179], v[208:211], v[80:83]
	v_mfma_f32_16x16x32_bf16 v[116:119], v[172:175], v[190:193], v[116:119]
	v_mfma_f32_16x16x32_bf16 v[96:99], v[182:185], v[198:201], v[96:99]
	v_mfma_f32_16x16x32_bf16 v[84:87], v[172:175], v[212:215], v[84:87]
	v_mfma_f32_16x16x32_bf16 v[64:67], v[182:185], v[220:223], v[64:67]
	v_mfma_f32_16x16x32_bf16 v[100:103], v[172:175], v[198:201], v[100:103]
	v_mfma_f32_16x16x32_bf16 v[112:115], v[182:185], v[190:193], v[112:115]
	v_mfma_f32_16x16x32_bf16 v[68:71], v[172:175], v[220:223], v[68:71]
	v_mfma_f32_16x16x32_bf16 v[80:83], v[182:185], v[212:215], v[80:83]
	s_setprio 0
	s_barrier
; #define PG8_STAGE(bufoff, gbase, voff) do { _Pragma("unroll") for (int _i = 0; _i < 2; ++_i) \
;         __builtin_amdgcn_global_load_lds((const unsigned*)((const char*)(gbase) + (voff)[_i]), (PG8_LAS unsigned*)(lds + (bufoff) + ldsw + _i * 8192), 16, 0, 0); } while (0)
; #define PG8_LDA(dst, b, h) do { _Pragma("unroll") for (int m = 0; m < 4; ++m) _Pragma("unroll") for (int k = 0; k < 2; ++k) dst[m][k] = *(const PG8_LAS bf16x8*)(lds + PG8_SA(b, h) + aoff + m * 2048 + k * 1024); } while (0)
; #define PG8_LDB(dst, b, h) do { _Pragma("unroll") for (int n = 0; n < 2; ++n) _Pragma("unroll") for (int k = 0; k < 2; ++k) dst[n][k] = *(const PG8_LAS bf16x8*)(lds + PG8_SB(b, h) + boff + n * 2048 + k * 1024); } while (0)
; template <class Epi, class Sched, bool ALIGN_EPI = false, bool SP2 = false>
; __device__ __forceinline__ void gemm_phase(PG8_LAS unsigned char* lds, const Gemm g, const Sched& S, const Epi& E) {
;     ...
;         for (int t = 0; t < nt; t += 2) {
;             const bool last = (t == nt - 2);
;             const char* a1 = cA + (size_t)(t + 1) * kstep;
;             const char* a2 = last ? nA : cA + (size_t)(t + 2) * kstep; const char* b2 = last ? nB : cB + (size_t)(t + 2) * kstep;
;             const char* a3 = a2 + kstep; const char* b3 = b2 + kstep;
;             if (last && has_next) S.a_ready(nxt);
;             if constexpr (SP2) {
;             PG8_LDB(B0, 0, 0); PG8_LDB(B1, 0, 1); PG8_SCHED; PG8_LDA(At, 0, 0); PG8_STAGE(PG8_SA(1, 1), a1 + hstep, voffA);
;             PG8_WAIT_V(8); PG8_WAIT_L(0); PG8_BAR; PG8_MMA(0, 0, At, B0); PG8_MMA(0, 1, At, B1); PG8_BAR; PG8_SCHED;
;             PG8_LDA(At, 0, 1); PG8_STAGE(PG8_SB(0, 0), b2, voffB); PG8_STAGE(PG8_SB(0, 1), b2 + hstep, voffB); PG8_STAGE(PG8_SA(0, 0), a2, voffA);
;             PG8_WAIT_V(8); PG8_WAIT_L(0); PG8_BAR; PG8_MMA(1, 0, At, B0); PG8_MMA(1, 1, At, B1); PG8_BAR; PG8_SCHED;
;             PG8_LDB(B0, 1, 0); PG8_LDB(B1, 1, 1); PG8_SCHED; PG8_LDA(At, 1, 0); PG8_STAGE(PG8_SA(0, 1), a2 + hstep, voffA);
;             PG8_WAIT_V(8); PG8_WAIT_L(0); PG8_BAR; PG8_MMA(0, 0, At, B0); PG8_MMA(0, 1, At, B1); PG8_BAR; PG8_SCHED;
;             PG8_LDA(At, 1, 1); PG8_STAGE(PG8_SB(1, 0), b3, voffB); PG8_STAGE(PG8_SB(1, 1), b3 + hstep, voffB); PG8_STAGE(PG8_SA(1, 0), a3, voffA);
;             PG8_WAIT_V(8); PG8_WAIT_L(0); PG8_BAR; PG8_MMA(1, 0, At, B0); PG8_MMA(1, 1, At, B1); PG8_BAR; PG8_SCHED;
	s_add_i32 s3, s3, s14
	v_lshl_add_u64 v[202:203], v[202:203], 0, s[38:39]
	s_mov_b32 m0, s3
	ds_read_b128 v[186:189], v153 offset:49152
	ds_read_b128 v[190:193], v153 offset:50176
	ds_read_b128 v[194:197], v153 offset:51200
	ds_read_b128 v[198:201], v153 offset:52224
	ds_read_b128 v[208:211], v153 offset:53248
	ds_read_b128 v[212:215], v153 offset:54272
	ds_read_b128 v[216:219], v153 offset:55296
	ds_read_b128 v[220:223], v153 offset:56320
	global_load_lds_dwordx4 v[202:203], off
	s_add_i32 m0, s3, 0x2000
	s_add_u32 s60, s60, 0x20080
	v_lshl_add_u64 v[202:203], v[224:225], 0, s[38:39]
	s_addc_u32 s61, s61, 0
	s_add_i32 s3, s33, s14
	global_load_lds_dwordx4 v[202:203], off
	v_lshl_add_u64 v[202:203], s[60:61], 0, v[130:131]
	s_mov_b32 m0, s3
	s_nop 0
	global_load_lds_dwordx4 v[202:203], off
	v_lshl_add_u64 v[202:203], s[60:61], 0, v[134:135]
	s_add_i32 m0, s3, 0x2000
	s_nop 0
	global_load_lds_dwordx4 v[202:203], off
	s_waitcnt vmcnt(6)
	s_waitcnt lgkmcnt(0)
	s_barrier
	s_setprio 1
	s_waitcnt lgkmcnt(0)
	v_mfma_f32_16x16x32_bf16 v[60:63], v[144:147], v[186:189], v[60:63]
	v_mfma_f32_16x16x32_bf16 v[40:43], v[160:163], v[194:197], v[40:43]
	v_mfma_f32_16x16x32_bf16 v[28:31], v[144:147], v[208:211], v[28:31]
	v_mfma_f32_16x16x32_bf16 v[8:11], v[160:163], v[216:219], v[8:11]
	v_mfma_f32_16x16x32_bf16 v[44:47], v[144:147], v[194:197], v[44:47]
	v_mfma_f32_16x16x32_bf16 v[56:59], v[160:163], v[186:189], v[56:59]
	v_mfma_f32_16x16x32_bf16 v[12:15], v[144:147], v[216:219], v[12:15]
	v_mfma_f32_16x16x32_bf16 v[24:27], v[160:163], v[208:211], v[24:27]
	v_mfma_f32_16x16x32_bf16 v[60:63], v[156:159], v[190:193], v[60:63]
	v_mfma_f32_16x16x32_bf16 v[40:43], v[164:167], v[198:201], v[40:43]
	v_mfma_f32_16x16x32_bf16 v[28:31], v[156:159], v[212:215], v[28:31]
	v_mfma_f32_16x16x32_bf16 v[8:11], v[164:167], v[220:223], v[8:11]
	v_mfma_f32_16x16x32_bf16 v[44:47], v[156:159], v[198:201], v[44:47]
	v_mfma_f32_16x16x32_bf16 v[56:59], v[164:167], v[190:193], v[56:59]
	v_lshl_add_u64 v[202:203], v[226:227], 0, s[38:39]
	s_mov_b32 m0, s66
	s_nop 0
	global_load_lds_dwordx4 v[202:203], off
	v_mfma_f32_16x16x32_bf16 v[12:15], v[156:159], v[220:223], v[12:15]
	v_mfma_f32_16x16x32_bf16 v[24:27], v[164:167], v[212:215], v[24:27]
	s_setprio 0
	s_setprio 1
	v_mfma_f32_16x16x32_bf16 v[52:55], v[168:171], v[186:189], v[52:55]
	v_mfma_f32_16x16x32_bf16 v[32:35], v[176:179], v[194:197], v[32:35]
	v_mfma_f32_16x16x32_bf16 v[20:23], v[168:171], v[208:211], v[20:23]
	v_mfma_f32_16x16x32_bf16 v[0:3], v[176:179], v[216:219], v[0:3]
	v_mfma_f32_16x16x32_bf16 v[36:39], v[168:171], v[194:197], v[36:39]
	v_mfma_f32_16x16x32_bf16 v[48:51], v[176:179], v[186:189], v[48:51]
	v_mfma_f32_16x16x32_bf16 v[4:7], v[168:171], v[216:219], v[4:7]
	v_mfma_f32_16x16x32_bf16 v[16:19], v[176:179], v[208:211], v[16:19]
	v_mfma_f32_16x16x32_bf16 v[52:55], v[172:175], v[190:193], v[52:55]
	v_mfma_f32_16x16x32_bf16 v[32:35], v[182:185], v[198:201], v[32:35]
	v_mfma_f32_16x16x32_bf16 v[20:23], v[172:175], v[212:215], v[20:23]
	v_mfma_f32_16x16x32_bf16 v[0:3], v[182:185], v[220:223], v[0:3]
	v_mfma_f32_16x16x32_bf16 v[36:39], v[172:175], v[198:201], v[36:39]
	v_mfma_f32_16x16x32_bf16 v[48:51], v[182:185], v[190:193], v[48:51]
	v_lshl_add_u64 v[202:203], v[228:229], 0, s[38:39]
	s_mov_b32 m0, s67
	s_nop 0
	global_load_lds_dwordx4 v[202:203], off
	v_mfma_f32_16x16x32_bf16 v[4:7], v[172:175], v[220:223], v[4:7]
	v_mfma_f32_16x16x32_bf16 v[16:19], v[182:185], v[212:215], v[16:19]
	s_setprio 0
	s_barrier
	s_add_i32 s87, s87, 2
	s_add_u32 s58, s58, 0x100
	s_addc_u32 s59, s59, 0
	s_add_u32 s85, s85, 0x100
	s_addc_u32 s86, s86, 0
.LBB0_873:
	ds_read_b128 v[144:147], v151
	ds_read_b128 v[156:159], v151 offset:1024
	ds_read_b128 v[160:163], v151 offset:2048
	ds_read_b128 v[164:167], v151 offset:3072
	ds_read_b128 v[168:171], v152
	ds_read_b128 v[172:175], v152 offset:1024
	ds_read_b128 v[176:179], v152 offset:2048
	ds_read_b128 v[182:185], v152 offset:3072
	s_add_u32 s3, s58, 0xfffe0080
	s_addc_u32 s33, s59, -1
	s_cmp_eq_u32 s87, 4
	s_cselect_b32 s63, s49, s33
	s_cselect_b32 s62, s55, s3
	s_cselect_b32 s61, s45, s86
	s_cselect_b32 s60, s84, s85
	v_lshl_add_u64 v[202:203], s[58:59], 0, v[136:137]
	s_add_i32 m0, s15, 0xc000
	ds_read_b128 v[186:189], v153
	ds_read_b128 v[190:193], v153 offset:1024
	ds_read_b128 v[194:197], v153 offset:2048
	ds_read_b128 v[198:201], v153 offset:3072
	ds_read_b128 v[208:211], v153 offset:4096
	ds_read_b128 v[212:215], v153 offset:5120
	ds_read_b128 v[216:219], v153 offset:6144
	ds_read_b128 v[220:223], v153 offset:7168
	global_load_lds_dwordx4 v[202:203], off
	v_lshl_add_u64 v[202:203], s[58:59], 0, v[138:139]
	s_add_i32 m0, s15, 0xe000
	s_nop 0
	global_load_lds_dwordx4 v[202:203], off
	s_waitcnt vmcnt(8)
	s_waitcnt lgkmcnt(0)
	s_barrier
; #define PG8_STAGE(bufoff, gbase, voff) do { _Pragma("unroll") for (int _i = 0; _i < 2; ++_i) \
;         __builtin_amdgcn_global_load_lds((const unsigned*)((const char*)(gbase) + (voff)[_i]), (PG8_LAS unsigned*)(lds + (bufoff) + ldsw + _i * 8192), 16, 0, 0); } while (0)
; #define PG8_LDA(dst, b, h) do { _Pragma("unroll") for (int m = 0; m < 4; ++m) _Pragma("unroll") for (int k = 0; k < 2; ++k) dst[m][k] = *(const PG8_LAS bf16x8*)(lds + PG8_SA(b, h) + aoff + m * 2048 + k * 1024); } while (0)
; #define PG8_LDB(dst, b, h) do { _Pragma("unroll") for (int n = 0; n < 2; ++n) _Pragma("unroll") for (int k = 0; k < 2; ++k) dst[n][k] = *(const PG8_LAS bf16x8*)(lds + PG8_SB(b, h) + boff + n * 2048 + k * 1024); } while (0)
; #define PG8_MMA(ai, bj, At, Bt) do { __builtin_amdgcn_s_setprio(1); _Pragma("unroll") for (int m = 0; m < 4; ++m) _Pragma("unroll") for (int n = 0; n < 2; ++n) _Pragma("unroll") for (int k = 0; k < 2; ++k) \
;         acc[ai][bj][m][n] = __builtin_amdgcn_mfma_f32_16x16x32_bf16(Bt[n][k], At[m][k], acc[ai][bj][m][n], 0, 0, 0); __builtin_amdgcn_s_setprio(0); } while (0)
; #define PG8_WAIT_V(n) asm volatile("s_waitcnt vmcnt(" #n ")" ::: "memory")
; template <class Epi, class Sched, bool ALIGN_EPI = false, bool SP2 = false>
; __device__ __forceinline__ void gemm_phase(PG8_LAS unsigned char* lds, const Gemm g, const Sched& S, const Epi& E) {
;     ...
;             PG8_LDB(B0, 0, 0); PG8_LDB(B1, 0, 1); PG8_SCHED; PG8_LDA(At, 0, 0); PG8_STAGE(PG8_SA(1, 1), a1 + hstep, voffA);
;             PG8_WAIT_V(8); PG8_WAIT_L(0); PG8_BAR; PG8_MMA(0, 0, At, B0); PG8_MMA(0, 1, At, B1); PG8_BAR; PG8_SCHED;
;             PG8_LDA(At, 0, 1); PG8_STAGE(PG8_SB(0, 0), b2, voffB); PG8_STAGE(PG8_SB(0, 1), b2 + hstep, voffB); PG8_STAGE(PG8_SA(0, 0), a2, voffA);
;             PG8_WAIT_V(8); PG8_WAIT_L(0); PG8_BAR; PG8_MMA(1, 0, At, B0); PG8_MMA(1, 1, At, B1); PG8_BAR; PG8_SCHED;
;             PG8_LDB(B0, 1, 0); PG8_LDB(B1, 1, 1); PG8_SCHED; PG8_LDA(At, 1, 0); PG8_STAGE(PG8_SA(0, 1), a2 + hstep, voffA);
;             PG8_WAIT_V(8); PG8_WAIT_L(0); PG8_BAR; PG8_MMA(0, 0, At, B0); PG8_MMA(0, 1, At, B1); PG8_BAR; PG8_SCHED;
;             PG8_LDA(At, 1, 1); PG8_STAGE(PG8_SB(1, 0), b3, voffB); PG8_STAGE(PG8_SB(1, 1), b3 + hstep, voffB); PG8_STAGE(PG8_SA(1, 0), a3, voffA);
;             PG8_WAIT_V(8); PG8_WAIT_L(0); PG8_BAR; PG8_MMA(1, 0, At, B0); PG8_MMA(1, 1, At, B1); PG8_BAR; PG8_SCHED;
	s_setprio 1
	s_waitcnt lgkmcnt(0)
	v_mfma_f32_16x16x32_bf16 v[124:127], v[144:147], v[186:189], v[124:127]
	v_mfma_f32_16x16x32_bf16 v[104:107], v[160:163], v[194:197], v[104:107]
	v_mfma_f32_16x16x32_bf16 v[92:95], v[144:147], v[208:211], v[92:95]
	v_mfma_f32_16x16x32_bf16 v[72:75], v[160:163], v[216:219], v[72:75]
	v_mfma_f32_16x16x32_bf16 v[108:111], v[144:147], v[194:197], v[108:111]
	v_mfma_f32_16x16x32_bf16 v[120:123], v[160:163], v[186:189], v[120:123]
	v_mfma_f32_16x16x32_bf16 v[76:79], v[144:147], v[216:219], v[76:79]
	v_mfma_f32_16x16x32_bf16 v[88:91], v[160:163], v[208:211], v[88:91]
	v_mfma_f32_16x16x32_bf16 v[124:127], v[156:159], v[190:193], v[124:127]
	v_mfma_f32_16x16x32_bf16 v[104:107], v[164:167], v[198:201], v[104:107]
	v_mfma_f32_16x16x32_bf16 v[92:95], v[156:159], v[212:215], v[92:95]
	v_mfma_f32_16x16x32_bf16 v[72:75], v[164:167], v[220:223], v[72:75]
	v_mfma_f32_16x16x32_bf16 v[108:111], v[156:159], v[198:201], v[108:111]
	v_mfma_f32_16x16x32_bf16 v[120:123], v[164:167], v[190:193], v[120:123]
	v_mfma_f32_16x16x32_bf16 v[76:79], v[156:159], v[220:223], v[76:79]
	v_mfma_f32_16x16x32_bf16 v[88:91], v[164:167], v[212:215], v[88:91]
	s_setprio 0
	s_setprio 1
	v_mfma_f32_16x16x32_bf16 v[116:119], v[168:171], v[186:189], v[116:119]
	v_mfma_f32_16x16x32_bf16 v[96:99], v[176:179], v[194:197], v[96:99]
	v_mfma_f32_16x16x32_bf16 v[84:87], v[168:171], v[208:211], v[84:87]
	v_mfma_f32_16x16x32_bf16 v[64:67], v[176:179], v[216:219], v[64:67]
	v_mfma_f32_16x16x32_bf16 v[100:103], v[168:171], v[194:197], v[100:103]
	v_mfma_f32_16x16x32_bf16 v[112:115], v[176:179], v[186:189], v[112:115]
	v_mfma_f32_16x16x32_bf16 v[68:71], v[168:171], v[216:219], v[68:71]
	v_mfma_f32_16x16x32_bf16 v[80:83], v[176:179], v[208:211], v[80:83]
	v_mfma_f32_16x16x32_bf16 v[116:119], v[172:175], v[190:193], v[116:119]
	v_mfma_f32_16x16x32_bf16 v[96:99], v[182:185], v[198:201], v[96:99]
	v_mfma_f32_16x16x32_bf16 v[84:87], v[172:175], v[212:215], v[84:87]
	v_mfma_f32_16x16x32_bf16 v[64:67], v[182:185], v[220:223], v[64:67]
	v_mfma_f32_16x16x32_bf16 v[100:103], v[172:175], v[198:201], v[100:103]
	v_mfma_f32_16x16x32_bf16 v[112:115], v[182:185], v[190:193], v[112:115]
	v_mfma_f32_16x16x32_bf16 v[68:71], v[172:175], v[220:223], v[68:71]
	v_mfma_f32_16x16x32_bf16 v[80:83], v[182:185], v[212:215], v[80:83]
	s_setprio 0
	s_barrier
	s_add_i32 s3, s74, s14
	v_lshl_add_u64 v[202:203], s[60:61], 0, v[130:131]
	s_mov_b32 m0, s3
	ds_read_b128 v[186:189], v153 offset:16384
	ds_read_b128 v[190:193], v153 offset:17408
	ds_read_b128 v[194:197], v153 offset:18432
	ds_read_b128 v[198:201], v153 offset:19456
	ds_read_b128 v[208:211], v153 offset:20480
	ds_read_b128 v[212:215], v153 offset:21504
	ds_read_b128 v[216:219], v153 offset:22528
	ds_read_b128 v[220:223], v153 offset:23552
	global_load_lds_dwordx4 v[202:203], off
	s_add_i32 m0, s3, 0x2000
	s_add_u32 s78, s60, 0x20000
	v_lshl_add_u64 v[224:225], s[60:61], 0, v[134:135]
	s_addc_u32 s79, s61, 0
	s_add_i32 s3, s75, s14
	global_load_lds_dwordx4 v[224:225], off
	v_lshl_add_u64 v[226:227], s[78:79], 0, v[130:131]
	s_mov_b32 m0, s3
	global_load_lds_dwordx4 v[226:227], off
	v_lshl_add_u64 v[226:227], s[78:79], 0, v[134:135]
	s_add_i32 m0, s3, 0x2000
	s_nop 0
	global_load_lds_dwordx4 v[226:227], off
	s_waitcnt vmcnt(6)
	s_waitcnt lgkmcnt(0)
	s_barrier
	s_setprio 1
	s_waitcnt lgkmcnt(0)
	v_mfma_f32_16x16x32_bf16 v[60:63], v[144:147], v[186:189], v[60:63]
	v_mfma_f32_16x16x32_bf16 v[40:43], v[160:163], v[194:197], v[40:43]
	v_mfma_f32_16x16x32_bf16 v[28:31], v[144:147], v[208:211], v[28:31]
	v_mfma_f32_16x16x32_bf16 v[8:11], v[160:163], v[216:219], v[8:11]
	v_mfma_f32_16x16x32_bf16 v[44:47], v[144:147], v[194:197], v[44:47]
	v_mfma_f32_16x16x32_bf16 v[56:59], v[160:163], v[186:189], v[56:59]
	v_mfma_f32_16x16x32_bf16 v[12:15], v[144:147], v[216:219], v[12:15]
	v_mfma_f32_16x16x32_bf16 v[24:27], v[160:163], v[208:211], v[24:27]
	v_mfma_f32_16x16x32_bf16 v[60:63], v[156:159], v[190:193], v[60:63]
	v_mfma_f32_16x16x32_bf16 v[40:43], v[164:167], v[198:201], v[40:43]
	v_mfma_f32_16x16x32_bf16 v[28:31], v[156:159], v[212:215], v[28:31]
	v_mfma_f32_16x16x32_bf16 v[8:11], v[164:167], v[220:223], v[8:11]
	v_mfma_f32_16x16x32_bf16 v[44:47], v[156:159], v[198:201], v[44:47]
	v_mfma_f32_16x16x32_bf16 v[56:59], v[164:167], v[190:193], v[56:59]
	v_lshl_add_u64 v[226:227], s[62:63], 0, v[128:129]
	s_mov_b32 m0, s15
	s_nop 0
	global_load_lds_dwordx4 v[226:227], off
	v_mfma_f32_16x16x32_bf16 v[12:15], v[156:159], v[220:223], v[12:15]
	v_mfma_f32_16x16x32_bf16 v[24:27], v[164:167], v[212:215], v[24:27]
	s_setprio 0
	s_setprio 1
	v_mfma_f32_16x16x32_bf16 v[52:55], v[168:171], v[186:189], v[52:55]
	v_mfma_f32_16x16x32_bf16 v[32:35], v[176:179], v[194:197], v[32:35]
	v_mfma_f32_16x16x32_bf16 v[20:23], v[168:171], v[208:211], v[20:23]
	v_mfma_f32_16x16x32_bf16 v[0:3], v[176:179], v[216:219], v[0:3]
	v_mfma_f32_16x16x32_bf16 v[36:39], v[168:171], v[194:197], v[36:39]
	v_mfma_f32_16x16x32_bf16 v[48:51], v[176:179], v[186:189], v[48:51]
	v_mfma_f32_16x16x32_bf16 v[4:7], v[168:171], v[216:219], v[4:7]
	v_mfma_f32_16x16x32_bf16 v[16:19], v[176:179], v[208:211], v[16:19]
	v_mfma_f32_16x16x32_bf16 v[52:55], v[172:175], v[190:193], v[52:55]
	v_mfma_f32_16x16x32_bf16 v[32:35], v[182:185], v[198:201], v[32:35]
	v_mfma_f32_16x16x32_bf16 v[20:23], v[172:175], v[212:215], v[20:23]
	v_mfma_f32_16x16x32_bf16 v[0:3], v[182:185], v[220:223], v[0:3]
	v_mfma_f32_16x16x32_bf16 v[36:39], v[172:175], v[198:201], v[36:39]
	v_mfma_f32_16x16x32_bf16 v[48:51], v[182:185], v[190:193], v[48:51]
	v_lshl_add_u64 v[228:229], s[62:63], 0, v[132:133]
	s_mov_b32 m0, s34
	s_nop 0
	global_load_lds_dwordx4 v[228:229], off
	v_mfma_f32_16x16x32_bf16 v[4:7], v[172:175], v[220:223], v[4:7]
	v_mfma_f32_16x16x32_bf16 v[16:19], v[182:185], v[212:215], v[16:19]
	s_setprio 0
	s_barrier
; #define PG8_STAGE(bufoff, gbase, voff) do { _Pragma("unroll") for (int _i = 0; _i < 2; ++_i) \
;         __builtin_amdgcn_global_load_lds((const unsigned*)((const char*)(gbase) + (voff)[_i]), (PG8_LAS unsigned*)(lds + (bufoff) + ldsw + _i * 8192), 16, 0, 0); } while (0)
; #define PG8_LDA(dst, b, h) do { _Pragma("unroll") for (int m = 0; m < 4; ++m) _Pragma("unroll") for (int k = 0; k < 2; ++k) dst[m][k] = *(const PG8_LAS bf16x8*)(lds + PG8_SA(b, h) + aoff + m * 2048 + k * 1024); } while (0)
; #define PG8_LDB(dst, b, h) do { _Pragma("unroll") for (int n = 0; n < 2; ++n) _Pragma("unroll") for (int k = 0; k < 2; ++k) dst[n][k] = *(const PG8_LAS bf16x8*)(lds + PG8_SB(b, h) + boff + n * 2048 + k * 1024); } while (0)
; #define PG8_MMA(ai, bj, At, Bt) do { __builtin_amdgcn_s_setprio(1); _Pragma("unroll") for (int m = 0; m < 4; ++m) _Pragma("unroll") for (int n = 0; n < 2; ++n) _Pragma("unroll") for (int k = 0; k < 2; ++k) \
;         acc[ai][bj][m][n] = __builtin_amdgcn_mfma_f32_16x16x32_bf16(Bt[n][k], At[m][k], acc[ai][bj][m][n], 0, 0, 0); __builtin_amdgcn_s_setprio(0); } while (0)
; #define PG8_WAIT_V(n) asm volatile("s_waitcnt vmcnt(" #n ")" ::: "memory")
; #define PG8_WAIT_L(n) asm volatile("s_waitcnt lgkmcnt(" #n ")" ::: "memory")
; #define PG8_BAR __builtin_amdgcn_s_barrier()
; #define PG8_SCHED __builtin_amdgcn_sched_barrier(0)
; template <class Epi, class Sched, bool ALIGN_EPI = false, bool SP2 = false>
; __device__ __forceinline__ void gemm_phase(PG8_LAS unsigned char* lds, const Gemm g, const Sched& S, const Epi& E) {
;     ...
;             PG8_LDB(B0, 1, 0); PG8_LDB(B1, 1, 1); PG8_SCHED; PG8_LDA(At, 1, 0); PG8_STAGE(PG8_SA(0, 1), a2 + hstep, voffA);
;             PG8_WAIT_V(8); PG8_WAIT_L(0); PG8_BAR; PG8_MMA(0, 0, At, B0); PG8_MMA(0, 1, At, B1); PG8_BAR; PG8_SCHED;
	s_add_i32 s3, 0, 0x18000
	v_add_u32_e32 v155, s3, v149
	s_add_i32 s33, 0, 0x1c000
	ds_read_b128 v[144:147], v155
	ds_read_b128 v[156:159], v155 offset:1024
	ds_read_b128 v[160:163], v155 offset:2048
	ds_read_b128 v[164:167], v155 offset:3072
	v_add_u32_e32 v155, s33, v149
	ds_read_b128 v[168:171], v155
	ds_read_b128 v[172:175], v155 offset:1024
	ds_read_b128 v[176:179], v155 offset:2048
	ds_read_b128 v[182:185], v155 offset:3072
	s_add_u32 s62, s62, 0x20000
	s_addc_u32 s63, s63, 0
	s_mov_b32 m0, s57
	v_lshl_add_u64 v[230:231], s[62:63], 0, v[128:129]
	ds_read_b128 v[186:189], v153 offset:32768
	ds_read_b128 v[190:193], v153 offset:33792
	ds_read_b128 v[194:197], v153 offset:34816
	ds_read_b128 v[198:201], v153 offset:35840
	ds_read_b128 v[208:211], v153 offset:36864
	ds_read_b128 v[212:215], v153 offset:37888
	ds_read_b128 v[216:219], v153 offset:38912
	ds_read_b128 v[220:223], v153 offset:39936
	global_load_lds_dwordx4 v[230:231], off
	v_lshl_add_u64 v[230:231], s[62:63], 0, v[132:133]
	s_mov_b32 m0, s64
	s_nop 0
	global_load_lds_dwordx4 v[230:231], off
	s_waitcnt vmcnt(8)
	s_waitcnt lgkmcnt(0)
	s_barrier
	s_setprio 1
	s_waitcnt lgkmcnt(0)
	v_mfma_f32_16x16x32_bf16 v[124:127], v[144:147], v[186:189], v[124:127]
	v_mfma_f32_16x16x32_bf16 v[104:107], v[160:163], v[194:197], v[104:107]
	v_mfma_f32_16x16x32_bf16 v[92:95], v[144:147], v[208:211], v[92:95]
	v_mfma_f32_16x16x32_bf16 v[72:75], v[160:163], v[216:219], v[72:75]
	v_mfma_f32_16x16x32_bf16 v[108:111], v[144:147], v[194:197], v[108:111]
	v_mfma_f32_16x16x32_bf16 v[120:123], v[160:163], v[186:189], v[120:123]
	v_mfma_f32_16x16x32_bf16 v[76:79], v[144:147], v[216:219], v[76:79]
	v_mfma_f32_16x16x32_bf16 v[88:91], v[160:163], v[208:211], v[88:91]
	v_mfma_f32_16x16x32_bf16 v[124:127], v[156:159], v[190:193], v[124:127]
	v_mfma_f32_16x16x32_bf16 v[104:107], v[164:167], v[198:201], v[104:107]
	v_mfma_f32_16x16x32_bf16 v[92:95], v[156:159], v[212:215], v[92:95]
	v_mfma_f32_16x16x32_bf16 v[72:75], v[164:167], v[220:223], v[72:75]
	v_mfma_f32_16x16x32_bf16 v[108:111], v[156:159], v[198:201], v[108:111]
	v_mfma_f32_16x16x32_bf16 v[120:123], v[164:167], v[190:193], v[120:123]
	v_mfma_f32_16x16x32_bf16 v[76:79], v[156:159], v[220:223], v[76:79]
	v_mfma_f32_16x16x32_bf16 v[88:91], v[164:167], v[212:215], v[88:91]
	s_setprio 0
	s_setprio 1
	v_mfma_f32_16x16x32_bf16 v[116:119], v[168:171], v[186:189], v[116:119]
	v_mfma_f32_16x16x32_bf16 v[96:99], v[176:179], v[194:197], v[96:99]
	v_mfma_f32_16x16x32_bf16 v[84:87], v[168:171], v[208:211], v[84:87]
	v_mfma_f32_16x16x32_bf16 v[64:67], v[176:179], v[216:219], v[64:67]
	v_mfma_f32_16x16x32_bf16 v[100:103], v[168:171], v[194:197], v[100:103]
	v_mfma_f32_16x16x32_bf16 v[112:115], v[176:179], v[186:189], v[112:115]
	v_mfma_f32_16x16x32_bf16 v[68:71], v[168:171], v[216:219], v[68:71]
	v_mfma_f32_16x16x32_bf16 v[80:83], v[176:179], v[208:211], v[80:83]
	v_mfma_f32_16x16x32_bf16 v[116:119], v[172:175], v[190:193], v[116:119]
	v_mfma_f32_16x16x32_bf16 v[96:99], v[182:185], v[198:201], v[96:99]
	v_mfma_f32_16x16x32_bf16 v[84:87], v[172:175], v[212:215], v[84:87]
	v_mfma_f32_16x16x32_bf16 v[64:67], v[182:185], v[220:223], v[64:67]
	v_mfma_f32_16x16x32_bf16 v[100:103], v[172:175], v[198:201], v[100:103]
	v_mfma_f32_16x16x32_bf16 v[112:115], v[182:185], v[190:193], v[112:115]
	v_mfma_f32_16x16x32_bf16 v[68:71], v[172:175], v[220:223], v[68:71]
	v_mfma_f32_16x16x32_bf16 v[80:83], v[182:185], v[212:215], v[80:83]
	s_setprio 0
	s_barrier
; #define PG8_STAGE(bufoff, gbase, voff) do { _Pragma("unroll") for (int _i = 0; _i < 2; ++_i) \
;         __builtin_amdgcn_global_load_lds((const unsigned*)((const char*)(gbase) + (voff)[_i]), (PG8_LAS unsigned*)(lds + (bufoff) + ldsw + _i * 8192), 16, 0, 0); } while (0)
; #define PG8_LDA(dst, b, h) do { _Pragma("unroll") for (int m = 0; m < 4; ++m) _Pragma("unroll") for (int k = 0; k < 2; ++k) dst[m][k] = *(const PG8_LAS bf16x8*)(lds + PG8_SA(b, h) + aoff + m * 2048 + k * 1024); } while (0)
; #define PG8_LDB(dst, b, h) do { _Pragma("unroll") for (int n = 0; n < 2; ++n) _Pragma("unroll") for (int k = 0; k < 2; ++k) dst[n][k] = *(const PG8_LAS bf16x8*)(lds + PG8_SB(b, h) + boff + n * 2048 + k * 1024); } while (0)
; template <class Epi, class Sched, bool ALIGN_EPI = false, bool SP2 = false>
; __device__ __forceinline__ void gemm_phase(PG8_LAS unsigned char* lds, const Gemm g, const Sched& S, const Epi& E) {
;     ...
;         for (int t = 0; t < nt; t += 2) {
;             const bool last = (t == nt - 2);
;             const char* a1 = cA + (size_t)(t + 1) * kstep;
;             const char* a2 = last ? nA : cA + (size_t)(t + 2) * kstep; const char* b2 = last ? nB : cB + (size_t)(t + 2) * kstep;
;             const char* a3 = a2 + kstep; const char* b3 = b2 + kstep;
;             if (last && has_next) S.a_ready(nxt);
;             if constexpr (SP2) {
;             PG8_LDB(B0, 0, 0); PG8_LDB(B1, 0, 1); PG8_SCHED; PG8_LDA(At, 0, 0); PG8_STAGE(PG8_SA(1, 1), a1 + hstep, voffA);
;             PG8_WAIT_V(8); PG8_WAIT_L(0); PG8_BAR; PG8_MMA(0, 0, At, B0); PG8_MMA(0, 1, At, B1); PG8_BAR; PG8_SCHED;
;             PG8_LDA(At, 0, 1); PG8_STAGE(PG8_SB(0, 0), b2, voffB); PG8_STAGE(PG8_SB(0, 1), b2 + hstep, voffB); PG8_STAGE(PG8_SA(0, 0), a2, voffA);
;             PG8_WAIT_V(8); PG8_WAIT_L(0); PG8_BAR; PG8_MMA(1, 0, At, B0); PG8_MMA(1, 1, At, B1); PG8_BAR; PG8_SCHED;
;             PG8_LDB(B0, 1, 0); PG8_LDB(B1, 1, 1); PG8_SCHED; PG8_LDA(At, 1, 0); PG8_STAGE(PG8_SA(0, 1), a2 + hstep, voffA);
;             PG8_WAIT_V(8); PG8_WAIT_L(0); PG8_BAR; PG8_MMA(0, 0, At, B0); PG8_MMA(0, 1, At, B1); PG8_BAR; PG8_SCHED;
;             PG8_LDA(At, 1, 1); PG8_STAGE(PG8_SB(1, 0), b3, voffB); PG8_STAGE(PG8_SB(1, 1), b3 + hstep, voffB); PG8_STAGE(PG8_SA(1, 0), a3, voffA);
;             PG8_WAIT_V(8); PG8_WAIT_L(0); PG8_BAR; PG8_MMA(1, 0, At, B0); PG8_MMA(1, 1, At, B1); PG8_BAR; PG8_SCHED;
	s_add_i32 s3, s3, s14
	v_lshl_add_u64 v[202:203], v[202:203], 0, s[38:39]
	s_mov_b32 m0, s3
	ds_read_b128 v[186:189], v153 offset:49152
	ds_read_b128 v[190:193], v153 offset:50176
	ds_read_b128 v[194:197], v153 offset:51200
	ds_read_b128 v[198:201], v153 offset:52224
	ds_read_b128 v[208:211], v153 offset:53248
	ds_read_b128 v[212:215], v153 offset:54272
	ds_read_b128 v[216:219], v153 offset:55296
	ds_read_b128 v[220:223], v153 offset:56320
	global_load_lds_dwordx4 v[202:203], off
	s_add_i32 m0, s3, 0x2000
	s_add_u32 s60, s60, 0x20080
	v_lshl_add_u64 v[202:203], v[224:225], 0, s[38:39]
	s_addc_u32 s61, s61, 0
	s_add_i32 s3, s33, s14
	global_load_lds_dwordx4 v[202:203], off
	v_lshl_add_u64 v[202:203], s[60:61], 0, v[130:131]
	s_mov_b32 m0, s3
	s_nop 0
	global_load_lds_dwordx4 v[202:203], off
	v_lshl_add_u64 v[202:203], s[60:61], 0, v[134:135]
	s_add_i32 m0, s3, 0x2000
	s_nop 0
	global_load_lds_dwordx4 v[202:203], off
	s_waitcnt vmcnt(6)
	s_waitcnt lgkmcnt(0)
	s_barrier
	s_setprio 1
	s_waitcnt lgkmcnt(0)
	v_mfma_f32_16x16x32_bf16 v[60:63], v[144:147], v[186:189], v[60:63]
	v_mfma_f32_16x16x32_bf16 v[40:43], v[160:163], v[194:197], v[40:43]
	v_mfma_f32_16x16x32_bf16 v[28:31], v[144:147], v[208:211], v[28:31]
	v_mfma_f32_16x16x32_bf16 v[8:11], v[160:163], v[216:219], v[8:11]
	v_mfma_f32_16x16x32_bf16 v[44:47], v[144:147], v[194:197], v[44:47]
	v_mfma_f32_16x16x32_bf16 v[56:59], v[160:163], v[186:189], v[56:59]
	v_mfma_f32_16x16x32_bf16 v[12:15], v[144:147], v[216:219], v[12:15]
	v_mfma_f32_16x16x32_bf16 v[24:27], v[160:163], v[208:211], v[24:27]
	v_mfma_f32_16x16x32_bf16 v[60:63], v[156:159], v[190:193], v[60:63]
	v_mfma_f32_16x16x32_bf16 v[40:43], v[164:167], v[198:201], v[40:43]
	v_mfma_f32_16x16x32_bf16 v[28:31], v[156:159], v[212:215], v[28:31]
	v_mfma_f32_16x16x32_bf16 v[8:11], v[164:167], v[220:223], v[8:11]
	v_mfma_f32_16x16x32_bf16 v[44:47], v[156:159], v[198:201], v[44:47]
	v_mfma_f32_16x16x32_bf16 v[56:59], v[164:167], v[190:193], v[56:59]
	v_lshl_add_u64 v[202:203], v[226:227], 0, s[38:39]
	s_mov_b32 m0, s66
	s_nop 0
	global_load_lds_dwordx4 v[202:203], off
	v_mfma_f32_16x16x32_bf16 v[12:15], v[156:159], v[220:223], v[12:15]
	v_mfma_f32_16x16x32_bf16 v[24:27], v[164:167], v[212:215], v[24:27]
	s_setprio 0
	s_setprio 1
	v_mfma_f32_16x16x32_bf16 v[52:55], v[168:171], v[186:189], v[52:55]
	v_mfma_f32_16x16x32_bf16 v[32:35], v[176:179], v[194:197], v[32:35]
	v_mfma_f32_16x16x32_bf16 v[20:23], v[168:171], v[208:211], v[20:23]
	v_mfma_f32_16x16x32_bf16 v[0:3], v[176:179], v[216:219], v[0:3]
	v_mfma_f32_16x16x32_bf16 v[36:39], v[168:171], v[194:197], v[36:39]
	v_mfma_f32_16x16x32_bf16 v[48:51], v[176:179], v[186:189], v[48:51]
	v_mfma_f32_16x16x32_bf16 v[4:7], v[168:171], v[216:219], v[4:7]
	v_mfma_f32_16x16x32_bf16 v[16:19], v[176:179], v[208:211], v[16:19]
	v_mfma_f32_16x16x32_bf16 v[52:55], v[172:175], v[190:193], v[52:55]
	v_mfma_f32_16x16x32_bf16 v[32:35], v[182:185], v[198:201], v[32:35]
	v_mfma_f32_16x16x32_bf16 v[20:23], v[172:175], v[212:215], v[20:23]
	v_mfma_f32_16x16x32_bf16 v[0:3], v[182:185], v[220:223], v[0:3]
	v_mfma_f32_16x16x32_bf16 v[36:39], v[172:175], v[198:201], v[36:39]
	v_mfma_f32_16x16x32_bf16 v[48:51], v[182:185], v[190:193], v[48:51]
	v_lshl_add_u64 v[202:203], v[228:229], 0, s[38:39]
	s_mov_b32 m0, s67
	s_nop 0
	global_load_lds_dwordx4 v[202:203], off
	v_mfma_f32_16x16x32_bf16 v[4:7], v[172:175], v[220:223], v[4:7]
	v_mfma_f32_16x16x32_bf16 v[16:19], v[182:185], v[212:215], v[16:19]
	s_setprio 0
	s_barrier
	s_add_i32 s87, s87, 2
	s_add_u32 s58, s58, 0x100
	s_addc_u32 s59, s59, 0
	s_add_u32 s85, s85, 0x100
	s_addc_u32 s86, s86, 0
	s_cmp_gt_u32 s87, 5
	s_cbranch_scc0 .LBB0_873
	s_and_b64 vcc, exec, s[42:43]
	s_cbranch_vccz .LBB0_876
	s_barrier

; #define PG8_STAGE(bufoff, gbase, voff) do { _Pragma("unroll") for (int _i = 0; _i < 2; ++_i) \
;         __builtin_amdgcn_global_load_lds((const unsigned*)((const char*)(gbase) + (voff)[_i]), (PG8_LAS unsigned*)(lds + (bufoff) + ldsw + _i * 8192), 16, 0, 0); } while (0)
; #define PG8_LDA(dst, b, h) do { _Pragma("unroll") for (int m = 0; m < 4; ++m) _Pragma("unroll") for (int k = 0; k < 2; ++k) dst[m][k] = *(const PG8_LAS bf16x8*)(lds + PG8_SA(b, h) + aoff + m * 2048 + k * 1024); } while (0)
; #define PG8_LDB(dst, b, h) do { _Pragma("unroll") for (int n = 0; n < 2; ++n) _Pragma("unroll") for (int k = 0; k < 2; ++k) dst[n][k] = *(const PG8_LAS bf16x8*)(lds + PG8_SB(b, h) + boff + n * 2048 + k * 1024); } while (0)
; #define PG8_BAR __builtin_amdgcn_s_barrier()
; template <class Epi, class Sched, bool ALIGN_EPI = false, bool SP2 = false>
; __device__ __forceinline__ void gemm_phase(PG8_LAS unsigned char* lds, const Gemm g, const Sched& S, const Epi& E) {
;     ...
;         const bool has_next = S.next(ui + 1, nxt);
;         const char* nA = has_next ? (const char*)g.A + (size_t)nxt.pm * tstep : cA; const char* nB = has_next ? (const char*)g.Bt + (size_t)nxt.pn * tstep : cB;
;         for (int t = 0; t < nt; t += 2) {
;             const bool last = (t == nt - 2);
;             const char* a1 = cA + (size_t)(t + 1) * kstep;
;             const char* a2 = last ? nA : cA + (size_t)(t + 2) * kstep; const char* b2 = last ? nB : cB + (size_t)(t + 2) * kstep;
;             const char* a3 = a2 + kstep; const char* b3 = b2 + kstep;
;             if (last && has_next) S.a_ready(nxt);
;             if constexpr (SP2) {
;             PG8_LDB(B0, 0, 0); PG8_LDB(B1, 0, 1); PG8_SCHED; PG8_LDA(At, 0, 0); PG8_STAGE(PG8_SA(1, 1), a1 + hstep, voffA);
;             PG8_WAIT_V(8); PG8_WAIT_L(0); PG8_BAR; PG8_MMA(0, 0, At, B0); PG8_MMA(0, 1, At, B1); PG8_BAR; PG8_SCHED;
;             PG8_LDA(At, 0, 1); PG8_STAGE(PG8_SB(0, 0), b2, voffB); PG8_STAGE(PG8_SB(0, 1), b2 + hstep, voffB); PG8_STAGE(PG8_SA(0, 0), a2, voffA);
;             PG8_WAIT_V(8); PG8_WAIT_L(0); PG8_BAR; PG8_MMA(1, 0, At, B0); PG8_MMA(1, 1, At, B1); PG8_BAR; PG8_SCHED;
;             PG8_LDB(B0, 1, 0); PG8_LDB(B1, 1, 1); PG8_SCHED; PG8_LDA(At, 1, 0); PG8_STAGE(PG8_SA(0, 1), a2 + hstep, voffA);
;             PG8_WAIT_V(8); PG8_WAIT_L(0); PG8_BAR; PG8_MMA(0, 0, At, B0); PG8_MMA(0, 1, At, B1); PG8_BAR; PG8_SCHED;
.LBB0_956:
	s_ashr_i32 s45, s44, 31
	s_lshl_b64 s[48:49], s[44:45], 19
	s_add_u32 s48, s22, s48
	s_addc_u32 s49, s23, s49
	s_and_b64 s[50:51], s[10:11], exec
	s_cselect_b32 s45, s49, s55
	s_cselect_b32 s75, s48, s54
	s_ashr_i32 s43, s42, 31
	s_lshl_b64 s[50:51], s[42:43], 19
	v_readlane_b32 s3, v250, 18
	s_add_u32 s50, s3, s50
	v_readlane_b32 s3, v250, 19
	s_addc_u32 s51, s3, s51
	s_and_b64 s[58:59], s[10:11], exec
	s_cselect_b32 s43, s51, s57
	s_cselect_b32 s76, s50, s56
	s_add_u32 s54, s54, 0x40080
	s_addc_u32 s55, s55, 0
	s_add_u32 s77, s56, 0x100
	s_addc_u32 s82, s57, 0
	s_mov_b32 s83, -2
	ds_read_b128 v[144:147], v155
	ds_read_b128 v[148:151], v155 offset:1024
	ds_read_b128 v[160:163], v155 offset:2048
	ds_read_b128 v[164:167], v155 offset:3072
	ds_read_b128 v[168:171], v156
	ds_read_b128 v[172:175], v156 offset:1024
	ds_read_b128 v[176:179], v156 offset:2048
	ds_read_b128 v[182:185], v156 offset:3072
	s_add_u32 s3, s54, 0xfffc0080
	s_addc_u32 s33, s55, -1
	s_cmp_eq_u32 s83, 12
	s_cselect_b32 s59, s45, s33
	s_cselect_b32 s58, s75, s3
	s_cselect_b32 s57, s43, s82
	s_cselect_b32 s56, s76, s77
	v_lshl_add_u64 v[202:203], s[54:55], 0, v[136:137]
	s_add_i32 m0, s34, 0xc000
	ds_read_b128 v[186:189], v157
	ds_read_b128 v[190:193], v157 offset:1024
	ds_read_b128 v[194:197], v157 offset:2048
	ds_read_b128 v[198:201], v157 offset:3072
	ds_read_b128 v[208:211], v157 offset:4096
	ds_read_b128 v[212:215], v157 offset:5120
	ds_read_b128 v[216:219], v157 offset:6144
	ds_read_b128 v[220:223], v157 offset:7168
	global_load_lds_dwordx4 v[202:203], off
	v_lshl_add_u64 v[202:203], s[54:55], 0, v[138:139]
	s_add_i32 m0, s34, 0xe000
	s_nop 0
	global_load_lds_dwordx4 v[202:203], off
	s_waitcnt vmcnt(8)
	s_waitcnt lgkmcnt(0)
	s_barrier
	s_setprio 1
	s_waitcnt lgkmcnt(0)
	v_mfma_f32_16x16x32_bf16 v[124:127], v[144:147], v[186:189], 0
	v_mfma_f32_16x16x32_bf16 v[104:107], v[160:163], v[194:197], 0
	v_mfma_f32_16x16x32_bf16 v[92:95], v[144:147], v[208:211], 0
	v_mfma_f32_16x16x32_bf16 v[72:75], v[160:163], v[216:219], 0
	v_mfma_f32_16x16x32_bf16 v[108:111], v[144:147], v[194:197], 0
	v_mfma_f32_16x16x32_bf16 v[120:123], v[160:163], v[186:189], 0
	v_mfma_f32_16x16x32_bf16 v[76:79], v[144:147], v[216:219], 0
	v_mfma_f32_16x16x32_bf16 v[88:91], v[160:163], v[208:211], 0
	v_mfma_f32_16x16x32_bf16 v[124:127], v[148:151], v[190:193], v[124:127]
	v_mfma_f32_16x16x32_bf16 v[104:107], v[164:167], v[198:201], v[104:107]
	v_mfma_f32_16x16x32_bf16 v[92:95], v[148:151], v[212:215], v[92:95]
	v_mfma_f32_16x16x32_bf16 v[72:75], v[164:167], v[220:223], v[72:75]
	v_mfma_f32_16x16x32_bf16 v[108:111], v[148:151], v[198:201], v[108:111]
	v_mfma_f32_16x16x32_bf16 v[120:123], v[164:167], v[190:193], v[120:123]
	v_mfma_f32_16x16x32_bf16 v[76:79], v[148:151], v[220:223], v[76:79]
	v_mfma_f32_16x16x32_bf16 v[88:91], v[164:167], v[212:215], v[88:91]
	s_setprio 0
	s_setprio 1
	v_mfma_f32_16x16x32_bf16 v[116:119], v[168:171], v[186:189], 0
	v_mfma_f32_16x16x32_bf16 v[96:99], v[176:179], v[194:197], 0
	v_mfma_f32_16x16x32_bf16 v[84:87], v[168:171], v[208:211], 0
	v_mfma_f32_16x16x32_bf16 v[64:67], v[176:179], v[216:219], 0
	v_mfma_f32_16x16x32_bf16 v[100:103], v[168:171], v[194:197], 0
	v_mfma_f32_16x16x32_bf16 v[112:115], v[176:179], v[186:189], 0
	v_mfma_f32_16x16x32_bf16 v[68:71], v[168:171], v[216:219], 0
	v_mfma_f32_16x16x32_bf16 v[80:83], v[176:179], v[208:211], 0
	v_mfma_f32_16x16x32_bf16 v[116:119], v[172:175], v[190:193], v[116:119]
	v_mfma_f32_16x16x32_bf16 v[96:99], v[182:185], v[198:201], v[96:99]
	v_mfma_f32_16x16x32_bf16 v[84:87], v[172:175], v[212:215], v[84:87]
	v_mfma_f32_16x16x32_bf16 v[64:67], v[182:185], v[220:223], v[64:67]
	v_mfma_f32_16x16x32_bf16 v[100:103], v[172:175], v[198:201], v[100:103]
	v_mfma_f32_16x16x32_bf16 v[112:115], v[182:185], v[190:193], v[112:115]
	v_mfma_f32_16x16x32_bf16 v[68:71], v[172:175], v[220:223], v[68:71]
	v_mfma_f32_16x16x32_bf16 v[80:83], v[182:185], v[212:215], v[80:83]
	s_setprio 0
	s_barrier
	s_add_i32 s3, s65, s14
	v_lshl_add_u64 v[202:203], s[56:57], 0, v[132:133]
	s_mov_b32 m0, s3
	ds_read_b128 v[186:189], v157 offset:16384
	ds_read_b128 v[190:193], v157 offset:17408
	ds_read_b128 v[194:197], v157 offset:18432
	ds_read_b128 v[198:201], v157 offset:19456
	ds_read_b128 v[208:211], v157 offset:20480
	ds_read_b128 v[212:215], v157 offset:21504
	ds_read_b128 v[216:219], v157 offset:22528
	ds_read_b128 v[220:223], v157 offset:23552
	global_load_lds_dwordx4 v[202:203], off
	s_add_i32 m0, s3, 0x2000
	s_add_u32 s78, s56, 0x40000
	v_lshl_add_u64 v[224:225], s[56:57], 0, v[128:129]
	s_addc_u32 s79, s57, 0
	s_add_i32 s3, s66, s14
	global_load_lds_dwordx4 v[224:225], off
	v_lshl_add_u64 v[226:227], s[78:79], 0, v[132:133]
	s_mov_b32 m0, s3
	global_load_lds_dwordx4 v[226:227], off
	v_lshl_add_u64 v[226:227], s[78:79], 0, v[128:129]
	s_add_i32 m0, s3, 0x2000
	s_nop 0
	global_load_lds_dwordx4 v[226:227], off
	s_waitcnt vmcnt(6)
	s_waitcnt lgkmcnt(0)
	s_barrier
; #define PG8_STAGE(bufoff, gbase, voff) do { _Pragma("unroll") for (int _i = 0; _i < 2; ++_i) \
;         __builtin_amdgcn_global_load_lds((const unsigned*)((const char*)(gbase) + (voff)[_i]), (PG8_LAS unsigned*)(lds + (bufoff) + ldsw + _i * 8192), 16, 0, 0); } while (0)
; #define PG8_LDA(dst, b, h) do { _Pragma("unroll") for (int m = 0; m < 4; ++m) _Pragma("unroll") for (int k = 0; k < 2; ++k) dst[m][k] = *(const PG8_LAS bf16x8*)(lds + PG8_SA(b, h) + aoff + m * 2048 + k * 1024); } while (0)
; #define PG8_LDB(dst, b, h) do { _Pragma("unroll") for (int n = 0; n < 2; ++n) _Pragma("unroll") for (int k = 0; k < 2; ++k) dst[n][k] = *(const PG8_LAS bf16x8*)(lds + PG8_SB(b, h) + boff + n * 2048 + k * 1024); } while (0)
; #define PG8_MMA(ai, bj, At, Bt) do { __builtin_amdgcn_s_setprio(1); _Pragma("unroll") for (int m = 0; m < 4; ++m) _Pragma("unroll") for (int n = 0; n < 2; ++n) _Pragma("unroll") for (int k = 0; k < 2; ++k) \
;         acc[ai][bj][m][n] = __builtin_amdgcn_mfma_f32_16x16x32_bf16(Bt[n][k], At[m][k], acc[ai][bj][m][n], 0, 0, 0); __builtin_amdgcn_s_setprio(0); } while (0)
; #define PG8_WAIT_V(n) asm volatile("s_waitcnt vmcnt(" #n ")" ::: "memory")
; template <class Epi, class Sched, bool ALIGN_EPI = false, bool SP2 = false>
; __device__ __forceinline__ void gemm_phase(PG8_LAS unsigned char* lds, const Gemm g, const Sched& S, const Epi& E) {
;     ...
;             PG8_LDB(B0, 0, 0); PG8_LDB(B1, 0, 1); PG8_SCHED; PG8_LDA(At, 0, 0); PG8_STAGE(PG8_SA(1, 1), a1 + hstep, voffA);
;             PG8_WAIT_V(8); PG8_WAIT_L(0); PG8_BAR; PG8_MMA(0, 0, At, B0); PG8_MMA(0, 1, At, B1); PG8_BAR; PG8_SCHED;
;             PG8_LDA(At, 0, 1); PG8_STAGE(PG8_SB(0, 0), b2, voffB); PG8_STAGE(PG8_SB(0, 1), b2 + hstep, voffB); PG8_STAGE(PG8_SA(0, 0), a2, voffA);
;             PG8_WAIT_V(8); PG8_WAIT_L(0); PG8_BAR; PG8_MMA(1, 0, At, B0); PG8_MMA(1, 1, At, B1); PG8_BAR; PG8_SCHED;
;             PG8_LDB(B0, 1, 0); PG8_LDB(B1, 1, 1); PG8_SCHED; PG8_LDA(At, 1, 0); PG8_STAGE(PG8_SA(0, 1), a2 + hstep, voffA);
;             PG8_WAIT_V(8); PG8_WAIT_L(0); PG8_BAR; PG8_MMA(0, 0, At, B0); PG8_MMA(0, 1, At, B1); PG8_BAR; PG8_SCHED;
;             PG8_LDA(At, 1, 1); PG8_STAGE(PG8_SB(1, 0), b3, voffB); PG8_STAGE(PG8_SB(1, 1), b3 + hstep, voffB); PG8_STAGE(PG8_SA(1, 0), a3, voffA);
;             PG8_WAIT_V(8); PG8_WAIT_L(0); PG8_BAR; PG8_MMA(1, 0, At, B0); PG8_MMA(1, 1, At, B1); PG8_BAR; PG8_SCHED;
	s_setprio 1
	s_waitcnt lgkmcnt(0)
	v_mfma_f32_16x16x32_bf16 v[60:63], v[144:147], v[186:189], 0
	v_mfma_f32_16x16x32_bf16 v[40:43], v[160:163], v[194:197], 0
	v_mfma_f32_16x16x32_bf16 v[28:31], v[144:147], v[208:211], 0
	v_mfma_f32_16x16x32_bf16 v[8:11], v[160:163], v[216:219], 0
	v_mfma_f32_16x16x32_bf16 v[44:47], v[144:147], v[194:197], 0
	v_mfma_f32_16x16x32_bf16 v[56:59], v[160:163], v[186:189], 0
	v_mfma_f32_16x16x32_bf16 v[12:15], v[144:147], v[216:219], 0
	v_mfma_f32_16x16x32_bf16 v[24:27], v[160:163], v[208:211], 0
	v_mfma_f32_16x16x32_bf16 v[60:63], v[148:151], v[190:193], v[60:63]
	v_mfma_f32_16x16x32_bf16 v[40:43], v[164:167], v[198:201], v[40:43]
	v_mfma_f32_16x16x32_bf16 v[28:31], v[148:151], v[212:215], v[28:31]
	v_mfma_f32_16x16x32_bf16 v[8:11], v[164:167], v[220:223], v[8:11]
	v_mfma_f32_16x16x32_bf16 v[44:47], v[148:151], v[198:201], v[44:47]
	v_mfma_f32_16x16x32_bf16 v[56:59], v[164:167], v[190:193], v[56:59]
	v_lshl_add_u64 v[226:227], s[58:59], 0, v[134:135]
	s_mov_b32 m0, s34
	s_nop 0
	global_load_lds_dwordx4 v[226:227], off
	v_mfma_f32_16x16x32_bf16 v[12:15], v[148:151], v[220:223], v[12:15]
	v_mfma_f32_16x16x32_bf16 v[24:27], v[164:167], v[212:215], v[24:27]
	s_setprio 0
	s_setprio 1
	v_mfma_f32_16x16x32_bf16 v[52:55], v[168:171], v[186:189], 0
	v_mfma_f32_16x16x32_bf16 v[32:35], v[176:179], v[194:197], 0
	v_mfma_f32_16x16x32_bf16 v[20:23], v[168:171], v[208:211], 0
	v_mfma_f32_16x16x32_bf16 v[0:3], v[176:179], v[216:219], 0
	v_mfma_f32_16x16x32_bf16 v[36:39], v[168:171], v[194:197], 0
	v_mfma_f32_16x16x32_bf16 v[48:51], v[176:179], v[186:189], 0
	v_mfma_f32_16x16x32_bf16 v[4:7], v[168:171], v[216:219], 0
	v_mfma_f32_16x16x32_bf16 v[16:19], v[176:179], v[208:211], 0
	v_mfma_f32_16x16x32_bf16 v[52:55], v[172:175], v[190:193], v[52:55]
	v_mfma_f32_16x16x32_bf16 v[32:35], v[182:185], v[198:201], v[32:35]
	v_mfma_f32_16x16x32_bf16 v[20:23], v[172:175], v[212:215], v[20:23]
	v_mfma_f32_16x16x32_bf16 v[0:3], v[182:185], v[220:223], v[0:3]
	v_mfma_f32_16x16x32_bf16 v[36:39], v[172:175], v[198:201], v[36:39]
	v_mfma_f32_16x16x32_bf16 v[48:51], v[182:185], v[190:193], v[48:51]
	v_lshl_add_u64 v[228:229], s[58:59], 0, v[130:131]
	s_mov_b32 m0, s53
	s_nop 0
	global_load_lds_dwordx4 v[228:229], off
	v_mfma_f32_16x16x32_bf16 v[4:7], v[172:175], v[220:223], v[4:7]
	v_mfma_f32_16x16x32_bf16 v[16:19], v[182:185], v[212:215], v[16:19]
	s_setprio 0
	s_barrier
	s_add_i32 s3, 0, 0x18000
	v_add_u32_e32 v159, s3, v153
	s_add_i32 s33, 0, 0x1c000
	ds_read_b128 v[144:147], v159
	ds_read_b128 v[148:151], v159 offset:1024
	ds_read_b128 v[160:163], v159 offset:2048
	ds_read_b128 v[164:167], v159 offset:3072
	v_add_u32_e32 v159, s33, v153
	ds_read_b128 v[168:171], v159
	ds_read_b128 v[172:175], v159 offset:1024
	ds_read_b128 v[176:179], v159 offset:2048
	ds_read_b128 v[182:185], v159 offset:3072
	s_add_u32 s58, s58, 0x40000
	s_addc_u32 s59, s59, 0
	s_mov_b32 m0, s60
	v_lshl_add_u64 v[230:231], s[58:59], 0, v[134:135]
	ds_read_b128 v[186:189], v157 offset:32768
	ds_read_b128 v[190:193], v157 offset:33792
	ds_read_b128 v[194:197], v157 offset:34816
	ds_read_b128 v[198:201], v157 offset:35840
	ds_read_b128 v[208:211], v157 offset:36864
	ds_read_b128 v[212:215], v157 offset:37888
	ds_read_b128 v[216:219], v157 offset:38912
	ds_read_b128 v[220:223], v157 offset:39936
	global_load_lds_dwordx4 v[230:231], off
	v_lshl_add_u64 v[230:231], s[58:59], 0, v[130:131]
	s_mov_b32 m0, s61
	s_nop 0
	global_load_lds_dwordx4 v[230:231], off
	s_waitcnt vmcnt(8)
	s_waitcnt lgkmcnt(0)
	s_barrier
	s_setprio 1
	s_waitcnt lgkmcnt(0)
	v_mfma_f32_16x16x32_bf16 v[124:127], v[144:147], v[186:189], v[124:127]
	v_mfma_f32_16x16x32_bf16 v[104:107], v[160:163], v[194:197], v[104:107]
	v_mfma_f32_16x16x32_bf16 v[92:95], v[144:147], v[208:211], v[92:95]
	v_mfma_f32_16x16x32_bf16 v[72:75], v[160:163], v[216:219], v[72:75]
	v_mfma_f32_16x16x32_bf16 v[108:111], v[144:147], v[194:197], v[108:111]
	v_mfma_f32_16x16x32_bf16 v[120:123], v[160:163], v[186:189], v[120:123]
	v_mfma_f32_16x16x32_bf16 v[76:79], v[144:147], v[216:219], v[76:79]
	v_mfma_f32_16x16x32_bf16 v[88:91], v[160:163], v[208:211], v[88:91]
	v_mfma_f32_16x16x32_bf16 v[124:127], v[148:151], v[190:193], v[124:127]
	v_mfma_f32_16x16x32_bf16 v[104:107], v[164:167], v[198:201], v[104:107]
	v_mfma_f32_16x16x32_bf16 v[92:95], v[148:151], v[212:215], v[92:95]
	v_mfma_f32_16x16x32_bf16 v[72:75], v[164:167], v[220:223], v[72:75]
	v_mfma_f32_16x16x32_bf16 v[108:111], v[148:151], v[198:201], v[108:111]
	v_mfma_f32_16x16x32_bf16 v[120:123], v[164:167], v[190:193], v[120:123]
	v_mfma_f32_16x16x32_bf16 v[76:79], v[148:151], v[220:223], v[76:79]
	v_mfma_f32_16x16x32_bf16 v[88:91], v[164:167], v[212:215], v[88:91]
	s_setprio 0
	s_setprio 1
	v_mfma_f32_16x16x32_bf16 v[116:119], v[168:171], v[186:189], v[116:119]
	v_mfma_f32_16x16x32_bf16 v[96:99], v[176:179], v[194:197], v[96:99]
	v_mfma_f32_16x16x32_bf16 v[84:87], v[168:171], v[208:211], v[84:87]
	v_mfma_f32_16x16x32_bf16 v[64:67], v[176:179], v[216:219], v[64:67]
	v_mfma_f32_16x16x32_bf16 v[100:103], v[168:171], v[194:197], v[100:103]
	v_mfma_f32_16x16x32_bf16 v[112:115], v[176:179], v[186:189], v[112:115]
	v_mfma_f32_16x16x32_bf16 v[68:71], v[168:171], v[216:219], v[68:71]
	v_mfma_f32_16x16x32_bf16 v[80:83], v[176:179], v[208:211], v[80:83]
	v_mfma_f32_16x16x32_bf16 v[116:119], v[172:175], v[190:193], v[116:119]
	v_mfma_f32_16x16x32_bf16 v[96:99], v[182:185], v[198:201], v[96:99]
	v_mfma_f32_16x16x32_bf16 v[84:87], v[172:175], v[212:215], v[84:87]
	v_mfma_f32_16x16x32_bf16 v[64:67], v[182:185], v[220:223], v[64:67]
	v_mfma_f32_16x16x32_bf16 v[100:103], v[172:175], v[198:201], v[100:103]
	v_mfma_f32_16x16x32_bf16 v[112:115], v[182:185], v[190:193], v[112:115]
	v_mfma_f32_16x16x32_bf16 v[68:71], v[172:175], v[220:223], v[68:71]
	v_mfma_f32_16x16x32_bf16 v[80:83], v[182:185], v[212:215], v[80:83]
	s_setprio 0
	s_barrier
; #define PG8_STAGE(bufoff, gbase, voff) do { _Pragma("unroll") for (int _i = 0; _i < 2; ++_i) \
;         __builtin_amdgcn_global_load_lds((const unsigned*)((const char*)(gbase) + (voff)[_i]), (PG8_LAS unsigned*)(lds + (bufoff) + ldsw + _i * 8192), 16, 0, 0); } while (0)
; #define PG8_LDA(dst, b, h) do { _Pragma("unroll") for (int m = 0; m < 4; ++m) _Pragma("unroll") for (int k = 0; k < 2; ++k) dst[m][k] = *(const PG8_LAS bf16x8*)(lds + PG8_SA(b, h) + aoff + m * 2048 + k * 1024); } while (0)
; #define PG8_LDB(dst, b, h) do { _Pragma("unroll") for (int n = 0; n < 2; ++n) _Pragma("unroll") for (int k = 0; k < 2; ++k) dst[n][k] = *(const PG8_LAS bf16x8*)(lds + PG8_SB(b, h) + boff + n * 2048 + k * 1024); } while (0)
; template <class Epi, class Sched, bool ALIGN_EPI = false, bool SP2 = false>
; __device__ __forceinline__ void gemm_phase(PG8_LAS unsigned char* lds, const Gemm g, const Sched& S, const Epi& E) {
;     ...
;         for (int t = 0; t < nt; t += 2) {
;             const bool last = (t == nt - 2);
;             const char* a1 = cA + (size_t)(t + 1) * kstep;
;             const char* a2 = last ? nA : cA + (size_t)(t + 2) * kstep; const char* b2 = last ? nB : cB + (size_t)(t + 2) * kstep;
;             const char* a3 = a2 + kstep; const char* b3 = b2 + kstep;
;             if (last && has_next) S.a_ready(nxt);
;             if constexpr (SP2) {
;             PG8_LDB(B0, 0, 0); PG8_LDB(B1, 0, 1); PG8_SCHED; PG8_LDA(At, 0, 0); PG8_STAGE(PG8_SA(1, 1), a1 + hstep, voffA);
;             PG8_WAIT_V(8); PG8_WAIT_L(0); PG8_BAR; PG8_MMA(0, 0, At, B0); PG8_MMA(0, 1, At, B1); PG8_BAR; PG8_SCHED;
;             PG8_LDA(At, 0, 1); PG8_STAGE(PG8_SB(0, 0), b2, voffB); PG8_STAGE(PG8_SB(0, 1), b2 + hstep, voffB); PG8_STAGE(PG8_SA(0, 0), a2, voffA);
;             PG8_WAIT_V(8); PG8_WAIT_L(0); PG8_BAR; PG8_MMA(1, 0, At, B0); PG8_MMA(1, 1, At, B1); PG8_BAR; PG8_SCHED;
;             PG8_LDB(B0, 1, 0); PG8_LDB(B1, 1, 1); PG8_SCHED; PG8_LDA(At, 1, 0); PG8_STAGE(PG8_SA(0, 1), a2 + hstep, voffA);
;             PG8_WAIT_V(8); PG8_WAIT_L(0); PG8_BAR; PG8_MMA(0, 0, At, B0); PG8_MMA(0, 1, At, B1); PG8_BAR; PG8_SCHED;
;             PG8_LDA(At, 1, 1); PG8_STAGE(PG8_SB(1, 0), b3, voffB); PG8_STAGE(PG8_SB(1, 1), b3 + hstep, voffB); PG8_STAGE(PG8_SA(1, 0), a3, voffA);
;             PG8_WAIT_V(8); PG8_WAIT_L(0); PG8_BAR; PG8_MMA(1, 0, At, B0); PG8_MMA(1, 1, At, B1); PG8_BAR; PG8_SCHED;
	s_add_i32 s3, s3, s14
	v_lshl_add_u64 v[202:203], v[202:203], 0, s[36:37]
	s_mov_b32 m0, s3
	ds_read_b128 v[186:189], v157 offset:49152
	ds_read_b128 v[190:193], v157 offset:50176
	ds_read_b128 v[194:197], v157 offset:51200
	ds_read_b128 v[198:201], v157 offset:52224
	ds_read_b128 v[208:211], v157 offset:53248
	ds_read_b128 v[212:215], v157 offset:54272
	ds_read_b128 v[216:219], v157 offset:55296
	ds_read_b128 v[220:223], v157 offset:56320
	global_load_lds_dwordx4 v[202:203], off
	s_add_i32 m0, s3, 0x2000
	s_add_u32 s56, s56, 0x40080
	v_lshl_add_u64 v[202:203], v[224:225], 0, s[36:37]
	s_addc_u32 s57, s57, 0
	s_add_i32 s3, s33, s14
	global_load_lds_dwordx4 v[202:203], off
	v_lshl_add_u64 v[202:203], s[56:57], 0, v[132:133]
	s_mov_b32 m0, s3
	s_nop 0
	global_load_lds_dwordx4 v[202:203], off
	v_lshl_add_u64 v[202:203], s[56:57], 0, v[128:129]
	s_add_i32 m0, s3, 0x2000
	s_nop 0
	global_load_lds_dwordx4 v[202:203], off
	s_waitcnt vmcnt(6)
	s_waitcnt lgkmcnt(0)
	s_barrier
	s_setprio 1
	s_waitcnt lgkmcnt(0)
	v_mfma_f32_16x16x32_bf16 v[60:63], v[144:147], v[186:189], v[60:63]
	v_mfma_f32_16x16x32_bf16 v[40:43], v[160:163], v[194:197], v[40:43]
	v_mfma_f32_16x16x32_bf16 v[28:31], v[144:147], v[208:211], v[28:31]
	v_mfma_f32_16x16x32_bf16 v[8:11], v[160:163], v[216:219], v[8:11]
	v_mfma_f32_16x16x32_bf16 v[44:47], v[144:147], v[194:197], v[44:47]
	v_mfma_f32_16x16x32_bf16 v[56:59], v[160:163], v[186:189], v[56:59]
	v_mfma_f32_16x16x32_bf16 v[12:15], v[144:147], v[216:219], v[12:15]
	v_mfma_f32_16x16x32_bf16 v[24:27], v[160:163], v[208:211], v[24:27]
	v_mfma_f32_16x16x32_bf16 v[60:63], v[148:151], v[190:193], v[60:63]
	v_mfma_f32_16x16x32_bf16 v[40:43], v[164:167], v[198:201], v[40:43]
	v_mfma_f32_16x16x32_bf16 v[28:31], v[148:151], v[212:215], v[28:31]
	v_mfma_f32_16x16x32_bf16 v[8:11], v[164:167], v[220:223], v[8:11]
	v_mfma_f32_16x16x32_bf16 v[44:47], v[148:151], v[198:201], v[44:47]
	v_mfma_f32_16x16x32_bf16 v[56:59], v[164:167], v[190:193], v[56:59]
	v_lshl_add_u64 v[202:203], v[226:227], 0, s[36:37]
	s_mov_b32 m0, s63
	s_nop 0
	global_load_lds_dwordx4 v[202:203], off
	v_mfma_f32_16x16x32_bf16 v[12:15], v[148:151], v[220:223], v[12:15]
	v_mfma_f32_16x16x32_bf16 v[24:27], v[164:167], v[212:215], v[24:27]
	s_setprio 0
	s_setprio 1
	v_mfma_f32_16x16x32_bf16 v[52:55], v[168:171], v[186:189], v[52:55]
	v_mfma_f32_16x16x32_bf16 v[32:35], v[176:179], v[194:197], v[32:35]
	v_mfma_f32_16x16x32_bf16 v[20:23], v[168:171], v[208:211], v[20:23]
	v_mfma_f32_16x16x32_bf16 v[0:3], v[176:179], v[216:219], v[0:3]
	v_mfma_f32_16x16x32_bf16 v[36:39], v[168:171], v[194:197], v[36:39]
	v_mfma_f32_16x16x32_bf16 v[48:51], v[176:179], v[186:189], v[48:51]
	v_mfma_f32_16x16x32_bf16 v[4:7], v[168:171], v[216:219], v[4:7]
	v_mfma_f32_16x16x32_bf16 v[16:19], v[176:179], v[208:211], v[16:19]
	v_mfma_f32_16x16x32_bf16 v[52:55], v[172:175], v[190:193], v[52:55]
	v_mfma_f32_16x16x32_bf16 v[32:35], v[182:185], v[198:201], v[32:35]
	v_mfma_f32_16x16x32_bf16 v[20:23], v[172:175], v[212:215], v[20:23]
	v_mfma_f32_16x16x32_bf16 v[0:3], v[182:185], v[220:223], v[0:3]
	v_mfma_f32_16x16x32_bf16 v[36:39], v[172:175], v[198:201], v[36:39]
	v_mfma_f32_16x16x32_bf16 v[48:51], v[182:185], v[190:193], v[48:51]
	v_lshl_add_u64 v[202:203], v[228:229], 0, s[36:37]
	s_mov_b32 m0, s64
	s_nop 0
	global_load_lds_dwordx4 v[202:203], off
	v_mfma_f32_16x16x32_bf16 v[4:7], v[172:175], v[220:223], v[4:7]
	v_mfma_f32_16x16x32_bf16 v[16:19], v[182:185], v[212:215], v[16:19]
	s_setprio 0
	s_barrier
	s_add_i32 s83, s83, 2
	s_add_u32 s54, s54, 0x100
	s_addc_u32 s55, s55, 0
	s_add_u32 s77, s77, 0x100
	s_addc_u32 s82, s82, 0
.LBB0_957:
	ds_read_b128 v[144:147], v155
	ds_read_b128 v[148:151], v155 offset:1024
	ds_read_b128 v[160:163], v155 offset:2048
	ds_read_b128 v[164:167], v155 offset:3072
	ds_read_b128 v[168:171], v156
	ds_read_b128 v[172:175], v156 offset:1024
	ds_read_b128 v[176:179], v156 offset:2048
	ds_read_b128 v[182:185], v156 offset:3072
	s_add_u32 s3, s54, 0xfffc0080
	s_addc_u32 s33, s55, -1
	s_cmp_eq_u32 s83, 12
	s_cselect_b32 s59, s45, s33
	s_cselect_b32 s58, s75, s3
	s_cselect_b32 s57, s43, s82
	s_cselect_b32 s56, s76, s77
	v_lshl_add_u64 v[202:203], s[54:55], 0, v[136:137]
	s_add_i32 m0, s34, 0xc000
	ds_read_b128 v[186:189], v157
	ds_read_b128 v[190:193], v157 offset:1024
	ds_read_b128 v[194:197], v157 offset:2048
	ds_read_b128 v[198:201], v157 offset:3072
	ds_read_b128 v[208:211], v157 offset:4096
	ds_read_b128 v[212:215], v157 offset:5120
	ds_read_b128 v[216:219], v157 offset:6144
	ds_read_b128 v[220:223], v157 offset:7168
	global_load_lds_dwordx4 v[202:203], off
	v_lshl_add_u64 v[202:203], s[54:55], 0, v[138:139]
	s_add_i32 m0, s34, 0xe000
	s_nop 0
	global_load_lds_dwordx4 v[202:203], off
	s_waitcnt vmcnt(8)
	s_waitcnt lgkmcnt(0)
	s_barrier
; #define PG8_STAGE(bufoff, gbase, voff) do { _Pragma("unroll") for (int _i = 0; _i < 2; ++_i) \
;         __builtin_amdgcn_global_load_lds((const unsigned*)((const char*)(gbase) + (voff)[_i]), (PG8_LAS unsigned*)(lds + (bufoff) + ldsw + _i * 8192), 16, 0, 0); } while (0)
; #define PG8_LDA(dst, b, h) do { _Pragma("unroll") for (int m = 0; m < 4; ++m) _Pragma("unroll") for (int k = 0; k < 2; ++k) dst[m][k] = *(const PG8_LAS bf16x8*)(lds + PG8_SA(b, h) + aoff + m * 2048 + k * 1024); } while (0)
; #define PG8_LDB(dst, b, h) do { _Pragma("unroll") for (int n = 0; n < 2; ++n) _Pragma("unroll") for (int k = 0; k < 2; ++k) dst[n][k] = *(const PG8_LAS bf16x8*)(lds + PG8_SB(b, h) + boff + n * 2048 + k * 1024); } while (0)
; #define PG8_MMA(ai, bj, At, Bt) do { __builtin_amdgcn_s_setprio(1); _Pragma("unroll") for (int m = 0; m < 4; ++m) _Pragma("unroll") for (int n = 0; n < 2; ++n) _Pragma("unroll") for (int k = 0; k < 2; ++k) \
;         acc[ai][bj][m][n] = __builtin_amdgcn_mfma_f32_16x16x32_bf16(Bt[n][k], At[m][k], acc[ai][bj][m][n], 0, 0, 0); __builtin_amdgcn_s_setprio(0); } while (0)
; #define PG8_WAIT_V(n) asm volatile("s_waitcnt vmcnt(" #n ")" ::: "memory")
; template <class Epi, class Sched, bool ALIGN_EPI = false, bool SP2 = false>
; __device__ __forceinline__ void gemm_phase(PG8_LAS unsigned char* lds, const Gemm g, const Sched& S, const Epi& E) {
;     ...
;             PG8_LDB(B0, 0, 0); PG8_LDB(B1, 0, 1); PG8_SCHED; PG8_LDA(At, 0, 0); PG8_STAGE(PG8_SA(1, 1), a1 + hstep, voffA);
;             PG8_WAIT_V(8); PG8_WAIT_L(0); PG8_BAR; PG8_MMA(0, 0, At, B0); PG8_MMA(0, 1, At, B1); PG8_BAR; PG8_SCHED;
;             PG8_LDA(At, 0, 1); PG8_STAGE(PG8_SB(0, 0), b2, voffB); PG8_STAGE(PG8_SB(0, 1), b2 + hstep, voffB); PG8_STAGE(PG8_SA(0, 0), a2, voffA);
;             PG8_WAIT_V(8); PG8_WAIT_L(0); PG8_BAR; PG8_MMA(1, 0, At, B0); PG8_MMA(1, 1, At, B1); PG8_BAR; PG8_SCHED;
;             PG8_LDB(B0, 1, 0); PG8_LDB(B1, 1, 1); PG8_SCHED; PG8_LDA(At, 1, 0); PG8_STAGE(PG8_SA(0, 1), a2 + hstep, voffA);
;             PG8_WAIT_V(8); PG8_WAIT_L(0); PG8_BAR; PG8_MMA(0, 0, At, B0); PG8_MMA(0, 1, At, B1); PG8_BAR; PG8_SCHED;
;             PG8_LDA(At, 1, 1); PG8_STAGE(PG8_SB(1, 0), b3, voffB); PG8_STAGE(PG8_SB(1, 1), b3 + hstep, voffB); PG8_STAGE(PG8_SA(1, 0), a3, voffA);
;             PG8_WAIT_V(8); PG8_WAIT_L(0); PG8_BAR; PG8_MMA(1, 0, At, B0); PG8_MMA(1, 1, At, B1); PG8_BAR; PG8_SCHED;
	s_setprio 1
	s_waitcnt lgkmcnt(0)
	v_mfma_f32_16x16x32_bf16 v[124:127], v[144:147], v[186:189], v[124:127]
	v_mfma_f32_16x16x32_bf16 v[104:107], v[160:163], v[194:197], v[104:107]
	v_mfma_f32_16x16x32_bf16 v[92:95], v[144:147], v[208:211], v[92:95]
	v_mfma_f32_16x16x32_bf16 v[72:75], v[160:163], v[216:219], v[72:75]
	v_mfma_f32_16x16x32_bf16 v[108:111], v[144:147], v[194:197], v[108:111]
	v_mfma_f32_16x16x32_bf16 v[120:123], v[160:163], v[186:189], v[120:123]
	v_mfma_f32_16x16x32_bf16 v[76:79], v[144:147], v[216:219], v[76:79]
	v_mfma_f32_16x16x32_bf16 v[88:91], v[160:163], v[208:211], v[88:91]
	v_mfma_f32_16x16x32_bf16 v[124:127], v[148:151], v[190:193], v[124:127]
	v_mfma_f32_16x16x32_bf16 v[104:107], v[164:167], v[198:201], v[104:107]
	v_mfma_f32_16x16x32_bf16 v[92:95], v[148:151], v[212:215], v[92:95]
	v_mfma_f32_16x16x32_bf16 v[72:75], v[164:167], v[220:223], v[72:75]
	v_mfma_f32_16x16x32_bf16 v[108:111], v[148:151], v[198:201], v[108:111]
	v_mfma_f32_16x16x32_bf16 v[120:123], v[164:167], v[190:193], v[120:123]
	v_mfma_f32_16x16x32_bf16 v[76:79], v[148:151], v[220:223], v[76:79]
	v_mfma_f32_16x16x32_bf16 v[88:91], v[164:167], v[212:215], v[88:91]
	s_setprio 0
	s_setprio 1
	v_mfma_f32_16x16x32_bf16 v[116:119], v[168:171], v[186:189], v[116:119]
	v_mfma_f32_16x16x32_bf16 v[96:99], v[176:179], v[194:197], v[96:99]
	v_mfma_f32_16x16x32_bf16 v[84:87], v[168:171], v[208:211], v[84:87]
	v_mfma_f32_16x16x32_bf16 v[64:67], v[176:179], v[216:219], v[64:67]
	v_mfma_f32_16x16x32_bf16 v[100:103], v[168:171], v[194:197], v[100:103]
	v_mfma_f32_16x16x32_bf16 v[112:115], v[176:179], v[186:189], v[112:115]
	v_mfma_f32_16x16x32_bf16 v[68:71], v[168:171], v[216:219], v[68:71]
	v_mfma_f32_16x16x32_bf16 v[80:83], v[176:179], v[208:211], v[80:83]
	v_mfma_f32_16x16x32_bf16 v[116:119], v[172:175], v[190:193], v[116:119]
	v_mfma_f32_16x16x32_bf16 v[96:99], v[182:185], v[198:201], v[96:99]
	v_mfma_f32_16x16x32_bf16 v[84:87], v[172:175], v[212:215], v[84:87]
	v_mfma_f32_16x16x32_bf16 v[64:67], v[182:185], v[220:223], v[64:67]
	v_mfma_f32_16x16x32_bf16 v[100:103], v[172:175], v[198:201], v[100:103]
	v_mfma_f32_16x16x32_bf16 v[112:115], v[182:185], v[190:193], v[112:115]
	v_mfma_f32_16x16x32_bf16 v[68:71], v[172:175], v[220:223], v[68:71]
	v_mfma_f32_16x16x32_bf16 v[80:83], v[182:185], v[212:215], v[80:83]
	s_setprio 0
	s_barrier
	s_add_i32 s3, s65, s14
	v_lshl_add_u64 v[202:203], s[56:57], 0, v[132:133]
	s_mov_b32 m0, s3
	ds_read_b128 v[186:189], v157 offset:16384
	ds_read_b128 v[190:193], v157 offset:17408
	ds_read_b128 v[194:197], v157 offset:18432
	ds_read_b128 v[198:201], v157 offset:19456
	ds_read_b128 v[208:211], v157 offset:20480
	ds_read_b128 v[212:215], v157 offset:21504
	ds_read_b128 v[216:219], v157 offset:22528
	ds_read_b128 v[220:223], v157 offset:23552
	global_load_lds_dwordx4 v[202:203], off
	s_add_i32 m0, s3, 0x2000
	s_add_u32 s78, s56, 0x40000
	v_lshl_add_u64 v[224:225], s[56:57], 0, v[128:129]
	s_addc_u32 s79, s57, 0
	s_add_i32 s3, s66, s14
	global_load_lds_dwordx4 v[224:225], off
	v_lshl_add_u64 v[226:227], s[78:79], 0, v[132:133]
	s_mov_b32 m0, s3
	global_load_lds_dwordx4 v[226:227], off
	v_lshl_add_u64 v[226:227], s[78:79], 0, v[128:129]
	s_add_i32 m0, s3, 0x2000
	s_nop 0
	global_load_lds_dwordx4 v[226:227], off
	s_waitcnt vmcnt(6)
	s_waitcnt lgkmcnt(0)
	s_barrier
	s_setprio 1
	s_waitcnt lgkmcnt(0)
	v_mfma_f32_16x16x32_bf16 v[60:63], v[144:147], v[186:189], v[60:63]
	v_mfma_f32_16x16x32_bf16 v[40:43], v[160:163], v[194:197], v[40:43]
	v_mfma_f32_16x16x32_bf16 v[28:31], v[144:147], v[208:211], v[28:31]
	v_mfma_f32_16x16x32_bf16 v[8:11], v[160:163], v[216:219], v[8:11]
	v_mfma_f32_16x16x32_bf16 v[44:47], v[144:147], v[194:197], v[44:47]
	v_mfma_f32_16x16x32_bf16 v[56:59], v[160:163], v[186:189], v[56:59]
	v_mfma_f32_16x16x32_bf16 v[12:15], v[144:147], v[216:219], v[12:15]
	v_mfma_f32_16x16x32_bf16 v[24:27], v[160:163], v[208:211], v[24:27]
	v_mfma_f32_16x16x32_bf16 v[60:63], v[148:151], v[190:193], v[60:63]
	v_mfma_f32_16x16x32_bf16 v[40:43], v[164:167], v[198:201], v[40:43]
	v_mfma_f32_16x16x32_bf16 v[28:31], v[148:151], v[212:215], v[28:31]
	v_mfma_f32_16x16x32_bf16 v[8:11], v[164:167], v[220:223], v[8:11]
	v_mfma_f32_16x16x32_bf16 v[44:47], v[148:151], v[198:201], v[44:47]
	v_mfma_f32_16x16x32_bf16 v[56:59], v[164:167], v[190:193], v[56:59]
	v_lshl_add_u64 v[226:227], s[58:59], 0, v[134:135]
	s_mov_b32 m0, s34
	s_nop 0
	global_load_lds_dwordx4 v[226:227], off
	v_mfma_f32_16x16x32_bf16 v[12:15], v[148:151], v[220:223], v[12:15]
	v_mfma_f32_16x16x32_bf16 v[24:27], v[164:167], v[212:215], v[24:27]
	s_setprio 0
	s_setprio 1
	v_mfma_f32_16x16x32_bf16 v[52:55], v[168:171], v[186:189], v[52:55]
	v_mfma_f32_16x16x32_bf16 v[32:35], v[176:179], v[194:197], v[32:35]
	v_mfma_f32_16x16x32_bf16 v[20:23], v[168:171], v[208:211], v[20:23]
	v_mfma_f32_16x16x32_bf16 v[0:3], v[176:179], v[216:219], v[0:3]
	v_mfma_f32_16x16x32_bf16 v[36:39], v[168:171], v[194:197], v[36:39]
	v_mfma_f32_16x16x32_bf16 v[48:51], v[176:179], v[186:189], v[48:51]
	v_mfma_f32_16x16x32_bf16 v[4:7], v[168:171], v[216:219], v[4:7]
	v_mfma_f32_16x16x32_bf16 v[16:19], v[176:179], v[208:211], v[16:19]
	v_mfma_f32_16x16x32_bf16 v[52:55], v[172:175], v[190:193], v[52:55]
	v_mfma_f32_16x16x32_bf16 v[32:35], v[182:185], v[198:201], v[32:35]
	v_mfma_f32_16x16x32_bf16 v[20:23], v[172:175], v[212:215], v[20:23]
	v_mfma_f32_16x16x32_bf16 v[0:3], v[182:185], v[220:223], v[0:3]
	v_mfma_f32_16x16x32_bf16 v[36:39], v[172:175], v[198:201], v[36:39]
	v_mfma_f32_16x16x32_bf16 v[48:51], v[182:185], v[190:193], v[48:51]
	v_lshl_add_u64 v[228:229], s[58:59], 0, v[130:131]
	s_mov_b32 m0, s53
	s_nop 0
	global_load_lds_dwordx4 v[228:229], off
	v_mfma_f32_16x16x32_bf16 v[4:7], v[172:175], v[220:223], v[4:7]
	v_mfma_f32_16x16x32_bf16 v[16:19], v[182:185], v[212:215], v[16:19]
	s_setprio 0
	s_barrier
; #define PG8_STAGE(bufoff, gbase, voff) do { _Pragma("unroll") for (int _i = 0; _i < 2; ++_i) \
;         __builtin_amdgcn_global_load_lds((const unsigned*)((const char*)(gbase) + (voff)[_i]), (PG8_LAS unsigned*)(lds + (bufoff) + ldsw + _i * 8192), 16, 0, 0); } while (0)
; #define PG8_LDA(dst, b, h) do { _Pragma("unroll") for (int m = 0; m < 4; ++m) _Pragma("unroll") for (int k = 0; k < 2; ++k) dst[m][k] = *(const PG8_LAS bf16x8*)(lds + PG8_SA(b, h) + aoff + m * 2048 + k * 1024); } while (0)
; #define PG8_LDB(dst, b, h) do { _Pragma("unroll") for (int n = 0; n < 2; ++n) _Pragma("unroll") for (int k = 0; k < 2; ++k) dst[n][k] = *(const PG8_LAS bf16x8*)(lds + PG8_SB(b, h) + boff + n * 2048 + k * 1024); } while (0)
; #define PG8_MMA(ai, bj, At, Bt) do { __builtin_amdgcn_s_setprio(1); _Pragma("unroll") for (int m = 0; m < 4; ++m) _Pragma("unroll") for (int n = 0; n < 2; ++n) _Pragma("unroll") for (int k = 0; k < 2; ++k) \
;         acc[ai][bj][m][n] = __builtin_amdgcn_mfma_f32_16x16x32_bf16(Bt[n][k], At[m][k], acc[ai][bj][m][n], 0, 0, 0); __builtin_amdgcn_s_setprio(0); } while (0)
; #define PG8_WAIT_V(n) asm volatile("s_waitcnt vmcnt(" #n ")" ::: "memory")
; #define PG8_WAIT_L(n) asm volatile("s_waitcnt lgkmcnt(" #n ")" ::: "memory")
; #define PG8_BAR __builtin_amdgcn_s_barrier()
; #define PG8_SCHED __builtin_amdgcn_sched_barrier(0)
; template <class Epi, class Sched, bool ALIGN_EPI = false, bool SP2 = false>
; __device__ __forceinline__ void gemm_phase(PG8_LAS unsigned char* lds, const Gemm g, const Sched& S, const Epi& E) {
;     ...
;             PG8_LDB(B0, 1, 0); PG8_LDB(B1, 1, 1); PG8_SCHED; PG8_LDA(At, 1, 0); PG8_STAGE(PG8_SA(0, 1), a2 + hstep, voffA);
;             PG8_WAIT_V(8); PG8_WAIT_L(0); PG8_BAR; PG8_MMA(0, 0, At, B0); PG8_MMA(0, 1, At, B1); PG8_BAR; PG8_SCHED;
	s_add_i32 s3, 0, 0x18000
	v_add_u32_e32 v159, s3, v153
	s_add_i32 s33, 0, 0x1c000
	ds_read_b128 v[144:147], v159
	ds_read_b128 v[148:151], v159 offset:1024
	ds_read_b128 v[160:163], v159 offset:2048
	ds_read_b128 v[164:167], v159 offset:3072
	v_add_u32_e32 v159, s33, v153
	ds_read_b128 v[168:171], v159
	ds_read_b128 v[172:175], v159 offset:1024
	ds_read_b128 v[176:179], v159 offset:2048
	ds_read_b128 v[182:185], v159 offset:3072
	s_add_u32 s58, s58, 0x40000
	s_addc_u32 s59, s59, 0
	s_mov_b32 m0, s60
	v_lshl_add_u64 v[230:231], s[58:59], 0, v[134:135]
	ds_read_b128 v[186:189], v157 offset:32768
	ds_read_b128 v[190:193], v157 offset:33792
	ds_read_b128 v[194:197], v157 offset:34816
	ds_read_b128 v[198:201], v157 offset:35840
	ds_read_b128 v[208:211], v157 offset:36864
	ds_read_b128 v[212:215], v157 offset:37888
	ds_read_b128 v[216:219], v157 offset:38912
	ds_read_b128 v[220:223], v157 offset:39936
	global_load_lds_dwordx4 v[230:231], off
	v_lshl_add_u64 v[230:231], s[58:59], 0, v[130:131]
	s_mov_b32 m0, s61
	s_nop 0
	global_load_lds_dwordx4 v[230:231], off
	s_waitcnt vmcnt(8)
	s_waitcnt lgkmcnt(0)
	s_barrier
	s_setprio 1
	s_waitcnt lgkmcnt(0)
	v_mfma_f32_16x16x32_bf16 v[124:127], v[144:147], v[186:189], v[124:127]
	v_mfma_f32_16x16x32_bf16 v[104:107], v[160:163], v[194:197], v[104:107]
	v_mfma_f32_16x16x32_bf16 v[92:95], v[144:147], v[208:211], v[92:95]
	v_mfma_f32_16x16x32_bf16 v[72:75], v[160:163], v[216:219], v[72:75]
	v_mfma_f32_16x16x32_bf16 v[108:111], v[144:147], v[194:197], v[108:111]
	v_mfma_f32_16x16x32_bf16 v[120:123], v[160:163], v[186:189], v[120:123]
	v_mfma_f32_16x16x32_bf16 v[76:79], v[144:147], v[216:219], v[76:79]
	v_mfma_f32_16x16x32_bf16 v[88:91], v[160:163], v[208:211], v[88:91]
	v_mfma_f32_16x16x32_bf16 v[124:127], v[148:151], v[190:193], v[124:127]
	v_mfma_f32_16x16x32_bf16 v[104:107], v[164:167], v[198:201], v[104:107]
	v_mfma_f32_16x16x32_bf16 v[92:95], v[148:151], v[212:215], v[92:95]
	v_mfma_f32_16x16x32_bf16 v[72:75], v[164:167], v[220:223], v[72:75]
	v_mfma_f32_16x16x32_bf16 v[108:111], v[148:151], v[198:201], v[108:111]
	v_mfma_f32_16x16x32_bf16 v[120:123], v[164:167], v[190:193], v[120:123]
	v_mfma_f32_16x16x32_bf16 v[76:79], v[148:151], v[220:223], v[76:79]
	v_mfma_f32_16x16x32_bf16 v[88:91], v[164:167], v[212:215], v[88:91]
	s_setprio 0
	s_setprio 1
	v_mfma_f32_16x16x32_bf16 v[116:119], v[168:171], v[186:189], v[116:119]
	v_mfma_f32_16x16x32_bf16 v[96:99], v[176:179], v[194:197], v[96:99]
	v_mfma_f32_16x16x32_bf16 v[84:87], v[168:171], v[208:211], v[84:87]
	v_mfma_f32_16x16x32_bf16 v[64:67], v[176:179], v[216:219], v[64:67]
	v_mfma_f32_16x16x32_bf16 v[100:103], v[168:171], v[194:197], v[100:103]
	v_mfma_f32_16x16x32_bf16 v[112:115], v[176:179], v[186:189], v[112:115]
	v_mfma_f32_16x16x32_bf16 v[68:71], v[168:171], v[216:219], v[68:71]
	v_mfma_f32_16x16x32_bf16 v[80:83], v[176:179], v[208:211], v[80:83]
	v_mfma_f32_16x16x32_bf16 v[116:119], v[172:175], v[190:193], v[116:119]
	v_mfma_f32_16x16x32_bf16 v[96:99], v[182:185], v[198:201], v[96:99]
	v_mfma_f32_16x16x32_bf16 v[84:87], v[172:175], v[212:215], v[84:87]
	v_mfma_f32_16x16x32_bf16 v[64:67], v[182:185], v[220:223], v[64:67]
	v_mfma_f32_16x16x32_bf16 v[100:103], v[172:175], v[198:201], v[100:103]
	v_mfma_f32_16x16x32_bf16 v[112:115], v[182:185], v[190:193], v[112:115]
	v_mfma_f32_16x16x32_bf16 v[68:71], v[172:175], v[220:223], v[68:71]
	v_mfma_f32_16x16x32_bf16 v[80:83], v[182:185], v[212:215], v[80:83]
	s_setprio 0
	s_barrier
; #define PG8_STAGE(bufoff, gbase, voff) do { _Pragma("unroll") for (int _i = 0; _i < 2; ++_i) \
;         __builtin_amdgcn_global_load_lds((const unsigned*)((const char*)(gbase) + (voff)[_i]), (PG8_LAS unsigned*)(lds + (bufoff) + ldsw + _i * 8192), 16, 0, 0); } while (0)
; #define PG8_WAIT_V(n) asm volatile("s_waitcnt vmcnt(" #n ")" ::: "memory")
; #define PG8_WAIT_L(n) asm volatile("s_waitcnt lgkmcnt(" #n ")" ::: "memory")
; #define PG8_BAR __builtin_amdgcn_s_barrier()
; __device__ __forceinline__ float row_rs(const float* ssp, int row) { const unsigned long long v = ((const unsigned long long*)ssp)[row];
;     return __builtin_amdgcn_rsqf((float)v * (1.0f / 4294967296.0f) * (1.0f / 1024.0f) + RMS_EPS); }
; template <class Epi, class Sched, bool ALIGN_EPI = false, bool SP2 = false>
; __device__ __forceinline__ void gemm_phase(PG8_LAS unsigned char* lds, const Gemm g, const Sched& S, const Epi& E) {
;     ...
;         for (int t = 0; t < nt; t += 2) {
;             const bool last = (t == nt - 2);
;             const char* a1 = cA + (size_t)(t + 1) * kstep;
;             const char* a2 = last ? nA : cA + (size_t)(t + 2) * kstep; const char* b2 = last ? nB : cB + (size_t)(t + 2) * kstep;
;             const char* a3 = a2 + kstep; const char* b3 = b2 + kstep;
;             if (last && has_next) S.a_ready(nxt);
;             if constexpr (SP2) {
;             PG8_LDB(B0, 0, 0); PG8_LDB(B1, 0, 1); PG8_SCHED; PG8_LDA(At, 0, 0); PG8_STAGE(PG8_SA(1, 1), a1 + hstep, voffA);
;             PG8_WAIT_V(8); PG8_WAIT_L(0); PG8_BAR; PG8_MMA(0, 0, At, B0); PG8_MMA(0, 1, At, B1); PG8_BAR; PG8_SCHED;
;             PG8_LDA(At, 0, 1); PG8_STAGE(PG8_SB(0, 0), b2, voffB); PG8_STAGE(PG8_SB(0, 1), b2 + hstep, voffB); PG8_STAGE(PG8_SA(0, 0), a2, voffA);
;             PG8_WAIT_V(8); PG8_WAIT_L(0); PG8_BAR; PG8_MMA(1, 0, At, B0); PG8_MMA(1, 1, At, B1); PG8_BAR; PG8_SCHED;
;             PG8_LDB(B0, 1, 0); PG8_LDB(B1, 1, 1); PG8_SCHED; PG8_LDA(At, 1, 0); PG8_STAGE(PG8_SA(0, 1), a2 + hstep, voffA);
;             PG8_WAIT_V(8); PG8_WAIT_L(0); PG8_BAR; PG8_MMA(0, 0, At, B0); PG8_MMA(0, 1, At, B1); PG8_BAR; PG8_SCHED;
;             PG8_LDA(At, 1, 1); PG8_STAGE(PG8_SB(1, 0), b3, voffB); PG8_STAGE(PG8_SB(1, 1), b3 + hstep, voffB); PG8_STAGE(PG8_SA(1, 0), a3, voffA);
;             PG8_WAIT_V(8); PG8_WAIT_L(0); PG8_BAR; PG8_MMA(1, 0, At, B0); PG8_MMA(1, 1, At, B1); PG8_BAR; PG8_SCHED;
	s_add_i32 s3, s3, s14
	v_lshl_add_u64 v[202:203], v[202:203], 0, s[36:37]
	s_mov_b32 m0, s3
	ds_read_b128 v[186:189], v157 offset:49152
	ds_read_b128 v[190:193], v157 offset:50176
	ds_read_b128 v[194:197], v157 offset:51200
	ds_read_b128 v[198:201], v157 offset:52224
	ds_read_b128 v[208:211], v157 offset:53248
	ds_read_b128 v[212:215], v157 offset:54272
	ds_read_b128 v[216:219], v157 offset:55296
	ds_read_b128 v[220:223], v157 offset:56320
	global_load_lds_dwordx4 v[202:203], off
	s_add_i32 m0, s3, 0x2000
	s_add_u32 s56, s56, 0x40080
	v_lshl_add_u64 v[202:203], v[224:225], 0, s[36:37]
	s_addc_u32 s57, s57, 0
	s_add_i32 s3, s33, s14
	global_load_lds_dwordx4 v[202:203], off
	v_lshl_add_u64 v[202:203], s[56:57], 0, v[132:133]
	s_mov_b32 m0, s3
	s_nop 0
	global_load_lds_dwordx4 v[202:203], off
	v_lshl_add_u64 v[202:203], s[56:57], 0, v[128:129]
	s_add_i32 m0, s3, 0x2000
	s_nop 0
	global_load_lds_dwordx4 v[202:203], off
	s_waitcnt vmcnt(6)
	s_waitcnt lgkmcnt(0)
	s_barrier
	s_setprio 1
	s_waitcnt lgkmcnt(0)
	v_mfma_f32_16x16x32_bf16 v[60:63], v[144:147], v[186:189], v[60:63]
	v_mfma_f32_16x16x32_bf16 v[40:43], v[160:163], v[194:197], v[40:43]
	v_mfma_f32_16x16x32_bf16 v[28:31], v[144:147], v[208:211], v[28:31]
	v_mfma_f32_16x16x32_bf16 v[8:11], v[160:163], v[216:219], v[8:11]
	v_mfma_f32_16x16x32_bf16 v[44:47], v[144:147], v[194:197], v[44:47]
	v_mfma_f32_16x16x32_bf16 v[56:59], v[160:163], v[186:189], v[56:59]
	v_mfma_f32_16x16x32_bf16 v[12:15], v[144:147], v[216:219], v[12:15]
	v_mfma_f32_16x16x32_bf16 v[24:27], v[160:163], v[208:211], v[24:27]
	v_mfma_f32_16x16x32_bf16 v[60:63], v[148:151], v[190:193], v[60:63]
	v_mfma_f32_16x16x32_bf16 v[40:43], v[164:167], v[198:201], v[40:43]
	v_mfma_f32_16x16x32_bf16 v[28:31], v[148:151], v[212:215], v[28:31]
	v_mfma_f32_16x16x32_bf16 v[8:11], v[164:167], v[220:223], v[8:11]
	v_mfma_f32_16x16x32_bf16 v[44:47], v[148:151], v[198:201], v[44:47]
	v_mfma_f32_16x16x32_bf16 v[56:59], v[164:167], v[190:193], v[56:59]
	v_lshl_add_u64 v[202:203], v[226:227], 0, s[36:37]
	s_mov_b32 m0, s63
	s_nop 0
	global_load_lds_dwordx4 v[202:203], off
	v_mfma_f32_16x16x32_bf16 v[12:15], v[148:151], v[220:223], v[12:15]
	v_mfma_f32_16x16x32_bf16 v[24:27], v[164:167], v[212:215], v[24:27]
	s_setprio 0
	s_setprio 1
	v_mfma_f32_16x16x32_bf16 v[52:55], v[168:171], v[186:189], v[52:55]
	v_mfma_f32_16x16x32_bf16 v[32:35], v[176:179], v[194:197], v[32:35]
	v_mfma_f32_16x16x32_bf16 v[20:23], v[168:171], v[208:211], v[20:23]
	v_mfma_f32_16x16x32_bf16 v[0:3], v[176:179], v[216:219], v[0:3]
	v_mfma_f32_16x16x32_bf16 v[36:39], v[168:171], v[194:197], v[36:39]
	v_mfma_f32_16x16x32_bf16 v[48:51], v[176:179], v[186:189], v[48:51]
	v_mfma_f32_16x16x32_bf16 v[4:7], v[168:171], v[216:219], v[4:7]
	v_mfma_f32_16x16x32_bf16 v[16:19], v[176:179], v[208:211], v[16:19]
	v_mfma_f32_16x16x32_bf16 v[52:55], v[172:175], v[190:193], v[52:55]
	v_mfma_f32_16x16x32_bf16 v[32:35], v[182:185], v[198:201], v[32:35]
	v_mfma_f32_16x16x32_bf16 v[20:23], v[172:175], v[212:215], v[20:23]
	v_mfma_f32_16x16x32_bf16 v[0:3], v[182:185], v[220:223], v[0:3]
	v_mfma_f32_16x16x32_bf16 v[36:39], v[172:175], v[198:201], v[36:39]
	v_mfma_f32_16x16x32_bf16 v[48:51], v[182:185], v[190:193], v[48:51]
	v_lshl_add_u64 v[202:203], v[228:229], 0, s[36:37]
	s_mov_b32 m0, s64
	s_nop 0
	global_load_lds_dwordx4 v[202:203], off
	v_mfma_f32_16x16x32_bf16 v[4:7], v[172:175], v[220:223], v[4:7]
	v_mfma_f32_16x16x32_bf16 v[16:19], v[182:185], v[212:215], v[16:19]
	s_setprio 0
	s_barrier
	s_add_i32 s83, s83, 2
	s_add_u32 s54, s54, 0x100
	s_addc_u32 s55, s55, 0
	s_add_u32 s77, s77, 0x100
	s_addc_u32 s82, s82, 0
	s_cmp_gt_u32 s83, 13
	s_cbranch_scc0 .LBB0_957
	v_lshl_add_u32 v144, s52, 8, v152
	v_ashrrev_i32_e32 v145, 31, v144
	v_lshl_add_u64 v[150:151], v[144:145], 3, s[0:1]
	global_load_dwordx2 v[182:183], v[150:151], off
	global_load_dwordx2 v[184:185], v[150:151], off offset:128
	global_load_dwordx2 v[186:187], v[150:151], off offset:256
	global_load_dwordx2 v[188:189], v[150:151], off offset:384
	global_load_dwordx2 v[190:191], v[150:151], off offset:1024
	global_load_dwordx2 v[192:193], v[150:151], off offset:1152
	global_load_dwordx2 v[194:195], v[150:151], off offset:1280
	global_load_dwordx2 v[196:197], v[150:151], off offset:1408
	s_and_b64 vcc, exec, s[38:39]
	s_cbranch_vccz .LBB0_960
	s_barrier

; #define PG8_STAGE(bufoff, gbase, voff) do { _Pragma("unroll") for (int _i = 0; _i < 2; ++_i) \
;         __builtin_amdgcn_global_load_lds((const unsigned*)((const char*)(gbase) + (voff)[_i]), (PG8_LAS unsigned*)(lds + (bufoff) + ldsw + _i * 8192), 16, 0, 0); } while (0)
; #define PG8_LDA(dst, b, h) do { _Pragma("unroll") for (int m = 0; m < 4; ++m) _Pragma("unroll") for (int k = 0; k < 2; ++k) dst[m][k] = *(const PG8_LAS bf16x8*)(lds + PG8_SA(b, h) + aoff + m * 2048 + k * 1024); } while (0)
; #define PG8_LDB(dst, b, h) do { _Pragma("unroll") for (int n = 0; n < 2; ++n) _Pragma("unroll") for (int k = 0; k < 2; ++k) dst[n][k] = *(const PG8_LAS bf16x8*)(lds + PG8_SB(b, h) + boff + n * 2048 + k * 1024); } while (0)
; #define PG8_BAR __builtin_amdgcn_s_barrier()
; template <class Epi, class Sched, bool ALIGN_EPI = false, bool SP2 = false>
; __device__ __forceinline__ void gemm_phase(PG8_LAS unsigned char* lds, const Gemm g, const Sched& S, const Epi& E) {
;     ...
;         const bool has_next = S.next(ui + 1, nxt);
;         const char* nA = has_next ? (const char*)g.A + (size_t)nxt.pm * tstep : cA; const char* nB = has_next ? (const char*)g.Bt + (size_t)nxt.pn * tstep : cB;
;         for (int t = 0; t < nt; t += 2) {
;             const bool last = (t == nt - 2);
;             const char* a1 = cA + (size_t)(t + 1) * kstep;
;             const char* a2 = last ? nA : cA + (size_t)(t + 2) * kstep; const char* b2 = last ? nB : cB + (size_t)(t + 2) * kstep;
;             const char* a3 = a2 + kstep; const char* b3 = b2 + kstep;
;             if (last && has_next) S.a_ready(nxt);
;             if constexpr (SP2) {
;             PG8_LDB(B0, 0, 0); PG8_LDB(B1, 0, 1); PG8_SCHED; PG8_LDA(At, 0, 0); PG8_STAGE(PG8_SA(1, 1), a1 + hstep, voffA);
;             PG8_WAIT_V(8); PG8_WAIT_L(0); PG8_BAR; PG8_MMA(0, 0, At, B0); PG8_MMA(0, 1, At, B1); PG8_BAR; PG8_SCHED;
;             PG8_LDA(At, 0, 1); PG8_STAGE(PG8_SB(0, 0), b2, voffB); PG8_STAGE(PG8_SB(0, 1), b2 + hstep, voffB); PG8_STAGE(PG8_SA(0, 0), a2, voffA);
;             PG8_WAIT_V(8); PG8_WAIT_L(0); PG8_BAR; PG8_MMA(1, 0, At, B0); PG8_MMA(1, 1, At, B1); PG8_BAR; PG8_SCHED;
;             PG8_LDB(B0, 1, 0); PG8_LDB(B1, 1, 1); PG8_SCHED; PG8_LDA(At, 1, 0); PG8_STAGE(PG8_SA(0, 1), a2 + hstep, voffA);
;             PG8_WAIT_V(8); PG8_WAIT_L(0); PG8_BAR; PG8_MMA(0, 0, At, B0); PG8_MMA(0, 1, At, B1); PG8_BAR; PG8_SCHED;
.LBB0_1034:
	s_add_u32 s75, s52, 0x100
	s_addc_u32 s76, s53, 0
	s_mov_b32 s77, -2
	s_waitcnt lgkmcnt(0)
	ds_read_b128 v[144:147], v151
	ds_read_b128 v[156:159], v151 offset:1024
	ds_read_b128 v[160:163], v151 offset:2048
	ds_read_b128 v[164:167], v151 offset:3072
	ds_read_b128 v[168:171], v152
	ds_read_b128 v[172:175], v152 offset:1024
	ds_read_b128 v[176:179], v152 offset:2048
	ds_read_b128 v[182:185], v152 offset:3072
	s_add_u32 s52, s50, 0x100
	s_addc_u32 s53, s51, 0
	s_cmp_eq_u32 s77, 40
	s_cselect_b32 s57, s1, s53
	s_cselect_b32 s56, s0, s52
	s_cselect_b32 s55, s49, s76
	s_cselect_b32 s54, s48, s75
	v_lshl_add_u64 v[202:203], s[50:51], 0, v[136:137]
	s_add_i32 m0, s14, 0xc000
	ds_read_b128 v[186:189], v153
	ds_read_b128 v[190:193], v153 offset:1024
	ds_read_b128 v[194:197], v153 offset:2048
	ds_read_b128 v[198:201], v153 offset:3072
	ds_read_b128 v[208:211], v153 offset:4096
	ds_read_b128 v[212:215], v153 offset:5120
	ds_read_b128 v[216:219], v153 offset:6144
	ds_read_b128 v[220:223], v153 offset:7168
	global_load_lds_dwordx4 v[202:203], off
	v_lshl_add_u64 v[202:203], s[50:51], 0, v[138:139]
	s_add_i32 m0, s14, 0xe000
	s_nop 0
	global_load_lds_dwordx4 v[202:203], off
	s_waitcnt vmcnt(8)
	s_waitcnt lgkmcnt(0)
	s_barrier
	s_setprio 1
	s_waitcnt lgkmcnt(0)
	v_mfma_f32_16x16x32_bf16 v[124:127], v[144:147], v[186:189], 0
	v_mfma_f32_16x16x32_bf16 v[104:107], v[160:163], v[194:197], 0
	v_mfma_f32_16x16x32_bf16 v[92:95], v[144:147], v[208:211], 0
	v_mfma_f32_16x16x32_bf16 v[72:75], v[160:163], v[216:219], 0
	v_mfma_f32_16x16x32_bf16 v[108:111], v[144:147], v[194:197], 0
	v_mfma_f32_16x16x32_bf16 v[120:123], v[160:163], v[186:189], 0
	v_mfma_f32_16x16x32_bf16 v[76:79], v[144:147], v[216:219], 0
	v_mfma_f32_16x16x32_bf16 v[88:91], v[160:163], v[208:211], 0
	v_mfma_f32_16x16x32_bf16 v[124:127], v[156:159], v[190:193], v[124:127]
	v_mfma_f32_16x16x32_bf16 v[104:107], v[164:167], v[198:201], v[104:107]
	v_mfma_f32_16x16x32_bf16 v[92:95], v[156:159], v[212:215], v[92:95]
	v_mfma_f32_16x16x32_bf16 v[72:75], v[164:167], v[220:223], v[72:75]
	v_mfma_f32_16x16x32_bf16 v[108:111], v[156:159], v[198:201], v[108:111]
	v_mfma_f32_16x16x32_bf16 v[120:123], v[164:167], v[190:193], v[120:123]
	v_mfma_f32_16x16x32_bf16 v[76:79], v[156:159], v[220:223], v[76:79]
	v_mfma_f32_16x16x32_bf16 v[88:91], v[164:167], v[212:215], v[88:91]
	s_setprio 0
	s_setprio 1
	v_mfma_f32_16x16x32_bf16 v[116:119], v[168:171], v[186:189], 0
	v_mfma_f32_16x16x32_bf16 v[96:99], v[176:179], v[194:197], 0
	v_mfma_f32_16x16x32_bf16 v[84:87], v[168:171], v[208:211], 0
	v_mfma_f32_16x16x32_bf16 v[64:67], v[176:179], v[216:219], 0
	v_mfma_f32_16x16x32_bf16 v[100:103], v[168:171], v[194:197], 0
	v_mfma_f32_16x16x32_bf16 v[112:115], v[176:179], v[186:189], 0
	v_mfma_f32_16x16x32_bf16 v[68:71], v[168:171], v[216:219], 0
	v_mfma_f32_16x16x32_bf16 v[80:83], v[176:179], v[208:211], 0
	v_mfma_f32_16x16x32_bf16 v[116:119], v[172:175], v[190:193], v[116:119]
	v_mfma_f32_16x16x32_bf16 v[96:99], v[182:185], v[198:201], v[96:99]
	v_mfma_f32_16x16x32_bf16 v[84:87], v[172:175], v[212:215], v[84:87]
	v_mfma_f32_16x16x32_bf16 v[64:67], v[182:185], v[220:223], v[64:67]
	v_mfma_f32_16x16x32_bf16 v[100:103], v[172:175], v[198:201], v[100:103]
	v_mfma_f32_16x16x32_bf16 v[112:115], v[182:185], v[190:193], v[112:115]
	v_mfma_f32_16x16x32_bf16 v[68:71], v[172:175], v[220:223], v[68:71]
	v_mfma_f32_16x16x32_bf16 v[80:83], v[182:185], v[212:215], v[80:83]
	s_setprio 0
	s_barrier
	s_add_i32 s50, s61, s3
	v_lshl_add_u64 v[202:203], s[54:55], 0, v[130:131]
	s_mov_b32 m0, s50
	ds_read_b128 v[186:189], v153 offset:16384
	ds_read_b128 v[190:193], v153 offset:17408
	ds_read_b128 v[194:197], v153 offset:18432
	ds_read_b128 v[198:201], v153 offset:19456
	ds_read_b128 v[208:211], v153 offset:20480
	ds_read_b128 v[212:215], v153 offset:21504
	ds_read_b128 v[216:219], v153 offset:22528
	ds_read_b128 v[220:223], v153 offset:23552
	global_load_lds_dwordx4 v[202:203], off
	s_add_i32 m0, s50, 0x2000
	s_add_u32 s50, s54, 0xb0000
	v_lshl_add_u64 v[224:225], s[54:55], 0, v[134:135]
	s_addc_u32 s51, s55, 0
	s_add_i32 s78, s62, s3
	global_load_lds_dwordx4 v[224:225], off
	v_lshl_add_u64 v[226:227], s[50:51], 0, v[130:131]
	s_mov_b32 m0, s78
	global_load_lds_dwordx4 v[226:227], off
	v_lshl_add_u64 v[226:227], s[50:51], 0, v[134:135]
	s_add_i32 m0, s78, 0x2000
	s_nop 0
	global_load_lds_dwordx4 v[226:227], off
	s_waitcnt vmcnt(6)
	s_waitcnt lgkmcnt(0)
	s_barrier
; #define PG8_STAGE(bufoff, gbase, voff) do { _Pragma("unroll") for (int _i = 0; _i < 2; ++_i) \
;         __builtin_amdgcn_global_load_lds((const unsigned*)((const char*)(gbase) + (voff)[_i]), (PG8_LAS unsigned*)(lds + (bufoff) + ldsw + _i * 8192), 16, 0, 0); } while (0)
; #define PG8_LDA(dst, b, h) do { _Pragma("unroll") for (int m = 0; m < 4; ++m) _Pragma("unroll") for (int k = 0; k < 2; ++k) dst[m][k] = *(const PG8_LAS bf16x8*)(lds + PG8_SA(b, h) + aoff + m * 2048 + k * 1024); } while (0)
; #define PG8_LDB(dst, b, h) do { _Pragma("unroll") for (int n = 0; n < 2; ++n) _Pragma("unroll") for (int k = 0; k < 2; ++k) dst[n][k] = *(const PG8_LAS bf16x8*)(lds + PG8_SB(b, h) + boff + n * 2048 + k * 1024); } while (0)
; #define PG8_MMA(ai, bj, At, Bt) do { __builtin_amdgcn_s_setprio(1); _Pragma("unroll") for (int m = 0; m < 4; ++m) _Pragma("unroll") for (int n = 0; n < 2; ++n) _Pragma("unroll") for (int k = 0; k < 2; ++k) \
;         acc[ai][bj][m][n] = __builtin_amdgcn_mfma_f32_16x16x32_bf16(Bt[n][k], At[m][k], acc[ai][bj][m][n], 0, 0, 0); __builtin_amdgcn_s_setprio(0); } while (0)
; #define PG8_WAIT_V(n) asm volatile("s_waitcnt vmcnt(" #n ")" ::: "memory")
; template <class Epi, class Sched, bool ALIGN_EPI = false, bool SP2 = false>
; __device__ __forceinline__ void gemm_phase(PG8_LAS unsigned char* lds, const Gemm g, const Sched& S, const Epi& E) {
;     ...
;             PG8_LDB(B0, 0, 0); PG8_LDB(B1, 0, 1); PG8_SCHED; PG8_LDA(At, 0, 0); PG8_STAGE(PG8_SA(1, 1), a1 + hstep, voffA);
;             PG8_WAIT_V(8); PG8_WAIT_L(0); PG8_BAR; PG8_MMA(0, 0, At, B0); PG8_MMA(0, 1, At, B1); PG8_BAR; PG8_SCHED;
;             PG8_LDA(At, 0, 1); PG8_STAGE(PG8_SB(0, 0), b2, voffB); PG8_STAGE(PG8_SB(0, 1), b2 + hstep, voffB); PG8_STAGE(PG8_SA(0, 0), a2, voffA);
;             PG8_WAIT_V(8); PG8_WAIT_L(0); PG8_BAR; PG8_MMA(1, 0, At, B0); PG8_MMA(1, 1, At, B1); PG8_BAR; PG8_SCHED;
;             PG8_LDB(B0, 1, 0); PG8_LDB(B1, 1, 1); PG8_SCHED; PG8_LDA(At, 1, 0); PG8_STAGE(PG8_SA(0, 1), a2 + hstep, voffA);
;             PG8_WAIT_V(8); PG8_WAIT_L(0); PG8_BAR; PG8_MMA(0, 0, At, B0); PG8_MMA(0, 1, At, B1); PG8_BAR; PG8_SCHED;
;             PG8_LDA(At, 1, 1); PG8_STAGE(PG8_SB(1, 0), b3, voffB); PG8_STAGE(PG8_SB(1, 1), b3 + hstep, voffB); PG8_STAGE(PG8_SA(1, 0), a3, voffA);
;             PG8_WAIT_V(8); PG8_WAIT_L(0); PG8_BAR; PG8_MMA(1, 0, At, B0); PG8_MMA(1, 1, At, B1); PG8_BAR; PG8_SCHED;
	s_setprio 1
	s_waitcnt lgkmcnt(0)
	v_mfma_f32_16x16x32_bf16 v[60:63], v[144:147], v[186:189], 0
	v_mfma_f32_16x16x32_bf16 v[40:43], v[160:163], v[194:197], 0
	v_mfma_f32_16x16x32_bf16 v[28:31], v[144:147], v[208:211], 0
	v_mfma_f32_16x16x32_bf16 v[8:11], v[160:163], v[216:219], 0
	v_mfma_f32_16x16x32_bf16 v[44:47], v[144:147], v[194:197], 0
	v_mfma_f32_16x16x32_bf16 v[56:59], v[160:163], v[186:189], 0
	v_mfma_f32_16x16x32_bf16 v[12:15], v[144:147], v[216:219], 0
	v_mfma_f32_16x16x32_bf16 v[24:27], v[160:163], v[208:211], 0
	v_mfma_f32_16x16x32_bf16 v[60:63], v[156:159], v[190:193], v[60:63]
	v_mfma_f32_16x16x32_bf16 v[40:43], v[164:167], v[198:201], v[40:43]
	v_mfma_f32_16x16x32_bf16 v[28:31], v[156:159], v[212:215], v[28:31]
	v_mfma_f32_16x16x32_bf16 v[8:11], v[164:167], v[220:223], v[8:11]
	v_mfma_f32_16x16x32_bf16 v[44:47], v[156:159], v[198:201], v[44:47]
	v_mfma_f32_16x16x32_bf16 v[56:59], v[164:167], v[190:193], v[56:59]
	v_lshl_add_u64 v[226:227], s[56:57], 0, v[128:129]
	s_mov_b32 m0, s14
	s_nop 0
	global_load_lds_dwordx4 v[226:227], off
	v_mfma_f32_16x16x32_bf16 v[12:15], v[156:159], v[220:223], v[12:15]
	v_mfma_f32_16x16x32_bf16 v[24:27], v[164:167], v[212:215], v[24:27]
	s_setprio 0
	s_setprio 1
	v_mfma_f32_16x16x32_bf16 v[52:55], v[168:171], v[186:189], 0
	v_mfma_f32_16x16x32_bf16 v[32:35], v[176:179], v[194:197], 0
	v_mfma_f32_16x16x32_bf16 v[20:23], v[168:171], v[208:211], 0
	v_mfma_f32_16x16x32_bf16 v[0:3], v[176:179], v[216:219], 0
	v_mfma_f32_16x16x32_bf16 v[36:39], v[168:171], v[194:197], 0
	v_mfma_f32_16x16x32_bf16 v[48:51], v[176:179], v[186:189], 0
	v_mfma_f32_16x16x32_bf16 v[4:7], v[168:171], v[216:219], 0
	v_mfma_f32_16x16x32_bf16 v[16:19], v[176:179], v[208:211], 0
	v_mfma_f32_16x16x32_bf16 v[52:55], v[172:175], v[190:193], v[52:55]
	v_mfma_f32_16x16x32_bf16 v[32:35], v[182:185], v[198:201], v[32:35]
	v_mfma_f32_16x16x32_bf16 v[20:23], v[172:175], v[212:215], v[20:23]
	v_mfma_f32_16x16x32_bf16 v[0:3], v[182:185], v[220:223], v[0:3]
	v_mfma_f32_16x16x32_bf16 v[36:39], v[172:175], v[198:201], v[36:39]
	v_mfma_f32_16x16x32_bf16 v[48:51], v[182:185], v[190:193], v[48:51]
	v_lshl_add_u64 v[228:229], s[56:57], 0, v[132:133]
	s_mov_b32 m0, s15
	s_nop 0
	global_load_lds_dwordx4 v[228:229], off
	v_mfma_f32_16x16x32_bf16 v[4:7], v[172:175], v[220:223], v[4:7]
	v_mfma_f32_16x16x32_bf16 v[16:19], v[182:185], v[212:215], v[16:19]
	s_setprio 0
	s_barrier
	s_add_i32 s78, 0, 0x18000
	v_add_u32_e32 v155, s78, v149
	s_add_i32 s79, 0, 0x1c000
	ds_read_b128 v[144:147], v155
	ds_read_b128 v[156:159], v155 offset:1024
	ds_read_b128 v[160:163], v155 offset:2048
	ds_read_b128 v[164:167], v155 offset:3072
	v_add_u32_e32 v155, s79, v149
	ds_read_b128 v[168:171], v155
	ds_read_b128 v[172:175], v155 offset:1024
	ds_read_b128 v[176:179], v155 offset:2048
	ds_read_b128 v[182:185], v155 offset:3072
	s_add_u32 s50, s56, 0xb0000
	s_addc_u32 s51, s57, 0
	s_mov_b32 m0, s33
	v_lshl_add_u64 v[230:231], s[50:51], 0, v[128:129]
	ds_read_b128 v[186:189], v153 offset:32768
	ds_read_b128 v[190:193], v153 offset:33792
	ds_read_b128 v[194:197], v153 offset:34816
	ds_read_b128 v[198:201], v153 offset:35840
	ds_read_b128 v[208:211], v153 offset:36864
	ds_read_b128 v[212:215], v153 offset:37888
	ds_read_b128 v[216:219], v153 offset:38912
	ds_read_b128 v[220:223], v153 offset:39936
	global_load_lds_dwordx4 v[230:231], off
	v_lshl_add_u64 v[230:231], s[50:51], 0, v[132:133]
	s_mov_b32 m0, s34
	s_nop 0
	global_load_lds_dwordx4 v[230:231], off
	s_waitcnt vmcnt(8)
	s_waitcnt lgkmcnt(0)
	s_barrier
	s_setprio 1
	s_waitcnt lgkmcnt(0)
	v_mfma_f32_16x16x32_bf16 v[124:127], v[144:147], v[186:189], v[124:127]
	v_mfma_f32_16x16x32_bf16 v[104:107], v[160:163], v[194:197], v[104:107]
	v_mfma_f32_16x16x32_bf16 v[92:95], v[144:147], v[208:211], v[92:95]
	v_mfma_f32_16x16x32_bf16 v[72:75], v[160:163], v[216:219], v[72:75]
	v_mfma_f32_16x16x32_bf16 v[108:111], v[144:147], v[194:197], v[108:111]
	v_mfma_f32_16x16x32_bf16 v[120:123], v[160:163], v[186:189], v[120:123]
	v_mfma_f32_16x16x32_bf16 v[76:79], v[144:147], v[216:219], v[76:79]
	v_mfma_f32_16x16x32_bf16 v[88:91], v[160:163], v[208:211], v[88:91]
	v_mfma_f32_16x16x32_bf16 v[124:127], v[156:159], v[190:193], v[124:127]
	v_mfma_f32_16x16x32_bf16 v[104:107], v[164:167], v[198:201], v[104:107]
	v_mfma_f32_16x16x32_bf16 v[92:95], v[156:159], v[212:215], v[92:95]
	v_mfma_f32_16x16x32_bf16 v[72:75], v[164:167], v[220:223], v[72:75]
	v_mfma_f32_16x16x32_bf16 v[108:111], v[156:159], v[198:201], v[108:111]
	v_mfma_f32_16x16x32_bf16 v[120:123], v[164:167], v[190:193], v[120:123]
	v_mfma_f32_16x16x32_bf16 v[76:79], v[156:159], v[220:223], v[76:79]
	v_mfma_f32_16x16x32_bf16 v[88:91], v[164:167], v[212:215], v[88:91]
	s_setprio 0
	s_setprio 1
	v_mfma_f32_16x16x32_bf16 v[116:119], v[168:171], v[186:189], v[116:119]
	v_mfma_f32_16x16x32_bf16 v[96:99], v[176:179], v[194:197], v[96:99]
	v_mfma_f32_16x16x32_bf16 v[84:87], v[168:171], v[208:211], v[84:87]
	v_mfma_f32_16x16x32_bf16 v[64:67], v[176:179], v[216:219], v[64:67]
	v_mfma_f32_16x16x32_bf16 v[100:103], v[168:171], v[194:197], v[100:103]
	v_mfma_f32_16x16x32_bf16 v[112:115], v[176:179], v[186:189], v[112:115]
	v_mfma_f32_16x16x32_bf16 v[68:71], v[168:171], v[216:219], v[68:71]
	v_mfma_f32_16x16x32_bf16 v[80:83], v[176:179], v[208:211], v[80:83]
	v_mfma_f32_16x16x32_bf16 v[116:119], v[172:175], v[190:193], v[116:119]
	v_mfma_f32_16x16x32_bf16 v[96:99], v[182:185], v[198:201], v[96:99]
	v_mfma_f32_16x16x32_bf16 v[84:87], v[172:175], v[212:215], v[84:87]
	v_mfma_f32_16x16x32_bf16 v[64:67], v[182:185], v[220:223], v[64:67]
	v_mfma_f32_16x16x32_bf16 v[100:103], v[172:175], v[198:201], v[100:103]
	v_mfma_f32_16x16x32_bf16 v[112:115], v[182:185], v[190:193], v[112:115]
	v_mfma_f32_16x16x32_bf16 v[68:71], v[172:175], v[220:223], v[68:71]
	v_mfma_f32_16x16x32_bf16 v[80:83], v[182:185], v[212:215], v[80:83]
	s_setprio 0
	s_barrier
; #define PG8_STAGE(bufoff, gbase, voff) do { _Pragma("unroll") for (int _i = 0; _i < 2; ++_i) \
;         __builtin_amdgcn_global_load_lds((const unsigned*)((const char*)(gbase) + (voff)[_i]), (PG8_LAS unsigned*)(lds + (bufoff) + ldsw + _i * 8192), 16, 0, 0); } while (0)
; #define PG8_LDA(dst, b, h) do { _Pragma("unroll") for (int m = 0; m < 4; ++m) _Pragma("unroll") for (int k = 0; k < 2; ++k) dst[m][k] = *(const PG8_LAS bf16x8*)(lds + PG8_SA(b, h) + aoff + m * 2048 + k * 1024); } while (0)
; #define PG8_LDB(dst, b, h) do { _Pragma("unroll") for (int n = 0; n < 2; ++n) _Pragma("unroll") for (int k = 0; k < 2; ++k) dst[n][k] = *(const PG8_LAS bf16x8*)(lds + PG8_SB(b, h) + boff + n * 2048 + k * 1024); } while (0)
; template <class Epi, class Sched, bool ALIGN_EPI = false, bool SP2 = false>
; __device__ __forceinline__ void gemm_phase(PG8_LAS unsigned char* lds, const Gemm g, const Sched& S, const Epi& E) {
;     ...
;         for (int t = 0; t < nt; t += 2) {
;             const bool last = (t == nt - 2);
;             const char* a1 = cA + (size_t)(t + 1) * kstep;
;             const char* a2 = last ? nA : cA + (size_t)(t + 2) * kstep; const char* b2 = last ? nB : cB + (size_t)(t + 2) * kstep;
;             const char* a3 = a2 + kstep; const char* b3 = b2 + kstep;
;             if (last && has_next) S.a_ready(nxt);
;             if constexpr (SP2) {
;             PG8_LDB(B0, 0, 0); PG8_LDB(B1, 0, 1); PG8_SCHED; PG8_LDA(At, 0, 0); PG8_STAGE(PG8_SA(1, 1), a1 + hstep, voffA);
;             PG8_WAIT_V(8); PG8_WAIT_L(0); PG8_BAR; PG8_MMA(0, 0, At, B0); PG8_MMA(0, 1, At, B1); PG8_BAR; PG8_SCHED;
;             PG8_LDA(At, 0, 1); PG8_STAGE(PG8_SB(0, 0), b2, voffB); PG8_STAGE(PG8_SB(0, 1), b2 + hstep, voffB); PG8_STAGE(PG8_SA(0, 0), a2, voffA);
;             PG8_WAIT_V(8); PG8_WAIT_L(0); PG8_BAR; PG8_MMA(1, 0, At, B0); PG8_MMA(1, 1, At, B1); PG8_BAR; PG8_SCHED;
;             PG8_LDB(B0, 1, 0); PG8_LDB(B1, 1, 1); PG8_SCHED; PG8_LDA(At, 1, 0); PG8_STAGE(PG8_SA(0, 1), a2 + hstep, voffA);
;             PG8_WAIT_V(8); PG8_WAIT_L(0); PG8_BAR; PG8_MMA(0, 0, At, B0); PG8_MMA(0, 1, At, B1); PG8_BAR; PG8_SCHED;
;             PG8_LDA(At, 1, 1); PG8_STAGE(PG8_SB(1, 0), b3, voffB); PG8_STAGE(PG8_SB(1, 1), b3 + hstep, voffB); PG8_STAGE(PG8_SA(1, 0), a3, voffA);
;             PG8_WAIT_V(8); PG8_WAIT_L(0); PG8_BAR; PG8_MMA(1, 0, At, B0); PG8_MMA(1, 1, At, B1); PG8_BAR; PG8_SCHED;
	s_add_i32 s50, s78, s3
	v_lshl_add_u64 v[202:203], v[202:203], 0, s[42:43]
	s_mov_b32 m0, s50
	ds_read_b128 v[186:189], v153 offset:49152
	ds_read_b128 v[190:193], v153 offset:50176
	ds_read_b128 v[194:197], v153 offset:51200
	ds_read_b128 v[198:201], v153 offset:52224
	ds_read_b128 v[208:211], v153 offset:53248
	ds_read_b128 v[212:215], v153 offset:54272
	ds_read_b128 v[216:219], v153 offset:55296
	ds_read_b128 v[220:223], v153 offset:56320
	global_load_lds_dwordx4 v[202:203], off
	s_add_i32 m0, s50, 0x2000
	s_add_u32 s50, s54, 0xb0080
	v_lshl_add_u64 v[202:203], v[224:225], 0, s[42:43]
	s_addc_u32 s51, s55, 0
	s_add_i32 s54, s79, s3
	global_load_lds_dwordx4 v[202:203], off
	v_lshl_add_u64 v[202:203], s[50:51], 0, v[130:131]
	s_mov_b32 m0, s54
	s_nop 0
	global_load_lds_dwordx4 v[202:203], off
	v_lshl_add_u64 v[202:203], s[50:51], 0, v[134:135]
	s_add_i32 m0, s54, 0x2000
	s_nop 0
	global_load_lds_dwordx4 v[202:203], off
	s_waitcnt vmcnt(6)
	s_waitcnt lgkmcnt(0)
	s_barrier
	s_setprio 1
	s_waitcnt lgkmcnt(0)
	v_mfma_f32_16x16x32_bf16 v[60:63], v[144:147], v[186:189], v[60:63]
	v_mfma_f32_16x16x32_bf16 v[40:43], v[160:163], v[194:197], v[40:43]
	v_mfma_f32_16x16x32_bf16 v[28:31], v[144:147], v[208:211], v[28:31]
	v_mfma_f32_16x16x32_bf16 v[8:11], v[160:163], v[216:219], v[8:11]
	v_mfma_f32_16x16x32_bf16 v[44:47], v[144:147], v[194:197], v[44:47]
	v_mfma_f32_16x16x32_bf16 v[56:59], v[160:163], v[186:189], v[56:59]
	v_mfma_f32_16x16x32_bf16 v[12:15], v[144:147], v[216:219], v[12:15]
	v_mfma_f32_16x16x32_bf16 v[24:27], v[160:163], v[208:211], v[24:27]
	v_mfma_f32_16x16x32_bf16 v[60:63], v[156:159], v[190:193], v[60:63]
	v_mfma_f32_16x16x32_bf16 v[40:43], v[164:167], v[198:201], v[40:43]
	v_mfma_f32_16x16x32_bf16 v[28:31], v[156:159], v[212:215], v[28:31]
	v_mfma_f32_16x16x32_bf16 v[8:11], v[164:167], v[220:223], v[8:11]
	v_mfma_f32_16x16x32_bf16 v[44:47], v[156:159], v[198:201], v[44:47]
	v_mfma_f32_16x16x32_bf16 v[56:59], v[164:167], v[190:193], v[56:59]
	v_lshl_add_u64 v[202:203], v[226:227], 0, s[42:43]
	s_mov_b32 m0, s59
	s_nop 0
	global_load_lds_dwordx4 v[202:203], off
	v_mfma_f32_16x16x32_bf16 v[12:15], v[156:159], v[220:223], v[12:15]
	v_mfma_f32_16x16x32_bf16 v[24:27], v[164:167], v[212:215], v[24:27]
	s_setprio 0
	s_setprio 1
	v_mfma_f32_16x16x32_bf16 v[52:55], v[168:171], v[186:189], v[52:55]
	v_mfma_f32_16x16x32_bf16 v[32:35], v[176:179], v[194:197], v[32:35]
	v_mfma_f32_16x16x32_bf16 v[20:23], v[168:171], v[208:211], v[20:23]
	v_mfma_f32_16x16x32_bf16 v[0:3], v[176:179], v[216:219], v[0:3]
	v_mfma_f32_16x16x32_bf16 v[36:39], v[168:171], v[194:197], v[36:39]
	v_mfma_f32_16x16x32_bf16 v[48:51], v[176:179], v[186:189], v[48:51]
	v_mfma_f32_16x16x32_bf16 v[4:7], v[168:171], v[216:219], v[4:7]
	v_mfma_f32_16x16x32_bf16 v[16:19], v[176:179], v[208:211], v[16:19]
	v_mfma_f32_16x16x32_bf16 v[52:55], v[172:175], v[190:193], v[52:55]
	v_mfma_f32_16x16x32_bf16 v[32:35], v[182:185], v[198:201], v[32:35]
	v_mfma_f32_16x16x32_bf16 v[20:23], v[172:175], v[212:215], v[20:23]
	v_mfma_f32_16x16x32_bf16 v[0:3], v[182:185], v[220:223], v[0:3]
	v_mfma_f32_16x16x32_bf16 v[36:39], v[172:175], v[198:201], v[36:39]
	v_mfma_f32_16x16x32_bf16 v[48:51], v[182:185], v[190:193], v[48:51]
	v_lshl_add_u64 v[202:203], v[228:229], 0, s[42:43]
	s_mov_b32 m0, s60
	s_nop 0
	global_load_lds_dwordx4 v[202:203], off
	v_mfma_f32_16x16x32_bf16 v[4:7], v[172:175], v[220:223], v[4:7]
	v_mfma_f32_16x16x32_bf16 v[16:19], v[182:185], v[212:215], v[16:19]
	s_setprio 0
	s_barrier
	s_add_i32 s77, s77, 2
	s_add_u32 s75, s75, 0x100
	s_addc_u32 s76, s76, 0
	s_mov_b64 s[50:51], s[52:53]
.LBB0_1035:
	ds_read_b128 v[144:147], v151
	ds_read_b128 v[156:159], v151 offset:1024
	ds_read_b128 v[160:163], v151 offset:2048
	ds_read_b128 v[164:167], v151 offset:3072
	ds_read_b128 v[168:171], v152
	ds_read_b128 v[172:175], v152 offset:1024
	ds_read_b128 v[176:179], v152 offset:2048
	ds_read_b128 v[182:185], v152 offset:3072
	s_add_u32 s52, s50, 0x100
	s_addc_u32 s53, s51, 0
	s_cmp_eq_u32 s77, 40
	s_cselect_b32 s57, s1, s53
	s_cselect_b32 s56, s0, s52
	s_cselect_b32 s55, s49, s76
	s_cselect_b32 s54, s48, s75
	v_lshl_add_u64 v[202:203], s[50:51], 0, v[136:137]
	s_add_i32 m0, s14, 0xc000
	ds_read_b128 v[186:189], v153
	ds_read_b128 v[190:193], v153 offset:1024
	ds_read_b128 v[194:197], v153 offset:2048
	ds_read_b128 v[198:201], v153 offset:3072
	ds_read_b128 v[208:211], v153 offset:4096
	ds_read_b128 v[212:215], v153 offset:5120
	ds_read_b128 v[216:219], v153 offset:6144
	ds_read_b128 v[220:223], v153 offset:7168
	global_load_lds_dwordx4 v[202:203], off
	v_lshl_add_u64 v[202:203], s[50:51], 0, v[138:139]
	s_add_i32 m0, s14, 0xe000
	s_nop 0
	global_load_lds_dwordx4 v[202:203], off
	s_waitcnt vmcnt(8)
	s_waitcnt lgkmcnt(0)
	s_barrier
; #define PG8_STAGE(bufoff, gbase, voff) do { _Pragma("unroll") for (int _i = 0; _i < 2; ++_i) \
;         __builtin_amdgcn_global_load_lds((const unsigned*)((const char*)(gbase) + (voff)[_i]), (PG8_LAS unsigned*)(lds + (bufoff) + ldsw + _i * 8192), 16, 0, 0); } while (0)
; #define PG8_LDA(dst, b, h) do { _Pragma("unroll") for (int m = 0; m < 4; ++m) _Pragma("unroll") for (int k = 0; k < 2; ++k) dst[m][k] = *(const PG8_LAS bf16x8*)(lds + PG8_SA(b, h) + aoff + m * 2048 + k * 1024); } while (0)
; #define PG8_MMA(ai, bj, At, Bt) do { __builtin_amdgcn_s_setprio(1); _Pragma("unroll") for (int m = 0; m < 4; ++m) _Pragma("unroll") for (int n = 0; n < 2; ++n) _Pragma("unroll") for (int k = 0; k < 2; ++k) \
;         acc[ai][bj][m][n] = __builtin_amdgcn_mfma_f32_16x16x32_bf16(Bt[n][k], At[m][k], acc[ai][bj][m][n], 0, 0, 0); __builtin_amdgcn_s_setprio(0); } while (0)
; #define PG8_WAIT_V(n) asm volatile("s_waitcnt vmcnt(" #n ")" ::: "memory")
; #define PG8_WAIT_L(n) asm volatile("s_waitcnt lgkmcnt(" #n ")" ::: "memory")
; #define PG8_BAR __builtin_amdgcn_s_barrier()
; #define PG8_SCHED __builtin_amdgcn_sched_barrier(0)
; template <class Epi, class Sched, bool ALIGN_EPI = false, bool SP2 = false>
; __device__ __forceinline__ void gemm_phase(PG8_LAS unsigned char* lds, const Gemm g, const Sched& S, const Epi& E) {
;     ...
;             PG8_WAIT_V(8); PG8_WAIT_L(0); PG8_BAR; PG8_MMA(0, 0, At, B0); PG8_MMA(0, 1, At, B1); PG8_BAR; PG8_SCHED;
;             PG8_LDA(At, 0, 1); PG8_STAGE(PG8_SB(0, 0), b2, voffB); PG8_STAGE(PG8_SB(0, 1), b2 + hstep, voffB); PG8_STAGE(PG8_SA(0, 0), a2, voffA);
;             PG8_WAIT_V(8); PG8_WAIT_L(0); PG8_BAR; PG8_MMA(1, 0, At, B0); PG8_MMA(1, 1, At, B1); PG8_BAR; PG8_SCHED;
	s_setprio 1
	s_waitcnt lgkmcnt(0)
	v_mfma_f32_16x16x32_bf16 v[124:127], v[144:147], v[186:189], v[124:127]
	v_mfma_f32_16x16x32_bf16 v[104:107], v[160:163], v[194:197], v[104:107]
	v_mfma_f32_16x16x32_bf16 v[92:95], v[144:147], v[208:211], v[92:95]
	v_mfma_f32_16x16x32_bf16 v[72:75], v[160:163], v[216:219], v[72:75]
	v_mfma_f32_16x16x32_bf16 v[108:111], v[144:147], v[194:197], v[108:111]
	v_mfma_f32_16x16x32_bf16 v[120:123], v[160:163], v[186:189], v[120:123]
	v_mfma_f32_16x16x32_bf16 v[76:79], v[144:147], v[216:219], v[76:79]
	v_mfma_f32_16x16x32_bf16 v[88:91], v[160:163], v[208:211], v[88:91]
	v_mfma_f32_16x16x32_bf16 v[124:127], v[156:159], v[190:193], v[124:127]
	v_mfma_f32_16x16x32_bf16 v[104:107], v[164:167], v[198:201], v[104:107]
	v_mfma_f32_16x16x32_bf16 v[92:95], v[156:159], v[212:215], v[92:95]
	v_mfma_f32_16x16x32_bf16 v[72:75], v[164:167], v[220:223], v[72:75]
	v_mfma_f32_16x16x32_bf16 v[108:111], v[156:159], v[198:201], v[108:111]
	v_mfma_f32_16x16x32_bf16 v[120:123], v[164:167], v[190:193], v[120:123]
	v_mfma_f32_16x16x32_bf16 v[76:79], v[156:159], v[220:223], v[76:79]
	v_mfma_f32_16x16x32_bf16 v[88:91], v[164:167], v[212:215], v[88:91]
	s_setprio 0
	s_setprio 1
	v_mfma_f32_16x16x32_bf16 v[116:119], v[168:171], v[186:189], v[116:119]
	v_mfma_f32_16x16x32_bf16 v[96:99], v[176:179], v[194:197], v[96:99]
	v_mfma_f32_16x16x32_bf16 v[84:87], v[168:171], v[208:211], v[84:87]
	v_mfma_f32_16x16x32_bf16 v[64:67], v[176:179], v[216:219], v[64:67]
	v_mfma_f32_16x16x32_bf16 v[100:103], v[168:171], v[194:197], v[100:103]
	v_mfma_f32_16x16x32_bf16 v[112:115], v[176:179], v[186:189], v[112:115]
	v_mfma_f32_16x16x32_bf16 v[68:71], v[168:171], v[216:219], v[68:71]
	v_mfma_f32_16x16x32_bf16 v[80:83], v[176:179], v[208:211], v[80:83]
	v_mfma_f32_16x16x32_bf16 v[116:119], v[172:175], v[190:193], v[116:119]
	v_mfma_f32_16x16x32_bf16 v[96:99], v[182:185], v[198:201], v[96:99]
	v_mfma_f32_16x16x32_bf16 v[84:87], v[172:175], v[212:215], v[84:87]
	v_mfma_f32_16x16x32_bf16 v[64:67], v[182:185], v[220:223], v[64:67]
	v_mfma_f32_16x16x32_bf16 v[100:103], v[172:175], v[198:201], v[100:103]
	v_mfma_f32_16x16x32_bf16 v[112:115], v[182:185], v[190:193], v[112:115]
	v_mfma_f32_16x16x32_bf16 v[68:71], v[172:175], v[220:223], v[68:71]
	v_mfma_f32_16x16x32_bf16 v[80:83], v[182:185], v[212:215], v[80:83]
	s_setprio 0
	s_barrier
	s_add_i32 s50, s61, s3
	v_lshl_add_u64 v[202:203], s[54:55], 0, v[130:131]
	s_mov_b32 m0, s50
	ds_read_b128 v[186:189], v153 offset:16384
	ds_read_b128 v[190:193], v153 offset:17408
	ds_read_b128 v[194:197], v153 offset:18432
	ds_read_b128 v[198:201], v153 offset:19456
	ds_read_b128 v[208:211], v153 offset:20480
	ds_read_b128 v[212:215], v153 offset:21504
	ds_read_b128 v[216:219], v153 offset:22528
	ds_read_b128 v[220:223], v153 offset:23552
	global_load_lds_dwordx4 v[202:203], off
	s_add_i32 m0, s50, 0x2000
	s_add_u32 s50, s54, 0xb0000
	v_lshl_add_u64 v[224:225], s[54:55], 0, v[134:135]
	s_addc_u32 s51, s55, 0
	s_add_i32 s78, s62, s3
	global_load_lds_dwordx4 v[224:225], off
	v_lshl_add_u64 v[226:227], s[50:51], 0, v[130:131]
	s_mov_b32 m0, s78
	global_load_lds_dwordx4 v[226:227], off
	v_lshl_add_u64 v[226:227], s[50:51], 0, v[134:135]
	s_add_i32 m0, s78, 0x2000
	s_nop 0
	global_load_lds_dwordx4 v[226:227], off
	s_waitcnt vmcnt(6)
	s_waitcnt lgkmcnt(0)
	s_barrier
	s_setprio 1
	s_waitcnt lgkmcnt(0)
	v_mfma_f32_16x16x32_bf16 v[60:63], v[144:147], v[186:189], v[60:63]
	v_mfma_f32_16x16x32_bf16 v[40:43], v[160:163], v[194:197], v[40:43]
	v_mfma_f32_16x16x32_bf16 v[28:31], v[144:147], v[208:211], v[28:31]
	v_mfma_f32_16x16x32_bf16 v[8:11], v[160:163], v[216:219], v[8:11]
	v_mfma_f32_16x16x32_bf16 v[44:47], v[144:147], v[194:197], v[44:47]
	v_mfma_f32_16x16x32_bf16 v[56:59], v[160:163], v[186:189], v[56:59]
	v_mfma_f32_16x16x32_bf16 v[12:15], v[144:147], v[216:219], v[12:15]
	v_mfma_f32_16x16x32_bf16 v[24:27], v[160:163], v[208:211], v[24:27]
	v_mfma_f32_16x16x32_bf16 v[60:63], v[156:159], v[190:193], v[60:63]
	v_mfma_f32_16x16x32_bf16 v[40:43], v[164:167], v[198:201], v[40:43]
	v_mfma_f32_16x16x32_bf16 v[28:31], v[156:159], v[212:215], v[28:31]
	v_mfma_f32_16x16x32_bf16 v[8:11], v[164:167], v[220:223], v[8:11]
	v_mfma_f32_16x16x32_bf16 v[44:47], v[156:159], v[198:201], v[44:47]
	v_mfma_f32_16x16x32_bf16 v[56:59], v[164:167], v[190:193], v[56:59]
	v_lshl_add_u64 v[226:227], s[56:57], 0, v[128:129]
	s_mov_b32 m0, s14
	s_nop 0
	global_load_lds_dwordx4 v[226:227], off
	v_mfma_f32_16x16x32_bf16 v[12:15], v[156:159], v[220:223], v[12:15]
	v_mfma_f32_16x16x32_bf16 v[24:27], v[164:167], v[212:215], v[24:27]
	s_setprio 0
	s_setprio 1
	v_mfma_f32_16x16x32_bf16 v[52:55], v[168:171], v[186:189], v[52:55]
	v_mfma_f32_16x16x32_bf16 v[32:35], v[176:179], v[194:197], v[32:35]
	v_mfma_f32_16x16x32_bf16 v[20:23], v[168:171], v[208:211], v[20:23]
	v_mfma_f32_16x16x32_bf16 v[0:3], v[176:179], v[216:219], v[0:3]
	v_mfma_f32_16x16x32_bf16 v[36:39], v[168:171], v[194:197], v[36:39]
	v_mfma_f32_16x16x32_bf16 v[48:51], v[176:179], v[186:189], v[48:51]
	v_mfma_f32_16x16x32_bf16 v[4:7], v[168:171], v[216:219], v[4:7]
	v_mfma_f32_16x16x32_bf16 v[16:19], v[176:179], v[208:211], v[16:19]
	v_mfma_f32_16x16x32_bf16 v[52:55], v[172:175], v[190:193], v[52:55]
	v_mfma_f32_16x16x32_bf16 v[32:35], v[182:185], v[198:201], v[32:35]
	v_mfma_f32_16x16x32_bf16 v[20:23], v[172:175], v[212:215], v[20:23]
	v_mfma_f32_16x16x32_bf16 v[0:3], v[182:185], v[220:223], v[0:3]
	v_mfma_f32_16x16x32_bf16 v[36:39], v[172:175], v[198:201], v[36:39]
	v_mfma_f32_16x16x32_bf16 v[48:51], v[182:185], v[190:193], v[48:51]
	v_lshl_add_u64 v[228:229], s[56:57], 0, v[132:133]
	s_mov_b32 m0, s15
	s_nop 0
	global_load_lds_dwordx4 v[228:229], off
	v_mfma_f32_16x16x32_bf16 v[4:7], v[172:175], v[220:223], v[4:7]
	v_mfma_f32_16x16x32_bf16 v[16:19], v[182:185], v[212:215], v[16:19]
	s_setprio 0
	s_barrier
; #define PG8_STAGE(bufoff, gbase, voff) do { _Pragma("unroll") for (int _i = 0; _i < 2; ++_i) \
;         __builtin_amdgcn_global_load_lds((const unsigned*)((const char*)(gbase) + (voff)[_i]), (PG8_LAS unsigned*)(lds + (bufoff) + ldsw + _i * 8192), 16, 0, 0); } while (0)
; #define PG8_LDA(dst, b, h) do { _Pragma("unroll") for (int m = 0; m < 4; ++m) _Pragma("unroll") for (int k = 0; k < 2; ++k) dst[m][k] = *(const PG8_LAS bf16x8*)(lds + PG8_SA(b, h) + aoff + m * 2048 + k * 1024); } while (0)
; #define PG8_LDB(dst, b, h) do { _Pragma("unroll") for (int n = 0; n < 2; ++n) _Pragma("unroll") for (int k = 0; k < 2; ++k) dst[n][k] = *(const PG8_LAS bf16x8*)(lds + PG8_SB(b, h) + boff + n * 2048 + k * 1024); } while (0)
; #define PG8_MMA(ai, bj, At, Bt) do { __builtin_amdgcn_s_setprio(1); _Pragma("unroll") for (int m = 0; m < 4; ++m) _Pragma("unroll") for (int n = 0; n < 2; ++n) _Pragma("unroll") for (int k = 0; k < 2; ++k) \
;         acc[ai][bj][m][n] = __builtin_amdgcn_mfma_f32_16x16x32_bf16(Bt[n][k], At[m][k], acc[ai][bj][m][n], 0, 0, 0); __builtin_amdgcn_s_setprio(0); } while (0)
; #define PG8_WAIT_V(n) asm volatile("s_waitcnt vmcnt(" #n ")" ::: "memory")
; #define PG8_WAIT_L(n) asm volatile("s_waitcnt lgkmcnt(" #n ")" ::: "memory")
; #define PG8_BAR __builtin_amdgcn_s_barrier()
; #define PG8_SCHED __builtin_amdgcn_sched_barrier(0)
; template <class Epi, class Sched, bool ALIGN_EPI = false, bool SP2 = false>
; __device__ __forceinline__ void gemm_phase(PG8_LAS unsigned char* lds, const Gemm g, const Sched& S, const Epi& E) {
;     ...
;             PG8_LDB(B0, 1, 0); PG8_LDB(B1, 1, 1); PG8_SCHED; PG8_LDA(At, 1, 0); PG8_STAGE(PG8_SA(0, 1), a2 + hstep, voffA);
;             PG8_WAIT_V(8); PG8_WAIT_L(0); PG8_BAR; PG8_MMA(0, 0, At, B0); PG8_MMA(0, 1, At, B1); PG8_BAR; PG8_SCHED;
	s_add_i32 s78, 0, 0x18000
	v_add_u32_e32 v155, s78, v149
	s_add_i32 s79, 0, 0x1c000
	ds_read_b128 v[144:147], v155
	ds_read_b128 v[156:159], v155 offset:1024
	ds_read_b128 v[160:163], v155 offset:2048
	ds_read_b128 v[164:167], v155 offset:3072
	v_add_u32_e32 v155, s79, v149
	ds_read_b128 v[168:171], v155
	ds_read_b128 v[172:175], v155 offset:1024
	ds_read_b128 v[176:179], v155 offset:2048
	ds_read_b128 v[182:185], v155 offset:3072
	s_add_u32 s50, s56, 0xb0000
	s_addc_u32 s51, s57, 0
	s_mov_b32 m0, s33
	v_lshl_add_u64 v[230:231], s[50:51], 0, v[128:129]
	ds_read_b128 v[186:189], v153 offset:32768
	ds_read_b128 v[190:193], v153 offset:33792
	ds_read_b128 v[194:197], v153 offset:34816
	ds_read_b128 v[198:201], v153 offset:35840
	ds_read_b128 v[208:211], v153 offset:36864
	ds_read_b128 v[212:215], v153 offset:37888
	ds_read_b128 v[216:219], v153 offset:38912
	ds_read_b128 v[220:223], v153 offset:39936
	global_load_lds_dwordx4 v[230:231], off
	v_lshl_add_u64 v[230:231], s[50:51], 0, v[132:133]
	s_mov_b32 m0, s34
	s_nop 0
	global_load_lds_dwordx4 v[230:231], off
	s_waitcnt vmcnt(8)
	s_waitcnt lgkmcnt(0)
	s_barrier
	s_setprio 1
	s_waitcnt lgkmcnt(0)
	v_mfma_f32_16x16x32_bf16 v[124:127], v[144:147], v[186:189], v[124:127]
	v_mfma_f32_16x16x32_bf16 v[104:107], v[160:163], v[194:197], v[104:107]
	v_mfma_f32_16x16x32_bf16 v[92:95], v[144:147], v[208:211], v[92:95]
	v_mfma_f32_16x16x32_bf16 v[72:75], v[160:163], v[216:219], v[72:75]
	v_mfma_f32_16x16x32_bf16 v[108:111], v[144:147], v[194:197], v[108:111]
	v_mfma_f32_16x16x32_bf16 v[120:123], v[160:163], v[186:189], v[120:123]
	v_mfma_f32_16x16x32_bf16 v[76:79], v[144:147], v[216:219], v[76:79]
	v_mfma_f32_16x16x32_bf16 v[88:91], v[160:163], v[208:211], v[88:91]
	v_mfma_f32_16x16x32_bf16 v[124:127], v[156:159], v[190:193], v[124:127]
	v_mfma_f32_16x16x32_bf16 v[104:107], v[164:167], v[198:201], v[104:107]
	v_mfma_f32_16x16x32_bf16 v[92:95], v[156:159], v[212:215], v[92:95]
	v_mfma_f32_16x16x32_bf16 v[72:75], v[164:167], v[220:223], v[72:75]
	v_mfma_f32_16x16x32_bf16 v[108:111], v[156:159], v[198:201], v[108:111]
	v_mfma_f32_16x16x32_bf16 v[120:123], v[164:167], v[190:193], v[120:123]
	v_mfma_f32_16x16x32_bf16 v[76:79], v[156:159], v[220:223], v[76:79]
	v_mfma_f32_16x16x32_bf16 v[88:91], v[164:167], v[212:215], v[88:91]
	s_setprio 0
	s_setprio 1
	v_mfma_f32_16x16x32_bf16 v[116:119], v[168:171], v[186:189], v[116:119]
	v_mfma_f32_16x16x32_bf16 v[96:99], v[176:179], v[194:197], v[96:99]
	v_mfma_f32_16x16x32_bf16 v[84:87], v[168:171], v[208:211], v[84:87]
	v_mfma_f32_16x16x32_bf16 v[64:67], v[176:179], v[216:219], v[64:67]
	v_mfma_f32_16x16x32_bf16 v[100:103], v[168:171], v[194:197], v[100:103]
	v_mfma_f32_16x16x32_bf16 v[112:115], v[176:179], v[186:189], v[112:115]
	v_mfma_f32_16x16x32_bf16 v[68:71], v[168:171], v[216:219], v[68:71]
	v_mfma_f32_16x16x32_bf16 v[80:83], v[176:179], v[208:211], v[80:83]
	v_mfma_f32_16x16x32_bf16 v[116:119], v[172:175], v[190:193], v[116:119]
	v_mfma_f32_16x16x32_bf16 v[96:99], v[182:185], v[198:201], v[96:99]
	v_mfma_f32_16x16x32_bf16 v[84:87], v[172:175], v[212:215], v[84:87]
	v_mfma_f32_16x16x32_bf16 v[64:67], v[182:185], v[220:223], v[64:67]
	v_mfma_f32_16x16x32_bf16 v[100:103], v[172:175], v[198:201], v[100:103]
	v_mfma_f32_16x16x32_bf16 v[112:115], v[182:185], v[190:193], v[112:115]
	v_mfma_f32_16x16x32_bf16 v[68:71], v[172:175], v[220:223], v[68:71]
	v_mfma_f32_16x16x32_bf16 v[80:83], v[182:185], v[212:215], v[80:83]
	s_setprio 0
	s_barrier
; #define PG8_STAGE(bufoff, gbase, voff) do { _Pragma("unroll") for (int _i = 0; _i < 2; ++_i) \
;         __builtin_amdgcn_global_load_lds((const unsigned*)((const char*)(gbase) + (voff)[_i]), (PG8_LAS unsigned*)(lds + (bufoff) + ldsw + _i * 8192), 16, 0, 0); } while (0)
; #define PG8_LDA(dst, b, h) do { _Pragma("unroll") for (int m = 0; m < 4; ++m) _Pragma("unroll") for (int k = 0; k < 2; ++k) dst[m][k] = *(const PG8_LAS bf16x8*)(lds + PG8_SA(b, h) + aoff + m * 2048 + k * 1024); } while (0)
; #define PG8_MMA(ai, bj, At, Bt) do { __builtin_amdgcn_s_setprio(1); _Pragma("unroll") for (int m = 0; m < 4; ++m) _Pragma("unroll") for (int n = 0; n < 2; ++n) _Pragma("unroll") for (int k = 0; k < 2; ++k) \
;         acc[ai][bj][m][n] = __builtin_amdgcn_mfma_f32_16x16x32_bf16(Bt[n][k], At[m][k], acc[ai][bj][m][n], 0, 0, 0); __builtin_amdgcn_s_setprio(0); } while (0)
; #define PG8_WAIT_V(n) asm volatile("s_waitcnt vmcnt(" #n ")" ::: "memory")
; #define PG8_WAIT_L(n) asm volatile("s_waitcnt lgkmcnt(" #n ")" ::: "memory")
; #define PG8_BAR __builtin_amdgcn_s_barrier()
; #define PG8_SCHED __builtin_amdgcn_sched_barrier(0)
; template <class Epi, class Sched, bool ALIGN_EPI = false, bool SP2 = false>
; __device__ __forceinline__ void gemm_phase(PG8_LAS unsigned char* lds, const Gemm g, const Sched& S, const Epi& E) {
;     ...
;         for (int t = 0; t < nt; t += 2) {
;             const bool last = (t == nt - 2);
;     ...
;             PG8_LDA(At, 1, 1); PG8_STAGE(PG8_SB(1, 0), b3, voffB); PG8_STAGE(PG8_SB(1, 1), b3 + hstep, voffB); PG8_STAGE(PG8_SA(1, 0), a3, voffA);
;             PG8_WAIT_V(8); PG8_WAIT_L(0); PG8_BAR; PG8_MMA(1, 0, At, B0); PG8_MMA(1, 1, At, B1); PG8_BAR; PG8_SCHED;
	s_add_i32 s50, s78, s3
	v_lshl_add_u64 v[202:203], v[202:203], 0, s[42:43]
	s_mov_b32 m0, s50
	ds_read_b128 v[186:189], v153 offset:49152
	ds_read_b128 v[190:193], v153 offset:50176
	ds_read_b128 v[194:197], v153 offset:51200
	ds_read_b128 v[198:201], v153 offset:52224
	ds_read_b128 v[208:211], v153 offset:53248
	ds_read_b128 v[212:215], v153 offset:54272
	ds_read_b128 v[216:219], v153 offset:55296
	ds_read_b128 v[220:223], v153 offset:56320
	global_load_lds_dwordx4 v[202:203], off
	s_add_i32 m0, s50, 0x2000
	s_add_u32 s50, s54, 0xb0080
	v_lshl_add_u64 v[202:203], v[224:225], 0, s[42:43]
	s_addc_u32 s51, s55, 0
	s_add_i32 s54, s79, s3
	global_load_lds_dwordx4 v[202:203], off
	v_lshl_add_u64 v[202:203], s[50:51], 0, v[130:131]
	s_mov_b32 m0, s54
	s_nop 0
	global_load_lds_dwordx4 v[202:203], off
	v_lshl_add_u64 v[202:203], s[50:51], 0, v[134:135]
	s_add_i32 m0, s54, 0x2000
	s_nop 0
	global_load_lds_dwordx4 v[202:203], off
	s_waitcnt vmcnt(6)
	s_waitcnt lgkmcnt(0)
	s_barrier
	s_setprio 1
	s_waitcnt lgkmcnt(0)
	v_mfma_f32_16x16x32_bf16 v[60:63], v[144:147], v[186:189], v[60:63]
	v_mfma_f32_16x16x32_bf16 v[40:43], v[160:163], v[194:197], v[40:43]
	v_mfma_f32_16x16x32_bf16 v[28:31], v[144:147], v[208:211], v[28:31]
	v_mfma_f32_16x16x32_bf16 v[8:11], v[160:163], v[216:219], v[8:11]
	v_mfma_f32_16x16x32_bf16 v[44:47], v[144:147], v[194:197], v[44:47]
	v_mfma_f32_16x16x32_bf16 v[56:59], v[160:163], v[186:189], v[56:59]
	v_mfma_f32_16x16x32_bf16 v[12:15], v[144:147], v[216:219], v[12:15]
	v_mfma_f32_16x16x32_bf16 v[24:27], v[160:163], v[208:211], v[24:27]
	v_mfma_f32_16x16x32_bf16 v[60:63], v[156:159], v[190:193], v[60:63]
	v_mfma_f32_16x16x32_bf16 v[40:43], v[164:167], v[198:201], v[40:43]
	v_mfma_f32_16x16x32_bf16 v[28:31], v[156:159], v[212:215], v[28:31]
	v_mfma_f32_16x16x32_bf16 v[8:11], v[164:167], v[220:223], v[8:11]
	v_mfma_f32_16x16x32_bf16 v[44:47], v[156:159], v[198:201], v[44:47]
	v_mfma_f32_16x16x32_bf16 v[56:59], v[164:167], v[190:193], v[56:59]
	v_lshl_add_u64 v[202:203], v[226:227], 0, s[42:43]
	s_mov_b32 m0, s59
	s_nop 0
	global_load_lds_dwordx4 v[202:203], off
	v_mfma_f32_16x16x32_bf16 v[12:15], v[156:159], v[220:223], v[12:15]
	v_mfma_f32_16x16x32_bf16 v[24:27], v[164:167], v[212:215], v[24:27]
	s_setprio 0
	s_setprio 1
	v_mfma_f32_16x16x32_bf16 v[52:55], v[168:171], v[186:189], v[52:55]
	v_mfma_f32_16x16x32_bf16 v[32:35], v[176:179], v[194:197], v[32:35]
	v_mfma_f32_16x16x32_bf16 v[20:23], v[168:171], v[208:211], v[20:23]
	v_mfma_f32_16x16x32_bf16 v[0:3], v[176:179], v[216:219], v[0:3]
	v_mfma_f32_16x16x32_bf16 v[36:39], v[168:171], v[194:197], v[36:39]
	v_mfma_f32_16x16x32_bf16 v[48:51], v[176:179], v[186:189], v[48:51]
	v_mfma_f32_16x16x32_bf16 v[4:7], v[168:171], v[216:219], v[4:7]
	v_mfma_f32_16x16x32_bf16 v[16:19], v[176:179], v[208:211], v[16:19]
	v_mfma_f32_16x16x32_bf16 v[52:55], v[172:175], v[190:193], v[52:55]
	v_mfma_f32_16x16x32_bf16 v[32:35], v[182:185], v[198:201], v[32:35]
	v_mfma_f32_16x16x32_bf16 v[20:23], v[172:175], v[212:215], v[20:23]
	v_mfma_f32_16x16x32_bf16 v[0:3], v[182:185], v[220:223], v[0:3]
	v_mfma_f32_16x16x32_bf16 v[36:39], v[172:175], v[198:201], v[36:39]
	v_mfma_f32_16x16x32_bf16 v[48:51], v[182:185], v[190:193], v[48:51]
	v_lshl_add_u64 v[202:203], v[228:229], 0, s[42:43]
	s_mov_b32 m0, s60
	s_nop 0
	global_load_lds_dwordx4 v[202:203], off
	v_mfma_f32_16x16x32_bf16 v[4:7], v[172:175], v[220:223], v[4:7]
	v_mfma_f32_16x16x32_bf16 v[16:19], v[182:185], v[212:215], v[16:19]
	s_setprio 0
	s_barrier
	s_add_i32 s77, s77, 2
	s_add_u32 s75, s75, 0x100
	s_addc_u32 s76, s76, 0
	s_cmp_gt_u32 s77, 41
	s_mov_b64 s[50:51], s[52:53]
	s_cbranch_scc0 .LBB0_1035
	s_and_b64 vcc, exec, s[44:45]
	s_cbranch_vccz .LBB0_1038
	s_barrier

; #define PG8_STAGE(bufoff, gbase, voff) do { _Pragma("unroll") for (int _i = 0; _i < 2; ++_i) \
;         __builtin_amdgcn_global_load_lds((const unsigned*)((const char*)(gbase) + (voff)[_i]), (PG8_LAS unsigned*)(lds + (bufoff) + ldsw + _i * 8192), 16, 0, 0); } while (0)
; #define PG8_LDA(dst, b, h) do { _Pragma("unroll") for (int m = 0; m < 4; ++m) _Pragma("unroll") for (int k = 0; k < 2; ++k) dst[m][k] = *(const PG8_LAS bf16x8*)(lds + PG8_SA(b, h) + aoff + m * 2048 + k * 1024); } while (0)
; #define PG8_LDB(dst, b, h) do { _Pragma("unroll") for (int n = 0; n < 2; ++n) _Pragma("unroll") for (int k = 0; k < 2; ++k) dst[n][k] = *(const PG8_LAS bf16x8*)(lds + PG8_SB(b, h) + boff + n * 2048 + k * 1024); } while (0)
; #define PG8_BAR __builtin_amdgcn_s_barrier()
; template <class Epi, class Sched, bool ALIGN_EPI = false, bool SP2 = false>
; __device__ __forceinline__ void gemm_phase(PG8_LAS unsigned char* lds, const Gemm g, const Sched& S, const Epi& E) {
;     ...
;         const bool has_next = S.next(ui + 1, nxt);
;         const char* nA = has_next ? (const char*)g.A + (size_t)nxt.pm * tstep : cA; const char* nB = has_next ? (const char*)g.Bt + (size_t)nxt.pn * tstep : cB;
;         for (int t = 0; t < nt; t += 2) {
;             const bool last = (t == nt - 2);
;             const char* a1 = cA + (size_t)(t + 1) * kstep;
;             const char* a2 = last ? nA : cA + (size_t)(t + 2) * kstep; const char* b2 = last ? nB : cB + (size_t)(t + 2) * kstep;
;             const char* a3 = a2 + kstep; const char* b3 = b2 + kstep;
;             if (last && has_next) S.a_ready(nxt);
;             if constexpr (SP2) {
;             PG8_LDB(B0, 0, 0); PG8_LDB(B1, 0, 1); PG8_SCHED; PG8_LDA(At, 0, 0); PG8_STAGE(PG8_SA(1, 1), a1 + hstep, voffA);
;             PG8_WAIT_V(8); PG8_WAIT_L(0); PG8_BAR; PG8_MMA(0, 0, At, B0); PG8_MMA(0, 1, At, B1); PG8_BAR; PG8_SCHED;
;             PG8_LDA(At, 0, 1); PG8_STAGE(PG8_SB(0, 0), b2, voffB); PG8_STAGE(PG8_SB(0, 1), b2 + hstep, voffB); PG8_STAGE(PG8_SA(0, 0), a2, voffA);
;             PG8_WAIT_V(8); PG8_WAIT_L(0); PG8_BAR; PG8_MMA(1, 0, At, B0); PG8_MMA(1, 1, At, B1); PG8_BAR; PG8_SCHED;
;             PG8_LDB(B0, 1, 0); PG8_LDB(B1, 1, 1); PG8_SCHED; PG8_LDA(At, 1, 0); PG8_STAGE(PG8_SA(0, 1), a2 + hstep, voffA);
;             PG8_WAIT_V(8); PG8_WAIT_L(0); PG8_BAR; PG8_MMA(0, 0, At, B0); PG8_MMA(0, 1, At, B1); PG8_BAR; PG8_SCHED;
.LBB0_1118:
	s_ashr_i32 s45, s44, 31
	s_lshl_b64 s[48:49], s[44:45], 19
	s_add_u32 s48, s22, s48
	s_addc_u32 s49, s23, s49
	s_and_b64 s[50:51], s[10:11], exec
	s_cselect_b32 s45, s49, s55
	s_cselect_b32 s76, s48, s54
	s_ashr_i32 s43, s42, 31
	s_lshl_b64 s[50:51], s[42:43], 19
	s_add_u32 s50, s14, s50
	s_addc_u32 s51, s15, s51
	s_and_b64 s[58:59], s[10:11], exec
	s_cselect_b32 s43, s51, s57
	s_cselect_b32 s77, s50, s56
	s_add_u32 s54, s54, 0x40080
	s_addc_u32 s55, s55, 0
	s_add_u32 s82, s56, 0x100
	s_addc_u32 s83, s57, 0
	s_mov_b32 s84, -2
	ds_read_b128 v[144:147], v155
	ds_read_b128 v[148:151], v155 offset:1024
	ds_read_b128 v[160:163], v155 offset:2048
	ds_read_b128 v[164:167], v155 offset:3072
	ds_read_b128 v[168:171], v156
	ds_read_b128 v[172:175], v156 offset:1024
	ds_read_b128 v[176:179], v156 offset:2048
	ds_read_b128 v[182:185], v156 offset:3072
	s_add_u32 s56, s54, 0xfffc0080
	s_addc_u32 s57, s55, -1
	s_cmp_eq_u32 s84, 12
	s_cselect_b32 s59, s45, s57
	s_cselect_b32 s58, s76, s56
	s_cselect_b32 s57, s43, s83
	s_cselect_b32 s56, s77, s82
	v_lshl_add_u64 v[224:225], s[54:55], 0, v[136:137]
	s_add_i32 m0, s53, 0xc000
	ds_read_b128 v[186:189], v157
	ds_read_b128 v[190:193], v157 offset:1024
	ds_read_b128 v[194:197], v157 offset:2048
	ds_read_b128 v[198:201], v157 offset:3072
	ds_read_b128 v[208:211], v157 offset:4096
	ds_read_b128 v[212:215], v157 offset:5120
	ds_read_b128 v[216:219], v157 offset:6144
	ds_read_b128 v[220:223], v157 offset:7168
	global_load_lds_dwordx4 v[224:225], off
	v_lshl_add_u64 v[224:225], s[54:55], 0, v[138:139]
	s_add_i32 m0, s53, 0xe000
	s_nop 0
	global_load_lds_dwordx4 v[224:225], off
	s_waitcnt vmcnt(8)
	s_waitcnt lgkmcnt(0)
	s_barrier
	s_setprio 1
	s_waitcnt lgkmcnt(0)
	v_mfma_f32_16x16x32_bf16 v[124:127], v[144:147], v[186:189], 0
	v_mfma_f32_16x16x32_bf16 v[104:107], v[160:163], v[194:197], 0
	v_mfma_f32_16x16x32_bf16 v[92:95], v[144:147], v[208:211], 0
	v_mfma_f32_16x16x32_bf16 v[72:75], v[160:163], v[216:219], 0
	v_mfma_f32_16x16x32_bf16 v[108:111], v[144:147], v[194:197], 0
	v_mfma_f32_16x16x32_bf16 v[120:123], v[160:163], v[186:189], 0
	v_mfma_f32_16x16x32_bf16 v[76:79], v[144:147], v[216:219], 0
	v_mfma_f32_16x16x32_bf16 v[88:91], v[160:163], v[208:211], 0
	v_mfma_f32_16x16x32_bf16 v[124:127], v[148:151], v[190:193], v[124:127]
	v_mfma_f32_16x16x32_bf16 v[104:107], v[164:167], v[198:201], v[104:107]
	v_mfma_f32_16x16x32_bf16 v[92:95], v[148:151], v[212:215], v[92:95]
	v_mfma_f32_16x16x32_bf16 v[72:75], v[164:167], v[220:223], v[72:75]
	v_mfma_f32_16x16x32_bf16 v[108:111], v[148:151], v[198:201], v[108:111]
	v_mfma_f32_16x16x32_bf16 v[120:123], v[164:167], v[190:193], v[120:123]
	v_mfma_f32_16x16x32_bf16 v[76:79], v[148:151], v[220:223], v[76:79]
	v_mfma_f32_16x16x32_bf16 v[88:91], v[164:167], v[212:215], v[88:91]
	s_setprio 0
	s_setprio 1
	v_mfma_f32_16x16x32_bf16 v[116:119], v[168:171], v[186:189], 0
	v_mfma_f32_16x16x32_bf16 v[96:99], v[176:179], v[194:197], 0
	v_mfma_f32_16x16x32_bf16 v[84:87], v[168:171], v[208:211], 0
	v_mfma_f32_16x16x32_bf16 v[64:67], v[176:179], v[216:219], 0
	v_mfma_f32_16x16x32_bf16 v[100:103], v[168:171], v[194:197], 0
	v_mfma_f32_16x16x32_bf16 v[112:115], v[176:179], v[186:189], 0
	v_mfma_f32_16x16x32_bf16 v[68:71], v[168:171], v[216:219], 0
	v_mfma_f32_16x16x32_bf16 v[80:83], v[176:179], v[208:211], 0
	v_mfma_f32_16x16x32_bf16 v[116:119], v[172:175], v[190:193], v[116:119]
	v_mfma_f32_16x16x32_bf16 v[96:99], v[182:185], v[198:201], v[96:99]
	v_mfma_f32_16x16x32_bf16 v[84:87], v[172:175], v[212:215], v[84:87]
	v_mfma_f32_16x16x32_bf16 v[64:67], v[182:185], v[220:223], v[64:67]
	v_mfma_f32_16x16x32_bf16 v[100:103], v[172:175], v[198:201], v[100:103]
	v_mfma_f32_16x16x32_bf16 v[112:115], v[182:185], v[190:193], v[112:115]
	v_mfma_f32_16x16x32_bf16 v[68:71], v[172:175], v[220:223], v[68:71]
	v_mfma_f32_16x16x32_bf16 v[80:83], v[182:185], v[212:215], v[80:83]
	s_setprio 0
	s_barrier
	s_add_i32 s78, s66, s33
	v_lshl_add_u64 v[224:225], s[56:57], 0, v[132:133]
	s_mov_b32 m0, s78
	ds_read_b128 v[186:189], v157 offset:16384
	ds_read_b128 v[190:193], v157 offset:17408
	ds_read_b128 v[194:197], v157 offset:18432
	ds_read_b128 v[198:201], v157 offset:19456
	ds_read_b128 v[208:211], v157 offset:20480
	ds_read_b128 v[212:215], v157 offset:21504
	ds_read_b128 v[216:219], v157 offset:22528
	ds_read_b128 v[220:223], v157 offset:23552
	global_load_lds_dwordx4 v[224:225], off
	s_add_i32 m0, s78, 0x2000
	s_add_u32 s78, s56, 0x40000
	v_lshl_add_u64 v[226:227], s[56:57], 0, v[128:129]
	s_addc_u32 s79, s57, 0
	s_add_i32 s85, s67, s33
	global_load_lds_dwordx4 v[226:227], off
	v_lshl_add_u64 v[228:229], s[78:79], 0, v[132:133]
	s_mov_b32 m0, s85
	global_load_lds_dwordx4 v[228:229], off
	v_lshl_add_u64 v[228:229], s[78:79], 0, v[128:129]
	s_add_i32 m0, s85, 0x2000
	s_nop 0
	global_load_lds_dwordx4 v[228:229], off
	s_waitcnt vmcnt(6)
	s_waitcnt lgkmcnt(0)
	s_barrier
; #define PG8_STAGE(bufoff, gbase, voff) do { _Pragma("unroll") for (int _i = 0; _i < 2; ++_i) \
;         __builtin_amdgcn_global_load_lds((const unsigned*)((const char*)(gbase) + (voff)[_i]), (PG8_LAS unsigned*)(lds + (bufoff) + ldsw + _i * 8192), 16, 0, 0); } while (0)
; #define PG8_LDA(dst, b, h) do { _Pragma("unroll") for (int m = 0; m < 4; ++m) _Pragma("unroll") for (int k = 0; k < 2; ++k) dst[m][k] = *(const PG8_LAS bf16x8*)(lds + PG8_SA(b, h) + aoff + m * 2048 + k * 1024); } while (0)
; #define PG8_LDB(dst, b, h) do { _Pragma("unroll") for (int n = 0; n < 2; ++n) _Pragma("unroll") for (int k = 0; k < 2; ++k) dst[n][k] = *(const PG8_LAS bf16x8*)(lds + PG8_SB(b, h) + boff + n * 2048 + k * 1024); } while (0)
; #define PG8_MMA(ai, bj, At, Bt) do { __builtin_amdgcn_s_setprio(1); _Pragma("unroll") for (int m = 0; m < 4; ++m) _Pragma("unroll") for (int n = 0; n < 2; ++n) _Pragma("unroll") for (int k = 0; k < 2; ++k) \
;         acc[ai][bj][m][n] = __builtin_amdgcn_mfma_f32_16x16x32_bf16(Bt[n][k], At[m][k], acc[ai][bj][m][n], 0, 0, 0); __builtin_amdgcn_s_setprio(0); } while (0)
; #define PG8_WAIT_V(n) asm volatile("s_waitcnt vmcnt(" #n ")" ::: "memory")
; #define PG8_WAIT_L(n) asm volatile("s_waitcnt lgkmcnt(" #n ")" ::: "memory")
; #define PG8_BAR __builtin_amdgcn_s_barrier()
; #define PG8_SCHED __builtin_amdgcn_sched_barrier(0)
; template <class Epi, class Sched, bool ALIGN_EPI = false, bool SP2 = false>
; __device__ __forceinline__ void gemm_phase(PG8_LAS unsigned char* lds, const Gemm g, const Sched& S, const Epi& E) {
;     ...
;             PG8_LDA(At, 0, 1); PG8_STAGE(PG8_SB(0, 0), b2, voffB); PG8_STAGE(PG8_SB(0, 1), b2 + hstep, voffB); PG8_STAGE(PG8_SA(0, 0), a2, voffA);
;             PG8_WAIT_V(8); PG8_WAIT_L(0); PG8_BAR; PG8_MMA(1, 0, At, B0); PG8_MMA(1, 1, At, B1); PG8_BAR; PG8_SCHED;
;             PG8_LDB(B0, 1, 0); PG8_LDB(B1, 1, 1); PG8_SCHED; PG8_LDA(At, 1, 0); PG8_STAGE(PG8_SA(0, 1), a2 + hstep, voffA);
;             PG8_WAIT_V(8); PG8_WAIT_L(0); PG8_BAR; PG8_MMA(0, 0, At, B0); PG8_MMA(0, 1, At, B1); PG8_BAR; PG8_SCHED;
	s_setprio 1
	s_waitcnt lgkmcnt(0)
	v_mfma_f32_16x16x32_bf16 v[60:63], v[144:147], v[186:189], 0
	v_mfma_f32_16x16x32_bf16 v[40:43], v[160:163], v[194:197], 0
	v_mfma_f32_16x16x32_bf16 v[28:31], v[144:147], v[208:211], 0
	v_mfma_f32_16x16x32_bf16 v[8:11], v[160:163], v[216:219], 0
	v_mfma_f32_16x16x32_bf16 v[44:47], v[144:147], v[194:197], 0
	v_mfma_f32_16x16x32_bf16 v[56:59], v[160:163], v[186:189], 0
	v_mfma_f32_16x16x32_bf16 v[12:15], v[144:147], v[216:219], 0
	v_mfma_f32_16x16x32_bf16 v[24:27], v[160:163], v[208:211], 0
	v_mfma_f32_16x16x32_bf16 v[60:63], v[148:151], v[190:193], v[60:63]
	v_mfma_f32_16x16x32_bf16 v[40:43], v[164:167], v[198:201], v[40:43]
	v_mfma_f32_16x16x32_bf16 v[28:31], v[148:151], v[212:215], v[28:31]
	v_mfma_f32_16x16x32_bf16 v[8:11], v[164:167], v[220:223], v[8:11]
	v_mfma_f32_16x16x32_bf16 v[44:47], v[148:151], v[198:201], v[44:47]
	v_mfma_f32_16x16x32_bf16 v[56:59], v[164:167], v[190:193], v[56:59]
	v_lshl_add_u64 v[228:229], s[58:59], 0, v[134:135]
	s_mov_b32 m0, s53
	s_nop 0
	global_load_lds_dwordx4 v[228:229], off
	v_mfma_f32_16x16x32_bf16 v[12:15], v[148:151], v[220:223], v[12:15]
	v_mfma_f32_16x16x32_bf16 v[24:27], v[164:167], v[212:215], v[24:27]
	s_setprio 0
	s_setprio 1
	v_mfma_f32_16x16x32_bf16 v[52:55], v[168:171], v[186:189], 0
	v_mfma_f32_16x16x32_bf16 v[32:35], v[176:179], v[194:197], 0
	v_mfma_f32_16x16x32_bf16 v[20:23], v[168:171], v[208:211], 0
	v_mfma_f32_16x16x32_bf16 v[0:3], v[176:179], v[216:219], 0
	v_mfma_f32_16x16x32_bf16 v[36:39], v[168:171], v[194:197], 0
	v_mfma_f32_16x16x32_bf16 v[48:51], v[176:179], v[186:189], 0
	v_mfma_f32_16x16x32_bf16 v[4:7], v[168:171], v[216:219], 0
	v_mfma_f32_16x16x32_bf16 v[16:19], v[176:179], v[208:211], 0
	v_mfma_f32_16x16x32_bf16 v[52:55], v[172:175], v[190:193], v[52:55]
	v_mfma_f32_16x16x32_bf16 v[32:35], v[182:185], v[198:201], v[32:35]
	v_mfma_f32_16x16x32_bf16 v[20:23], v[172:175], v[212:215], v[20:23]
	v_mfma_f32_16x16x32_bf16 v[0:3], v[182:185], v[220:223], v[0:3]
	v_mfma_f32_16x16x32_bf16 v[36:39], v[172:175], v[198:201], v[36:39]
	v_mfma_f32_16x16x32_bf16 v[48:51], v[182:185], v[190:193], v[48:51]
	v_lshl_add_u64 v[230:231], s[58:59], 0, v[130:131]
	s_mov_b32 m0, s60
	s_nop 0
	global_load_lds_dwordx4 v[230:231], off
	v_mfma_f32_16x16x32_bf16 v[4:7], v[172:175], v[220:223], v[4:7]
	v_mfma_f32_16x16x32_bf16 v[16:19], v[182:185], v[212:215], v[16:19]
	s_setprio 0
	s_barrier
	s_add_i32 s78, 0, 0x18000
	v_add_u32_e32 v159, s78, v153
	s_add_i32 s79, 0, 0x1c000
	ds_read_b128 v[144:147], v159
	ds_read_b128 v[148:151], v159 offset:1024
	ds_read_b128 v[160:163], v159 offset:2048
	ds_read_b128 v[164:167], v159 offset:3072
	v_add_u32_e32 v159, s79, v153
	ds_read_b128 v[168:171], v159
	ds_read_b128 v[172:175], v159 offset:1024
	ds_read_b128 v[176:179], v159 offset:2048
	ds_read_b128 v[182:185], v159 offset:3072
	s_add_u32 s58, s58, 0x40000
	s_addc_u32 s59, s59, 0
	s_mov_b32 m0, s61
	v_lshl_add_u64 v[232:233], s[58:59], 0, v[134:135]
	ds_read_b128 v[186:189], v157 offset:32768
	ds_read_b128 v[190:193], v157 offset:33792
	ds_read_b128 v[194:197], v157 offset:34816
	ds_read_b128 v[198:201], v157 offset:35840
	ds_read_b128 v[208:211], v157 offset:36864
	ds_read_b128 v[212:215], v157 offset:37888
	ds_read_b128 v[216:219], v157 offset:38912
	ds_read_b128 v[220:223], v157 offset:39936
	global_load_lds_dwordx4 v[232:233], off
	v_lshl_add_u64 v[232:233], s[58:59], 0, v[130:131]
	s_mov_b32 m0, s62
	s_nop 0
	global_load_lds_dwordx4 v[232:233], off
	s_waitcnt vmcnt(8)
	s_waitcnt lgkmcnt(0)
	s_barrier
	s_setprio 1
	s_waitcnt lgkmcnt(0)
	v_mfma_f32_16x16x32_bf16 v[124:127], v[144:147], v[186:189], v[124:127]
	v_mfma_f32_16x16x32_bf16 v[104:107], v[160:163], v[194:197], v[104:107]
	v_mfma_f32_16x16x32_bf16 v[92:95], v[144:147], v[208:211], v[92:95]
	v_mfma_f32_16x16x32_bf16 v[72:75], v[160:163], v[216:219], v[72:75]
	v_mfma_f32_16x16x32_bf16 v[108:111], v[144:147], v[194:197], v[108:111]
	v_mfma_f32_16x16x32_bf16 v[120:123], v[160:163], v[186:189], v[120:123]
	v_mfma_f32_16x16x32_bf16 v[76:79], v[144:147], v[216:219], v[76:79]
	v_mfma_f32_16x16x32_bf16 v[88:91], v[160:163], v[208:211], v[88:91]
	v_mfma_f32_16x16x32_bf16 v[124:127], v[148:151], v[190:193], v[124:127]
	v_mfma_f32_16x16x32_bf16 v[104:107], v[164:167], v[198:201], v[104:107]
	v_mfma_f32_16x16x32_bf16 v[92:95], v[148:151], v[212:215], v[92:95]
	v_mfma_f32_16x16x32_bf16 v[72:75], v[164:167], v[220:223], v[72:75]
	v_mfma_f32_16x16x32_bf16 v[108:111], v[148:151], v[198:201], v[108:111]
	v_mfma_f32_16x16x32_bf16 v[120:123], v[164:167], v[190:193], v[120:123]
	v_mfma_f32_16x16x32_bf16 v[76:79], v[148:151], v[220:223], v[76:79]
	v_mfma_f32_16x16x32_bf16 v[88:91], v[164:167], v[212:215], v[88:91]
	s_setprio 0
	s_setprio 1
	v_mfma_f32_16x16x32_bf16 v[116:119], v[168:171], v[186:189], v[116:119]
	v_mfma_f32_16x16x32_bf16 v[96:99], v[176:179], v[194:197], v[96:99]
	v_mfma_f32_16x16x32_bf16 v[84:87], v[168:171], v[208:211], v[84:87]
	v_mfma_f32_16x16x32_bf16 v[64:67], v[176:179], v[216:219], v[64:67]
	v_mfma_f32_16x16x32_bf16 v[100:103], v[168:171], v[194:197], v[100:103]
	v_mfma_f32_16x16x32_bf16 v[112:115], v[176:179], v[186:189], v[112:115]
	v_mfma_f32_16x16x32_bf16 v[68:71], v[168:171], v[216:219], v[68:71]
	v_mfma_f32_16x16x32_bf16 v[80:83], v[176:179], v[208:211], v[80:83]
	v_mfma_f32_16x16x32_bf16 v[116:119], v[172:175], v[190:193], v[116:119]
	v_mfma_f32_16x16x32_bf16 v[96:99], v[182:185], v[198:201], v[96:99]
	v_mfma_f32_16x16x32_bf16 v[84:87], v[172:175], v[212:215], v[84:87]
	v_mfma_f32_16x16x32_bf16 v[64:67], v[182:185], v[220:223], v[64:67]
	v_mfma_f32_16x16x32_bf16 v[100:103], v[172:175], v[198:201], v[100:103]
	v_mfma_f32_16x16x32_bf16 v[112:115], v[182:185], v[190:193], v[112:115]
	v_mfma_f32_16x16x32_bf16 v[68:71], v[172:175], v[220:223], v[68:71]
	v_mfma_f32_16x16x32_bf16 v[80:83], v[182:185], v[212:215], v[80:83]
	s_setprio 0
	s_barrier
; #define PG8_STAGE(bufoff, gbase, voff) do { _Pragma("unroll") for (int _i = 0; _i < 2; ++_i) \
;         __builtin_amdgcn_global_load_lds((const unsigned*)((const char*)(gbase) + (voff)[_i]), (PG8_LAS unsigned*)(lds + (bufoff) + ldsw + _i * 8192), 16, 0, 0); } while (0)
; #define PG8_LDA(dst, b, h) do { _Pragma("unroll") for (int m = 0; m < 4; ++m) _Pragma("unroll") for (int k = 0; k < 2; ++k) dst[m][k] = *(const PG8_LAS bf16x8*)(lds + PG8_SA(b, h) + aoff + m * 2048 + k * 1024); } while (0)
; #define PG8_LDB(dst, b, h) do { _Pragma("unroll") for (int n = 0; n < 2; ++n) _Pragma("unroll") for (int k = 0; k < 2; ++k) dst[n][k] = *(const PG8_LAS bf16x8*)(lds + PG8_SB(b, h) + boff + n * 2048 + k * 1024); } while (0)
; #define PG8_MMA(ai, bj, At, Bt) do { __builtin_amdgcn_s_setprio(1); _Pragma("unroll") for (int m = 0; m < 4; ++m) _Pragma("unroll") for (int n = 0; n < 2; ++n) _Pragma("unroll") for (int k = 0; k < 2; ++k) \
;         acc[ai][bj][m][n] = __builtin_amdgcn_mfma_f32_16x16x32_bf16(Bt[n][k], At[m][k], acc[ai][bj][m][n], 0, 0, 0); __builtin_amdgcn_s_setprio(0); } while (0)
; #define PG8_WAIT_V(n) asm volatile("s_waitcnt vmcnt(" #n ")" ::: "memory")
; template <class Epi, class Sched, bool ALIGN_EPI = false, bool SP2 = false>
; __device__ __forceinline__ void gemm_phase(PG8_LAS unsigned char* lds, const Gemm g, const Sched& S, const Epi& E) {
;     ...
;             PG8_LDB(B0, 0, 0); PG8_LDB(B1, 0, 1); PG8_SCHED; PG8_LDA(At, 0, 0); PG8_STAGE(PG8_SA(1, 1), a1 + hstep, voffA);
;             PG8_WAIT_V(8); PG8_WAIT_L(0); PG8_BAR; PG8_MMA(0, 0, At, B0); PG8_MMA(0, 1, At, B1); PG8_BAR; PG8_SCHED;
;             PG8_LDA(At, 0, 1); PG8_STAGE(PG8_SB(0, 0), b2, voffB); PG8_STAGE(PG8_SB(0, 1), b2 + hstep, voffB); PG8_STAGE(PG8_SA(0, 0), a2, voffA);
;             PG8_WAIT_V(8); PG8_WAIT_L(0); PG8_BAR; PG8_MMA(1, 0, At, B0); PG8_MMA(1, 1, At, B1); PG8_BAR; PG8_SCHED;
;             PG8_LDB(B0, 1, 0); PG8_LDB(B1, 1, 1); PG8_SCHED; PG8_LDA(At, 1, 0); PG8_STAGE(PG8_SA(0, 1), a2 + hstep, voffA);
;             PG8_WAIT_V(8); PG8_WAIT_L(0); PG8_BAR; PG8_MMA(0, 0, At, B0); PG8_MMA(0, 1, At, B1); PG8_BAR; PG8_SCHED;
;             PG8_LDA(At, 1, 1); PG8_STAGE(PG8_SB(1, 0), b3, voffB); PG8_STAGE(PG8_SB(1, 1), b3 + hstep, voffB); PG8_STAGE(PG8_SA(1, 0), a3, voffA);
;             PG8_WAIT_V(8); PG8_WAIT_L(0); PG8_BAR; PG8_MMA(1, 0, At, B0); PG8_MMA(1, 1, At, B1); PG8_BAR; PG8_SCHED;
	s_add_i32 s58, s78, s33
	v_lshl_add_u64 v[224:225], v[224:225], 0, s[12:13]
	s_mov_b32 m0, s58
	ds_read_b128 v[186:189], v157 offset:49152
	ds_read_b128 v[190:193], v157 offset:50176
	ds_read_b128 v[194:197], v157 offset:51200
	ds_read_b128 v[198:201], v157 offset:52224
	ds_read_b128 v[208:211], v157 offset:53248
	ds_read_b128 v[212:215], v157 offset:54272
	ds_read_b128 v[216:219], v157 offset:55296
	ds_read_b128 v[220:223], v157 offset:56320
	global_load_lds_dwordx4 v[224:225], off
	s_add_i32 m0, s58, 0x2000
	s_add_u32 s56, s56, 0x40080
	v_lshl_add_u64 v[224:225], v[226:227], 0, s[12:13]
	s_addc_u32 s57, s57, 0
	s_add_i32 s58, s79, s33
	global_load_lds_dwordx4 v[224:225], off
	v_lshl_add_u64 v[224:225], s[56:57], 0, v[132:133]
	s_mov_b32 m0, s58
	s_nop 0
	global_load_lds_dwordx4 v[224:225], off
	v_lshl_add_u64 v[224:225], s[56:57], 0, v[128:129]
	s_add_i32 m0, s58, 0x2000
	s_nop 0
	global_load_lds_dwordx4 v[224:225], off
	s_waitcnt vmcnt(6)
	s_waitcnt lgkmcnt(0)
	s_barrier
	s_setprio 1
	s_waitcnt lgkmcnt(0)
	v_mfma_f32_16x16x32_bf16 v[60:63], v[144:147], v[186:189], v[60:63]
	v_mfma_f32_16x16x32_bf16 v[40:43], v[160:163], v[194:197], v[40:43]
	v_mfma_f32_16x16x32_bf16 v[28:31], v[144:147], v[208:211], v[28:31]
	v_mfma_f32_16x16x32_bf16 v[8:11], v[160:163], v[216:219], v[8:11]
	v_mfma_f32_16x16x32_bf16 v[44:47], v[144:147], v[194:197], v[44:47]
	v_mfma_f32_16x16x32_bf16 v[56:59], v[160:163], v[186:189], v[56:59]
	v_mfma_f32_16x16x32_bf16 v[12:15], v[144:147], v[216:219], v[12:15]
	v_mfma_f32_16x16x32_bf16 v[24:27], v[160:163], v[208:211], v[24:27]
	v_mfma_f32_16x16x32_bf16 v[60:63], v[148:151], v[190:193], v[60:63]
	v_mfma_f32_16x16x32_bf16 v[40:43], v[164:167], v[198:201], v[40:43]
	v_mfma_f32_16x16x32_bf16 v[28:31], v[148:151], v[212:215], v[28:31]
	v_mfma_f32_16x16x32_bf16 v[8:11], v[164:167], v[220:223], v[8:11]
	v_mfma_f32_16x16x32_bf16 v[44:47], v[148:151], v[198:201], v[44:47]
	v_mfma_f32_16x16x32_bf16 v[56:59], v[164:167], v[190:193], v[56:59]
	v_lshl_add_u64 v[224:225], v[228:229], 0, s[12:13]
	s_mov_b32 m0, s64
	s_nop 0
	global_load_lds_dwordx4 v[224:225], off
	v_mfma_f32_16x16x32_bf16 v[12:15], v[148:151], v[220:223], v[12:15]
	v_mfma_f32_16x16x32_bf16 v[24:27], v[164:167], v[212:215], v[24:27]
	s_setprio 0
	s_setprio 1
	v_mfma_f32_16x16x32_bf16 v[52:55], v[168:171], v[186:189], v[52:55]
	v_mfma_f32_16x16x32_bf16 v[32:35], v[176:179], v[194:197], v[32:35]
	v_mfma_f32_16x16x32_bf16 v[20:23], v[168:171], v[208:211], v[20:23]
	v_mfma_f32_16x16x32_bf16 v[0:3], v[176:179], v[216:219], v[0:3]
	v_mfma_f32_16x16x32_bf16 v[36:39], v[168:171], v[194:197], v[36:39]
	v_mfma_f32_16x16x32_bf16 v[48:51], v[176:179], v[186:189], v[48:51]
	v_mfma_f32_16x16x32_bf16 v[4:7], v[168:171], v[216:219], v[4:7]
	v_mfma_f32_16x16x32_bf16 v[16:19], v[176:179], v[208:211], v[16:19]
	v_mfma_f32_16x16x32_bf16 v[52:55], v[172:175], v[190:193], v[52:55]
	v_mfma_f32_16x16x32_bf16 v[32:35], v[182:185], v[198:201], v[32:35]
	v_mfma_f32_16x16x32_bf16 v[20:23], v[172:175], v[212:215], v[20:23]
	v_mfma_f32_16x16x32_bf16 v[0:3], v[182:185], v[220:223], v[0:3]
	v_mfma_f32_16x16x32_bf16 v[36:39], v[172:175], v[198:201], v[36:39]
	v_mfma_f32_16x16x32_bf16 v[48:51], v[182:185], v[190:193], v[48:51]
	v_lshl_add_u64 v[224:225], v[230:231], 0, s[12:13]
	s_mov_b32 m0, s65
	s_nop 0
	global_load_lds_dwordx4 v[224:225], off
	v_mfma_f32_16x16x32_bf16 v[4:7], v[172:175], v[220:223], v[4:7]
	v_mfma_f32_16x16x32_bf16 v[16:19], v[182:185], v[212:215], v[16:19]
	s_setprio 0
	s_barrier
	s_add_i32 s84, s84, 2
	s_add_u32 s54, s54, 0x100
	s_addc_u32 s55, s55, 0
	s_add_u32 s82, s82, 0x100
	s_addc_u32 s83, s83, 0
.LBB0_1119:
	ds_read_b128 v[144:147], v155
	ds_read_b128 v[148:151], v155 offset:1024
	ds_read_b128 v[160:163], v155 offset:2048
	ds_read_b128 v[164:167], v155 offset:3072
	ds_read_b128 v[168:171], v156
	ds_read_b128 v[172:175], v156 offset:1024
	ds_read_b128 v[176:179], v156 offset:2048
	ds_read_b128 v[182:185], v156 offset:3072
	s_add_u32 s56, s54, 0xfffc0080
	s_addc_u32 s57, s55, -1
	s_cmp_eq_u32 s84, 12
	s_cselect_b32 s59, s45, s57
	s_cselect_b32 s58, s76, s56
	s_cselect_b32 s57, s43, s83
	s_cselect_b32 s56, s77, s82
	v_lshl_add_u64 v[224:225], s[54:55], 0, v[136:137]
	s_add_i32 m0, s53, 0xc000
	ds_read_b128 v[186:189], v157
	ds_read_b128 v[190:193], v157 offset:1024
	ds_read_b128 v[194:197], v157 offset:2048
	ds_read_b128 v[198:201], v157 offset:3072
	ds_read_b128 v[208:211], v157 offset:4096
	ds_read_b128 v[212:215], v157 offset:5120
	ds_read_b128 v[216:219], v157 offset:6144
	ds_read_b128 v[220:223], v157 offset:7168
	global_load_lds_dwordx4 v[224:225], off
	v_lshl_add_u64 v[224:225], s[54:55], 0, v[138:139]
	s_add_i32 m0, s53, 0xe000
	s_nop 0
	global_load_lds_dwordx4 v[224:225], off
	s_waitcnt vmcnt(8)
	s_waitcnt lgkmcnt(0)
	s_barrier
; #define PG8_STAGE(bufoff, gbase, voff) do { _Pragma("unroll") for (int _i = 0; _i < 2; ++_i) \
;         __builtin_amdgcn_global_load_lds((const unsigned*)((const char*)(gbase) + (voff)[_i]), (PG8_LAS unsigned*)(lds + (bufoff) + ldsw + _i * 8192), 16, 0, 0); } while (0)
; #define PG8_LDA(dst, b, h) do { _Pragma("unroll") for (int m = 0; m < 4; ++m) _Pragma("unroll") for (int k = 0; k < 2; ++k) dst[m][k] = *(const PG8_LAS bf16x8*)(lds + PG8_SA(b, h) + aoff + m * 2048 + k * 1024); } while (0)
; #define PG8_MMA(ai, bj, At, Bt) do { __builtin_amdgcn_s_setprio(1); _Pragma("unroll") for (int m = 0; m < 4; ++m) _Pragma("unroll") for (int n = 0; n < 2; ++n) _Pragma("unroll") for (int k = 0; k < 2; ++k) \
;         acc[ai][bj][m][n] = __builtin_amdgcn_mfma_f32_16x16x32_bf16(Bt[n][k], At[m][k], acc[ai][bj][m][n], 0, 0, 0); __builtin_amdgcn_s_setprio(0); } while (0)
; #define PG8_WAIT_V(n) asm volatile("s_waitcnt vmcnt(" #n ")" ::: "memory")
; #define PG8_WAIT_L(n) asm volatile("s_waitcnt lgkmcnt(" #n ")" ::: "memory")
; #define PG8_BAR __builtin_amdgcn_s_barrier()
; #define PG8_SCHED __builtin_amdgcn_sched_barrier(0)
; template <class Epi, class Sched, bool ALIGN_EPI = false, bool SP2 = false>
; __device__ __forceinline__ void gemm_phase(PG8_LAS unsigned char* lds, const Gemm g, const Sched& S, const Epi& E) {
;     ...
;             PG8_WAIT_V(8); PG8_WAIT_L(0); PG8_BAR; PG8_MMA(0, 0, At, B0); PG8_MMA(0, 1, At, B1); PG8_BAR; PG8_SCHED;
;             PG8_LDA(At, 0, 1); PG8_STAGE(PG8_SB(0, 0), b2, voffB); PG8_STAGE(PG8_SB(0, 1), b2 + hstep, voffB); PG8_STAGE(PG8_SA(0, 0), a2, voffA);
;             PG8_WAIT_V(8); PG8_WAIT_L(0); PG8_BAR; PG8_MMA(1, 0, At, B0); PG8_MMA(1, 1, At, B1); PG8_BAR; PG8_SCHED;
	s_setprio 1
	s_waitcnt lgkmcnt(0)
	v_mfma_f32_16x16x32_bf16 v[124:127], v[144:147], v[186:189], v[124:127]
	v_mfma_f32_16x16x32_bf16 v[104:107], v[160:163], v[194:197], v[104:107]
	v_mfma_f32_16x16x32_bf16 v[92:95], v[144:147], v[208:211], v[92:95]
	v_mfma_f32_16x16x32_bf16 v[72:75], v[160:163], v[216:219], v[72:75]
	v_mfma_f32_16x16x32_bf16 v[108:111], v[144:147], v[194:197], v[108:111]
	v_mfma_f32_16x16x32_bf16 v[120:123], v[160:163], v[186:189], v[120:123]
	v_mfma_f32_16x16x32_bf16 v[76:79], v[144:147], v[216:219], v[76:79]
	v_mfma_f32_16x16x32_bf16 v[88:91], v[160:163], v[208:211], v[88:91]
	v_mfma_f32_16x16x32_bf16 v[124:127], v[148:151], v[190:193], v[124:127]
	v_mfma_f32_16x16x32_bf16 v[104:107], v[164:167], v[198:201], v[104:107]
	v_mfma_f32_16x16x32_bf16 v[92:95], v[148:151], v[212:215], v[92:95]
	v_mfma_f32_16x16x32_bf16 v[72:75], v[164:167], v[220:223], v[72:75]
	v_mfma_f32_16x16x32_bf16 v[108:111], v[148:151], v[198:201], v[108:111]
	v_mfma_f32_16x16x32_bf16 v[120:123], v[164:167], v[190:193], v[120:123]
	v_mfma_f32_16x16x32_bf16 v[76:79], v[148:151], v[220:223], v[76:79]
	v_mfma_f32_16x16x32_bf16 v[88:91], v[164:167], v[212:215], v[88:91]
	s_setprio 0
	s_setprio 1
	v_mfma_f32_16x16x32_bf16 v[116:119], v[168:171], v[186:189], v[116:119]
	v_mfma_f32_16x16x32_bf16 v[96:99], v[176:179], v[194:197], v[96:99]
	v_mfma_f32_16x16x32_bf16 v[84:87], v[168:171], v[208:211], v[84:87]
	v_mfma_f32_16x16x32_bf16 v[64:67], v[176:179], v[216:219], v[64:67]
	v_mfma_f32_16x16x32_bf16 v[100:103], v[168:171], v[194:197], v[100:103]
	v_mfma_f32_16x16x32_bf16 v[112:115], v[176:179], v[186:189], v[112:115]
	v_mfma_f32_16x16x32_bf16 v[68:71], v[168:171], v[216:219], v[68:71]
	v_mfma_f32_16x16x32_bf16 v[80:83], v[176:179], v[208:211], v[80:83]
	v_mfma_f32_16x16x32_bf16 v[116:119], v[172:175], v[190:193], v[116:119]
	v_mfma_f32_16x16x32_bf16 v[96:99], v[182:185], v[198:201], v[96:99]
	v_mfma_f32_16x16x32_bf16 v[84:87], v[172:175], v[212:215], v[84:87]
	v_mfma_f32_16x16x32_bf16 v[64:67], v[182:185], v[220:223], v[64:67]
	v_mfma_f32_16x16x32_bf16 v[100:103], v[172:175], v[198:201], v[100:103]
	v_mfma_f32_16x16x32_bf16 v[112:115], v[182:185], v[190:193], v[112:115]
	v_mfma_f32_16x16x32_bf16 v[68:71], v[172:175], v[220:223], v[68:71]
	v_mfma_f32_16x16x32_bf16 v[80:83], v[182:185], v[212:215], v[80:83]
	s_setprio 0
	s_barrier
	s_add_i32 s78, s66, s33
	v_lshl_add_u64 v[224:225], s[56:57], 0, v[132:133]
	s_mov_b32 m0, s78
	ds_read_b128 v[186:189], v157 offset:16384
	ds_read_b128 v[190:193], v157 offset:17408
	ds_read_b128 v[194:197], v157 offset:18432
	ds_read_b128 v[198:201], v157 offset:19456
	ds_read_b128 v[208:211], v157 offset:20480
	ds_read_b128 v[212:215], v157 offset:21504
	ds_read_b128 v[216:219], v157 offset:22528
	ds_read_b128 v[220:223], v157 offset:23552
	global_load_lds_dwordx4 v[224:225], off
	s_add_i32 m0, s78, 0x2000
	s_add_u32 s78, s56, 0x40000
	v_lshl_add_u64 v[226:227], s[56:57], 0, v[128:129]
	s_addc_u32 s79, s57, 0
	s_add_i32 s85, s67, s33
	global_load_lds_dwordx4 v[226:227], off
	v_lshl_add_u64 v[228:229], s[78:79], 0, v[132:133]
	s_mov_b32 m0, s85
	global_load_lds_dwordx4 v[228:229], off
	v_lshl_add_u64 v[228:229], s[78:79], 0, v[128:129]
	s_add_i32 m0, s85, 0x2000
	s_nop 0
	global_load_lds_dwordx4 v[228:229], off
	s_waitcnt vmcnt(6)
	s_waitcnt lgkmcnt(0)
	s_barrier
	s_setprio 1
	s_waitcnt lgkmcnt(0)
	v_mfma_f32_16x16x32_bf16 v[60:63], v[144:147], v[186:189], v[60:63]
	v_mfma_f32_16x16x32_bf16 v[40:43], v[160:163], v[194:197], v[40:43]
	v_mfma_f32_16x16x32_bf16 v[28:31], v[144:147], v[208:211], v[28:31]
	v_mfma_f32_16x16x32_bf16 v[8:11], v[160:163], v[216:219], v[8:11]
	v_mfma_f32_16x16x32_bf16 v[44:47], v[144:147], v[194:197], v[44:47]
	v_mfma_f32_16x16x32_bf16 v[56:59], v[160:163], v[186:189], v[56:59]
	v_mfma_f32_16x16x32_bf16 v[12:15], v[144:147], v[216:219], v[12:15]
	v_mfma_f32_16x16x32_bf16 v[24:27], v[160:163], v[208:211], v[24:27]
	v_mfma_f32_16x16x32_bf16 v[60:63], v[148:151], v[190:193], v[60:63]
	v_mfma_f32_16x16x32_bf16 v[40:43], v[164:167], v[198:201], v[40:43]
	v_mfma_f32_16x16x32_bf16 v[28:31], v[148:151], v[212:215], v[28:31]
	v_mfma_f32_16x16x32_bf16 v[8:11], v[164:167], v[220:223], v[8:11]
	v_mfma_f32_16x16x32_bf16 v[44:47], v[148:151], v[198:201], v[44:47]
	v_mfma_f32_16x16x32_bf16 v[56:59], v[164:167], v[190:193], v[56:59]
	v_lshl_add_u64 v[228:229], s[58:59], 0, v[134:135]
	s_mov_b32 m0, s53
	s_nop 0
	global_load_lds_dwordx4 v[228:229], off
	v_mfma_f32_16x16x32_bf16 v[12:15], v[148:151], v[220:223], v[12:15]
	v_mfma_f32_16x16x32_bf16 v[24:27], v[164:167], v[212:215], v[24:27]
	s_setprio 0
	s_setprio 1
	v_mfma_f32_16x16x32_bf16 v[52:55], v[168:171], v[186:189], v[52:55]
	v_mfma_f32_16x16x32_bf16 v[32:35], v[176:179], v[194:197], v[32:35]
	v_mfma_f32_16x16x32_bf16 v[20:23], v[168:171], v[208:211], v[20:23]
	v_mfma_f32_16x16x32_bf16 v[0:3], v[176:179], v[216:219], v[0:3]
	v_mfma_f32_16x16x32_bf16 v[36:39], v[168:171], v[194:197], v[36:39]
	v_mfma_f32_16x16x32_bf16 v[48:51], v[176:179], v[186:189], v[48:51]
	v_mfma_f32_16x16x32_bf16 v[4:7], v[168:171], v[216:219], v[4:7]
	v_mfma_f32_16x16x32_bf16 v[16:19], v[176:179], v[208:211], v[16:19]
	v_mfma_f32_16x16x32_bf16 v[52:55], v[172:175], v[190:193], v[52:55]
	v_mfma_f32_16x16x32_bf16 v[32:35], v[182:185], v[198:201], v[32:35]
	v_mfma_f32_16x16x32_bf16 v[20:23], v[172:175], v[212:215], v[20:23]
	v_mfma_f32_16x16x32_bf16 v[0:3], v[182:185], v[220:223], v[0:3]
	v_mfma_f32_16x16x32_bf16 v[36:39], v[172:175], v[198:201], v[36:39]
	v_mfma_f32_16x16x32_bf16 v[48:51], v[182:185], v[190:193], v[48:51]
	v_lshl_add_u64 v[230:231], s[58:59], 0, v[130:131]
	s_mov_b32 m0, s60
	s_nop 0
	global_load_lds_dwordx4 v[230:231], off
	v_mfma_f32_16x16x32_bf16 v[4:7], v[172:175], v[220:223], v[4:7]
	v_mfma_f32_16x16x32_bf16 v[16:19], v[182:185], v[212:215], v[16:19]
	s_setprio 0
	s_barrier
; #define PG8_STAGE(bufoff, gbase, voff) do { _Pragma("unroll") for (int _i = 0; _i < 2; ++_i) \
;         __builtin_amdgcn_global_load_lds((const unsigned*)((const char*)(gbase) + (voff)[_i]), (PG8_LAS unsigned*)(lds + (bufoff) + ldsw + _i * 8192), 16, 0, 0); } while (0)
; #define PG8_LDA(dst, b, h) do { _Pragma("unroll") for (int m = 0; m < 4; ++m) _Pragma("unroll") for (int k = 0; k < 2; ++k) dst[m][k] = *(const PG8_LAS bf16x8*)(lds + PG8_SA(b, h) + aoff + m * 2048 + k * 1024); } while (0)
; #define PG8_LDB(dst, b, h) do { _Pragma("unroll") for (int n = 0; n < 2; ++n) _Pragma("unroll") for (int k = 0; k < 2; ++k) dst[n][k] = *(const PG8_LAS bf16x8*)(lds + PG8_SB(b, h) + boff + n * 2048 + k * 1024); } while (0)
; #define PG8_MMA(ai, bj, At, Bt) do { __builtin_amdgcn_s_setprio(1); _Pragma("unroll") for (int m = 0; m < 4; ++m) _Pragma("unroll") for (int n = 0; n < 2; ++n) _Pragma("unroll") for (int k = 0; k < 2; ++k) \
;         acc[ai][bj][m][n] = __builtin_amdgcn_mfma_f32_16x16x32_bf16(Bt[n][k], At[m][k], acc[ai][bj][m][n], 0, 0, 0); __builtin_amdgcn_s_setprio(0); } while (0)
; #define PG8_WAIT_V(n) asm volatile("s_waitcnt vmcnt(" #n ")" ::: "memory")
; #define PG8_WAIT_L(n) asm volatile("s_waitcnt lgkmcnt(" #n ")" ::: "memory")
; #define PG8_BAR __builtin_amdgcn_s_barrier()
; #define PG8_SCHED __builtin_amdgcn_sched_barrier(0)
; template <class Epi, class Sched, bool ALIGN_EPI = false, bool SP2 = false>
; __device__ __forceinline__ void gemm_phase(PG8_LAS unsigned char* lds, const Gemm g, const Sched& S, const Epi& E) {
;     ...
;             PG8_LDB(B0, 1, 0); PG8_LDB(B1, 1, 1); PG8_SCHED; PG8_LDA(At, 1, 0); PG8_STAGE(PG8_SA(0, 1), a2 + hstep, voffA);
;             PG8_WAIT_V(8); PG8_WAIT_L(0); PG8_BAR; PG8_MMA(0, 0, At, B0); PG8_MMA(0, 1, At, B1); PG8_BAR; PG8_SCHED;
	s_add_i32 s78, 0, 0x18000
	v_add_u32_e32 v159, s78, v153
	s_add_i32 s79, 0, 0x1c000
	ds_read_b128 v[144:147], v159
	ds_read_b128 v[148:151], v159 offset:1024
	ds_read_b128 v[160:163], v159 offset:2048
	ds_read_b128 v[164:167], v159 offset:3072
	v_add_u32_e32 v159, s79, v153
	ds_read_b128 v[168:171], v159
	ds_read_b128 v[172:175], v159 offset:1024
	ds_read_b128 v[176:179], v159 offset:2048
	ds_read_b128 v[182:185], v159 offset:3072
	s_add_u32 s58, s58, 0x40000
	s_addc_u32 s59, s59, 0
	s_mov_b32 m0, s61
	v_lshl_add_u64 v[232:233], s[58:59], 0, v[134:135]
	ds_read_b128 v[186:189], v157 offset:32768
	ds_read_b128 v[190:193], v157 offset:33792
	ds_read_b128 v[194:197], v157 offset:34816
	ds_read_b128 v[198:201], v157 offset:35840
	ds_read_b128 v[208:211], v157 offset:36864
	ds_read_b128 v[212:215], v157 offset:37888
	ds_read_b128 v[216:219], v157 offset:38912
	ds_read_b128 v[220:223], v157 offset:39936
	global_load_lds_dwordx4 v[232:233], off
	v_lshl_add_u64 v[232:233], s[58:59], 0, v[130:131]
	s_mov_b32 m0, s62
	s_nop 0
	global_load_lds_dwordx4 v[232:233], off
	s_waitcnt vmcnt(8)
	s_waitcnt lgkmcnt(0)
	s_barrier
	s_setprio 1
	s_waitcnt lgkmcnt(0)
	v_mfma_f32_16x16x32_bf16 v[124:127], v[144:147], v[186:189], v[124:127]
	v_mfma_f32_16x16x32_bf16 v[104:107], v[160:163], v[194:197], v[104:107]
	v_mfma_f32_16x16x32_bf16 v[92:95], v[144:147], v[208:211], v[92:95]
	v_mfma_f32_16x16x32_bf16 v[72:75], v[160:163], v[216:219], v[72:75]
	v_mfma_f32_16x16x32_bf16 v[108:111], v[144:147], v[194:197], v[108:111]
	v_mfma_f32_16x16x32_bf16 v[120:123], v[160:163], v[186:189], v[120:123]
	v_mfma_f32_16x16x32_bf16 v[76:79], v[144:147], v[216:219], v[76:79]
	v_mfma_f32_16x16x32_bf16 v[88:91], v[160:163], v[208:211], v[88:91]
	v_mfma_f32_16x16x32_bf16 v[124:127], v[148:151], v[190:193], v[124:127]
	v_mfma_f32_16x16x32_bf16 v[104:107], v[164:167], v[198:201], v[104:107]
	v_mfma_f32_16x16x32_bf16 v[92:95], v[148:151], v[212:215], v[92:95]
	v_mfma_f32_16x16x32_bf16 v[72:75], v[164:167], v[220:223], v[72:75]
	v_mfma_f32_16x16x32_bf16 v[108:111], v[148:151], v[198:201], v[108:111]
	v_mfma_f32_16x16x32_bf16 v[120:123], v[164:167], v[190:193], v[120:123]
	v_mfma_f32_16x16x32_bf16 v[76:79], v[148:151], v[220:223], v[76:79]
	v_mfma_f32_16x16x32_bf16 v[88:91], v[164:167], v[212:215], v[88:91]
	s_setprio 0
	s_setprio 1
	v_mfma_f32_16x16x32_bf16 v[116:119], v[168:171], v[186:189], v[116:119]
	v_mfma_f32_16x16x32_bf16 v[96:99], v[176:179], v[194:197], v[96:99]
	v_mfma_f32_16x16x32_bf16 v[84:87], v[168:171], v[208:211], v[84:87]
	v_mfma_f32_16x16x32_bf16 v[64:67], v[176:179], v[216:219], v[64:67]
	v_mfma_f32_16x16x32_bf16 v[100:103], v[168:171], v[194:197], v[100:103]
	v_mfma_f32_16x16x32_bf16 v[112:115], v[176:179], v[186:189], v[112:115]
	v_mfma_f32_16x16x32_bf16 v[68:71], v[168:171], v[216:219], v[68:71]
	v_mfma_f32_16x16x32_bf16 v[80:83], v[176:179], v[208:211], v[80:83]
	v_mfma_f32_16x16x32_bf16 v[116:119], v[172:175], v[190:193], v[116:119]
	v_mfma_f32_16x16x32_bf16 v[96:99], v[182:185], v[198:201], v[96:99]
	v_mfma_f32_16x16x32_bf16 v[84:87], v[172:175], v[212:215], v[84:87]
	v_mfma_f32_16x16x32_bf16 v[64:67], v[182:185], v[220:223], v[64:67]
	v_mfma_f32_16x16x32_bf16 v[100:103], v[172:175], v[198:201], v[100:103]
	v_mfma_f32_16x16x32_bf16 v[112:115], v[182:185], v[190:193], v[112:115]
	v_mfma_f32_16x16x32_bf16 v[68:71], v[172:175], v[220:223], v[68:71]
	v_mfma_f32_16x16x32_bf16 v[80:83], v[182:185], v[212:215], v[80:83]
	s_setprio 0
	s_barrier
; #define PG8_STAGE(bufoff, gbase, voff) do { _Pragma("unroll") for (int _i = 0; _i < 2; ++_i) \
;         __builtin_amdgcn_global_load_lds((const unsigned*)((const char*)(gbase) + (voff)[_i]), (PG8_LAS unsigned*)(lds + (bufoff) + ldsw + _i * 8192), 16, 0, 0); } while (0)
; #define PG8_LDA(dst, b, h) do { _Pragma("unroll") for (int m = 0; m < 4; ++m) _Pragma("unroll") for (int k = 0; k < 2; ++k) dst[m][k] = *(const PG8_LAS bf16x8*)(lds + PG8_SA(b, h) + aoff + m * 2048 + k * 1024); } while (0)
; #define PG8_MMA(ai, bj, At, Bt) do { __builtin_amdgcn_s_setprio(1); _Pragma("unroll") for (int m = 0; m < 4; ++m) _Pragma("unroll") for (int n = 0; n < 2; ++n) _Pragma("unroll") for (int k = 0; k < 2; ++k) \
;         acc[ai][bj][m][n] = __builtin_amdgcn_mfma_f32_16x16x32_bf16(Bt[n][k], At[m][k], acc[ai][bj][m][n], 0, 0, 0); __builtin_amdgcn_s_setprio(0); } while (0)
; #define PG8_WAIT_V(n) asm volatile("s_waitcnt vmcnt(" #n ")" ::: "memory")
; #define PG8_WAIT_L(n) asm volatile("s_waitcnt lgkmcnt(" #n ")" ::: "memory")
; #define PG8_BAR __builtin_amdgcn_s_barrier()
; #define PG8_SCHED __builtin_amdgcn_sched_barrier(0)
;     __device__ __forceinline__ void operator()(const f32x4 (&acc)[2][2][4][2], const Unit& u, int wr, int wc, int fr, int fq) const {
;     ...
;             for (int m = 0; m < 4; ++m) { const int row = row0 + ai * HALF + m * 16; const float rs = row_rs(ss, row);
; template <class Epi, class Sched, bool ALIGN_EPI = false, bool SP2 = false>
; __device__ __forceinline__ void gemm_phase(PG8_LAS unsigned char* lds, const Gemm g, const Sched& S, const Epi& E) {
;     ...
;             PG8_LDA(At, 1, 1); PG8_STAGE(PG8_SB(1, 0), b3, voffB); PG8_STAGE(PG8_SB(1, 1), b3 + hstep, voffB); PG8_STAGE(PG8_SA(1, 0), a3, voffA);
;             PG8_WAIT_V(8); PG8_WAIT_L(0); PG8_BAR; PG8_MMA(1, 0, At, B0); PG8_MMA(1, 1, At, B1); PG8_BAR; PG8_SCHED;
	s_add_i32 s58, s78, s33
	v_lshl_add_u64 v[224:225], v[224:225], 0, s[12:13]
	s_mov_b32 m0, s58
	ds_read_b128 v[186:189], v157 offset:49152
	ds_read_b128 v[190:193], v157 offset:50176
	ds_read_b128 v[194:197], v157 offset:51200
	ds_read_b128 v[198:201], v157 offset:52224
	ds_read_b128 v[208:211], v157 offset:53248
	ds_read_b128 v[212:215], v157 offset:54272
	ds_read_b128 v[216:219], v157 offset:55296
	ds_read_b128 v[220:223], v157 offset:56320
	global_load_lds_dwordx4 v[224:225], off
	s_add_i32 m0, s58, 0x2000
	s_add_u32 s56, s56, 0x40080
	v_lshl_add_u64 v[224:225], v[226:227], 0, s[12:13]
	s_addc_u32 s57, s57, 0
	s_add_i32 s58, s79, s33
	global_load_lds_dwordx4 v[224:225], off
	v_lshl_add_u64 v[224:225], s[56:57], 0, v[132:133]
	s_mov_b32 m0, s58
	s_nop 0
	global_load_lds_dwordx4 v[224:225], off
	v_lshl_add_u64 v[224:225], s[56:57], 0, v[128:129]
	s_add_i32 m0, s58, 0x2000
	s_nop 0
	global_load_lds_dwordx4 v[224:225], off
	s_waitcnt vmcnt(6)
	s_waitcnt lgkmcnt(0)
	s_barrier
	s_setprio 1
	s_waitcnt lgkmcnt(0)
	v_mfma_f32_16x16x32_bf16 v[60:63], v[144:147], v[186:189], v[60:63]
	v_mfma_f32_16x16x32_bf16 v[40:43], v[160:163], v[194:197], v[40:43]
	v_mfma_f32_16x16x32_bf16 v[28:31], v[144:147], v[208:211], v[28:31]
	v_mfma_f32_16x16x32_bf16 v[8:11], v[160:163], v[216:219], v[8:11]
	v_mfma_f32_16x16x32_bf16 v[44:47], v[144:147], v[194:197], v[44:47]
	v_mfma_f32_16x16x32_bf16 v[56:59], v[160:163], v[186:189], v[56:59]
	v_mfma_f32_16x16x32_bf16 v[12:15], v[144:147], v[216:219], v[12:15]
	v_mfma_f32_16x16x32_bf16 v[24:27], v[160:163], v[208:211], v[24:27]
	v_mfma_f32_16x16x32_bf16 v[60:63], v[148:151], v[190:193], v[60:63]
	v_mfma_f32_16x16x32_bf16 v[40:43], v[164:167], v[198:201], v[40:43]
	v_mfma_f32_16x16x32_bf16 v[28:31], v[148:151], v[212:215], v[28:31]
	v_mfma_f32_16x16x32_bf16 v[8:11], v[164:167], v[220:223], v[8:11]
	v_mfma_f32_16x16x32_bf16 v[44:47], v[148:151], v[198:201], v[44:47]
	v_mfma_f32_16x16x32_bf16 v[56:59], v[164:167], v[190:193], v[56:59]
	v_lshl_add_u64 v[224:225], v[228:229], 0, s[12:13]
	s_mov_b32 m0, s64
	s_nop 0
	global_load_lds_dwordx4 v[224:225], off
	v_mfma_f32_16x16x32_bf16 v[12:15], v[148:151], v[220:223], v[12:15]
	v_mfma_f32_16x16x32_bf16 v[24:27], v[164:167], v[212:215], v[24:27]
	s_setprio 0
	s_setprio 1
	v_mfma_f32_16x16x32_bf16 v[52:55], v[168:171], v[186:189], v[52:55]
	v_mfma_f32_16x16x32_bf16 v[32:35], v[176:179], v[194:197], v[32:35]
	v_mfma_f32_16x16x32_bf16 v[20:23], v[168:171], v[208:211], v[20:23]
	v_mfma_f32_16x16x32_bf16 v[0:3], v[176:179], v[216:219], v[0:3]
	v_mfma_f32_16x16x32_bf16 v[36:39], v[168:171], v[194:197], v[36:39]
	v_mfma_f32_16x16x32_bf16 v[48:51], v[176:179], v[186:189], v[48:51]
	v_mfma_f32_16x16x32_bf16 v[4:7], v[168:171], v[216:219], v[4:7]
	v_mfma_f32_16x16x32_bf16 v[16:19], v[176:179], v[208:211], v[16:19]
	v_mfma_f32_16x16x32_bf16 v[52:55], v[172:175], v[190:193], v[52:55]
	v_mfma_f32_16x16x32_bf16 v[32:35], v[182:185], v[198:201], v[32:35]
	v_mfma_f32_16x16x32_bf16 v[20:23], v[172:175], v[212:215], v[20:23]
	v_mfma_f32_16x16x32_bf16 v[0:3], v[182:185], v[220:223], v[0:3]
	v_mfma_f32_16x16x32_bf16 v[36:39], v[172:175], v[198:201], v[36:39]
	v_mfma_f32_16x16x32_bf16 v[48:51], v[182:185], v[190:193], v[48:51]
	v_lshl_add_u64 v[224:225], v[230:231], 0, s[12:13]
	s_mov_b32 m0, s65
	s_nop 0
	global_load_lds_dwordx4 v[224:225], off
	v_mfma_f32_16x16x32_bf16 v[4:7], v[172:175], v[220:223], v[4:7]
	v_mfma_f32_16x16x32_bf16 v[16:19], v[182:185], v[212:215], v[16:19]
	s_setprio 0
	s_barrier
	s_add_i32 s84, s84, 2
	s_add_u32 s54, s54, 0x100
	s_addc_u32 s55, s55, 0
	s_add_u32 s82, s82, 0x100
	s_addc_u32 s83, s83, 0
	s_cmp_gt_u32 s84, 13
	s_cbranch_scc0 .LBB0_1119
	v_lshl_add_u32 v144, s52, 8, v152
	v_ashrrev_i32_e32 v145, 31, v144
	v_lshl_add_u64 v[150:151], v[144:145], 3, s[36:37]
	global_load_dwordx2 v[182:183], v[150:151], off
	global_load_dwordx2 v[184:185], v[150:151], off offset:128
	global_load_dwordx2 v[186:187], v[150:151], off offset:256
	global_load_dwordx2 v[188:189], v[150:151], off offset:384
	global_load_dwordx2 v[190:191], v[150:151], off offset:1024
	global_load_dwordx2 v[192:193], v[150:151], off offset:1152
	global_load_dwordx2 v[194:195], v[150:151], off offset:1280
	global_load_dwordx2 v[196:197], v[150:151], off offset:1408
	s_and_b64 vcc, exec, s[38:39]
	s_cbranch_vccz .LBB0_1122
	s_barrier

; #define PG8_STAGE(bufoff, gbase, voff) do { _Pragma("unroll") for (int _i = 0; _i < 2; ++_i) \
;         __builtin_amdgcn_global_load_lds((const unsigned*)((const char*)(gbase) + (voff)[_i]), (PG8_LAS unsigned*)(lds + (bufoff) + ldsw + _i * 8192), 16, 0, 0); } while (0)
; #define PG8_LDA(dst, b, h) do { _Pragma("unroll") for (int m = 0; m < 4; ++m) _Pragma("unroll") for (int k = 0; k < 2; ++k) dst[m][k] = *(const PG8_LAS bf16x8*)(lds + PG8_SA(b, h) + aoff + m * 2048 + k * 1024); } while (0)
; #define PG8_LDB(dst, b, h) do { _Pragma("unroll") for (int n = 0; n < 2; ++n) _Pragma("unroll") for (int k = 0; k < 2; ++k) dst[n][k] = *(const PG8_LAS bf16x8*)(lds + PG8_SB(b, h) + boff + n * 2048 + k * 1024); } while (0)
; #define PG8_MMA(ai, bj, At, Bt) do { __builtin_amdgcn_s_setprio(1); _Pragma("unroll") for (int m = 0; m < 4; ++m) _Pragma("unroll") for (int n = 0; n < 2; ++n) _Pragma("unroll") for (int k = 0; k < 2; ++k) \
;         acc[ai][bj][m][n] = __builtin_amdgcn_mfma_f32_16x16x32_bf16(Bt[n][k], At[m][k], acc[ai][bj][m][n], 0, 0, 0); __builtin_amdgcn_s_setprio(0); } while (0)
; #define PG8_WAIT_V(n) asm volatile("s_waitcnt vmcnt(" #n ")" ::: "memory")
; #define PG8_WAIT_L(n) asm volatile("s_waitcnt lgkmcnt(" #n ")" ::: "memory")
; #define PG8_BAR __builtin_amdgcn_s_barrier()
; #define PG8_SCHED __builtin_amdgcn_sched_barrier(0)
; template <class Epi, class Sched, bool ALIGN_EPI = false, bool SP2 = false>
; __device__ __forceinline__ void gemm_phase(PG8_LAS unsigned char* lds, const Gemm g, const Sched& S, const Epi& E) {
;     ...
;             const char* a1 = cA + (size_t)(t + 1) * kstep;
;             const char* a2 = last ? nA : cA + (size_t)(t + 2) * kstep; const char* b2 = last ? nB : cB + (size_t)(t + 2) * kstep;
;             const char* a3 = a2 + kstep; const char* b3 = b2 + kstep;
;             if (last && has_next) S.a_ready(nxt);
;             if constexpr (SP2) {
;             PG8_LDB(B0, 0, 0); PG8_LDB(B1, 0, 1); PG8_SCHED; PG8_LDA(At, 0, 0); PG8_STAGE(PG8_SA(1, 1), a1 + hstep, voffA);
;             PG8_WAIT_V(8); PG8_WAIT_L(0); PG8_BAR; PG8_MMA(0, 0, At, B0); PG8_MMA(0, 1, At, B1); PG8_BAR; PG8_SCHED;
;             PG8_LDA(At, 0, 1); PG8_STAGE(PG8_SB(0, 0), b2, voffB); PG8_STAGE(PG8_SB(0, 1), b2 + hstep, voffB); PG8_STAGE(PG8_SA(0, 0), a2, voffA);
.LBB0_1196:
	s_add_u32 s82, s52, 0x100
	s_addc_u32 s83, s53, 0
	s_mov_b32 s84, -2
	s_waitcnt lgkmcnt(0)
	ds_read_b128 v[144:147], v151
	ds_read_b128 v[156:159], v151 offset:1024
	ds_read_b128 v[160:163], v151 offset:2048
	ds_read_b128 v[164:167], v151 offset:3072
	ds_read_b128 v[168:171], v152
	ds_read_b128 v[172:175], v152 offset:1024
	ds_read_b128 v[176:179], v152 offset:2048
	ds_read_b128 v[182:185], v152 offset:3072
	s_add_u32 s52, s50, 0x100
	s_addc_u32 s53, s51, 0
	s_cmp_eq_u32 s84, 40
	s_cselect_b32 s57, s1, s53
	s_cselect_b32 s56, s0, s52
	s_cselect_b32 s55, s49, s83
	s_cselect_b32 s54, s48, s82
	v_lshl_add_u64 v[224:225], s[50:51], 0, v[136:137]
	s_add_i32 m0, s34, 0xc000
	ds_read_b128 v[186:189], v153
	ds_read_b128 v[190:193], v153 offset:1024
	ds_read_b128 v[194:197], v153 offset:2048
	ds_read_b128 v[198:201], v153 offset:3072
	ds_read_b128 v[208:211], v153 offset:4096
	ds_read_b128 v[212:215], v153 offset:5120
	ds_read_b128 v[216:219], v153 offset:6144
	ds_read_b128 v[220:223], v153 offset:7168
	global_load_lds_dwordx4 v[224:225], off
	v_lshl_add_u64 v[224:225], s[50:51], 0, v[138:139]
	s_add_i32 m0, s34, 0xe000
	s_nop 0
	global_load_lds_dwordx4 v[224:225], off
	s_waitcnt vmcnt(8)
	s_waitcnt lgkmcnt(0)
	s_barrier
	s_setprio 1
	s_waitcnt lgkmcnt(0)
	v_mfma_f32_16x16x32_bf16 v[124:127], v[144:147], v[186:189], 0
	v_mfma_f32_16x16x32_bf16 v[104:107], v[160:163], v[194:197], 0
	v_mfma_f32_16x16x32_bf16 v[92:95], v[144:147], v[208:211], 0
	v_mfma_f32_16x16x32_bf16 v[72:75], v[160:163], v[216:219], 0
	v_mfma_f32_16x16x32_bf16 v[108:111], v[144:147], v[194:197], 0
	v_mfma_f32_16x16x32_bf16 v[120:123], v[160:163], v[186:189], 0
	v_mfma_f32_16x16x32_bf16 v[76:79], v[144:147], v[216:219], 0
	v_mfma_f32_16x16x32_bf16 v[88:91], v[160:163], v[208:211], 0
	v_mfma_f32_16x16x32_bf16 v[124:127], v[156:159], v[190:193], v[124:127]
	v_mfma_f32_16x16x32_bf16 v[104:107], v[164:167], v[198:201], v[104:107]
	v_mfma_f32_16x16x32_bf16 v[92:95], v[156:159], v[212:215], v[92:95]
	v_mfma_f32_16x16x32_bf16 v[72:75], v[164:167], v[220:223], v[72:75]
	v_mfma_f32_16x16x32_bf16 v[108:111], v[156:159], v[198:201], v[108:111]
	v_mfma_f32_16x16x32_bf16 v[120:123], v[164:167], v[190:193], v[120:123]
	v_mfma_f32_16x16x32_bf16 v[76:79], v[156:159], v[220:223], v[76:79]
	v_mfma_f32_16x16x32_bf16 v[88:91], v[164:167], v[212:215], v[88:91]
	s_setprio 0
	s_setprio 1
	v_mfma_f32_16x16x32_bf16 v[116:119], v[168:171], v[186:189], 0
	v_mfma_f32_16x16x32_bf16 v[96:99], v[176:179], v[194:197], 0
	v_mfma_f32_16x16x32_bf16 v[84:87], v[168:171], v[208:211], 0
	v_mfma_f32_16x16x32_bf16 v[64:67], v[176:179], v[216:219], 0
	v_mfma_f32_16x16x32_bf16 v[100:103], v[168:171], v[194:197], 0
	v_mfma_f32_16x16x32_bf16 v[112:115], v[176:179], v[186:189], 0
	v_mfma_f32_16x16x32_bf16 v[68:71], v[168:171], v[216:219], 0
	v_mfma_f32_16x16x32_bf16 v[80:83], v[176:179], v[208:211], 0
	v_mfma_f32_16x16x32_bf16 v[116:119], v[172:175], v[190:193], v[116:119]
	v_mfma_f32_16x16x32_bf16 v[96:99], v[182:185], v[198:201], v[96:99]
	v_mfma_f32_16x16x32_bf16 v[84:87], v[172:175], v[212:215], v[84:87]
	v_mfma_f32_16x16x32_bf16 v[64:67], v[182:185], v[220:223], v[64:67]
	v_mfma_f32_16x16x32_bf16 v[100:103], v[172:175], v[198:201], v[100:103]
	v_mfma_f32_16x16x32_bf16 v[112:115], v[182:185], v[190:193], v[112:115]
	v_mfma_f32_16x16x32_bf16 v[68:71], v[172:175], v[220:223], v[68:71]
	v_mfma_f32_16x16x32_bf16 v[80:83], v[182:185], v[212:215], v[80:83]
	s_setprio 0
	s_barrier
	s_add_i32 s50, s64, s33
	v_lshl_add_u64 v[224:225], s[54:55], 0, v[130:131]
	s_mov_b32 m0, s50
	ds_read_b128 v[186:189], v153 offset:16384
	ds_read_b128 v[190:193], v153 offset:17408
	ds_read_b128 v[194:197], v153 offset:18432
	ds_read_b128 v[198:201], v153 offset:19456
	ds_read_b128 v[208:211], v153 offset:20480
	ds_read_b128 v[212:215], v153 offset:21504
	ds_read_b128 v[216:219], v153 offset:22528
	ds_read_b128 v[220:223], v153 offset:23552
	global_load_lds_dwordx4 v[224:225], off
	s_add_i32 m0, s50, 0x2000
	s_add_u32 s50, s54, 0xb0000
	v_lshl_add_u64 v[226:227], s[54:55], 0, v[134:135]
	s_addc_u32 s51, s55, 0
	s_add_i32 s78, s65, s33
	global_load_lds_dwordx4 v[226:227], off
	v_lshl_add_u64 v[228:229], s[50:51], 0, v[130:131]
	s_mov_b32 m0, s78
	global_load_lds_dwordx4 v[228:229], off
	v_lshl_add_u64 v[228:229], s[50:51], 0, v[134:135]
	s_add_i32 m0, s78, 0x2000
	s_nop 0
	global_load_lds_dwordx4 v[228:229], off
	s_waitcnt vmcnt(6)
	s_waitcnt lgkmcnt(0)
	s_barrier
; #define PG8_STAGE(bufoff, gbase, voff) do { _Pragma("unroll") for (int _i = 0; _i < 2; ++_i) \
;         __builtin_amdgcn_global_load_lds((const unsigned*)((const char*)(gbase) + (voff)[_i]), (PG8_LAS unsigned*)(lds + (bufoff) + ldsw + _i * 8192), 16, 0, 0); } while (0)
; #define PG8_LDA(dst, b, h) do { _Pragma("unroll") for (int m = 0; m < 4; ++m) _Pragma("unroll") for (int k = 0; k < 2; ++k) dst[m][k] = *(const PG8_LAS bf16x8*)(lds + PG8_SA(b, h) + aoff + m * 2048 + k * 1024); } while (0)
; #define PG8_LDB(dst, b, h) do { _Pragma("unroll") for (int n = 0; n < 2; ++n) _Pragma("unroll") for (int k = 0; k < 2; ++k) dst[n][k] = *(const PG8_LAS bf16x8*)(lds + PG8_SB(b, h) + boff + n * 2048 + k * 1024); } while (0)
; #define PG8_MMA(ai, bj, At, Bt) do { __builtin_amdgcn_s_setprio(1); _Pragma("unroll") for (int m = 0; m < 4; ++m) _Pragma("unroll") for (int n = 0; n < 2; ++n) _Pragma("unroll") for (int k = 0; k < 2; ++k) \
;         acc[ai][bj][m][n] = __builtin_amdgcn_mfma_f32_16x16x32_bf16(Bt[n][k], At[m][k], acc[ai][bj][m][n], 0, 0, 0); __builtin_amdgcn_s_setprio(0); } while (0)
; #define PG8_WAIT_V(n) asm volatile("s_waitcnt vmcnt(" #n ")" ::: "memory")
; #define PG8_WAIT_L(n) asm volatile("s_waitcnt lgkmcnt(" #n ")" ::: "memory")
; #define PG8_BAR __builtin_amdgcn_s_barrier()
; #define PG8_SCHED __builtin_amdgcn_sched_barrier(0)
; template <class Epi, class Sched, bool ALIGN_EPI = false, bool SP2 = false>
; __device__ __forceinline__ void gemm_phase(PG8_LAS unsigned char* lds, const Gemm g, const Sched& S, const Epi& E) {
;     ...
;             PG8_WAIT_V(8); PG8_WAIT_L(0); PG8_BAR; PG8_MMA(1, 0, At, B0); PG8_MMA(1, 1, At, B1); PG8_BAR; PG8_SCHED;
;             PG8_LDB(B0, 1, 0); PG8_LDB(B1, 1, 1); PG8_SCHED; PG8_LDA(At, 1, 0); PG8_STAGE(PG8_SA(0, 1), a2 + hstep, voffA);
;             PG8_WAIT_V(8); PG8_WAIT_L(0); PG8_BAR; PG8_MMA(0, 0, At, B0); PG8_MMA(0, 1, At, B1); PG8_BAR; PG8_SCHED;
	s_setprio 1
	s_waitcnt lgkmcnt(0)
	v_mfma_f32_16x16x32_bf16 v[60:63], v[144:147], v[186:189], 0
	v_mfma_f32_16x16x32_bf16 v[40:43], v[160:163], v[194:197], 0
	v_mfma_f32_16x16x32_bf16 v[28:31], v[144:147], v[208:211], 0
	v_mfma_f32_16x16x32_bf16 v[8:11], v[160:163], v[216:219], 0
	v_mfma_f32_16x16x32_bf16 v[44:47], v[144:147], v[194:197], 0
	v_mfma_f32_16x16x32_bf16 v[56:59], v[160:163], v[186:189], 0
	v_mfma_f32_16x16x32_bf16 v[12:15], v[144:147], v[216:219], 0
	v_mfma_f32_16x16x32_bf16 v[24:27], v[160:163], v[208:211], 0
	v_mfma_f32_16x16x32_bf16 v[60:63], v[156:159], v[190:193], v[60:63]
	v_mfma_f32_16x16x32_bf16 v[40:43], v[164:167], v[198:201], v[40:43]
	v_mfma_f32_16x16x32_bf16 v[28:31], v[156:159], v[212:215], v[28:31]
	v_mfma_f32_16x16x32_bf16 v[8:11], v[164:167], v[220:223], v[8:11]
	v_mfma_f32_16x16x32_bf16 v[44:47], v[156:159], v[198:201], v[44:47]
	v_mfma_f32_16x16x32_bf16 v[56:59], v[164:167], v[190:193], v[56:59]
	v_lshl_add_u64 v[228:229], s[56:57], 0, v[128:129]
	s_mov_b32 m0, s34
	s_nop 0
	global_load_lds_dwordx4 v[228:229], off
	v_mfma_f32_16x16x32_bf16 v[12:15], v[156:159], v[220:223], v[12:15]
	v_mfma_f32_16x16x32_bf16 v[24:27], v[164:167], v[212:215], v[24:27]
	s_setprio 0
	s_setprio 1
	v_mfma_f32_16x16x32_bf16 v[52:55], v[168:171], v[186:189], 0
	v_mfma_f32_16x16x32_bf16 v[32:35], v[176:179], v[194:197], 0
	v_mfma_f32_16x16x32_bf16 v[20:23], v[168:171], v[208:211], 0
	v_mfma_f32_16x16x32_bf16 v[0:3], v[176:179], v[216:219], 0
	v_mfma_f32_16x16x32_bf16 v[36:39], v[168:171], v[194:197], 0
	v_mfma_f32_16x16x32_bf16 v[48:51], v[176:179], v[186:189], 0
	v_mfma_f32_16x16x32_bf16 v[4:7], v[168:171], v[216:219], 0
	v_mfma_f32_16x16x32_bf16 v[16:19], v[176:179], v[208:211], 0
	v_mfma_f32_16x16x32_bf16 v[52:55], v[172:175], v[190:193], v[52:55]
	v_mfma_f32_16x16x32_bf16 v[32:35], v[182:185], v[198:201], v[32:35]
	v_mfma_f32_16x16x32_bf16 v[20:23], v[172:175], v[212:215], v[20:23]
	v_mfma_f32_16x16x32_bf16 v[0:3], v[182:185], v[220:223], v[0:3]
	v_mfma_f32_16x16x32_bf16 v[36:39], v[172:175], v[198:201], v[36:39]
	v_mfma_f32_16x16x32_bf16 v[48:51], v[182:185], v[190:193], v[48:51]
	v_lshl_add_u64 v[230:231], s[56:57], 0, v[132:133]
	s_mov_b32 m0, s58
	s_nop 0
	global_load_lds_dwordx4 v[230:231], off
	v_mfma_f32_16x16x32_bf16 v[4:7], v[172:175], v[220:223], v[4:7]
	v_mfma_f32_16x16x32_bf16 v[16:19], v[182:185], v[212:215], v[16:19]
	s_setprio 0
	s_barrier
	s_add_i32 s78, 0, 0x18000
	v_add_u32_e32 v155, s78, v149
	s_add_i32 s79, 0, 0x1c000
	ds_read_b128 v[144:147], v155
	ds_read_b128 v[156:159], v155 offset:1024
	ds_read_b128 v[160:163], v155 offset:2048
	ds_read_b128 v[164:167], v155 offset:3072
	v_add_u32_e32 v155, s79, v149
	ds_read_b128 v[168:171], v155
	ds_read_b128 v[172:175], v155 offset:1024
	ds_read_b128 v[176:179], v155 offset:2048
	ds_read_b128 v[182:185], v155 offset:3072
	s_add_u32 s50, s56, 0xb0000
	s_addc_u32 s51, s57, 0
	s_mov_b32 m0, s59
	v_lshl_add_u64 v[232:233], s[50:51], 0, v[128:129]
	ds_read_b128 v[186:189], v153 offset:32768
	ds_read_b128 v[190:193], v153 offset:33792
	ds_read_b128 v[194:197], v153 offset:34816
	ds_read_b128 v[198:201], v153 offset:35840
	ds_read_b128 v[208:211], v153 offset:36864
	ds_read_b128 v[212:215], v153 offset:37888
	ds_read_b128 v[216:219], v153 offset:38912
	ds_read_b128 v[220:223], v153 offset:39936
	global_load_lds_dwordx4 v[232:233], off
	v_lshl_add_u64 v[232:233], s[50:51], 0, v[132:133]
	s_mov_b32 m0, s60
	s_nop 0
	global_load_lds_dwordx4 v[232:233], off
	s_waitcnt vmcnt(8)
	s_waitcnt lgkmcnt(0)
	s_barrier
	s_setprio 1
	s_waitcnt lgkmcnt(0)
	v_mfma_f32_16x16x32_bf16 v[124:127], v[144:147], v[186:189], v[124:127]
	v_mfma_f32_16x16x32_bf16 v[104:107], v[160:163], v[194:197], v[104:107]
	v_mfma_f32_16x16x32_bf16 v[92:95], v[144:147], v[208:211], v[92:95]
	v_mfma_f32_16x16x32_bf16 v[72:75], v[160:163], v[216:219], v[72:75]
	v_mfma_f32_16x16x32_bf16 v[108:111], v[144:147], v[194:197], v[108:111]
	v_mfma_f32_16x16x32_bf16 v[120:123], v[160:163], v[186:189], v[120:123]
	v_mfma_f32_16x16x32_bf16 v[76:79], v[144:147], v[216:219], v[76:79]
	v_mfma_f32_16x16x32_bf16 v[88:91], v[160:163], v[208:211], v[88:91]
	v_mfma_f32_16x16x32_bf16 v[124:127], v[156:159], v[190:193], v[124:127]
	v_mfma_f32_16x16x32_bf16 v[104:107], v[164:167], v[198:201], v[104:107]
	v_mfma_f32_16x16x32_bf16 v[92:95], v[156:159], v[212:215], v[92:95]
	v_mfma_f32_16x16x32_bf16 v[72:75], v[164:167], v[220:223], v[72:75]
	v_mfma_f32_16x16x32_bf16 v[108:111], v[156:159], v[198:201], v[108:111]
	v_mfma_f32_16x16x32_bf16 v[120:123], v[164:167], v[190:193], v[120:123]
	v_mfma_f32_16x16x32_bf16 v[76:79], v[156:159], v[220:223], v[76:79]
	v_mfma_f32_16x16x32_bf16 v[88:91], v[164:167], v[212:215], v[88:91]
	s_setprio 0
	s_setprio 1
	v_mfma_f32_16x16x32_bf16 v[116:119], v[168:171], v[186:189], v[116:119]
	v_mfma_f32_16x16x32_bf16 v[96:99], v[176:179], v[194:197], v[96:99]
	v_mfma_f32_16x16x32_bf16 v[84:87], v[168:171], v[208:211], v[84:87]
	v_mfma_f32_16x16x32_bf16 v[64:67], v[176:179], v[216:219], v[64:67]
	v_mfma_f32_16x16x32_bf16 v[100:103], v[168:171], v[194:197], v[100:103]
	v_mfma_f32_16x16x32_bf16 v[112:115], v[176:179], v[186:189], v[112:115]
	v_mfma_f32_16x16x32_bf16 v[68:71], v[168:171], v[216:219], v[68:71]
	v_mfma_f32_16x16x32_bf16 v[80:83], v[176:179], v[208:211], v[80:83]
	v_mfma_f32_16x16x32_bf16 v[116:119], v[172:175], v[190:193], v[116:119]
	v_mfma_f32_16x16x32_bf16 v[96:99], v[182:185], v[198:201], v[96:99]
	v_mfma_f32_16x16x32_bf16 v[84:87], v[172:175], v[212:215], v[84:87]
	v_mfma_f32_16x16x32_bf16 v[64:67], v[182:185], v[220:223], v[64:67]
	v_mfma_f32_16x16x32_bf16 v[100:103], v[172:175], v[198:201], v[100:103]
	v_mfma_f32_16x16x32_bf16 v[112:115], v[182:185], v[190:193], v[112:115]
	v_mfma_f32_16x16x32_bf16 v[68:71], v[172:175], v[220:223], v[68:71]
	v_mfma_f32_16x16x32_bf16 v[80:83], v[182:185], v[212:215], v[80:83]
	s_setprio 0
	s_barrier
; #define PG8_STAGE(bufoff, gbase, voff) do { _Pragma("unroll") for (int _i = 0; _i < 2; ++_i) \
;         __builtin_amdgcn_global_load_lds((const unsigned*)((const char*)(gbase) + (voff)[_i]), (PG8_LAS unsigned*)(lds + (bufoff) + ldsw + _i * 8192), 16, 0, 0); } while (0)
; #define PG8_LDA(dst, b, h) do { _Pragma("unroll") for (int m = 0; m < 4; ++m) _Pragma("unroll") for (int k = 0; k < 2; ++k) dst[m][k] = *(const PG8_LAS bf16x8*)(lds + PG8_SA(b, h) + aoff + m * 2048 + k * 1024); } while (0)
; #define PG8_LDB(dst, b, h) do { _Pragma("unroll") for (int n = 0; n < 2; ++n) _Pragma("unroll") for (int k = 0; k < 2; ++k) dst[n][k] = *(const PG8_LAS bf16x8*)(lds + PG8_SB(b, h) + boff + n * 2048 + k * 1024); } while (0)
; #define PG8_MMA(ai, bj, At, Bt) do { __builtin_amdgcn_s_setprio(1); _Pragma("unroll") for (int m = 0; m < 4; ++m) _Pragma("unroll") for (int n = 0; n < 2; ++n) _Pragma("unroll") for (int k = 0; k < 2; ++k) \
;         acc[ai][bj][m][n] = __builtin_amdgcn_mfma_f32_16x16x32_bf16(Bt[n][k], At[m][k], acc[ai][bj][m][n], 0, 0, 0); __builtin_amdgcn_s_setprio(0); } while (0)
; #define PG8_WAIT_V(n) asm volatile("s_waitcnt vmcnt(" #n ")" ::: "memory")
; template <class Epi, class Sched, bool ALIGN_EPI = false, bool SP2 = false>
; __device__ __forceinline__ void gemm_phase(PG8_LAS unsigned char* lds, const Gemm g, const Sched& S, const Epi& E) {
;     ...
;             PG8_LDB(B0, 0, 0); PG8_LDB(B1, 0, 1); PG8_SCHED; PG8_LDA(At, 0, 0); PG8_STAGE(PG8_SA(1, 1), a1 + hstep, voffA);
;             PG8_WAIT_V(8); PG8_WAIT_L(0); PG8_BAR; PG8_MMA(0, 0, At, B0); PG8_MMA(0, 1, At, B1); PG8_BAR; PG8_SCHED;
;             PG8_LDA(At, 0, 1); PG8_STAGE(PG8_SB(0, 0), b2, voffB); PG8_STAGE(PG8_SB(0, 1), b2 + hstep, voffB); PG8_STAGE(PG8_SA(0, 0), a2, voffA);
;             PG8_WAIT_V(8); PG8_WAIT_L(0); PG8_BAR; PG8_MMA(1, 0, At, B0); PG8_MMA(1, 1, At, B1); PG8_BAR; PG8_SCHED;
;             PG8_LDB(B0, 1, 0); PG8_LDB(B1, 1, 1); PG8_SCHED; PG8_LDA(At, 1, 0); PG8_STAGE(PG8_SA(0, 1), a2 + hstep, voffA);
;             PG8_WAIT_V(8); PG8_WAIT_L(0); PG8_BAR; PG8_MMA(0, 0, At, B0); PG8_MMA(0, 1, At, B1); PG8_BAR; PG8_SCHED;
;             PG8_LDA(At, 1, 1); PG8_STAGE(PG8_SB(1, 0), b3, voffB); PG8_STAGE(PG8_SB(1, 1), b3 + hstep, voffB); PG8_STAGE(PG8_SA(1, 0), a3, voffA);
;             PG8_WAIT_V(8); PG8_WAIT_L(0); PG8_BAR; PG8_MMA(1, 0, At, B0); PG8_MMA(1, 1, At, B1); PG8_BAR; PG8_SCHED;
	s_add_i32 s50, s78, s33
	v_lshl_add_u64 v[224:225], v[224:225], 0, s[42:43]
	s_mov_b32 m0, s50
	ds_read_b128 v[186:189], v153 offset:49152
	ds_read_b128 v[190:193], v153 offset:50176
	ds_read_b128 v[194:197], v153 offset:51200
	ds_read_b128 v[198:201], v153 offset:52224
	ds_read_b128 v[208:211], v153 offset:53248
	ds_read_b128 v[212:215], v153 offset:54272
	ds_read_b128 v[216:219], v153 offset:55296
	ds_read_b128 v[220:223], v153 offset:56320
	global_load_lds_dwordx4 v[224:225], off
	s_add_i32 m0, s50, 0x2000
	s_add_u32 s50, s54, 0xb0080
	v_lshl_add_u64 v[224:225], v[226:227], 0, s[42:43]
	s_addc_u32 s51, s55, 0
	s_add_i32 s54, s79, s33
	global_load_lds_dwordx4 v[224:225], off
	v_lshl_add_u64 v[224:225], s[50:51], 0, v[130:131]
	s_mov_b32 m0, s54
	s_nop 0
	global_load_lds_dwordx4 v[224:225], off
	v_lshl_add_u64 v[224:225], s[50:51], 0, v[134:135]
	s_add_i32 m0, s54, 0x2000
	s_nop 0
	global_load_lds_dwordx4 v[224:225], off
	s_waitcnt vmcnt(6)
	s_waitcnt lgkmcnt(0)
	s_barrier
	s_setprio 1
	s_waitcnt lgkmcnt(0)
	v_mfma_f32_16x16x32_bf16 v[60:63], v[144:147], v[186:189], v[60:63]
	v_mfma_f32_16x16x32_bf16 v[40:43], v[160:163], v[194:197], v[40:43]
	v_mfma_f32_16x16x32_bf16 v[28:31], v[144:147], v[208:211], v[28:31]
	v_mfma_f32_16x16x32_bf16 v[8:11], v[160:163], v[216:219], v[8:11]
	v_mfma_f32_16x16x32_bf16 v[44:47], v[144:147], v[194:197], v[44:47]
	v_mfma_f32_16x16x32_bf16 v[56:59], v[160:163], v[186:189], v[56:59]
	v_mfma_f32_16x16x32_bf16 v[12:15], v[144:147], v[216:219], v[12:15]
	v_mfma_f32_16x16x32_bf16 v[24:27], v[160:163], v[208:211], v[24:27]
	v_mfma_f32_16x16x32_bf16 v[60:63], v[156:159], v[190:193], v[60:63]
	v_mfma_f32_16x16x32_bf16 v[40:43], v[164:167], v[198:201], v[40:43]
	v_mfma_f32_16x16x32_bf16 v[28:31], v[156:159], v[212:215], v[28:31]
	v_mfma_f32_16x16x32_bf16 v[8:11], v[164:167], v[220:223], v[8:11]
	v_mfma_f32_16x16x32_bf16 v[44:47], v[156:159], v[198:201], v[44:47]
	v_mfma_f32_16x16x32_bf16 v[56:59], v[164:167], v[190:193], v[56:59]
	v_lshl_add_u64 v[224:225], v[228:229], 0, s[42:43]
	s_mov_b32 m0, s62
	s_nop 0
	global_load_lds_dwordx4 v[224:225], off
	v_mfma_f32_16x16x32_bf16 v[12:15], v[156:159], v[220:223], v[12:15]
	v_mfma_f32_16x16x32_bf16 v[24:27], v[164:167], v[212:215], v[24:27]
	s_setprio 0
	s_setprio 1
	v_mfma_f32_16x16x32_bf16 v[52:55], v[168:171], v[186:189], v[52:55]
	v_mfma_f32_16x16x32_bf16 v[32:35], v[176:179], v[194:197], v[32:35]
	v_mfma_f32_16x16x32_bf16 v[20:23], v[168:171], v[208:211], v[20:23]
	v_mfma_f32_16x16x32_bf16 v[0:3], v[176:179], v[216:219], v[0:3]
	v_mfma_f32_16x16x32_bf16 v[36:39], v[168:171], v[194:197], v[36:39]
	v_mfma_f32_16x16x32_bf16 v[48:51], v[176:179], v[186:189], v[48:51]
	v_mfma_f32_16x16x32_bf16 v[4:7], v[168:171], v[216:219], v[4:7]
	v_mfma_f32_16x16x32_bf16 v[16:19], v[176:179], v[208:211], v[16:19]
	v_mfma_f32_16x16x32_bf16 v[52:55], v[172:175], v[190:193], v[52:55]
	v_mfma_f32_16x16x32_bf16 v[32:35], v[182:185], v[198:201], v[32:35]
	v_mfma_f32_16x16x32_bf16 v[20:23], v[172:175], v[212:215], v[20:23]
	v_mfma_f32_16x16x32_bf16 v[0:3], v[182:185], v[220:223], v[0:3]
	v_mfma_f32_16x16x32_bf16 v[36:39], v[172:175], v[198:201], v[36:39]
	v_mfma_f32_16x16x32_bf16 v[48:51], v[182:185], v[190:193], v[48:51]
	v_lshl_add_u64 v[224:225], v[230:231], 0, s[42:43]
	s_mov_b32 m0, s63
	s_nop 0
	global_load_lds_dwordx4 v[224:225], off
	v_mfma_f32_16x16x32_bf16 v[4:7], v[172:175], v[220:223], v[4:7]
	v_mfma_f32_16x16x32_bf16 v[16:19], v[182:185], v[212:215], v[16:19]
	s_setprio 0
	s_barrier
	s_add_i32 s84, s84, 2
	s_add_u32 s82, s82, 0x100
	s_addc_u32 s83, s83, 0
	s_mov_b64 s[50:51], s[52:53]
.LBB0_1197:
	ds_read_b128 v[144:147], v151
	ds_read_b128 v[156:159], v151 offset:1024
	ds_read_b128 v[160:163], v151 offset:2048
	ds_read_b128 v[164:167], v151 offset:3072
	ds_read_b128 v[168:171], v152
	ds_read_b128 v[172:175], v152 offset:1024
	ds_read_b128 v[176:179], v152 offset:2048
	ds_read_b128 v[182:185], v152 offset:3072
	s_add_u32 s52, s50, 0x100
	s_addc_u32 s53, s51, 0
	s_cmp_eq_u32 s84, 40
	s_cselect_b32 s57, s1, s53
	s_cselect_b32 s56, s0, s52
	s_cselect_b32 s55, s49, s83
	s_cselect_b32 s54, s48, s82
	v_lshl_add_u64 v[224:225], s[50:51], 0, v[136:137]
	s_add_i32 m0, s34, 0xc000
	ds_read_b128 v[186:189], v153
	ds_read_b128 v[190:193], v153 offset:1024
	ds_read_b128 v[194:197], v153 offset:2048
	ds_read_b128 v[198:201], v153 offset:3072
	ds_read_b128 v[208:211], v153 offset:4096
	ds_read_b128 v[212:215], v153 offset:5120
	ds_read_b128 v[216:219], v153 offset:6144
	ds_read_b128 v[220:223], v153 offset:7168
	global_load_lds_dwordx4 v[224:225], off
	v_lshl_add_u64 v[224:225], s[50:51], 0, v[138:139]
	s_add_i32 m0, s34, 0xe000
	s_nop 0
	global_load_lds_dwordx4 v[224:225], off
	s_waitcnt vmcnt(8)
	s_waitcnt lgkmcnt(0)
	s_barrier
; #define PG8_STAGE(bufoff, gbase, voff) do { _Pragma("unroll") for (int _i = 0; _i < 2; ++_i) \
;         __builtin_amdgcn_global_load_lds((const unsigned*)((const char*)(gbase) + (voff)[_i]), (PG8_LAS unsigned*)(lds + (bufoff) + ldsw + _i * 8192), 16, 0, 0); } while (0)
; #define PG8_LDA(dst, b, h) do { _Pragma("unroll") for (int m = 0; m < 4; ++m) _Pragma("unroll") for (int k = 0; k < 2; ++k) dst[m][k] = *(const PG8_LAS bf16x8*)(lds + PG8_SA(b, h) + aoff + m * 2048 + k * 1024); } while (0)
; #define PG8_MMA(ai, bj, At, Bt) do { __builtin_amdgcn_s_setprio(1); _Pragma("unroll") for (int m = 0; m < 4; ++m) _Pragma("unroll") for (int n = 0; n < 2; ++n) _Pragma("unroll") for (int k = 0; k < 2; ++k) \
;         acc[ai][bj][m][n] = __builtin_amdgcn_mfma_f32_16x16x32_bf16(Bt[n][k], At[m][k], acc[ai][bj][m][n], 0, 0, 0); __builtin_amdgcn_s_setprio(0); } while (0)
; #define PG8_WAIT_V(n) asm volatile("s_waitcnt vmcnt(" #n ")" ::: "memory")
; #define PG8_WAIT_L(n) asm volatile("s_waitcnt lgkmcnt(" #n ")" ::: "memory")
; #define PG8_BAR __builtin_amdgcn_s_barrier()
; #define PG8_SCHED __builtin_amdgcn_sched_barrier(0)
; template <class Epi, class Sched, bool ALIGN_EPI = false, bool SP2 = false>
; __device__ __forceinline__ void gemm_phase(PG8_LAS unsigned char* lds, const Gemm g, const Sched& S, const Epi& E) {
;     ...
;             PG8_WAIT_V(8); PG8_WAIT_L(0); PG8_BAR; PG8_MMA(0, 0, At, B0); PG8_MMA(0, 1, At, B1); PG8_BAR; PG8_SCHED;
;             PG8_LDA(At, 0, 1); PG8_STAGE(PG8_SB(0, 0), b2, voffB); PG8_STAGE(PG8_SB(0, 1), b2 + hstep, voffB); PG8_STAGE(PG8_SA(0, 0), a2, voffA);
;             PG8_WAIT_V(8); PG8_WAIT_L(0); PG8_BAR; PG8_MMA(1, 0, At, B0); PG8_MMA(1, 1, At, B1); PG8_BAR; PG8_SCHED;
	s_setprio 1
	s_waitcnt lgkmcnt(0)
	v_mfma_f32_16x16x32_bf16 v[124:127], v[144:147], v[186:189], v[124:127]
	v_mfma_f32_16x16x32_bf16 v[104:107], v[160:163], v[194:197], v[104:107]
	v_mfma_f32_16x16x32_bf16 v[92:95], v[144:147], v[208:211], v[92:95]
	v_mfma_f32_16x16x32_bf16 v[72:75], v[160:163], v[216:219], v[72:75]
	v_mfma_f32_16x16x32_bf16 v[108:111], v[144:147], v[194:197], v[108:111]
	v_mfma_f32_16x16x32_bf16 v[120:123], v[160:163], v[186:189], v[120:123]
	v_mfma_f32_16x16x32_bf16 v[76:79], v[144:147], v[216:219], v[76:79]
	v_mfma_f32_16x16x32_bf16 v[88:91], v[160:163], v[208:211], v[88:91]
	v_mfma_f32_16x16x32_bf16 v[124:127], v[156:159], v[190:193], v[124:127]
	v_mfma_f32_16x16x32_bf16 v[104:107], v[164:167], v[198:201], v[104:107]
	v_mfma_f32_16x16x32_bf16 v[92:95], v[156:159], v[212:215], v[92:95]
	v_mfma_f32_16x16x32_bf16 v[72:75], v[164:167], v[220:223], v[72:75]
	v_mfma_f32_16x16x32_bf16 v[108:111], v[156:159], v[198:201], v[108:111]
	v_mfma_f32_16x16x32_bf16 v[120:123], v[164:167], v[190:193], v[120:123]
	v_mfma_f32_16x16x32_bf16 v[76:79], v[156:159], v[220:223], v[76:79]
	v_mfma_f32_16x16x32_bf16 v[88:91], v[164:167], v[212:215], v[88:91]
	s_setprio 0
	s_setprio 1
	v_mfma_f32_16x16x32_bf16 v[116:119], v[168:171], v[186:189], v[116:119]
	v_mfma_f32_16x16x32_bf16 v[96:99], v[176:179], v[194:197], v[96:99]
	v_mfma_f32_16x16x32_bf16 v[84:87], v[168:171], v[208:211], v[84:87]
	v_mfma_f32_16x16x32_bf16 v[64:67], v[176:179], v[216:219], v[64:67]
	v_mfma_f32_16x16x32_bf16 v[100:103], v[168:171], v[194:197], v[100:103]
	v_mfma_f32_16x16x32_bf16 v[112:115], v[176:179], v[186:189], v[112:115]
	v_mfma_f32_16x16x32_bf16 v[68:71], v[168:171], v[216:219], v[68:71]
	v_mfma_f32_16x16x32_bf16 v[80:83], v[176:179], v[208:211], v[80:83]
	v_mfma_f32_16x16x32_bf16 v[116:119], v[172:175], v[190:193], v[116:119]
	v_mfma_f32_16x16x32_bf16 v[96:99], v[182:185], v[198:201], v[96:99]
	v_mfma_f32_16x16x32_bf16 v[84:87], v[172:175], v[212:215], v[84:87]
	v_mfma_f32_16x16x32_bf16 v[64:67], v[182:185], v[220:223], v[64:67]
	v_mfma_f32_16x16x32_bf16 v[100:103], v[172:175], v[198:201], v[100:103]
	v_mfma_f32_16x16x32_bf16 v[112:115], v[182:185], v[190:193], v[112:115]
	v_mfma_f32_16x16x32_bf16 v[68:71], v[172:175], v[220:223], v[68:71]
	v_mfma_f32_16x16x32_bf16 v[80:83], v[182:185], v[212:215], v[80:83]
	s_setprio 0
	s_barrier
	s_add_i32 s50, s64, s33
	v_lshl_add_u64 v[224:225], s[54:55], 0, v[130:131]
	s_mov_b32 m0, s50
	ds_read_b128 v[186:189], v153 offset:16384
	ds_read_b128 v[190:193], v153 offset:17408
	ds_read_b128 v[194:197], v153 offset:18432
	ds_read_b128 v[198:201], v153 offset:19456
	ds_read_b128 v[208:211], v153 offset:20480
	ds_read_b128 v[212:215], v153 offset:21504
	ds_read_b128 v[216:219], v153 offset:22528
	ds_read_b128 v[220:223], v153 offset:23552
	global_load_lds_dwordx4 v[224:225], off
	s_add_i32 m0, s50, 0x2000
	s_add_u32 s50, s54, 0xb0000
	v_lshl_add_u64 v[226:227], s[54:55], 0, v[134:135]
	s_addc_u32 s51, s55, 0
	s_add_i32 s78, s65, s33
	global_load_lds_dwordx4 v[226:227], off
	v_lshl_add_u64 v[228:229], s[50:51], 0, v[130:131]
	s_mov_b32 m0, s78
	global_load_lds_dwordx4 v[228:229], off
	v_lshl_add_u64 v[228:229], s[50:51], 0, v[134:135]
	s_add_i32 m0, s78, 0x2000
	s_nop 0
	global_load_lds_dwordx4 v[228:229], off
	s_waitcnt vmcnt(6)
	s_waitcnt lgkmcnt(0)
	s_barrier
	s_setprio 1
	s_waitcnt lgkmcnt(0)
	v_mfma_f32_16x16x32_bf16 v[60:63], v[144:147], v[186:189], v[60:63]
	v_mfma_f32_16x16x32_bf16 v[40:43], v[160:163], v[194:197], v[40:43]
	v_mfma_f32_16x16x32_bf16 v[28:31], v[144:147], v[208:211], v[28:31]
	v_mfma_f32_16x16x32_bf16 v[8:11], v[160:163], v[216:219], v[8:11]
	v_mfma_f32_16x16x32_bf16 v[44:47], v[144:147], v[194:197], v[44:47]
	v_mfma_f32_16x16x32_bf16 v[56:59], v[160:163], v[186:189], v[56:59]
	v_mfma_f32_16x16x32_bf16 v[12:15], v[144:147], v[216:219], v[12:15]
	v_mfma_f32_16x16x32_bf16 v[24:27], v[160:163], v[208:211], v[24:27]
	v_mfma_f32_16x16x32_bf16 v[60:63], v[156:159], v[190:193], v[60:63]
	v_mfma_f32_16x16x32_bf16 v[40:43], v[164:167], v[198:201], v[40:43]
	v_mfma_f32_16x16x32_bf16 v[28:31], v[156:159], v[212:215], v[28:31]
	v_mfma_f32_16x16x32_bf16 v[8:11], v[164:167], v[220:223], v[8:11]
	v_mfma_f32_16x16x32_bf16 v[44:47], v[156:159], v[198:201], v[44:47]
	v_mfma_f32_16x16x32_bf16 v[56:59], v[164:167], v[190:193], v[56:59]
	v_lshl_add_u64 v[228:229], s[56:57], 0, v[128:129]
	s_mov_b32 m0, s34
	s_nop 0
	global_load_lds_dwordx4 v[228:229], off
	v_mfma_f32_16x16x32_bf16 v[12:15], v[156:159], v[220:223], v[12:15]
	v_mfma_f32_16x16x32_bf16 v[24:27], v[164:167], v[212:215], v[24:27]
	s_setprio 0
	s_setprio 1
	v_mfma_f32_16x16x32_bf16 v[52:55], v[168:171], v[186:189], v[52:55]
	v_mfma_f32_16x16x32_bf16 v[32:35], v[176:179], v[194:197], v[32:35]
	v_mfma_f32_16x16x32_bf16 v[20:23], v[168:171], v[208:211], v[20:23]
	v_mfma_f32_16x16x32_bf16 v[0:3], v[176:179], v[216:219], v[0:3]
	v_mfma_f32_16x16x32_bf16 v[36:39], v[168:171], v[194:197], v[36:39]
	v_mfma_f32_16x16x32_bf16 v[48:51], v[176:179], v[186:189], v[48:51]
	v_mfma_f32_16x16x32_bf16 v[4:7], v[168:171], v[216:219], v[4:7]
	v_mfma_f32_16x16x32_bf16 v[16:19], v[176:179], v[208:211], v[16:19]
	v_mfma_f32_16x16x32_bf16 v[52:55], v[172:175], v[190:193], v[52:55]
	v_mfma_f32_16x16x32_bf16 v[32:35], v[182:185], v[198:201], v[32:35]
	v_mfma_f32_16x16x32_bf16 v[20:23], v[172:175], v[212:215], v[20:23]
	v_mfma_f32_16x16x32_bf16 v[0:3], v[182:185], v[220:223], v[0:3]
	v_mfma_f32_16x16x32_bf16 v[36:39], v[172:175], v[198:201], v[36:39]
	v_mfma_f32_16x16x32_bf16 v[48:51], v[182:185], v[190:193], v[48:51]
	v_lshl_add_u64 v[230:231], s[56:57], 0, v[132:133]
	s_mov_b32 m0, s58
	s_nop 0
	global_load_lds_dwordx4 v[230:231], off
	v_mfma_f32_16x16x32_bf16 v[4:7], v[172:175], v[220:223], v[4:7]
	v_mfma_f32_16x16x32_bf16 v[16:19], v[182:185], v[212:215], v[16:19]
	s_setprio 0
	s_barrier
; #define PG8_STAGE(bufoff, gbase, voff) do { _Pragma("unroll") for (int _i = 0; _i < 2; ++_i) \
;         __builtin_amdgcn_global_load_lds((const unsigned*)((const char*)(gbase) + (voff)[_i]), (PG8_LAS unsigned*)(lds + (bufoff) + ldsw + _i * 8192), 16, 0, 0); } while (0)
; #define PG8_LDA(dst, b, h) do { _Pragma("unroll") for (int m = 0; m < 4; ++m) _Pragma("unroll") for (int k = 0; k < 2; ++k) dst[m][k] = *(const PG8_LAS bf16x8*)(lds + PG8_SA(b, h) + aoff + m * 2048 + k * 1024); } while (0)
; #define PG8_LDB(dst, b, h) do { _Pragma("unroll") for (int n = 0; n < 2; ++n) _Pragma("unroll") for (int k = 0; k < 2; ++k) dst[n][k] = *(const PG8_LAS bf16x8*)(lds + PG8_SB(b, h) + boff + n * 2048 + k * 1024); } while (0)
; #define PG8_MMA(ai, bj, At, Bt) do { __builtin_amdgcn_s_setprio(1); _Pragma("unroll") for (int m = 0; m < 4; ++m) _Pragma("unroll") for (int n = 0; n < 2; ++n) _Pragma("unroll") for (int k = 0; k < 2; ++k) \
;         acc[ai][bj][m][n] = __builtin_amdgcn_mfma_f32_16x16x32_bf16(Bt[n][k], At[m][k], acc[ai][bj][m][n], 0, 0, 0); __builtin_amdgcn_s_setprio(0); } while (0)
; #define PG8_WAIT_V(n) asm volatile("s_waitcnt vmcnt(" #n ")" ::: "memory")
; #define PG8_WAIT_L(n) asm volatile("s_waitcnt lgkmcnt(" #n ")" ::: "memory")
; #define PG8_BAR __builtin_amdgcn_s_barrier()
; #define PG8_SCHED __builtin_amdgcn_sched_barrier(0)
; template <class Epi, class Sched, bool ALIGN_EPI = false, bool SP2 = false>
; __device__ __forceinline__ void gemm_phase(PG8_LAS unsigned char* lds, const Gemm g, const Sched& S, const Epi& E) {
;     ...
;             PG8_LDB(B0, 1, 0); PG8_LDB(B1, 1, 1); PG8_SCHED; PG8_LDA(At, 1, 0); PG8_STAGE(PG8_SA(0, 1), a2 + hstep, voffA);
;             PG8_WAIT_V(8); PG8_WAIT_L(0); PG8_BAR; PG8_MMA(0, 0, At, B0); PG8_MMA(0, 1, At, B1); PG8_BAR; PG8_SCHED;
	s_add_i32 s78, 0, 0x18000
	v_add_u32_e32 v155, s78, v149
	s_add_i32 s79, 0, 0x1c000
	ds_read_b128 v[144:147], v155
	ds_read_b128 v[156:159], v155 offset:1024
	ds_read_b128 v[160:163], v155 offset:2048
	ds_read_b128 v[164:167], v155 offset:3072
	v_add_u32_e32 v155, s79, v149
	ds_read_b128 v[168:171], v155
	ds_read_b128 v[172:175], v155 offset:1024
	ds_read_b128 v[176:179], v155 offset:2048
	ds_read_b128 v[182:185], v155 offset:3072
	s_add_u32 s50, s56, 0xb0000
	s_addc_u32 s51, s57, 0
	s_mov_b32 m0, s59
	v_lshl_add_u64 v[232:233], s[50:51], 0, v[128:129]
	ds_read_b128 v[186:189], v153 offset:32768
	ds_read_b128 v[190:193], v153 offset:33792
	ds_read_b128 v[194:197], v153 offset:34816
	ds_read_b128 v[198:201], v153 offset:35840
	ds_read_b128 v[208:211], v153 offset:36864
	ds_read_b128 v[212:215], v153 offset:37888
	ds_read_b128 v[216:219], v153 offset:38912
	ds_read_b128 v[220:223], v153 offset:39936
	global_load_lds_dwordx4 v[232:233], off
	v_lshl_add_u64 v[232:233], s[50:51], 0, v[132:133]
	s_mov_b32 m0, s60
	s_nop 0
	global_load_lds_dwordx4 v[232:233], off
	s_waitcnt vmcnt(8)
	s_waitcnt lgkmcnt(0)
	s_barrier
	s_setprio 1
	s_waitcnt lgkmcnt(0)
	v_mfma_f32_16x16x32_bf16 v[124:127], v[144:147], v[186:189], v[124:127]
	v_mfma_f32_16x16x32_bf16 v[104:107], v[160:163], v[194:197], v[104:107]
	v_mfma_f32_16x16x32_bf16 v[92:95], v[144:147], v[208:211], v[92:95]
	v_mfma_f32_16x16x32_bf16 v[72:75], v[160:163], v[216:219], v[72:75]
	v_mfma_f32_16x16x32_bf16 v[108:111], v[144:147], v[194:197], v[108:111]
	v_mfma_f32_16x16x32_bf16 v[120:123], v[160:163], v[186:189], v[120:123]
	v_mfma_f32_16x16x32_bf16 v[76:79], v[144:147], v[216:219], v[76:79]
	v_mfma_f32_16x16x32_bf16 v[88:91], v[160:163], v[208:211], v[88:91]
	v_mfma_f32_16x16x32_bf16 v[124:127], v[156:159], v[190:193], v[124:127]
	v_mfma_f32_16x16x32_bf16 v[104:107], v[164:167], v[198:201], v[104:107]
	v_mfma_f32_16x16x32_bf16 v[92:95], v[156:159], v[212:215], v[92:95]
	v_mfma_f32_16x16x32_bf16 v[72:75], v[164:167], v[220:223], v[72:75]
	v_mfma_f32_16x16x32_bf16 v[108:111], v[156:159], v[198:201], v[108:111]
	v_mfma_f32_16x16x32_bf16 v[120:123], v[164:167], v[190:193], v[120:123]
	v_mfma_f32_16x16x32_bf16 v[76:79], v[156:159], v[220:223], v[76:79]
	v_mfma_f32_16x16x32_bf16 v[88:91], v[164:167], v[212:215], v[88:91]
	s_setprio 0
	s_setprio 1
	v_mfma_f32_16x16x32_bf16 v[116:119], v[168:171], v[186:189], v[116:119]
	v_mfma_f32_16x16x32_bf16 v[96:99], v[176:179], v[194:197], v[96:99]
	v_mfma_f32_16x16x32_bf16 v[84:87], v[168:171], v[208:211], v[84:87]
	v_mfma_f32_16x16x32_bf16 v[64:67], v[176:179], v[216:219], v[64:67]
	v_mfma_f32_16x16x32_bf16 v[100:103], v[168:171], v[194:197], v[100:103]
	v_mfma_f32_16x16x32_bf16 v[112:115], v[176:179], v[186:189], v[112:115]
	v_mfma_f32_16x16x32_bf16 v[68:71], v[168:171], v[216:219], v[68:71]
	v_mfma_f32_16x16x32_bf16 v[80:83], v[176:179], v[208:211], v[80:83]
	v_mfma_f32_16x16x32_bf16 v[116:119], v[172:175], v[190:193], v[116:119]
	v_mfma_f32_16x16x32_bf16 v[96:99], v[182:185], v[198:201], v[96:99]
	v_mfma_f32_16x16x32_bf16 v[84:87], v[172:175], v[212:215], v[84:87]
	v_mfma_f32_16x16x32_bf16 v[64:67], v[182:185], v[220:223], v[64:67]
	v_mfma_f32_16x16x32_bf16 v[100:103], v[172:175], v[198:201], v[100:103]
	v_mfma_f32_16x16x32_bf16 v[112:115], v[182:185], v[190:193], v[112:115]
	v_mfma_f32_16x16x32_bf16 v[68:71], v[172:175], v[220:223], v[68:71]
	v_mfma_f32_16x16x32_bf16 v[80:83], v[182:185], v[212:215], v[80:83]
	s_setprio 0
	s_barrier
; #define PG8_STAGE(bufoff, gbase, voff) do { _Pragma("unroll") for (int _i = 0; _i < 2; ++_i) \
;         __builtin_amdgcn_global_load_lds((const unsigned*)((const char*)(gbase) + (voff)[_i]), (PG8_LAS unsigned*)(lds + (bufoff) + ldsw + _i * 8192), 16, 0, 0); } while (0)
; #define PG8_LDA(dst, b, h) do { _Pragma("unroll") for (int m = 0; m < 4; ++m) _Pragma("unroll") for (int k = 0; k < 2; ++k) dst[m][k] = *(const PG8_LAS bf16x8*)(lds + PG8_SA(b, h) + aoff + m * 2048 + k * 1024); } while (0)
; #define PG8_MMA(ai, bj, At, Bt) do { __builtin_amdgcn_s_setprio(1); _Pragma("unroll") for (int m = 0; m < 4; ++m) _Pragma("unroll") for (int n = 0; n < 2; ++n) _Pragma("unroll") for (int k = 0; k < 2; ++k) \
;         acc[ai][bj][m][n] = __builtin_amdgcn_mfma_f32_16x16x32_bf16(Bt[n][k], At[m][k], acc[ai][bj][m][n], 0, 0, 0); __builtin_amdgcn_s_setprio(0); } while (0)
; #define PG8_WAIT_V(n) asm volatile("s_waitcnt vmcnt(" #n ")" ::: "memory")
; #define PG8_WAIT_L(n) asm volatile("s_waitcnt lgkmcnt(" #n ")" ::: "memory")
; #define PG8_BAR __builtin_amdgcn_s_barrier()
; #define PG8_SCHED __builtin_amdgcn_sched_barrier(0)
; template <class Epi, class Sched, bool ALIGN_EPI = false, bool SP2 = false>
; __device__ __forceinline__ void gemm_phase(PG8_LAS unsigned char* lds, const Gemm g, const Sched& S, const Epi& E) {
;     ...
;         for (int t = 0; t < nt; t += 2) {
;             const bool last = (t == nt - 2);
;     ...
;             PG8_LDA(At, 1, 1); PG8_STAGE(PG8_SB(1, 0), b3, voffB); PG8_STAGE(PG8_SB(1, 1), b3 + hstep, voffB); PG8_STAGE(PG8_SA(1, 0), a3, voffA);
;             PG8_WAIT_V(8); PG8_WAIT_L(0); PG8_BAR; PG8_MMA(1, 0, At, B0); PG8_MMA(1, 1, At, B1); PG8_BAR; PG8_SCHED;
	s_add_i32 s50, s78, s33
	v_lshl_add_u64 v[224:225], v[224:225], 0, s[42:43]
	s_mov_b32 m0, s50
	ds_read_b128 v[186:189], v153 offset:49152
	ds_read_b128 v[190:193], v153 offset:50176
	ds_read_b128 v[194:197], v153 offset:51200
	ds_read_b128 v[198:201], v153 offset:52224
	ds_read_b128 v[208:211], v153 offset:53248
	ds_read_b128 v[212:215], v153 offset:54272
	ds_read_b128 v[216:219], v153 offset:55296
	ds_read_b128 v[220:223], v153 offset:56320
	global_load_lds_dwordx4 v[224:225], off
	s_add_i32 m0, s50, 0x2000
	s_add_u32 s50, s54, 0xb0080
	v_lshl_add_u64 v[224:225], v[226:227], 0, s[42:43]
	s_addc_u32 s51, s55, 0
	s_add_i32 s54, s79, s33
	global_load_lds_dwordx4 v[224:225], off
	v_lshl_add_u64 v[224:225], s[50:51], 0, v[130:131]
	s_mov_b32 m0, s54
	s_nop 0
	global_load_lds_dwordx4 v[224:225], off
	v_lshl_add_u64 v[224:225], s[50:51], 0, v[134:135]
	s_add_i32 m0, s54, 0x2000
	s_nop 0
	global_load_lds_dwordx4 v[224:225], off
	s_waitcnt vmcnt(6)
	s_waitcnt lgkmcnt(0)
	s_barrier
	s_setprio 1
	s_waitcnt lgkmcnt(0)
	v_mfma_f32_16x16x32_bf16 v[60:63], v[144:147], v[186:189], v[60:63]
	v_mfma_f32_16x16x32_bf16 v[40:43], v[160:163], v[194:197], v[40:43]
	v_mfma_f32_16x16x32_bf16 v[28:31], v[144:147], v[208:211], v[28:31]
	v_mfma_f32_16x16x32_bf16 v[8:11], v[160:163], v[216:219], v[8:11]
	v_mfma_f32_16x16x32_bf16 v[44:47], v[144:147], v[194:197], v[44:47]
	v_mfma_f32_16x16x32_bf16 v[56:59], v[160:163], v[186:189], v[56:59]
	v_mfma_f32_16x16x32_bf16 v[12:15], v[144:147], v[216:219], v[12:15]
	v_mfma_f32_16x16x32_bf16 v[24:27], v[160:163], v[208:211], v[24:27]
	v_mfma_f32_16x16x32_bf16 v[60:63], v[156:159], v[190:193], v[60:63]
	v_mfma_f32_16x16x32_bf16 v[40:43], v[164:167], v[198:201], v[40:43]
	v_mfma_f32_16x16x32_bf16 v[28:31], v[156:159], v[212:215], v[28:31]
	v_mfma_f32_16x16x32_bf16 v[8:11], v[164:167], v[220:223], v[8:11]
	v_mfma_f32_16x16x32_bf16 v[44:47], v[156:159], v[198:201], v[44:47]
	v_mfma_f32_16x16x32_bf16 v[56:59], v[164:167], v[190:193], v[56:59]
	v_lshl_add_u64 v[224:225], v[228:229], 0, s[42:43]
	s_mov_b32 m0, s62
	s_nop 0
	global_load_lds_dwordx4 v[224:225], off
	v_mfma_f32_16x16x32_bf16 v[12:15], v[156:159], v[220:223], v[12:15]
	v_mfma_f32_16x16x32_bf16 v[24:27], v[164:167], v[212:215], v[24:27]
	s_setprio 0
	s_setprio 1
	v_mfma_f32_16x16x32_bf16 v[52:55], v[168:171], v[186:189], v[52:55]
	v_mfma_f32_16x16x32_bf16 v[32:35], v[176:179], v[194:197], v[32:35]
	v_mfma_f32_16x16x32_bf16 v[20:23], v[168:171], v[208:211], v[20:23]
	v_mfma_f32_16x16x32_bf16 v[0:3], v[176:179], v[216:219], v[0:3]
	v_mfma_f32_16x16x32_bf16 v[36:39], v[168:171], v[194:197], v[36:39]
	v_mfma_f32_16x16x32_bf16 v[48:51], v[176:179], v[186:189], v[48:51]
	v_mfma_f32_16x16x32_bf16 v[4:7], v[168:171], v[216:219], v[4:7]
	v_mfma_f32_16x16x32_bf16 v[16:19], v[176:179], v[208:211], v[16:19]
	v_mfma_f32_16x16x32_bf16 v[52:55], v[172:175], v[190:193], v[52:55]
	v_mfma_f32_16x16x32_bf16 v[32:35], v[182:185], v[198:201], v[32:35]
	v_mfma_f32_16x16x32_bf16 v[20:23], v[172:175], v[212:215], v[20:23]
	v_mfma_f32_16x16x32_bf16 v[0:3], v[182:185], v[220:223], v[0:3]
	v_mfma_f32_16x16x32_bf16 v[36:39], v[172:175], v[198:201], v[36:39]
	v_mfma_f32_16x16x32_bf16 v[48:51], v[182:185], v[190:193], v[48:51]
	v_lshl_add_u64 v[224:225], v[230:231], 0, s[42:43]
	s_mov_b32 m0, s63
	s_nop 0
	global_load_lds_dwordx4 v[224:225], off
	v_mfma_f32_16x16x32_bf16 v[4:7], v[172:175], v[220:223], v[4:7]
	v_mfma_f32_16x16x32_bf16 v[16:19], v[182:185], v[212:215], v[16:19]
	s_setprio 0
	s_barrier
	s_add_i32 s84, s84, 2
	s_add_u32 s82, s82, 0x100
	s_addc_u32 s83, s83, 0
	s_cmp_gt_u32 s84, 41
	s_mov_b64 s[50:51], s[52:53]
	s_cbranch_scc0 .LBB0_1197
	s_and_b64 vcc, exec, s[44:45]
	s_cbranch_vccz .LBB0_1200
	s_barrier

; #define PG8_STAGE(bufoff, gbase, voff) do { _Pragma("unroll") for (int _i = 0; _i < 2; ++_i) \
;         __builtin_amdgcn_global_load_lds((const unsigned*)((const char*)(gbase) + (voff)[_i]), (PG8_LAS unsigned*)(lds + (bufoff) + ldsw + _i * 8192), 16, 0, 0); } while (0)
; #define PG8_LDA(dst, b, h) do { _Pragma("unroll") for (int m = 0; m < 4; ++m) _Pragma("unroll") for (int k = 0; k < 2; ++k) dst[m][k] = *(const PG8_LAS bf16x8*)(lds + PG8_SA(b, h) + aoff + m * 2048 + k * 1024); } while (0)
; #define PG8_LDB(dst, b, h) do { _Pragma("unroll") for (int n = 0; n < 2; ++n) _Pragma("unroll") for (int k = 0; k < 2; ++k) dst[n][k] = *(const PG8_LAS bf16x8*)(lds + PG8_SB(b, h) + boff + n * 2048 + k * 1024); } while (0)
; #define PG8_MMA(ai, bj, At, Bt) do { __builtin_amdgcn_s_setprio(1); _Pragma("unroll") for (int m = 0; m < 4; ++m) _Pragma("unroll") for (int n = 0; n < 2; ++n) _Pragma("unroll") for (int k = 0; k < 2; ++k) \
;         acc[ai][bj][m][n] = __builtin_amdgcn_mfma_f32_16x16x32_bf16(Bt[n][k], At[m][k], acc[ai][bj][m][n], 0, 0, 0); __builtin_amdgcn_s_setprio(0); } while (0)
; #define PG8_BAR __builtin_amdgcn_s_barrier()
; template <class Epi, class Sched, bool ALIGN_EPI = false, bool SP2 = false>
; __device__ __forceinline__ void gemm_phase(PG8_LAS unsigned char* lds, const Gemm g, const Sched& S, const Epi& E) {
;     ...
;         const bool has_next = S.next(ui + 1, nxt);
;         const char* nA = has_next ? (const char*)g.A + (size_t)nxt.pm * tstep : cA; const char* nB = has_next ? (const char*)g.Bt + (size_t)nxt.pn * tstep : cB;
;         for (int t = 0; t < nt; t += 2) {
;             const bool last = (t == nt - 2);
;             const char* a1 = cA + (size_t)(t + 1) * kstep;
;             const char* a2 = last ? nA : cA + (size_t)(t + 2) * kstep; const char* b2 = last ? nB : cB + (size_t)(t + 2) * kstep;
;             const char* a3 = a2 + kstep; const char* b3 = b2 + kstep;
;             if (last && has_next) S.a_ready(nxt);
;             if constexpr (SP2) {
;             PG8_LDB(B0, 0, 0); PG8_LDB(B1, 0, 1); PG8_SCHED; PG8_LDA(At, 0, 0); PG8_STAGE(PG8_SA(1, 1), a1 + hstep, voffA);
;             PG8_WAIT_V(8); PG8_WAIT_L(0); PG8_BAR; PG8_MMA(0, 0, At, B0); PG8_MMA(0, 1, At, B1); PG8_BAR; PG8_SCHED;
;             PG8_LDA(At, 0, 1); PG8_STAGE(PG8_SB(0, 0), b2, voffB); PG8_STAGE(PG8_SB(0, 1), b2 + hstep, voffB); PG8_STAGE(PG8_SA(0, 0), a2, voffA);
.LBB0_1286:
	s_ashr_i32 s51, s50, 31
	s_lshl_b64 s[52:53], s[50:51], 19
	s_add_u32 s52, s22, s52
	s_addc_u32 s53, s23, s53
	s_and_b64 s[54:55], s[12:13], exec
	s_cselect_b32 s51, s53, s59
	s_cselect_b32 s61, s52, s58
	s_ashr_i32 s49, s48, 31
	s_lshl_b64 s[54:55], s[48:49], 19
	v_readlane_b32 s64, v250, 9
	v_readlane_b32 s65, v250, 10
	s_add_u32 s54, s64, s54
	s_addc_u32 s55, s65, s55
	s_and_b64 s[64:65], s[12:13], exec
	s_cselect_b32 s49, s55, s63
	s_cselect_b32 s87, s54, s62
	s_add_u32 s58, s58, 0x40080
	s_addc_u32 s59, s59, 0
	s_add_u32 s88, s62, 0x100
	s_addc_u32 s89, s63, 0
	s_mov_b32 s90, -2
	s_waitcnt lgkmcnt(0)
	ds_read_b128 v[128:131], v181
	ds_read_b128 v[160:163], v181 offset:1024
	ds_read_b128 v[164:167], v181 offset:2048
	ds_read_b128 v[168:171], v181 offset:3072
	ds_read_b128 v[172:175], v203
	ds_read_b128 v[176:179], v203 offset:1024
	ds_read_b128 v[182:185], v203 offset:2048
	ds_read_b128 v[186:189], v203 offset:3072
	s_add_u32 s62, s58, 0xfffc0080
	s_addc_u32 s63, s59, -1
	s_cmp_eq_u32 s90, 12
	s_cselect_b32 s65, s51, s63
	s_cselect_b32 s64, s61, s62
	s_cselect_b32 s63, s49, s89
	s_cselect_b32 s62, s87, s88
	v_lshl_add_u64 v[232:233], s[58:59], 0, v[152:153]
	s_add_i32 m0, s15, 0xc000
	ds_read_b128 v[190:193], v208
	ds_read_b128 v[194:197], v208 offset:1024
	ds_read_b128 v[198:201], v208 offset:2048
	ds_read_b128 v[212:215], v208 offset:3072
	ds_read_b128 v[216:219], v208 offset:4096
	ds_read_b128 v[220:223], v208 offset:5120
	ds_read_b128 v[224:227], v208 offset:6144
	ds_read_b128 v[228:231], v208 offset:7168
	global_load_lds_dwordx4 v[232:233], off
	v_lshl_add_u64 v[232:233], s[58:59], 0, v[154:155]
	s_add_i32 m0, s15, 0xe000
	s_nop 0
	global_load_lds_dwordx4 v[232:233], off
	s_waitcnt vmcnt(8)
	s_waitcnt lgkmcnt(0)
	s_barrier
	s_setprio 1
	s_waitcnt lgkmcnt(0)
	v_mfma_f32_16x16x32_bf16 v[124:127], v[128:131], v[190:193], 0
	v_mfma_f32_16x16x32_bf16 v[112:115], v[164:167], v[198:201], 0
	v_mfma_f32_16x16x32_bf16 v[108:111], v[128:131], v[216:219], 0
	v_mfma_f32_16x16x32_bf16 v[96:99], v[164:167], v[224:227], 0
	v_mfma_f32_16x16x32_bf16 v[116:119], v[128:131], v[198:201], 0
	v_mfma_f32_16x16x32_bf16 v[120:123], v[164:167], v[190:193], 0
	v_mfma_f32_16x16x32_bf16 v[100:103], v[128:131], v[224:227], 0
	v_mfma_f32_16x16x32_bf16 v[104:107], v[164:167], v[216:219], 0
	v_mfma_f32_16x16x32_bf16 v[124:127], v[160:163], v[194:197], v[124:127]
	v_mfma_f32_16x16x32_bf16 v[112:115], v[168:171], v[212:215], v[112:115]
	v_mfma_f32_16x16x32_bf16 v[108:111], v[160:163], v[220:223], v[108:111]
	v_mfma_f32_16x16x32_bf16 v[96:99], v[168:171], v[228:231], v[96:99]
	v_mfma_f32_16x16x32_bf16 v[116:119], v[160:163], v[212:215], v[116:119]
	v_mfma_f32_16x16x32_bf16 v[120:123], v[168:171], v[194:197], v[120:123]
	v_mfma_f32_16x16x32_bf16 v[100:103], v[160:163], v[228:231], v[100:103]
	v_mfma_f32_16x16x32_bf16 v[104:107], v[168:171], v[220:223], v[104:107]
	s_setprio 0
	s_setprio 1
	v_mfma_f32_16x16x32_bf16 v[60:63], v[172:175], v[190:193], 0
	v_mfma_f32_16x16x32_bf16 v[48:51], v[182:185], v[198:201], 0
	v_mfma_f32_16x16x32_bf16 v[44:47], v[172:175], v[216:219], 0
	v_mfma_f32_16x16x32_bf16 v[32:35], v[182:185], v[224:227], 0
	v_mfma_f32_16x16x32_bf16 v[52:55], v[172:175], v[198:201], 0
	v_mfma_f32_16x16x32_bf16 v[56:59], v[182:185], v[190:193], 0
	v_mfma_f32_16x16x32_bf16 v[36:39], v[172:175], v[224:227], 0
	v_mfma_f32_16x16x32_bf16 v[40:43], v[182:185], v[216:219], 0
	v_mfma_f32_16x16x32_bf16 v[60:63], v[176:179], v[194:197], v[60:63]
	v_mfma_f32_16x16x32_bf16 v[48:51], v[186:189], v[212:215], v[48:51]
	v_mfma_f32_16x16x32_bf16 v[44:47], v[176:179], v[220:223], v[44:47]
	v_mfma_f32_16x16x32_bf16 v[32:35], v[186:189], v[228:231], v[32:35]
	v_mfma_f32_16x16x32_bf16 v[52:55], v[176:179], v[212:215], v[52:55]
	v_mfma_f32_16x16x32_bf16 v[56:59], v[186:189], v[194:197], v[56:59]
	v_mfma_f32_16x16x32_bf16 v[36:39], v[176:179], v[228:231], v[36:39]
	v_mfma_f32_16x16x32_bf16 v[40:43], v[186:189], v[220:223], v[40:43]
	s_setprio 0
	s_barrier
	s_add_i32 s78, s75, s14
	v_lshl_add_u64 v[232:233], s[62:63], 0, v[134:135]
	s_mov_b32 m0, s78
	ds_read_b128 v[190:193], v208 offset:16384
	ds_read_b128 v[194:197], v208 offset:17408
	ds_read_b128 v[198:201], v208 offset:18432
	ds_read_b128 v[212:215], v208 offset:19456
	ds_read_b128 v[216:219], v208 offset:20480
	ds_read_b128 v[220:223], v208 offset:21504
	ds_read_b128 v[224:227], v208 offset:22528
	ds_read_b128 v[228:231], v208 offset:23552
	global_load_lds_dwordx4 v[232:233], off
	s_add_i32 m0, s78, 0x2000
	s_add_u32 s78, s62, 0x40000
	v_lshl_add_u64 v[234:235], s[62:63], 0, v[138:139]
	s_addc_u32 s79, s63, 0
	s_add_i32 s91, s76, s14
	global_load_lds_dwordx4 v[234:235], off
	v_lshl_add_u64 v[236:237], s[78:79], 0, v[134:135]
	s_mov_b32 m0, s91
	global_load_lds_dwordx4 v[236:237], off
	v_lshl_add_u64 v[236:237], s[78:79], 0, v[138:139]
	s_add_i32 m0, s91, 0x2000
	s_nop 0
	global_load_lds_dwordx4 v[236:237], off
	s_waitcnt vmcnt(6)
	s_waitcnt lgkmcnt(0)
	s_barrier
; #define PG8_STAGE(bufoff, gbase, voff) do { _Pragma("unroll") for (int _i = 0; _i < 2; ++_i) \
;         __builtin_amdgcn_global_load_lds((const unsigned*)((const char*)(gbase) + (voff)[_i]), (PG8_LAS unsigned*)(lds + (bufoff) + ldsw + _i * 8192), 16, 0, 0); } while (0)
; #define PG8_LDA(dst, b, h) do { _Pragma("unroll") for (int m = 0; m < 4; ++m) _Pragma("unroll") for (int k = 0; k < 2; ++k) dst[m][k] = *(const PG8_LAS bf16x8*)(lds + PG8_SA(b, h) + aoff + m * 2048 + k * 1024); } while (0)
; #define PG8_LDB(dst, b, h) do { _Pragma("unroll") for (int n = 0; n < 2; ++n) _Pragma("unroll") for (int k = 0; k < 2; ++k) dst[n][k] = *(const PG8_LAS bf16x8*)(lds + PG8_SB(b, h) + boff + n * 2048 + k * 1024); } while (0)
; #define PG8_MMA(ai, bj, At, Bt) do { __builtin_amdgcn_s_setprio(1); _Pragma("unroll") for (int m = 0; m < 4; ++m) _Pragma("unroll") for (int n = 0; n < 2; ++n) _Pragma("unroll") for (int k = 0; k < 2; ++k) \
;         acc[ai][bj][m][n] = __builtin_amdgcn_mfma_f32_16x16x32_bf16(Bt[n][k], At[m][k], acc[ai][bj][m][n], 0, 0, 0); __builtin_amdgcn_s_setprio(0); } while (0)
; #define PG8_BAR __builtin_amdgcn_s_barrier()
; template <class Epi, class Sched, bool ALIGN_EPI = false, bool SP2 = false>
; __device__ __forceinline__ void gemm_phase(PG8_LAS unsigned char* lds, const Gemm g, const Sched& S, const Epi& E) {
;     ...
;             if constexpr (SP2) {
;             PG8_LDB(B0, 0, 0); PG8_LDB(B1, 0, 1); PG8_SCHED; PG8_LDA(At, 0, 0); PG8_STAGE(PG8_SA(1, 1), a1 + hstep, voffA);
;             PG8_WAIT_V(8); PG8_WAIT_L(0); PG8_BAR; PG8_MMA(0, 0, At, B0); PG8_MMA(0, 1, At, B1); PG8_BAR; PG8_SCHED;
;             PG8_LDA(At, 0, 1); PG8_STAGE(PG8_SB(0, 0), b2, voffB); PG8_STAGE(PG8_SB(0, 1), b2 + hstep, voffB); PG8_STAGE(PG8_SA(0, 0), a2, voffA);
;             PG8_WAIT_V(8); PG8_WAIT_L(0); PG8_BAR; PG8_MMA(1, 0, At, B0); PG8_MMA(1, 1, At, B1); PG8_BAR; PG8_SCHED;
;             PG8_LDB(B0, 1, 0); PG8_LDB(B1, 1, 1); PG8_SCHED; PG8_LDA(At, 1, 0); PG8_STAGE(PG8_SA(0, 1), a2 + hstep, voffA);
;             PG8_WAIT_V(8); PG8_WAIT_L(0); PG8_BAR; PG8_MMA(0, 0, At, B0); PG8_MMA(0, 1, At, B1); PG8_BAR; PG8_SCHED;
;             PG8_LDA(At, 1, 1); PG8_STAGE(PG8_SB(1, 0), b3, voffB); PG8_STAGE(PG8_SB(1, 1), b3 + hstep, voffB); PG8_STAGE(PG8_SA(1, 0), a3, voffA);
;             PG8_WAIT_V(8); PG8_WAIT_L(0); PG8_BAR; PG8_MMA(1, 0, At, B0); PG8_MMA(1, 1, At, B1); PG8_BAR; PG8_SCHED;
	s_setprio 1
	s_waitcnt lgkmcnt(0)
	v_mfma_f32_16x16x32_bf16 v[92:95], v[128:131], v[190:193], 0
	v_mfma_f32_16x16x32_bf16 v[80:83], v[164:167], v[198:201], 0
	v_mfma_f32_16x16x32_bf16 v[76:79], v[128:131], v[216:219], 0
	v_mfma_f32_16x16x32_bf16 v[64:67], v[164:167], v[224:227], 0
	v_mfma_f32_16x16x32_bf16 v[84:87], v[128:131], v[198:201], 0
	v_mfma_f32_16x16x32_bf16 v[88:91], v[164:167], v[190:193], 0
	v_mfma_f32_16x16x32_bf16 v[68:71], v[128:131], v[224:227], 0
	v_mfma_f32_16x16x32_bf16 v[72:75], v[164:167], v[216:219], 0
	v_mfma_f32_16x16x32_bf16 v[92:95], v[160:163], v[194:197], v[92:95]
	v_mfma_f32_16x16x32_bf16 v[80:83], v[168:171], v[212:215], v[80:83]
	v_mfma_f32_16x16x32_bf16 v[76:79], v[160:163], v[220:223], v[76:79]
	v_mfma_f32_16x16x32_bf16 v[64:67], v[168:171], v[228:231], v[64:67]
	v_mfma_f32_16x16x32_bf16 v[84:87], v[160:163], v[212:215], v[84:87]
	v_mfma_f32_16x16x32_bf16 v[88:91], v[168:171], v[194:197], v[88:91]
	v_lshl_add_u64 v[236:237], s[64:65], 0, v[132:133]
	s_mov_b32 m0, s15
	s_nop 0
	global_load_lds_dwordx4 v[236:237], off
	v_mfma_f32_16x16x32_bf16 v[68:71], v[160:163], v[228:231], v[68:71]
	v_mfma_f32_16x16x32_bf16 v[72:75], v[168:171], v[220:223], v[72:75]
	s_setprio 0
	s_setprio 1
	v_mfma_f32_16x16x32_bf16 v[28:31], v[172:175], v[190:193], 0
	v_mfma_f32_16x16x32_bf16 v[16:19], v[182:185], v[198:201], 0
	v_mfma_f32_16x16x32_bf16 v[12:15], v[172:175], v[216:219], 0
	v_mfma_f32_16x16x32_bf16 v[0:3], v[182:185], v[224:227], 0
	v_mfma_f32_16x16x32_bf16 v[20:23], v[172:175], v[198:201], 0
	v_mfma_f32_16x16x32_bf16 v[24:27], v[182:185], v[190:193], 0
	v_mfma_f32_16x16x32_bf16 v[4:7], v[172:175], v[224:227], 0
	v_mfma_f32_16x16x32_bf16 v[8:11], v[182:185], v[216:219], 0
	v_mfma_f32_16x16x32_bf16 v[28:31], v[176:179], v[194:197], v[28:31]
	v_mfma_f32_16x16x32_bf16 v[16:19], v[186:189], v[212:215], v[16:19]
	v_mfma_f32_16x16x32_bf16 v[12:15], v[176:179], v[220:223], v[12:15]
	v_mfma_f32_16x16x32_bf16 v[0:3], v[186:189], v[228:231], v[0:3]
	v_mfma_f32_16x16x32_bf16 v[20:23], v[176:179], v[212:215], v[20:23]
	v_mfma_f32_16x16x32_bf16 v[24:27], v[186:189], v[194:197], v[24:27]
	v_lshl_add_u64 v[238:239], s[64:65], 0, v[136:137]
	s_mov_b32 m0, s33
	s_nop 0
	global_load_lds_dwordx4 v[238:239], off
	v_mfma_f32_16x16x32_bf16 v[4:7], v[176:179], v[228:231], v[4:7]
	v_mfma_f32_16x16x32_bf16 v[8:11], v[186:189], v[220:223], v[8:11]
	s_setprio 0
	s_barrier
	s_add_i32 s78, 0, 0x18000
	v_add_u32_e32 v140, s78, v147
	s_add_i32 s79, 0, 0x1c000
	ds_read_b128 v[128:131], v140
	ds_read_b128 v[160:163], v140 offset:1024
	ds_read_b128 v[164:167], v140 offset:2048
	ds_read_b128 v[168:171], v140 offset:3072
	v_add_u32_e32 v140, s79, v147
	ds_read_b128 v[172:175], v140
	ds_read_b128 v[176:179], v140 offset:1024
	ds_read_b128 v[182:185], v140 offset:2048
	ds_read_b128 v[186:189], v140 offset:3072
	s_add_u32 s64, s64, 0x40000
	s_addc_u32 s65, s65, 0
	s_mov_b32 m0, s34
	v_lshl_add_u64 v[240:241], s[64:65], 0, v[132:133]
	ds_read_b128 v[190:193], v208 offset:32768
	ds_read_b128 v[194:197], v208 offset:33792
	ds_read_b128 v[198:201], v208 offset:34816
	ds_read_b128 v[212:215], v208 offset:35840
	ds_read_b128 v[216:219], v208 offset:36864
	ds_read_b128 v[220:223], v208 offset:37888
	ds_read_b128 v[224:227], v208 offset:38912
	ds_read_b128 v[228:231], v208 offset:39936
	global_load_lds_dwordx4 v[240:241], off
	v_lshl_add_u64 v[240:241], s[64:65], 0, v[136:137]
	s_mov_b32 m0, s57
	s_nop 0
	global_load_lds_dwordx4 v[240:241], off
	s_waitcnt vmcnt(8)
	s_waitcnt lgkmcnt(0)
	s_barrier
	s_setprio 1
	s_waitcnt lgkmcnt(0)
	v_mfma_f32_16x16x32_bf16 v[124:127], v[128:131], v[190:193], v[124:127]
	v_mfma_f32_16x16x32_bf16 v[112:115], v[164:167], v[198:201], v[112:115]
	v_mfma_f32_16x16x32_bf16 v[108:111], v[128:131], v[216:219], v[108:111]
	v_mfma_f32_16x16x32_bf16 v[96:99], v[164:167], v[224:227], v[96:99]
	v_mfma_f32_16x16x32_bf16 v[116:119], v[128:131], v[198:201], v[116:119]
	v_mfma_f32_16x16x32_bf16 v[120:123], v[164:167], v[190:193], v[120:123]
	v_mfma_f32_16x16x32_bf16 v[100:103], v[128:131], v[224:227], v[100:103]
	v_mfma_f32_16x16x32_bf16 v[104:107], v[164:167], v[216:219], v[104:107]
	v_mfma_f32_16x16x32_bf16 v[124:127], v[160:163], v[194:197], v[124:127]
	v_mfma_f32_16x16x32_bf16 v[112:115], v[168:171], v[212:215], v[112:115]
	v_mfma_f32_16x16x32_bf16 v[108:111], v[160:163], v[220:223], v[108:111]
	v_mfma_f32_16x16x32_bf16 v[96:99], v[168:171], v[228:231], v[96:99]
	v_mfma_f32_16x16x32_bf16 v[116:119], v[160:163], v[212:215], v[116:119]
	v_mfma_f32_16x16x32_bf16 v[120:123], v[168:171], v[194:197], v[120:123]
	v_mfma_f32_16x16x32_bf16 v[100:103], v[160:163], v[228:231], v[100:103]
	v_mfma_f32_16x16x32_bf16 v[104:107], v[168:171], v[220:223], v[104:107]
	s_setprio 0
	s_setprio 1
	v_mfma_f32_16x16x32_bf16 v[60:63], v[172:175], v[190:193], v[60:63]
	v_mfma_f32_16x16x32_bf16 v[48:51], v[182:185], v[198:201], v[48:51]
	v_mfma_f32_16x16x32_bf16 v[44:47], v[172:175], v[216:219], v[44:47]
	v_mfma_f32_16x16x32_bf16 v[32:35], v[182:185], v[224:227], v[32:35]
	v_mfma_f32_16x16x32_bf16 v[52:55], v[172:175], v[198:201], v[52:55]
	v_mfma_f32_16x16x32_bf16 v[56:59], v[182:185], v[190:193], v[56:59]
	v_mfma_f32_16x16x32_bf16 v[36:39], v[172:175], v[224:227], v[36:39]
	v_mfma_f32_16x16x32_bf16 v[40:43], v[182:185], v[216:219], v[40:43]
	v_mfma_f32_16x16x32_bf16 v[60:63], v[176:179], v[194:197], v[60:63]
	v_mfma_f32_16x16x32_bf16 v[48:51], v[186:189], v[212:215], v[48:51]
	v_mfma_f32_16x16x32_bf16 v[44:47], v[176:179], v[220:223], v[44:47]
	v_mfma_f32_16x16x32_bf16 v[32:35], v[186:189], v[228:231], v[32:35]
	v_mfma_f32_16x16x32_bf16 v[52:55], v[176:179], v[212:215], v[52:55]
	v_mfma_f32_16x16x32_bf16 v[56:59], v[186:189], v[194:197], v[56:59]
	v_mfma_f32_16x16x32_bf16 v[36:39], v[176:179], v[228:231], v[36:39]
	v_mfma_f32_16x16x32_bf16 v[40:43], v[186:189], v[220:223], v[40:43]
	s_setprio 0
	s_barrier
; #define PG8_STAGE(bufoff, gbase, voff) do { _Pragma("unroll") for (int _i = 0; _i < 2; ++_i) \
;         __builtin_amdgcn_global_load_lds((const unsigned*)((const char*)(gbase) + (voff)[_i]), (PG8_LAS unsigned*)(lds + (bufoff) + ldsw + _i * 8192), 16, 0, 0); } while (0)
; #define PG8_LDA(dst, b, h) do { _Pragma("unroll") for (int m = 0; m < 4; ++m) _Pragma("unroll") for (int k = 0; k < 2; ++k) dst[m][k] = *(const PG8_LAS bf16x8*)(lds + PG8_SA(b, h) + aoff + m * 2048 + k * 1024); } while (0)
; #define PG8_LDB(dst, b, h) do { _Pragma("unroll") for (int n = 0; n < 2; ++n) _Pragma("unroll") for (int k = 0; k < 2; ++k) dst[n][k] = *(const PG8_LAS bf16x8*)(lds + PG8_SB(b, h) + boff + n * 2048 + k * 1024); } while (0)
; #define PG8_WAIT_V(n) asm volatile("s_waitcnt vmcnt(" #n ")" ::: "memory")
; #define PG8_BAR __builtin_amdgcn_s_barrier()
; template <class Epi, class Sched, bool ALIGN_EPI = false, bool SP2 = false>
; __device__ __forceinline__ void gemm_phase(PG8_LAS unsigned char* lds, const Gemm g, const Sched& S, const Epi& E) {
;     ...
;         for (int t = 0; t < nt; t += 2) {
;             const bool last = (t == nt - 2);
;             const char* a1 = cA + (size_t)(t + 1) * kstep;
;             const char* a2 = last ? nA : cA + (size_t)(t + 2) * kstep; const char* b2 = last ? nB : cB + (size_t)(t + 2) * kstep;
;             const char* a3 = a2 + kstep; const char* b3 = b2 + kstep;
;             if (last && has_next) S.a_ready(nxt);
;             if constexpr (SP2) {
;             PG8_LDB(B0, 0, 0); PG8_LDB(B1, 0, 1); PG8_SCHED; PG8_LDA(At, 0, 0); PG8_STAGE(PG8_SA(1, 1), a1 + hstep, voffA);
;     ...
;             PG8_LDA(At, 0, 1); PG8_STAGE(PG8_SB(0, 0), b2, voffB); PG8_STAGE(PG8_SB(0, 1), b2 + hstep, voffB); PG8_STAGE(PG8_SA(0, 0), a2, voffA);
;             PG8_WAIT_V(8); PG8_WAIT_L(0); PG8_BAR; PG8_MMA(1, 0, At, B0); PG8_MMA(1, 1, At, B1); PG8_BAR; PG8_SCHED;
;             PG8_LDB(B0, 1, 0); PG8_LDB(B1, 1, 1); PG8_SCHED; PG8_LDA(At, 1, 0); PG8_STAGE(PG8_SA(0, 1), a2 + hstep, voffA);
;             PG8_WAIT_V(8); PG8_WAIT_L(0); PG8_BAR; PG8_MMA(0, 0, At, B0); PG8_MMA(0, 1, At, B1); PG8_BAR; PG8_SCHED;
;             PG8_LDA(At, 1, 1); PG8_STAGE(PG8_SB(1, 0), b3, voffB); PG8_STAGE(PG8_SB(1, 1), b3 + hstep, voffB); PG8_STAGE(PG8_SA(1, 0), a3, voffA);
;             PG8_WAIT_V(8); PG8_WAIT_L(0); PG8_BAR; PG8_MMA(1, 0, At, B0); PG8_MMA(1, 1, At, B1); PG8_BAR; PG8_SCHED;
	s_add_i32 s64, s78, s14
	v_lshl_add_u64 v[232:233], v[232:233], 0, s[42:43]
	s_mov_b32 m0, s64
	ds_read_b128 v[190:193], v208 offset:49152
	ds_read_b128 v[194:197], v208 offset:50176
	ds_read_b128 v[198:201], v208 offset:51200
	ds_read_b128 v[212:215], v208 offset:52224
	ds_read_b128 v[216:219], v208 offset:53248
	ds_read_b128 v[220:223], v208 offset:54272
	ds_read_b128 v[224:227], v208 offset:55296
	ds_read_b128 v[228:231], v208 offset:56320
	global_load_lds_dwordx4 v[232:233], off
	s_add_i32 m0, s64, 0x2000
	s_add_u32 s62, s62, 0x40080
	v_lshl_add_u64 v[232:233], v[234:235], 0, s[42:43]
	s_addc_u32 s63, s63, 0
	s_add_i32 s64, s79, s14
	global_load_lds_dwordx4 v[232:233], off
	v_lshl_add_u64 v[232:233], s[62:63], 0, v[134:135]
	s_mov_b32 m0, s64
	s_nop 0
	global_load_lds_dwordx4 v[232:233], off
	v_lshl_add_u64 v[232:233], s[62:63], 0, v[138:139]
	s_add_i32 m0, s64, 0x2000
	s_nop 0
	global_load_lds_dwordx4 v[232:233], off
	s_waitcnt vmcnt(6)
	s_waitcnt lgkmcnt(0)
	s_barrier
	s_setprio 1
	s_waitcnt lgkmcnt(0)
	v_mfma_f32_16x16x32_bf16 v[92:95], v[128:131], v[190:193], v[92:95]
	v_mfma_f32_16x16x32_bf16 v[80:83], v[164:167], v[198:201], v[80:83]
	v_mfma_f32_16x16x32_bf16 v[76:79], v[128:131], v[216:219], v[76:79]
	v_mfma_f32_16x16x32_bf16 v[64:67], v[164:167], v[224:227], v[64:67]
	v_mfma_f32_16x16x32_bf16 v[84:87], v[128:131], v[198:201], v[84:87]
	v_mfma_f32_16x16x32_bf16 v[88:91], v[164:167], v[190:193], v[88:91]
	v_mfma_f32_16x16x32_bf16 v[68:71], v[128:131], v[224:227], v[68:71]
	v_mfma_f32_16x16x32_bf16 v[72:75], v[164:167], v[216:219], v[72:75]
	v_mfma_f32_16x16x32_bf16 v[92:95], v[160:163], v[194:197], v[92:95]
	v_mfma_f32_16x16x32_bf16 v[80:83], v[168:171], v[212:215], v[80:83]
	v_mfma_f32_16x16x32_bf16 v[76:79], v[160:163], v[220:223], v[76:79]
	v_mfma_f32_16x16x32_bf16 v[64:67], v[168:171], v[228:231], v[64:67]
	v_mfma_f32_16x16x32_bf16 v[84:87], v[160:163], v[212:215], v[84:87]
	v_mfma_f32_16x16x32_bf16 v[88:91], v[168:171], v[194:197], v[88:91]
	v_lshl_add_u64 v[232:233], v[236:237], 0, s[42:43]
	s_mov_b32 m0, s67
	s_nop 0
	global_load_lds_dwordx4 v[232:233], off
	v_mfma_f32_16x16x32_bf16 v[68:71], v[160:163], v[228:231], v[68:71]
	v_mfma_f32_16x16x32_bf16 v[72:75], v[168:171], v[220:223], v[72:75]
	s_setprio 0
	s_setprio 1
	v_mfma_f32_16x16x32_bf16 v[28:31], v[172:175], v[190:193], v[28:31]
	v_mfma_f32_16x16x32_bf16 v[16:19], v[182:185], v[198:201], v[16:19]
	v_mfma_f32_16x16x32_bf16 v[12:15], v[172:175], v[216:219], v[12:15]
	v_mfma_f32_16x16x32_bf16 v[0:3], v[182:185], v[224:227], v[0:3]
	v_mfma_f32_16x16x32_bf16 v[20:23], v[172:175], v[198:201], v[20:23]
	v_mfma_f32_16x16x32_bf16 v[24:27], v[182:185], v[190:193], v[24:27]
	v_mfma_f32_16x16x32_bf16 v[4:7], v[172:175], v[224:227], v[4:7]
	v_mfma_f32_16x16x32_bf16 v[8:11], v[182:185], v[216:219], v[8:11]
	v_mfma_f32_16x16x32_bf16 v[28:31], v[176:179], v[194:197], v[28:31]
	v_mfma_f32_16x16x32_bf16 v[16:19], v[186:189], v[212:215], v[16:19]
	v_mfma_f32_16x16x32_bf16 v[12:15], v[176:179], v[220:223], v[12:15]
	v_mfma_f32_16x16x32_bf16 v[0:3], v[186:189], v[228:231], v[0:3]
	v_mfma_f32_16x16x32_bf16 v[20:23], v[176:179], v[212:215], v[20:23]
	v_mfma_f32_16x16x32_bf16 v[24:27], v[186:189], v[194:197], v[24:27]
	v_lshl_add_u64 v[232:233], v[238:239], 0, s[42:43]
	s_mov_b32 m0, s74
	s_nop 0
	global_load_lds_dwordx4 v[232:233], off
	v_mfma_f32_16x16x32_bf16 v[4:7], v[176:179], v[228:231], v[4:7]
	v_mfma_f32_16x16x32_bf16 v[8:11], v[186:189], v[220:223], v[8:11]
	s_setprio 0
	s_barrier
	s_add_i32 s90, s90, 2
	s_add_u32 s58, s58, 0x100
	s_addc_u32 s59, s59, 0
	s_add_u32 s88, s88, 0x100
	s_addc_u32 s89, s89, 0
.LBB0_1287:
	ds_read_b128 v[128:131], v181
	ds_read_b128 v[160:163], v181 offset:1024
	ds_read_b128 v[164:167], v181 offset:2048
	ds_read_b128 v[168:171], v181 offset:3072
	ds_read_b128 v[172:175], v203
	ds_read_b128 v[176:179], v203 offset:1024
	ds_read_b128 v[182:185], v203 offset:2048
	ds_read_b128 v[186:189], v203 offset:3072
	s_add_u32 s62, s58, 0xfffc0080
	s_addc_u32 s63, s59, -1
	s_cmp_eq_u32 s90, 12
	s_cselect_b32 s65, s51, s63
	s_cselect_b32 s64, s61, s62
	s_cselect_b32 s63, s49, s89
	s_cselect_b32 s62, s87, s88
	v_lshl_add_u64 v[232:233], s[58:59], 0, v[152:153]
	s_add_i32 m0, s15, 0xc000
	ds_read_b128 v[190:193], v208
	ds_read_b128 v[194:197], v208 offset:1024
	ds_read_b128 v[198:201], v208 offset:2048
	ds_read_b128 v[212:215], v208 offset:3072
	ds_read_b128 v[216:219], v208 offset:4096
	ds_read_b128 v[220:223], v208 offset:5120
	ds_read_b128 v[224:227], v208 offset:6144
	ds_read_b128 v[228:231], v208 offset:7168
	global_load_lds_dwordx4 v[232:233], off
	v_lshl_add_u64 v[232:233], s[58:59], 0, v[154:155]
	s_add_i32 m0, s15, 0xe000
	s_nop 0
	global_load_lds_dwordx4 v[232:233], off
	s_waitcnt vmcnt(8)
	s_waitcnt lgkmcnt(0)
	s_barrier
; #define PG8_STAGE(bufoff, gbase, voff) do { _Pragma("unroll") for (int _i = 0; _i < 2; ++_i) \
;         __builtin_amdgcn_global_load_lds((const unsigned*)((const char*)(gbase) + (voff)[_i]), (PG8_LAS unsigned*)(lds + (bufoff) + ldsw + _i * 8192), 16, 0, 0); } while (0)
; #define PG8_LDA(dst, b, h) do { _Pragma("unroll") for (int m = 0; m < 4; ++m) _Pragma("unroll") for (int k = 0; k < 2; ++k) dst[m][k] = *(const PG8_LAS bf16x8*)(lds + PG8_SA(b, h) + aoff + m * 2048 + k * 1024); } while (0)
; #define PG8_LDB(dst, b, h) do { _Pragma("unroll") for (int n = 0; n < 2; ++n) _Pragma("unroll") for (int k = 0; k < 2; ++k) dst[n][k] = *(const PG8_LAS bf16x8*)(lds + PG8_SB(b, h) + boff + n * 2048 + k * 1024); } while (0)
; #define PG8_MMA(ai, bj, At, Bt) do { __builtin_amdgcn_s_setprio(1); _Pragma("unroll") for (int m = 0; m < 4; ++m) _Pragma("unroll") for (int n = 0; n < 2; ++n) _Pragma("unroll") for (int k = 0; k < 2; ++k) \
;         acc[ai][bj][m][n] = __builtin_amdgcn_mfma_f32_16x16x32_bf16(Bt[n][k], At[m][k], acc[ai][bj][m][n], 0, 0, 0); __builtin_amdgcn_s_setprio(0); } while (0)
; #define PG8_WAIT_V(n) asm volatile("s_waitcnt vmcnt(" #n ")" ::: "memory")
; #define PG8_WAIT_L(n) asm volatile("s_waitcnt lgkmcnt(" #n ")" ::: "memory")
; #define PG8_BAR __builtin_amdgcn_s_barrier()
; #define PG8_SCHED __builtin_amdgcn_sched_barrier(0)
; template <class Epi, class Sched, bool ALIGN_EPI = false, bool SP2 = false>
; __device__ __forceinline__ void gemm_phase(PG8_LAS unsigned char* lds, const Gemm g, const Sched& S, const Epi& E) {
;     ...
;             if constexpr (SP2) {
;             PG8_LDB(B0, 0, 0); PG8_LDB(B1, 0, 1); PG8_SCHED; PG8_LDA(At, 0, 0); PG8_STAGE(PG8_SA(1, 1), a1 + hstep, voffA);
;             PG8_WAIT_V(8); PG8_WAIT_L(0); PG8_BAR; PG8_MMA(0, 0, At, B0); PG8_MMA(0, 1, At, B1); PG8_BAR; PG8_SCHED;
;             PG8_LDA(At, 0, 1); PG8_STAGE(PG8_SB(0, 0), b2, voffB); PG8_STAGE(PG8_SB(0, 1), b2 + hstep, voffB); PG8_STAGE(PG8_SA(0, 0), a2, voffA);
;             PG8_WAIT_V(8); PG8_WAIT_L(0); PG8_BAR; PG8_MMA(1, 0, At, B0); PG8_MMA(1, 1, At, B1); PG8_BAR; PG8_SCHED;
	s_setprio 1
	s_waitcnt lgkmcnt(0)
	v_mfma_f32_16x16x32_bf16 v[124:127], v[128:131], v[190:193], v[124:127]
	v_mfma_f32_16x16x32_bf16 v[112:115], v[164:167], v[198:201], v[112:115]
	v_mfma_f32_16x16x32_bf16 v[108:111], v[128:131], v[216:219], v[108:111]
	v_mfma_f32_16x16x32_bf16 v[96:99], v[164:167], v[224:227], v[96:99]
	v_mfma_f32_16x16x32_bf16 v[116:119], v[128:131], v[198:201], v[116:119]
	v_mfma_f32_16x16x32_bf16 v[120:123], v[164:167], v[190:193], v[120:123]
	v_mfma_f32_16x16x32_bf16 v[100:103], v[128:131], v[224:227], v[100:103]
	v_mfma_f32_16x16x32_bf16 v[104:107], v[164:167], v[216:219], v[104:107]
	v_mfma_f32_16x16x32_bf16 v[124:127], v[160:163], v[194:197], v[124:127]
	v_mfma_f32_16x16x32_bf16 v[112:115], v[168:171], v[212:215], v[112:115]
	v_mfma_f32_16x16x32_bf16 v[108:111], v[160:163], v[220:223], v[108:111]
	v_mfma_f32_16x16x32_bf16 v[96:99], v[168:171], v[228:231], v[96:99]
	v_mfma_f32_16x16x32_bf16 v[116:119], v[160:163], v[212:215], v[116:119]
	v_mfma_f32_16x16x32_bf16 v[120:123], v[168:171], v[194:197], v[120:123]
	v_mfma_f32_16x16x32_bf16 v[100:103], v[160:163], v[228:231], v[100:103]
	v_mfma_f32_16x16x32_bf16 v[104:107], v[168:171], v[220:223], v[104:107]
	s_setprio 0
	s_setprio 1
	v_mfma_f32_16x16x32_bf16 v[60:63], v[172:175], v[190:193], v[60:63]
	v_mfma_f32_16x16x32_bf16 v[48:51], v[182:185], v[198:201], v[48:51]
	v_mfma_f32_16x16x32_bf16 v[44:47], v[172:175], v[216:219], v[44:47]
	v_mfma_f32_16x16x32_bf16 v[32:35], v[182:185], v[224:227], v[32:35]
	v_mfma_f32_16x16x32_bf16 v[52:55], v[172:175], v[198:201], v[52:55]
	v_mfma_f32_16x16x32_bf16 v[56:59], v[182:185], v[190:193], v[56:59]
	v_mfma_f32_16x16x32_bf16 v[36:39], v[172:175], v[224:227], v[36:39]
	v_mfma_f32_16x16x32_bf16 v[40:43], v[182:185], v[216:219], v[40:43]
	v_mfma_f32_16x16x32_bf16 v[60:63], v[176:179], v[194:197], v[60:63]
	v_mfma_f32_16x16x32_bf16 v[48:51], v[186:189], v[212:215], v[48:51]
	v_mfma_f32_16x16x32_bf16 v[44:47], v[176:179], v[220:223], v[44:47]
	v_mfma_f32_16x16x32_bf16 v[32:35], v[186:189], v[228:231], v[32:35]
	v_mfma_f32_16x16x32_bf16 v[52:55], v[176:179], v[212:215], v[52:55]
	v_mfma_f32_16x16x32_bf16 v[56:59], v[186:189], v[194:197], v[56:59]
	v_mfma_f32_16x16x32_bf16 v[36:39], v[176:179], v[228:231], v[36:39]
	v_mfma_f32_16x16x32_bf16 v[40:43], v[186:189], v[220:223], v[40:43]
	s_setprio 0
	s_barrier
	s_add_i32 s78, s75, s14
	v_lshl_add_u64 v[232:233], s[62:63], 0, v[134:135]
	s_mov_b32 m0, s78
	ds_read_b128 v[190:193], v208 offset:16384
	ds_read_b128 v[194:197], v208 offset:17408
	ds_read_b128 v[198:201], v208 offset:18432
	ds_read_b128 v[212:215], v208 offset:19456
	ds_read_b128 v[216:219], v208 offset:20480
	ds_read_b128 v[220:223], v208 offset:21504
	ds_read_b128 v[224:227], v208 offset:22528
	ds_read_b128 v[228:231], v208 offset:23552
	global_load_lds_dwordx4 v[232:233], off
	s_add_i32 m0, s78, 0x2000
	s_add_u32 s78, s62, 0x40000
	v_lshl_add_u64 v[234:235], s[62:63], 0, v[138:139]
	s_addc_u32 s79, s63, 0
	s_add_i32 s91, s76, s14
	global_load_lds_dwordx4 v[234:235], off
	v_lshl_add_u64 v[236:237], s[78:79], 0, v[134:135]
	s_mov_b32 m0, s91
	global_load_lds_dwordx4 v[236:237], off
	v_lshl_add_u64 v[236:237], s[78:79], 0, v[138:139]
	s_add_i32 m0, s91, 0x2000
	s_nop 0
	global_load_lds_dwordx4 v[236:237], off
	s_waitcnt vmcnt(6)
	s_waitcnt lgkmcnt(0)
	s_barrier
	s_setprio 1
	s_waitcnt lgkmcnt(0)
	v_mfma_f32_16x16x32_bf16 v[92:95], v[128:131], v[190:193], v[92:95]
	v_mfma_f32_16x16x32_bf16 v[80:83], v[164:167], v[198:201], v[80:83]
	v_mfma_f32_16x16x32_bf16 v[76:79], v[128:131], v[216:219], v[76:79]
	v_mfma_f32_16x16x32_bf16 v[64:67], v[164:167], v[224:227], v[64:67]
	v_mfma_f32_16x16x32_bf16 v[84:87], v[128:131], v[198:201], v[84:87]
	v_mfma_f32_16x16x32_bf16 v[88:91], v[164:167], v[190:193], v[88:91]
	v_mfma_f32_16x16x32_bf16 v[68:71], v[128:131], v[224:227], v[68:71]
	v_mfma_f32_16x16x32_bf16 v[72:75], v[164:167], v[216:219], v[72:75]
	v_mfma_f32_16x16x32_bf16 v[92:95], v[160:163], v[194:197], v[92:95]
	v_mfma_f32_16x16x32_bf16 v[80:83], v[168:171], v[212:215], v[80:83]
	v_mfma_f32_16x16x32_bf16 v[76:79], v[160:163], v[220:223], v[76:79]
	v_mfma_f32_16x16x32_bf16 v[64:67], v[168:171], v[228:231], v[64:67]
	v_mfma_f32_16x16x32_bf16 v[84:87], v[160:163], v[212:215], v[84:87]
	v_mfma_f32_16x16x32_bf16 v[88:91], v[168:171], v[194:197], v[88:91]
	v_lshl_add_u64 v[236:237], s[64:65], 0, v[132:133]
	s_mov_b32 m0, s15
	s_nop 0
	global_load_lds_dwordx4 v[236:237], off
	v_mfma_f32_16x16x32_bf16 v[68:71], v[160:163], v[228:231], v[68:71]
	v_mfma_f32_16x16x32_bf16 v[72:75], v[168:171], v[220:223], v[72:75]
	s_setprio 0
	s_setprio 1
	v_mfma_f32_16x16x32_bf16 v[28:31], v[172:175], v[190:193], v[28:31]
	v_mfma_f32_16x16x32_bf16 v[16:19], v[182:185], v[198:201], v[16:19]
	v_mfma_f32_16x16x32_bf16 v[12:15], v[172:175], v[216:219], v[12:15]
	v_mfma_f32_16x16x32_bf16 v[0:3], v[182:185], v[224:227], v[0:3]
	v_mfma_f32_16x16x32_bf16 v[20:23], v[172:175], v[198:201], v[20:23]
	v_mfma_f32_16x16x32_bf16 v[24:27], v[182:185], v[190:193], v[24:27]
	v_mfma_f32_16x16x32_bf16 v[4:7], v[172:175], v[224:227], v[4:7]
	v_mfma_f32_16x16x32_bf16 v[8:11], v[182:185], v[216:219], v[8:11]
	v_mfma_f32_16x16x32_bf16 v[28:31], v[176:179], v[194:197], v[28:31]
	v_mfma_f32_16x16x32_bf16 v[16:19], v[186:189], v[212:215], v[16:19]
	v_mfma_f32_16x16x32_bf16 v[12:15], v[176:179], v[220:223], v[12:15]
	v_mfma_f32_16x16x32_bf16 v[0:3], v[186:189], v[228:231], v[0:3]
	v_mfma_f32_16x16x32_bf16 v[20:23], v[176:179], v[212:215], v[20:23]
	v_mfma_f32_16x16x32_bf16 v[24:27], v[186:189], v[194:197], v[24:27]
	v_lshl_add_u64 v[238:239], s[64:65], 0, v[136:137]
	s_mov_b32 m0, s33
	s_nop 0
	global_load_lds_dwordx4 v[238:239], off
	v_mfma_f32_16x16x32_bf16 v[4:7], v[176:179], v[228:231], v[4:7]
	v_mfma_f32_16x16x32_bf16 v[8:11], v[186:189], v[220:223], v[8:11]
	s_setprio 0
	s_barrier
; #define PG8_STAGE(bufoff, gbase, voff) do { _Pragma("unroll") for (int _i = 0; _i < 2; ++_i) \
;         __builtin_amdgcn_global_load_lds((const unsigned*)((const char*)(gbase) + (voff)[_i]), (PG8_LAS unsigned*)(lds + (bufoff) + ldsw + _i * 8192), 16, 0, 0); } while (0)
; #define PG8_LDA(dst, b, h) do { _Pragma("unroll") for (int m = 0; m < 4; ++m) _Pragma("unroll") for (int k = 0; k < 2; ++k) dst[m][k] = *(const PG8_LAS bf16x8*)(lds + PG8_SA(b, h) + aoff + m * 2048 + k * 1024); } while (0)
; #define PG8_LDB(dst, b, h) do { _Pragma("unroll") for (int n = 0; n < 2; ++n) _Pragma("unroll") for (int k = 0; k < 2; ++k) dst[n][k] = *(const PG8_LAS bf16x8*)(lds + PG8_SB(b, h) + boff + n * 2048 + k * 1024); } while (0)
; #define PG8_MMA(ai, bj, At, Bt) do { __builtin_amdgcn_s_setprio(1); _Pragma("unroll") for (int m = 0; m < 4; ++m) _Pragma("unroll") for (int n = 0; n < 2; ++n) _Pragma("unroll") for (int k = 0; k < 2; ++k) \
;         acc[ai][bj][m][n] = __builtin_amdgcn_mfma_f32_16x16x32_bf16(Bt[n][k], At[m][k], acc[ai][bj][m][n], 0, 0, 0); __builtin_amdgcn_s_setprio(0); } while (0)
; #define PG8_WAIT_V(n) asm volatile("s_waitcnt vmcnt(" #n ")" ::: "memory")
; #define PG8_WAIT_L(n) asm volatile("s_waitcnt lgkmcnt(" #n ")" ::: "memory")
; #define PG8_BAR __builtin_amdgcn_s_barrier()
; #define PG8_SCHED __builtin_amdgcn_sched_barrier(0)
; template <class Epi, class Sched, bool ALIGN_EPI = false, bool SP2 = false>
; __device__ __forceinline__ void gemm_phase(PG8_LAS unsigned char* lds, const Gemm g, const Sched& S, const Epi& E) {
;     ...
;             PG8_LDB(B0, 1, 0); PG8_LDB(B1, 1, 1); PG8_SCHED; PG8_LDA(At, 1, 0); PG8_STAGE(PG8_SA(0, 1), a2 + hstep, voffA);
;             PG8_WAIT_V(8); PG8_WAIT_L(0); PG8_BAR; PG8_MMA(0, 0, At, B0); PG8_MMA(0, 1, At, B1); PG8_BAR; PG8_SCHED;
	s_add_i32 s78, 0, 0x18000
	v_add_u32_e32 v140, s78, v147
	s_add_i32 s79, 0, 0x1c000
	ds_read_b128 v[128:131], v140
	ds_read_b128 v[160:163], v140 offset:1024
	ds_read_b128 v[164:167], v140 offset:2048
	ds_read_b128 v[168:171], v140 offset:3072
	v_add_u32_e32 v140, s79, v147
	ds_read_b128 v[172:175], v140
	ds_read_b128 v[176:179], v140 offset:1024
	ds_read_b128 v[182:185], v140 offset:2048
	ds_read_b128 v[186:189], v140 offset:3072
	s_add_u32 s64, s64, 0x40000
	s_addc_u32 s65, s65, 0
	s_mov_b32 m0, s34
	v_lshl_add_u64 v[240:241], s[64:65], 0, v[132:133]
	ds_read_b128 v[190:193], v208 offset:32768
	ds_read_b128 v[194:197], v208 offset:33792
	ds_read_b128 v[198:201], v208 offset:34816
	ds_read_b128 v[212:215], v208 offset:35840
	ds_read_b128 v[216:219], v208 offset:36864
	ds_read_b128 v[220:223], v208 offset:37888
	ds_read_b128 v[224:227], v208 offset:38912
	ds_read_b128 v[228:231], v208 offset:39936
	global_load_lds_dwordx4 v[240:241], off
	v_lshl_add_u64 v[240:241], s[64:65], 0, v[136:137]
	s_mov_b32 m0, s57
	s_nop 0
	global_load_lds_dwordx4 v[240:241], off
	s_waitcnt vmcnt(8)
	s_waitcnt lgkmcnt(0)
	s_barrier
	s_setprio 1
	s_waitcnt lgkmcnt(0)
	v_mfma_f32_16x16x32_bf16 v[124:127], v[128:131], v[190:193], v[124:127]
	v_mfma_f32_16x16x32_bf16 v[112:115], v[164:167], v[198:201], v[112:115]
	v_mfma_f32_16x16x32_bf16 v[108:111], v[128:131], v[216:219], v[108:111]
	v_mfma_f32_16x16x32_bf16 v[96:99], v[164:167], v[224:227], v[96:99]
	v_mfma_f32_16x16x32_bf16 v[116:119], v[128:131], v[198:201], v[116:119]
	v_mfma_f32_16x16x32_bf16 v[120:123], v[164:167], v[190:193], v[120:123]
	v_mfma_f32_16x16x32_bf16 v[100:103], v[128:131], v[224:227], v[100:103]
	v_mfma_f32_16x16x32_bf16 v[104:107], v[164:167], v[216:219], v[104:107]
	v_mfma_f32_16x16x32_bf16 v[124:127], v[160:163], v[194:197], v[124:127]
	v_mfma_f32_16x16x32_bf16 v[112:115], v[168:171], v[212:215], v[112:115]
	v_mfma_f32_16x16x32_bf16 v[108:111], v[160:163], v[220:223], v[108:111]
	v_mfma_f32_16x16x32_bf16 v[96:99], v[168:171], v[228:231], v[96:99]
	v_mfma_f32_16x16x32_bf16 v[116:119], v[160:163], v[212:215], v[116:119]
	v_mfma_f32_16x16x32_bf16 v[120:123], v[168:171], v[194:197], v[120:123]
	v_mfma_f32_16x16x32_bf16 v[100:103], v[160:163], v[228:231], v[100:103]
	v_mfma_f32_16x16x32_bf16 v[104:107], v[168:171], v[220:223], v[104:107]
	s_setprio 0
	s_setprio 1
	v_mfma_f32_16x16x32_bf16 v[60:63], v[172:175], v[190:193], v[60:63]
	v_mfma_f32_16x16x32_bf16 v[48:51], v[182:185], v[198:201], v[48:51]
	v_mfma_f32_16x16x32_bf16 v[44:47], v[172:175], v[216:219], v[44:47]
	v_mfma_f32_16x16x32_bf16 v[32:35], v[182:185], v[224:227], v[32:35]
	v_mfma_f32_16x16x32_bf16 v[52:55], v[172:175], v[198:201], v[52:55]
	v_mfma_f32_16x16x32_bf16 v[56:59], v[182:185], v[190:193], v[56:59]
	v_mfma_f32_16x16x32_bf16 v[36:39], v[172:175], v[224:227], v[36:39]
	v_mfma_f32_16x16x32_bf16 v[40:43], v[182:185], v[216:219], v[40:43]
	v_mfma_f32_16x16x32_bf16 v[60:63], v[176:179], v[194:197], v[60:63]
	v_mfma_f32_16x16x32_bf16 v[48:51], v[186:189], v[212:215], v[48:51]
	v_mfma_f32_16x16x32_bf16 v[44:47], v[176:179], v[220:223], v[44:47]
	v_mfma_f32_16x16x32_bf16 v[32:35], v[186:189], v[228:231], v[32:35]
	v_mfma_f32_16x16x32_bf16 v[52:55], v[176:179], v[212:215], v[52:55]
	v_mfma_f32_16x16x32_bf16 v[56:59], v[186:189], v[194:197], v[56:59]
	v_mfma_f32_16x16x32_bf16 v[36:39], v[176:179], v[228:231], v[36:39]
	v_mfma_f32_16x16x32_bf16 v[40:43], v[186:189], v[220:223], v[40:43]
	s_setprio 0
	s_barrier
; #define PG8_STAGE(bufoff, gbase, voff) do { _Pragma("unroll") for (int _i = 0; _i < 2; ++_i) \
;         __builtin_amdgcn_global_load_lds((const unsigned*)((const char*)(gbase) + (voff)[_i]), (PG8_LAS unsigned*)(lds + (bufoff) + ldsw + _i * 8192), 16, 0, 0); } while (0)
; #define PG8_LDA(dst, b, h) do { _Pragma("unroll") for (int m = 0; m < 4; ++m) _Pragma("unroll") for (int k = 0; k < 2; ++k) dst[m][k] = *(const PG8_LAS bf16x8*)(lds + PG8_SA(b, h) + aoff + m * 2048 + k * 1024); } while (0)
; #define PG8_MMA(ai, bj, At, Bt) do { __builtin_amdgcn_s_setprio(1); _Pragma("unroll") for (int m = 0; m < 4; ++m) _Pragma("unroll") for (int n = 0; n < 2; ++n) _Pragma("unroll") for (int k = 0; k < 2; ++k) \
;         acc[ai][bj][m][n] = __builtin_amdgcn_mfma_f32_16x16x32_bf16(Bt[n][k], At[m][k], acc[ai][bj][m][n], 0, 0, 0); __builtin_amdgcn_s_setprio(0); } while (0)
; #define PG8_WAIT_V(n) asm volatile("s_waitcnt vmcnt(" #n ")" ::: "memory")
; #define PG8_WAIT_L(n) asm volatile("s_waitcnt lgkmcnt(" #n ")" ::: "memory")
; #define PG8_BAR __builtin_amdgcn_s_barrier()
; #define PG8_SCHED __builtin_amdgcn_sched_barrier(0)
; template <class Epi, class Sched, bool ALIGN_EPI = false, bool SP2 = false>
; __device__ __forceinline__ void gemm_phase(PG8_LAS unsigned char* lds, const Gemm g, const Sched& S, const Epi& E) {
;     ...
;         for (int t = 0; t < nt; t += 2) {
;             const bool last = (t == nt - 2);
;     ...
;             PG8_LDA(At, 1, 1); PG8_STAGE(PG8_SB(1, 0), b3, voffB); PG8_STAGE(PG8_SB(1, 1), b3 + hstep, voffB); PG8_STAGE(PG8_SA(1, 0), a3, voffA);
;             PG8_WAIT_V(8); PG8_WAIT_L(0); PG8_BAR; PG8_MMA(1, 0, At, B0); PG8_MMA(1, 1, At, B1); PG8_BAR; PG8_SCHED;
;     ...
;         if constexpr (ALIGN_EPI) { if (wr == 0) PG8_BAR; }
	s_add_i32 s64, s78, s14
	v_lshl_add_u64 v[232:233], v[232:233], 0, s[42:43]
	s_mov_b32 m0, s64
	ds_read_b128 v[190:193], v208 offset:49152
	ds_read_b128 v[194:197], v208 offset:50176
	ds_read_b128 v[198:201], v208 offset:51200
	ds_read_b128 v[212:215], v208 offset:52224
	ds_read_b128 v[216:219], v208 offset:53248
	ds_read_b128 v[220:223], v208 offset:54272
	ds_read_b128 v[224:227], v208 offset:55296
	ds_read_b128 v[228:231], v208 offset:56320
	global_load_lds_dwordx4 v[232:233], off
	s_add_i32 m0, s64, 0x2000
	s_add_u32 s62, s62, 0x40080
	v_lshl_add_u64 v[232:233], v[234:235], 0, s[42:43]
	s_addc_u32 s63, s63, 0
	s_add_i32 s64, s79, s14
	global_load_lds_dwordx4 v[232:233], off
	v_lshl_add_u64 v[232:233], s[62:63], 0, v[134:135]
	s_mov_b32 m0, s64
	s_nop 0
	global_load_lds_dwordx4 v[232:233], off
	v_lshl_add_u64 v[232:233], s[62:63], 0, v[138:139]
	s_add_i32 m0, s64, 0x2000
	s_nop 0
	global_load_lds_dwordx4 v[232:233], off
	s_waitcnt vmcnt(6)
	s_waitcnt lgkmcnt(0)
	s_barrier
	s_setprio 1
	s_waitcnt lgkmcnt(0)
	v_mfma_f32_16x16x32_bf16 v[92:95], v[128:131], v[190:193], v[92:95]
	v_mfma_f32_16x16x32_bf16 v[80:83], v[164:167], v[198:201], v[80:83]
	v_mfma_f32_16x16x32_bf16 v[76:79], v[128:131], v[216:219], v[76:79]
	v_mfma_f32_16x16x32_bf16 v[64:67], v[164:167], v[224:227], v[64:67]
	v_mfma_f32_16x16x32_bf16 v[84:87], v[128:131], v[198:201], v[84:87]
	v_mfma_f32_16x16x32_bf16 v[88:91], v[164:167], v[190:193], v[88:91]
	v_mfma_f32_16x16x32_bf16 v[68:71], v[128:131], v[224:227], v[68:71]
	v_mfma_f32_16x16x32_bf16 v[72:75], v[164:167], v[216:219], v[72:75]
	v_mfma_f32_16x16x32_bf16 v[92:95], v[160:163], v[194:197], v[92:95]
	v_mfma_f32_16x16x32_bf16 v[80:83], v[168:171], v[212:215], v[80:83]
	v_mfma_f32_16x16x32_bf16 v[76:79], v[160:163], v[220:223], v[76:79]
	v_mfma_f32_16x16x32_bf16 v[64:67], v[168:171], v[228:231], v[64:67]
	v_mfma_f32_16x16x32_bf16 v[84:87], v[160:163], v[212:215], v[84:87]
	v_mfma_f32_16x16x32_bf16 v[88:91], v[168:171], v[194:197], v[88:91]
	v_lshl_add_u64 v[232:233], v[236:237], 0, s[42:43]
	s_mov_b32 m0, s67
	s_nop 0
	global_load_lds_dwordx4 v[232:233], off
	v_mfma_f32_16x16x32_bf16 v[68:71], v[160:163], v[228:231], v[68:71]
	v_mfma_f32_16x16x32_bf16 v[72:75], v[168:171], v[220:223], v[72:75]
	s_setprio 0
	s_setprio 1
	v_mfma_f32_16x16x32_bf16 v[28:31], v[172:175], v[190:193], v[28:31]
	v_mfma_f32_16x16x32_bf16 v[16:19], v[182:185], v[198:201], v[16:19]
	v_mfma_f32_16x16x32_bf16 v[12:15], v[172:175], v[216:219], v[12:15]
	v_mfma_f32_16x16x32_bf16 v[0:3], v[182:185], v[224:227], v[0:3]
	v_mfma_f32_16x16x32_bf16 v[20:23], v[172:175], v[198:201], v[20:23]
	v_mfma_f32_16x16x32_bf16 v[24:27], v[182:185], v[190:193], v[24:27]
	v_mfma_f32_16x16x32_bf16 v[4:7], v[172:175], v[224:227], v[4:7]
	v_mfma_f32_16x16x32_bf16 v[8:11], v[182:185], v[216:219], v[8:11]
	v_mfma_f32_16x16x32_bf16 v[28:31], v[176:179], v[194:197], v[28:31]
	v_mfma_f32_16x16x32_bf16 v[16:19], v[186:189], v[212:215], v[16:19]
	v_mfma_f32_16x16x32_bf16 v[12:15], v[176:179], v[220:223], v[12:15]
	v_mfma_f32_16x16x32_bf16 v[0:3], v[186:189], v[228:231], v[0:3]
	v_mfma_f32_16x16x32_bf16 v[20:23], v[176:179], v[212:215], v[20:23]
	v_mfma_f32_16x16x32_bf16 v[24:27], v[186:189], v[194:197], v[24:27]
	v_lshl_add_u64 v[232:233], v[238:239], 0, s[42:43]
	s_mov_b32 m0, s74
	s_nop 0
	global_load_lds_dwordx4 v[232:233], off
	v_mfma_f32_16x16x32_bf16 v[4:7], v[176:179], v[228:231], v[4:7]
	v_mfma_f32_16x16x32_bf16 v[8:11], v[186:189], v[220:223], v[8:11]
	s_setprio 0
	s_barrier
	s_add_i32 s90, s90, 2
	s_add_u32 s58, s58, 0x100
	s_addc_u32 s59, s59, 0
	s_add_u32 s88, s88, 0x100
	s_addc_u32 s89, s89, 0
	s_cmp_gt_u32 s90, 13
	s_cbranch_scc0 .LBB0_1287
	s_and_b64 vcc, exec, s[44:45]
	s_cbranch_vccz .LBB0_1290
	s_barrier

; #define PG8_STAGE(bufoff, gbase, voff) do { _Pragma("unroll") for (int _i = 0; _i < 2; ++_i) \
;         __builtin_amdgcn_global_load_lds((const unsigned*)((const char*)(gbase) + (voff)[_i]), (PG8_LAS unsigned*)(lds + (bufoff) + ldsw + _i * 8192), 16, 0, 0); } while (0)
; #define PG8_LDA(dst, b, h) do { _Pragma("unroll") for (int m = 0; m < 4; ++m) _Pragma("unroll") for (int k = 0; k < 2; ++k) dst[m][k] = *(const PG8_LAS bf16x8*)(lds + PG8_SA(b, h) + aoff + m * 2048 + k * 1024); } while (0)
; #define PG8_LDB(dst, b, h) do { _Pragma("unroll") for (int n = 0; n < 2; ++n) _Pragma("unroll") for (int k = 0; k < 2; ++k) dst[n][k] = *(const PG8_LAS bf16x8*)(lds + PG8_SB(b, h) + boff + n * 2048 + k * 1024); } while (0)
; #define PG8_WAIT_V(n) asm volatile("s_waitcnt vmcnt(" #n ")" ::: "memory")
; #define PG8_WAIT_L(n) asm volatile("s_waitcnt lgkmcnt(" #n ")" ::: "memory")
; #define PG8_BAR __builtin_amdgcn_s_barrier()
; #define PG8_SCHED __builtin_amdgcn_sched_barrier(0)
; template <class Epi, class Sched, bool ALIGN_EPI = false, bool SP2 = false>
; __device__ __forceinline__ void gemm_phase(PG8_LAS unsigned char* lds, const Gemm g, const Sched& S, const Epi& E) {
;     ...
;         const bool has_next = S.next(ui + 1, nxt);
;         const char* nA = has_next ? (const char*)g.A + (size_t)nxt.pm * tstep : cA; const char* nB = has_next ? (const char*)g.Bt + (size_t)nxt.pn * tstep : cB;
;         for (int t = 0; t < nt; t += 2) {
;             const bool last = (t == nt - 2);
;             const char* a1 = cA + (size_t)(t + 1) * kstep;
;             const char* a2 = last ? nA : cA + (size_t)(t + 2) * kstep; const char* b2 = last ? nB : cB + (size_t)(t + 2) * kstep;
;             const char* a3 = a2 + kstep; const char* b3 = b2 + kstep;
;             if (last && has_next) S.a_ready(nxt);
;             if constexpr (SP2) {
;             PG8_LDB(B0, 0, 0); PG8_LDB(B1, 0, 1); PG8_SCHED; PG8_LDA(At, 0, 0); PG8_STAGE(PG8_SA(1, 1), a1 + hstep, voffA);
;             PG8_WAIT_V(8); PG8_WAIT_L(0); PG8_BAR; PG8_MMA(0, 0, At, B0); PG8_MMA(0, 1, At, B1); PG8_BAR; PG8_SCHED;
;             PG8_LDA(At, 0, 1); PG8_STAGE(PG8_SB(0, 0), b2, voffB); PG8_STAGE(PG8_SB(0, 1), b2 + hstep, voffB); PG8_STAGE(PG8_SA(0, 0), a2, voffA);
;             PG8_WAIT_V(8); PG8_WAIT_L(0); PG8_BAR; PG8_MMA(1, 0, At, B0); PG8_MMA(1, 1, At, B1); PG8_BAR; PG8_SCHED;
.LBB0_1592:
	s_ashr_i32 s39, s38, 31
	s_lshl_b64 s[42:43], s[38:39], 19
	s_add_u32 s42, s40, s42
	s_addc_u32 s43, s41, s43
	s_and_b64 s[44:45], s[10:11], exec
	s_cselect_b32 s39, s43, s51
	s_cselect_b32 s47, s42, s50
	s_ashr_i32 s37, s36, 31
	s_lshl_b64 s[44:45], s[36:37], 19
	v_readlane_b32 s54, v250, 11
	v_readlane_b32 s55, v250, 12
	s_add_u32 s44, s54, s44
	s_addc_u32 s45, s55, s45
	s_and_b64 s[54:55], s[10:11], exec
	s_cselect_b32 s37, s45, s53
	s_cselect_b32 s64, s44, s52
	s_add_u32 s50, s50, 0x40080
	s_addc_u32 s51, s51, 0
	s_add_u32 s65, s52, 0x100
	s_addc_u32 s66, s53, 0
	s_mov_b32 s67, -2
	s_waitcnt lgkmcnt(0)
	ds_read_b128 v[146:149], v152
	ds_read_b128 v[156:159], v152 offset:1024
	ds_read_b128 v[160:163], v152 offset:2048
	ds_read_b128 v[164:167], v152 offset:3072
	ds_read_b128 v[168:171], v153
	ds_read_b128 v[172:175], v153 offset:1024
	ds_read_b128 v[180:183], v153 offset:2048
	ds_read_b128 v[184:187], v153 offset:3072
	s_add_u32 s52, s50, 0xfffc0080
	s_addc_u32 s53, s51, -1
	s_cmp_eq_u32 s67, 12
	s_cselect_b32 s55, s39, s53
	s_cselect_b32 s54, s47, s52
	s_cselect_b32 s53, s37, s66
	s_cselect_b32 s52, s64, s65
	v_lshl_add_u64 v[200:201], s[50:51], 0, v[136:137]
	s_add_i32 m0, s33, 0xc000
	ds_read_b128 v[188:191], v154
	ds_read_b128 v[192:195], v154 offset:1024
	ds_read_b128 v[196:199], v154 offset:2048
	ds_read_b128 v[206:209], v154 offset:3072
	ds_read_b128 v[210:213], v154 offset:4096
	ds_read_b128 v[214:217], v154 offset:5120
	ds_read_b128 v[218:221], v154 offset:6144
	ds_read_b128 v[222:225], v154 offset:7168
	global_load_lds_dwordx4 v[200:201], off
	v_lshl_add_u64 v[200:201], s[50:51], 0, v[138:139]
	s_add_i32 m0, s33, 0xe000
	s_nop 0
	global_load_lds_dwordx4 v[200:201], off
	s_waitcnt vmcnt(8)
	s_waitcnt lgkmcnt(0)
	s_barrier
	s_setprio 1
	s_waitcnt lgkmcnt(0)
	v_mfma_f32_16x16x32_bf16 v[124:127], v[146:149], v[188:191], 0
	v_mfma_f32_16x16x32_bf16 v[104:107], v[160:163], v[196:199], 0
	v_mfma_f32_16x16x32_bf16 v[92:95], v[146:149], v[210:213], 0
	v_mfma_f32_16x16x32_bf16 v[72:75], v[160:163], v[218:221], 0
	v_mfma_f32_16x16x32_bf16 v[108:111], v[146:149], v[196:199], 0
	v_mfma_f32_16x16x32_bf16 v[120:123], v[160:163], v[188:191], 0
	v_mfma_f32_16x16x32_bf16 v[76:79], v[146:149], v[218:221], 0
	v_mfma_f32_16x16x32_bf16 v[88:91], v[160:163], v[210:213], 0
	v_mfma_f32_16x16x32_bf16 v[124:127], v[156:159], v[192:195], v[124:127]
	v_mfma_f32_16x16x32_bf16 v[104:107], v[164:167], v[206:209], v[104:107]
	v_mfma_f32_16x16x32_bf16 v[92:95], v[156:159], v[214:217], v[92:95]
	v_mfma_f32_16x16x32_bf16 v[72:75], v[164:167], v[222:225], v[72:75]
	v_mfma_f32_16x16x32_bf16 v[108:111], v[156:159], v[206:209], v[108:111]
	v_mfma_f32_16x16x32_bf16 v[120:123], v[164:167], v[192:195], v[120:123]
	v_mfma_f32_16x16x32_bf16 v[76:79], v[156:159], v[222:225], v[76:79]
	v_mfma_f32_16x16x32_bf16 v[88:91], v[164:167], v[214:217], v[88:91]
	s_setprio 0
	s_setprio 1
	v_mfma_f32_16x16x32_bf16 v[116:119], v[168:171], v[188:191], 0
	v_mfma_f32_16x16x32_bf16 v[96:99], v[180:183], v[196:199], 0
	v_mfma_f32_16x16x32_bf16 v[84:87], v[168:171], v[210:213], 0
	v_mfma_f32_16x16x32_bf16 v[64:67], v[180:183], v[218:221], 0
	v_mfma_f32_16x16x32_bf16 v[100:103], v[168:171], v[196:199], 0
	v_mfma_f32_16x16x32_bf16 v[112:115], v[180:183], v[188:191], 0
	v_mfma_f32_16x16x32_bf16 v[68:71], v[168:171], v[218:221], 0
	v_mfma_f32_16x16x32_bf16 v[80:83], v[180:183], v[210:213], 0
	v_mfma_f32_16x16x32_bf16 v[116:119], v[172:175], v[192:195], v[116:119]
	v_mfma_f32_16x16x32_bf16 v[96:99], v[184:187], v[206:209], v[96:99]
	v_mfma_f32_16x16x32_bf16 v[84:87], v[172:175], v[214:217], v[84:87]
	v_mfma_f32_16x16x32_bf16 v[64:67], v[184:187], v[222:225], v[64:67]
	v_mfma_f32_16x16x32_bf16 v[100:103], v[172:175], v[206:209], v[100:103]
	v_mfma_f32_16x16x32_bf16 v[112:115], v[184:187], v[192:195], v[112:115]
	v_mfma_f32_16x16x32_bf16 v[68:71], v[172:175], v[222:225], v[68:71]
	v_mfma_f32_16x16x32_bf16 v[80:83], v[184:187], v[214:217], v[80:83]
	s_setprio 0
	s_barrier
	s_add_i32 s74, s60, s15
	v_lshl_add_u64 v[200:201], s[52:53], 0, v[130:131]
	s_mov_b32 m0, s74
	ds_read_b128 v[188:191], v154 offset:16384
	ds_read_b128 v[192:195], v154 offset:17408
	ds_read_b128 v[196:199], v154 offset:18432
	ds_read_b128 v[206:209], v154 offset:19456
	ds_read_b128 v[210:213], v154 offset:20480
	ds_read_b128 v[214:217], v154 offset:21504
	ds_read_b128 v[218:221], v154 offset:22528
	ds_read_b128 v[222:225], v154 offset:23552
	global_load_lds_dwordx4 v[200:201], off
	s_add_i32 m0, s74, 0x2000
	s_add_u32 s74, s52, 0x40000
	v_lshl_add_u64 v[226:227], s[52:53], 0, v[134:135]
	s_addc_u32 s75, s53, 0
	s_add_i32 s76, s61, s15
	global_load_lds_dwordx4 v[226:227], off
	v_lshl_add_u64 v[228:229], s[74:75], 0, v[130:131]
	s_mov_b32 m0, s76
	global_load_lds_dwordx4 v[228:229], off
	v_lshl_add_u64 v[228:229], s[74:75], 0, v[134:135]
	s_add_i32 m0, s76, 0x2000
	s_nop 0
	global_load_lds_dwordx4 v[228:229], off
	s_waitcnt vmcnt(6)
	s_waitcnt lgkmcnt(0)
	s_barrier
; #define PG8_STAGE(bufoff, gbase, voff) do { _Pragma("unroll") for (int _i = 0; _i < 2; ++_i) \
;         __builtin_amdgcn_global_load_lds((const unsigned*)((const char*)(gbase) + (voff)[_i]), (PG8_LAS unsigned*)(lds + (bufoff) + ldsw + _i * 8192), 16, 0, 0); } while (0)
; #define PG8_LDA(dst, b, h) do { _Pragma("unroll") for (int m = 0; m < 4; ++m) _Pragma("unroll") for (int k = 0; k < 2; ++k) dst[m][k] = *(const PG8_LAS bf16x8*)(lds + PG8_SA(b, h) + aoff + m * 2048 + k * 1024); } while (0)
; #define PG8_LDB(dst, b, h) do { _Pragma("unroll") for (int n = 0; n < 2; ++n) _Pragma("unroll") for (int k = 0; k < 2; ++k) dst[n][k] = *(const PG8_LAS bf16x8*)(lds + PG8_SB(b, h) + boff + n * 2048 + k * 1024); } while (0)
; #define PG8_MMA(ai, bj, At, Bt) do { __builtin_amdgcn_s_setprio(1); _Pragma("unroll") for (int m = 0; m < 4; ++m) _Pragma("unroll") for (int n = 0; n < 2; ++n) _Pragma("unroll") for (int k = 0; k < 2; ++k) \
;         acc[ai][bj][m][n] = __builtin_amdgcn_mfma_f32_16x16x32_bf16(Bt[n][k], At[m][k], acc[ai][bj][m][n], 0, 0, 0); __builtin_amdgcn_s_setprio(0); } while (0)
; #define PG8_WAIT_V(n) asm volatile("s_waitcnt vmcnt(" #n ")" ::: "memory")
; #define PG8_WAIT_L(n) asm volatile("s_waitcnt lgkmcnt(" #n ")" ::: "memory")
; #define PG8_BAR __builtin_amdgcn_s_barrier()
; #define PG8_SCHED __builtin_amdgcn_sched_barrier(0)
; template <class Epi, class Sched, bool ALIGN_EPI = false, bool SP2 = false>
; __device__ __forceinline__ void gemm_phase(PG8_LAS unsigned char* lds, const Gemm g, const Sched& S, const Epi& E) {
;     ...
;             PG8_WAIT_V(8); PG8_WAIT_L(0); PG8_BAR; PG8_MMA(0, 0, At, B0); PG8_MMA(0, 1, At, B1); PG8_BAR; PG8_SCHED;
;             PG8_LDA(At, 0, 1); PG8_STAGE(PG8_SB(0, 0), b2, voffB); PG8_STAGE(PG8_SB(0, 1), b2 + hstep, voffB); PG8_STAGE(PG8_SA(0, 0), a2, voffA);
;             PG8_WAIT_V(8); PG8_WAIT_L(0); PG8_BAR; PG8_MMA(1, 0, At, B0); PG8_MMA(1, 1, At, B1); PG8_BAR; PG8_SCHED;
;             PG8_LDB(B0, 1, 0); PG8_LDB(B1, 1, 1); PG8_SCHED; PG8_LDA(At, 1, 0); PG8_STAGE(PG8_SA(0, 1), a2 + hstep, voffA);
;             PG8_WAIT_V(8); PG8_WAIT_L(0); PG8_BAR; PG8_MMA(0, 0, At, B0); PG8_MMA(0, 1, At, B1); PG8_BAR; PG8_SCHED;
	s_setprio 1
	s_waitcnt lgkmcnt(0)
	v_mfma_f32_16x16x32_bf16 v[60:63], v[146:149], v[188:191], 0
	v_mfma_f32_16x16x32_bf16 v[40:43], v[160:163], v[196:199], 0
	v_mfma_f32_16x16x32_bf16 v[28:31], v[146:149], v[210:213], 0
	v_mfma_f32_16x16x32_bf16 v[8:11], v[160:163], v[218:221], 0
	v_mfma_f32_16x16x32_bf16 v[44:47], v[146:149], v[196:199], 0
	v_mfma_f32_16x16x32_bf16 v[56:59], v[160:163], v[188:191], 0
	v_mfma_f32_16x16x32_bf16 v[12:15], v[146:149], v[218:221], 0
	v_mfma_f32_16x16x32_bf16 v[24:27], v[160:163], v[210:213], 0
	v_mfma_f32_16x16x32_bf16 v[60:63], v[156:159], v[192:195], v[60:63]
	v_mfma_f32_16x16x32_bf16 v[40:43], v[164:167], v[206:209], v[40:43]
	v_mfma_f32_16x16x32_bf16 v[28:31], v[156:159], v[214:217], v[28:31]
	v_mfma_f32_16x16x32_bf16 v[8:11], v[164:167], v[222:225], v[8:11]
	v_mfma_f32_16x16x32_bf16 v[44:47], v[156:159], v[206:209], v[44:47]
	v_mfma_f32_16x16x32_bf16 v[56:59], v[164:167], v[192:195], v[56:59]
	v_lshl_add_u64 v[228:229], s[54:55], 0, v[128:129]
	s_mov_b32 m0, s33
	s_nop 0
	global_load_lds_dwordx4 v[228:229], off
	v_mfma_f32_16x16x32_bf16 v[12:15], v[156:159], v[222:225], v[12:15]
	v_mfma_f32_16x16x32_bf16 v[24:27], v[164:167], v[214:217], v[24:27]
	s_setprio 0
	s_setprio 1
	v_mfma_f32_16x16x32_bf16 v[52:55], v[168:171], v[188:191], 0
	v_mfma_f32_16x16x32_bf16 v[32:35], v[180:183], v[196:199], 0
	v_mfma_f32_16x16x32_bf16 v[20:23], v[168:171], v[210:213], 0
	v_mfma_f32_16x16x32_bf16 v[0:3], v[180:183], v[218:221], 0
	v_mfma_f32_16x16x32_bf16 v[36:39], v[168:171], v[196:199], 0
	v_mfma_f32_16x16x32_bf16 v[48:51], v[180:183], v[188:191], 0
	v_mfma_f32_16x16x32_bf16 v[4:7], v[168:171], v[218:221], 0
	v_mfma_f32_16x16x32_bf16 v[16:19], v[180:183], v[210:213], 0
	v_mfma_f32_16x16x32_bf16 v[52:55], v[172:175], v[192:195], v[52:55]
	v_mfma_f32_16x16x32_bf16 v[32:35], v[184:187], v[206:209], v[32:35]
	v_mfma_f32_16x16x32_bf16 v[20:23], v[172:175], v[214:217], v[20:23]
	v_mfma_f32_16x16x32_bf16 v[0:3], v[184:187], v[222:225], v[0:3]
	v_mfma_f32_16x16x32_bf16 v[36:39], v[172:175], v[206:209], v[36:39]
	v_mfma_f32_16x16x32_bf16 v[48:51], v[184:187], v[192:195], v[48:51]
	v_lshl_add_u64 v[230:231], s[54:55], 0, v[132:133]
	s_mov_b32 m0, s34
	s_nop 0
	global_load_lds_dwordx4 v[230:231], off
	v_mfma_f32_16x16x32_bf16 v[4:7], v[172:175], v[222:225], v[4:7]
	v_mfma_f32_16x16x32_bf16 v[16:19], v[184:187], v[214:217], v[16:19]
	s_setprio 0
	s_barrier
	s_add_i32 s74, 0, 0x18000
	s_add_i32 s75, 0, 0x1c000
	v_add_u32_e32 v164, s74, v150
	v_add_u32_e32 v179, s75, v150
	ds_read_b128 v[146:149], v164
	ds_read_b128 v[156:159], v164 offset:1024
	ds_read_b128 v[160:163], v164 offset:2048
	ds_read_b128 v[164:167], v164 offset:3072
	ds_read_b128 v[168:171], v179
	ds_read_b128 v[172:175], v179 offset:1024
	ds_read_b128 v[180:183], v179 offset:2048
	ds_read_b128 v[184:187], v179 offset:3072
	s_add_u32 s54, s54, 0x40000
	s_addc_u32 s55, s55, 0
	s_mov_b32 m0, s49
	v_lshl_add_u64 v[232:233], s[54:55], 0, v[128:129]
	ds_read_b128 v[188:191], v154 offset:32768
	ds_read_b128 v[192:195], v154 offset:33792
	ds_read_b128 v[196:199], v154 offset:34816
	ds_read_b128 v[206:209], v154 offset:35840
	ds_read_b128 v[210:213], v154 offset:36864
	ds_read_b128 v[214:217], v154 offset:37888
	ds_read_b128 v[218:221], v154 offset:38912
	ds_read_b128 v[222:225], v154 offset:39936
	global_load_lds_dwordx4 v[232:233], off
	v_lshl_add_u64 v[232:233], s[54:55], 0, v[132:133]
	s_mov_b32 m0, s56
	s_nop 0
	global_load_lds_dwordx4 v[232:233], off
	s_waitcnt vmcnt(8)
	s_waitcnt lgkmcnt(0)
	s_barrier
	s_setprio 1
	s_waitcnt lgkmcnt(0)
	v_mfma_f32_16x16x32_bf16 v[124:127], v[146:149], v[188:191], v[124:127]
	v_mfma_f32_16x16x32_bf16 v[104:107], v[160:163], v[196:199], v[104:107]
	v_mfma_f32_16x16x32_bf16 v[92:95], v[146:149], v[210:213], v[92:95]
	v_mfma_f32_16x16x32_bf16 v[72:75], v[160:163], v[218:221], v[72:75]
	v_mfma_f32_16x16x32_bf16 v[108:111], v[146:149], v[196:199], v[108:111]
	v_mfma_f32_16x16x32_bf16 v[120:123], v[160:163], v[188:191], v[120:123]
	v_mfma_f32_16x16x32_bf16 v[76:79], v[146:149], v[218:221], v[76:79]
	v_mfma_f32_16x16x32_bf16 v[88:91], v[160:163], v[210:213], v[88:91]
	v_mfma_f32_16x16x32_bf16 v[124:127], v[156:159], v[192:195], v[124:127]
	v_mfma_f32_16x16x32_bf16 v[104:107], v[164:167], v[206:209], v[104:107]
	v_mfma_f32_16x16x32_bf16 v[92:95], v[156:159], v[214:217], v[92:95]
	v_mfma_f32_16x16x32_bf16 v[72:75], v[164:167], v[222:225], v[72:75]
	v_mfma_f32_16x16x32_bf16 v[108:111], v[156:159], v[206:209], v[108:111]
	v_mfma_f32_16x16x32_bf16 v[120:123], v[164:167], v[192:195], v[120:123]
	v_mfma_f32_16x16x32_bf16 v[76:79], v[156:159], v[222:225], v[76:79]
	v_mfma_f32_16x16x32_bf16 v[88:91], v[164:167], v[214:217], v[88:91]
	s_setprio 0
	s_setprio 1
	v_mfma_f32_16x16x32_bf16 v[116:119], v[168:171], v[188:191], v[116:119]
	v_mfma_f32_16x16x32_bf16 v[96:99], v[180:183], v[196:199], v[96:99]
	v_mfma_f32_16x16x32_bf16 v[84:87], v[168:171], v[210:213], v[84:87]
	v_mfma_f32_16x16x32_bf16 v[64:67], v[180:183], v[218:221], v[64:67]
	v_mfma_f32_16x16x32_bf16 v[100:103], v[168:171], v[196:199], v[100:103]
	v_mfma_f32_16x16x32_bf16 v[112:115], v[180:183], v[188:191], v[112:115]
	v_mfma_f32_16x16x32_bf16 v[68:71], v[168:171], v[218:221], v[68:71]
	v_mfma_f32_16x16x32_bf16 v[80:83], v[180:183], v[210:213], v[80:83]
	v_mfma_f32_16x16x32_bf16 v[116:119], v[172:175], v[192:195], v[116:119]
	v_mfma_f32_16x16x32_bf16 v[96:99], v[184:187], v[206:209], v[96:99]
	v_mfma_f32_16x16x32_bf16 v[84:87], v[172:175], v[214:217], v[84:87]
	v_mfma_f32_16x16x32_bf16 v[64:67], v[184:187], v[222:225], v[64:67]
	v_mfma_f32_16x16x32_bf16 v[100:103], v[172:175], v[206:209], v[100:103]
	v_mfma_f32_16x16x32_bf16 v[112:115], v[184:187], v[192:195], v[112:115]
	v_mfma_f32_16x16x32_bf16 v[68:71], v[172:175], v[222:225], v[68:71]
	v_mfma_f32_16x16x32_bf16 v[80:83], v[184:187], v[214:217], v[80:83]
	s_setprio 0
	s_barrier
; #define PG8_STAGE(bufoff, gbase, voff) do { _Pragma("unroll") for (int _i = 0; _i < 2; ++_i) \
;         __builtin_amdgcn_global_load_lds((const unsigned*)((const char*)(gbase) + (voff)[_i]), (PG8_LAS unsigned*)(lds + (bufoff) + ldsw + _i * 8192), 16, 0, 0); } while (0)
; #define PG8_LDA(dst, b, h) do { _Pragma("unroll") for (int m = 0; m < 4; ++m) _Pragma("unroll") for (int k = 0; k < 2; ++k) dst[m][k] = *(const PG8_LAS bf16x8*)(lds + PG8_SA(b, h) + aoff + m * 2048 + k * 1024); } while (0)
; #define PG8_LDB(dst, b, h) do { _Pragma("unroll") for (int n = 0; n < 2; ++n) _Pragma("unroll") for (int k = 0; k < 2; ++k) dst[n][k] = *(const PG8_LAS bf16x8*)(lds + PG8_SB(b, h) + boff + n * 2048 + k * 1024); } while (0)
; #define PG8_MMA(ai, bj, At, Bt) do { __builtin_amdgcn_s_setprio(1); _Pragma("unroll") for (int m = 0; m < 4; ++m) _Pragma("unroll") for (int n = 0; n < 2; ++n) _Pragma("unroll") for (int k = 0; k < 2; ++k) \
;         acc[ai][bj][m][n] = __builtin_amdgcn_mfma_f32_16x16x32_bf16(Bt[n][k], At[m][k], acc[ai][bj][m][n], 0, 0, 0); __builtin_amdgcn_s_setprio(0); } while (0)
; #define PG8_WAIT_V(n) asm volatile("s_waitcnt vmcnt(" #n ")" ::: "memory")
; #define PG8_WAIT_L(n) asm volatile("s_waitcnt lgkmcnt(" #n ")" ::: "memory")
; #define PG8_BAR __builtin_amdgcn_s_barrier()
; #define PG8_SCHED __builtin_amdgcn_sched_barrier(0)
; template <class Epi, class Sched, bool ALIGN_EPI = false, bool SP2 = false>
; __device__ __forceinline__ void gemm_phase(PG8_LAS unsigned char* lds, const Gemm g, const Sched& S, const Epi& E) {
;     ...
;         for (int t = 0; t < nt; t += 2) {
;             const bool last = (t == nt - 2);
;             const char* a1 = cA + (size_t)(t + 1) * kstep;
;             const char* a2 = last ? nA : cA + (size_t)(t + 2) * kstep; const char* b2 = last ? nB : cB + (size_t)(t + 2) * kstep;
;             const char* a3 = a2 + kstep; const char* b3 = b2 + kstep;
;             if (last && has_next) S.a_ready(nxt);
;             if constexpr (SP2) {
;             PG8_LDB(B0, 0, 0); PG8_LDB(B1, 0, 1); PG8_SCHED; PG8_LDA(At, 0, 0); PG8_STAGE(PG8_SA(1, 1), a1 + hstep, voffA);
;     ...
;             PG8_LDA(At, 1, 1); PG8_STAGE(PG8_SB(1, 0), b3, voffB); PG8_STAGE(PG8_SB(1, 1), b3 + hstep, voffB); PG8_STAGE(PG8_SA(1, 0), a3, voffA);
;             PG8_WAIT_V(8); PG8_WAIT_L(0); PG8_BAR; PG8_MMA(1, 0, At, B0); PG8_MMA(1, 1, At, B1); PG8_BAR; PG8_SCHED;
	s_add_i32 s54, s74, s15
	v_lshl_add_u64 v[200:201], v[200:201], 0, s[26:27]
	s_mov_b32 m0, s54
	ds_read_b128 v[188:191], v154 offset:49152
	ds_read_b128 v[192:195], v154 offset:50176
	ds_read_b128 v[196:199], v154 offset:51200
	ds_read_b128 v[206:209], v154 offset:52224
	ds_read_b128 v[210:213], v154 offset:53248
	ds_read_b128 v[214:217], v154 offset:54272
	ds_read_b128 v[218:221], v154 offset:55296
	ds_read_b128 v[222:225], v154 offset:56320
	global_load_lds_dwordx4 v[200:201], off
	s_add_i32 m0, s54, 0x2000
	s_add_u32 s52, s52, 0x40080
	v_lshl_add_u64 v[200:201], v[226:227], 0, s[26:27]
	s_addc_u32 s53, s53, 0
	s_add_i32 s54, s75, s15
	global_load_lds_dwordx4 v[200:201], off
	v_lshl_add_u64 v[200:201], s[52:53], 0, v[130:131]
	s_mov_b32 m0, s54
	s_nop 0
	global_load_lds_dwordx4 v[200:201], off
	v_lshl_add_u64 v[200:201], s[52:53], 0, v[134:135]
	s_add_i32 m0, s54, 0x2000
	s_nop 0
	global_load_lds_dwordx4 v[200:201], off
	s_waitcnt vmcnt(6)
	s_waitcnt lgkmcnt(0)
	s_barrier
	s_setprio 1
	s_waitcnt lgkmcnt(0)
	v_mfma_f32_16x16x32_bf16 v[60:63], v[146:149], v[188:191], v[60:63]
	v_mfma_f32_16x16x32_bf16 v[40:43], v[160:163], v[196:199], v[40:43]
	v_mfma_f32_16x16x32_bf16 v[28:31], v[146:149], v[210:213], v[28:31]
	v_mfma_f32_16x16x32_bf16 v[8:11], v[160:163], v[218:221], v[8:11]
	v_mfma_f32_16x16x32_bf16 v[44:47], v[146:149], v[196:199], v[44:47]
	v_mfma_f32_16x16x32_bf16 v[56:59], v[160:163], v[188:191], v[56:59]
	v_mfma_f32_16x16x32_bf16 v[12:15], v[146:149], v[218:221], v[12:15]
	v_mfma_f32_16x16x32_bf16 v[24:27], v[160:163], v[210:213], v[24:27]
	v_mfma_f32_16x16x32_bf16 v[60:63], v[156:159], v[192:195], v[60:63]
	v_mfma_f32_16x16x32_bf16 v[40:43], v[164:167], v[206:209], v[40:43]
	v_mfma_f32_16x16x32_bf16 v[28:31], v[156:159], v[214:217], v[28:31]
	v_mfma_f32_16x16x32_bf16 v[8:11], v[164:167], v[222:225], v[8:11]
	v_mfma_f32_16x16x32_bf16 v[44:47], v[156:159], v[206:209], v[44:47]
	v_mfma_f32_16x16x32_bf16 v[56:59], v[164:167], v[192:195], v[56:59]
	v_lshl_add_u64 v[200:201], v[228:229], 0, s[26:27]
	s_mov_b32 m0, s58
	s_nop 0
	global_load_lds_dwordx4 v[200:201], off
	v_mfma_f32_16x16x32_bf16 v[12:15], v[156:159], v[222:225], v[12:15]
	v_mfma_f32_16x16x32_bf16 v[24:27], v[164:167], v[214:217], v[24:27]
	s_setprio 0
	s_setprio 1
	v_mfma_f32_16x16x32_bf16 v[52:55], v[168:171], v[188:191], v[52:55]
	v_mfma_f32_16x16x32_bf16 v[32:35], v[180:183], v[196:199], v[32:35]
	v_mfma_f32_16x16x32_bf16 v[20:23], v[168:171], v[210:213], v[20:23]
	v_mfma_f32_16x16x32_bf16 v[0:3], v[180:183], v[218:221], v[0:3]
	v_mfma_f32_16x16x32_bf16 v[36:39], v[168:171], v[196:199], v[36:39]
	v_mfma_f32_16x16x32_bf16 v[48:51], v[180:183], v[188:191], v[48:51]
	v_mfma_f32_16x16x32_bf16 v[4:7], v[168:171], v[218:221], v[4:7]
	v_mfma_f32_16x16x32_bf16 v[16:19], v[180:183], v[210:213], v[16:19]
	v_mfma_f32_16x16x32_bf16 v[52:55], v[172:175], v[192:195], v[52:55]
	v_mfma_f32_16x16x32_bf16 v[32:35], v[184:187], v[206:209], v[32:35]
	v_mfma_f32_16x16x32_bf16 v[20:23], v[172:175], v[214:217], v[20:23]
	v_mfma_f32_16x16x32_bf16 v[0:3], v[184:187], v[222:225], v[0:3]
	v_mfma_f32_16x16x32_bf16 v[36:39], v[172:175], v[206:209], v[36:39]
	v_mfma_f32_16x16x32_bf16 v[48:51], v[184:187], v[192:195], v[48:51]
	v_lshl_add_u64 v[200:201], v[230:231], 0, s[26:27]
	s_mov_b32 m0, s59
	s_nop 0
	global_load_lds_dwordx4 v[200:201], off
	v_mfma_f32_16x16x32_bf16 v[4:7], v[172:175], v[222:225], v[4:7]
	v_mfma_f32_16x16x32_bf16 v[16:19], v[184:187], v[214:217], v[16:19]
	s_setprio 0
	s_barrier
	s_add_i32 s67, s67, 2
	s_add_u32 s50, s50, 0x100
	s_addc_u32 s51, s51, 0
	s_add_u32 s65, s65, 0x100
	s_addc_u32 s66, s66, 0
.LBB0_1593:
	ds_read_b128 v[146:149], v152
	ds_read_b128 v[156:159], v152 offset:1024
	ds_read_b128 v[160:163], v152 offset:2048
	ds_read_b128 v[164:167], v152 offset:3072
	ds_read_b128 v[168:171], v153
	ds_read_b128 v[172:175], v153 offset:1024
	ds_read_b128 v[180:183], v153 offset:2048
	ds_read_b128 v[184:187], v153 offset:3072
	s_add_u32 s52, s50, 0xfffc0080
	s_addc_u32 s53, s51, -1
	s_cmp_eq_u32 s67, 12
	s_cselect_b32 s55, s39, s53
	s_cselect_b32 s54, s47, s52
	s_cselect_b32 s53, s37, s66
	s_cselect_b32 s52, s64, s65
	v_lshl_add_u64 v[200:201], s[50:51], 0, v[136:137]
	s_add_i32 m0, s33, 0xc000
	ds_read_b128 v[188:191], v154
	ds_read_b128 v[192:195], v154 offset:1024
	ds_read_b128 v[196:199], v154 offset:2048
	ds_read_b128 v[206:209], v154 offset:3072
	ds_read_b128 v[210:213], v154 offset:4096
	ds_read_b128 v[214:217], v154 offset:5120
	ds_read_b128 v[218:221], v154 offset:6144
	ds_read_b128 v[222:225], v154 offset:7168
	global_load_lds_dwordx4 v[200:201], off
	v_lshl_add_u64 v[200:201], s[50:51], 0, v[138:139]
	s_add_i32 m0, s33, 0xe000
	s_nop 0
	global_load_lds_dwordx4 v[200:201], off
	s_waitcnt vmcnt(8)
	s_waitcnt lgkmcnt(0)
	s_barrier
; #define PG8_STAGE(bufoff, gbase, voff) do { _Pragma("unroll") for (int _i = 0; _i < 2; ++_i) \
;         __builtin_amdgcn_global_load_lds((const unsigned*)((const char*)(gbase) + (voff)[_i]), (PG8_LAS unsigned*)(lds + (bufoff) + ldsw + _i * 8192), 16, 0, 0); } while (0)
; #define PG8_LDA(dst, b, h) do { _Pragma("unroll") for (int m = 0; m < 4; ++m) _Pragma("unroll") for (int k = 0; k < 2; ++k) dst[m][k] = *(const PG8_LAS bf16x8*)(lds + PG8_SA(b, h) + aoff + m * 2048 + k * 1024); } while (0)
; #define PG8_LDB(dst, b, h) do { _Pragma("unroll") for (int n = 0; n < 2; ++n) _Pragma("unroll") for (int k = 0; k < 2; ++k) dst[n][k] = *(const PG8_LAS bf16x8*)(lds + PG8_SB(b, h) + boff + n * 2048 + k * 1024); } while (0)
; #define PG8_MMA(ai, bj, At, Bt) do { __builtin_amdgcn_s_setprio(1); _Pragma("unroll") for (int m = 0; m < 4; ++m) _Pragma("unroll") for (int n = 0; n < 2; ++n) _Pragma("unroll") for (int k = 0; k < 2; ++k) \
;         acc[ai][bj][m][n] = __builtin_amdgcn_mfma_f32_16x16x32_bf16(Bt[n][k], At[m][k], acc[ai][bj][m][n], 0, 0, 0); __builtin_amdgcn_s_setprio(0); } while (0)
; #define PG8_WAIT_V(n) asm volatile("s_waitcnt vmcnt(" #n ")" ::: "memory")
; #define PG8_WAIT_L(n) asm volatile("s_waitcnt lgkmcnt(" #n ")" ::: "memory")
; #define PG8_BAR __builtin_amdgcn_s_barrier()
; #define PG8_SCHED __builtin_amdgcn_sched_barrier(0)
; template <class Epi, class Sched, bool ALIGN_EPI = false, bool SP2 = false>
; __device__ __forceinline__ void gemm_phase(PG8_LAS unsigned char* lds, const Gemm g, const Sched& S, const Epi& E) {
;     ...
;             if constexpr (SP2) {
;             PG8_LDB(B0, 0, 0); PG8_LDB(B1, 0, 1); PG8_SCHED; PG8_LDA(At, 0, 0); PG8_STAGE(PG8_SA(1, 1), a1 + hstep, voffA);
;             PG8_WAIT_V(8); PG8_WAIT_L(0); PG8_BAR; PG8_MMA(0, 0, At, B0); PG8_MMA(0, 1, At, B1); PG8_BAR; PG8_SCHED;
;             PG8_LDA(At, 0, 1); PG8_STAGE(PG8_SB(0, 0), b2, voffB); PG8_STAGE(PG8_SB(0, 1), b2 + hstep, voffB); PG8_STAGE(PG8_SA(0, 0), a2, voffA);
;             PG8_WAIT_V(8); PG8_WAIT_L(0); PG8_BAR; PG8_MMA(1, 0, At, B0); PG8_MMA(1, 1, At, B1); PG8_BAR; PG8_SCHED;
	s_setprio 1
	s_waitcnt lgkmcnt(0)
	v_mfma_f32_16x16x32_bf16 v[124:127], v[146:149], v[188:191], v[124:127]
	v_mfma_f32_16x16x32_bf16 v[104:107], v[160:163], v[196:199], v[104:107]
	v_mfma_f32_16x16x32_bf16 v[92:95], v[146:149], v[210:213], v[92:95]
	v_mfma_f32_16x16x32_bf16 v[72:75], v[160:163], v[218:221], v[72:75]
	v_mfma_f32_16x16x32_bf16 v[108:111], v[146:149], v[196:199], v[108:111]
	v_mfma_f32_16x16x32_bf16 v[120:123], v[160:163], v[188:191], v[120:123]
	v_mfma_f32_16x16x32_bf16 v[76:79], v[146:149], v[218:221], v[76:79]
	v_mfma_f32_16x16x32_bf16 v[88:91], v[160:163], v[210:213], v[88:91]
	v_mfma_f32_16x16x32_bf16 v[124:127], v[156:159], v[192:195], v[124:127]
	v_mfma_f32_16x16x32_bf16 v[104:107], v[164:167], v[206:209], v[104:107]
	v_mfma_f32_16x16x32_bf16 v[92:95], v[156:159], v[214:217], v[92:95]
	v_mfma_f32_16x16x32_bf16 v[72:75], v[164:167], v[222:225], v[72:75]
	v_mfma_f32_16x16x32_bf16 v[108:111], v[156:159], v[206:209], v[108:111]
	v_mfma_f32_16x16x32_bf16 v[120:123], v[164:167], v[192:195], v[120:123]
	v_mfma_f32_16x16x32_bf16 v[76:79], v[156:159], v[222:225], v[76:79]
	v_mfma_f32_16x16x32_bf16 v[88:91], v[164:167], v[214:217], v[88:91]
	s_setprio 0
	s_setprio 1
	v_mfma_f32_16x16x32_bf16 v[116:119], v[168:171], v[188:191], v[116:119]
	v_mfma_f32_16x16x32_bf16 v[96:99], v[180:183], v[196:199], v[96:99]
	v_mfma_f32_16x16x32_bf16 v[84:87], v[168:171], v[210:213], v[84:87]
	v_mfma_f32_16x16x32_bf16 v[64:67], v[180:183], v[218:221], v[64:67]
	v_mfma_f32_16x16x32_bf16 v[100:103], v[168:171], v[196:199], v[100:103]
	v_mfma_f32_16x16x32_bf16 v[112:115], v[180:183], v[188:191], v[112:115]
	v_mfma_f32_16x16x32_bf16 v[68:71], v[168:171], v[218:221], v[68:71]
	v_mfma_f32_16x16x32_bf16 v[80:83], v[180:183], v[210:213], v[80:83]
	v_mfma_f32_16x16x32_bf16 v[116:119], v[172:175], v[192:195], v[116:119]
	v_mfma_f32_16x16x32_bf16 v[96:99], v[184:187], v[206:209], v[96:99]
	v_mfma_f32_16x16x32_bf16 v[84:87], v[172:175], v[214:217], v[84:87]
	v_mfma_f32_16x16x32_bf16 v[64:67], v[184:187], v[222:225], v[64:67]
	v_mfma_f32_16x16x32_bf16 v[100:103], v[172:175], v[206:209], v[100:103]
	v_mfma_f32_16x16x32_bf16 v[112:115], v[184:187], v[192:195], v[112:115]
	v_mfma_f32_16x16x32_bf16 v[68:71], v[172:175], v[222:225], v[68:71]
	v_mfma_f32_16x16x32_bf16 v[80:83], v[184:187], v[214:217], v[80:83]
	s_setprio 0
	s_barrier
	s_add_i32 s74, s60, s15
	v_lshl_add_u64 v[200:201], s[52:53], 0, v[130:131]
	s_mov_b32 m0, s74
	ds_read_b128 v[188:191], v154 offset:16384
	ds_read_b128 v[192:195], v154 offset:17408
	ds_read_b128 v[196:199], v154 offset:18432
	ds_read_b128 v[206:209], v154 offset:19456
	ds_read_b128 v[210:213], v154 offset:20480
	ds_read_b128 v[214:217], v154 offset:21504
	ds_read_b128 v[218:221], v154 offset:22528
	ds_read_b128 v[222:225], v154 offset:23552
	global_load_lds_dwordx4 v[200:201], off
	s_add_i32 m0, s74, 0x2000
	s_add_u32 s74, s52, 0x40000
	v_lshl_add_u64 v[226:227], s[52:53], 0, v[134:135]
	s_addc_u32 s75, s53, 0
	s_add_i32 s76, s61, s15
	global_load_lds_dwordx4 v[226:227], off
	v_lshl_add_u64 v[228:229], s[74:75], 0, v[130:131]
	s_mov_b32 m0, s76
	global_load_lds_dwordx4 v[228:229], off
	v_lshl_add_u64 v[228:229], s[74:75], 0, v[134:135]
	s_add_i32 m0, s76, 0x2000
	s_nop 0
	global_load_lds_dwordx4 v[228:229], off
	s_waitcnt vmcnt(6)
	s_waitcnt lgkmcnt(0)
	s_barrier
	s_setprio 1
	s_waitcnt lgkmcnt(0)
	v_mfma_f32_16x16x32_bf16 v[60:63], v[146:149], v[188:191], v[60:63]
	v_mfma_f32_16x16x32_bf16 v[40:43], v[160:163], v[196:199], v[40:43]
	v_mfma_f32_16x16x32_bf16 v[28:31], v[146:149], v[210:213], v[28:31]
	v_mfma_f32_16x16x32_bf16 v[8:11], v[160:163], v[218:221], v[8:11]
	v_mfma_f32_16x16x32_bf16 v[44:47], v[146:149], v[196:199], v[44:47]
	v_mfma_f32_16x16x32_bf16 v[56:59], v[160:163], v[188:191], v[56:59]
	v_mfma_f32_16x16x32_bf16 v[12:15], v[146:149], v[218:221], v[12:15]
	v_mfma_f32_16x16x32_bf16 v[24:27], v[160:163], v[210:213], v[24:27]
	v_mfma_f32_16x16x32_bf16 v[60:63], v[156:159], v[192:195], v[60:63]
	v_mfma_f32_16x16x32_bf16 v[40:43], v[164:167], v[206:209], v[40:43]
	v_mfma_f32_16x16x32_bf16 v[28:31], v[156:159], v[214:217], v[28:31]
	v_mfma_f32_16x16x32_bf16 v[8:11], v[164:167], v[222:225], v[8:11]
	v_mfma_f32_16x16x32_bf16 v[44:47], v[156:159], v[206:209], v[44:47]
	v_mfma_f32_16x16x32_bf16 v[56:59], v[164:167], v[192:195], v[56:59]
	v_lshl_add_u64 v[228:229], s[54:55], 0, v[128:129]
	s_mov_b32 m0, s33
	s_nop 0
	global_load_lds_dwordx4 v[228:229], off
	v_mfma_f32_16x16x32_bf16 v[12:15], v[156:159], v[222:225], v[12:15]
	v_mfma_f32_16x16x32_bf16 v[24:27], v[164:167], v[214:217], v[24:27]
	s_setprio 0
	s_setprio 1
	v_mfma_f32_16x16x32_bf16 v[52:55], v[168:171], v[188:191], v[52:55]
	v_mfma_f32_16x16x32_bf16 v[32:35], v[180:183], v[196:199], v[32:35]
	v_mfma_f32_16x16x32_bf16 v[20:23], v[168:171], v[210:213], v[20:23]
	v_mfma_f32_16x16x32_bf16 v[0:3], v[180:183], v[218:221], v[0:3]
	v_mfma_f32_16x16x32_bf16 v[36:39], v[168:171], v[196:199], v[36:39]
	v_mfma_f32_16x16x32_bf16 v[48:51], v[180:183], v[188:191], v[48:51]
	v_mfma_f32_16x16x32_bf16 v[4:7], v[168:171], v[218:221], v[4:7]
	v_mfma_f32_16x16x32_bf16 v[16:19], v[180:183], v[210:213], v[16:19]
	v_mfma_f32_16x16x32_bf16 v[52:55], v[172:175], v[192:195], v[52:55]
	v_mfma_f32_16x16x32_bf16 v[32:35], v[184:187], v[206:209], v[32:35]
	v_mfma_f32_16x16x32_bf16 v[20:23], v[172:175], v[214:217], v[20:23]
	v_mfma_f32_16x16x32_bf16 v[0:3], v[184:187], v[222:225], v[0:3]
	v_mfma_f32_16x16x32_bf16 v[36:39], v[172:175], v[206:209], v[36:39]
	v_mfma_f32_16x16x32_bf16 v[48:51], v[184:187], v[192:195], v[48:51]
	v_lshl_add_u64 v[230:231], s[54:55], 0, v[132:133]
	s_mov_b32 m0, s34
	s_nop 0
	global_load_lds_dwordx4 v[230:231], off
	v_mfma_f32_16x16x32_bf16 v[4:7], v[172:175], v[222:225], v[4:7]
	v_mfma_f32_16x16x32_bf16 v[16:19], v[184:187], v[214:217], v[16:19]
	s_setprio 0
	s_barrier
; #define PG8_STAGE(bufoff, gbase, voff) do { _Pragma("unroll") for (int _i = 0; _i < 2; ++_i) \
;         __builtin_amdgcn_global_load_lds((const unsigned*)((const char*)(gbase) + (voff)[_i]), (PG8_LAS unsigned*)(lds + (bufoff) + ldsw + _i * 8192), 16, 0, 0); } while (0)
; #define PG8_LDA(dst, b, h) do { _Pragma("unroll") for (int m = 0; m < 4; ++m) _Pragma("unroll") for (int k = 0; k < 2; ++k) dst[m][k] = *(const PG8_LAS bf16x8*)(lds + PG8_SA(b, h) + aoff + m * 2048 + k * 1024); } while (0)
; #define PG8_LDB(dst, b, h) do { _Pragma("unroll") for (int n = 0; n < 2; ++n) _Pragma("unroll") for (int k = 0; k < 2; ++k) dst[n][k] = *(const PG8_LAS bf16x8*)(lds + PG8_SB(b, h) + boff + n * 2048 + k * 1024); } while (0)
; #define PG8_MMA(ai, bj, At, Bt) do { __builtin_amdgcn_s_setprio(1); _Pragma("unroll") for (int m = 0; m < 4; ++m) _Pragma("unroll") for (int n = 0; n < 2; ++n) _Pragma("unroll") for (int k = 0; k < 2; ++k) \
;         acc[ai][bj][m][n] = __builtin_amdgcn_mfma_f32_16x16x32_bf16(Bt[n][k], At[m][k], acc[ai][bj][m][n], 0, 0, 0); __builtin_amdgcn_s_setprio(0); } while (0)
; #define PG8_WAIT_V(n) asm volatile("s_waitcnt vmcnt(" #n ")" ::: "memory")
; #define PG8_WAIT_L(n) asm volatile("s_waitcnt lgkmcnt(" #n ")" ::: "memory")
; #define PG8_BAR __builtin_amdgcn_s_barrier()
; #define PG8_SCHED __builtin_amdgcn_sched_barrier(0)
; template <class Epi, class Sched, bool ALIGN_EPI = false, bool SP2 = false>
; __device__ __forceinline__ void gemm_phase(PG8_LAS unsigned char* lds, const Gemm g, const Sched& S, const Epi& E) {
;     ...
;             PG8_LDB(B0, 1, 0); PG8_LDB(B1, 1, 1); PG8_SCHED; PG8_LDA(At, 1, 0); PG8_STAGE(PG8_SA(0, 1), a2 + hstep, voffA);
;             PG8_WAIT_V(8); PG8_WAIT_L(0); PG8_BAR; PG8_MMA(0, 0, At, B0); PG8_MMA(0, 1, At, B1); PG8_BAR; PG8_SCHED;
	s_add_i32 s74, 0, 0x18000
	s_add_i32 s75, 0, 0x1c000
	v_add_u32_e32 v164, s74, v150
	v_add_u32_e32 v179, s75, v150
	ds_read_b128 v[146:149], v164
	ds_read_b128 v[156:159], v164 offset:1024
	ds_read_b128 v[160:163], v164 offset:2048
	ds_read_b128 v[164:167], v164 offset:3072
	ds_read_b128 v[168:171], v179
	ds_read_b128 v[172:175], v179 offset:1024
	ds_read_b128 v[180:183], v179 offset:2048
	ds_read_b128 v[184:187], v179 offset:3072
	s_add_u32 s54, s54, 0x40000
	s_addc_u32 s55, s55, 0
	s_mov_b32 m0, s49
	v_lshl_add_u64 v[232:233], s[54:55], 0, v[128:129]
	ds_read_b128 v[188:191], v154 offset:32768
	ds_read_b128 v[192:195], v154 offset:33792
	ds_read_b128 v[196:199], v154 offset:34816
	ds_read_b128 v[206:209], v154 offset:35840
	ds_read_b128 v[210:213], v154 offset:36864
	ds_read_b128 v[214:217], v154 offset:37888
	ds_read_b128 v[218:221], v154 offset:38912
	ds_read_b128 v[222:225], v154 offset:39936
	global_load_lds_dwordx4 v[232:233], off
	v_lshl_add_u64 v[232:233], s[54:55], 0, v[132:133]
	s_mov_b32 m0, s56
	s_nop 0
	global_load_lds_dwordx4 v[232:233], off
	s_waitcnt vmcnt(8)
	s_waitcnt lgkmcnt(0)
	s_barrier
	s_setprio 1
	s_waitcnt lgkmcnt(0)
	v_mfma_f32_16x16x32_bf16 v[124:127], v[146:149], v[188:191], v[124:127]
	v_mfma_f32_16x16x32_bf16 v[104:107], v[160:163], v[196:199], v[104:107]
	v_mfma_f32_16x16x32_bf16 v[92:95], v[146:149], v[210:213], v[92:95]
	v_mfma_f32_16x16x32_bf16 v[72:75], v[160:163], v[218:221], v[72:75]
	v_mfma_f32_16x16x32_bf16 v[108:111], v[146:149], v[196:199], v[108:111]
	v_mfma_f32_16x16x32_bf16 v[120:123], v[160:163], v[188:191], v[120:123]
	v_mfma_f32_16x16x32_bf16 v[76:79], v[146:149], v[218:221], v[76:79]
	v_mfma_f32_16x16x32_bf16 v[88:91], v[160:163], v[210:213], v[88:91]
	v_mfma_f32_16x16x32_bf16 v[124:127], v[156:159], v[192:195], v[124:127]
	v_mfma_f32_16x16x32_bf16 v[104:107], v[164:167], v[206:209], v[104:107]
	v_mfma_f32_16x16x32_bf16 v[92:95], v[156:159], v[214:217], v[92:95]
	v_mfma_f32_16x16x32_bf16 v[72:75], v[164:167], v[222:225], v[72:75]
	v_mfma_f32_16x16x32_bf16 v[108:111], v[156:159], v[206:209], v[108:111]
	v_mfma_f32_16x16x32_bf16 v[120:123], v[164:167], v[192:195], v[120:123]
	v_mfma_f32_16x16x32_bf16 v[76:79], v[156:159], v[222:225], v[76:79]
	v_mfma_f32_16x16x32_bf16 v[88:91], v[164:167], v[214:217], v[88:91]
	s_setprio 0
	s_setprio 1
	v_mfma_f32_16x16x32_bf16 v[116:119], v[168:171], v[188:191], v[116:119]
	v_mfma_f32_16x16x32_bf16 v[96:99], v[180:183], v[196:199], v[96:99]
	v_mfma_f32_16x16x32_bf16 v[84:87], v[168:171], v[210:213], v[84:87]
	v_mfma_f32_16x16x32_bf16 v[64:67], v[180:183], v[218:221], v[64:67]
	v_mfma_f32_16x16x32_bf16 v[100:103], v[168:171], v[196:199], v[100:103]
	v_mfma_f32_16x16x32_bf16 v[112:115], v[180:183], v[188:191], v[112:115]
	v_mfma_f32_16x16x32_bf16 v[68:71], v[168:171], v[218:221], v[68:71]
	v_mfma_f32_16x16x32_bf16 v[80:83], v[180:183], v[210:213], v[80:83]
	v_mfma_f32_16x16x32_bf16 v[116:119], v[172:175], v[192:195], v[116:119]
	v_mfma_f32_16x16x32_bf16 v[96:99], v[184:187], v[206:209], v[96:99]
	v_mfma_f32_16x16x32_bf16 v[84:87], v[172:175], v[214:217], v[84:87]
	v_mfma_f32_16x16x32_bf16 v[64:67], v[184:187], v[222:225], v[64:67]
	v_mfma_f32_16x16x32_bf16 v[100:103], v[172:175], v[206:209], v[100:103]
	v_mfma_f32_16x16x32_bf16 v[112:115], v[184:187], v[192:195], v[112:115]
	v_mfma_f32_16x16x32_bf16 v[68:71], v[172:175], v[222:225], v[68:71]
	v_mfma_f32_16x16x32_bf16 v[80:83], v[184:187], v[214:217], v[80:83]
	s_setprio 0
	s_barrier
; #define PG8_STAGE(bufoff, gbase, voff) do { _Pragma("unroll") for (int _i = 0; _i < 2; ++_i) \
;         __builtin_amdgcn_global_load_lds((const unsigned*)((const char*)(gbase) + (voff)[_i]), (PG8_LAS unsigned*)(lds + (bufoff) + ldsw + _i * 8192), 16, 0, 0); } while (0)
; #define PG8_LDA(dst, b, h) do { _Pragma("unroll") for (int m = 0; m < 4; ++m) _Pragma("unroll") for (int k = 0; k < 2; ++k) dst[m][k] = *(const PG8_LAS bf16x8*)(lds + PG8_SA(b, h) + aoff + m * 2048 + k * 1024); } while (0)
; #define PG8_MMA(ai, bj, At, Bt) do { __builtin_amdgcn_s_setprio(1); _Pragma("unroll") for (int m = 0; m < 4; ++m) _Pragma("unroll") for (int n = 0; n < 2; ++n) _Pragma("unroll") for (int k = 0; k < 2; ++k) \
;         acc[ai][bj][m][n] = __builtin_amdgcn_mfma_f32_16x16x32_bf16(Bt[n][k], At[m][k], acc[ai][bj][m][n], 0, 0, 0); __builtin_amdgcn_s_setprio(0); } while (0)
; #define PG8_WAIT_V(n) asm volatile("s_waitcnt vmcnt(" #n ")" ::: "memory")
; #define PG8_WAIT_L(n) asm volatile("s_waitcnt lgkmcnt(" #n ")" ::: "memory")
; #define PG8_BAR __builtin_amdgcn_s_barrier()
; #define PG8_SCHED __builtin_amdgcn_sched_barrier(0)
; template <class Epi, class Sched, bool ALIGN_EPI = false, bool SP2 = false>
; __device__ __forceinline__ void gemm_phase(PG8_LAS unsigned char* lds, const Gemm g, const Sched& S, const Epi& E) {
;     ...
;         for (int t = 0; t < nt; t += 2) {
;             const bool last = (t == nt - 2);
;     ...
;             PG8_LDA(At, 1, 1); PG8_STAGE(PG8_SB(1, 0), b3, voffB); PG8_STAGE(PG8_SB(1, 1), b3 + hstep, voffB); PG8_STAGE(PG8_SA(1, 0), a3, voffA);
;             PG8_WAIT_V(8); PG8_WAIT_L(0); PG8_BAR; PG8_MMA(1, 0, At, B0); PG8_MMA(1, 1, At, B1); PG8_BAR; PG8_SCHED;
;     ...
;         if constexpr (ALIGN_EPI) { if (wr == 0) PG8_BAR; }
	s_add_i32 s54, s74, s15
	v_lshl_add_u64 v[200:201], v[200:201], 0, s[26:27]
	s_mov_b32 m0, s54
	ds_read_b128 v[188:191], v154 offset:49152
	ds_read_b128 v[192:195], v154 offset:50176
	ds_read_b128 v[196:199], v154 offset:51200
	ds_read_b128 v[206:209], v154 offset:52224
	ds_read_b128 v[210:213], v154 offset:53248
	ds_read_b128 v[214:217], v154 offset:54272
	ds_read_b128 v[218:221], v154 offset:55296
	ds_read_b128 v[222:225], v154 offset:56320
	global_load_lds_dwordx4 v[200:201], off
	s_add_i32 m0, s54, 0x2000
	s_add_u32 s52, s52, 0x40080
	v_lshl_add_u64 v[200:201], v[226:227], 0, s[26:27]
	s_addc_u32 s53, s53, 0
	s_add_i32 s54, s75, s15
	global_load_lds_dwordx4 v[200:201], off
	v_lshl_add_u64 v[200:201], s[52:53], 0, v[130:131]
	s_mov_b32 m0, s54
	s_nop 0
	global_load_lds_dwordx4 v[200:201], off
	v_lshl_add_u64 v[200:201], s[52:53], 0, v[134:135]
	s_add_i32 m0, s54, 0x2000
	s_nop 0
	global_load_lds_dwordx4 v[200:201], off
	s_waitcnt vmcnt(6)
	s_waitcnt lgkmcnt(0)
	s_barrier
	s_setprio 1
	s_waitcnt lgkmcnt(0)
	v_mfma_f32_16x16x32_bf16 v[60:63], v[146:149], v[188:191], v[60:63]
	v_mfma_f32_16x16x32_bf16 v[40:43], v[160:163], v[196:199], v[40:43]
	v_mfma_f32_16x16x32_bf16 v[28:31], v[146:149], v[210:213], v[28:31]
	v_mfma_f32_16x16x32_bf16 v[8:11], v[160:163], v[218:221], v[8:11]
	v_mfma_f32_16x16x32_bf16 v[44:47], v[146:149], v[196:199], v[44:47]
	v_mfma_f32_16x16x32_bf16 v[56:59], v[160:163], v[188:191], v[56:59]
	v_mfma_f32_16x16x32_bf16 v[12:15], v[146:149], v[218:221], v[12:15]
	v_mfma_f32_16x16x32_bf16 v[24:27], v[160:163], v[210:213], v[24:27]
	v_mfma_f32_16x16x32_bf16 v[60:63], v[156:159], v[192:195], v[60:63]
	v_mfma_f32_16x16x32_bf16 v[40:43], v[164:167], v[206:209], v[40:43]
	v_mfma_f32_16x16x32_bf16 v[28:31], v[156:159], v[214:217], v[28:31]
	v_mfma_f32_16x16x32_bf16 v[8:11], v[164:167], v[222:225], v[8:11]
	v_mfma_f32_16x16x32_bf16 v[44:47], v[156:159], v[206:209], v[44:47]
	v_mfma_f32_16x16x32_bf16 v[56:59], v[164:167], v[192:195], v[56:59]
	v_lshl_add_u64 v[200:201], v[228:229], 0, s[26:27]
	s_mov_b32 m0, s58
	s_nop 0
	global_load_lds_dwordx4 v[200:201], off
	v_mfma_f32_16x16x32_bf16 v[12:15], v[156:159], v[222:225], v[12:15]
	v_mfma_f32_16x16x32_bf16 v[24:27], v[164:167], v[214:217], v[24:27]
	s_setprio 0
	s_setprio 1
	v_mfma_f32_16x16x32_bf16 v[52:55], v[168:171], v[188:191], v[52:55]
	v_mfma_f32_16x16x32_bf16 v[32:35], v[180:183], v[196:199], v[32:35]
	v_mfma_f32_16x16x32_bf16 v[20:23], v[168:171], v[210:213], v[20:23]
	v_mfma_f32_16x16x32_bf16 v[0:3], v[180:183], v[218:221], v[0:3]
	v_mfma_f32_16x16x32_bf16 v[36:39], v[168:171], v[196:199], v[36:39]
	v_mfma_f32_16x16x32_bf16 v[48:51], v[180:183], v[188:191], v[48:51]
	v_mfma_f32_16x16x32_bf16 v[4:7], v[168:171], v[218:221], v[4:7]
	v_mfma_f32_16x16x32_bf16 v[16:19], v[180:183], v[210:213], v[16:19]
	v_mfma_f32_16x16x32_bf16 v[52:55], v[172:175], v[192:195], v[52:55]
	v_mfma_f32_16x16x32_bf16 v[32:35], v[184:187], v[206:209], v[32:35]
	v_mfma_f32_16x16x32_bf16 v[20:23], v[172:175], v[214:217], v[20:23]
	v_mfma_f32_16x16x32_bf16 v[0:3], v[184:187], v[222:225], v[0:3]
	v_mfma_f32_16x16x32_bf16 v[36:39], v[172:175], v[206:209], v[36:39]
	v_mfma_f32_16x16x32_bf16 v[48:51], v[184:187], v[192:195], v[48:51]
	v_lshl_add_u64 v[200:201], v[230:231], 0, s[26:27]
	s_mov_b32 m0, s59
	s_nop 0
	global_load_lds_dwordx4 v[200:201], off
	v_mfma_f32_16x16x32_bf16 v[4:7], v[172:175], v[222:225], v[4:7]
	v_mfma_f32_16x16x32_bf16 v[16:19], v[184:187], v[214:217], v[16:19]
	s_setprio 0
	s_barrier
	s_add_i32 s67, s67, 2
	s_add_u32 s50, s50, 0x100
	s_addc_u32 s51, s51, 0
	s_add_u32 s65, s65, 0x100
	s_addc_u32 s66, s66, 0
	s_cmp_gt_u32 s67, 13
	s_cbranch_scc0 .LBB0_1593
	s_and_b64 vcc, exec, s[28:29]
	s_cbranch_vccz .LBB0_1596
	s_barrier

; #define PG8_STAGE(bufoff, gbase, voff) do { _Pragma("unroll") for (int _i = 0; _i < 2; ++_i) \
;         __builtin_amdgcn_global_load_lds((const unsigned*)((const char*)(gbase) + (voff)[_i]), (PG8_LAS unsigned*)(lds + (bufoff) + ldsw + _i * 8192), 16, 0, 0); } while (0)
; #define PG8_LDA(dst, b, h) do { _Pragma("unroll") for (int m = 0; m < 4; ++m) _Pragma("unroll") for (int k = 0; k < 2; ++k) dst[m][k] = *(const PG8_LAS bf16x8*)(lds + PG8_SA(b, h) + aoff + m * 2048 + k * 1024); } while (0)
; #define PG8_LDB(dst, b, h) do { _Pragma("unroll") for (int n = 0; n < 2; ++n) _Pragma("unroll") for (int k = 0; k < 2; ++k) dst[n][k] = *(const PG8_LAS bf16x8*)(lds + PG8_SB(b, h) + boff + n * 2048 + k * 1024); } while (0)
; #define PG8_WAIT_V(n) asm volatile("s_waitcnt vmcnt(" #n ")" ::: "memory")
; #define PG8_WAIT_L(n) asm volatile("s_waitcnt lgkmcnt(" #n ")" ::: "memory")
; #define PG8_BAR __builtin_amdgcn_s_barrier()
; #define PG8_SCHED __builtin_amdgcn_sched_barrier(0)
; template <class Epi, class Sched, bool ALIGN_EPI = false, bool SP2 = false>
; __device__ __forceinline__ void gemm_phase(PG8_LAS unsigned char* lds, const Gemm g, const Sched& S, const Epi& E) {
;     ...
;         const bool has_next = S.next(ui + 1, nxt);
;         const char* nA = has_next ? (const char*)g.A + (size_t)nxt.pm * tstep : cA; const char* nB = has_next ? (const char*)g.Bt + (size_t)nxt.pn * tstep : cB;
;         for (int t = 0; t < nt; t += 2) {
;             const bool last = (t == nt - 2);
;             const char* a1 = cA + (size_t)(t + 1) * kstep;
;             const char* a2 = last ? nA : cA + (size_t)(t + 2) * kstep; const char* b2 = last ? nB : cB + (size_t)(t + 2) * kstep;
;             const char* a3 = a2 + kstep; const char* b3 = b2 + kstep;
;             if (last && has_next) S.a_ready(nxt);
;             if constexpr (SP2) {
;             PG8_LDB(B0, 0, 0); PG8_LDB(B1, 0, 1); PG8_SCHED; PG8_LDA(At, 0, 0); PG8_STAGE(PG8_SA(1, 1), a1 + hstep, voffA);
;             PG8_WAIT_V(8); PG8_WAIT_L(0); PG8_BAR; PG8_MMA(0, 0, At, B0); PG8_MMA(0, 1, At, B1); PG8_BAR; PG8_SCHED;
;             PG8_LDA(At, 0, 1); PG8_STAGE(PG8_SB(0, 0), b2, voffB); PG8_STAGE(PG8_SB(0, 1), b2 + hstep, voffB); PG8_STAGE(PG8_SA(0, 0), a2, voffA);
;             PG8_WAIT_V(8); PG8_WAIT_L(0); PG8_BAR; PG8_MMA(1, 0, At, B0); PG8_MMA(1, 1, At, B1); PG8_BAR; PG8_SCHED;
.LBB0_1680:
	s_ashr_i32 s47, s46, 31
	s_lshl_b64 s[48:49], s[46:47], 19
	s_add_u32 s48, s22, s48
	s_addc_u32 s49, s23, s49
	s_and_b64 s[50:51], s[4:5], exec
	s_cselect_b32 s47, s49, s53
	s_cselect_b32 s77, s48, s52
	s_ashr_i32 s45, s44, 31
	s_lshl_b64 s[50:51], s[44:45], 19
	s_add_u32 s50, s15, s50
	s_addc_u32 s51, s33, s51
	s_and_b64 s[56:57], s[4:5], exec
	s_cselect_b32 s45, s51, s55
	s_cselect_b32 s78, s50, s54
	s_add_u32 s52, s52, 0x40080
	s_addc_u32 s53, s53, 0
	s_add_u32 s79, s54, 0x100
	s_addc_u32 s80, s55, 0
	s_mov_b32 s81, -2
	ds_read_b128 v[146:149], v152
	ds_read_b128 v[156:159], v152 offset:1024
	ds_read_b128 v[160:163], v152 offset:2048
	ds_read_b128 v[164:167], v152 offset:3072
	ds_read_b128 v[168:171], v153
	ds_read_b128 v[172:175], v153 offset:1024
	ds_read_b128 v[180:183], v153 offset:2048
	ds_read_b128 v[184:187], v153 offset:3072
	s_add_u32 s54, s52, 0xfffc0080
	s_addc_u32 s55, s53, -1
	s_cmp_eq_u32 s81, 12
	s_cselect_b32 s57, s47, s55
	s_cselect_b32 s56, s77, s54
	s_cselect_b32 s55, s45, s80
	s_cselect_b32 s54, s78, s79
	v_lshl_add_u64 v[200:201], s[52:53], 0, v[136:137]
	s_add_i32 m0, s58, 0xc000
	ds_read_b128 v[188:191], v154
	ds_read_b128 v[192:195], v154 offset:1024
	ds_read_b128 v[196:199], v154 offset:2048
	ds_read_b128 v[206:209], v154 offset:3072
	ds_read_b128 v[210:213], v154 offset:4096
	ds_read_b128 v[214:217], v154 offset:5120
	ds_read_b128 v[218:221], v154 offset:6144
	ds_read_b128 v[222:225], v154 offset:7168
	global_load_lds_dwordx4 v[200:201], off
	v_lshl_add_u64 v[200:201], s[52:53], 0, v[138:139]
	s_add_i32 m0, s58, 0xe000
	s_nop 0
	global_load_lds_dwordx4 v[200:201], off
	s_waitcnt vmcnt(8)
	s_waitcnt lgkmcnt(0)
	s_barrier
	s_setprio 1
	s_waitcnt lgkmcnt(0)
	v_mfma_f32_16x16x32_bf16 v[124:127], v[146:149], v[188:191], 0
	v_mfma_f32_16x16x32_bf16 v[104:107], v[160:163], v[196:199], 0
	v_mfma_f32_16x16x32_bf16 v[92:95], v[146:149], v[210:213], 0
	v_mfma_f32_16x16x32_bf16 v[72:75], v[160:163], v[218:221], 0
	v_mfma_f32_16x16x32_bf16 v[108:111], v[146:149], v[196:199], 0
	v_mfma_f32_16x16x32_bf16 v[120:123], v[160:163], v[188:191], 0
	v_mfma_f32_16x16x32_bf16 v[76:79], v[146:149], v[218:221], 0
	v_mfma_f32_16x16x32_bf16 v[88:91], v[160:163], v[210:213], 0
	v_mfma_f32_16x16x32_bf16 v[124:127], v[156:159], v[192:195], v[124:127]
	v_mfma_f32_16x16x32_bf16 v[104:107], v[164:167], v[206:209], v[104:107]
	v_mfma_f32_16x16x32_bf16 v[92:95], v[156:159], v[214:217], v[92:95]
	v_mfma_f32_16x16x32_bf16 v[72:75], v[164:167], v[222:225], v[72:75]
	v_mfma_f32_16x16x32_bf16 v[108:111], v[156:159], v[206:209], v[108:111]
	v_mfma_f32_16x16x32_bf16 v[120:123], v[164:167], v[192:195], v[120:123]
	v_mfma_f32_16x16x32_bf16 v[76:79], v[156:159], v[222:225], v[76:79]
	v_mfma_f32_16x16x32_bf16 v[88:91], v[164:167], v[214:217], v[88:91]
	s_setprio 0
	s_setprio 1
	v_mfma_f32_16x16x32_bf16 v[116:119], v[168:171], v[188:191], 0
	v_mfma_f32_16x16x32_bf16 v[96:99], v[180:183], v[196:199], 0
	v_mfma_f32_16x16x32_bf16 v[84:87], v[168:171], v[210:213], 0
	v_mfma_f32_16x16x32_bf16 v[64:67], v[180:183], v[218:221], 0
	v_mfma_f32_16x16x32_bf16 v[100:103], v[168:171], v[196:199], 0
	v_mfma_f32_16x16x32_bf16 v[112:115], v[180:183], v[188:191], 0
	v_mfma_f32_16x16x32_bf16 v[68:71], v[168:171], v[218:221], 0
	v_mfma_f32_16x16x32_bf16 v[80:83], v[180:183], v[210:213], 0
	v_mfma_f32_16x16x32_bf16 v[116:119], v[172:175], v[192:195], v[116:119]
	v_mfma_f32_16x16x32_bf16 v[96:99], v[184:187], v[206:209], v[96:99]
	v_mfma_f32_16x16x32_bf16 v[84:87], v[172:175], v[214:217], v[84:87]
	v_mfma_f32_16x16x32_bf16 v[64:67], v[184:187], v[222:225], v[64:67]
	v_mfma_f32_16x16x32_bf16 v[100:103], v[172:175], v[206:209], v[100:103]
	v_mfma_f32_16x16x32_bf16 v[112:115], v[184:187], v[192:195], v[112:115]
	v_mfma_f32_16x16x32_bf16 v[68:71], v[172:175], v[222:225], v[68:71]
	v_mfma_f32_16x16x32_bf16 v[80:83], v[184:187], v[214:217], v[80:83]
	s_setprio 0
	s_barrier
	s_add_i32 s82, s65, s34
	v_lshl_add_u64 v[200:201], s[54:55], 0, v[132:133]
	s_mov_b32 m0, s82
	ds_read_b128 v[188:191], v154 offset:16384
	ds_read_b128 v[192:195], v154 offset:17408
	ds_read_b128 v[196:199], v154 offset:18432
	ds_read_b128 v[206:209], v154 offset:19456
	ds_read_b128 v[210:213], v154 offset:20480
	ds_read_b128 v[214:217], v154 offset:21504
	ds_read_b128 v[218:221], v154 offset:22528
	ds_read_b128 v[222:225], v154 offset:23552
	global_load_lds_dwordx4 v[200:201], off
	s_add_i32 m0, s82, 0x2000
	s_add_u32 s82, s54, 0x40000
	v_lshl_add_u64 v[226:227], s[54:55], 0, v[128:129]
	s_addc_u32 s83, s55, 0
	s_add_i32 s84, s66, s34
	global_load_lds_dwordx4 v[226:227], off
	v_lshl_add_u64 v[228:229], s[82:83], 0, v[132:133]
	s_mov_b32 m0, s84
	global_load_lds_dwordx4 v[228:229], off
	v_lshl_add_u64 v[228:229], s[82:83], 0, v[128:129]
	s_add_i32 m0, s84, 0x2000
	s_nop 0
	global_load_lds_dwordx4 v[228:229], off
	s_waitcnt vmcnt(6)
	s_waitcnt lgkmcnt(0)
	s_barrier
; #define PG8_STAGE(bufoff, gbase, voff) do { _Pragma("unroll") for (int _i = 0; _i < 2; ++_i) \
;         __builtin_amdgcn_global_load_lds((const unsigned*)((const char*)(gbase) + (voff)[_i]), (PG8_LAS unsigned*)(lds + (bufoff) + ldsw + _i * 8192), 16, 0, 0); } while (0)
; #define PG8_LDA(dst, b, h) do { _Pragma("unroll") for (int m = 0; m < 4; ++m) _Pragma("unroll") for (int k = 0; k < 2; ++k) dst[m][k] = *(const PG8_LAS bf16x8*)(lds + PG8_SA(b, h) + aoff + m * 2048 + k * 1024); } while (0)
; #define PG8_LDB(dst, b, h) do { _Pragma("unroll") for (int n = 0; n < 2; ++n) _Pragma("unroll") for (int k = 0; k < 2; ++k) dst[n][k] = *(const PG8_LAS bf16x8*)(lds + PG8_SB(b, h) + boff + n * 2048 + k * 1024); } while (0)
; #define PG8_MMA(ai, bj, At, Bt) do { __builtin_amdgcn_s_setprio(1); _Pragma("unroll") for (int m = 0; m < 4; ++m) _Pragma("unroll") for (int n = 0; n < 2; ++n) _Pragma("unroll") for (int k = 0; k < 2; ++k) \
;         acc[ai][bj][m][n] = __builtin_amdgcn_mfma_f32_16x16x32_bf16(Bt[n][k], At[m][k], acc[ai][bj][m][n], 0, 0, 0); __builtin_amdgcn_s_setprio(0); } while (0)
; #define PG8_WAIT_V(n) asm volatile("s_waitcnt vmcnt(" #n ")" ::: "memory")
; #define PG8_WAIT_L(n) asm volatile("s_waitcnt lgkmcnt(" #n ")" ::: "memory")
; #define PG8_BAR __builtin_amdgcn_s_barrier()
; #define PG8_SCHED __builtin_amdgcn_sched_barrier(0)
; template <class Epi, class Sched, bool ALIGN_EPI = false, bool SP2 = false>
; __device__ __forceinline__ void gemm_phase(PG8_LAS unsigned char* lds, const Gemm g, const Sched& S, const Epi& E) {
;     ...
;             PG8_WAIT_V(8); PG8_WAIT_L(0); PG8_BAR; PG8_MMA(0, 0, At, B0); PG8_MMA(0, 1, At, B1); PG8_BAR; PG8_SCHED;
;             PG8_LDA(At, 0, 1); PG8_STAGE(PG8_SB(0, 0), b2, voffB); PG8_STAGE(PG8_SB(0, 1), b2 + hstep, voffB); PG8_STAGE(PG8_SA(0, 0), a2, voffA);
;             PG8_WAIT_V(8); PG8_WAIT_L(0); PG8_BAR; PG8_MMA(1, 0, At, B0); PG8_MMA(1, 1, At, B1); PG8_BAR; PG8_SCHED;
;             PG8_LDB(B0, 1, 0); PG8_LDB(B1, 1, 1); PG8_SCHED; PG8_LDA(At, 1, 0); PG8_STAGE(PG8_SA(0, 1), a2 + hstep, voffA);
;             PG8_WAIT_V(8); PG8_WAIT_L(0); PG8_BAR; PG8_MMA(0, 0, At, B0); PG8_MMA(0, 1, At, B1); PG8_BAR; PG8_SCHED;
	s_setprio 1
	s_waitcnt lgkmcnt(0)
	v_mfma_f32_16x16x32_bf16 v[60:63], v[146:149], v[188:191], 0
	v_mfma_f32_16x16x32_bf16 v[40:43], v[160:163], v[196:199], 0
	v_mfma_f32_16x16x32_bf16 v[28:31], v[146:149], v[210:213], 0
	v_mfma_f32_16x16x32_bf16 v[8:11], v[160:163], v[218:221], 0
	v_mfma_f32_16x16x32_bf16 v[44:47], v[146:149], v[196:199], 0
	v_mfma_f32_16x16x32_bf16 v[56:59], v[160:163], v[188:191], 0
	v_mfma_f32_16x16x32_bf16 v[12:15], v[146:149], v[218:221], 0
	v_mfma_f32_16x16x32_bf16 v[24:27], v[160:163], v[210:213], 0
	v_mfma_f32_16x16x32_bf16 v[60:63], v[156:159], v[192:195], v[60:63]
	v_mfma_f32_16x16x32_bf16 v[40:43], v[164:167], v[206:209], v[40:43]
	v_mfma_f32_16x16x32_bf16 v[28:31], v[156:159], v[214:217], v[28:31]
	v_mfma_f32_16x16x32_bf16 v[8:11], v[164:167], v[222:225], v[8:11]
	v_mfma_f32_16x16x32_bf16 v[44:47], v[156:159], v[206:209], v[44:47]
	v_mfma_f32_16x16x32_bf16 v[56:59], v[164:167], v[192:195], v[56:59]
	v_lshl_add_u64 v[228:229], s[56:57], 0, v[134:135]
	s_mov_b32 m0, s58
	s_nop 0
	global_load_lds_dwordx4 v[228:229], off
	v_mfma_f32_16x16x32_bf16 v[12:15], v[156:159], v[222:225], v[12:15]
	v_mfma_f32_16x16x32_bf16 v[24:27], v[164:167], v[214:217], v[24:27]
	s_setprio 0
	s_setprio 1
	v_mfma_f32_16x16x32_bf16 v[52:55], v[168:171], v[188:191], 0
	v_mfma_f32_16x16x32_bf16 v[32:35], v[180:183], v[196:199], 0
	v_mfma_f32_16x16x32_bf16 v[20:23], v[168:171], v[210:213], 0
	v_mfma_f32_16x16x32_bf16 v[0:3], v[180:183], v[218:221], 0
	v_mfma_f32_16x16x32_bf16 v[36:39], v[168:171], v[196:199], 0
	v_mfma_f32_16x16x32_bf16 v[48:51], v[180:183], v[188:191], 0
	v_mfma_f32_16x16x32_bf16 v[4:7], v[168:171], v[218:221], 0
	v_mfma_f32_16x16x32_bf16 v[16:19], v[180:183], v[210:213], 0
	v_mfma_f32_16x16x32_bf16 v[52:55], v[172:175], v[192:195], v[52:55]
	v_mfma_f32_16x16x32_bf16 v[32:35], v[184:187], v[206:209], v[32:35]
	v_mfma_f32_16x16x32_bf16 v[20:23], v[172:175], v[214:217], v[20:23]
	v_mfma_f32_16x16x32_bf16 v[0:3], v[184:187], v[222:225], v[0:3]
	v_mfma_f32_16x16x32_bf16 v[36:39], v[172:175], v[206:209], v[36:39]
	v_mfma_f32_16x16x32_bf16 v[48:51], v[184:187], v[192:195], v[48:51]
	v_lshl_add_u64 v[230:231], s[56:57], 0, v[130:131]
	s_mov_b32 m0, s59
	s_nop 0
	global_load_lds_dwordx4 v[230:231], off
	v_mfma_f32_16x16x32_bf16 v[4:7], v[172:175], v[222:225], v[4:7]
	v_mfma_f32_16x16x32_bf16 v[16:19], v[184:187], v[214:217], v[16:19]
	s_setprio 0
	s_barrier
	s_add_i32 s82, 0, 0x18000
	s_add_i32 s83, 0, 0x1c000
	v_add_u32_e32 v164, s82, v150
	v_add_u32_e32 v179, s83, v150
	ds_read_b128 v[146:149], v164
	ds_read_b128 v[156:159], v164 offset:1024
	ds_read_b128 v[160:163], v164 offset:2048
	ds_read_b128 v[164:167], v164 offset:3072
	ds_read_b128 v[168:171], v179
	ds_read_b128 v[172:175], v179 offset:1024
	ds_read_b128 v[180:183], v179 offset:2048
	ds_read_b128 v[184:187], v179 offset:3072
	s_add_u32 s56, s56, 0x40000
	s_addc_u32 s57, s57, 0
	s_mov_b32 m0, s60
	v_lshl_add_u64 v[232:233], s[56:57], 0, v[134:135]
	ds_read_b128 v[188:191], v154 offset:32768
	ds_read_b128 v[192:195], v154 offset:33792
	ds_read_b128 v[196:199], v154 offset:34816
	ds_read_b128 v[206:209], v154 offset:35840
	ds_read_b128 v[210:213], v154 offset:36864
	ds_read_b128 v[214:217], v154 offset:37888
	ds_read_b128 v[218:221], v154 offset:38912
	ds_read_b128 v[222:225], v154 offset:39936
	global_load_lds_dwordx4 v[232:233], off
	v_lshl_add_u64 v[232:233], s[56:57], 0, v[130:131]
	s_mov_b32 m0, s61
	s_nop 0
	global_load_lds_dwordx4 v[232:233], off
	s_waitcnt vmcnt(8)
	s_waitcnt lgkmcnt(0)
	s_barrier
	s_setprio 1
	s_waitcnt lgkmcnt(0)
	v_mfma_f32_16x16x32_bf16 v[124:127], v[146:149], v[188:191], v[124:127]
	v_mfma_f32_16x16x32_bf16 v[104:107], v[160:163], v[196:199], v[104:107]
	v_mfma_f32_16x16x32_bf16 v[92:95], v[146:149], v[210:213], v[92:95]
	v_mfma_f32_16x16x32_bf16 v[72:75], v[160:163], v[218:221], v[72:75]
	v_mfma_f32_16x16x32_bf16 v[108:111], v[146:149], v[196:199], v[108:111]
	v_mfma_f32_16x16x32_bf16 v[120:123], v[160:163], v[188:191], v[120:123]
	v_mfma_f32_16x16x32_bf16 v[76:79], v[146:149], v[218:221], v[76:79]
	v_mfma_f32_16x16x32_bf16 v[88:91], v[160:163], v[210:213], v[88:91]
	v_mfma_f32_16x16x32_bf16 v[124:127], v[156:159], v[192:195], v[124:127]
	v_mfma_f32_16x16x32_bf16 v[104:107], v[164:167], v[206:209], v[104:107]
	v_mfma_f32_16x16x32_bf16 v[92:95], v[156:159], v[214:217], v[92:95]
	v_mfma_f32_16x16x32_bf16 v[72:75], v[164:167], v[222:225], v[72:75]
	v_mfma_f32_16x16x32_bf16 v[108:111], v[156:159], v[206:209], v[108:111]
	v_mfma_f32_16x16x32_bf16 v[120:123], v[164:167], v[192:195], v[120:123]
	v_mfma_f32_16x16x32_bf16 v[76:79], v[156:159], v[222:225], v[76:79]
	v_mfma_f32_16x16x32_bf16 v[88:91], v[164:167], v[214:217], v[88:91]
	s_setprio 0
	s_setprio 1
	v_mfma_f32_16x16x32_bf16 v[116:119], v[168:171], v[188:191], v[116:119]
	v_mfma_f32_16x16x32_bf16 v[96:99], v[180:183], v[196:199], v[96:99]
	v_mfma_f32_16x16x32_bf16 v[84:87], v[168:171], v[210:213], v[84:87]
	v_mfma_f32_16x16x32_bf16 v[64:67], v[180:183], v[218:221], v[64:67]
	v_mfma_f32_16x16x32_bf16 v[100:103], v[168:171], v[196:199], v[100:103]
	v_mfma_f32_16x16x32_bf16 v[112:115], v[180:183], v[188:191], v[112:115]
	v_mfma_f32_16x16x32_bf16 v[68:71], v[168:171], v[218:221], v[68:71]
	v_mfma_f32_16x16x32_bf16 v[80:83], v[180:183], v[210:213], v[80:83]
	v_mfma_f32_16x16x32_bf16 v[116:119], v[172:175], v[192:195], v[116:119]
	v_mfma_f32_16x16x32_bf16 v[96:99], v[184:187], v[206:209], v[96:99]
	v_mfma_f32_16x16x32_bf16 v[84:87], v[172:175], v[214:217], v[84:87]
	v_mfma_f32_16x16x32_bf16 v[64:67], v[184:187], v[222:225], v[64:67]
	v_mfma_f32_16x16x32_bf16 v[100:103], v[172:175], v[206:209], v[100:103]
	v_mfma_f32_16x16x32_bf16 v[112:115], v[184:187], v[192:195], v[112:115]
	v_mfma_f32_16x16x32_bf16 v[68:71], v[172:175], v[222:225], v[68:71]
	v_mfma_f32_16x16x32_bf16 v[80:83], v[184:187], v[214:217], v[80:83]
	s_setprio 0
	s_barrier
; #define PG8_STAGE(bufoff, gbase, voff) do { _Pragma("unroll") for (int _i = 0; _i < 2; ++_i) \
;         __builtin_amdgcn_global_load_lds((const unsigned*)((const char*)(gbase) + (voff)[_i]), (PG8_LAS unsigned*)(lds + (bufoff) + ldsw + _i * 8192), 16, 0, 0); } while (0)
; #define PG8_LDA(dst, b, h) do { _Pragma("unroll") for (int m = 0; m < 4; ++m) _Pragma("unroll") for (int k = 0; k < 2; ++k) dst[m][k] = *(const PG8_LAS bf16x8*)(lds + PG8_SA(b, h) + aoff + m * 2048 + k * 1024); } while (0)
; #define PG8_LDB(dst, b, h) do { _Pragma("unroll") for (int n = 0; n < 2; ++n) _Pragma("unroll") for (int k = 0; k < 2; ++k) dst[n][k] = *(const PG8_LAS bf16x8*)(lds + PG8_SB(b, h) + boff + n * 2048 + k * 1024); } while (0)
; #define PG8_MMA(ai, bj, At, Bt) do { __builtin_amdgcn_s_setprio(1); _Pragma("unroll") for (int m = 0; m < 4; ++m) _Pragma("unroll") for (int n = 0; n < 2; ++n) _Pragma("unroll") for (int k = 0; k < 2; ++k) \
;         acc[ai][bj][m][n] = __builtin_amdgcn_mfma_f32_16x16x32_bf16(Bt[n][k], At[m][k], acc[ai][bj][m][n], 0, 0, 0); __builtin_amdgcn_s_setprio(0); } while (0)
; #define PG8_WAIT_V(n) asm volatile("s_waitcnt vmcnt(" #n ")" ::: "memory")
; #define PG8_WAIT_L(n) asm volatile("s_waitcnt lgkmcnt(" #n ")" ::: "memory")
; #define PG8_BAR __builtin_amdgcn_s_barrier()
; #define PG8_SCHED __builtin_amdgcn_sched_barrier(0)
; template <class Epi, class Sched, bool ALIGN_EPI = false, bool SP2 = false>
; __device__ __forceinline__ void gemm_phase(PG8_LAS unsigned char* lds, const Gemm g, const Sched& S, const Epi& E) {
;     ...
;         for (int t = 0; t < nt; t += 2) {
;             const bool last = (t == nt - 2);
;             const char* a1 = cA + (size_t)(t + 1) * kstep;
;             const char* a2 = last ? nA : cA + (size_t)(t + 2) * kstep; const char* b2 = last ? nB : cB + (size_t)(t + 2) * kstep;
;             const char* a3 = a2 + kstep; const char* b3 = b2 + kstep;
;             if (last && has_next) S.a_ready(nxt);
;             if constexpr (SP2) {
;             PG8_LDB(B0, 0, 0); PG8_LDB(B1, 0, 1); PG8_SCHED; PG8_LDA(At, 0, 0); PG8_STAGE(PG8_SA(1, 1), a1 + hstep, voffA);
;     ...
;             PG8_LDA(At, 1, 1); PG8_STAGE(PG8_SB(1, 0), b3, voffB); PG8_STAGE(PG8_SB(1, 1), b3 + hstep, voffB); PG8_STAGE(PG8_SA(1, 0), a3, voffA);
;             PG8_WAIT_V(8); PG8_WAIT_L(0); PG8_BAR; PG8_MMA(1, 0, At, B0); PG8_MMA(1, 1, At, B1); PG8_BAR; PG8_SCHED;
	s_add_i32 s56, s82, s34
	v_lshl_add_u64 v[200:201], v[200:201], 0, s[26:27]
	s_mov_b32 m0, s56
	ds_read_b128 v[188:191], v154 offset:49152
	ds_read_b128 v[192:195], v154 offset:50176
	ds_read_b128 v[196:199], v154 offset:51200
	ds_read_b128 v[206:209], v154 offset:52224
	ds_read_b128 v[210:213], v154 offset:53248
	ds_read_b128 v[214:217], v154 offset:54272
	ds_read_b128 v[218:221], v154 offset:55296
	ds_read_b128 v[222:225], v154 offset:56320
	global_load_lds_dwordx4 v[200:201], off
	s_add_i32 m0, s56, 0x2000
	s_add_u32 s54, s54, 0x40080
	v_lshl_add_u64 v[200:201], v[226:227], 0, s[26:27]
	s_addc_u32 s55, s55, 0
	s_add_i32 s56, s83, s34
	global_load_lds_dwordx4 v[200:201], off
	v_lshl_add_u64 v[200:201], s[54:55], 0, v[132:133]
	s_mov_b32 m0, s56
	s_nop 0
	global_load_lds_dwordx4 v[200:201], off
	v_lshl_add_u64 v[200:201], s[54:55], 0, v[128:129]
	s_add_i32 m0, s56, 0x2000
	s_nop 0
	global_load_lds_dwordx4 v[200:201], off
	s_waitcnt vmcnt(6)
	s_waitcnt lgkmcnt(0)
	s_barrier
	s_setprio 1
	s_waitcnt lgkmcnt(0)
	v_mfma_f32_16x16x32_bf16 v[60:63], v[146:149], v[188:191], v[60:63]
	v_mfma_f32_16x16x32_bf16 v[40:43], v[160:163], v[196:199], v[40:43]
	v_mfma_f32_16x16x32_bf16 v[28:31], v[146:149], v[210:213], v[28:31]
	v_mfma_f32_16x16x32_bf16 v[8:11], v[160:163], v[218:221], v[8:11]
	v_mfma_f32_16x16x32_bf16 v[44:47], v[146:149], v[196:199], v[44:47]
	v_mfma_f32_16x16x32_bf16 v[56:59], v[160:163], v[188:191], v[56:59]
	v_mfma_f32_16x16x32_bf16 v[12:15], v[146:149], v[218:221], v[12:15]
	v_mfma_f32_16x16x32_bf16 v[24:27], v[160:163], v[210:213], v[24:27]
	v_mfma_f32_16x16x32_bf16 v[60:63], v[156:159], v[192:195], v[60:63]
	v_mfma_f32_16x16x32_bf16 v[40:43], v[164:167], v[206:209], v[40:43]
	v_mfma_f32_16x16x32_bf16 v[28:31], v[156:159], v[214:217], v[28:31]
	v_mfma_f32_16x16x32_bf16 v[8:11], v[164:167], v[222:225], v[8:11]
	v_mfma_f32_16x16x32_bf16 v[44:47], v[156:159], v[206:209], v[44:47]
	v_mfma_f32_16x16x32_bf16 v[56:59], v[164:167], v[192:195], v[56:59]
	v_lshl_add_u64 v[200:201], v[228:229], 0, s[26:27]
	s_mov_b32 m0, s63
	s_nop 0
	global_load_lds_dwordx4 v[200:201], off
	v_mfma_f32_16x16x32_bf16 v[12:15], v[156:159], v[222:225], v[12:15]
	v_mfma_f32_16x16x32_bf16 v[24:27], v[164:167], v[214:217], v[24:27]
	s_setprio 0
	s_setprio 1
	v_mfma_f32_16x16x32_bf16 v[52:55], v[168:171], v[188:191], v[52:55]
	v_mfma_f32_16x16x32_bf16 v[32:35], v[180:183], v[196:199], v[32:35]
	v_mfma_f32_16x16x32_bf16 v[20:23], v[168:171], v[210:213], v[20:23]
	v_mfma_f32_16x16x32_bf16 v[0:3], v[180:183], v[218:221], v[0:3]
	v_mfma_f32_16x16x32_bf16 v[36:39], v[168:171], v[196:199], v[36:39]
	v_mfma_f32_16x16x32_bf16 v[48:51], v[180:183], v[188:191], v[48:51]
	v_mfma_f32_16x16x32_bf16 v[4:7], v[168:171], v[218:221], v[4:7]
	v_mfma_f32_16x16x32_bf16 v[16:19], v[180:183], v[210:213], v[16:19]
	v_mfma_f32_16x16x32_bf16 v[52:55], v[172:175], v[192:195], v[52:55]
	v_mfma_f32_16x16x32_bf16 v[32:35], v[184:187], v[206:209], v[32:35]
	v_mfma_f32_16x16x32_bf16 v[20:23], v[172:175], v[214:217], v[20:23]
	v_mfma_f32_16x16x32_bf16 v[0:3], v[184:187], v[222:225], v[0:3]
	v_mfma_f32_16x16x32_bf16 v[36:39], v[172:175], v[206:209], v[36:39]
	v_mfma_f32_16x16x32_bf16 v[48:51], v[184:187], v[192:195], v[48:51]
	v_lshl_add_u64 v[200:201], v[230:231], 0, s[26:27]
	s_mov_b32 m0, s64
	s_nop 0
	global_load_lds_dwordx4 v[200:201], off
	v_mfma_f32_16x16x32_bf16 v[4:7], v[172:175], v[222:225], v[4:7]
	v_mfma_f32_16x16x32_bf16 v[16:19], v[184:187], v[214:217], v[16:19]
	s_setprio 0
	s_barrier
	s_add_i32 s81, s81, 2
	s_add_u32 s52, s52, 0x100
	s_addc_u32 s53, s53, 0
	s_add_u32 s79, s79, 0x100
	s_addc_u32 s80, s80, 0
.LBB0_1681:
	ds_read_b128 v[146:149], v152
	ds_read_b128 v[156:159], v152 offset:1024
	ds_read_b128 v[160:163], v152 offset:2048
	ds_read_b128 v[164:167], v152 offset:3072
	ds_read_b128 v[168:171], v153
	ds_read_b128 v[172:175], v153 offset:1024
	ds_read_b128 v[180:183], v153 offset:2048
	ds_read_b128 v[184:187], v153 offset:3072
	s_add_u32 s54, s52, 0xfffc0080
	s_addc_u32 s55, s53, -1
	s_cmp_eq_u32 s81, 12
	s_cselect_b32 s57, s47, s55
	s_cselect_b32 s56, s77, s54
	s_cselect_b32 s55, s45, s80
	s_cselect_b32 s54, s78, s79
	v_lshl_add_u64 v[200:201], s[52:53], 0, v[136:137]
	s_add_i32 m0, s58, 0xc000
	ds_read_b128 v[188:191], v154
	ds_read_b128 v[192:195], v154 offset:1024
	ds_read_b128 v[196:199], v154 offset:2048
	ds_read_b128 v[206:209], v154 offset:3072
	ds_read_b128 v[210:213], v154 offset:4096
	ds_read_b128 v[214:217], v154 offset:5120
	ds_read_b128 v[218:221], v154 offset:6144
	ds_read_b128 v[222:225], v154 offset:7168
	global_load_lds_dwordx4 v[200:201], off
	v_lshl_add_u64 v[200:201], s[52:53], 0, v[138:139]
	s_add_i32 m0, s58, 0xe000
	s_nop 0
	global_load_lds_dwordx4 v[200:201], off
	s_waitcnt vmcnt(8)
	s_waitcnt lgkmcnt(0)
	s_barrier
; #define PG8_STAGE(bufoff, gbase, voff) do { _Pragma("unroll") for (int _i = 0; _i < 2; ++_i) \
;         __builtin_amdgcn_global_load_lds((const unsigned*)((const char*)(gbase) + (voff)[_i]), (PG8_LAS unsigned*)(lds + (bufoff) + ldsw + _i * 8192), 16, 0, 0); } while (0)
; #define PG8_LDA(dst, b, h) do { _Pragma("unroll") for (int m = 0; m < 4; ++m) _Pragma("unroll") for (int k = 0; k < 2; ++k) dst[m][k] = *(const PG8_LAS bf16x8*)(lds + PG8_SA(b, h) + aoff + m * 2048 + k * 1024); } while (0)
; #define PG8_LDB(dst, b, h) do { _Pragma("unroll") for (int n = 0; n < 2; ++n) _Pragma("unroll") for (int k = 0; k < 2; ++k) dst[n][k] = *(const PG8_LAS bf16x8*)(lds + PG8_SB(b, h) + boff + n * 2048 + k * 1024); } while (0)
; #define PG8_MMA(ai, bj, At, Bt) do { __builtin_amdgcn_s_setprio(1); _Pragma("unroll") for (int m = 0; m < 4; ++m) _Pragma("unroll") for (int n = 0; n < 2; ++n) _Pragma("unroll") for (int k = 0; k < 2; ++k) \
;         acc[ai][bj][m][n] = __builtin_amdgcn_mfma_f32_16x16x32_bf16(Bt[n][k], At[m][k], acc[ai][bj][m][n], 0, 0, 0); __builtin_amdgcn_s_setprio(0); } while (0)
; #define PG8_WAIT_V(n) asm volatile("s_waitcnt vmcnt(" #n ")" ::: "memory")
; #define PG8_WAIT_L(n) asm volatile("s_waitcnt lgkmcnt(" #n ")" ::: "memory")
; #define PG8_BAR __builtin_amdgcn_s_barrier()
; #define PG8_SCHED __builtin_amdgcn_sched_barrier(0)
; template <class Epi, class Sched, bool ALIGN_EPI = false, bool SP2 = false>
; __device__ __forceinline__ void gemm_phase(PG8_LAS unsigned char* lds, const Gemm g, const Sched& S, const Epi& E) {
;     ...
;             if constexpr (SP2) {
;             PG8_LDB(B0, 0, 0); PG8_LDB(B1, 0, 1); PG8_SCHED; PG8_LDA(At, 0, 0); PG8_STAGE(PG8_SA(1, 1), a1 + hstep, voffA);
;             PG8_WAIT_V(8); PG8_WAIT_L(0); PG8_BAR; PG8_MMA(0, 0, At, B0); PG8_MMA(0, 1, At, B1); PG8_BAR; PG8_SCHED;
;             PG8_LDA(At, 0, 1); PG8_STAGE(PG8_SB(0, 0), b2, voffB); PG8_STAGE(PG8_SB(0, 1), b2 + hstep, voffB); PG8_STAGE(PG8_SA(0, 0), a2, voffA);
;             PG8_WAIT_V(8); PG8_WAIT_L(0); PG8_BAR; PG8_MMA(1, 0, At, B0); PG8_MMA(1, 1, At, B1); PG8_BAR; PG8_SCHED;
	s_setprio 1
	s_waitcnt lgkmcnt(0)
	v_mfma_f32_16x16x32_bf16 v[124:127], v[146:149], v[188:191], v[124:127]
	v_mfma_f32_16x16x32_bf16 v[104:107], v[160:163], v[196:199], v[104:107]
	v_mfma_f32_16x16x32_bf16 v[92:95], v[146:149], v[210:213], v[92:95]
	v_mfma_f32_16x16x32_bf16 v[72:75], v[160:163], v[218:221], v[72:75]
	v_mfma_f32_16x16x32_bf16 v[108:111], v[146:149], v[196:199], v[108:111]
	v_mfma_f32_16x16x32_bf16 v[120:123], v[160:163], v[188:191], v[120:123]
	v_mfma_f32_16x16x32_bf16 v[76:79], v[146:149], v[218:221], v[76:79]
	v_mfma_f32_16x16x32_bf16 v[88:91], v[160:163], v[210:213], v[88:91]
	v_mfma_f32_16x16x32_bf16 v[124:127], v[156:159], v[192:195], v[124:127]
	v_mfma_f32_16x16x32_bf16 v[104:107], v[164:167], v[206:209], v[104:107]
	v_mfma_f32_16x16x32_bf16 v[92:95], v[156:159], v[214:217], v[92:95]
	v_mfma_f32_16x16x32_bf16 v[72:75], v[164:167], v[222:225], v[72:75]
	v_mfma_f32_16x16x32_bf16 v[108:111], v[156:159], v[206:209], v[108:111]
	v_mfma_f32_16x16x32_bf16 v[120:123], v[164:167], v[192:195], v[120:123]
	v_mfma_f32_16x16x32_bf16 v[76:79], v[156:159], v[222:225], v[76:79]
	v_mfma_f32_16x16x32_bf16 v[88:91], v[164:167], v[214:217], v[88:91]
	s_setprio 0
	s_setprio 1
	v_mfma_f32_16x16x32_bf16 v[116:119], v[168:171], v[188:191], v[116:119]
	v_mfma_f32_16x16x32_bf16 v[96:99], v[180:183], v[196:199], v[96:99]
	v_mfma_f32_16x16x32_bf16 v[84:87], v[168:171], v[210:213], v[84:87]
	v_mfma_f32_16x16x32_bf16 v[64:67], v[180:183], v[218:221], v[64:67]
	v_mfma_f32_16x16x32_bf16 v[100:103], v[168:171], v[196:199], v[100:103]
	v_mfma_f32_16x16x32_bf16 v[112:115], v[180:183], v[188:191], v[112:115]
	v_mfma_f32_16x16x32_bf16 v[68:71], v[168:171], v[218:221], v[68:71]
	v_mfma_f32_16x16x32_bf16 v[80:83], v[180:183], v[210:213], v[80:83]
	v_mfma_f32_16x16x32_bf16 v[116:119], v[172:175], v[192:195], v[116:119]
	v_mfma_f32_16x16x32_bf16 v[96:99], v[184:187], v[206:209], v[96:99]
	v_mfma_f32_16x16x32_bf16 v[84:87], v[172:175], v[214:217], v[84:87]
	v_mfma_f32_16x16x32_bf16 v[64:67], v[184:187], v[222:225], v[64:67]
	v_mfma_f32_16x16x32_bf16 v[100:103], v[172:175], v[206:209], v[100:103]
	v_mfma_f32_16x16x32_bf16 v[112:115], v[184:187], v[192:195], v[112:115]
	v_mfma_f32_16x16x32_bf16 v[68:71], v[172:175], v[222:225], v[68:71]
	v_mfma_f32_16x16x32_bf16 v[80:83], v[184:187], v[214:217], v[80:83]
	s_setprio 0
	s_barrier
	s_add_i32 s82, s65, s34
	v_lshl_add_u64 v[200:201], s[54:55], 0, v[132:133]
	s_mov_b32 m0, s82
	ds_read_b128 v[188:191], v154 offset:16384
	ds_read_b128 v[192:195], v154 offset:17408
	ds_read_b128 v[196:199], v154 offset:18432
	ds_read_b128 v[206:209], v154 offset:19456
	ds_read_b128 v[210:213], v154 offset:20480
	ds_read_b128 v[214:217], v154 offset:21504
	ds_read_b128 v[218:221], v154 offset:22528
	ds_read_b128 v[222:225], v154 offset:23552
	global_load_lds_dwordx4 v[200:201], off
	s_add_i32 m0, s82, 0x2000
	s_add_u32 s82, s54, 0x40000
	v_lshl_add_u64 v[226:227], s[54:55], 0, v[128:129]
	s_addc_u32 s83, s55, 0
	s_add_i32 s84, s66, s34
	global_load_lds_dwordx4 v[226:227], off
	v_lshl_add_u64 v[228:229], s[82:83], 0, v[132:133]
	s_mov_b32 m0, s84
	global_load_lds_dwordx4 v[228:229], off
	v_lshl_add_u64 v[228:229], s[82:83], 0, v[128:129]
	s_add_i32 m0, s84, 0x2000
	s_nop 0
	global_load_lds_dwordx4 v[228:229], off
	s_waitcnt vmcnt(6)
	s_waitcnt lgkmcnt(0)
	s_barrier
	s_setprio 1
	s_waitcnt lgkmcnt(0)
	v_mfma_f32_16x16x32_bf16 v[60:63], v[146:149], v[188:191], v[60:63]
	v_mfma_f32_16x16x32_bf16 v[40:43], v[160:163], v[196:199], v[40:43]
	v_mfma_f32_16x16x32_bf16 v[28:31], v[146:149], v[210:213], v[28:31]
	v_mfma_f32_16x16x32_bf16 v[8:11], v[160:163], v[218:221], v[8:11]
	v_mfma_f32_16x16x32_bf16 v[44:47], v[146:149], v[196:199], v[44:47]
	v_mfma_f32_16x16x32_bf16 v[56:59], v[160:163], v[188:191], v[56:59]
	v_mfma_f32_16x16x32_bf16 v[12:15], v[146:149], v[218:221], v[12:15]
	v_mfma_f32_16x16x32_bf16 v[24:27], v[160:163], v[210:213], v[24:27]
	v_mfma_f32_16x16x32_bf16 v[60:63], v[156:159], v[192:195], v[60:63]
	v_mfma_f32_16x16x32_bf16 v[40:43], v[164:167], v[206:209], v[40:43]
	v_mfma_f32_16x16x32_bf16 v[28:31], v[156:159], v[214:217], v[28:31]
	v_mfma_f32_16x16x32_bf16 v[8:11], v[164:167], v[222:225], v[8:11]
	v_mfma_f32_16x16x32_bf16 v[44:47], v[156:159], v[206:209], v[44:47]
	v_mfma_f32_16x16x32_bf16 v[56:59], v[164:167], v[192:195], v[56:59]
	v_lshl_add_u64 v[228:229], s[56:57], 0, v[134:135]
	s_mov_b32 m0, s58
	s_nop 0
	global_load_lds_dwordx4 v[228:229], off
	v_mfma_f32_16x16x32_bf16 v[12:15], v[156:159], v[222:225], v[12:15]
	v_mfma_f32_16x16x32_bf16 v[24:27], v[164:167], v[214:217], v[24:27]
	s_setprio 0
	s_setprio 1
	v_mfma_f32_16x16x32_bf16 v[52:55], v[168:171], v[188:191], v[52:55]
	v_mfma_f32_16x16x32_bf16 v[32:35], v[180:183], v[196:199], v[32:35]
	v_mfma_f32_16x16x32_bf16 v[20:23], v[168:171], v[210:213], v[20:23]
	v_mfma_f32_16x16x32_bf16 v[0:3], v[180:183], v[218:221], v[0:3]
	v_mfma_f32_16x16x32_bf16 v[36:39], v[168:171], v[196:199], v[36:39]
	v_mfma_f32_16x16x32_bf16 v[48:51], v[180:183], v[188:191], v[48:51]
	v_mfma_f32_16x16x32_bf16 v[4:7], v[168:171], v[218:221], v[4:7]
	v_mfma_f32_16x16x32_bf16 v[16:19], v[180:183], v[210:213], v[16:19]
	v_mfma_f32_16x16x32_bf16 v[52:55], v[172:175], v[192:195], v[52:55]
	v_mfma_f32_16x16x32_bf16 v[32:35], v[184:187], v[206:209], v[32:35]
	v_mfma_f32_16x16x32_bf16 v[20:23], v[172:175], v[214:217], v[20:23]
	v_mfma_f32_16x16x32_bf16 v[0:3], v[184:187], v[222:225], v[0:3]
	v_mfma_f32_16x16x32_bf16 v[36:39], v[172:175], v[206:209], v[36:39]
	v_mfma_f32_16x16x32_bf16 v[48:51], v[184:187], v[192:195], v[48:51]
	v_lshl_add_u64 v[230:231], s[56:57], 0, v[130:131]
	s_mov_b32 m0, s59
	s_nop 0
	global_load_lds_dwordx4 v[230:231], off
	v_mfma_f32_16x16x32_bf16 v[4:7], v[172:175], v[222:225], v[4:7]
	v_mfma_f32_16x16x32_bf16 v[16:19], v[184:187], v[214:217], v[16:19]
	s_setprio 0
	s_barrier
; #define PG8_STAGE(bufoff, gbase, voff) do { _Pragma("unroll") for (int _i = 0; _i < 2; ++_i) \
;         __builtin_amdgcn_global_load_lds((const unsigned*)((const char*)(gbase) + (voff)[_i]), (PG8_LAS unsigned*)(lds + (bufoff) + ldsw + _i * 8192), 16, 0, 0); } while (0)
; #define PG8_LDA(dst, b, h) do { _Pragma("unroll") for (int m = 0; m < 4; ++m) _Pragma("unroll") for (int k = 0; k < 2; ++k) dst[m][k] = *(const PG8_LAS bf16x8*)(lds + PG8_SA(b, h) + aoff + m * 2048 + k * 1024); } while (0)
; #define PG8_LDB(dst, b, h) do { _Pragma("unroll") for (int n = 0; n < 2; ++n) _Pragma("unroll") for (int k = 0; k < 2; ++k) dst[n][k] = *(const PG8_LAS bf16x8*)(lds + PG8_SB(b, h) + boff + n * 2048 + k * 1024); } while (0)
; #define PG8_MMA(ai, bj, At, Bt) do { __builtin_amdgcn_s_setprio(1); _Pragma("unroll") for (int m = 0; m < 4; ++m) _Pragma("unroll") for (int n = 0; n < 2; ++n) _Pragma("unroll") for (int k = 0; k < 2; ++k) \
;         acc[ai][bj][m][n] = __builtin_amdgcn_mfma_f32_16x16x32_bf16(Bt[n][k], At[m][k], acc[ai][bj][m][n], 0, 0, 0); __builtin_amdgcn_s_setprio(0); } while (0)
; #define PG8_WAIT_V(n) asm volatile("s_waitcnt vmcnt(" #n ")" ::: "memory")
; #define PG8_WAIT_L(n) asm volatile("s_waitcnt lgkmcnt(" #n ")" ::: "memory")
; #define PG8_BAR __builtin_amdgcn_s_barrier()
; #define PG8_SCHED __builtin_amdgcn_sched_barrier(0)
; template <class Epi, class Sched, bool ALIGN_EPI = false, bool SP2 = false>
; __device__ __forceinline__ void gemm_phase(PG8_LAS unsigned char* lds, const Gemm g, const Sched& S, const Epi& E) {
;     ...
;             PG8_LDB(B0, 1, 0); PG8_LDB(B1, 1, 1); PG8_SCHED; PG8_LDA(At, 1, 0); PG8_STAGE(PG8_SA(0, 1), a2 + hstep, voffA);
;             PG8_WAIT_V(8); PG8_WAIT_L(0); PG8_BAR; PG8_MMA(0, 0, At, B0); PG8_MMA(0, 1, At, B1); PG8_BAR; PG8_SCHED;
	s_add_i32 s82, 0, 0x18000
	s_add_i32 s83, 0, 0x1c000
	v_add_u32_e32 v164, s82, v150
	v_add_u32_e32 v179, s83, v150
	ds_read_b128 v[146:149], v164
	ds_read_b128 v[156:159], v164 offset:1024
	ds_read_b128 v[160:163], v164 offset:2048
	ds_read_b128 v[164:167], v164 offset:3072
	ds_read_b128 v[168:171], v179
	ds_read_b128 v[172:175], v179 offset:1024
	ds_read_b128 v[180:183], v179 offset:2048
	ds_read_b128 v[184:187], v179 offset:3072
	s_add_u32 s56, s56, 0x40000
	s_addc_u32 s57, s57, 0
	s_mov_b32 m0, s60
	v_lshl_add_u64 v[232:233], s[56:57], 0, v[134:135]
	ds_read_b128 v[188:191], v154 offset:32768
	ds_read_b128 v[192:195], v154 offset:33792
	ds_read_b128 v[196:199], v154 offset:34816
	ds_read_b128 v[206:209], v154 offset:35840
	ds_read_b128 v[210:213], v154 offset:36864
	ds_read_b128 v[214:217], v154 offset:37888
	ds_read_b128 v[218:221], v154 offset:38912
	ds_read_b128 v[222:225], v154 offset:39936
	global_load_lds_dwordx4 v[232:233], off
	v_lshl_add_u64 v[232:233], s[56:57], 0, v[130:131]
	s_mov_b32 m0, s61
	s_nop 0
	global_load_lds_dwordx4 v[232:233], off
	s_waitcnt vmcnt(8)
	s_waitcnt lgkmcnt(0)
	s_barrier
	s_setprio 1
	s_waitcnt lgkmcnt(0)
	v_mfma_f32_16x16x32_bf16 v[124:127], v[146:149], v[188:191], v[124:127]
	v_mfma_f32_16x16x32_bf16 v[104:107], v[160:163], v[196:199], v[104:107]
	v_mfma_f32_16x16x32_bf16 v[92:95], v[146:149], v[210:213], v[92:95]
	v_mfma_f32_16x16x32_bf16 v[72:75], v[160:163], v[218:221], v[72:75]
	v_mfma_f32_16x16x32_bf16 v[108:111], v[146:149], v[196:199], v[108:111]
	v_mfma_f32_16x16x32_bf16 v[120:123], v[160:163], v[188:191], v[120:123]
	v_mfma_f32_16x16x32_bf16 v[76:79], v[146:149], v[218:221], v[76:79]
	v_mfma_f32_16x16x32_bf16 v[88:91], v[160:163], v[210:213], v[88:91]
	v_mfma_f32_16x16x32_bf16 v[124:127], v[156:159], v[192:195], v[124:127]
	v_mfma_f32_16x16x32_bf16 v[104:107], v[164:167], v[206:209], v[104:107]
	v_mfma_f32_16x16x32_bf16 v[92:95], v[156:159], v[214:217], v[92:95]
	v_mfma_f32_16x16x32_bf16 v[72:75], v[164:167], v[222:225], v[72:75]
	v_mfma_f32_16x16x32_bf16 v[108:111], v[156:159], v[206:209], v[108:111]
	v_mfma_f32_16x16x32_bf16 v[120:123], v[164:167], v[192:195], v[120:123]
	v_mfma_f32_16x16x32_bf16 v[76:79], v[156:159], v[222:225], v[76:79]
	v_mfma_f32_16x16x32_bf16 v[88:91], v[164:167], v[214:217], v[88:91]
	s_setprio 0
	s_setprio 1
	v_mfma_f32_16x16x32_bf16 v[116:119], v[168:171], v[188:191], v[116:119]
	v_mfma_f32_16x16x32_bf16 v[96:99], v[180:183], v[196:199], v[96:99]
	v_mfma_f32_16x16x32_bf16 v[84:87], v[168:171], v[210:213], v[84:87]
	v_mfma_f32_16x16x32_bf16 v[64:67], v[180:183], v[218:221], v[64:67]
	v_mfma_f32_16x16x32_bf16 v[100:103], v[168:171], v[196:199], v[100:103]
	v_mfma_f32_16x16x32_bf16 v[112:115], v[180:183], v[188:191], v[112:115]
	v_mfma_f32_16x16x32_bf16 v[68:71], v[168:171], v[218:221], v[68:71]
	v_mfma_f32_16x16x32_bf16 v[80:83], v[180:183], v[210:213], v[80:83]
	v_mfma_f32_16x16x32_bf16 v[116:119], v[172:175], v[192:195], v[116:119]
	v_mfma_f32_16x16x32_bf16 v[96:99], v[184:187], v[206:209], v[96:99]
	v_mfma_f32_16x16x32_bf16 v[84:87], v[172:175], v[214:217], v[84:87]
	v_mfma_f32_16x16x32_bf16 v[64:67], v[184:187], v[222:225], v[64:67]
	v_mfma_f32_16x16x32_bf16 v[100:103], v[172:175], v[206:209], v[100:103]
	v_mfma_f32_16x16x32_bf16 v[112:115], v[184:187], v[192:195], v[112:115]
	v_mfma_f32_16x16x32_bf16 v[68:71], v[172:175], v[222:225], v[68:71]
	v_mfma_f32_16x16x32_bf16 v[80:83], v[184:187], v[214:217], v[80:83]
	s_setprio 0
	s_barrier
; #define PG8_STAGE(bufoff, gbase, voff) do { _Pragma("unroll") for (int _i = 0; _i < 2; ++_i) \
;         __builtin_amdgcn_global_load_lds((const unsigned*)((const char*)(gbase) + (voff)[_i]), (PG8_LAS unsigned*)(lds + (bufoff) + ldsw + _i * 8192), 16, 0, 0); } while (0)
; #define PG8_LDA(dst, b, h) do { _Pragma("unroll") for (int m = 0; m < 4; ++m) _Pragma("unroll") for (int k = 0; k < 2; ++k) dst[m][k] = *(const PG8_LAS bf16x8*)(lds + PG8_SA(b, h) + aoff + m * 2048 + k * 1024); } while (0)
; #define PG8_MMA(ai, bj, At, Bt) do { __builtin_amdgcn_s_setprio(1); _Pragma("unroll") for (int m = 0; m < 4; ++m) _Pragma("unroll") for (int n = 0; n < 2; ++n) _Pragma("unroll") for (int k = 0; k < 2; ++k) \
;         acc[ai][bj][m][n] = __builtin_amdgcn_mfma_f32_16x16x32_bf16(Bt[n][k], At[m][k], acc[ai][bj][m][n], 0, 0, 0); __builtin_amdgcn_s_setprio(0); } while (0)
; #define PG8_WAIT_V(n) asm volatile("s_waitcnt vmcnt(" #n ")" ::: "memory")
; #define PG8_WAIT_L(n) asm volatile("s_waitcnt lgkmcnt(" #n ")" ::: "memory")
; #define PG8_BAR __builtin_amdgcn_s_barrier()
; #define PG8_SCHED __builtin_amdgcn_sched_barrier(0)
; template <class Epi, class Sched, bool ALIGN_EPI = false, bool SP2 = false>
; __device__ __forceinline__ void gemm_phase(PG8_LAS unsigned char* lds, const Gemm g, const Sched& S, const Epi& E) {
;     ...
;         for (int t = 0; t < nt; t += 2) {
;             const bool last = (t == nt - 2);
;     ...
;             PG8_LDA(At, 1, 1); PG8_STAGE(PG8_SB(1, 0), b3, voffB); PG8_STAGE(PG8_SB(1, 1), b3 + hstep, voffB); PG8_STAGE(PG8_SA(1, 0), a3, voffA);
;             PG8_WAIT_V(8); PG8_WAIT_L(0); PG8_BAR; PG8_MMA(1, 0, At, B0); PG8_MMA(1, 1, At, B1); PG8_BAR; PG8_SCHED;
;     ...
;         if constexpr (ALIGN_EPI) { if (wr == 0) PG8_BAR; }
	s_add_i32 s56, s82, s34
	v_lshl_add_u64 v[200:201], v[200:201], 0, s[26:27]
	s_mov_b32 m0, s56
	ds_read_b128 v[188:191], v154 offset:49152
	ds_read_b128 v[192:195], v154 offset:50176
	ds_read_b128 v[196:199], v154 offset:51200
	ds_read_b128 v[206:209], v154 offset:52224
	ds_read_b128 v[210:213], v154 offset:53248
	ds_read_b128 v[214:217], v154 offset:54272
	ds_read_b128 v[218:221], v154 offset:55296
	ds_read_b128 v[222:225], v154 offset:56320
	global_load_lds_dwordx4 v[200:201], off
	s_add_i32 m0, s56, 0x2000
	s_add_u32 s54, s54, 0x40080
	v_lshl_add_u64 v[200:201], v[226:227], 0, s[26:27]
	s_addc_u32 s55, s55, 0
	s_add_i32 s56, s83, s34
	global_load_lds_dwordx4 v[200:201], off
	v_lshl_add_u64 v[200:201], s[54:55], 0, v[132:133]
	s_mov_b32 m0, s56
	s_nop 0
	global_load_lds_dwordx4 v[200:201], off
	v_lshl_add_u64 v[200:201], s[54:55], 0, v[128:129]
	s_add_i32 m0, s56, 0x2000
	s_nop 0
	global_load_lds_dwordx4 v[200:201], off
	s_waitcnt vmcnt(6)
	s_waitcnt lgkmcnt(0)
	s_barrier
	s_setprio 1
	s_waitcnt lgkmcnt(0)
	v_mfma_f32_16x16x32_bf16 v[60:63], v[146:149], v[188:191], v[60:63]
	v_mfma_f32_16x16x32_bf16 v[40:43], v[160:163], v[196:199], v[40:43]
	v_mfma_f32_16x16x32_bf16 v[28:31], v[146:149], v[210:213], v[28:31]
	v_mfma_f32_16x16x32_bf16 v[8:11], v[160:163], v[218:221], v[8:11]
	v_mfma_f32_16x16x32_bf16 v[44:47], v[146:149], v[196:199], v[44:47]
	v_mfma_f32_16x16x32_bf16 v[56:59], v[160:163], v[188:191], v[56:59]
	v_mfma_f32_16x16x32_bf16 v[12:15], v[146:149], v[218:221], v[12:15]
	v_mfma_f32_16x16x32_bf16 v[24:27], v[160:163], v[210:213], v[24:27]
	v_mfma_f32_16x16x32_bf16 v[60:63], v[156:159], v[192:195], v[60:63]
	v_mfma_f32_16x16x32_bf16 v[40:43], v[164:167], v[206:209], v[40:43]
	v_mfma_f32_16x16x32_bf16 v[28:31], v[156:159], v[214:217], v[28:31]
	v_mfma_f32_16x16x32_bf16 v[8:11], v[164:167], v[222:225], v[8:11]
	v_mfma_f32_16x16x32_bf16 v[44:47], v[156:159], v[206:209], v[44:47]
	v_mfma_f32_16x16x32_bf16 v[56:59], v[164:167], v[192:195], v[56:59]
	v_lshl_add_u64 v[200:201], v[228:229], 0, s[26:27]
	s_mov_b32 m0, s63
	s_nop 0
	global_load_lds_dwordx4 v[200:201], off
	v_mfma_f32_16x16x32_bf16 v[12:15], v[156:159], v[222:225], v[12:15]
	v_mfma_f32_16x16x32_bf16 v[24:27], v[164:167], v[214:217], v[24:27]
	s_setprio 0
	s_setprio 1
	v_mfma_f32_16x16x32_bf16 v[52:55], v[168:171], v[188:191], v[52:55]
	v_mfma_f32_16x16x32_bf16 v[32:35], v[180:183], v[196:199], v[32:35]
	v_mfma_f32_16x16x32_bf16 v[20:23], v[168:171], v[210:213], v[20:23]
	v_mfma_f32_16x16x32_bf16 v[0:3], v[180:183], v[218:221], v[0:3]
	v_mfma_f32_16x16x32_bf16 v[36:39], v[168:171], v[196:199], v[36:39]
	v_mfma_f32_16x16x32_bf16 v[48:51], v[180:183], v[188:191], v[48:51]
	v_mfma_f32_16x16x32_bf16 v[4:7], v[168:171], v[218:221], v[4:7]
	v_mfma_f32_16x16x32_bf16 v[16:19], v[180:183], v[210:213], v[16:19]
	v_mfma_f32_16x16x32_bf16 v[52:55], v[172:175], v[192:195], v[52:55]
	v_mfma_f32_16x16x32_bf16 v[32:35], v[184:187], v[206:209], v[32:35]
	v_mfma_f32_16x16x32_bf16 v[20:23], v[172:175], v[214:217], v[20:23]
	v_mfma_f32_16x16x32_bf16 v[0:3], v[184:187], v[222:225], v[0:3]
	v_mfma_f32_16x16x32_bf16 v[36:39], v[172:175], v[206:209], v[36:39]
	v_mfma_f32_16x16x32_bf16 v[48:51], v[184:187], v[192:195], v[48:51]
	v_lshl_add_u64 v[200:201], v[230:231], 0, s[26:27]
	s_mov_b32 m0, s64
	s_nop 0
	global_load_lds_dwordx4 v[200:201], off
	v_mfma_f32_16x16x32_bf16 v[4:7], v[172:175], v[222:225], v[4:7]
	v_mfma_f32_16x16x32_bf16 v[16:19], v[184:187], v[214:217], v[16:19]
	s_setprio 0
	s_barrier
	s_add_i32 s81, s81, 2
	s_add_u32 s52, s52, 0x100
	s_addc_u32 s53, s53, 0
	s_add_u32 s79, s79, 0x100
	s_addc_u32 s80, s80, 0
	s_cmp_gt_u32 s81, 13
	s_cbranch_scc0 .LBB0_1681
	s_and_b64 vcc, exec, s[28:29]
	s_cbranch_vccz .LBB0_1684
	s_barrier

; #define PG8_STAGE(bufoff, gbase, voff) do { _Pragma("unroll") for (int _i = 0; _i < 2; ++_i) \
;         __builtin_amdgcn_global_load_lds((const unsigned*)((const char*)(gbase) + (voff)[_i]), (PG8_LAS unsigned*)(lds + (bufoff) + ldsw + _i * 8192), 16, 0, 0); } while (0)
; #define PG8_LDA(dst, b, h) do { _Pragma("unroll") for (int m = 0; m < 4; ++m) _Pragma("unroll") for (int k = 0; k < 2; ++k) dst[m][k] = *(const PG8_LAS bf16x8*)(lds + PG8_SA(b, h) + aoff + m * 2048 + k * 1024); } while (0)
; #define PG8_LDB(dst, b, h) do { _Pragma("unroll") for (int n = 0; n < 2; ++n) _Pragma("unroll") for (int k = 0; k < 2; ++k) dst[n][k] = *(const PG8_LAS bf16x8*)(lds + PG8_SB(b, h) + boff + n * 2048 + k * 1024); } while (0)
; #define PG8_WAIT_V(n) asm volatile("s_waitcnt vmcnt(" #n ")" ::: "memory")
; #define PG8_WAIT_L(n) asm volatile("s_waitcnt lgkmcnt(" #n ")" ::: "memory")
; #define PG8_BAR __builtin_amdgcn_s_barrier()
; #define PG8_SCHED __builtin_amdgcn_sched_barrier(0)
; template <class Epi, class Sched, bool ALIGN_EPI = false, bool SP2 = false>
; __device__ __forceinline__ void gemm_phase(PG8_LAS unsigned char* lds, const Gemm g, const Sched& S, const Epi& E) {
;     ...
;         const bool has_next = S.next(ui + 1, nxt);
;         const char* nA = has_next ? (const char*)g.A + (size_t)nxt.pm * tstep : cA; const char* nB = has_next ? (const char*)g.Bt + (size_t)nxt.pn * tstep : cB;
;         for (int t = 0; t < nt; t += 2) {
;             const bool last = (t == nt - 2);
;             const char* a1 = cA + (size_t)(t + 1) * kstep;
;             const char* a2 = last ? nA : cA + (size_t)(t + 2) * kstep; const char* b2 = last ? nB : cB + (size_t)(t + 2) * kstep;
;             const char* a3 = a2 + kstep; const char* b3 = b2 + kstep;
;             if (last && has_next) S.a_ready(nxt);
;             if constexpr (SP2) {
;             PG8_LDB(B0, 0, 0); PG8_LDB(B1, 0, 1); PG8_SCHED; PG8_LDA(At, 0, 0); PG8_STAGE(PG8_SA(1, 1), a1 + hstep, voffA);
;             PG8_WAIT_V(8); PG8_WAIT_L(0); PG8_BAR; PG8_MMA(0, 0, At, B0); PG8_MMA(0, 1, At, B1); PG8_BAR; PG8_SCHED;
;             PG8_LDA(At, 0, 1); PG8_STAGE(PG8_SB(0, 0), b2, voffB); PG8_STAGE(PG8_SB(0, 1), b2 + hstep, voffB); PG8_STAGE(PG8_SA(0, 0), a2, voffA);
;             PG8_WAIT_V(8); PG8_WAIT_L(0); PG8_BAR; PG8_MMA(1, 0, At, B0); PG8_MMA(1, 1, At, B1); PG8_BAR; PG8_SCHED;
.LBB0_1815:
	s_ashr_i32 s29, s28, 31
	s_lshl_b64 s[36:37], s[28:29], 18
	s_add_u32 s36, s92, s36
	s_addc_u32 s37, s93, s37
	s_and_b64 s[38:39], s[6:7], exec
	s_cselect_b32 s29, s37, s45
	s_cselect_b32 s41, s36, s44
	s_ashr_i32 s27, s26, 31
	s_lshl_b64 s[38:39], s[26:27], 18
	s_add_u32 s38, s3, s38
	s_addc_u32 s39, s14, s39
	s_and_b64 s[48:49], s[6:7], exec
	s_cselect_b32 s27, s39, s47
	s_cselect_b32 s58, s38, s46
	s_add_u32 s44, s44, 0x20080
	s_addc_u32 s45, s45, 0
	s_add_u32 s59, s46, 0x100
	s_addc_u32 s60, s47, 0
	s_mov_b32 s61, -2
	s_waitcnt lgkmcnt(0)
	ds_read_b128 v[144:147], v151
	ds_read_b128 v[156:159], v151 offset:1024
	ds_read_b128 v[160:163], v151 offset:2048
	ds_read_b128 v[164:167], v151 offset:3072
	ds_read_b128 v[168:171], v152
	ds_read_b128 v[172:175], v152 offset:1024
	ds_read_b128 v[176:179], v152 offset:2048
	ds_read_b128 v[180:183], v152 offset:3072
	s_add_u32 s46, s44, 0xfffe0080
	s_addc_u32 s47, s45, -1
	s_cmp_eq_u32 s61, 4
	s_cselect_b32 s49, s29, s47
	s_cselect_b32 s48, s41, s46
	s_cselect_b32 s47, s27, s60
	s_cselect_b32 s46, s58, s59
	v_lshl_add_u64 v[218:219], s[44:45], 0, v[136:137]
	s_add_i32 m0, s33, 0xc000
	ds_read_b128 v[184:187], v153
	ds_read_b128 v[188:191], v153 offset:1024
	ds_read_b128 v[192:195], v153 offset:2048
	ds_read_b128 v[196:199], v153 offset:3072
	ds_read_b128 v[200:203], v153 offset:4096
	ds_read_b128 v[206:209], v153 offset:5120
	ds_read_b128 v[210:213], v153 offset:6144
	ds_read_b128 v[214:217], v153 offset:7168
	global_load_lds_dwordx4 v[218:219], off
	v_lshl_add_u64 v[218:219], s[44:45], 0, v[138:139]
	s_add_i32 m0, s33, 0xe000
	s_nop 0
	global_load_lds_dwordx4 v[218:219], off
	s_waitcnt vmcnt(8)
	s_waitcnt lgkmcnt(0)
	s_barrier
	s_setprio 1
	s_waitcnt lgkmcnt(0)
	v_mfma_f32_16x16x32_bf16 v[124:127], v[144:147], v[184:187], 0
	v_mfma_f32_16x16x32_bf16 v[104:107], v[160:163], v[192:195], 0
	v_mfma_f32_16x16x32_bf16 v[92:95], v[144:147], v[200:203], 0
	v_mfma_f32_16x16x32_bf16 v[72:75], v[160:163], v[210:213], 0
	v_mfma_f32_16x16x32_bf16 v[108:111], v[144:147], v[192:195], 0
	v_mfma_f32_16x16x32_bf16 v[120:123], v[160:163], v[184:187], 0
	v_mfma_f32_16x16x32_bf16 v[76:79], v[144:147], v[210:213], 0
	v_mfma_f32_16x16x32_bf16 v[88:91], v[160:163], v[200:203], 0
	v_mfma_f32_16x16x32_bf16 v[124:127], v[156:159], v[188:191], v[124:127]
	v_mfma_f32_16x16x32_bf16 v[104:107], v[164:167], v[196:199], v[104:107]
	v_mfma_f32_16x16x32_bf16 v[92:95], v[156:159], v[206:209], v[92:95]
	v_mfma_f32_16x16x32_bf16 v[72:75], v[164:167], v[214:217], v[72:75]
	v_mfma_f32_16x16x32_bf16 v[108:111], v[156:159], v[196:199], v[108:111]
	v_mfma_f32_16x16x32_bf16 v[120:123], v[164:167], v[188:191], v[120:123]
	v_mfma_f32_16x16x32_bf16 v[76:79], v[156:159], v[214:217], v[76:79]
	v_mfma_f32_16x16x32_bf16 v[88:91], v[164:167], v[206:209], v[88:91]
	s_setprio 0
	s_setprio 1
	v_mfma_f32_16x16x32_bf16 v[116:119], v[168:171], v[184:187], 0
	v_mfma_f32_16x16x32_bf16 v[96:99], v[176:179], v[192:195], 0
	v_mfma_f32_16x16x32_bf16 v[84:87], v[168:171], v[200:203], 0
	v_mfma_f32_16x16x32_bf16 v[64:67], v[176:179], v[210:213], 0
	v_mfma_f32_16x16x32_bf16 v[100:103], v[168:171], v[192:195], 0
	v_mfma_f32_16x16x32_bf16 v[112:115], v[176:179], v[184:187], 0
	v_mfma_f32_16x16x32_bf16 v[68:71], v[168:171], v[210:213], 0
	v_mfma_f32_16x16x32_bf16 v[80:83], v[176:179], v[200:203], 0
	v_mfma_f32_16x16x32_bf16 v[116:119], v[172:175], v[188:191], v[116:119]
	v_mfma_f32_16x16x32_bf16 v[96:99], v[180:183], v[196:199], v[96:99]
	v_mfma_f32_16x16x32_bf16 v[84:87], v[172:175], v[206:209], v[84:87]
	v_mfma_f32_16x16x32_bf16 v[64:67], v[180:183], v[214:217], v[64:67]
	v_mfma_f32_16x16x32_bf16 v[100:103], v[172:175], v[196:199], v[100:103]
	v_mfma_f32_16x16x32_bf16 v[112:115], v[180:183], v[188:191], v[112:115]
	v_mfma_f32_16x16x32_bf16 v[68:71], v[172:175], v[214:217], v[68:71]
	v_mfma_f32_16x16x32_bf16 v[80:83], v[180:183], v[206:209], v[80:83]
	s_setprio 0
	s_barrier
	s_add_i32 s62, s54, s15
	v_lshl_add_u64 v[218:219], s[46:47], 0, v[130:131]
	s_mov_b32 m0, s62
	ds_read_b128 v[184:187], v153 offset:16384
	ds_read_b128 v[188:191], v153 offset:17408
	ds_read_b128 v[192:195], v153 offset:18432
	ds_read_b128 v[196:199], v153 offset:19456
	ds_read_b128 v[200:203], v153 offset:20480
	ds_read_b128 v[206:209], v153 offset:21504
	ds_read_b128 v[210:213], v153 offset:22528
	ds_read_b128 v[214:217], v153 offset:23552
	global_load_lds_dwordx4 v[218:219], off
	s_add_i32 m0, s62, 0x2000
	s_add_u32 s62, s46, 0x20000
	v_lshl_add_u64 v[220:221], s[46:47], 0, v[134:135]
	s_addc_u32 s63, s47, 0
	s_add_i32 s64, s55, s15
	global_load_lds_dwordx4 v[220:221], off
	v_lshl_add_u64 v[222:223], s[62:63], 0, v[130:131]
	s_mov_b32 m0, s64
	global_load_lds_dwordx4 v[222:223], off
	v_lshl_add_u64 v[222:223], s[62:63], 0, v[134:135]
	s_add_i32 m0, s64, 0x2000
	s_nop 0
	global_load_lds_dwordx4 v[222:223], off
	s_waitcnt vmcnt(6)
	s_waitcnt lgkmcnt(0)
	s_barrier
; #define PG8_STAGE(bufoff, gbase, voff) do { _Pragma("unroll") for (int _i = 0; _i < 2; ++_i) \
;         __builtin_amdgcn_global_load_lds((const unsigned*)((const char*)(gbase) + (voff)[_i]), (PG8_LAS unsigned*)(lds + (bufoff) + ldsw + _i * 8192), 16, 0, 0); } while (0)
; #define PG8_LDA(dst, b, h) do { _Pragma("unroll") for (int m = 0; m < 4; ++m) _Pragma("unroll") for (int k = 0; k < 2; ++k) dst[m][k] = *(const PG8_LAS bf16x8*)(lds + PG8_SA(b, h) + aoff + m * 2048 + k * 1024); } while (0)
; #define PG8_LDB(dst, b, h) do { _Pragma("unroll") for (int n = 0; n < 2; ++n) _Pragma("unroll") for (int k = 0; k < 2; ++k) dst[n][k] = *(const PG8_LAS bf16x8*)(lds + PG8_SB(b, h) + boff + n * 2048 + k * 1024); } while (0)
; #define PG8_MMA(ai, bj, At, Bt) do { __builtin_amdgcn_s_setprio(1); _Pragma("unroll") for (int m = 0; m < 4; ++m) _Pragma("unroll") for (int n = 0; n < 2; ++n) _Pragma("unroll") for (int k = 0; k < 2; ++k) \
;         acc[ai][bj][m][n] = __builtin_amdgcn_mfma_f32_16x16x32_bf16(Bt[n][k], At[m][k], acc[ai][bj][m][n], 0, 0, 0); __builtin_amdgcn_s_setprio(0); } while (0)
; #define PG8_WAIT_V(n) asm volatile("s_waitcnt vmcnt(" #n ")" ::: "memory")
; #define PG8_WAIT_L(n) asm volatile("s_waitcnt lgkmcnt(" #n ")" ::: "memory")
; #define PG8_BAR __builtin_amdgcn_s_barrier()
; #define PG8_SCHED __builtin_amdgcn_sched_barrier(0)
; template <class Epi, class Sched, bool ALIGN_EPI = false, bool SP2 = false>
; __device__ __forceinline__ void gemm_phase(PG8_LAS unsigned char* lds, const Gemm g, const Sched& S, const Epi& E) {
;     ...
;             PG8_WAIT_V(8); PG8_WAIT_L(0); PG8_BAR; PG8_MMA(1, 0, At, B0); PG8_MMA(1, 1, At, B1); PG8_BAR; PG8_SCHED;
;             PG8_LDB(B0, 1, 0); PG8_LDB(B1, 1, 1); PG8_SCHED; PG8_LDA(At, 1, 0); PG8_STAGE(PG8_SA(0, 1), a2 + hstep, voffA);
;             PG8_WAIT_V(8); PG8_WAIT_L(0); PG8_BAR; PG8_MMA(0, 0, At, B0); PG8_MMA(0, 1, At, B1); PG8_BAR; PG8_SCHED;
	s_setprio 1
	s_waitcnt lgkmcnt(0)
	v_mfma_f32_16x16x32_bf16 v[60:63], v[144:147], v[184:187], 0
	v_mfma_f32_16x16x32_bf16 v[40:43], v[160:163], v[192:195], 0
	v_mfma_f32_16x16x32_bf16 v[28:31], v[144:147], v[200:203], 0
	v_mfma_f32_16x16x32_bf16 v[8:11], v[160:163], v[210:213], 0
	v_mfma_f32_16x16x32_bf16 v[44:47], v[144:147], v[192:195], 0
	v_mfma_f32_16x16x32_bf16 v[56:59], v[160:163], v[184:187], 0
	v_mfma_f32_16x16x32_bf16 v[12:15], v[144:147], v[210:213], 0
	v_mfma_f32_16x16x32_bf16 v[24:27], v[160:163], v[200:203], 0
	v_mfma_f32_16x16x32_bf16 v[60:63], v[156:159], v[188:191], v[60:63]
	v_mfma_f32_16x16x32_bf16 v[40:43], v[164:167], v[196:199], v[40:43]
	v_mfma_f32_16x16x32_bf16 v[28:31], v[156:159], v[206:209], v[28:31]
	v_mfma_f32_16x16x32_bf16 v[8:11], v[164:167], v[214:217], v[8:11]
	v_mfma_f32_16x16x32_bf16 v[44:47], v[156:159], v[196:199], v[44:47]
	v_mfma_f32_16x16x32_bf16 v[56:59], v[164:167], v[188:191], v[56:59]
	v_lshl_add_u64 v[222:223], s[48:49], 0, v[128:129]
	s_mov_b32 m0, s33
	s_nop 0
	global_load_lds_dwordx4 v[222:223], off
	v_mfma_f32_16x16x32_bf16 v[12:15], v[156:159], v[214:217], v[12:15]
	v_mfma_f32_16x16x32_bf16 v[24:27], v[164:167], v[206:209], v[24:27]
	s_setprio 0
	s_setprio 1
	v_mfma_f32_16x16x32_bf16 v[52:55], v[168:171], v[184:187], 0
	v_mfma_f32_16x16x32_bf16 v[32:35], v[176:179], v[192:195], 0
	v_mfma_f32_16x16x32_bf16 v[20:23], v[168:171], v[200:203], 0
	v_mfma_f32_16x16x32_bf16 v[0:3], v[176:179], v[210:213], 0
	v_mfma_f32_16x16x32_bf16 v[36:39], v[168:171], v[192:195], 0
	v_mfma_f32_16x16x32_bf16 v[48:51], v[176:179], v[184:187], 0
	v_mfma_f32_16x16x32_bf16 v[4:7], v[168:171], v[210:213], 0
	v_mfma_f32_16x16x32_bf16 v[16:19], v[176:179], v[200:203], 0
	v_mfma_f32_16x16x32_bf16 v[52:55], v[172:175], v[188:191], v[52:55]
	v_mfma_f32_16x16x32_bf16 v[32:35], v[180:183], v[196:199], v[32:35]
	v_mfma_f32_16x16x32_bf16 v[20:23], v[172:175], v[206:209], v[20:23]
	v_mfma_f32_16x16x32_bf16 v[0:3], v[180:183], v[214:217], v[0:3]
	v_mfma_f32_16x16x32_bf16 v[36:39], v[172:175], v[196:199], v[36:39]
	v_mfma_f32_16x16x32_bf16 v[48:51], v[180:183], v[188:191], v[48:51]
	v_lshl_add_u64 v[224:225], s[48:49], 0, v[132:133]
	s_mov_b32 m0, s34
	s_nop 0
	global_load_lds_dwordx4 v[224:225], off
	v_mfma_f32_16x16x32_bf16 v[4:7], v[172:175], v[214:217], v[4:7]
	v_mfma_f32_16x16x32_bf16 v[16:19], v[180:183], v[206:209], v[16:19]
	s_setprio 0
	s_barrier
	s_add_i32 s62, 0, 0x18000
	v_add_u32_e32 v155, s62, v149
	s_add_i32 s63, 0, 0x1c000
	ds_read_b128 v[144:147], v155
	ds_read_b128 v[156:159], v155 offset:1024
	ds_read_b128 v[160:163], v155 offset:2048
	ds_read_b128 v[164:167], v155 offset:3072
	v_add_u32_e32 v155, s63, v149
	ds_read_b128 v[168:171], v155
	ds_read_b128 v[172:175], v155 offset:1024
	ds_read_b128 v[176:179], v155 offset:2048
	ds_read_b128 v[180:183], v155 offset:3072
	s_add_u32 s48, s48, 0x20000
	s_addc_u32 s49, s49, 0
	s_mov_b32 m0, s43
	v_lshl_add_u64 v[226:227], s[48:49], 0, v[128:129]
	ds_read_b128 v[184:187], v153 offset:32768
	ds_read_b128 v[188:191], v153 offset:33792
	ds_read_b128 v[192:195], v153 offset:34816
	ds_read_b128 v[196:199], v153 offset:35840
	ds_read_b128 v[200:203], v153 offset:36864
	ds_read_b128 v[206:209], v153 offset:37888
	ds_read_b128 v[210:213], v153 offset:38912
	ds_read_b128 v[214:217], v153 offset:39936
	global_load_lds_dwordx4 v[226:227], off
	v_lshl_add_u64 v[226:227], s[48:49], 0, v[132:133]
	s_mov_b32 m0, s50
	s_nop 0
	global_load_lds_dwordx4 v[226:227], off
	s_waitcnt vmcnt(8)
	s_waitcnt lgkmcnt(0)
	s_barrier
	s_setprio 1
	s_waitcnt lgkmcnt(0)
	v_mfma_f32_16x16x32_bf16 v[124:127], v[144:147], v[184:187], v[124:127]
	v_mfma_f32_16x16x32_bf16 v[104:107], v[160:163], v[192:195], v[104:107]
	v_mfma_f32_16x16x32_bf16 v[92:95], v[144:147], v[200:203], v[92:95]
	v_mfma_f32_16x16x32_bf16 v[72:75], v[160:163], v[210:213], v[72:75]
	v_mfma_f32_16x16x32_bf16 v[108:111], v[144:147], v[192:195], v[108:111]
	v_mfma_f32_16x16x32_bf16 v[120:123], v[160:163], v[184:187], v[120:123]
	v_mfma_f32_16x16x32_bf16 v[76:79], v[144:147], v[210:213], v[76:79]
	v_mfma_f32_16x16x32_bf16 v[88:91], v[160:163], v[200:203], v[88:91]
	v_mfma_f32_16x16x32_bf16 v[124:127], v[156:159], v[188:191], v[124:127]
	v_mfma_f32_16x16x32_bf16 v[104:107], v[164:167], v[196:199], v[104:107]
	v_mfma_f32_16x16x32_bf16 v[92:95], v[156:159], v[206:209], v[92:95]
	v_mfma_f32_16x16x32_bf16 v[72:75], v[164:167], v[214:217], v[72:75]
	v_mfma_f32_16x16x32_bf16 v[108:111], v[156:159], v[196:199], v[108:111]
	v_mfma_f32_16x16x32_bf16 v[120:123], v[164:167], v[188:191], v[120:123]
	v_mfma_f32_16x16x32_bf16 v[76:79], v[156:159], v[214:217], v[76:79]
	v_mfma_f32_16x16x32_bf16 v[88:91], v[164:167], v[206:209], v[88:91]
	s_setprio 0
	s_setprio 1
	v_mfma_f32_16x16x32_bf16 v[116:119], v[168:171], v[184:187], v[116:119]
	v_mfma_f32_16x16x32_bf16 v[96:99], v[176:179], v[192:195], v[96:99]
	v_mfma_f32_16x16x32_bf16 v[84:87], v[168:171], v[200:203], v[84:87]
	v_mfma_f32_16x16x32_bf16 v[64:67], v[176:179], v[210:213], v[64:67]
	v_mfma_f32_16x16x32_bf16 v[100:103], v[168:171], v[192:195], v[100:103]
	v_mfma_f32_16x16x32_bf16 v[112:115], v[176:179], v[184:187], v[112:115]
	v_mfma_f32_16x16x32_bf16 v[68:71], v[168:171], v[210:213], v[68:71]
	v_mfma_f32_16x16x32_bf16 v[80:83], v[176:179], v[200:203], v[80:83]
	v_mfma_f32_16x16x32_bf16 v[116:119], v[172:175], v[188:191], v[116:119]
	v_mfma_f32_16x16x32_bf16 v[96:99], v[180:183], v[196:199], v[96:99]
	v_mfma_f32_16x16x32_bf16 v[84:87], v[172:175], v[206:209], v[84:87]
	v_mfma_f32_16x16x32_bf16 v[64:67], v[180:183], v[214:217], v[64:67]
	v_mfma_f32_16x16x32_bf16 v[100:103], v[172:175], v[196:199], v[100:103]
	v_mfma_f32_16x16x32_bf16 v[112:115], v[180:183], v[188:191], v[112:115]
	v_mfma_f32_16x16x32_bf16 v[68:71], v[172:175], v[214:217], v[68:71]
	v_mfma_f32_16x16x32_bf16 v[80:83], v[180:183], v[206:209], v[80:83]
	s_setprio 0
	s_barrier
; #define PG8_STAGE(bufoff, gbase, voff) do { _Pragma("unroll") for (int _i = 0; _i < 2; ++_i) \
;         __builtin_amdgcn_global_load_lds((const unsigned*)((const char*)(gbase) + (voff)[_i]), (PG8_LAS unsigned*)(lds + (bufoff) + ldsw + _i * 8192), 16, 0, 0); } while (0)
; #define PG8_LDA(dst, b, h) do { _Pragma("unroll") for (int m = 0; m < 4; ++m) _Pragma("unroll") for (int k = 0; k < 2; ++k) dst[m][k] = *(const PG8_LAS bf16x8*)(lds + PG8_SA(b, h) + aoff + m * 2048 + k * 1024); } while (0)
; #define PG8_LDB(dst, b, h) do { _Pragma("unroll") for (int n = 0; n < 2; ++n) _Pragma("unroll") for (int k = 0; k < 2; ++k) dst[n][k] = *(const PG8_LAS bf16x8*)(lds + PG8_SB(b, h) + boff + n * 2048 + k * 1024); } while (0)
; #define PG8_MMA(ai, bj, At, Bt) do { __builtin_amdgcn_s_setprio(1); _Pragma("unroll") for (int m = 0; m < 4; ++m) _Pragma("unroll") for (int n = 0; n < 2; ++n) _Pragma("unroll") for (int k = 0; k < 2; ++k) \
;         acc[ai][bj][m][n] = __builtin_amdgcn_mfma_f32_16x16x32_bf16(Bt[n][k], At[m][k], acc[ai][bj][m][n], 0, 0, 0); __builtin_amdgcn_s_setprio(0); } while (0)
; #define PG8_WAIT_V(n) asm volatile("s_waitcnt vmcnt(" #n ")" ::: "memory")
; #define PG8_WAIT_L(n) asm volatile("s_waitcnt lgkmcnt(" #n ")" ::: "memory")
; #define PG8_BAR __builtin_amdgcn_s_barrier()
; #define PG8_SCHED __builtin_amdgcn_sched_barrier(0)
; template <class Epi, class Sched, bool ALIGN_EPI = false, bool SP2 = false>
; __device__ __forceinline__ void gemm_phase(PG8_LAS unsigned char* lds, const Gemm g, const Sched& S, const Epi& E) {
;     ...
;         for (int t = 0; t < nt; t += 2) {
;             const bool last = (t == nt - 2);
;             const char* a1 = cA + (size_t)(t + 1) * kstep;
;             const char* a2 = last ? nA : cA + (size_t)(t + 2) * kstep; const char* b2 = last ? nB : cB + (size_t)(t + 2) * kstep;
;             const char* a3 = a2 + kstep; const char* b3 = b2 + kstep;
;             if (last && has_next) S.a_ready(nxt);
;             if constexpr (SP2) {
;             PG8_LDB(B0, 0, 0); PG8_LDB(B1, 0, 1); PG8_SCHED; PG8_LDA(At, 0, 0); PG8_STAGE(PG8_SA(1, 1), a1 + hstep, voffA);
;     ...
;             PG8_LDA(At, 1, 1); PG8_STAGE(PG8_SB(1, 0), b3, voffB); PG8_STAGE(PG8_SB(1, 1), b3 + hstep, voffB); PG8_STAGE(PG8_SA(1, 0), a3, voffA);
;             PG8_WAIT_V(8); PG8_WAIT_L(0); PG8_BAR; PG8_MMA(1, 0, At, B0); PG8_MMA(1, 1, At, B1); PG8_BAR; PG8_SCHED;
	s_add_i32 s48, s62, s15
	v_lshl_add_u64 v[218:219], v[218:219], 0, s[12:13]
	s_mov_b32 m0, s48
	ds_read_b128 v[184:187], v153 offset:49152
	ds_read_b128 v[188:191], v153 offset:50176
	ds_read_b128 v[192:195], v153 offset:51200
	ds_read_b128 v[196:199], v153 offset:52224
	ds_read_b128 v[200:203], v153 offset:53248
	ds_read_b128 v[206:209], v153 offset:54272
	ds_read_b128 v[210:213], v153 offset:55296
	ds_read_b128 v[214:217], v153 offset:56320
	global_load_lds_dwordx4 v[218:219], off
	s_add_i32 m0, s48, 0x2000
	s_add_u32 s46, s46, 0x20080
	v_lshl_add_u64 v[218:219], v[220:221], 0, s[12:13]
	s_addc_u32 s47, s47, 0
	s_add_i32 s48, s63, s15
	global_load_lds_dwordx4 v[218:219], off
	v_lshl_add_u64 v[218:219], s[46:47], 0, v[130:131]
	s_mov_b32 m0, s48
	s_nop 0
	global_load_lds_dwordx4 v[218:219], off
	v_lshl_add_u64 v[218:219], s[46:47], 0, v[134:135]
	s_add_i32 m0, s48, 0x2000
	s_nop 0
	global_load_lds_dwordx4 v[218:219], off
	s_waitcnt vmcnt(6)
	s_waitcnt lgkmcnt(0)
	s_barrier
	s_setprio 1
	s_waitcnt lgkmcnt(0)
	v_mfma_f32_16x16x32_bf16 v[60:63], v[144:147], v[184:187], v[60:63]
	v_mfma_f32_16x16x32_bf16 v[40:43], v[160:163], v[192:195], v[40:43]
	v_mfma_f32_16x16x32_bf16 v[28:31], v[144:147], v[200:203], v[28:31]
	v_mfma_f32_16x16x32_bf16 v[8:11], v[160:163], v[210:213], v[8:11]
	v_mfma_f32_16x16x32_bf16 v[44:47], v[144:147], v[192:195], v[44:47]
	v_mfma_f32_16x16x32_bf16 v[56:59], v[160:163], v[184:187], v[56:59]
	v_mfma_f32_16x16x32_bf16 v[12:15], v[144:147], v[210:213], v[12:15]
	v_mfma_f32_16x16x32_bf16 v[24:27], v[160:163], v[200:203], v[24:27]
	v_mfma_f32_16x16x32_bf16 v[60:63], v[156:159], v[188:191], v[60:63]
	v_mfma_f32_16x16x32_bf16 v[40:43], v[164:167], v[196:199], v[40:43]
	v_mfma_f32_16x16x32_bf16 v[28:31], v[156:159], v[206:209], v[28:31]
	v_mfma_f32_16x16x32_bf16 v[8:11], v[164:167], v[214:217], v[8:11]
	v_mfma_f32_16x16x32_bf16 v[44:47], v[156:159], v[196:199], v[44:47]
	v_mfma_f32_16x16x32_bf16 v[56:59], v[164:167], v[188:191], v[56:59]
	v_lshl_add_u64 v[218:219], v[222:223], 0, s[12:13]
	s_mov_b32 m0, s52
	s_nop 0
	global_load_lds_dwordx4 v[218:219], off
	v_mfma_f32_16x16x32_bf16 v[12:15], v[156:159], v[214:217], v[12:15]
	v_mfma_f32_16x16x32_bf16 v[24:27], v[164:167], v[206:209], v[24:27]
	s_setprio 0
	s_setprio 1
	v_mfma_f32_16x16x32_bf16 v[52:55], v[168:171], v[184:187], v[52:55]
	v_mfma_f32_16x16x32_bf16 v[32:35], v[176:179], v[192:195], v[32:35]
	v_mfma_f32_16x16x32_bf16 v[20:23], v[168:171], v[200:203], v[20:23]
	v_mfma_f32_16x16x32_bf16 v[0:3], v[176:179], v[210:213], v[0:3]
	v_mfma_f32_16x16x32_bf16 v[36:39], v[168:171], v[192:195], v[36:39]
	v_mfma_f32_16x16x32_bf16 v[48:51], v[176:179], v[184:187], v[48:51]
	v_mfma_f32_16x16x32_bf16 v[4:7], v[168:171], v[210:213], v[4:7]
	v_mfma_f32_16x16x32_bf16 v[16:19], v[176:179], v[200:203], v[16:19]
	v_mfma_f32_16x16x32_bf16 v[52:55], v[172:175], v[188:191], v[52:55]
	v_mfma_f32_16x16x32_bf16 v[32:35], v[180:183], v[196:199], v[32:35]
	v_mfma_f32_16x16x32_bf16 v[20:23], v[172:175], v[206:209], v[20:23]
	v_mfma_f32_16x16x32_bf16 v[0:3], v[180:183], v[214:217], v[0:3]
	v_mfma_f32_16x16x32_bf16 v[36:39], v[172:175], v[196:199], v[36:39]
	v_mfma_f32_16x16x32_bf16 v[48:51], v[180:183], v[188:191], v[48:51]
	v_lshl_add_u64 v[218:219], v[224:225], 0, s[12:13]
	s_mov_b32 m0, s53
	s_nop 0
	global_load_lds_dwordx4 v[218:219], off
	v_mfma_f32_16x16x32_bf16 v[4:7], v[172:175], v[214:217], v[4:7]
	v_mfma_f32_16x16x32_bf16 v[16:19], v[180:183], v[206:209], v[16:19]
	s_setprio 0
	s_barrier
	s_add_i32 s61, s61, 2
	s_add_u32 s44, s44, 0x100
	s_addc_u32 s45, s45, 0
	s_add_u32 s59, s59, 0x100
	s_addc_u32 s60, s60, 0
.LBB0_1816:
	ds_read_b128 v[144:147], v151
	ds_read_b128 v[156:159], v151 offset:1024
	ds_read_b128 v[160:163], v151 offset:2048
	ds_read_b128 v[164:167], v151 offset:3072
	ds_read_b128 v[168:171], v152
	ds_read_b128 v[172:175], v152 offset:1024
	ds_read_b128 v[176:179], v152 offset:2048
	ds_read_b128 v[180:183], v152 offset:3072
	s_add_u32 s46, s44, 0xfffe0080
	s_addc_u32 s47, s45, -1
	s_cmp_eq_u32 s61, 4
	s_cselect_b32 s49, s29, s47
	s_cselect_b32 s48, s41, s46
	s_cselect_b32 s47, s27, s60
	s_cselect_b32 s46, s58, s59
	v_lshl_add_u64 v[218:219], s[44:45], 0, v[136:137]
	s_add_i32 m0, s33, 0xc000
	ds_read_b128 v[184:187], v153
	ds_read_b128 v[188:191], v153 offset:1024
	ds_read_b128 v[192:195], v153 offset:2048
	ds_read_b128 v[196:199], v153 offset:3072
	ds_read_b128 v[200:203], v153 offset:4096
	ds_read_b128 v[206:209], v153 offset:5120
	ds_read_b128 v[210:213], v153 offset:6144
	ds_read_b128 v[214:217], v153 offset:7168
	global_load_lds_dwordx4 v[218:219], off
	v_lshl_add_u64 v[218:219], s[44:45], 0, v[138:139]
	s_add_i32 m0, s33, 0xe000
	s_nop 0
	global_load_lds_dwordx4 v[218:219], off
	s_waitcnt vmcnt(8)
	s_waitcnt lgkmcnt(0)
	s_barrier
; #define PG8_STAGE(bufoff, gbase, voff) do { _Pragma("unroll") for (int _i = 0; _i < 2; ++_i) \
;         __builtin_amdgcn_global_load_lds((const unsigned*)((const char*)(gbase) + (voff)[_i]), (PG8_LAS unsigned*)(lds + (bufoff) + ldsw + _i * 8192), 16, 0, 0); } while (0)
; #define PG8_LDA(dst, b, h) do { _Pragma("unroll") for (int m = 0; m < 4; ++m) _Pragma("unroll") for (int k = 0; k < 2; ++k) dst[m][k] = *(const PG8_LAS bf16x8*)(lds + PG8_SA(b, h) + aoff + m * 2048 + k * 1024); } while (0)
; #define PG8_MMA(ai, bj, At, Bt) do { __builtin_amdgcn_s_setprio(1); _Pragma("unroll") for (int m = 0; m < 4; ++m) _Pragma("unroll") for (int n = 0; n < 2; ++n) _Pragma("unroll") for (int k = 0; k < 2; ++k) \
;         acc[ai][bj][m][n] = __builtin_amdgcn_mfma_f32_16x16x32_bf16(Bt[n][k], At[m][k], acc[ai][bj][m][n], 0, 0, 0); __builtin_amdgcn_s_setprio(0); } while (0)
; #define PG8_WAIT_V(n) asm volatile("s_waitcnt vmcnt(" #n ")" ::: "memory")
; #define PG8_WAIT_L(n) asm volatile("s_waitcnt lgkmcnt(" #n ")" ::: "memory")
; #define PG8_BAR __builtin_amdgcn_s_barrier()
; #define PG8_SCHED __builtin_amdgcn_sched_barrier(0)
; template <class Epi, class Sched, bool ALIGN_EPI = false, bool SP2 = false>
; __device__ __forceinline__ void gemm_phase(PG8_LAS unsigned char* lds, const Gemm g, const Sched& S, const Epi& E) {
;     ...
;             PG8_WAIT_V(8); PG8_WAIT_L(0); PG8_BAR; PG8_MMA(0, 0, At, B0); PG8_MMA(0, 1, At, B1); PG8_BAR; PG8_SCHED;
;             PG8_LDA(At, 0, 1); PG8_STAGE(PG8_SB(0, 0), b2, voffB); PG8_STAGE(PG8_SB(0, 1), b2 + hstep, voffB); PG8_STAGE(PG8_SA(0, 0), a2, voffA);
;             PG8_WAIT_V(8); PG8_WAIT_L(0); PG8_BAR; PG8_MMA(1, 0, At, B0); PG8_MMA(1, 1, At, B1); PG8_BAR; PG8_SCHED;
	s_setprio 1
	s_waitcnt lgkmcnt(0)
	v_mfma_f32_16x16x32_bf16 v[124:127], v[144:147], v[184:187], v[124:127]
	v_mfma_f32_16x16x32_bf16 v[104:107], v[160:163], v[192:195], v[104:107]
	v_mfma_f32_16x16x32_bf16 v[92:95], v[144:147], v[200:203], v[92:95]
	v_mfma_f32_16x16x32_bf16 v[72:75], v[160:163], v[210:213], v[72:75]
	v_mfma_f32_16x16x32_bf16 v[108:111], v[144:147], v[192:195], v[108:111]
	v_mfma_f32_16x16x32_bf16 v[120:123], v[160:163], v[184:187], v[120:123]
	v_mfma_f32_16x16x32_bf16 v[76:79], v[144:147], v[210:213], v[76:79]
	v_mfma_f32_16x16x32_bf16 v[88:91], v[160:163], v[200:203], v[88:91]
	v_mfma_f32_16x16x32_bf16 v[124:127], v[156:159], v[188:191], v[124:127]
	v_mfma_f32_16x16x32_bf16 v[104:107], v[164:167], v[196:199], v[104:107]
	v_mfma_f32_16x16x32_bf16 v[92:95], v[156:159], v[206:209], v[92:95]
	v_mfma_f32_16x16x32_bf16 v[72:75], v[164:167], v[214:217], v[72:75]
	v_mfma_f32_16x16x32_bf16 v[108:111], v[156:159], v[196:199], v[108:111]
	v_mfma_f32_16x16x32_bf16 v[120:123], v[164:167], v[188:191], v[120:123]
	v_mfma_f32_16x16x32_bf16 v[76:79], v[156:159], v[214:217], v[76:79]
	v_mfma_f32_16x16x32_bf16 v[88:91], v[164:167], v[206:209], v[88:91]
	s_setprio 0
	s_setprio 1
	v_mfma_f32_16x16x32_bf16 v[116:119], v[168:171], v[184:187], v[116:119]
	v_mfma_f32_16x16x32_bf16 v[96:99], v[176:179], v[192:195], v[96:99]
	v_mfma_f32_16x16x32_bf16 v[84:87], v[168:171], v[200:203], v[84:87]
	v_mfma_f32_16x16x32_bf16 v[64:67], v[176:179], v[210:213], v[64:67]
	v_mfma_f32_16x16x32_bf16 v[100:103], v[168:171], v[192:195], v[100:103]
	v_mfma_f32_16x16x32_bf16 v[112:115], v[176:179], v[184:187], v[112:115]
	v_mfma_f32_16x16x32_bf16 v[68:71], v[168:171], v[210:213], v[68:71]
	v_mfma_f32_16x16x32_bf16 v[80:83], v[176:179], v[200:203], v[80:83]
	v_mfma_f32_16x16x32_bf16 v[116:119], v[172:175], v[188:191], v[116:119]
	v_mfma_f32_16x16x32_bf16 v[96:99], v[180:183], v[196:199], v[96:99]
	v_mfma_f32_16x16x32_bf16 v[84:87], v[172:175], v[206:209], v[84:87]
	v_mfma_f32_16x16x32_bf16 v[64:67], v[180:183], v[214:217], v[64:67]
	v_mfma_f32_16x16x32_bf16 v[100:103], v[172:175], v[196:199], v[100:103]
	v_mfma_f32_16x16x32_bf16 v[112:115], v[180:183], v[188:191], v[112:115]
	v_mfma_f32_16x16x32_bf16 v[68:71], v[172:175], v[214:217], v[68:71]
	v_mfma_f32_16x16x32_bf16 v[80:83], v[180:183], v[206:209], v[80:83]
	s_setprio 0
	s_barrier
	s_add_i32 s62, s54, s15
	v_lshl_add_u64 v[218:219], s[46:47], 0, v[130:131]
	s_mov_b32 m0, s62
	ds_read_b128 v[184:187], v153 offset:16384
	ds_read_b128 v[188:191], v153 offset:17408
	ds_read_b128 v[192:195], v153 offset:18432
	ds_read_b128 v[196:199], v153 offset:19456
	ds_read_b128 v[200:203], v153 offset:20480
	ds_read_b128 v[206:209], v153 offset:21504
	ds_read_b128 v[210:213], v153 offset:22528
	ds_read_b128 v[214:217], v153 offset:23552
	global_load_lds_dwordx4 v[218:219], off
	s_add_i32 m0, s62, 0x2000
	s_add_u32 s62, s46, 0x20000
	v_lshl_add_u64 v[220:221], s[46:47], 0, v[134:135]
	s_addc_u32 s63, s47, 0
	s_add_i32 s64, s55, s15
	global_load_lds_dwordx4 v[220:221], off
	v_lshl_add_u64 v[222:223], s[62:63], 0, v[130:131]
	s_mov_b32 m0, s64
	global_load_lds_dwordx4 v[222:223], off
	v_lshl_add_u64 v[222:223], s[62:63], 0, v[134:135]
	s_add_i32 m0, s64, 0x2000
	s_nop 0
	global_load_lds_dwordx4 v[222:223], off
	s_waitcnt vmcnt(6)
	s_waitcnt lgkmcnt(0)
	s_barrier
	s_setprio 1
	s_waitcnt lgkmcnt(0)
	v_mfma_f32_16x16x32_bf16 v[60:63], v[144:147], v[184:187], v[60:63]
	v_mfma_f32_16x16x32_bf16 v[40:43], v[160:163], v[192:195], v[40:43]
	v_mfma_f32_16x16x32_bf16 v[28:31], v[144:147], v[200:203], v[28:31]
	v_mfma_f32_16x16x32_bf16 v[8:11], v[160:163], v[210:213], v[8:11]
	v_mfma_f32_16x16x32_bf16 v[44:47], v[144:147], v[192:195], v[44:47]
	v_mfma_f32_16x16x32_bf16 v[56:59], v[160:163], v[184:187], v[56:59]
	v_mfma_f32_16x16x32_bf16 v[12:15], v[144:147], v[210:213], v[12:15]
	v_mfma_f32_16x16x32_bf16 v[24:27], v[160:163], v[200:203], v[24:27]
	v_mfma_f32_16x16x32_bf16 v[60:63], v[156:159], v[188:191], v[60:63]
	v_mfma_f32_16x16x32_bf16 v[40:43], v[164:167], v[196:199], v[40:43]
	v_mfma_f32_16x16x32_bf16 v[28:31], v[156:159], v[206:209], v[28:31]
	v_mfma_f32_16x16x32_bf16 v[8:11], v[164:167], v[214:217], v[8:11]
	v_mfma_f32_16x16x32_bf16 v[44:47], v[156:159], v[196:199], v[44:47]
	v_mfma_f32_16x16x32_bf16 v[56:59], v[164:167], v[188:191], v[56:59]
	v_lshl_add_u64 v[222:223], s[48:49], 0, v[128:129]
	s_mov_b32 m0, s33
	s_nop 0
	global_load_lds_dwordx4 v[222:223], off
	v_mfma_f32_16x16x32_bf16 v[12:15], v[156:159], v[214:217], v[12:15]
	v_mfma_f32_16x16x32_bf16 v[24:27], v[164:167], v[206:209], v[24:27]
	s_setprio 0
	s_setprio 1
	v_mfma_f32_16x16x32_bf16 v[52:55], v[168:171], v[184:187], v[52:55]
	v_mfma_f32_16x16x32_bf16 v[32:35], v[176:179], v[192:195], v[32:35]
	v_mfma_f32_16x16x32_bf16 v[20:23], v[168:171], v[200:203], v[20:23]
	v_mfma_f32_16x16x32_bf16 v[0:3], v[176:179], v[210:213], v[0:3]
	v_mfma_f32_16x16x32_bf16 v[36:39], v[168:171], v[192:195], v[36:39]
	v_mfma_f32_16x16x32_bf16 v[48:51], v[176:179], v[184:187], v[48:51]
	v_mfma_f32_16x16x32_bf16 v[4:7], v[168:171], v[210:213], v[4:7]
	v_mfma_f32_16x16x32_bf16 v[16:19], v[176:179], v[200:203], v[16:19]
	v_mfma_f32_16x16x32_bf16 v[52:55], v[172:175], v[188:191], v[52:55]
	v_mfma_f32_16x16x32_bf16 v[32:35], v[180:183], v[196:199], v[32:35]
	v_mfma_f32_16x16x32_bf16 v[20:23], v[172:175], v[206:209], v[20:23]
	v_mfma_f32_16x16x32_bf16 v[0:3], v[180:183], v[214:217], v[0:3]
	v_mfma_f32_16x16x32_bf16 v[36:39], v[172:175], v[196:199], v[36:39]
	v_mfma_f32_16x16x32_bf16 v[48:51], v[180:183], v[188:191], v[48:51]
	v_lshl_add_u64 v[224:225], s[48:49], 0, v[132:133]
	s_mov_b32 m0, s34
	s_nop 0
	global_load_lds_dwordx4 v[224:225], off
	v_mfma_f32_16x16x32_bf16 v[4:7], v[172:175], v[214:217], v[4:7]
	v_mfma_f32_16x16x32_bf16 v[16:19], v[180:183], v[206:209], v[16:19]
	s_setprio 0
	s_barrier
; #define PG8_STAGE(bufoff, gbase, voff) do { _Pragma("unroll") for (int _i = 0; _i < 2; ++_i) \
;         __builtin_amdgcn_global_load_lds((const unsigned*)((const char*)(gbase) + (voff)[_i]), (PG8_LAS unsigned*)(lds + (bufoff) + ldsw + _i * 8192), 16, 0, 0); } while (0)
; #define PG8_LDA(dst, b, h) do { _Pragma("unroll") for (int m = 0; m < 4; ++m) _Pragma("unroll") for (int k = 0; k < 2; ++k) dst[m][k] = *(const PG8_LAS bf16x8*)(lds + PG8_SA(b, h) + aoff + m * 2048 + k * 1024); } while (0)
; #define PG8_LDB(dst, b, h) do { _Pragma("unroll") for (int n = 0; n < 2; ++n) _Pragma("unroll") for (int k = 0; k < 2; ++k) dst[n][k] = *(const PG8_LAS bf16x8*)(lds + PG8_SB(b, h) + boff + n * 2048 + k * 1024); } while (0)
; #define PG8_MMA(ai, bj, At, Bt) do { __builtin_amdgcn_s_setprio(1); _Pragma("unroll") for (int m = 0; m < 4; ++m) _Pragma("unroll") for (int n = 0; n < 2; ++n) _Pragma("unroll") for (int k = 0; k < 2; ++k) \
;         acc[ai][bj][m][n] = __builtin_amdgcn_mfma_f32_16x16x32_bf16(Bt[n][k], At[m][k], acc[ai][bj][m][n], 0, 0, 0); __builtin_amdgcn_s_setprio(0); } while (0)
; #define PG8_WAIT_V(n) asm volatile("s_waitcnt vmcnt(" #n ")" ::: "memory")
; #define PG8_WAIT_L(n) asm volatile("s_waitcnt lgkmcnt(" #n ")" ::: "memory")
; #define PG8_BAR __builtin_amdgcn_s_barrier()
; #define PG8_SCHED __builtin_amdgcn_sched_barrier(0)
; template <class Epi, class Sched, bool ALIGN_EPI = false, bool SP2 = false>
; __device__ __forceinline__ void gemm_phase(PG8_LAS unsigned char* lds, const Gemm g, const Sched& S, const Epi& E) {
;     ...
;             PG8_LDB(B0, 1, 0); PG8_LDB(B1, 1, 1); PG8_SCHED; PG8_LDA(At, 1, 0); PG8_STAGE(PG8_SA(0, 1), a2 + hstep, voffA);
;             PG8_WAIT_V(8); PG8_WAIT_L(0); PG8_BAR; PG8_MMA(0, 0, At, B0); PG8_MMA(0, 1, At, B1); PG8_BAR; PG8_SCHED;
	s_add_i32 s62, 0, 0x18000
	v_add_u32_e32 v155, s62, v149
	s_add_i32 s63, 0, 0x1c000
	ds_read_b128 v[144:147], v155
	ds_read_b128 v[156:159], v155 offset:1024
	ds_read_b128 v[160:163], v155 offset:2048
	ds_read_b128 v[164:167], v155 offset:3072
	v_add_u32_e32 v155, s63, v149
	ds_read_b128 v[168:171], v155
	ds_read_b128 v[172:175], v155 offset:1024
	ds_read_b128 v[176:179], v155 offset:2048
	ds_read_b128 v[180:183], v155 offset:3072
	s_add_u32 s48, s48, 0x20000
	s_addc_u32 s49, s49, 0
	s_mov_b32 m0, s43
	v_lshl_add_u64 v[226:227], s[48:49], 0, v[128:129]
	ds_read_b128 v[184:187], v153 offset:32768
	ds_read_b128 v[188:191], v153 offset:33792
	ds_read_b128 v[192:195], v153 offset:34816
	ds_read_b128 v[196:199], v153 offset:35840
	ds_read_b128 v[200:203], v153 offset:36864
	ds_read_b128 v[206:209], v153 offset:37888
	ds_read_b128 v[210:213], v153 offset:38912
	ds_read_b128 v[214:217], v153 offset:39936
	global_load_lds_dwordx4 v[226:227], off
	v_lshl_add_u64 v[226:227], s[48:49], 0, v[132:133]
	s_mov_b32 m0, s50
	s_nop 0
	global_load_lds_dwordx4 v[226:227], off
	s_waitcnt vmcnt(8)
	s_waitcnt lgkmcnt(0)
	s_barrier
	s_setprio 1
	s_waitcnt lgkmcnt(0)
	v_mfma_f32_16x16x32_bf16 v[124:127], v[144:147], v[184:187], v[124:127]
	v_mfma_f32_16x16x32_bf16 v[104:107], v[160:163], v[192:195], v[104:107]
	v_mfma_f32_16x16x32_bf16 v[92:95], v[144:147], v[200:203], v[92:95]
	v_mfma_f32_16x16x32_bf16 v[72:75], v[160:163], v[210:213], v[72:75]
	v_mfma_f32_16x16x32_bf16 v[108:111], v[144:147], v[192:195], v[108:111]
	v_mfma_f32_16x16x32_bf16 v[120:123], v[160:163], v[184:187], v[120:123]
	v_mfma_f32_16x16x32_bf16 v[76:79], v[144:147], v[210:213], v[76:79]
	v_mfma_f32_16x16x32_bf16 v[88:91], v[160:163], v[200:203], v[88:91]
	v_mfma_f32_16x16x32_bf16 v[124:127], v[156:159], v[188:191], v[124:127]
	v_mfma_f32_16x16x32_bf16 v[104:107], v[164:167], v[196:199], v[104:107]
	v_mfma_f32_16x16x32_bf16 v[92:95], v[156:159], v[206:209], v[92:95]
	v_mfma_f32_16x16x32_bf16 v[72:75], v[164:167], v[214:217], v[72:75]
	v_mfma_f32_16x16x32_bf16 v[108:111], v[156:159], v[196:199], v[108:111]
	v_mfma_f32_16x16x32_bf16 v[120:123], v[164:167], v[188:191], v[120:123]
	v_mfma_f32_16x16x32_bf16 v[76:79], v[156:159], v[214:217], v[76:79]
	v_mfma_f32_16x16x32_bf16 v[88:91], v[164:167], v[206:209], v[88:91]
	s_setprio 0
	s_setprio 1
	v_mfma_f32_16x16x32_bf16 v[116:119], v[168:171], v[184:187], v[116:119]
	v_mfma_f32_16x16x32_bf16 v[96:99], v[176:179], v[192:195], v[96:99]
	v_mfma_f32_16x16x32_bf16 v[84:87], v[168:171], v[200:203], v[84:87]
	v_mfma_f32_16x16x32_bf16 v[64:67], v[176:179], v[210:213], v[64:67]
	v_mfma_f32_16x16x32_bf16 v[100:103], v[168:171], v[192:195], v[100:103]
	v_mfma_f32_16x16x32_bf16 v[112:115], v[176:179], v[184:187], v[112:115]
	v_mfma_f32_16x16x32_bf16 v[68:71], v[168:171], v[210:213], v[68:71]
	v_mfma_f32_16x16x32_bf16 v[80:83], v[176:179], v[200:203], v[80:83]
	v_mfma_f32_16x16x32_bf16 v[116:119], v[172:175], v[188:191], v[116:119]
	v_mfma_f32_16x16x32_bf16 v[96:99], v[180:183], v[196:199], v[96:99]
	v_mfma_f32_16x16x32_bf16 v[84:87], v[172:175], v[206:209], v[84:87]
	v_mfma_f32_16x16x32_bf16 v[64:67], v[180:183], v[214:217], v[64:67]
	v_mfma_f32_16x16x32_bf16 v[100:103], v[172:175], v[196:199], v[100:103]
	v_mfma_f32_16x16x32_bf16 v[112:115], v[180:183], v[188:191], v[112:115]
	v_mfma_f32_16x16x32_bf16 v[68:71], v[172:175], v[214:217], v[68:71]
	v_mfma_f32_16x16x32_bf16 v[80:83], v[180:183], v[206:209], v[80:83]
	s_setprio 0
	s_barrier
; #define PG8_STAGE(bufoff, gbase, voff) do { _Pragma("unroll") for (int _i = 0; _i < 2; ++_i) \
;         __builtin_amdgcn_global_load_lds((const unsigned*)((const char*)(gbase) + (voff)[_i]), (PG8_LAS unsigned*)(lds + (bufoff) + ldsw + _i * 8192), 16, 0, 0); } while (0)
; #define PG8_LDA(dst, b, h) do { _Pragma("unroll") for (int m = 0; m < 4; ++m) _Pragma("unroll") for (int k = 0; k < 2; ++k) dst[m][k] = *(const PG8_LAS bf16x8*)(lds + PG8_SA(b, h) + aoff + m * 2048 + k * 1024); } while (0)
; #define PG8_MMA(ai, bj, At, Bt) do { __builtin_amdgcn_s_setprio(1); _Pragma("unroll") for (int m = 0; m < 4; ++m) _Pragma("unroll") for (int n = 0; n < 2; ++n) _Pragma("unroll") for (int k = 0; k < 2; ++k) \
;         acc[ai][bj][m][n] = __builtin_amdgcn_mfma_f32_16x16x32_bf16(Bt[n][k], At[m][k], acc[ai][bj][m][n], 0, 0, 0); __builtin_amdgcn_s_setprio(0); } while (0)
; #define PG8_WAIT_V(n) asm volatile("s_waitcnt vmcnt(" #n ")" ::: "memory")
; #define PG8_WAIT_L(n) asm volatile("s_waitcnt lgkmcnt(" #n ")" ::: "memory")
; #define PG8_BAR __builtin_amdgcn_s_barrier()
; #define PG8_SCHED __builtin_amdgcn_sched_barrier(0)
; template <class Epi, class Sched, bool ALIGN_EPI = false, bool SP2 = false>
; __device__ __forceinline__ void gemm_phase(PG8_LAS unsigned char* lds, const Gemm g, const Sched& S, const Epi& E) {
;     ...
;         for (int t = 0; t < nt; t += 2) {
;     ...
;             PG8_LDA(At, 1, 1); PG8_STAGE(PG8_SB(1, 0), b3, voffB); PG8_STAGE(PG8_SB(1, 1), b3 + hstep, voffB); PG8_STAGE(PG8_SA(1, 0), a3, voffA);
;             PG8_WAIT_V(8); PG8_WAIT_L(0); PG8_BAR; PG8_MMA(1, 0, At, B0); PG8_MMA(1, 1, At, B1); PG8_BAR; PG8_SCHED;
	s_add_i32 s48, s62, s15
	v_lshl_add_u64 v[218:219], v[218:219], 0, s[12:13]
	s_mov_b32 m0, s48
	ds_read_b128 v[184:187], v153 offset:49152
	ds_read_b128 v[188:191], v153 offset:50176
	ds_read_b128 v[192:195], v153 offset:51200
	ds_read_b128 v[196:199], v153 offset:52224
	ds_read_b128 v[200:203], v153 offset:53248
	ds_read_b128 v[206:209], v153 offset:54272
	ds_read_b128 v[210:213], v153 offset:55296
	ds_read_b128 v[214:217], v153 offset:56320
	global_load_lds_dwordx4 v[218:219], off
	s_add_i32 m0, s48, 0x2000
	s_add_u32 s46, s46, 0x20080
	v_lshl_add_u64 v[218:219], v[220:221], 0, s[12:13]
	s_addc_u32 s47, s47, 0
	s_add_i32 s48, s63, s15
	global_load_lds_dwordx4 v[218:219], off
	v_lshl_add_u64 v[218:219], s[46:47], 0, v[130:131]
	s_mov_b32 m0, s48
	s_nop 0
	global_load_lds_dwordx4 v[218:219], off
	v_lshl_add_u64 v[218:219], s[46:47], 0, v[134:135]
	s_add_i32 m0, s48, 0x2000
	s_nop 0
	global_load_lds_dwordx4 v[218:219], off
	s_waitcnt vmcnt(6)
	s_waitcnt lgkmcnt(0)
	s_barrier
	s_setprio 1
	s_waitcnt lgkmcnt(0)
	v_mfma_f32_16x16x32_bf16 v[60:63], v[144:147], v[184:187], v[60:63]
	v_mfma_f32_16x16x32_bf16 v[40:43], v[160:163], v[192:195], v[40:43]
	v_mfma_f32_16x16x32_bf16 v[28:31], v[144:147], v[200:203], v[28:31]
	v_mfma_f32_16x16x32_bf16 v[8:11], v[160:163], v[210:213], v[8:11]
	v_mfma_f32_16x16x32_bf16 v[44:47], v[144:147], v[192:195], v[44:47]
	v_mfma_f32_16x16x32_bf16 v[56:59], v[160:163], v[184:187], v[56:59]
	v_mfma_f32_16x16x32_bf16 v[12:15], v[144:147], v[210:213], v[12:15]
	v_mfma_f32_16x16x32_bf16 v[24:27], v[160:163], v[200:203], v[24:27]
	v_mfma_f32_16x16x32_bf16 v[60:63], v[156:159], v[188:191], v[60:63]
	v_mfma_f32_16x16x32_bf16 v[40:43], v[164:167], v[196:199], v[40:43]
	v_mfma_f32_16x16x32_bf16 v[28:31], v[156:159], v[206:209], v[28:31]
	v_mfma_f32_16x16x32_bf16 v[8:11], v[164:167], v[214:217], v[8:11]
	v_mfma_f32_16x16x32_bf16 v[44:47], v[156:159], v[196:199], v[44:47]
	v_mfma_f32_16x16x32_bf16 v[56:59], v[164:167], v[188:191], v[56:59]
	v_lshl_add_u64 v[218:219], v[222:223], 0, s[12:13]
	s_mov_b32 m0, s52
	s_nop 0
	global_load_lds_dwordx4 v[218:219], off
	v_mfma_f32_16x16x32_bf16 v[12:15], v[156:159], v[214:217], v[12:15]
	v_mfma_f32_16x16x32_bf16 v[24:27], v[164:167], v[206:209], v[24:27]
	s_setprio 0
	s_setprio 1
	v_mfma_f32_16x16x32_bf16 v[52:55], v[168:171], v[184:187], v[52:55]
	v_mfma_f32_16x16x32_bf16 v[32:35], v[176:179], v[192:195], v[32:35]
	v_mfma_f32_16x16x32_bf16 v[20:23], v[168:171], v[200:203], v[20:23]
	v_mfma_f32_16x16x32_bf16 v[0:3], v[176:179], v[210:213], v[0:3]
	v_mfma_f32_16x16x32_bf16 v[36:39], v[168:171], v[192:195], v[36:39]
	v_mfma_f32_16x16x32_bf16 v[48:51], v[176:179], v[184:187], v[48:51]
	v_mfma_f32_16x16x32_bf16 v[4:7], v[168:171], v[210:213], v[4:7]
	v_mfma_f32_16x16x32_bf16 v[16:19], v[176:179], v[200:203], v[16:19]
	v_mfma_f32_16x16x32_bf16 v[52:55], v[172:175], v[188:191], v[52:55]
	v_mfma_f32_16x16x32_bf16 v[32:35], v[180:183], v[196:199], v[32:35]
	v_mfma_f32_16x16x32_bf16 v[20:23], v[172:175], v[206:209], v[20:23]
	v_mfma_f32_16x16x32_bf16 v[0:3], v[180:183], v[214:217], v[0:3]
	v_mfma_f32_16x16x32_bf16 v[36:39], v[172:175], v[196:199], v[36:39]
	v_mfma_f32_16x16x32_bf16 v[48:51], v[180:183], v[188:191], v[48:51]
	v_lshl_add_u64 v[218:219], v[224:225], 0, s[12:13]
	s_mov_b32 m0, s53
	s_nop 0
	global_load_lds_dwordx4 v[218:219], off
	v_mfma_f32_16x16x32_bf16 v[4:7], v[172:175], v[214:217], v[4:7]
	v_mfma_f32_16x16x32_bf16 v[16:19], v[180:183], v[206:209], v[16:19]
	s_setprio 0
	s_barrier
	s_add_i32 s61, s61, 2
	s_add_u32 s44, s44, 0x100
	s_addc_u32 s45, s45, 0
	s_add_u32 s59, s59, 0x100
	s_addc_u32 s60, s60, 0
	s_cmp_gt_u32 s61, 5
	s_cbranch_scc0 .LBB0_1816
	s_and_b64 vcc, exec, s[24:25]
	s_cbranch_vccz .LBB0_1819
	s_barrier

; #define PG8_STAGE(bufoff, gbase, voff) do { _Pragma("unroll") for (int _i = 0; _i < 2; ++_i) \
;         __builtin_amdgcn_global_load_lds((const unsigned*)((const char*)(gbase) + (voff)[_i]), (PG8_LAS unsigned*)(lds + (bufoff) + ldsw + _i * 8192), 16, 0, 0); } while (0)
; #define PG8_LDA(dst, b, h) do { _Pragma("unroll") for (int m = 0; m < 4; ++m) _Pragma("unroll") for (int k = 0; k < 2; ++k) dst[m][k] = *(const PG8_LAS bf16x8*)(lds + PG8_SA(b, h) + aoff + m * 2048 + k * 1024); } while (0)
; #define PG8_LDB(dst, b, h) do { _Pragma("unroll") for (int n = 0; n < 2; ++n) _Pragma("unroll") for (int k = 0; k < 2; ++k) dst[n][k] = *(const PG8_LAS bf16x8*)(lds + PG8_SB(b, h) + boff + n * 2048 + k * 1024); } while (0)
; #define PG8_MMA(ai, bj, At, Bt) do { __builtin_amdgcn_s_setprio(1); _Pragma("unroll") for (int m = 0; m < 4; ++m) _Pragma("unroll") for (int n = 0; n < 2; ++n) _Pragma("unroll") for (int k = 0; k < 2; ++k) \
;         acc[ai][bj][m][n] = __builtin_amdgcn_mfma_f32_16x16x32_bf16(Bt[n][k], At[m][k], acc[ai][bj][m][n], 0, 0, 0); __builtin_amdgcn_s_setprio(0); } while (0)
; #define PG8_BAR __builtin_amdgcn_s_barrier()
; template <class Epi, class Sched, bool ALIGN_EPI = false, bool SP2 = false>
; __device__ __forceinline__ void gemm_phase(PG8_LAS unsigned char* lds, const Gemm g, const Sched& S, const Epi& E) {
;     ...
;         const bool has_next = S.next(ui + 1, nxt);
;         const char* nA = has_next ? (const char*)g.A + (size_t)nxt.pm * tstep : cA; const char* nB = has_next ? (const char*)g.Bt + (size_t)nxt.pn * tstep : cB;
;         for (int t = 0; t < nt; t += 2) {
;             const bool last = (t == nt - 2);
;             const char* a1 = cA + (size_t)(t + 1) * kstep;
;             const char* a2 = last ? nA : cA + (size_t)(t + 2) * kstep; const char* b2 = last ? nB : cB + (size_t)(t + 2) * kstep;
;             const char* a3 = a2 + kstep; const char* b3 = b2 + kstep;
;             if (last && has_next) S.a_ready(nxt);
;             if constexpr (SP2) {
;             PG8_LDB(B0, 0, 0); PG8_LDB(B1, 0, 1); PG8_SCHED; PG8_LDA(At, 0, 0); PG8_STAGE(PG8_SA(1, 1), a1 + hstep, voffA);
;             PG8_WAIT_V(8); PG8_WAIT_L(0); PG8_BAR; PG8_MMA(0, 0, At, B0); PG8_MMA(0, 1, At, B1); PG8_BAR; PG8_SCHED;
;             PG8_LDA(At, 0, 1); PG8_STAGE(PG8_SB(0, 0), b2, voffB); PG8_STAGE(PG8_SB(0, 1), b2 + hstep, voffB); PG8_STAGE(PG8_SA(0, 0), a2, voffA);
.LBB0_1899:
	s_ashr_i32 s25, s24, 31
	s_lshl_b64 s[26:27], s[24:25], 19
	s_add_u32 s26, s22, s26
	s_addc_u32 s27, s23, s27
	s_and_b64 s[28:29], s[4:5], exec
	s_cselect_b32 s25, s27, s39
	s_cselect_b32 s53, s26, s38
	s_ashr_i32 s13, s12, 31
	s_lshl_b64 s[28:29], s[12:13], 19
	s_add_u32 s28, s3, s28
	s_addc_u32 s29, s14, s29
	s_and_b64 s[42:43], s[4:5], exec
	s_cselect_b32 s13, s29, s41
	s_cselect_b32 s54, s28, s40
	s_add_u32 s38, s38, 0x40080
	s_addc_u32 s39, s39, 0
	s_add_u32 s55, s40, 0x100
	s_addc_u32 s56, s41, 0
	s_mov_b32 s57, -2
	ds_read_b128 v[144:147], v155
	ds_read_b128 v[148:151], v155 offset:1024
	ds_read_b128 v[160:163], v155 offset:2048
	ds_read_b128 v[164:167], v155 offset:3072
	ds_read_b128 v[168:171], v156
	ds_read_b128 v[172:175], v156 offset:1024
	ds_read_b128 v[176:179], v156 offset:2048
	ds_read_b128 v[180:183], v156 offset:3072
	s_add_u32 s40, s38, 0xfffc0080
	s_addc_u32 s41, s39, -1
	s_cmp_eq_u32 s57, 12
	s_cselect_b32 s43, s25, s41
	s_cselect_b32 s42, s53, s40
	s_cselect_b32 s41, s13, s56
	s_cselect_b32 s40, s54, s55
	v_lshl_add_u64 v[218:219], s[38:39], 0, v[136:137]
	s_add_i32 m0, s34, 0xc000
	ds_read_b128 v[184:187], v157
	ds_read_b128 v[188:191], v157 offset:1024
	ds_read_b128 v[192:195], v157 offset:2048
	ds_read_b128 v[196:199], v157 offset:3072
	ds_read_b128 v[200:203], v157 offset:4096
	ds_read_b128 v[206:209], v157 offset:5120
	ds_read_b128 v[210:213], v157 offset:6144
	ds_read_b128 v[214:217], v157 offset:7168
	global_load_lds_dwordx4 v[218:219], off
	v_lshl_add_u64 v[218:219], s[38:39], 0, v[138:139]
	s_add_i32 m0, s34, 0xe000
	s_nop 0
	global_load_lds_dwordx4 v[218:219], off
	s_waitcnt vmcnt(8)
	s_waitcnt lgkmcnt(0)
	s_barrier
	s_setprio 1
	s_waitcnt lgkmcnt(0)
	v_mfma_f32_16x16x32_bf16 v[124:127], v[144:147], v[184:187], 0
	v_mfma_f32_16x16x32_bf16 v[104:107], v[160:163], v[192:195], 0
	v_mfma_f32_16x16x32_bf16 v[92:95], v[144:147], v[200:203], 0
	v_mfma_f32_16x16x32_bf16 v[72:75], v[160:163], v[210:213], 0
	v_mfma_f32_16x16x32_bf16 v[108:111], v[144:147], v[192:195], 0
	v_mfma_f32_16x16x32_bf16 v[120:123], v[160:163], v[184:187], 0
	v_mfma_f32_16x16x32_bf16 v[76:79], v[144:147], v[210:213], 0
	v_mfma_f32_16x16x32_bf16 v[88:91], v[160:163], v[200:203], 0
	v_mfma_f32_16x16x32_bf16 v[124:127], v[148:151], v[188:191], v[124:127]
	v_mfma_f32_16x16x32_bf16 v[104:107], v[164:167], v[196:199], v[104:107]
	v_mfma_f32_16x16x32_bf16 v[92:95], v[148:151], v[206:209], v[92:95]
	v_mfma_f32_16x16x32_bf16 v[72:75], v[164:167], v[214:217], v[72:75]
	v_mfma_f32_16x16x32_bf16 v[108:111], v[148:151], v[196:199], v[108:111]
	v_mfma_f32_16x16x32_bf16 v[120:123], v[164:167], v[188:191], v[120:123]
	v_mfma_f32_16x16x32_bf16 v[76:79], v[148:151], v[214:217], v[76:79]
	v_mfma_f32_16x16x32_bf16 v[88:91], v[164:167], v[206:209], v[88:91]
	s_setprio 0
	s_setprio 1
	v_mfma_f32_16x16x32_bf16 v[116:119], v[168:171], v[184:187], 0
	v_mfma_f32_16x16x32_bf16 v[96:99], v[176:179], v[192:195], 0
	v_mfma_f32_16x16x32_bf16 v[84:87], v[168:171], v[200:203], 0
	v_mfma_f32_16x16x32_bf16 v[64:67], v[176:179], v[210:213], 0
	v_mfma_f32_16x16x32_bf16 v[100:103], v[168:171], v[192:195], 0
	v_mfma_f32_16x16x32_bf16 v[112:115], v[176:179], v[184:187], 0
	v_mfma_f32_16x16x32_bf16 v[68:71], v[168:171], v[210:213], 0
	v_mfma_f32_16x16x32_bf16 v[80:83], v[176:179], v[200:203], 0
	v_mfma_f32_16x16x32_bf16 v[116:119], v[172:175], v[188:191], v[116:119]
	v_mfma_f32_16x16x32_bf16 v[96:99], v[180:183], v[196:199], v[96:99]
	v_mfma_f32_16x16x32_bf16 v[84:87], v[172:175], v[206:209], v[84:87]
	v_mfma_f32_16x16x32_bf16 v[64:67], v[180:183], v[214:217], v[64:67]
	v_mfma_f32_16x16x32_bf16 v[100:103], v[172:175], v[196:199], v[100:103]
	v_mfma_f32_16x16x32_bf16 v[112:115], v[180:183], v[188:191], v[112:115]
	v_mfma_f32_16x16x32_bf16 v[68:71], v[172:175], v[214:217], v[68:71]
	v_mfma_f32_16x16x32_bf16 v[80:83], v[180:183], v[206:209], v[80:83]
	s_setprio 0
	s_barrier
	s_add_i32 s58, s49, s15
	v_lshl_add_u64 v[218:219], s[40:41], 0, v[132:133]
	s_mov_b32 m0, s58
	ds_read_b128 v[184:187], v157 offset:16384
	ds_read_b128 v[188:191], v157 offset:17408
	ds_read_b128 v[192:195], v157 offset:18432
	ds_read_b128 v[196:199], v157 offset:19456
	ds_read_b128 v[200:203], v157 offset:20480
	ds_read_b128 v[206:209], v157 offset:21504
	ds_read_b128 v[210:213], v157 offset:22528
	ds_read_b128 v[214:217], v157 offset:23552
	global_load_lds_dwordx4 v[218:219], off
	s_add_i32 m0, s58, 0x2000
	s_add_u32 s58, s40, 0x40000
	v_lshl_add_u64 v[220:221], s[40:41], 0, v[128:129]
	s_addc_u32 s59, s41, 0
	s_add_i32 s60, s50, s15
	global_load_lds_dwordx4 v[220:221], off
	v_lshl_add_u64 v[222:223], s[58:59], 0, v[132:133]
	s_mov_b32 m0, s60
	global_load_lds_dwordx4 v[222:223], off
	v_lshl_add_u64 v[222:223], s[58:59], 0, v[128:129]
	s_add_i32 m0, s60, 0x2000
	s_nop 0
	global_load_lds_dwordx4 v[222:223], off
	s_waitcnt vmcnt(6)
	s_waitcnt lgkmcnt(0)
	s_barrier
; #define PG8_STAGE(bufoff, gbase, voff) do { _Pragma("unroll") for (int _i = 0; _i < 2; ++_i) \
;         __builtin_amdgcn_global_load_lds((const unsigned*)((const char*)(gbase) + (voff)[_i]), (PG8_LAS unsigned*)(lds + (bufoff) + ldsw + _i * 8192), 16, 0, 0); } while (0)
; #define PG8_LDA(dst, b, h) do { _Pragma("unroll") for (int m = 0; m < 4; ++m) _Pragma("unroll") for (int k = 0; k < 2; ++k) dst[m][k] = *(const PG8_LAS bf16x8*)(lds + PG8_SA(b, h) + aoff + m * 2048 + k * 1024); } while (0)
; #define PG8_LDB(dst, b, h) do { _Pragma("unroll") for (int n = 0; n < 2; ++n) _Pragma("unroll") for (int k = 0; k < 2; ++k) dst[n][k] = *(const PG8_LAS bf16x8*)(lds + PG8_SB(b, h) + boff + n * 2048 + k * 1024); } while (0)
; #define PG8_MMA(ai, bj, At, Bt) do { __builtin_amdgcn_s_setprio(1); _Pragma("unroll") for (int m = 0; m < 4; ++m) _Pragma("unroll") for (int n = 0; n < 2; ++n) _Pragma("unroll") for (int k = 0; k < 2; ++k) \
;         acc[ai][bj][m][n] = __builtin_amdgcn_mfma_f32_16x16x32_bf16(Bt[n][k], At[m][k], acc[ai][bj][m][n], 0, 0, 0); __builtin_amdgcn_s_setprio(0); } while (0)
; #define PG8_WAIT_V(n) asm volatile("s_waitcnt vmcnt(" #n ")" ::: "memory")
; #define PG8_WAIT_L(n) asm volatile("s_waitcnt lgkmcnt(" #n ")" ::: "memory")
; #define PG8_BAR __builtin_amdgcn_s_barrier()
; #define PG8_SCHED __builtin_amdgcn_sched_barrier(0)
; template <class Epi, class Sched, bool ALIGN_EPI = false, bool SP2 = false>
; __device__ __forceinline__ void gemm_phase(PG8_LAS unsigned char* lds, const Gemm g, const Sched& S, const Epi& E) {
;     ...
;             PG8_WAIT_V(8); PG8_WAIT_L(0); PG8_BAR; PG8_MMA(1, 0, At, B0); PG8_MMA(1, 1, At, B1); PG8_BAR; PG8_SCHED;
;             PG8_LDB(B0, 1, 0); PG8_LDB(B1, 1, 1); PG8_SCHED; PG8_LDA(At, 1, 0); PG8_STAGE(PG8_SA(0, 1), a2 + hstep, voffA);
;             PG8_WAIT_V(8); PG8_WAIT_L(0); PG8_BAR; PG8_MMA(0, 0, At, B0); PG8_MMA(0, 1, At, B1); PG8_BAR; PG8_SCHED;
	s_setprio 1
	s_waitcnt lgkmcnt(0)
	v_mfma_f32_16x16x32_bf16 v[60:63], v[144:147], v[184:187], 0
	v_mfma_f32_16x16x32_bf16 v[40:43], v[160:163], v[192:195], 0
	v_mfma_f32_16x16x32_bf16 v[28:31], v[144:147], v[200:203], 0
	v_mfma_f32_16x16x32_bf16 v[8:11], v[160:163], v[210:213], 0
	v_mfma_f32_16x16x32_bf16 v[44:47], v[144:147], v[192:195], 0
	v_mfma_f32_16x16x32_bf16 v[56:59], v[160:163], v[184:187], 0
	v_mfma_f32_16x16x32_bf16 v[12:15], v[144:147], v[210:213], 0
	v_mfma_f32_16x16x32_bf16 v[24:27], v[160:163], v[200:203], 0
	v_mfma_f32_16x16x32_bf16 v[60:63], v[148:151], v[188:191], v[60:63]
	v_mfma_f32_16x16x32_bf16 v[40:43], v[164:167], v[196:199], v[40:43]
	v_mfma_f32_16x16x32_bf16 v[28:31], v[148:151], v[206:209], v[28:31]
	v_mfma_f32_16x16x32_bf16 v[8:11], v[164:167], v[214:217], v[8:11]
	v_mfma_f32_16x16x32_bf16 v[44:47], v[148:151], v[196:199], v[44:47]
	v_mfma_f32_16x16x32_bf16 v[56:59], v[164:167], v[188:191], v[56:59]
	v_lshl_add_u64 v[222:223], s[42:43], 0, v[134:135]
	s_mov_b32 m0, s34
	s_nop 0
	global_load_lds_dwordx4 v[222:223], off
	v_mfma_f32_16x16x32_bf16 v[12:15], v[148:151], v[214:217], v[12:15]
	v_mfma_f32_16x16x32_bf16 v[24:27], v[164:167], v[206:209], v[24:27]
	s_setprio 0
	s_setprio 1
	v_mfma_f32_16x16x32_bf16 v[52:55], v[168:171], v[184:187], 0
	v_mfma_f32_16x16x32_bf16 v[32:35], v[176:179], v[192:195], 0
	v_mfma_f32_16x16x32_bf16 v[20:23], v[168:171], v[200:203], 0
	v_mfma_f32_16x16x32_bf16 v[0:3], v[176:179], v[210:213], 0
	v_mfma_f32_16x16x32_bf16 v[36:39], v[168:171], v[192:195], 0
	v_mfma_f32_16x16x32_bf16 v[48:51], v[176:179], v[184:187], 0
	v_mfma_f32_16x16x32_bf16 v[4:7], v[168:171], v[210:213], 0
	v_mfma_f32_16x16x32_bf16 v[16:19], v[176:179], v[200:203], 0
	v_mfma_f32_16x16x32_bf16 v[52:55], v[172:175], v[188:191], v[52:55]
	v_mfma_f32_16x16x32_bf16 v[32:35], v[180:183], v[196:199], v[32:35]
	v_mfma_f32_16x16x32_bf16 v[20:23], v[172:175], v[206:209], v[20:23]
	v_mfma_f32_16x16x32_bf16 v[0:3], v[180:183], v[214:217], v[0:3]
	v_mfma_f32_16x16x32_bf16 v[36:39], v[172:175], v[196:199], v[36:39]
	v_mfma_f32_16x16x32_bf16 v[48:51], v[180:183], v[188:191], v[48:51]
	v_lshl_add_u64 v[224:225], s[42:43], 0, v[130:131]
	s_mov_b32 m0, s37
	s_nop 0
	global_load_lds_dwordx4 v[224:225], off
	v_mfma_f32_16x16x32_bf16 v[4:7], v[172:175], v[214:217], v[4:7]
	v_mfma_f32_16x16x32_bf16 v[16:19], v[180:183], v[206:209], v[16:19]
	s_setprio 0
	s_barrier
	s_add_i32 s58, 0, 0x18000
	v_add_u32_e32 v159, s58, v153
	s_add_i32 s59, 0, 0x1c000
	ds_read_b128 v[144:147], v159
	ds_read_b128 v[148:151], v159 offset:1024
	ds_read_b128 v[160:163], v159 offset:2048
	ds_read_b128 v[164:167], v159 offset:3072
	v_add_u32_e32 v159, s59, v153
	ds_read_b128 v[168:171], v159
	ds_read_b128 v[172:175], v159 offset:1024
	ds_read_b128 v[176:179], v159 offset:2048
	ds_read_b128 v[180:183], v159 offset:3072
	s_add_u32 s42, s42, 0x40000
	s_addc_u32 s43, s43, 0
	s_mov_b32 m0, s44
	v_lshl_add_u64 v[226:227], s[42:43], 0, v[134:135]
	ds_read_b128 v[184:187], v157 offset:32768
	ds_read_b128 v[188:191], v157 offset:33792
	ds_read_b128 v[192:195], v157 offset:34816
	ds_read_b128 v[196:199], v157 offset:35840
	ds_read_b128 v[200:203], v157 offset:36864
	ds_read_b128 v[206:209], v157 offset:37888
	ds_read_b128 v[210:213], v157 offset:38912
	ds_read_b128 v[214:217], v157 offset:39936
	global_load_lds_dwordx4 v[226:227], off
	v_lshl_add_u64 v[226:227], s[42:43], 0, v[130:131]
	s_mov_b32 m0, s45
	s_nop 0
	global_load_lds_dwordx4 v[226:227], off
	s_waitcnt vmcnt(8)
	s_waitcnt lgkmcnt(0)
	s_barrier
	s_setprio 1
	s_waitcnt lgkmcnt(0)
	v_mfma_f32_16x16x32_bf16 v[124:127], v[144:147], v[184:187], v[124:127]
	v_mfma_f32_16x16x32_bf16 v[104:107], v[160:163], v[192:195], v[104:107]
	v_mfma_f32_16x16x32_bf16 v[92:95], v[144:147], v[200:203], v[92:95]
	v_mfma_f32_16x16x32_bf16 v[72:75], v[160:163], v[210:213], v[72:75]
	v_mfma_f32_16x16x32_bf16 v[108:111], v[144:147], v[192:195], v[108:111]
	v_mfma_f32_16x16x32_bf16 v[120:123], v[160:163], v[184:187], v[120:123]
	v_mfma_f32_16x16x32_bf16 v[76:79], v[144:147], v[210:213], v[76:79]
	v_mfma_f32_16x16x32_bf16 v[88:91], v[160:163], v[200:203], v[88:91]
	v_mfma_f32_16x16x32_bf16 v[124:127], v[148:151], v[188:191], v[124:127]
	v_mfma_f32_16x16x32_bf16 v[104:107], v[164:167], v[196:199], v[104:107]
	v_mfma_f32_16x16x32_bf16 v[92:95], v[148:151], v[206:209], v[92:95]
	v_mfma_f32_16x16x32_bf16 v[72:75], v[164:167], v[214:217], v[72:75]
	v_mfma_f32_16x16x32_bf16 v[108:111], v[148:151], v[196:199], v[108:111]
	v_mfma_f32_16x16x32_bf16 v[120:123], v[164:167], v[188:191], v[120:123]
	v_mfma_f32_16x16x32_bf16 v[76:79], v[148:151], v[214:217], v[76:79]
	v_mfma_f32_16x16x32_bf16 v[88:91], v[164:167], v[206:209], v[88:91]
	s_setprio 0
	s_setprio 1
	v_mfma_f32_16x16x32_bf16 v[116:119], v[168:171], v[184:187], v[116:119]
	v_mfma_f32_16x16x32_bf16 v[96:99], v[176:179], v[192:195], v[96:99]
	v_mfma_f32_16x16x32_bf16 v[84:87], v[168:171], v[200:203], v[84:87]
	v_mfma_f32_16x16x32_bf16 v[64:67], v[176:179], v[210:213], v[64:67]
	v_mfma_f32_16x16x32_bf16 v[100:103], v[168:171], v[192:195], v[100:103]
	v_mfma_f32_16x16x32_bf16 v[112:115], v[176:179], v[184:187], v[112:115]
	v_mfma_f32_16x16x32_bf16 v[68:71], v[168:171], v[210:213], v[68:71]
	v_mfma_f32_16x16x32_bf16 v[80:83], v[176:179], v[200:203], v[80:83]
	v_mfma_f32_16x16x32_bf16 v[116:119], v[172:175], v[188:191], v[116:119]
	v_mfma_f32_16x16x32_bf16 v[96:99], v[180:183], v[196:199], v[96:99]
	v_mfma_f32_16x16x32_bf16 v[84:87], v[172:175], v[206:209], v[84:87]
	v_mfma_f32_16x16x32_bf16 v[64:67], v[180:183], v[214:217], v[64:67]
	v_mfma_f32_16x16x32_bf16 v[100:103], v[172:175], v[196:199], v[100:103]
	v_mfma_f32_16x16x32_bf16 v[112:115], v[180:183], v[188:191], v[112:115]
	v_mfma_f32_16x16x32_bf16 v[68:71], v[172:175], v[214:217], v[68:71]
	v_mfma_f32_16x16x32_bf16 v[80:83], v[180:183], v[206:209], v[80:83]
	s_setprio 0
	s_barrier
; #define PG8_STAGE(bufoff, gbase, voff) do { _Pragma("unroll") for (int _i = 0; _i < 2; ++_i) \
;         __builtin_amdgcn_global_load_lds((const unsigned*)((const char*)(gbase) + (voff)[_i]), (PG8_LAS unsigned*)(lds + (bufoff) + ldsw + _i * 8192), 16, 0, 0); } while (0)
; #define PG8_LDA(dst, b, h) do { _Pragma("unroll") for (int m = 0; m < 4; ++m) _Pragma("unroll") for (int k = 0; k < 2; ++k) dst[m][k] = *(const PG8_LAS bf16x8*)(lds + PG8_SA(b, h) + aoff + m * 2048 + k * 1024); } while (0)
; #define PG8_LDB(dst, b, h) do { _Pragma("unroll") for (int n = 0; n < 2; ++n) _Pragma("unroll") for (int k = 0; k < 2; ++k) dst[n][k] = *(const PG8_LAS bf16x8*)(lds + PG8_SB(b, h) + boff + n * 2048 + k * 1024); } while (0)
; #define PG8_MMA(ai, bj, At, Bt) do { __builtin_amdgcn_s_setprio(1); _Pragma("unroll") for (int m = 0; m < 4; ++m) _Pragma("unroll") for (int n = 0; n < 2; ++n) _Pragma("unroll") for (int k = 0; k < 2; ++k) \
;         acc[ai][bj][m][n] = __builtin_amdgcn_mfma_f32_16x16x32_bf16(Bt[n][k], At[m][k], acc[ai][bj][m][n], 0, 0, 0); __builtin_amdgcn_s_setprio(0); } while (0)
; #define PG8_WAIT_V(n) asm volatile("s_waitcnt vmcnt(" #n ")" ::: "memory")
; #define PG8_WAIT_L(n) asm volatile("s_waitcnt lgkmcnt(" #n ")" ::: "memory")
; #define PG8_BAR __builtin_amdgcn_s_barrier()
; #define PG8_SCHED __builtin_amdgcn_sched_barrier(0)
; template <class Epi, class Sched, bool ALIGN_EPI = false, bool SP2 = false>
; __device__ __forceinline__ void gemm_phase(PG8_LAS unsigned char* lds, const Gemm g, const Sched& S, const Epi& E) {
;     ...
;         for (int t = 0; t < nt; t += 2) {
;             const bool last = (t == nt - 2);
;             const char* a1 = cA + (size_t)(t + 1) * kstep;
;             const char* a2 = last ? nA : cA + (size_t)(t + 2) * kstep; const char* b2 = last ? nB : cB + (size_t)(t + 2) * kstep;
;             const char* a3 = a2 + kstep; const char* b3 = b2 + kstep;
;             if (last && has_next) S.a_ready(nxt);
;             if constexpr (SP2) {
;             PG8_LDB(B0, 0, 0); PG8_LDB(B1, 0, 1); PG8_SCHED; PG8_LDA(At, 0, 0); PG8_STAGE(PG8_SA(1, 1), a1 + hstep, voffA);
;     ...
;             PG8_LDA(At, 1, 1); PG8_STAGE(PG8_SB(1, 0), b3, voffB); PG8_STAGE(PG8_SB(1, 1), b3 + hstep, voffB); PG8_STAGE(PG8_SA(1, 0), a3, voffA);
;             PG8_WAIT_V(8); PG8_WAIT_L(0); PG8_BAR; PG8_MMA(1, 0, At, B0); PG8_MMA(1, 1, At, B1); PG8_BAR; PG8_SCHED;
	s_add_i32 s42, s58, s15
	v_lshl_add_u64 v[218:219], v[218:219], 0, s[8:9]
	s_mov_b32 m0, s42
	ds_read_b128 v[184:187], v157 offset:49152
	ds_read_b128 v[188:191], v157 offset:50176
	ds_read_b128 v[192:195], v157 offset:51200
	ds_read_b128 v[196:199], v157 offset:52224
	ds_read_b128 v[200:203], v157 offset:53248
	ds_read_b128 v[206:209], v157 offset:54272
	ds_read_b128 v[210:213], v157 offset:55296
	ds_read_b128 v[214:217], v157 offset:56320
	global_load_lds_dwordx4 v[218:219], off
	s_add_i32 m0, s42, 0x2000
	s_add_u32 s40, s40, 0x40080
	v_lshl_add_u64 v[218:219], v[220:221], 0, s[8:9]
	s_addc_u32 s41, s41, 0
	s_add_i32 s42, s59, s15
	global_load_lds_dwordx4 v[218:219], off
	v_lshl_add_u64 v[218:219], s[40:41], 0, v[132:133]
	s_mov_b32 m0, s42
	s_nop 0
	global_load_lds_dwordx4 v[218:219], off
	v_lshl_add_u64 v[218:219], s[40:41], 0, v[128:129]
	s_add_i32 m0, s42, 0x2000
	s_nop 0
	global_load_lds_dwordx4 v[218:219], off
	s_waitcnt vmcnt(6)
	s_waitcnt lgkmcnt(0)
	s_barrier
	s_setprio 1
	s_waitcnt lgkmcnt(0)
	v_mfma_f32_16x16x32_bf16 v[60:63], v[144:147], v[184:187], v[60:63]
	v_mfma_f32_16x16x32_bf16 v[40:43], v[160:163], v[192:195], v[40:43]
	v_mfma_f32_16x16x32_bf16 v[28:31], v[144:147], v[200:203], v[28:31]
	v_mfma_f32_16x16x32_bf16 v[8:11], v[160:163], v[210:213], v[8:11]
	v_mfma_f32_16x16x32_bf16 v[44:47], v[144:147], v[192:195], v[44:47]
	v_mfma_f32_16x16x32_bf16 v[56:59], v[160:163], v[184:187], v[56:59]
	v_mfma_f32_16x16x32_bf16 v[12:15], v[144:147], v[210:213], v[12:15]
	v_mfma_f32_16x16x32_bf16 v[24:27], v[160:163], v[200:203], v[24:27]
	v_mfma_f32_16x16x32_bf16 v[60:63], v[148:151], v[188:191], v[60:63]
	v_mfma_f32_16x16x32_bf16 v[40:43], v[164:167], v[196:199], v[40:43]
	v_mfma_f32_16x16x32_bf16 v[28:31], v[148:151], v[206:209], v[28:31]
	v_mfma_f32_16x16x32_bf16 v[8:11], v[164:167], v[214:217], v[8:11]
	v_mfma_f32_16x16x32_bf16 v[44:47], v[148:151], v[196:199], v[44:47]
	v_mfma_f32_16x16x32_bf16 v[56:59], v[164:167], v[188:191], v[56:59]
	v_lshl_add_u64 v[218:219], v[222:223], 0, s[8:9]
	s_mov_b32 m0, s47
	s_nop 0
	global_load_lds_dwordx4 v[218:219], off
	v_mfma_f32_16x16x32_bf16 v[12:15], v[148:151], v[214:217], v[12:15]
	v_mfma_f32_16x16x32_bf16 v[24:27], v[164:167], v[206:209], v[24:27]
	s_setprio 0
	s_setprio 1
	v_mfma_f32_16x16x32_bf16 v[52:55], v[168:171], v[184:187], v[52:55]
	v_mfma_f32_16x16x32_bf16 v[32:35], v[176:179], v[192:195], v[32:35]
	v_mfma_f32_16x16x32_bf16 v[20:23], v[168:171], v[200:203], v[20:23]
	v_mfma_f32_16x16x32_bf16 v[0:3], v[176:179], v[210:213], v[0:3]
	v_mfma_f32_16x16x32_bf16 v[36:39], v[168:171], v[192:195], v[36:39]
	v_mfma_f32_16x16x32_bf16 v[48:51], v[176:179], v[184:187], v[48:51]
	v_mfma_f32_16x16x32_bf16 v[4:7], v[168:171], v[210:213], v[4:7]
	v_mfma_f32_16x16x32_bf16 v[16:19], v[176:179], v[200:203], v[16:19]
	v_mfma_f32_16x16x32_bf16 v[52:55], v[172:175], v[188:191], v[52:55]
	v_mfma_f32_16x16x32_bf16 v[32:35], v[180:183], v[196:199], v[32:35]
	v_mfma_f32_16x16x32_bf16 v[20:23], v[172:175], v[206:209], v[20:23]
	v_mfma_f32_16x16x32_bf16 v[0:3], v[180:183], v[214:217], v[0:3]
	v_mfma_f32_16x16x32_bf16 v[36:39], v[172:175], v[196:199], v[36:39]
	v_mfma_f32_16x16x32_bf16 v[48:51], v[180:183], v[188:191], v[48:51]
	v_lshl_add_u64 v[218:219], v[224:225], 0, s[8:9]
	s_mov_b32 m0, s48
	s_nop 0
	global_load_lds_dwordx4 v[218:219], off
	v_mfma_f32_16x16x32_bf16 v[4:7], v[172:175], v[214:217], v[4:7]
	v_mfma_f32_16x16x32_bf16 v[16:19], v[180:183], v[206:209], v[16:19]
	s_setprio 0
	s_barrier
	s_add_i32 s57, s57, 2
	s_add_u32 s38, s38, 0x100
	s_addc_u32 s39, s39, 0
	s_add_u32 s55, s55, 0x100
	s_addc_u32 s56, s56, 0
.LBB0_1900:
	ds_read_b128 v[144:147], v155
	ds_read_b128 v[148:151], v155 offset:1024
	ds_read_b128 v[160:163], v155 offset:2048
	ds_read_b128 v[164:167], v155 offset:3072
	ds_read_b128 v[168:171], v156
	ds_read_b128 v[172:175], v156 offset:1024
	ds_read_b128 v[176:179], v156 offset:2048
	ds_read_b128 v[180:183], v156 offset:3072
	s_add_u32 s40, s38, 0xfffc0080
	s_addc_u32 s41, s39, -1
	s_cmp_eq_u32 s57, 12
	s_cselect_b32 s43, s25, s41
	s_cselect_b32 s42, s53, s40
	s_cselect_b32 s41, s13, s56
	s_cselect_b32 s40, s54, s55
	v_lshl_add_u64 v[218:219], s[38:39], 0, v[136:137]
	s_add_i32 m0, s34, 0xc000
	ds_read_b128 v[184:187], v157
	ds_read_b128 v[188:191], v157 offset:1024
	ds_read_b128 v[192:195], v157 offset:2048
	ds_read_b128 v[196:199], v157 offset:3072
	ds_read_b128 v[200:203], v157 offset:4096
	ds_read_b128 v[206:209], v157 offset:5120
	ds_read_b128 v[210:213], v157 offset:6144
	ds_read_b128 v[214:217], v157 offset:7168
	global_load_lds_dwordx4 v[218:219], off
	v_lshl_add_u64 v[218:219], s[38:39], 0, v[138:139]
	s_add_i32 m0, s34, 0xe000
	s_nop 0
	global_load_lds_dwordx4 v[218:219], off
	s_waitcnt vmcnt(8)
	s_waitcnt lgkmcnt(0)
	s_barrier
; #define PG8_STAGE(bufoff, gbase, voff) do { _Pragma("unroll") for (int _i = 0; _i < 2; ++_i) \
;         __builtin_amdgcn_global_load_lds((const unsigned*)((const char*)(gbase) + (voff)[_i]), (PG8_LAS unsigned*)(lds + (bufoff) + ldsw + _i * 8192), 16, 0, 0); } while (0)
; #define PG8_LDA(dst, b, h) do { _Pragma("unroll") for (int m = 0; m < 4; ++m) _Pragma("unroll") for (int k = 0; k < 2; ++k) dst[m][k] = *(const PG8_LAS bf16x8*)(lds + PG8_SA(b, h) + aoff + m * 2048 + k * 1024); } while (0)
; #define PG8_MMA(ai, bj, At, Bt) do { __builtin_amdgcn_s_setprio(1); _Pragma("unroll") for (int m = 0; m < 4; ++m) _Pragma("unroll") for (int n = 0; n < 2; ++n) _Pragma("unroll") for (int k = 0; k < 2; ++k) \
;         acc[ai][bj][m][n] = __builtin_amdgcn_mfma_f32_16x16x32_bf16(Bt[n][k], At[m][k], acc[ai][bj][m][n], 0, 0, 0); __builtin_amdgcn_s_setprio(0); } while (0)
; #define PG8_WAIT_V(n) asm volatile("s_waitcnt vmcnt(" #n ")" ::: "memory")
; #define PG8_WAIT_L(n) asm volatile("s_waitcnt lgkmcnt(" #n ")" ::: "memory")
; #define PG8_BAR __builtin_amdgcn_s_barrier()
; #define PG8_SCHED __builtin_amdgcn_sched_barrier(0)
; template <class Epi, class Sched, bool ALIGN_EPI = false, bool SP2 = false>
; __device__ __forceinline__ void gemm_phase(PG8_LAS unsigned char* lds, const Gemm g, const Sched& S, const Epi& E) {
;     ...
;             PG8_WAIT_V(8); PG8_WAIT_L(0); PG8_BAR; PG8_MMA(0, 0, At, B0); PG8_MMA(0, 1, At, B1); PG8_BAR; PG8_SCHED;
;             PG8_LDA(At, 0, 1); PG8_STAGE(PG8_SB(0, 0), b2, voffB); PG8_STAGE(PG8_SB(0, 1), b2 + hstep, voffB); PG8_STAGE(PG8_SA(0, 0), a2, voffA);
;             PG8_WAIT_V(8); PG8_WAIT_L(0); PG8_BAR; PG8_MMA(1, 0, At, B0); PG8_MMA(1, 1, At, B1); PG8_BAR; PG8_SCHED;
	s_setprio 1
	s_waitcnt lgkmcnt(0)
	v_mfma_f32_16x16x32_bf16 v[124:127], v[144:147], v[184:187], v[124:127]
	v_mfma_f32_16x16x32_bf16 v[104:107], v[160:163], v[192:195], v[104:107]
	v_mfma_f32_16x16x32_bf16 v[92:95], v[144:147], v[200:203], v[92:95]
	v_mfma_f32_16x16x32_bf16 v[72:75], v[160:163], v[210:213], v[72:75]
	v_mfma_f32_16x16x32_bf16 v[108:111], v[144:147], v[192:195], v[108:111]
	v_mfma_f32_16x16x32_bf16 v[120:123], v[160:163], v[184:187], v[120:123]
	v_mfma_f32_16x16x32_bf16 v[76:79], v[144:147], v[210:213], v[76:79]
	v_mfma_f32_16x16x32_bf16 v[88:91], v[160:163], v[200:203], v[88:91]
	v_mfma_f32_16x16x32_bf16 v[124:127], v[148:151], v[188:191], v[124:127]
	v_mfma_f32_16x16x32_bf16 v[104:107], v[164:167], v[196:199], v[104:107]
	v_mfma_f32_16x16x32_bf16 v[92:95], v[148:151], v[206:209], v[92:95]
	v_mfma_f32_16x16x32_bf16 v[72:75], v[164:167], v[214:217], v[72:75]
	v_mfma_f32_16x16x32_bf16 v[108:111], v[148:151], v[196:199], v[108:111]
	v_mfma_f32_16x16x32_bf16 v[120:123], v[164:167], v[188:191], v[120:123]
	v_mfma_f32_16x16x32_bf16 v[76:79], v[148:151], v[214:217], v[76:79]
	v_mfma_f32_16x16x32_bf16 v[88:91], v[164:167], v[206:209], v[88:91]
	s_setprio 0
	s_setprio 1
	v_mfma_f32_16x16x32_bf16 v[116:119], v[168:171], v[184:187], v[116:119]
	v_mfma_f32_16x16x32_bf16 v[96:99], v[176:179], v[192:195], v[96:99]
	v_mfma_f32_16x16x32_bf16 v[84:87], v[168:171], v[200:203], v[84:87]
	v_mfma_f32_16x16x32_bf16 v[64:67], v[176:179], v[210:213], v[64:67]
	v_mfma_f32_16x16x32_bf16 v[100:103], v[168:171], v[192:195], v[100:103]
	v_mfma_f32_16x16x32_bf16 v[112:115], v[176:179], v[184:187], v[112:115]
	v_mfma_f32_16x16x32_bf16 v[68:71], v[168:171], v[210:213], v[68:71]
	v_mfma_f32_16x16x32_bf16 v[80:83], v[176:179], v[200:203], v[80:83]
	v_mfma_f32_16x16x32_bf16 v[116:119], v[172:175], v[188:191], v[116:119]
	v_mfma_f32_16x16x32_bf16 v[96:99], v[180:183], v[196:199], v[96:99]
	v_mfma_f32_16x16x32_bf16 v[84:87], v[172:175], v[206:209], v[84:87]
	v_mfma_f32_16x16x32_bf16 v[64:67], v[180:183], v[214:217], v[64:67]
	v_mfma_f32_16x16x32_bf16 v[100:103], v[172:175], v[196:199], v[100:103]
	v_mfma_f32_16x16x32_bf16 v[112:115], v[180:183], v[188:191], v[112:115]
	v_mfma_f32_16x16x32_bf16 v[68:71], v[172:175], v[214:217], v[68:71]
	v_mfma_f32_16x16x32_bf16 v[80:83], v[180:183], v[206:209], v[80:83]
	s_setprio 0
	s_barrier
	s_add_i32 s58, s49, s15
	v_lshl_add_u64 v[218:219], s[40:41], 0, v[132:133]
	s_mov_b32 m0, s58
	ds_read_b128 v[184:187], v157 offset:16384
	ds_read_b128 v[188:191], v157 offset:17408
	ds_read_b128 v[192:195], v157 offset:18432
	ds_read_b128 v[196:199], v157 offset:19456
	ds_read_b128 v[200:203], v157 offset:20480
	ds_read_b128 v[206:209], v157 offset:21504
	ds_read_b128 v[210:213], v157 offset:22528
	ds_read_b128 v[214:217], v157 offset:23552
	global_load_lds_dwordx4 v[218:219], off
	s_add_i32 m0, s58, 0x2000
	s_add_u32 s58, s40, 0x40000
	v_lshl_add_u64 v[220:221], s[40:41], 0, v[128:129]
	s_addc_u32 s59, s41, 0
	s_add_i32 s60, s50, s15
	global_load_lds_dwordx4 v[220:221], off
	v_lshl_add_u64 v[222:223], s[58:59], 0, v[132:133]
	s_mov_b32 m0, s60
	global_load_lds_dwordx4 v[222:223], off
	v_lshl_add_u64 v[222:223], s[58:59], 0, v[128:129]
	s_add_i32 m0, s60, 0x2000
	s_nop 0
	global_load_lds_dwordx4 v[222:223], off
	s_waitcnt vmcnt(6)
	s_waitcnt lgkmcnt(0)
	s_barrier
	s_setprio 1
	s_waitcnt lgkmcnt(0)
	v_mfma_f32_16x16x32_bf16 v[60:63], v[144:147], v[184:187], v[60:63]
	v_mfma_f32_16x16x32_bf16 v[40:43], v[160:163], v[192:195], v[40:43]
	v_mfma_f32_16x16x32_bf16 v[28:31], v[144:147], v[200:203], v[28:31]
	v_mfma_f32_16x16x32_bf16 v[8:11], v[160:163], v[210:213], v[8:11]
	v_mfma_f32_16x16x32_bf16 v[44:47], v[144:147], v[192:195], v[44:47]
	v_mfma_f32_16x16x32_bf16 v[56:59], v[160:163], v[184:187], v[56:59]
	v_mfma_f32_16x16x32_bf16 v[12:15], v[144:147], v[210:213], v[12:15]
	v_mfma_f32_16x16x32_bf16 v[24:27], v[160:163], v[200:203], v[24:27]
	v_mfma_f32_16x16x32_bf16 v[60:63], v[148:151], v[188:191], v[60:63]
	v_mfma_f32_16x16x32_bf16 v[40:43], v[164:167], v[196:199], v[40:43]
	v_mfma_f32_16x16x32_bf16 v[28:31], v[148:151], v[206:209], v[28:31]
	v_mfma_f32_16x16x32_bf16 v[8:11], v[164:167], v[214:217], v[8:11]
	v_mfma_f32_16x16x32_bf16 v[44:47], v[148:151], v[196:199], v[44:47]
	v_mfma_f32_16x16x32_bf16 v[56:59], v[164:167], v[188:191], v[56:59]
	v_lshl_add_u64 v[222:223], s[42:43], 0, v[134:135]
	s_mov_b32 m0, s34
	s_nop 0
	global_load_lds_dwordx4 v[222:223], off
	v_mfma_f32_16x16x32_bf16 v[12:15], v[148:151], v[214:217], v[12:15]
	v_mfma_f32_16x16x32_bf16 v[24:27], v[164:167], v[206:209], v[24:27]
	s_setprio 0
	s_setprio 1
	v_mfma_f32_16x16x32_bf16 v[52:55], v[168:171], v[184:187], v[52:55]
	v_mfma_f32_16x16x32_bf16 v[32:35], v[176:179], v[192:195], v[32:35]
	v_mfma_f32_16x16x32_bf16 v[20:23], v[168:171], v[200:203], v[20:23]
	v_mfma_f32_16x16x32_bf16 v[0:3], v[176:179], v[210:213], v[0:3]
	v_mfma_f32_16x16x32_bf16 v[36:39], v[168:171], v[192:195], v[36:39]
	v_mfma_f32_16x16x32_bf16 v[48:51], v[176:179], v[184:187], v[48:51]
	v_mfma_f32_16x16x32_bf16 v[4:7], v[168:171], v[210:213], v[4:7]
	v_mfma_f32_16x16x32_bf16 v[16:19], v[176:179], v[200:203], v[16:19]
	v_mfma_f32_16x16x32_bf16 v[52:55], v[172:175], v[188:191], v[52:55]
	v_mfma_f32_16x16x32_bf16 v[32:35], v[180:183], v[196:199], v[32:35]
	v_mfma_f32_16x16x32_bf16 v[20:23], v[172:175], v[206:209], v[20:23]
	v_mfma_f32_16x16x32_bf16 v[0:3], v[180:183], v[214:217], v[0:3]
	v_mfma_f32_16x16x32_bf16 v[36:39], v[172:175], v[196:199], v[36:39]
	v_mfma_f32_16x16x32_bf16 v[48:51], v[180:183], v[188:191], v[48:51]
	v_lshl_add_u64 v[224:225], s[42:43], 0, v[130:131]
	s_mov_b32 m0, s37
	s_nop 0
	global_load_lds_dwordx4 v[224:225], off
	v_mfma_f32_16x16x32_bf16 v[4:7], v[172:175], v[214:217], v[4:7]
	v_mfma_f32_16x16x32_bf16 v[16:19], v[180:183], v[206:209], v[16:19]
	s_setprio 0
	s_barrier
; #define PG8_STAGE(bufoff, gbase, voff) do { _Pragma("unroll") for (int _i = 0; _i < 2; ++_i) \
;         __builtin_amdgcn_global_load_lds((const unsigned*)((const char*)(gbase) + (voff)[_i]), (PG8_LAS unsigned*)(lds + (bufoff) + ldsw + _i * 8192), 16, 0, 0); } while (0)
; #define PG8_LDA(dst, b, h) do { _Pragma("unroll") for (int m = 0; m < 4; ++m) _Pragma("unroll") for (int k = 0; k < 2; ++k) dst[m][k] = *(const PG8_LAS bf16x8*)(lds + PG8_SA(b, h) + aoff + m * 2048 + k * 1024); } while (0)
; #define PG8_LDB(dst, b, h) do { _Pragma("unroll") for (int n = 0; n < 2; ++n) _Pragma("unroll") for (int k = 0; k < 2; ++k) dst[n][k] = *(const PG8_LAS bf16x8*)(lds + PG8_SB(b, h) + boff + n * 2048 + k * 1024); } while (0)
; #define PG8_MMA(ai, bj, At, Bt) do { __builtin_amdgcn_s_setprio(1); _Pragma("unroll") for (int m = 0; m < 4; ++m) _Pragma("unroll") for (int n = 0; n < 2; ++n) _Pragma("unroll") for (int k = 0; k < 2; ++k) \
;         acc[ai][bj][m][n] = __builtin_amdgcn_mfma_f32_16x16x32_bf16(Bt[n][k], At[m][k], acc[ai][bj][m][n], 0, 0, 0); __builtin_amdgcn_s_setprio(0); } while (0)
; #define PG8_WAIT_V(n) asm volatile("s_waitcnt vmcnt(" #n ")" ::: "memory")
; #define PG8_WAIT_L(n) asm volatile("s_waitcnt lgkmcnt(" #n ")" ::: "memory")
; #define PG8_BAR __builtin_amdgcn_s_barrier()
; #define PG8_SCHED __builtin_amdgcn_sched_barrier(0)
; template <class Epi, class Sched, bool ALIGN_EPI = false, bool SP2 = false>
; __device__ __forceinline__ void gemm_phase(PG8_LAS unsigned char* lds, const Gemm g, const Sched& S, const Epi& E) {
;     ...
;             PG8_LDB(B0, 1, 0); PG8_LDB(B1, 1, 1); PG8_SCHED; PG8_LDA(At, 1, 0); PG8_STAGE(PG8_SA(0, 1), a2 + hstep, voffA);
;             PG8_WAIT_V(8); PG8_WAIT_L(0); PG8_BAR; PG8_MMA(0, 0, At, B0); PG8_MMA(0, 1, At, B1); PG8_BAR; PG8_SCHED;
	s_add_i32 s58, 0, 0x18000
	v_add_u32_e32 v159, s58, v153
	s_add_i32 s59, 0, 0x1c000
	ds_read_b128 v[144:147], v159
	ds_read_b128 v[148:151], v159 offset:1024
	ds_read_b128 v[160:163], v159 offset:2048
	ds_read_b128 v[164:167], v159 offset:3072
	v_add_u32_e32 v159, s59, v153
	ds_read_b128 v[168:171], v159
	ds_read_b128 v[172:175], v159 offset:1024
	ds_read_b128 v[176:179], v159 offset:2048
	ds_read_b128 v[180:183], v159 offset:3072
	s_add_u32 s42, s42, 0x40000
	s_addc_u32 s43, s43, 0
	s_mov_b32 m0, s44
	v_lshl_add_u64 v[226:227], s[42:43], 0, v[134:135]
	ds_read_b128 v[184:187], v157 offset:32768
	ds_read_b128 v[188:191], v157 offset:33792
	ds_read_b128 v[192:195], v157 offset:34816
	ds_read_b128 v[196:199], v157 offset:35840
	ds_read_b128 v[200:203], v157 offset:36864
	ds_read_b128 v[206:209], v157 offset:37888
	ds_read_b128 v[210:213], v157 offset:38912
	ds_read_b128 v[214:217], v157 offset:39936
	global_load_lds_dwordx4 v[226:227], off
	v_lshl_add_u64 v[226:227], s[42:43], 0, v[130:131]
	s_mov_b32 m0, s45
	s_nop 0
	global_load_lds_dwordx4 v[226:227], off
	s_waitcnt vmcnt(8)
	s_waitcnt lgkmcnt(0)
	s_barrier
	s_setprio 1
	s_waitcnt lgkmcnt(0)
	v_mfma_f32_16x16x32_bf16 v[124:127], v[144:147], v[184:187], v[124:127]
	v_mfma_f32_16x16x32_bf16 v[104:107], v[160:163], v[192:195], v[104:107]
	v_mfma_f32_16x16x32_bf16 v[92:95], v[144:147], v[200:203], v[92:95]
	v_mfma_f32_16x16x32_bf16 v[72:75], v[160:163], v[210:213], v[72:75]
	v_mfma_f32_16x16x32_bf16 v[108:111], v[144:147], v[192:195], v[108:111]
	v_mfma_f32_16x16x32_bf16 v[120:123], v[160:163], v[184:187], v[120:123]
	v_mfma_f32_16x16x32_bf16 v[76:79], v[144:147], v[210:213], v[76:79]
	v_mfma_f32_16x16x32_bf16 v[88:91], v[160:163], v[200:203], v[88:91]
	v_mfma_f32_16x16x32_bf16 v[124:127], v[148:151], v[188:191], v[124:127]
	v_mfma_f32_16x16x32_bf16 v[104:107], v[164:167], v[196:199], v[104:107]
	v_mfma_f32_16x16x32_bf16 v[92:95], v[148:151], v[206:209], v[92:95]
	v_mfma_f32_16x16x32_bf16 v[72:75], v[164:167], v[214:217], v[72:75]
	v_mfma_f32_16x16x32_bf16 v[108:111], v[148:151], v[196:199], v[108:111]
	v_mfma_f32_16x16x32_bf16 v[120:123], v[164:167], v[188:191], v[120:123]
	v_mfma_f32_16x16x32_bf16 v[76:79], v[148:151], v[214:217], v[76:79]
	v_mfma_f32_16x16x32_bf16 v[88:91], v[164:167], v[206:209], v[88:91]
	s_setprio 0
	s_setprio 1
	v_mfma_f32_16x16x32_bf16 v[116:119], v[168:171], v[184:187], v[116:119]
	v_mfma_f32_16x16x32_bf16 v[96:99], v[176:179], v[192:195], v[96:99]
	v_mfma_f32_16x16x32_bf16 v[84:87], v[168:171], v[200:203], v[84:87]
	v_mfma_f32_16x16x32_bf16 v[64:67], v[176:179], v[210:213], v[64:67]
	v_mfma_f32_16x16x32_bf16 v[100:103], v[168:171], v[192:195], v[100:103]
	v_mfma_f32_16x16x32_bf16 v[112:115], v[176:179], v[184:187], v[112:115]
	v_mfma_f32_16x16x32_bf16 v[68:71], v[168:171], v[210:213], v[68:71]
	v_mfma_f32_16x16x32_bf16 v[80:83], v[176:179], v[200:203], v[80:83]
	v_mfma_f32_16x16x32_bf16 v[116:119], v[172:175], v[188:191], v[116:119]
	v_mfma_f32_16x16x32_bf16 v[96:99], v[180:183], v[196:199], v[96:99]
	v_mfma_f32_16x16x32_bf16 v[84:87], v[172:175], v[206:209], v[84:87]
	v_mfma_f32_16x16x32_bf16 v[64:67], v[180:183], v[214:217], v[64:67]
	v_mfma_f32_16x16x32_bf16 v[100:103], v[172:175], v[196:199], v[100:103]
	v_mfma_f32_16x16x32_bf16 v[112:115], v[180:183], v[188:191], v[112:115]
	v_mfma_f32_16x16x32_bf16 v[68:71], v[172:175], v[214:217], v[68:71]
	v_mfma_f32_16x16x32_bf16 v[80:83], v[180:183], v[206:209], v[80:83]
	s_setprio 0
	s_barrier
; #define PG8_STAGE(bufoff, gbase, voff) do { _Pragma("unroll") for (int _i = 0; _i < 2; ++_i) \
;         __builtin_amdgcn_global_load_lds((const unsigned*)((const char*)(gbase) + (voff)[_i]), (PG8_LAS unsigned*)(lds + (bufoff) + ldsw + _i * 8192), 16, 0, 0); } while (0)
; #define PG8_LDA(dst, b, h) do { _Pragma("unroll") for (int m = 0; m < 4; ++m) _Pragma("unroll") for (int k = 0; k < 2; ++k) dst[m][k] = *(const PG8_LAS bf16x8*)(lds + PG8_SA(b, h) + aoff + m * 2048 + k * 1024); } while (0)
; #define PG8_MMA(ai, bj, At, Bt) do { __builtin_amdgcn_s_setprio(1); _Pragma("unroll") for (int m = 0; m < 4; ++m) _Pragma("unroll") for (int n = 0; n < 2; ++n) _Pragma("unroll") for (int k = 0; k < 2; ++k) \
;         acc[ai][bj][m][n] = __builtin_amdgcn_mfma_f32_16x16x32_bf16(Bt[n][k], At[m][k], acc[ai][bj][m][n], 0, 0, 0); __builtin_amdgcn_s_setprio(0); } while (0)
; #define PG8_WAIT_V(n) asm volatile("s_waitcnt vmcnt(" #n ")" ::: "memory")
; #define PG8_WAIT_L(n) asm volatile("s_waitcnt lgkmcnt(" #n ")" ::: "memory")
; #define PG8_BAR __builtin_amdgcn_s_barrier()
; #define PG8_SCHED __builtin_amdgcn_sched_barrier(0)
; __device__ __forceinline__ float row_rs(const float* ssp, int row) { const unsigned long long v = ((const unsigned long long*)ssp)[row];
;     return __builtin_amdgcn_rsqf((float)v * (1.0f / 4294967296.0f) * (1.0f / 1024.0f) + RMS_EPS); }
; template <class Epi, class Sched, bool ALIGN_EPI = false, bool SP2 = false>
; __device__ __forceinline__ void gemm_phase(PG8_LAS unsigned char* lds, const Gemm g, const Sched& S, const Epi& E) {
;     ...
;             PG8_LDA(At, 1, 1); PG8_STAGE(PG8_SB(1, 0), b3, voffB); PG8_STAGE(PG8_SB(1, 1), b3 + hstep, voffB); PG8_STAGE(PG8_SA(1, 0), a3, voffA);
;             PG8_WAIT_V(8); PG8_WAIT_L(0); PG8_BAR; PG8_MMA(1, 0, At, B0); PG8_MMA(1, 1, At, B1); PG8_BAR; PG8_SCHED;
	s_add_i32 s42, s58, s15
	v_lshl_add_u64 v[218:219], v[218:219], 0, s[8:9]
	s_mov_b32 m0, s42
	ds_read_b128 v[184:187], v157 offset:49152
	ds_read_b128 v[188:191], v157 offset:50176
	ds_read_b128 v[192:195], v157 offset:51200
	ds_read_b128 v[196:199], v157 offset:52224
	ds_read_b128 v[200:203], v157 offset:53248
	ds_read_b128 v[206:209], v157 offset:54272
	ds_read_b128 v[210:213], v157 offset:55296
	ds_read_b128 v[214:217], v157 offset:56320
	global_load_lds_dwordx4 v[218:219], off
	s_add_i32 m0, s42, 0x2000
	s_add_u32 s40, s40, 0x40080
	v_lshl_add_u64 v[218:219], v[220:221], 0, s[8:9]
	s_addc_u32 s41, s41, 0
	s_add_i32 s42, s59, s15
	global_load_lds_dwordx4 v[218:219], off
	v_lshl_add_u64 v[218:219], s[40:41], 0, v[132:133]
	s_mov_b32 m0, s42
	s_nop 0
	global_load_lds_dwordx4 v[218:219], off
	v_lshl_add_u64 v[218:219], s[40:41], 0, v[128:129]
	s_add_i32 m0, s42, 0x2000
	s_nop 0
	global_load_lds_dwordx4 v[218:219], off
	s_waitcnt vmcnt(6)
	s_waitcnt lgkmcnt(0)
	s_barrier
	s_setprio 1
	s_waitcnt lgkmcnt(0)
	v_mfma_f32_16x16x32_bf16 v[60:63], v[144:147], v[184:187], v[60:63]
	v_mfma_f32_16x16x32_bf16 v[40:43], v[160:163], v[192:195], v[40:43]
	v_mfma_f32_16x16x32_bf16 v[28:31], v[144:147], v[200:203], v[28:31]
	v_mfma_f32_16x16x32_bf16 v[8:11], v[160:163], v[210:213], v[8:11]
	v_mfma_f32_16x16x32_bf16 v[44:47], v[144:147], v[192:195], v[44:47]
	v_mfma_f32_16x16x32_bf16 v[56:59], v[160:163], v[184:187], v[56:59]
	v_mfma_f32_16x16x32_bf16 v[12:15], v[144:147], v[210:213], v[12:15]
	v_mfma_f32_16x16x32_bf16 v[24:27], v[160:163], v[200:203], v[24:27]
	v_mfma_f32_16x16x32_bf16 v[60:63], v[148:151], v[188:191], v[60:63]
	v_mfma_f32_16x16x32_bf16 v[40:43], v[164:167], v[196:199], v[40:43]
	v_mfma_f32_16x16x32_bf16 v[28:31], v[148:151], v[206:209], v[28:31]
	v_mfma_f32_16x16x32_bf16 v[8:11], v[164:167], v[214:217], v[8:11]
	v_mfma_f32_16x16x32_bf16 v[44:47], v[148:151], v[196:199], v[44:47]
	v_mfma_f32_16x16x32_bf16 v[56:59], v[164:167], v[188:191], v[56:59]
	v_lshl_add_u64 v[218:219], v[222:223], 0, s[8:9]
	s_mov_b32 m0, s47
	s_nop 0
	global_load_lds_dwordx4 v[218:219], off
	v_mfma_f32_16x16x32_bf16 v[12:15], v[148:151], v[214:217], v[12:15]
	v_mfma_f32_16x16x32_bf16 v[24:27], v[164:167], v[206:209], v[24:27]
	s_setprio 0
	s_setprio 1
	v_mfma_f32_16x16x32_bf16 v[52:55], v[168:171], v[184:187], v[52:55]
	v_mfma_f32_16x16x32_bf16 v[32:35], v[176:179], v[192:195], v[32:35]
	v_mfma_f32_16x16x32_bf16 v[20:23], v[168:171], v[200:203], v[20:23]
	v_mfma_f32_16x16x32_bf16 v[0:3], v[176:179], v[210:213], v[0:3]
	v_mfma_f32_16x16x32_bf16 v[36:39], v[168:171], v[192:195], v[36:39]
	v_mfma_f32_16x16x32_bf16 v[48:51], v[176:179], v[184:187], v[48:51]
	v_mfma_f32_16x16x32_bf16 v[4:7], v[168:171], v[210:213], v[4:7]
	v_mfma_f32_16x16x32_bf16 v[16:19], v[176:179], v[200:203], v[16:19]
	v_mfma_f32_16x16x32_bf16 v[52:55], v[172:175], v[188:191], v[52:55]
	v_mfma_f32_16x16x32_bf16 v[32:35], v[180:183], v[196:199], v[32:35]
	v_mfma_f32_16x16x32_bf16 v[20:23], v[172:175], v[206:209], v[20:23]
	v_mfma_f32_16x16x32_bf16 v[0:3], v[180:183], v[214:217], v[0:3]
	v_mfma_f32_16x16x32_bf16 v[36:39], v[172:175], v[196:199], v[36:39]
	v_mfma_f32_16x16x32_bf16 v[48:51], v[180:183], v[188:191], v[48:51]
	v_lshl_add_u64 v[218:219], v[224:225], 0, s[8:9]
	s_mov_b32 m0, s48
	s_nop 0
	global_load_lds_dwordx4 v[218:219], off
	v_mfma_f32_16x16x32_bf16 v[4:7], v[172:175], v[214:217], v[4:7]
	v_mfma_f32_16x16x32_bf16 v[16:19], v[180:183], v[206:209], v[16:19]
	s_setprio 0
	s_barrier
	s_add_i32 s57, s57, 2
	s_add_u32 s38, s38, 0x100
	s_addc_u32 s39, s39, 0
	s_add_u32 s55, s55, 0x100
	s_addc_u32 s56, s56, 0
	s_cmp_gt_u32 s57, 13
	s_cbranch_scc0 .LBB0_1900
	v_lshl_add_u32 v144, s36, 8, v152
	v_ashrrev_i32_e32 v145, 31, v144
	v_lshl_add_u64 v[150:151], v[144:145], 3, s[0:1]
	global_load_dwordx2 v[182:183], v[150:151], off
	global_load_dwordx2 v[184:185], v[150:151], off offset:128
	global_load_dwordx2 v[186:187], v[150:151], off offset:256
	global_load_dwordx2 v[188:189], v[150:151], off offset:384
	global_load_dwordx2 v[190:191], v[150:151], off offset:1024
	global_load_dwordx2 v[192:193], v[150:151], off offset:1152
	global_load_dwordx2 v[194:195], v[150:151], off offset:1280
	global_load_dwordx2 v[196:197], v[150:151], off offset:1408
	s_and_b64 vcc, exec, s[10:11]
	s_cbranch_vccz .LBB0_1903
	s_barrier

; #define PG8_STAGE(bufoff, gbase, voff) do { _Pragma("unroll") for (int _i = 0; _i < 2; ++_i) \
;         __builtin_amdgcn_global_load_lds((const unsigned*)((const char*)(gbase) + (voff)[_i]), (PG8_LAS unsigned*)(lds + (bufoff) + ldsw + _i * 8192), 16, 0, 0); } while (0)
; #define PG8_LDA(dst, b, h) do { _Pragma("unroll") for (int m = 0; m < 4; ++m) _Pragma("unroll") for (int k = 0; k < 2; ++k) dst[m][k] = *(const PG8_LAS bf16x8*)(lds + PG8_SA(b, h) + aoff + m * 2048 + k * 1024); } while (0)
; #define PG8_LDB(dst, b, h) do { _Pragma("unroll") for (int n = 0; n < 2; ++n) _Pragma("unroll") for (int k = 0; k < 2; ++k) dst[n][k] = *(const PG8_LAS bf16x8*)(lds + PG8_SB(b, h) + boff + n * 2048 + k * 1024); } while (0)
; #define PG8_MMA(ai, bj, At, Bt) do { __builtin_amdgcn_s_setprio(1); _Pragma("unroll") for (int m = 0; m < 4; ++m) _Pragma("unroll") for (int n = 0; n < 2; ++n) _Pragma("unroll") for (int k = 0; k < 2; ++k) \
;         acc[ai][bj][m][n] = __builtin_amdgcn_mfma_f32_16x16x32_bf16(Bt[n][k], At[m][k], acc[ai][bj][m][n], 0, 0, 0); __builtin_amdgcn_s_setprio(0); } while (0)
; #define PG8_BAR __builtin_amdgcn_s_barrier()
; template <class Epi, class Sched, bool ALIGN_EPI = false, bool SP2 = false>
; __device__ __forceinline__ void gemm_phase(PG8_LAS unsigned char* lds, const Gemm g, const Sched& S, const Epi& E) {
;     ...
;         const bool has_next = S.next(ui + 1, nxt);
;         const char* nA = has_next ? (const char*)g.A + (size_t)nxt.pm * tstep : cA; const char* nB = has_next ? (const char*)g.Bt + (size_t)nxt.pn * tstep : cB;
;         for (int t = 0; t < nt; t += 2) {
;             const bool last = (t == nt - 2);
;             const char* a1 = cA + (size_t)(t + 1) * kstep;
;             const char* a2 = last ? nA : cA + (size_t)(t + 2) * kstep; const char* b2 = last ? nB : cB + (size_t)(t + 2) * kstep;
;             const char* a3 = a2 + kstep; const char* b3 = b2 + kstep;
;             if (last && has_next) S.a_ready(nxt);
;             if constexpr (SP2) {
;             PG8_LDB(B0, 0, 0); PG8_LDB(B1, 0, 1); PG8_SCHED; PG8_LDA(At, 0, 0); PG8_STAGE(PG8_SA(1, 1), a1 + hstep, voffA);
;             PG8_WAIT_V(8); PG8_WAIT_L(0); PG8_BAR; PG8_MMA(0, 0, At, B0); PG8_MMA(0, 1, At, B1); PG8_BAR; PG8_SCHED;
;             PG8_LDA(At, 0, 1); PG8_STAGE(PG8_SB(0, 0), b2, voffB); PG8_STAGE(PG8_SB(0, 1), b2 + hstep, voffB); PG8_STAGE(PG8_SA(0, 0), a2, voffA);
.LBB0_1977:
	s_add_u32 s53, s28, 0x100
	s_addc_u32 s54, s29, 0
	s_mov_b32 s55, -2
	s_waitcnt lgkmcnt(0)
	ds_read_b128 v[144:147], v151
	ds_read_b128 v[156:159], v151 offset:1024
	ds_read_b128 v[160:163], v151 offset:2048
	ds_read_b128 v[164:167], v151 offset:3072
	ds_read_b128 v[168:171], v152
	ds_read_b128 v[172:175], v152 offset:1024
	ds_read_b128 v[176:179], v152 offset:2048
	ds_read_b128 v[180:183], v152 offset:3072
	s_add_u32 s28, s26, 0x100
	s_addc_u32 s29, s27, 0
	s_cmp_eq_u32 s55, 40
	s_cselect_b32 s39, s1, s29
	s_cselect_b32 s38, s0, s28
	s_cselect_b32 s37, s25, s54
	s_cselect_b32 s36, s24, s53
	v_lshl_add_u64 v[218:219], s[26:27], 0, v[136:137]
	s_add_i32 m0, s33, 0xc000
	ds_read_b128 v[184:187], v153
	ds_read_b128 v[188:191], v153 offset:1024
	ds_read_b128 v[192:195], v153 offset:2048
	ds_read_b128 v[196:199], v153 offset:3072
	ds_read_b128 v[200:203], v153 offset:4096
	ds_read_b128 v[206:209], v153 offset:5120
	ds_read_b128 v[210:213], v153 offset:6144
	ds_read_b128 v[214:217], v153 offset:7168
	global_load_lds_dwordx4 v[218:219], off
	v_lshl_add_u64 v[218:219], s[26:27], 0, v[138:139]
	s_add_i32 m0, s33, 0xe000
	s_nop 0
	global_load_lds_dwordx4 v[218:219], off
	s_waitcnt vmcnt(8)
	s_waitcnt lgkmcnt(0)
	s_barrier
	s_setprio 1
	s_waitcnt lgkmcnt(0)
	v_mfma_f32_16x16x32_bf16 v[124:127], v[144:147], v[184:187], 0
	v_mfma_f32_16x16x32_bf16 v[104:107], v[160:163], v[192:195], 0
	v_mfma_f32_16x16x32_bf16 v[92:95], v[144:147], v[200:203], 0
	v_mfma_f32_16x16x32_bf16 v[72:75], v[160:163], v[210:213], 0
	v_mfma_f32_16x16x32_bf16 v[108:111], v[144:147], v[192:195], 0
	v_mfma_f32_16x16x32_bf16 v[120:123], v[160:163], v[184:187], 0
	v_mfma_f32_16x16x32_bf16 v[76:79], v[144:147], v[210:213], 0
	v_mfma_f32_16x16x32_bf16 v[88:91], v[160:163], v[200:203], 0
	v_mfma_f32_16x16x32_bf16 v[124:127], v[156:159], v[188:191], v[124:127]
	v_mfma_f32_16x16x32_bf16 v[104:107], v[164:167], v[196:199], v[104:107]
	v_mfma_f32_16x16x32_bf16 v[92:95], v[156:159], v[206:209], v[92:95]
	v_mfma_f32_16x16x32_bf16 v[72:75], v[164:167], v[214:217], v[72:75]
	v_mfma_f32_16x16x32_bf16 v[108:111], v[156:159], v[196:199], v[108:111]
	v_mfma_f32_16x16x32_bf16 v[120:123], v[164:167], v[188:191], v[120:123]
	v_mfma_f32_16x16x32_bf16 v[76:79], v[156:159], v[214:217], v[76:79]
	v_mfma_f32_16x16x32_bf16 v[88:91], v[164:167], v[206:209], v[88:91]
	s_setprio 0
	s_setprio 1
	v_mfma_f32_16x16x32_bf16 v[116:119], v[168:171], v[184:187], 0
	v_mfma_f32_16x16x32_bf16 v[96:99], v[176:179], v[192:195], 0
	v_mfma_f32_16x16x32_bf16 v[84:87], v[168:171], v[200:203], 0
	v_mfma_f32_16x16x32_bf16 v[64:67], v[176:179], v[210:213], 0
	v_mfma_f32_16x16x32_bf16 v[100:103], v[168:171], v[192:195], 0
	v_mfma_f32_16x16x32_bf16 v[112:115], v[176:179], v[184:187], 0
	v_mfma_f32_16x16x32_bf16 v[68:71], v[168:171], v[210:213], 0
	v_mfma_f32_16x16x32_bf16 v[80:83], v[176:179], v[200:203], 0
	v_mfma_f32_16x16x32_bf16 v[116:119], v[172:175], v[188:191], v[116:119]
	v_mfma_f32_16x16x32_bf16 v[96:99], v[180:183], v[196:199], v[96:99]
	v_mfma_f32_16x16x32_bf16 v[84:87], v[172:175], v[206:209], v[84:87]
	v_mfma_f32_16x16x32_bf16 v[64:67], v[180:183], v[214:217], v[64:67]
	v_mfma_f32_16x16x32_bf16 v[100:103], v[172:175], v[196:199], v[100:103]
	v_mfma_f32_16x16x32_bf16 v[112:115], v[180:183], v[188:191], v[112:115]
	v_mfma_f32_16x16x32_bf16 v[68:71], v[172:175], v[214:217], v[68:71]
	v_mfma_f32_16x16x32_bf16 v[80:83], v[180:183], v[206:209], v[80:83]
	s_setprio 0
	s_barrier
	s_add_i32 s26, s45, s15
	v_lshl_add_u64 v[218:219], s[36:37], 0, v[130:131]
	s_mov_b32 m0, s26
	ds_read_b128 v[184:187], v153 offset:16384
	ds_read_b128 v[188:191], v153 offset:17408
	ds_read_b128 v[192:195], v153 offset:18432
	ds_read_b128 v[196:199], v153 offset:19456
	ds_read_b128 v[200:203], v153 offset:20480
	ds_read_b128 v[206:209], v153 offset:21504
	ds_read_b128 v[210:213], v153 offset:22528
	ds_read_b128 v[214:217], v153 offset:23552
	global_load_lds_dwordx4 v[218:219], off
	s_add_i32 m0, s26, 0x2000
	s_add_u32 s26, s36, 0xb0000
	v_lshl_add_u64 v[220:221], s[36:37], 0, v[134:135]
	s_addc_u32 s27, s37, 0
	s_add_i32 s56, s46, s15
	global_load_lds_dwordx4 v[220:221], off
	v_lshl_add_u64 v[222:223], s[26:27], 0, v[130:131]
	s_mov_b32 m0, s56
	global_load_lds_dwordx4 v[222:223], off
	v_lshl_add_u64 v[222:223], s[26:27], 0, v[134:135]
	s_add_i32 m0, s56, 0x2000
	s_nop 0
	global_load_lds_dwordx4 v[222:223], off
	s_waitcnt vmcnt(6)
	s_waitcnt lgkmcnt(0)
	s_barrier
; #define PG8_STAGE(bufoff, gbase, voff) do { _Pragma("unroll") for (int _i = 0; _i < 2; ++_i) \
;         __builtin_amdgcn_global_load_lds((const unsigned*)((const char*)(gbase) + (voff)[_i]), (PG8_LAS unsigned*)(lds + (bufoff) + ldsw + _i * 8192), 16, 0, 0); } while (0)
; #define PG8_LDA(dst, b, h) do { _Pragma("unroll") for (int m = 0; m < 4; ++m) _Pragma("unroll") for (int k = 0; k < 2; ++k) dst[m][k] = *(const PG8_LAS bf16x8*)(lds + PG8_SA(b, h) + aoff + m * 2048 + k * 1024); } while (0)
; #define PG8_LDB(dst, b, h) do { _Pragma("unroll") for (int n = 0; n < 2; ++n) _Pragma("unroll") for (int k = 0; k < 2; ++k) dst[n][k] = *(const PG8_LAS bf16x8*)(lds + PG8_SB(b, h) + boff + n * 2048 + k * 1024); } while (0)
; #define PG8_MMA(ai, bj, At, Bt) do { __builtin_amdgcn_s_setprio(1); _Pragma("unroll") for (int m = 0; m < 4; ++m) _Pragma("unroll") for (int n = 0; n < 2; ++n) _Pragma("unroll") for (int k = 0; k < 2; ++k) \
;         acc[ai][bj][m][n] = __builtin_amdgcn_mfma_f32_16x16x32_bf16(Bt[n][k], At[m][k], acc[ai][bj][m][n], 0, 0, 0); __builtin_amdgcn_s_setprio(0); } while (0)
; #define PG8_WAIT_V(n) asm volatile("s_waitcnt vmcnt(" #n ")" ::: "memory")
; #define PG8_WAIT_L(n) asm volatile("s_waitcnt lgkmcnt(" #n ")" ::: "memory")
; #define PG8_BAR __builtin_amdgcn_s_barrier()
; #define PG8_SCHED __builtin_amdgcn_sched_barrier(0)
; template <class Epi, class Sched, bool ALIGN_EPI = false, bool SP2 = false>
; __device__ __forceinline__ void gemm_phase(PG8_LAS unsigned char* lds, const Gemm g, const Sched& S, const Epi& E) {
;     ...
;             PG8_WAIT_V(8); PG8_WAIT_L(0); PG8_BAR; PG8_MMA(1, 0, At, B0); PG8_MMA(1, 1, At, B1); PG8_BAR; PG8_SCHED;
;             PG8_LDB(B0, 1, 0); PG8_LDB(B1, 1, 1); PG8_SCHED; PG8_LDA(At, 1, 0); PG8_STAGE(PG8_SA(0, 1), a2 + hstep, voffA);
;             PG8_WAIT_V(8); PG8_WAIT_L(0); PG8_BAR; PG8_MMA(0, 0, At, B0); PG8_MMA(0, 1, At, B1); PG8_BAR; PG8_SCHED;
	s_setprio 1
	s_waitcnt lgkmcnt(0)
	v_mfma_f32_16x16x32_bf16 v[60:63], v[144:147], v[184:187], 0
	v_mfma_f32_16x16x32_bf16 v[40:43], v[160:163], v[192:195], 0
	v_mfma_f32_16x16x32_bf16 v[28:31], v[144:147], v[200:203], 0
	v_mfma_f32_16x16x32_bf16 v[8:11], v[160:163], v[210:213], 0
	v_mfma_f32_16x16x32_bf16 v[44:47], v[144:147], v[192:195], 0
	v_mfma_f32_16x16x32_bf16 v[56:59], v[160:163], v[184:187], 0
	v_mfma_f32_16x16x32_bf16 v[12:15], v[144:147], v[210:213], 0
	v_mfma_f32_16x16x32_bf16 v[24:27], v[160:163], v[200:203], 0
	v_mfma_f32_16x16x32_bf16 v[60:63], v[156:159], v[188:191], v[60:63]
	v_mfma_f32_16x16x32_bf16 v[40:43], v[164:167], v[196:199], v[40:43]
	v_mfma_f32_16x16x32_bf16 v[28:31], v[156:159], v[206:209], v[28:31]
	v_mfma_f32_16x16x32_bf16 v[8:11], v[164:167], v[214:217], v[8:11]
	v_mfma_f32_16x16x32_bf16 v[44:47], v[156:159], v[196:199], v[44:47]
	v_mfma_f32_16x16x32_bf16 v[56:59], v[164:167], v[188:191], v[56:59]
	v_lshl_add_u64 v[222:223], s[38:39], 0, v[128:129]
	s_mov_b32 m0, s33
	s_nop 0
	global_load_lds_dwordx4 v[222:223], off
	v_mfma_f32_16x16x32_bf16 v[12:15], v[156:159], v[214:217], v[12:15]
	v_mfma_f32_16x16x32_bf16 v[24:27], v[164:167], v[206:209], v[24:27]
	s_setprio 0
	s_setprio 1
	v_mfma_f32_16x16x32_bf16 v[52:55], v[168:171], v[184:187], 0
	v_mfma_f32_16x16x32_bf16 v[32:35], v[176:179], v[192:195], 0
	v_mfma_f32_16x16x32_bf16 v[20:23], v[168:171], v[200:203], 0
	v_mfma_f32_16x16x32_bf16 v[0:3], v[176:179], v[210:213], 0
	v_mfma_f32_16x16x32_bf16 v[36:39], v[168:171], v[192:195], 0
	v_mfma_f32_16x16x32_bf16 v[48:51], v[176:179], v[184:187], 0
	v_mfma_f32_16x16x32_bf16 v[4:7], v[168:171], v[210:213], 0
	v_mfma_f32_16x16x32_bf16 v[16:19], v[176:179], v[200:203], 0
	v_mfma_f32_16x16x32_bf16 v[52:55], v[172:175], v[188:191], v[52:55]
	v_mfma_f32_16x16x32_bf16 v[32:35], v[180:183], v[196:199], v[32:35]
	v_mfma_f32_16x16x32_bf16 v[20:23], v[172:175], v[206:209], v[20:23]
	v_mfma_f32_16x16x32_bf16 v[0:3], v[180:183], v[214:217], v[0:3]
	v_mfma_f32_16x16x32_bf16 v[36:39], v[172:175], v[196:199], v[36:39]
	v_mfma_f32_16x16x32_bf16 v[48:51], v[180:183], v[188:191], v[48:51]
	v_lshl_add_u64 v[224:225], s[38:39], 0, v[132:133]
	s_mov_b32 m0, s34
	s_nop 0
	global_load_lds_dwordx4 v[224:225], off
	v_mfma_f32_16x16x32_bf16 v[4:7], v[172:175], v[214:217], v[4:7]
	v_mfma_f32_16x16x32_bf16 v[16:19], v[180:183], v[206:209], v[16:19]
	s_setprio 0
	s_barrier
	s_add_i32 s56, 0, 0x18000
	v_add_u32_e32 v155, s56, v149
	s_add_i32 s57, 0, 0x1c000
	ds_read_b128 v[144:147], v155
	ds_read_b128 v[156:159], v155 offset:1024
	ds_read_b128 v[160:163], v155 offset:2048
	ds_read_b128 v[164:167], v155 offset:3072
	v_add_u32_e32 v155, s57, v149
	ds_read_b128 v[168:171], v155
	ds_read_b128 v[172:175], v155 offset:1024
	ds_read_b128 v[176:179], v155 offset:2048
	ds_read_b128 v[180:183], v155 offset:3072
	s_add_u32 s26, s38, 0xb0000
	s_addc_u32 s27, s39, 0
	s_mov_b32 m0, s40
	v_lshl_add_u64 v[226:227], s[26:27], 0, v[128:129]
	ds_read_b128 v[184:187], v153 offset:32768
	ds_read_b128 v[188:191], v153 offset:33792
	ds_read_b128 v[192:195], v153 offset:34816
	ds_read_b128 v[196:199], v153 offset:35840
	ds_read_b128 v[200:203], v153 offset:36864
	ds_read_b128 v[206:209], v153 offset:37888
	ds_read_b128 v[210:213], v153 offset:38912
	ds_read_b128 v[214:217], v153 offset:39936
	global_load_lds_dwordx4 v[226:227], off
	v_lshl_add_u64 v[226:227], s[26:27], 0, v[132:133]
	s_mov_b32 m0, s41
	s_nop 0
	global_load_lds_dwordx4 v[226:227], off
	s_waitcnt vmcnt(8)
	s_waitcnt lgkmcnt(0)
	s_barrier
	s_setprio 1
	s_waitcnt lgkmcnt(0)
	v_mfma_f32_16x16x32_bf16 v[124:127], v[144:147], v[184:187], v[124:127]
	v_mfma_f32_16x16x32_bf16 v[104:107], v[160:163], v[192:195], v[104:107]
	v_mfma_f32_16x16x32_bf16 v[92:95], v[144:147], v[200:203], v[92:95]
	v_mfma_f32_16x16x32_bf16 v[72:75], v[160:163], v[210:213], v[72:75]
	v_mfma_f32_16x16x32_bf16 v[108:111], v[144:147], v[192:195], v[108:111]
	v_mfma_f32_16x16x32_bf16 v[120:123], v[160:163], v[184:187], v[120:123]
	v_mfma_f32_16x16x32_bf16 v[76:79], v[144:147], v[210:213], v[76:79]
	v_mfma_f32_16x16x32_bf16 v[88:91], v[160:163], v[200:203], v[88:91]
	v_mfma_f32_16x16x32_bf16 v[124:127], v[156:159], v[188:191], v[124:127]
	v_mfma_f32_16x16x32_bf16 v[104:107], v[164:167], v[196:199], v[104:107]
	v_mfma_f32_16x16x32_bf16 v[92:95], v[156:159], v[206:209], v[92:95]
	v_mfma_f32_16x16x32_bf16 v[72:75], v[164:167], v[214:217], v[72:75]
	v_mfma_f32_16x16x32_bf16 v[108:111], v[156:159], v[196:199], v[108:111]
	v_mfma_f32_16x16x32_bf16 v[120:123], v[164:167], v[188:191], v[120:123]
	v_mfma_f32_16x16x32_bf16 v[76:79], v[156:159], v[214:217], v[76:79]
	v_mfma_f32_16x16x32_bf16 v[88:91], v[164:167], v[206:209], v[88:91]
	s_setprio 0
	s_setprio 1
	v_mfma_f32_16x16x32_bf16 v[116:119], v[168:171], v[184:187], v[116:119]
	v_mfma_f32_16x16x32_bf16 v[96:99], v[176:179], v[192:195], v[96:99]
	v_mfma_f32_16x16x32_bf16 v[84:87], v[168:171], v[200:203], v[84:87]
	v_mfma_f32_16x16x32_bf16 v[64:67], v[176:179], v[210:213], v[64:67]
	v_mfma_f32_16x16x32_bf16 v[100:103], v[168:171], v[192:195], v[100:103]
	v_mfma_f32_16x16x32_bf16 v[112:115], v[176:179], v[184:187], v[112:115]
	v_mfma_f32_16x16x32_bf16 v[68:71], v[168:171], v[210:213], v[68:71]
	v_mfma_f32_16x16x32_bf16 v[80:83], v[176:179], v[200:203], v[80:83]
	v_mfma_f32_16x16x32_bf16 v[116:119], v[172:175], v[188:191], v[116:119]
	v_mfma_f32_16x16x32_bf16 v[96:99], v[180:183], v[196:199], v[96:99]
	v_mfma_f32_16x16x32_bf16 v[84:87], v[172:175], v[206:209], v[84:87]
	v_mfma_f32_16x16x32_bf16 v[64:67], v[180:183], v[214:217], v[64:67]
	v_mfma_f32_16x16x32_bf16 v[100:103], v[172:175], v[196:199], v[100:103]
	v_mfma_f32_16x16x32_bf16 v[112:115], v[180:183], v[188:191], v[112:115]
	v_mfma_f32_16x16x32_bf16 v[68:71], v[172:175], v[214:217], v[68:71]
	v_mfma_f32_16x16x32_bf16 v[80:83], v[180:183], v[206:209], v[80:83]
	s_setprio 0
	s_barrier
; #define PG8_STAGE(bufoff, gbase, voff) do { _Pragma("unroll") for (int _i = 0; _i < 2; ++_i) \
;         __builtin_amdgcn_global_load_lds((const unsigned*)((const char*)(gbase) + (voff)[_i]), (PG8_LAS unsigned*)(lds + (bufoff) + ldsw + _i * 8192), 16, 0, 0); } while (0)
; #define PG8_LDA(dst, b, h) do { _Pragma("unroll") for (int m = 0; m < 4; ++m) _Pragma("unroll") for (int k = 0; k < 2; ++k) dst[m][k] = *(const PG8_LAS bf16x8*)(lds + PG8_SA(b, h) + aoff + m * 2048 + k * 1024); } while (0)
; #define PG8_LDB(dst, b, h) do { _Pragma("unroll") for (int n = 0; n < 2; ++n) _Pragma("unroll") for (int k = 0; k < 2; ++k) dst[n][k] = *(const PG8_LAS bf16x8*)(lds + PG8_SB(b, h) + boff + n * 2048 + k * 1024); } while (0)
; #define PG8_MMA(ai, bj, At, Bt) do { __builtin_amdgcn_s_setprio(1); _Pragma("unroll") for (int m = 0; m < 4; ++m) _Pragma("unroll") for (int n = 0; n < 2; ++n) _Pragma("unroll") for (int k = 0; k < 2; ++k) \
;         acc[ai][bj][m][n] = __builtin_amdgcn_mfma_f32_16x16x32_bf16(Bt[n][k], At[m][k], acc[ai][bj][m][n], 0, 0, 0); __builtin_amdgcn_s_setprio(0); } while (0)
; #define PG8_WAIT_V(n) asm volatile("s_waitcnt vmcnt(" #n ")" ::: "memory")
; #define PG8_WAIT_L(n) asm volatile("s_waitcnt lgkmcnt(" #n ")" ::: "memory")
; #define PG8_BAR __builtin_amdgcn_s_barrier()
; #define PG8_SCHED __builtin_amdgcn_sched_barrier(0)
; template <class Epi, class Sched, bool ALIGN_EPI = false, bool SP2 = false>
; __device__ __forceinline__ void gemm_phase(PG8_LAS unsigned char* lds, const Gemm g, const Sched& S, const Epi& E) {
;     ...
;         for (int t = 0; t < nt; t += 2) {
;             const bool last = (t == nt - 2);
;             const char* a1 = cA + (size_t)(t + 1) * kstep;
;             const char* a2 = last ? nA : cA + (size_t)(t + 2) * kstep; const char* b2 = last ? nB : cB + (size_t)(t + 2) * kstep;
;             const char* a3 = a2 + kstep; const char* b3 = b2 + kstep;
;             if (last && has_next) S.a_ready(nxt);
;             if constexpr (SP2) {
;             PG8_LDB(B0, 0, 0); PG8_LDB(B1, 0, 1); PG8_SCHED; PG8_LDA(At, 0, 0); PG8_STAGE(PG8_SA(1, 1), a1 + hstep, voffA);
;     ...
;             PG8_LDA(At, 1, 1); PG8_STAGE(PG8_SB(1, 0), b3, voffB); PG8_STAGE(PG8_SB(1, 1), b3 + hstep, voffB); PG8_STAGE(PG8_SA(1, 0), a3, voffA);
;             PG8_WAIT_V(8); PG8_WAIT_L(0); PG8_BAR; PG8_MMA(1, 0, At, B0); PG8_MMA(1, 1, At, B1); PG8_BAR; PG8_SCHED;
	s_add_i32 s26, s56, s15
	v_lshl_add_u64 v[218:219], v[218:219], 0, s[12:13]
	s_mov_b32 m0, s26
	ds_read_b128 v[184:187], v153 offset:49152
	ds_read_b128 v[188:191], v153 offset:50176
	ds_read_b128 v[192:195], v153 offset:51200
	ds_read_b128 v[196:199], v153 offset:52224
	ds_read_b128 v[200:203], v153 offset:53248
	ds_read_b128 v[206:209], v153 offset:54272
	ds_read_b128 v[210:213], v153 offset:55296
	ds_read_b128 v[214:217], v153 offset:56320
	global_load_lds_dwordx4 v[218:219], off
	s_add_i32 m0, s26, 0x2000
	s_add_u32 s26, s36, 0xb0080
	v_lshl_add_u64 v[218:219], v[220:221], 0, s[12:13]
	s_addc_u32 s27, s37, 0
	s_add_i32 s36, s57, s15
	global_load_lds_dwordx4 v[218:219], off
	v_lshl_add_u64 v[218:219], s[26:27], 0, v[130:131]
	s_mov_b32 m0, s36
	s_nop 0
	global_load_lds_dwordx4 v[218:219], off
	v_lshl_add_u64 v[218:219], s[26:27], 0, v[134:135]
	s_add_i32 m0, s36, 0x2000
	s_nop 0
	global_load_lds_dwordx4 v[218:219], off
	s_waitcnt vmcnt(6)
	s_waitcnt lgkmcnt(0)
	s_barrier
	s_setprio 1
	s_waitcnt lgkmcnt(0)
	v_mfma_f32_16x16x32_bf16 v[60:63], v[144:147], v[184:187], v[60:63]
	v_mfma_f32_16x16x32_bf16 v[40:43], v[160:163], v[192:195], v[40:43]
	v_mfma_f32_16x16x32_bf16 v[28:31], v[144:147], v[200:203], v[28:31]
	v_mfma_f32_16x16x32_bf16 v[8:11], v[160:163], v[210:213], v[8:11]
	v_mfma_f32_16x16x32_bf16 v[44:47], v[144:147], v[192:195], v[44:47]
	v_mfma_f32_16x16x32_bf16 v[56:59], v[160:163], v[184:187], v[56:59]
	v_mfma_f32_16x16x32_bf16 v[12:15], v[144:147], v[210:213], v[12:15]
	v_mfma_f32_16x16x32_bf16 v[24:27], v[160:163], v[200:203], v[24:27]
	v_mfma_f32_16x16x32_bf16 v[60:63], v[156:159], v[188:191], v[60:63]
	v_mfma_f32_16x16x32_bf16 v[40:43], v[164:167], v[196:199], v[40:43]
	v_mfma_f32_16x16x32_bf16 v[28:31], v[156:159], v[206:209], v[28:31]
	v_mfma_f32_16x16x32_bf16 v[8:11], v[164:167], v[214:217], v[8:11]
	v_mfma_f32_16x16x32_bf16 v[44:47], v[156:159], v[196:199], v[44:47]
	v_mfma_f32_16x16x32_bf16 v[56:59], v[164:167], v[188:191], v[56:59]
	v_lshl_add_u64 v[218:219], v[222:223], 0, s[12:13]
	s_mov_b32 m0, s43
	s_nop 0
	global_load_lds_dwordx4 v[218:219], off
	v_mfma_f32_16x16x32_bf16 v[12:15], v[156:159], v[214:217], v[12:15]
	v_mfma_f32_16x16x32_bf16 v[24:27], v[164:167], v[206:209], v[24:27]
	s_setprio 0
	s_setprio 1
	v_mfma_f32_16x16x32_bf16 v[52:55], v[168:171], v[184:187], v[52:55]
	v_mfma_f32_16x16x32_bf16 v[32:35], v[176:179], v[192:195], v[32:35]
	v_mfma_f32_16x16x32_bf16 v[20:23], v[168:171], v[200:203], v[20:23]
	v_mfma_f32_16x16x32_bf16 v[0:3], v[176:179], v[210:213], v[0:3]
	v_mfma_f32_16x16x32_bf16 v[36:39], v[168:171], v[192:195], v[36:39]
	v_mfma_f32_16x16x32_bf16 v[48:51], v[176:179], v[184:187], v[48:51]
	v_mfma_f32_16x16x32_bf16 v[4:7], v[168:171], v[210:213], v[4:7]
	v_mfma_f32_16x16x32_bf16 v[16:19], v[176:179], v[200:203], v[16:19]
	v_mfma_f32_16x16x32_bf16 v[52:55], v[172:175], v[188:191], v[52:55]
	v_mfma_f32_16x16x32_bf16 v[32:35], v[180:183], v[196:199], v[32:35]
	v_mfma_f32_16x16x32_bf16 v[20:23], v[172:175], v[206:209], v[20:23]
	v_mfma_f32_16x16x32_bf16 v[0:3], v[180:183], v[214:217], v[0:3]
	v_mfma_f32_16x16x32_bf16 v[36:39], v[172:175], v[196:199], v[36:39]
	v_mfma_f32_16x16x32_bf16 v[48:51], v[180:183], v[188:191], v[48:51]
	v_lshl_add_u64 v[218:219], v[224:225], 0, s[12:13]
	s_mov_b32 m0, s44
	s_nop 0
	global_load_lds_dwordx4 v[218:219], off
	v_mfma_f32_16x16x32_bf16 v[4:7], v[172:175], v[214:217], v[4:7]
	v_mfma_f32_16x16x32_bf16 v[16:19], v[180:183], v[206:209], v[16:19]
	s_setprio 0
	s_barrier
	s_add_i32 s55, s55, 2
	s_add_u32 s53, s53, 0x100
	s_addc_u32 s54, s54, 0
	s_mov_b64 s[26:27], s[28:29]
.LBB0_1978:
	ds_read_b128 v[144:147], v151
	ds_read_b128 v[156:159], v151 offset:1024
	ds_read_b128 v[160:163], v151 offset:2048
	ds_read_b128 v[164:167], v151 offset:3072
	ds_read_b128 v[168:171], v152
	ds_read_b128 v[172:175], v152 offset:1024
	ds_read_b128 v[176:179], v152 offset:2048
	ds_read_b128 v[180:183], v152 offset:3072
	s_add_u32 s28, s26, 0x100
	s_addc_u32 s29, s27, 0
	s_cmp_eq_u32 s55, 40
	s_cselect_b32 s39, s1, s29
	s_cselect_b32 s38, s0, s28
	s_cselect_b32 s37, s25, s54
	s_cselect_b32 s36, s24, s53
	v_lshl_add_u64 v[218:219], s[26:27], 0, v[136:137]
	s_add_i32 m0, s33, 0xc000
	ds_read_b128 v[184:187], v153
	ds_read_b128 v[188:191], v153 offset:1024
	ds_read_b128 v[192:195], v153 offset:2048
	ds_read_b128 v[196:199], v153 offset:3072
	ds_read_b128 v[200:203], v153 offset:4096
	ds_read_b128 v[206:209], v153 offset:5120
	ds_read_b128 v[210:213], v153 offset:6144
	ds_read_b128 v[214:217], v153 offset:7168
	global_load_lds_dwordx4 v[218:219], off
	v_lshl_add_u64 v[218:219], s[26:27], 0, v[138:139]
	s_add_i32 m0, s33, 0xe000
	s_nop 0
	global_load_lds_dwordx4 v[218:219], off
	s_waitcnt vmcnt(8)
	s_waitcnt lgkmcnt(0)
	s_barrier
; #define PG8_STAGE(bufoff, gbase, voff) do { _Pragma("unroll") for (int _i = 0; _i < 2; ++_i) \
;         __builtin_amdgcn_global_load_lds((const unsigned*)((const char*)(gbase) + (voff)[_i]), (PG8_LAS unsigned*)(lds + (bufoff) + ldsw + _i * 8192), 16, 0, 0); } while (0)
; #define PG8_LDA(dst, b, h) do { _Pragma("unroll") for (int m = 0; m < 4; ++m) _Pragma("unroll") for (int k = 0; k < 2; ++k) dst[m][k] = *(const PG8_LAS bf16x8*)(lds + PG8_SA(b, h) + aoff + m * 2048 + k * 1024); } while (0)
; #define PG8_MMA(ai, bj, At, Bt) do { __builtin_amdgcn_s_setprio(1); _Pragma("unroll") for (int m = 0; m < 4; ++m) _Pragma("unroll") for (int n = 0; n < 2; ++n) _Pragma("unroll") for (int k = 0; k < 2; ++k) \
;         acc[ai][bj][m][n] = __builtin_amdgcn_mfma_f32_16x16x32_bf16(Bt[n][k], At[m][k], acc[ai][bj][m][n], 0, 0, 0); __builtin_amdgcn_s_setprio(0); } while (0)
; #define PG8_WAIT_V(n) asm volatile("s_waitcnt vmcnt(" #n ")" ::: "memory")
; #define PG8_WAIT_L(n) asm volatile("s_waitcnt lgkmcnt(" #n ")" ::: "memory")
; #define PG8_BAR __builtin_amdgcn_s_barrier()
; #define PG8_SCHED __builtin_amdgcn_sched_barrier(0)
; template <class Epi, class Sched, bool ALIGN_EPI = false, bool SP2 = false>
; __device__ __forceinline__ void gemm_phase(PG8_LAS unsigned char* lds, const Gemm g, const Sched& S, const Epi& E) {
;     ...
;             PG8_WAIT_V(8); PG8_WAIT_L(0); PG8_BAR; PG8_MMA(0, 0, At, B0); PG8_MMA(0, 1, At, B1); PG8_BAR; PG8_SCHED;
;             PG8_LDA(At, 0, 1); PG8_STAGE(PG8_SB(0, 0), b2, voffB); PG8_STAGE(PG8_SB(0, 1), b2 + hstep, voffB); PG8_STAGE(PG8_SA(0, 0), a2, voffA);
;             PG8_WAIT_V(8); PG8_WAIT_L(0); PG8_BAR; PG8_MMA(1, 0, At, B0); PG8_MMA(1, 1, At, B1); PG8_BAR; PG8_SCHED;
	s_setprio 1
	s_waitcnt lgkmcnt(0)
	v_mfma_f32_16x16x32_bf16 v[124:127], v[144:147], v[184:187], v[124:127]
	v_mfma_f32_16x16x32_bf16 v[104:107], v[160:163], v[192:195], v[104:107]
	v_mfma_f32_16x16x32_bf16 v[92:95], v[144:147], v[200:203], v[92:95]
	v_mfma_f32_16x16x32_bf16 v[72:75], v[160:163], v[210:213], v[72:75]
	v_mfma_f32_16x16x32_bf16 v[108:111], v[144:147], v[192:195], v[108:111]
	v_mfma_f32_16x16x32_bf16 v[120:123], v[160:163], v[184:187], v[120:123]
	v_mfma_f32_16x16x32_bf16 v[76:79], v[144:147], v[210:213], v[76:79]
	v_mfma_f32_16x16x32_bf16 v[88:91], v[160:163], v[200:203], v[88:91]
	v_mfma_f32_16x16x32_bf16 v[124:127], v[156:159], v[188:191], v[124:127]
	v_mfma_f32_16x16x32_bf16 v[104:107], v[164:167], v[196:199], v[104:107]
	v_mfma_f32_16x16x32_bf16 v[92:95], v[156:159], v[206:209], v[92:95]
	v_mfma_f32_16x16x32_bf16 v[72:75], v[164:167], v[214:217], v[72:75]
	v_mfma_f32_16x16x32_bf16 v[108:111], v[156:159], v[196:199], v[108:111]
	v_mfma_f32_16x16x32_bf16 v[120:123], v[164:167], v[188:191], v[120:123]
	v_mfma_f32_16x16x32_bf16 v[76:79], v[156:159], v[214:217], v[76:79]
	v_mfma_f32_16x16x32_bf16 v[88:91], v[164:167], v[206:209], v[88:91]
	s_setprio 0
	s_setprio 1
	v_mfma_f32_16x16x32_bf16 v[116:119], v[168:171], v[184:187], v[116:119]
	v_mfma_f32_16x16x32_bf16 v[96:99], v[176:179], v[192:195], v[96:99]
	v_mfma_f32_16x16x32_bf16 v[84:87], v[168:171], v[200:203], v[84:87]
	v_mfma_f32_16x16x32_bf16 v[64:67], v[176:179], v[210:213], v[64:67]
	v_mfma_f32_16x16x32_bf16 v[100:103], v[168:171], v[192:195], v[100:103]
	v_mfma_f32_16x16x32_bf16 v[112:115], v[176:179], v[184:187], v[112:115]
	v_mfma_f32_16x16x32_bf16 v[68:71], v[168:171], v[210:213], v[68:71]
	v_mfma_f32_16x16x32_bf16 v[80:83], v[176:179], v[200:203], v[80:83]
	v_mfma_f32_16x16x32_bf16 v[116:119], v[172:175], v[188:191], v[116:119]
	v_mfma_f32_16x16x32_bf16 v[96:99], v[180:183], v[196:199], v[96:99]
	v_mfma_f32_16x16x32_bf16 v[84:87], v[172:175], v[206:209], v[84:87]
	v_mfma_f32_16x16x32_bf16 v[64:67], v[180:183], v[214:217], v[64:67]
	v_mfma_f32_16x16x32_bf16 v[100:103], v[172:175], v[196:199], v[100:103]
	v_mfma_f32_16x16x32_bf16 v[112:115], v[180:183], v[188:191], v[112:115]
	v_mfma_f32_16x16x32_bf16 v[68:71], v[172:175], v[214:217], v[68:71]
	v_mfma_f32_16x16x32_bf16 v[80:83], v[180:183], v[206:209], v[80:83]
	s_setprio 0
	s_barrier
	s_add_i32 s26, s45, s15
	v_lshl_add_u64 v[218:219], s[36:37], 0, v[130:131]
	s_mov_b32 m0, s26
	ds_read_b128 v[184:187], v153 offset:16384
	ds_read_b128 v[188:191], v153 offset:17408
	ds_read_b128 v[192:195], v153 offset:18432
	ds_read_b128 v[196:199], v153 offset:19456
	ds_read_b128 v[200:203], v153 offset:20480
	ds_read_b128 v[206:209], v153 offset:21504
	ds_read_b128 v[210:213], v153 offset:22528
	ds_read_b128 v[214:217], v153 offset:23552
	global_load_lds_dwordx4 v[218:219], off
	s_add_i32 m0, s26, 0x2000
	s_add_u32 s26, s36, 0xb0000
	v_lshl_add_u64 v[220:221], s[36:37], 0, v[134:135]
	s_addc_u32 s27, s37, 0
	s_add_i32 s56, s46, s15
	global_load_lds_dwordx4 v[220:221], off
	v_lshl_add_u64 v[222:223], s[26:27], 0, v[130:131]
	s_mov_b32 m0, s56
	global_load_lds_dwordx4 v[222:223], off
	v_lshl_add_u64 v[222:223], s[26:27], 0, v[134:135]
	s_add_i32 m0, s56, 0x2000
	s_nop 0
	global_load_lds_dwordx4 v[222:223], off
	s_waitcnt vmcnt(6)
	s_waitcnt lgkmcnt(0)
	s_barrier
	s_setprio 1
	s_waitcnt lgkmcnt(0)
	v_mfma_f32_16x16x32_bf16 v[60:63], v[144:147], v[184:187], v[60:63]
	v_mfma_f32_16x16x32_bf16 v[40:43], v[160:163], v[192:195], v[40:43]
	v_mfma_f32_16x16x32_bf16 v[28:31], v[144:147], v[200:203], v[28:31]
	v_mfma_f32_16x16x32_bf16 v[8:11], v[160:163], v[210:213], v[8:11]
	v_mfma_f32_16x16x32_bf16 v[44:47], v[144:147], v[192:195], v[44:47]
	v_mfma_f32_16x16x32_bf16 v[56:59], v[160:163], v[184:187], v[56:59]
	v_mfma_f32_16x16x32_bf16 v[12:15], v[144:147], v[210:213], v[12:15]
	v_mfma_f32_16x16x32_bf16 v[24:27], v[160:163], v[200:203], v[24:27]
	v_mfma_f32_16x16x32_bf16 v[60:63], v[156:159], v[188:191], v[60:63]
	v_mfma_f32_16x16x32_bf16 v[40:43], v[164:167], v[196:199], v[40:43]
	v_mfma_f32_16x16x32_bf16 v[28:31], v[156:159], v[206:209], v[28:31]
	v_mfma_f32_16x16x32_bf16 v[8:11], v[164:167], v[214:217], v[8:11]
	v_mfma_f32_16x16x32_bf16 v[44:47], v[156:159], v[196:199], v[44:47]
	v_mfma_f32_16x16x32_bf16 v[56:59], v[164:167], v[188:191], v[56:59]
	v_lshl_add_u64 v[222:223], s[38:39], 0, v[128:129]
	s_mov_b32 m0, s33
	s_nop 0
	global_load_lds_dwordx4 v[222:223], off
	v_mfma_f32_16x16x32_bf16 v[12:15], v[156:159], v[214:217], v[12:15]
	v_mfma_f32_16x16x32_bf16 v[24:27], v[164:167], v[206:209], v[24:27]
	s_setprio 0
	s_setprio 1
	v_mfma_f32_16x16x32_bf16 v[52:55], v[168:171], v[184:187], v[52:55]
	v_mfma_f32_16x16x32_bf16 v[32:35], v[176:179], v[192:195], v[32:35]
	v_mfma_f32_16x16x32_bf16 v[20:23], v[168:171], v[200:203], v[20:23]
	v_mfma_f32_16x16x32_bf16 v[0:3], v[176:179], v[210:213], v[0:3]
	v_mfma_f32_16x16x32_bf16 v[36:39], v[168:171], v[192:195], v[36:39]
	v_mfma_f32_16x16x32_bf16 v[48:51], v[176:179], v[184:187], v[48:51]
	v_mfma_f32_16x16x32_bf16 v[4:7], v[168:171], v[210:213], v[4:7]
	v_mfma_f32_16x16x32_bf16 v[16:19], v[176:179], v[200:203], v[16:19]
	v_mfma_f32_16x16x32_bf16 v[52:55], v[172:175], v[188:191], v[52:55]
	v_mfma_f32_16x16x32_bf16 v[32:35], v[180:183], v[196:199], v[32:35]
	v_mfma_f32_16x16x32_bf16 v[20:23], v[172:175], v[206:209], v[20:23]
	v_mfma_f32_16x16x32_bf16 v[0:3], v[180:183], v[214:217], v[0:3]
	v_mfma_f32_16x16x32_bf16 v[36:39], v[172:175], v[196:199], v[36:39]
	v_mfma_f32_16x16x32_bf16 v[48:51], v[180:183], v[188:191], v[48:51]
	v_lshl_add_u64 v[224:225], s[38:39], 0, v[132:133]
	s_mov_b32 m0, s34
	s_nop 0
	global_load_lds_dwordx4 v[224:225], off
	v_mfma_f32_16x16x32_bf16 v[4:7], v[172:175], v[214:217], v[4:7]
	v_mfma_f32_16x16x32_bf16 v[16:19], v[180:183], v[206:209], v[16:19]
	s_setprio 0
	s_barrier
; #define PG8_STAGE(bufoff, gbase, voff) do { _Pragma("unroll") for (int _i = 0; _i < 2; ++_i) \
;         __builtin_amdgcn_global_load_lds((const unsigned*)((const char*)(gbase) + (voff)[_i]), (PG8_LAS unsigned*)(lds + (bufoff) + ldsw + _i * 8192), 16, 0, 0); } while (0)
; #define PG8_LDA(dst, b, h) do { _Pragma("unroll") for (int m = 0; m < 4; ++m) _Pragma("unroll") for (int k = 0; k < 2; ++k) dst[m][k] = *(const PG8_LAS bf16x8*)(lds + PG8_SA(b, h) + aoff + m * 2048 + k * 1024); } while (0)
; #define PG8_LDB(dst, b, h) do { _Pragma("unroll") for (int n = 0; n < 2; ++n) _Pragma("unroll") for (int k = 0; k < 2; ++k) dst[n][k] = *(const PG8_LAS bf16x8*)(lds + PG8_SB(b, h) + boff + n * 2048 + k * 1024); } while (0)
; #define PG8_MMA(ai, bj, At, Bt) do { __builtin_amdgcn_s_setprio(1); _Pragma("unroll") for (int m = 0; m < 4; ++m) _Pragma("unroll") for (int n = 0; n < 2; ++n) _Pragma("unroll") for (int k = 0; k < 2; ++k) \
;         acc[ai][bj][m][n] = __builtin_amdgcn_mfma_f32_16x16x32_bf16(Bt[n][k], At[m][k], acc[ai][bj][m][n], 0, 0, 0); __builtin_amdgcn_s_setprio(0); } while (0)
; #define PG8_WAIT_V(n) asm volatile("s_waitcnt vmcnt(" #n ")" ::: "memory")
; #define PG8_WAIT_L(n) asm volatile("s_waitcnt lgkmcnt(" #n ")" ::: "memory")
; #define PG8_BAR __builtin_amdgcn_s_barrier()
; #define PG8_SCHED __builtin_amdgcn_sched_barrier(0)
; template <class Epi, class Sched, bool ALIGN_EPI = false, bool SP2 = false>
; __device__ __forceinline__ void gemm_phase(PG8_LAS unsigned char* lds, const Gemm g, const Sched& S, const Epi& E) {
;     ...
;             PG8_LDB(B0, 1, 0); PG8_LDB(B1, 1, 1); PG8_SCHED; PG8_LDA(At, 1, 0); PG8_STAGE(PG8_SA(0, 1), a2 + hstep, voffA);
;             PG8_WAIT_V(8); PG8_WAIT_L(0); PG8_BAR; PG8_MMA(0, 0, At, B0); PG8_MMA(0, 1, At, B1); PG8_BAR; PG8_SCHED;
	s_add_i32 s56, 0, 0x18000
	v_add_u32_e32 v155, s56, v149
	s_add_i32 s57, 0, 0x1c000
	ds_read_b128 v[144:147], v155
	ds_read_b128 v[156:159], v155 offset:1024
	ds_read_b128 v[160:163], v155 offset:2048
	ds_read_b128 v[164:167], v155 offset:3072
	v_add_u32_e32 v155, s57, v149
	ds_read_b128 v[168:171], v155
	ds_read_b128 v[172:175], v155 offset:1024
	ds_read_b128 v[176:179], v155 offset:2048
	ds_read_b128 v[180:183], v155 offset:3072
	s_add_u32 s26, s38, 0xb0000
	s_addc_u32 s27, s39, 0
	s_mov_b32 m0, s40
	v_lshl_add_u64 v[226:227], s[26:27], 0, v[128:129]
	ds_read_b128 v[184:187], v153 offset:32768
	ds_read_b128 v[188:191], v153 offset:33792
	ds_read_b128 v[192:195], v153 offset:34816
	ds_read_b128 v[196:199], v153 offset:35840
	ds_read_b128 v[200:203], v153 offset:36864
	ds_read_b128 v[206:209], v153 offset:37888
	ds_read_b128 v[210:213], v153 offset:38912
	ds_read_b128 v[214:217], v153 offset:39936
	global_load_lds_dwordx4 v[226:227], off
	v_lshl_add_u64 v[226:227], s[26:27], 0, v[132:133]
	s_mov_b32 m0, s41
	s_nop 0
	global_load_lds_dwordx4 v[226:227], off
	s_waitcnt vmcnt(8)
	s_waitcnt lgkmcnt(0)
	s_barrier
	s_setprio 1
	s_waitcnt lgkmcnt(0)
	v_mfma_f32_16x16x32_bf16 v[124:127], v[144:147], v[184:187], v[124:127]
	v_mfma_f32_16x16x32_bf16 v[104:107], v[160:163], v[192:195], v[104:107]
	v_mfma_f32_16x16x32_bf16 v[92:95], v[144:147], v[200:203], v[92:95]
	v_mfma_f32_16x16x32_bf16 v[72:75], v[160:163], v[210:213], v[72:75]
	v_mfma_f32_16x16x32_bf16 v[108:111], v[144:147], v[192:195], v[108:111]
	v_mfma_f32_16x16x32_bf16 v[120:123], v[160:163], v[184:187], v[120:123]
	v_mfma_f32_16x16x32_bf16 v[76:79], v[144:147], v[210:213], v[76:79]
	v_mfma_f32_16x16x32_bf16 v[88:91], v[160:163], v[200:203], v[88:91]
	v_mfma_f32_16x16x32_bf16 v[124:127], v[156:159], v[188:191], v[124:127]
	v_mfma_f32_16x16x32_bf16 v[104:107], v[164:167], v[196:199], v[104:107]
	v_mfma_f32_16x16x32_bf16 v[92:95], v[156:159], v[206:209], v[92:95]
	v_mfma_f32_16x16x32_bf16 v[72:75], v[164:167], v[214:217], v[72:75]
	v_mfma_f32_16x16x32_bf16 v[108:111], v[156:159], v[196:199], v[108:111]
	v_mfma_f32_16x16x32_bf16 v[120:123], v[164:167], v[188:191], v[120:123]
	v_mfma_f32_16x16x32_bf16 v[76:79], v[156:159], v[214:217], v[76:79]
	v_mfma_f32_16x16x32_bf16 v[88:91], v[164:167], v[206:209], v[88:91]
	s_setprio 0
	s_setprio 1
	v_mfma_f32_16x16x32_bf16 v[116:119], v[168:171], v[184:187], v[116:119]
	v_mfma_f32_16x16x32_bf16 v[96:99], v[176:179], v[192:195], v[96:99]
	v_mfma_f32_16x16x32_bf16 v[84:87], v[168:171], v[200:203], v[84:87]
	v_mfma_f32_16x16x32_bf16 v[64:67], v[176:179], v[210:213], v[64:67]
	v_mfma_f32_16x16x32_bf16 v[100:103], v[168:171], v[192:195], v[100:103]
	v_mfma_f32_16x16x32_bf16 v[112:115], v[176:179], v[184:187], v[112:115]
	v_mfma_f32_16x16x32_bf16 v[68:71], v[168:171], v[210:213], v[68:71]
	v_mfma_f32_16x16x32_bf16 v[80:83], v[176:179], v[200:203], v[80:83]
	v_mfma_f32_16x16x32_bf16 v[116:119], v[172:175], v[188:191], v[116:119]
	v_mfma_f32_16x16x32_bf16 v[96:99], v[180:183], v[196:199], v[96:99]
	v_mfma_f32_16x16x32_bf16 v[84:87], v[172:175], v[206:209], v[84:87]
	v_mfma_f32_16x16x32_bf16 v[64:67], v[180:183], v[214:217], v[64:67]
	v_mfma_f32_16x16x32_bf16 v[100:103], v[172:175], v[196:199], v[100:103]
	v_mfma_f32_16x16x32_bf16 v[112:115], v[180:183], v[188:191], v[112:115]
	v_mfma_f32_16x16x32_bf16 v[68:71], v[172:175], v[214:217], v[68:71]
	v_mfma_f32_16x16x32_bf16 v[80:83], v[180:183], v[206:209], v[80:83]
	s_setprio 0
	s_barrier
; #define PG8_STAGE(bufoff, gbase, voff) do { _Pragma("unroll") for (int _i = 0; _i < 2; ++_i) \
;         __builtin_amdgcn_global_load_lds((const unsigned*)((const char*)(gbase) + (voff)[_i]), (PG8_LAS unsigned*)(lds + (bufoff) + ldsw + _i * 8192), 16, 0, 0); } while (0)
; #define PG8_LDA(dst, b, h) do { _Pragma("unroll") for (int m = 0; m < 4; ++m) _Pragma("unroll") for (int k = 0; k < 2; ++k) dst[m][k] = *(const PG8_LAS bf16x8*)(lds + PG8_SA(b, h) + aoff + m * 2048 + k * 1024); } while (0)
; #define PG8_MMA(ai, bj, At, Bt) do { __builtin_amdgcn_s_setprio(1); _Pragma("unroll") for (int m = 0; m < 4; ++m) _Pragma("unroll") for (int n = 0; n < 2; ++n) _Pragma("unroll") for (int k = 0; k < 2; ++k) \
;         acc[ai][bj][m][n] = __builtin_amdgcn_mfma_f32_16x16x32_bf16(Bt[n][k], At[m][k], acc[ai][bj][m][n], 0, 0, 0); __builtin_amdgcn_s_setprio(0); } while (0)
; #define PG8_WAIT_V(n) asm volatile("s_waitcnt vmcnt(" #n ")" ::: "memory")
; #define PG8_WAIT_L(n) asm volatile("s_waitcnt lgkmcnt(" #n ")" ::: "memory")
; #define PG8_BAR __builtin_amdgcn_s_barrier()
; #define PG8_SCHED __builtin_amdgcn_sched_barrier(0)
; template <class Epi, class Sched, bool ALIGN_EPI = false, bool SP2 = false>
; __device__ __forceinline__ void gemm_phase(PG8_LAS unsigned char* lds, const Gemm g, const Sched& S, const Epi& E) {
;     ...
;         for (int t = 0; t < nt; t += 2) {
;     ...
;             PG8_LDA(At, 1, 1); PG8_STAGE(PG8_SB(1, 0), b3, voffB); PG8_STAGE(PG8_SB(1, 1), b3 + hstep, voffB); PG8_STAGE(PG8_SA(1, 0), a3, voffA);
;             PG8_WAIT_V(8); PG8_WAIT_L(0); PG8_BAR; PG8_MMA(1, 0, At, B0); PG8_MMA(1, 1, At, B1); PG8_BAR; PG8_SCHED;
	s_add_i32 s26, s56, s15
	v_lshl_add_u64 v[218:219], v[218:219], 0, s[12:13]
	s_mov_b32 m0, s26
	ds_read_b128 v[184:187], v153 offset:49152
	ds_read_b128 v[188:191], v153 offset:50176
	ds_read_b128 v[192:195], v153 offset:51200
	ds_read_b128 v[196:199], v153 offset:52224
	ds_read_b128 v[200:203], v153 offset:53248
	ds_read_b128 v[206:209], v153 offset:54272
	ds_read_b128 v[210:213], v153 offset:55296
	ds_read_b128 v[214:217], v153 offset:56320
	global_load_lds_dwordx4 v[218:219], off
	s_add_i32 m0, s26, 0x2000
	s_add_u32 s26, s36, 0xb0080
	v_lshl_add_u64 v[218:219], v[220:221], 0, s[12:13]
	s_addc_u32 s27, s37, 0
	s_add_i32 s36, s57, s15
	global_load_lds_dwordx4 v[218:219], off
	v_lshl_add_u64 v[218:219], s[26:27], 0, v[130:131]
	s_mov_b32 m0, s36
	s_nop 0
	global_load_lds_dwordx4 v[218:219], off
	v_lshl_add_u64 v[218:219], s[26:27], 0, v[134:135]
	s_add_i32 m0, s36, 0x2000
	s_nop 0
	global_load_lds_dwordx4 v[218:219], off
	s_waitcnt vmcnt(6)
	s_waitcnt lgkmcnt(0)
	s_barrier
	s_setprio 1
	s_waitcnt lgkmcnt(0)
	v_mfma_f32_16x16x32_bf16 v[60:63], v[144:147], v[184:187], v[60:63]
	v_mfma_f32_16x16x32_bf16 v[40:43], v[160:163], v[192:195], v[40:43]
	v_mfma_f32_16x16x32_bf16 v[28:31], v[144:147], v[200:203], v[28:31]
	v_mfma_f32_16x16x32_bf16 v[8:11], v[160:163], v[210:213], v[8:11]
	v_mfma_f32_16x16x32_bf16 v[44:47], v[144:147], v[192:195], v[44:47]
	v_mfma_f32_16x16x32_bf16 v[56:59], v[160:163], v[184:187], v[56:59]
	v_mfma_f32_16x16x32_bf16 v[12:15], v[144:147], v[210:213], v[12:15]
	v_mfma_f32_16x16x32_bf16 v[24:27], v[160:163], v[200:203], v[24:27]
	v_mfma_f32_16x16x32_bf16 v[60:63], v[156:159], v[188:191], v[60:63]
	v_mfma_f32_16x16x32_bf16 v[40:43], v[164:167], v[196:199], v[40:43]
	v_mfma_f32_16x16x32_bf16 v[28:31], v[156:159], v[206:209], v[28:31]
	v_mfma_f32_16x16x32_bf16 v[8:11], v[164:167], v[214:217], v[8:11]
	v_mfma_f32_16x16x32_bf16 v[44:47], v[156:159], v[196:199], v[44:47]
	v_mfma_f32_16x16x32_bf16 v[56:59], v[164:167], v[188:191], v[56:59]
	v_lshl_add_u64 v[218:219], v[222:223], 0, s[12:13]
	s_mov_b32 m0, s43
	s_nop 0
	global_load_lds_dwordx4 v[218:219], off
	v_mfma_f32_16x16x32_bf16 v[12:15], v[156:159], v[214:217], v[12:15]
	v_mfma_f32_16x16x32_bf16 v[24:27], v[164:167], v[206:209], v[24:27]
	s_setprio 0
	s_setprio 1
	v_mfma_f32_16x16x32_bf16 v[52:55], v[168:171], v[184:187], v[52:55]
	v_mfma_f32_16x16x32_bf16 v[32:35], v[176:179], v[192:195], v[32:35]
	v_mfma_f32_16x16x32_bf16 v[20:23], v[168:171], v[200:203], v[20:23]
	v_mfma_f32_16x16x32_bf16 v[0:3], v[176:179], v[210:213], v[0:3]
	v_mfma_f32_16x16x32_bf16 v[36:39], v[168:171], v[192:195], v[36:39]
	v_mfma_f32_16x16x32_bf16 v[48:51], v[176:179], v[184:187], v[48:51]
	v_mfma_f32_16x16x32_bf16 v[4:7], v[168:171], v[210:213], v[4:7]
	v_mfma_f32_16x16x32_bf16 v[16:19], v[176:179], v[200:203], v[16:19]
	v_mfma_f32_16x16x32_bf16 v[52:55], v[172:175], v[188:191], v[52:55]
	v_mfma_f32_16x16x32_bf16 v[32:35], v[180:183], v[196:199], v[32:35]
	v_mfma_f32_16x16x32_bf16 v[20:23], v[172:175], v[206:209], v[20:23]
	v_mfma_f32_16x16x32_bf16 v[0:3], v[180:183], v[214:217], v[0:3]
	v_mfma_f32_16x16x32_bf16 v[36:39], v[172:175], v[196:199], v[36:39]
	v_mfma_f32_16x16x32_bf16 v[48:51], v[180:183], v[188:191], v[48:51]
	v_lshl_add_u64 v[218:219], v[224:225], 0, s[12:13]
	s_mov_b32 m0, s44
	s_nop 0
	global_load_lds_dwordx4 v[218:219], off
	v_mfma_f32_16x16x32_bf16 v[4:7], v[172:175], v[214:217], v[4:7]
	v_mfma_f32_16x16x32_bf16 v[16:19], v[180:183], v[206:209], v[16:19]
	s_setprio 0
	s_barrier
	s_add_i32 s55, s55, 2
	s_add_u32 s53, s53, 0x100
	s_addc_u32 s54, s54, 0
	s_cmp_gt_u32 s55, 41
	s_mov_b64 s[26:27], s[28:29]
	s_cbranch_scc0 .LBB0_1978
	s_and_b64 vcc, exec, s[16:17]
	s_cbranch_vccz .LBB0_1981
	s_barrier
